# GEMM loops: s_setprio 0 moved to just after the post-MFMA barrier (wave keeps raised priority until it starts its load segment); on top of v17
# speedup vs baseline: 1.0065x; 1.0065x over previous
; #define PG8_STAGE(bufoff, gbase, voff) do { _Pragma("unroll") for (int _i = 0; _i < 2; ++_i) \
;         __builtin_amdgcn_global_load_lds((const unsigned*)((const char*)(gbase) + (voff)[_i]), (LAS unsigned*)(lds + (bufoff) + ldsw + _i * 8192), 16, 0, 0); } while (0)
; #define PG8_WAIT_V(n) asm volatile("s_waitcnt vmcnt(" #n ")" ::: "memory")
; #define PG8_WAIT_L(n) asm volatile("s_waitcnt lgkmcnt(" #n ")" ::: "memory")
; template <class Epi, class Sched>
; __device__ __forceinline__ void gemm_phase(LAS unsigned char* lds, const Gemm g, const Sched& S, const Epi& E) {
;     ...
;         const bool has_next = S.next(ui + 1, nxt);
;         const char* nA = has_next ? (const char*)g.A + (size_t)nxt.pm * tstep : cA; const char* nB = has_next ? (const char*)g.Bt + (size_t)nxt.pn * tstep : cB;
;         for (int t = 0; t < nt; t += 2) {
;             const bool last = (t == nt - 2);
;             const char* a1 = cA + (size_t)(t + 1) * kstep;
;             const char* a2 = last ? nA : cA + (size_t)(t + 2) * kstep; const char* b2 = last ? nB : cB + (size_t)(t + 2) * kstep;
;             const char* a3 = a2 + kstep; const char* b3 = b2 + kstep;
;             PG8_LDB(B0, 0, 0); PG8_SCHED; PG8_LDA(At, 0, 0); PG8_STAGE(PG8_SA(1, 1), a1 + hstep, voffA);
;             PG8_WAIT_L(8); PG8_BAR; PG8_WAIT_L(0); PG8_MMA(0, 0, At, B0); PG8_BAR; PG8_SCHED;
;             PG8_LDB(B1, 0, 1); PG8_STAGE(PG8_SB(0, 0), b2, voffB);
;             PG8_BAR; PG8_WAIT_L(0); PG8_MMA(0, 1, At, B1); PG8_BAR;
;             PG8_LDA(At, 0, 1); PG8_STAGE(PG8_SA(0, 0), a2, voffA);
;             PG8_BAR; PG8_WAIT_L(0); PG8_MMA(1, 0, At, B0); PG8_BAR; PG8_SCHED;
;             PG8_STAGE(PG8_SB(0, 1), b2 + hstep, voffB);
;             PG8_WAIT_V(6); PG8_BAR; PG8_MMA(1, 1, At, B1); PG8_BAR;
;             PG8_LDB(B0, 1, 0); PG8_SCHED; PG8_LDA(At, 1, 0); PG8_STAGE(PG8_SA(0, 1), a2 + hstep, voffA);
;             PG8_WAIT_L(8); PG8_BAR; PG8_WAIT_L(0); PG8_MMA(0, 0, At, B0); PG8_BAR; PG8_SCHED;
;             PG8_LDB(B1, 1, 1); PG8_STAGE(PG8_SB(1, 0), b3, voffB);
;             PG8_BAR; PG8_WAIT_L(0); PG8_MMA(0, 1, At, B1); PG8_BAR;
;             PG8_LDA(At, 1, 1); PG8_STAGE(PG8_SA(1, 0), a3, voffA);
;             PG8_BAR; PG8_WAIT_L(0); PG8_MMA(1, 0, At, B0); PG8_BAR; PG8_SCHED;
;             PG8_STAGE(PG8_SB(1, 1), b3 + hstep, voffB);
;             PG8_WAIT_V(6); PG8_BAR; PG8_MMA(1, 1, At, B1); PG8_BAR;
.LBB0_234:
	s_ashr_i32 s7, s6, 31
	v_cmp_lt_i64_e32 vcc, s[8:9], v[140:141]
	s_lshl_b64 s[8:9], s[6:7], 19
	s_add_u32 s8, s96, s8
	s_addc_u32 s9, s97, s9
	s_and_b64 s[10:11], vcc, exec
	s_cselect_b32 s7, s9, s15
	s_cselect_b32 s44, s8, s14
	s_ashr_i32 s5, s4, 31
	s_lshl_b64 s[10:11], s[4:5], 19
	s_add_u32 s10, s72, s10
	s_addc_u32 s11, s73, s11
	s_and_b64 s[16:17], vcc, exec
	s_cselect_b32 s5, s11, s19
	s_cselect_b32 s45, s10, s18
	s_add_u32 s14, s14, 0x40080
	s_addc_u32 s15, s15, 0
	s_add_u32 s46, s18, 0x100
	s_addc_u32 s47, s19, 0
	s_mov_b32 s48, -2
	ds_read_b128 v[150:153], v147
	ds_read_b128 v[154:157], v147 offset:1024
	ds_read_b128 v[158:161], v147 offset:2048
	ds_read_b128 v[162:165], v147 offset:3072
	s_add_u32 s16, s14, 0xfffc0080
	s_addc_u32 s17, s15, -1
	s_cmp_eq_u32 s48, 12
	s_cselect_b32 s23, s7, s17
	s_cselect_b32 s22, s44, s16
	s_cselect_b32 s19, s5, s47
	s_cselect_b32 s18, s45, s46
	s_add_i32 m0, s13, 0xc000
	ds_read_b128 v[166:169], v148
	ds_read_b128 v[170:173], v148 offset:1024
	ds_read_b128 v[174:177], v148 offset:2048
	ds_read_b128 v[178:181], v148 offset:3072
	ds_read_b128 v[182:185], v148 offset:4096
	ds_read_b128 v[186:189], v148 offset:5120
	ds_read_b128 v[190:193], v148 offset:6144
	ds_read_b128 v[194:197], v148 offset:7168
	global_load_lds_dwordx4 v136, s[14:15]
	s_add_i32 m0, s13, 0xe000
	s_nop 0
	global_load_lds_dwordx4 v138, s[14:15]
	s_waitcnt lgkmcnt(8)
	s_waitcnt vmcnt(8)
	s_setprio 1
	s_barrier
	s_waitcnt lgkmcnt(0)
	v_mfma_f32_16x16x32_bf16 v[124:127], v[150:153], v[166:169], 0
	v_mfma_f32_16x16x32_bf16 v[116:119], v[158:161], v[166:169], 0
	v_mfma_f32_16x16x32_bf16 v[108:111], v[150:153], v[174:177], 0
	v_mfma_f32_16x16x32_bf16 v[100:103], v[158:161], v[174:177], 0
	v_mfma_f32_16x16x32_bf16 v[92:95], v[150:153], v[182:185], 0
	v_mfma_f32_16x16x32_bf16 v[84:87], v[158:161], v[182:185], 0
	v_mfma_f32_16x16x32_bf16 v[76:79], v[150:153], v[190:193], 0
	v_mfma_f32_16x16x32_bf16 v[68:71], v[158:161], v[190:193], 0
	v_mfma_f32_16x16x32_bf16 v[124:127], v[154:157], v[170:173], v[124:127]
	v_mfma_f32_16x16x32_bf16 v[116:119], v[162:165], v[170:173], v[116:119]
	v_mfma_f32_16x16x32_bf16 v[108:111], v[154:157], v[178:181], v[108:111]
	v_mfma_f32_16x16x32_bf16 v[100:103], v[162:165], v[178:181], v[100:103]
	v_mfma_f32_16x16x32_bf16 v[92:95], v[154:157], v[186:189], v[92:95]
	v_mfma_f32_16x16x32_bf16 v[84:87], v[162:165], v[186:189], v[84:87]
	v_mfma_f32_16x16x32_bf16 v[76:79], v[154:157], v[194:197], v[76:79]
	v_mfma_f32_16x16x32_bf16 v[68:71], v[162:165], v[194:197], v[68:71]
	s_barrier
	s_setprio 0
	s_add_i32 s16, s40, s25
	s_mov_b32 m0, s16
	ds_read_b128 v[202:205], v149
	ds_read_b128 v[206:209], v149 offset:1024
	ds_read_b128 v[210:213], v149 offset:2048
	ds_read_b128 v[214:217], v149 offset:3072
	global_load_lds_dwordx4 v132, s[18:19]
	s_add_i32 m0, s16, 0x2000
	s_nop 0
	global_load_lds_dwordx4 v128, s[18:19]
	s_waitcnt vmcnt(8)
	s_setprio 1
	s_barrier
	s_waitcnt lgkmcnt(0)
	v_mfma_f32_16x16x32_bf16 v[120:123], v[202:205], v[166:169], 0
	v_mfma_f32_16x16x32_bf16 v[112:115], v[210:213], v[166:169], 0
	v_mfma_f32_16x16x32_bf16 v[104:107], v[202:205], v[174:177], 0
	v_mfma_f32_16x16x32_bf16 v[96:99], v[210:213], v[174:177], 0
	v_mfma_f32_16x16x32_bf16 v[88:91], v[202:205], v[182:185], 0
	v_mfma_f32_16x16x32_bf16 v[80:83], v[210:213], v[182:185], 0
	v_mfma_f32_16x16x32_bf16 v[72:75], v[202:205], v[190:193], 0
	v_mfma_f32_16x16x32_bf16 v[64:67], v[210:213], v[190:193], 0
	v_mfma_f32_16x16x32_bf16 v[120:123], v[206:209], v[170:173], v[120:123]
	v_mfma_f32_16x16x32_bf16 v[112:115], v[214:217], v[170:173], v[112:115]
	v_mfma_f32_16x16x32_bf16 v[104:107], v[206:209], v[178:181], v[104:107]
	v_mfma_f32_16x16x32_bf16 v[96:99], v[214:217], v[178:181], v[96:99]
	v_mfma_f32_16x16x32_bf16 v[88:91], v[206:209], v[186:189], v[88:91]
	v_mfma_f32_16x16x32_bf16 v[80:83], v[214:217], v[186:189], v[80:83]
	v_mfma_f32_16x16x32_bf16 v[72:75], v[206:209], v[194:197], v[72:75]
	v_mfma_f32_16x16x32_bf16 v[64:67], v[214:217], v[194:197], v[64:67]
	s_mov_b32 m0, s13
	s_barrier
	s_setprio 0
	ds_read_b128 v[166:169], v148 offset:16384
	ds_read_b128 v[170:173], v148 offset:17408
	ds_read_b128 v[174:177], v148 offset:18432
	ds_read_b128 v[178:181], v148 offset:19456
	ds_read_b128 v[182:185], v148 offset:20480
	ds_read_b128 v[186:189], v148 offset:21504
	ds_read_b128 v[190:193], v148 offset:22528
	ds_read_b128 v[194:197], v148 offset:23552
	global_load_lds_dwordx4 v134, s[22:23]
	s_mov_b32 m0, s28
	s_nop 0
	global_load_lds_dwordx4 v130, s[22:23]
	s_setprio 1
	s_barrier
	s_waitcnt lgkmcnt(0)
	v_mfma_f32_16x16x32_bf16 v[60:63], v[150:153], v[166:169], 0
	v_mfma_f32_16x16x32_bf16 v[56:59], v[158:161], v[166:169], 0
	v_mfma_f32_16x16x32_bf16 v[44:47], v[150:153], v[174:177], 0
	v_mfma_f32_16x16x32_bf16 v[40:43], v[158:161], v[174:177], 0
	v_mfma_f32_16x16x32_bf16 v[28:31], v[150:153], v[182:185], 0
	v_mfma_f32_16x16x32_bf16 v[24:27], v[158:161], v[182:185], 0
	v_mfma_f32_16x16x32_bf16 v[12:15], v[150:153], v[190:193], 0
	v_mfma_f32_16x16x32_bf16 v[8:11], v[158:161], v[190:193], 0
	v_mfma_f32_16x16x32_bf16 v[60:63], v[154:157], v[170:173], v[60:63]
	v_mfma_f32_16x16x32_bf16 v[56:59], v[162:165], v[170:173], v[56:59]
	v_mfma_f32_16x16x32_bf16 v[44:47], v[154:157], v[178:181], v[44:47]
	v_mfma_f32_16x16x32_bf16 v[40:43], v[162:165], v[178:181], v[40:43]
	v_mfma_f32_16x16x32_bf16 v[28:31], v[154:157], v[186:189], v[28:31]
	v_mfma_f32_16x16x32_bf16 v[24:27], v[162:165], v[186:189], v[24:27]
	v_mfma_f32_16x16x32_bf16 v[12:15], v[154:157], v[194:197], v[12:15]
	v_mfma_f32_16x16x32_bf16 v[8:11], v[162:165], v[194:197], v[8:11]
	s_barrier
; #define PG8_STAGE(bufoff, gbase, voff) do { _Pragma("unroll") for (int _i = 0; _i < 2; ++_i) \
;         __builtin_amdgcn_global_load_lds((const unsigned*)((const char*)(gbase) + (voff)[_i]), (LAS unsigned*)(lds + (bufoff) + ldsw + _i * 8192), 16, 0, 0); } while (0)
; #define PG8_LDA(dst, b, h) do { _Pragma("unroll") for (int m = 0; m < 4; ++m) _Pragma("unroll") for (int k = 0; k < 2; ++k) dst[m][k] = *(const LAS bf16x8*)(lds + PG8_SA(b, h) + aoff + m * 2048 + k * 1024); } while (0)
; #define PG8_LDB(dst, b, h) do { _Pragma("unroll") for (int n = 0; n < 2; ++n) _Pragma("unroll") for (int k = 0; k < 2; ++k) dst[n][k] = *(const LAS bf16x8*)(lds + PG8_SB(b, h) + boff + n * 2048 + k * 1024); } while (0)
; #define PG8_MMA(ai, bj, At, Bt) do { __builtin_amdgcn_s_setprio(1); _Pragma("unroll") for (int m = 0; m < 4; ++m) _Pragma("unroll") for (int n = 0; n < 2; ++n) _Pragma("unroll") for (int k = 0; k < 2; ++k) \
;         acc[ai][bj][m][n] = __builtin_amdgcn_mfma_f32_16x16x32_bf16(Bt[n][k], At[m][k], acc[ai][bj][m][n], 0, 0, 0); __builtin_amdgcn_s_setprio(0); } while (0)
; #define PG8_WAIT_V(n) asm volatile("s_waitcnt vmcnt(" #n ")" ::: "memory")
; #define PG8_WAIT_L(n) asm volatile("s_waitcnt lgkmcnt(" #n ")" ::: "memory")
; #define PG8_BAR __builtin_amdgcn_s_barrier()
; #define PG8_SCHED __builtin_amdgcn_sched_barrier(0)
; template <class Epi, class Sched>
; __device__ __forceinline__ void gemm_phase(LAS unsigned char* lds, const Gemm g, const Sched& S, const Epi& E) {
;     ...
;             PG8_BAR; PG8_WAIT_L(0); PG8_MMA(1, 0, At, B0); PG8_BAR; PG8_SCHED;
;             PG8_STAGE(PG8_SB(0, 1), b2 + hstep, voffB);
;             PG8_WAIT_V(6); PG8_BAR; PG8_MMA(1, 1, At, B1); PG8_BAR;
;             PG8_LDB(B0, 1, 0); PG8_SCHED; PG8_LDA(At, 1, 0); PG8_STAGE(PG8_SA(0, 1), a2 + hstep, voffA);
;             PG8_WAIT_L(8); PG8_BAR; PG8_WAIT_L(0); PG8_MMA(0, 0, At, B0); PG8_BAR; PG8_SCHED;
;             PG8_LDB(B1, 1, 1); PG8_STAGE(PG8_SB(1, 0), b3, voffB);
;             PG8_BAR; PG8_WAIT_L(0); PG8_MMA(0, 1, At, B1); PG8_BAR;
;             PG8_LDA(At, 1, 1); PG8_STAGE(PG8_SA(1, 0), a3, voffA);
	s_setprio 0
	s_add_u32 s16, s18, 0x40000
	s_addc_u32 s17, s19, 0
	s_add_i32 s20, s41, s25
	s_mov_b32 m0, s20
	s_nop 0
	global_load_lds_dwordx4 v132, s[16:17]
	s_add_i32 m0, s20, 0x2000
	s_nop 0
	global_load_lds_dwordx4 v128, s[16:17]
	s_add_u32 s16, s22, 0x40000
	s_addc_u32 s17, s23, 0
	s_mov_b32 m0, s29
	s_nop 0
	global_load_lds_dwordx4 v134, s[16:17]
	s_mov_b32 m0, s33
	s_nop 0
	global_load_lds_dwordx4 v130, s[16:17]
	s_waitcnt vmcnt(10)
	s_setprio 1
	s_barrier
	v_mfma_f32_16x16x32_bf16 v[52:55], v[202:205], v[166:169], 0
	v_mfma_f32_16x16x32_bf16 v[48:51], v[210:213], v[166:169], 0
	v_mfma_f32_16x16x32_bf16 v[36:39], v[202:205], v[174:177], 0
	v_mfma_f32_16x16x32_bf16 v[32:35], v[210:213], v[174:177], 0
	v_mfma_f32_16x16x32_bf16 v[20:23], v[202:205], v[182:185], 0
	v_mfma_f32_16x16x32_bf16 v[16:19], v[210:213], v[182:185], 0
	v_mfma_f32_16x16x32_bf16 v[4:7], v[202:205], v[190:193], 0
	v_mfma_f32_16x16x32_bf16 v[0:3], v[210:213], v[190:193], 0
	v_mfma_f32_16x16x32_bf16 v[52:55], v[206:209], v[170:173], v[52:55]
	v_mfma_f32_16x16x32_bf16 v[48:51], v[214:217], v[170:173], v[48:51]
	v_mfma_f32_16x16x32_bf16 v[36:39], v[206:209], v[178:181], v[36:39]
	v_mfma_f32_16x16x32_bf16 v[32:35], v[214:217], v[178:181], v[32:35]
	v_mfma_f32_16x16x32_bf16 v[20:23], v[206:209], v[186:189], v[20:23]
	v_mfma_f32_16x16x32_bf16 v[16:19], v[214:217], v[186:189], v[16:19]
	v_mfma_f32_16x16x32_bf16 v[4:7], v[206:209], v[194:197], v[4:7]
	v_mfma_f32_16x16x32_bf16 v[0:3], v[214:217], v[194:197], v[0:3]
	s_add_i32 s20, 0, 0x18000
	v_add_u32_e32 v162, s20, v146
	s_barrier
	s_setprio 0
	ds_read_b128 v[150:153], v162
	ds_read_b128 v[154:157], v162 offset:1024
	ds_read_b128 v[158:161], v162 offset:2048
	ds_read_b128 v[162:165], v162 offset:3072
	ds_read_b128 v[166:169], v148 offset:32768
	ds_read_b128 v[170:173], v148 offset:33792
	ds_read_b128 v[174:177], v148 offset:34816
	ds_read_b128 v[178:181], v148 offset:35840
	ds_read_b128 v[182:185], v148 offset:36864
	ds_read_b128 v[186:189], v148 offset:37888
	ds_read_b128 v[190:193], v148 offset:38912
	ds_read_b128 v[194:197], v148 offset:39936
	s_waitcnt lgkmcnt(8)
	s_waitcnt vmcnt(8)
	s_setprio 1
	s_barrier
	s_waitcnt lgkmcnt(0)
	v_mfma_f32_16x16x32_bf16 v[124:127], v[150:153], v[166:169], v[124:127]
	v_mfma_f32_16x16x32_bf16 v[116:119], v[158:161], v[166:169], v[116:119]
	v_mfma_f32_16x16x32_bf16 v[108:111], v[150:153], v[174:177], v[108:111]
	v_mfma_f32_16x16x32_bf16 v[100:103], v[158:161], v[174:177], v[100:103]
	v_mfma_f32_16x16x32_bf16 v[92:95], v[150:153], v[182:185], v[92:95]
	v_mfma_f32_16x16x32_bf16 v[84:87], v[158:161], v[182:185], v[84:87]
	v_mfma_f32_16x16x32_bf16 v[76:79], v[150:153], v[190:193], v[76:79]
	v_mfma_f32_16x16x32_bf16 v[68:71], v[158:161], v[190:193], v[68:71]
	v_mfma_f32_16x16x32_bf16 v[124:127], v[154:157], v[170:173], v[124:127]
	v_mfma_f32_16x16x32_bf16 v[116:119], v[162:165], v[170:173], v[116:119]
	v_mfma_f32_16x16x32_bf16 v[108:111], v[154:157], v[178:181], v[108:111]
	v_mfma_f32_16x16x32_bf16 v[100:103], v[162:165], v[178:181], v[100:103]
	v_mfma_f32_16x16x32_bf16 v[92:95], v[154:157], v[186:189], v[92:95]
	v_mfma_f32_16x16x32_bf16 v[84:87], v[162:165], v[186:189], v[84:87]
	v_mfma_f32_16x16x32_bf16 v[76:79], v[154:157], v[194:197], v[76:79]
	v_mfma_f32_16x16x32_bf16 v[68:71], v[162:165], v[194:197], v[68:71]
	s_barrier
	s_setprio 0
	s_add_i32 s21, 0, 0x1c000
	s_add_i32 s16, s20, s25
	v_add_u32_e32 v214, s21, v146
	s_add_u32 s0, s18, 0x80
	s_addc_u32 s1, s19, 0
	s_mov_b32 m0, s16
	ds_read_b128 v[202:205], v214
	ds_read_b128 v[206:209], v214 offset:1024
	ds_read_b128 v[210:213], v214 offset:2048
	ds_read_b128 v[214:217], v214 offset:3072
	global_load_lds_dwordx4 v132, s[0:1]
	s_add_i32 m0, s16, 0x2000
	s_nop 0
	global_load_lds_dwordx4 v128, s[0:1]
	s_waitcnt vmcnt(8)
	s_setprio 1
	s_barrier
	s_waitcnt lgkmcnt(0)
	v_mfma_f32_16x16x32_bf16 v[120:123], v[202:205], v[166:169], v[120:123]
	v_mfma_f32_16x16x32_bf16 v[112:115], v[210:213], v[166:169], v[112:115]
	v_mfma_f32_16x16x32_bf16 v[104:107], v[202:205], v[174:177], v[104:107]
	v_mfma_f32_16x16x32_bf16 v[96:99], v[210:213], v[174:177], v[96:99]
	v_mfma_f32_16x16x32_bf16 v[88:91], v[202:205], v[182:185], v[88:91]
	v_mfma_f32_16x16x32_bf16 v[80:83], v[210:213], v[182:185], v[80:83]
	v_mfma_f32_16x16x32_bf16 v[72:75], v[202:205], v[190:193], v[72:75]
	v_mfma_f32_16x16x32_bf16 v[64:67], v[210:213], v[190:193], v[64:67]
	v_mfma_f32_16x16x32_bf16 v[120:123], v[206:209], v[170:173], v[120:123]
	v_mfma_f32_16x16x32_bf16 v[112:115], v[214:217], v[170:173], v[112:115]
	v_mfma_f32_16x16x32_bf16 v[104:107], v[206:209], v[178:181], v[104:107]
	v_mfma_f32_16x16x32_bf16 v[96:99], v[214:217], v[178:181], v[96:99]
	v_mfma_f32_16x16x32_bf16 v[88:91], v[206:209], v[186:189], v[88:91]
	v_mfma_f32_16x16x32_bf16 v[80:83], v[214:217], v[186:189], v[80:83]
	v_mfma_f32_16x16x32_bf16 v[72:75], v[206:209], v[194:197], v[72:75]
	v_mfma_f32_16x16x32_bf16 v[64:67], v[214:217], v[194:197], v[64:67]
	s_mov_b32 m0, s36
	s_add_u32 s0, s22, 0x80
	s_addc_u32 s1, s23, 0
	s_barrier
	s_setprio 0
	ds_read_b128 v[166:169], v148 offset:49152
	ds_read_b128 v[170:173], v148 offset:50176
	ds_read_b128 v[174:177], v148 offset:51200
	ds_read_b128 v[178:181], v148 offset:52224
	ds_read_b128 v[182:185], v148 offset:53248
	ds_read_b128 v[186:189], v148 offset:54272
	ds_read_b128 v[190:193], v148 offset:55296
	ds_read_b128 v[194:197], v148 offset:56320
	global_load_lds_dwordx4 v134, s[0:1]
	s_mov_b32 m0, s37
	s_nop 0
	global_load_lds_dwordx4 v130, s[0:1]
	s_setprio 1
	s_barrier
; #define PG8_STAGE(bufoff, gbase, voff) do { _Pragma("unroll") for (int _i = 0; _i < 2; ++_i) \
;         __builtin_amdgcn_global_load_lds((const unsigned*)((const char*)(gbase) + (voff)[_i]), (LAS unsigned*)(lds + (bufoff) + ldsw + _i * 8192), 16, 0, 0); } while (0)
; #define PG8_LDA(dst, b, h) do { _Pragma("unroll") for (int m = 0; m < 4; ++m) _Pragma("unroll") for (int k = 0; k < 2; ++k) dst[m][k] = *(const LAS bf16x8*)(lds + PG8_SA(b, h) + aoff + m * 2048 + k * 1024); } while (0)
; #define PG8_LDB(dst, b, h) do { _Pragma("unroll") for (int n = 0; n < 2; ++n) _Pragma("unroll") for (int k = 0; k < 2; ++k) dst[n][k] = *(const LAS bf16x8*)(lds + PG8_SB(b, h) + boff + n * 2048 + k * 1024); } while (0)
; #define PG8_MMA(ai, bj, At, Bt) do { __builtin_amdgcn_s_setprio(1); _Pragma("unroll") for (int m = 0; m < 4; ++m) _Pragma("unroll") for (int n = 0; n < 2; ++n) _Pragma("unroll") for (int k = 0; k < 2; ++k) \
;         acc[ai][bj][m][n] = __builtin_amdgcn_mfma_f32_16x16x32_bf16(Bt[n][k], At[m][k], acc[ai][bj][m][n], 0, 0, 0); __builtin_amdgcn_s_setprio(0); } while (0)
; #define PG8_WAIT_V(n) asm volatile("s_waitcnt vmcnt(" #n ")" ::: "memory")
; #define PG8_WAIT_L(n) asm volatile("s_waitcnt lgkmcnt(" #n ")" ::: "memory")
; #define PG8_BAR __builtin_amdgcn_s_barrier()
; #define PG8_SCHED __builtin_amdgcn_sched_barrier(0)
; template <class Epi, class Sched>
; __device__ __forceinline__ void gemm_phase(LAS unsigned char* lds, const Gemm g, const Sched& S, const Epi& E) {
;     ...
;             PG8_LDB(B0, 0, 0); PG8_SCHED; PG8_LDA(At, 0, 0); PG8_STAGE(PG8_SA(1, 1), a1 + hstep, voffA);
;             PG8_WAIT_L(8); PG8_BAR; PG8_WAIT_L(0); PG8_MMA(0, 0, At, B0); PG8_BAR; PG8_SCHED;
;             PG8_LDB(B1, 0, 1); PG8_STAGE(PG8_SB(0, 0), b2, voffB);
;             PG8_BAR; PG8_WAIT_L(0); PG8_MMA(0, 1, At, B1); PG8_BAR;
;             PG8_LDA(At, 0, 1); PG8_STAGE(PG8_SA(0, 0), a2, voffA);
;             PG8_BAR; PG8_WAIT_L(0); PG8_MMA(1, 0, At, B0); PG8_BAR; PG8_SCHED;
;             PG8_STAGE(PG8_SB(0, 1), b2 + hstep, voffB);
;             PG8_WAIT_V(6); PG8_BAR; PG8_MMA(1, 1, At, B1); PG8_BAR;
;     ...
;             PG8_STAGE(PG8_SB(1, 1), b3 + hstep, voffB);
;             PG8_WAIT_V(6); PG8_BAR; PG8_MMA(1, 1, At, B1); PG8_BAR;
	s_waitcnt lgkmcnt(0)
	v_mfma_f32_16x16x32_bf16 v[60:63], v[150:153], v[166:169], v[60:63]
	v_mfma_f32_16x16x32_bf16 v[56:59], v[158:161], v[166:169], v[56:59]
	v_mfma_f32_16x16x32_bf16 v[44:47], v[150:153], v[174:177], v[44:47]
	v_mfma_f32_16x16x32_bf16 v[40:43], v[158:161], v[174:177], v[40:43]
	v_mfma_f32_16x16x32_bf16 v[28:31], v[150:153], v[182:185], v[28:31]
	v_mfma_f32_16x16x32_bf16 v[24:27], v[158:161], v[182:185], v[24:27]
	v_mfma_f32_16x16x32_bf16 v[12:15], v[150:153], v[190:193], v[12:15]
	v_mfma_f32_16x16x32_bf16 v[8:11], v[158:161], v[190:193], v[8:11]
	v_mfma_f32_16x16x32_bf16 v[60:63], v[154:157], v[170:173], v[60:63]
	v_mfma_f32_16x16x32_bf16 v[56:59], v[162:165], v[170:173], v[56:59]
	v_mfma_f32_16x16x32_bf16 v[44:47], v[154:157], v[178:181], v[44:47]
	v_mfma_f32_16x16x32_bf16 v[40:43], v[162:165], v[178:181], v[40:43]
	v_mfma_f32_16x16x32_bf16 v[28:31], v[154:157], v[186:189], v[28:31]
	v_mfma_f32_16x16x32_bf16 v[24:27], v[162:165], v[186:189], v[24:27]
	v_mfma_f32_16x16x32_bf16 v[12:15], v[154:157], v[194:197], v[12:15]
	v_mfma_f32_16x16x32_bf16 v[8:11], v[162:165], v[194:197], v[8:11]
	s_barrier
	s_setprio 0
	s_add_u32 s16, s18, 0x40080
	s_addc_u32 s17, s19, 0
	s_add_i32 s18, s21, s25
	s_mov_b32 m0, s18
	s_nop 0
	global_load_lds_dwordx4 v132, s[16:17]
	s_add_i32 m0, s18, 0x2000
	s_nop 0
	global_load_lds_dwordx4 v128, s[16:17]
	s_waitcnt vmcnt(8)
	s_setprio 1
	s_barrier
	v_mfma_f32_16x16x32_bf16 v[52:55], v[202:205], v[166:169], v[52:55]
	v_mfma_f32_16x16x32_bf16 v[48:51], v[210:213], v[166:169], v[48:51]
	v_mfma_f32_16x16x32_bf16 v[36:39], v[202:205], v[174:177], v[36:39]
	v_mfma_f32_16x16x32_bf16 v[32:35], v[210:213], v[174:177], v[32:35]
	v_mfma_f32_16x16x32_bf16 v[20:23], v[202:205], v[182:185], v[20:23]
	v_mfma_f32_16x16x32_bf16 v[16:19], v[210:213], v[182:185], v[16:19]
	v_mfma_f32_16x16x32_bf16 v[4:7], v[202:205], v[190:193], v[4:7]
	v_mfma_f32_16x16x32_bf16 v[0:3], v[210:213], v[190:193], v[0:3]
	v_mfma_f32_16x16x32_bf16 v[52:55], v[206:209], v[170:173], v[52:55]
	v_mfma_f32_16x16x32_bf16 v[48:51], v[214:217], v[170:173], v[48:51]
	v_mfma_f32_16x16x32_bf16 v[36:39], v[206:209], v[178:181], v[36:39]
	v_mfma_f32_16x16x32_bf16 v[32:35], v[214:217], v[178:181], v[32:35]
	v_mfma_f32_16x16x32_bf16 v[20:23], v[206:209], v[186:189], v[20:23]
	v_mfma_f32_16x16x32_bf16 v[16:19], v[214:217], v[186:189], v[16:19]
	v_mfma_f32_16x16x32_bf16 v[4:7], v[206:209], v[194:197], v[4:7]
	v_mfma_f32_16x16x32_bf16 v[0:3], v[214:217], v[194:197], v[0:3]
	s_add_i32 s48, s48, 2
	s_add_u32 s14, s14, 0x100
	s_addc_u32 s15, s15, 0
	s_add_u32 s46, s46, 0x100
	s_addc_u32 s47, s47, 0
	s_cmp_gt_u32 s48, 13
	s_barrier
	s_setprio 0
.LBB0_235:
	ds_read_b128 v[150:153], v147
	ds_read_b128 v[154:157], v147 offset:1024
	ds_read_b128 v[158:161], v147 offset:2048
	ds_read_b128 v[162:165], v147 offset:3072
	s_add_u32 s16, s14, 0xfffc0080
	s_addc_u32 s17, s15, -1
	s_cmp_eq_u32 s48, 12
	s_cselect_b32 s23, s7, s17
	s_cselect_b32 s22, s44, s16
	s_cselect_b32 s19, s5, s47
	s_cselect_b32 s18, s45, s46
	s_add_i32 m0, s13, 0xc000
	ds_read_b128 v[166:169], v148
	ds_read_b128 v[170:173], v148 offset:1024
	ds_read_b128 v[174:177], v148 offset:2048
	ds_read_b128 v[178:181], v148 offset:3072
	ds_read_b128 v[182:185], v148 offset:4096
	ds_read_b128 v[186:189], v148 offset:5120
	ds_read_b128 v[190:193], v148 offset:6144
	ds_read_b128 v[194:197], v148 offset:7168
	global_load_lds_dwordx4 v136, s[14:15]
	s_add_i32 m0, s13, 0xe000
	s_nop 0
	global_load_lds_dwordx4 v138, s[14:15]
	s_waitcnt lgkmcnt(8)
	s_waitcnt vmcnt(8)
	s_setprio 1
	s_barrier
	s_waitcnt lgkmcnt(0)
	v_mfma_f32_16x16x32_bf16 v[124:127], v[150:153], v[166:169], v[124:127]
	v_mfma_f32_16x16x32_bf16 v[116:119], v[158:161], v[166:169], v[116:119]
	v_mfma_f32_16x16x32_bf16 v[108:111], v[150:153], v[174:177], v[108:111]
	v_mfma_f32_16x16x32_bf16 v[100:103], v[158:161], v[174:177], v[100:103]
	v_mfma_f32_16x16x32_bf16 v[92:95], v[150:153], v[182:185], v[92:95]
	v_mfma_f32_16x16x32_bf16 v[84:87], v[158:161], v[182:185], v[84:87]
	v_mfma_f32_16x16x32_bf16 v[76:79], v[150:153], v[190:193], v[76:79]
	v_mfma_f32_16x16x32_bf16 v[68:71], v[158:161], v[190:193], v[68:71]
	v_mfma_f32_16x16x32_bf16 v[124:127], v[154:157], v[170:173], v[124:127]
	v_mfma_f32_16x16x32_bf16 v[116:119], v[162:165], v[170:173], v[116:119]
	v_mfma_f32_16x16x32_bf16 v[108:111], v[154:157], v[178:181], v[108:111]
	v_mfma_f32_16x16x32_bf16 v[100:103], v[162:165], v[178:181], v[100:103]
	v_mfma_f32_16x16x32_bf16 v[92:95], v[154:157], v[186:189], v[92:95]
	v_mfma_f32_16x16x32_bf16 v[84:87], v[162:165], v[186:189], v[84:87]
	v_mfma_f32_16x16x32_bf16 v[76:79], v[154:157], v[194:197], v[76:79]
	v_mfma_f32_16x16x32_bf16 v[68:71], v[162:165], v[194:197], v[68:71]
	s_barrier
	s_setprio 0
	s_add_i32 s16, s40, s25
	s_mov_b32 m0, s16
	ds_read_b128 v[202:205], v149
	ds_read_b128 v[206:209], v149 offset:1024
	ds_read_b128 v[210:213], v149 offset:2048
	ds_read_b128 v[214:217], v149 offset:3072
	global_load_lds_dwordx4 v132, s[18:19]
	s_add_i32 m0, s16, 0x2000
	s_nop 0
	global_load_lds_dwordx4 v128, s[18:19]
	s_waitcnt vmcnt(8)
	s_setprio 1
	s_barrier
; #define PG8_STAGE(bufoff, gbase, voff) do { _Pragma("unroll") for (int _i = 0; _i < 2; ++_i) \
;         __builtin_amdgcn_global_load_lds((const unsigned*)((const char*)(gbase) + (voff)[_i]), (LAS unsigned*)(lds + (bufoff) + ldsw + _i * 8192), 16, 0, 0); } while (0)
; #define PG8_LDA(dst, b, h) do { _Pragma("unroll") for (int m = 0; m < 4; ++m) _Pragma("unroll") for (int k = 0; k < 2; ++k) dst[m][k] = *(const LAS bf16x8*)(lds + PG8_SA(b, h) + aoff + m * 2048 + k * 1024); } while (0)
; #define PG8_LDB(dst, b, h) do { _Pragma("unroll") for (int n = 0; n < 2; ++n) _Pragma("unroll") for (int k = 0; k < 2; ++k) dst[n][k] = *(const LAS bf16x8*)(lds + PG8_SB(b, h) + boff + n * 2048 + k * 1024); } while (0)
; #define PG8_MMA(ai, bj, At, Bt) do { __builtin_amdgcn_s_setprio(1); _Pragma("unroll") for (int m = 0; m < 4; ++m) _Pragma("unroll") for (int n = 0; n < 2; ++n) _Pragma("unroll") for (int k = 0; k < 2; ++k) \
;         acc[ai][bj][m][n] = __builtin_amdgcn_mfma_f32_16x16x32_bf16(Bt[n][k], At[m][k], acc[ai][bj][m][n], 0, 0, 0); __builtin_amdgcn_s_setprio(0); } while (0)
; #define PG8_WAIT_V(n) asm volatile("s_waitcnt vmcnt(" #n ")" ::: "memory")
; #define PG8_WAIT_L(n) asm volatile("s_waitcnt lgkmcnt(" #n ")" ::: "memory")
; #define PG8_BAR __builtin_amdgcn_s_barrier()
; #define PG8_SCHED __builtin_amdgcn_sched_barrier(0)
; template <class Epi, class Sched>
; __device__ __forceinline__ void gemm_phase(LAS unsigned char* lds, const Gemm g, const Sched& S, const Epi& E) {
;     ...
;             PG8_WAIT_L(8); PG8_BAR; PG8_WAIT_L(0); PG8_MMA(0, 0, At, B0); PG8_BAR; PG8_SCHED;
;             PG8_LDB(B1, 0, 1); PG8_STAGE(PG8_SB(0, 0), b2, voffB);
;             PG8_BAR; PG8_WAIT_L(0); PG8_MMA(0, 1, At, B1); PG8_BAR;
;             PG8_LDA(At, 0, 1); PG8_STAGE(PG8_SA(0, 0), a2, voffA);
;             PG8_BAR; PG8_WAIT_L(0); PG8_MMA(1, 0, At, B0); PG8_BAR; PG8_SCHED;
;             PG8_STAGE(PG8_SB(0, 1), b2 + hstep, voffB);
;             PG8_WAIT_V(6); PG8_BAR; PG8_MMA(1, 1, At, B1); PG8_BAR;
;             PG8_LDB(B0, 1, 0); PG8_SCHED; PG8_LDA(At, 1, 0); PG8_STAGE(PG8_SA(0, 1), a2 + hstep, voffA);
;             PG8_WAIT_L(8); PG8_BAR; PG8_WAIT_L(0); PG8_MMA(0, 0, At, B0); PG8_BAR; PG8_SCHED;
	s_waitcnt lgkmcnt(0)
	v_mfma_f32_16x16x32_bf16 v[120:123], v[202:205], v[166:169], v[120:123]
	v_mfma_f32_16x16x32_bf16 v[112:115], v[210:213], v[166:169], v[112:115]
	v_mfma_f32_16x16x32_bf16 v[104:107], v[202:205], v[174:177], v[104:107]
	v_mfma_f32_16x16x32_bf16 v[96:99], v[210:213], v[174:177], v[96:99]
	v_mfma_f32_16x16x32_bf16 v[88:91], v[202:205], v[182:185], v[88:91]
	v_mfma_f32_16x16x32_bf16 v[80:83], v[210:213], v[182:185], v[80:83]
	v_mfma_f32_16x16x32_bf16 v[72:75], v[202:205], v[190:193], v[72:75]
	v_mfma_f32_16x16x32_bf16 v[64:67], v[210:213], v[190:193], v[64:67]
	v_mfma_f32_16x16x32_bf16 v[120:123], v[206:209], v[170:173], v[120:123]
	v_mfma_f32_16x16x32_bf16 v[112:115], v[214:217], v[170:173], v[112:115]
	v_mfma_f32_16x16x32_bf16 v[104:107], v[206:209], v[178:181], v[104:107]
	v_mfma_f32_16x16x32_bf16 v[96:99], v[214:217], v[178:181], v[96:99]
	v_mfma_f32_16x16x32_bf16 v[88:91], v[206:209], v[186:189], v[88:91]
	v_mfma_f32_16x16x32_bf16 v[80:83], v[214:217], v[186:189], v[80:83]
	v_mfma_f32_16x16x32_bf16 v[72:75], v[206:209], v[194:197], v[72:75]
	v_mfma_f32_16x16x32_bf16 v[64:67], v[214:217], v[194:197], v[64:67]
	s_mov_b32 m0, s13
	s_barrier
	s_setprio 0
	ds_read_b128 v[166:169], v148 offset:16384
	ds_read_b128 v[170:173], v148 offset:17408
	ds_read_b128 v[174:177], v148 offset:18432
	ds_read_b128 v[178:181], v148 offset:19456
	ds_read_b128 v[182:185], v148 offset:20480
	ds_read_b128 v[186:189], v148 offset:21504
	ds_read_b128 v[190:193], v148 offset:22528
	ds_read_b128 v[194:197], v148 offset:23552
	global_load_lds_dwordx4 v134, s[22:23]
	s_mov_b32 m0, s28
	s_nop 0
	global_load_lds_dwordx4 v130, s[22:23]
	s_setprio 1
	s_barrier
	s_waitcnt lgkmcnt(0)
	v_mfma_f32_16x16x32_bf16 v[60:63], v[150:153], v[166:169], v[60:63]
	v_mfma_f32_16x16x32_bf16 v[56:59], v[158:161], v[166:169], v[56:59]
	v_mfma_f32_16x16x32_bf16 v[44:47], v[150:153], v[174:177], v[44:47]
	v_mfma_f32_16x16x32_bf16 v[40:43], v[158:161], v[174:177], v[40:43]
	v_mfma_f32_16x16x32_bf16 v[28:31], v[150:153], v[182:185], v[28:31]
	v_mfma_f32_16x16x32_bf16 v[24:27], v[158:161], v[182:185], v[24:27]
	v_mfma_f32_16x16x32_bf16 v[12:15], v[150:153], v[190:193], v[12:15]
	v_mfma_f32_16x16x32_bf16 v[8:11], v[158:161], v[190:193], v[8:11]
	v_mfma_f32_16x16x32_bf16 v[60:63], v[154:157], v[170:173], v[60:63]
	v_mfma_f32_16x16x32_bf16 v[56:59], v[162:165], v[170:173], v[56:59]
	v_mfma_f32_16x16x32_bf16 v[44:47], v[154:157], v[178:181], v[44:47]
	v_mfma_f32_16x16x32_bf16 v[40:43], v[162:165], v[178:181], v[40:43]
	v_mfma_f32_16x16x32_bf16 v[28:31], v[154:157], v[186:189], v[28:31]
	v_mfma_f32_16x16x32_bf16 v[24:27], v[162:165], v[186:189], v[24:27]
	v_mfma_f32_16x16x32_bf16 v[12:15], v[154:157], v[194:197], v[12:15]
	v_mfma_f32_16x16x32_bf16 v[8:11], v[162:165], v[194:197], v[8:11]
	s_barrier
	s_setprio 0
	s_add_u32 s16, s18, 0x40000
	s_addc_u32 s17, s19, 0
	s_add_i32 s20, s41, s25
	s_mov_b32 m0, s20
	s_nop 0
	global_load_lds_dwordx4 v132, s[16:17]
	s_add_i32 m0, s20, 0x2000
	s_nop 0
	global_load_lds_dwordx4 v128, s[16:17]
	s_add_u32 s16, s22, 0x40000
	s_addc_u32 s17, s23, 0
	s_mov_b32 m0, s29
	s_nop 0
	global_load_lds_dwordx4 v134, s[16:17]
	s_mov_b32 m0, s33
	s_nop 0
	global_load_lds_dwordx4 v130, s[16:17]
	s_waitcnt vmcnt(10)
	s_setprio 1
	s_barrier
	v_mfma_f32_16x16x32_bf16 v[52:55], v[202:205], v[166:169], v[52:55]
	v_mfma_f32_16x16x32_bf16 v[48:51], v[210:213], v[166:169], v[48:51]
	v_mfma_f32_16x16x32_bf16 v[36:39], v[202:205], v[174:177], v[36:39]
	v_mfma_f32_16x16x32_bf16 v[32:35], v[210:213], v[174:177], v[32:35]
	v_mfma_f32_16x16x32_bf16 v[20:23], v[202:205], v[182:185], v[20:23]
	v_mfma_f32_16x16x32_bf16 v[16:19], v[210:213], v[182:185], v[16:19]
	v_mfma_f32_16x16x32_bf16 v[4:7], v[202:205], v[190:193], v[4:7]
	v_mfma_f32_16x16x32_bf16 v[0:3], v[210:213], v[190:193], v[0:3]
	v_mfma_f32_16x16x32_bf16 v[52:55], v[206:209], v[170:173], v[52:55]
	v_mfma_f32_16x16x32_bf16 v[48:51], v[214:217], v[170:173], v[48:51]
	v_mfma_f32_16x16x32_bf16 v[36:39], v[206:209], v[178:181], v[36:39]
	v_mfma_f32_16x16x32_bf16 v[32:35], v[214:217], v[178:181], v[32:35]
	v_mfma_f32_16x16x32_bf16 v[20:23], v[206:209], v[186:189], v[20:23]
	v_mfma_f32_16x16x32_bf16 v[16:19], v[214:217], v[186:189], v[16:19]
	v_mfma_f32_16x16x32_bf16 v[4:7], v[206:209], v[194:197], v[4:7]
	v_mfma_f32_16x16x32_bf16 v[0:3], v[214:217], v[194:197], v[0:3]
	s_add_i32 s20, 0, 0x18000
	v_add_u32_e32 v162, s20, v146
	s_barrier
	s_setprio 0
	ds_read_b128 v[150:153], v162
	ds_read_b128 v[154:157], v162 offset:1024
	ds_read_b128 v[158:161], v162 offset:2048
	ds_read_b128 v[162:165], v162 offset:3072
	ds_read_b128 v[166:169], v148 offset:32768
	ds_read_b128 v[170:173], v148 offset:33792
	ds_read_b128 v[174:177], v148 offset:34816
	ds_read_b128 v[178:181], v148 offset:35840
	ds_read_b128 v[182:185], v148 offset:36864
	ds_read_b128 v[186:189], v148 offset:37888
	ds_read_b128 v[190:193], v148 offset:38912
	ds_read_b128 v[194:197], v148 offset:39936
	s_waitcnt lgkmcnt(8)
	s_waitcnt vmcnt(8)
	s_setprio 1
	s_barrier
; #define PG8_STAGE(bufoff, gbase, voff) do { _Pragma("unroll") for (int _i = 0; _i < 2; ++_i) \
;         __builtin_amdgcn_global_load_lds((const unsigned*)((const char*)(gbase) + (voff)[_i]), (LAS unsigned*)(lds + (bufoff) + ldsw + _i * 8192), 16, 0, 0); } while (0)
; #define PG8_LDA(dst, b, h) do { _Pragma("unroll") for (int m = 0; m < 4; ++m) _Pragma("unroll") for (int k = 0; k < 2; ++k) dst[m][k] = *(const LAS bf16x8*)(lds + PG8_SA(b, h) + aoff + m * 2048 + k * 1024); } while (0)
; #define PG8_LDB(dst, b, h) do { _Pragma("unroll") for (int n = 0; n < 2; ++n) _Pragma("unroll") for (int k = 0; k < 2; ++k) dst[n][k] = *(const LAS bf16x8*)(lds + PG8_SB(b, h) + boff + n * 2048 + k * 1024); } while (0)
; #define PG8_MMA(ai, bj, At, Bt) do { __builtin_amdgcn_s_setprio(1); _Pragma("unroll") for (int m = 0; m < 4; ++m) _Pragma("unroll") for (int n = 0; n < 2; ++n) _Pragma("unroll") for (int k = 0; k < 2; ++k) \
;         acc[ai][bj][m][n] = __builtin_amdgcn_mfma_f32_16x16x32_bf16(Bt[n][k], At[m][k], acc[ai][bj][m][n], 0, 0, 0); __builtin_amdgcn_s_setprio(0); } while (0)
; #define PG8_WAIT_V(n) asm volatile("s_waitcnt vmcnt(" #n ")" ::: "memory")
; #define PG8_WAIT_L(n) asm volatile("s_waitcnt lgkmcnt(" #n ")" ::: "memory")
; #define PG8_BAR __builtin_amdgcn_s_barrier()
; #define PG8_SCHED __builtin_amdgcn_sched_barrier(0)
; template <class Epi, class Sched>
; __device__ __forceinline__ void gemm_phase(LAS unsigned char* lds, const Gemm g, const Sched& S, const Epi& E) {
;     ...
;             PG8_LDB(B0, 1, 0); PG8_SCHED; PG8_LDA(At, 1, 0); PG8_STAGE(PG8_SA(0, 1), a2 + hstep, voffA);
;             PG8_WAIT_L(8); PG8_BAR; PG8_WAIT_L(0); PG8_MMA(0, 0, At, B0); PG8_BAR; PG8_SCHED;
;             PG8_LDB(B1, 1, 1); PG8_STAGE(PG8_SB(1, 0), b3, voffB);
;             PG8_BAR; PG8_WAIT_L(0); PG8_MMA(0, 1, At, B1); PG8_BAR;
;             PG8_LDA(At, 1, 1); PG8_STAGE(PG8_SA(1, 0), a3, voffA);
;             PG8_BAR; PG8_WAIT_L(0); PG8_MMA(1, 0, At, B0); PG8_BAR; PG8_SCHED;
;             PG8_STAGE(PG8_SB(1, 1), b3 + hstep, voffB);
;             PG8_WAIT_V(6); PG8_BAR; PG8_MMA(1, 1, At, B1); PG8_BAR;
	s_waitcnt lgkmcnt(0)
	v_mfma_f32_16x16x32_bf16 v[124:127], v[150:153], v[166:169], v[124:127]
	v_mfma_f32_16x16x32_bf16 v[116:119], v[158:161], v[166:169], v[116:119]
	v_mfma_f32_16x16x32_bf16 v[108:111], v[150:153], v[174:177], v[108:111]
	v_mfma_f32_16x16x32_bf16 v[100:103], v[158:161], v[174:177], v[100:103]
	v_mfma_f32_16x16x32_bf16 v[92:95], v[150:153], v[182:185], v[92:95]
	v_mfma_f32_16x16x32_bf16 v[84:87], v[158:161], v[182:185], v[84:87]
	v_mfma_f32_16x16x32_bf16 v[76:79], v[150:153], v[190:193], v[76:79]
	v_mfma_f32_16x16x32_bf16 v[68:71], v[158:161], v[190:193], v[68:71]
	v_mfma_f32_16x16x32_bf16 v[124:127], v[154:157], v[170:173], v[124:127]
	v_mfma_f32_16x16x32_bf16 v[116:119], v[162:165], v[170:173], v[116:119]
	v_mfma_f32_16x16x32_bf16 v[108:111], v[154:157], v[178:181], v[108:111]
	v_mfma_f32_16x16x32_bf16 v[100:103], v[162:165], v[178:181], v[100:103]
	v_mfma_f32_16x16x32_bf16 v[92:95], v[154:157], v[186:189], v[92:95]
	v_mfma_f32_16x16x32_bf16 v[84:87], v[162:165], v[186:189], v[84:87]
	v_mfma_f32_16x16x32_bf16 v[76:79], v[154:157], v[194:197], v[76:79]
	v_mfma_f32_16x16x32_bf16 v[68:71], v[162:165], v[194:197], v[68:71]
	s_barrier
	s_setprio 0
	s_add_i32 s21, 0, 0x1c000
	s_add_i32 s16, s20, s25
	v_add_u32_e32 v214, s21, v146
	s_add_u32 s0, s18, 0x80
	s_addc_u32 s1, s19, 0
	s_mov_b32 m0, s16
	ds_read_b128 v[202:205], v214
	ds_read_b128 v[206:209], v214 offset:1024
	ds_read_b128 v[210:213], v214 offset:2048
	ds_read_b128 v[214:217], v214 offset:3072
	global_load_lds_dwordx4 v132, s[0:1]
	s_add_i32 m0, s16, 0x2000
	s_nop 0
	global_load_lds_dwordx4 v128, s[0:1]
	s_waitcnt vmcnt(8)
	s_setprio 1
	s_barrier
	s_waitcnt lgkmcnt(0)
	v_mfma_f32_16x16x32_bf16 v[120:123], v[202:205], v[166:169], v[120:123]
	v_mfma_f32_16x16x32_bf16 v[112:115], v[210:213], v[166:169], v[112:115]
	v_mfma_f32_16x16x32_bf16 v[104:107], v[202:205], v[174:177], v[104:107]
	v_mfma_f32_16x16x32_bf16 v[96:99], v[210:213], v[174:177], v[96:99]
	v_mfma_f32_16x16x32_bf16 v[88:91], v[202:205], v[182:185], v[88:91]
	v_mfma_f32_16x16x32_bf16 v[80:83], v[210:213], v[182:185], v[80:83]
	v_mfma_f32_16x16x32_bf16 v[72:75], v[202:205], v[190:193], v[72:75]
	v_mfma_f32_16x16x32_bf16 v[64:67], v[210:213], v[190:193], v[64:67]
	v_mfma_f32_16x16x32_bf16 v[120:123], v[206:209], v[170:173], v[120:123]
	v_mfma_f32_16x16x32_bf16 v[112:115], v[214:217], v[170:173], v[112:115]
	v_mfma_f32_16x16x32_bf16 v[104:107], v[206:209], v[178:181], v[104:107]
	v_mfma_f32_16x16x32_bf16 v[96:99], v[214:217], v[178:181], v[96:99]
	v_mfma_f32_16x16x32_bf16 v[88:91], v[206:209], v[186:189], v[88:91]
	v_mfma_f32_16x16x32_bf16 v[80:83], v[214:217], v[186:189], v[80:83]
	v_mfma_f32_16x16x32_bf16 v[72:75], v[206:209], v[194:197], v[72:75]
	v_mfma_f32_16x16x32_bf16 v[64:67], v[214:217], v[194:197], v[64:67]
	s_mov_b32 m0, s36
	s_add_u32 s0, s22, 0x80
	s_addc_u32 s1, s23, 0
	s_barrier
	s_setprio 0
	ds_read_b128 v[166:169], v148 offset:49152
	ds_read_b128 v[170:173], v148 offset:50176
	ds_read_b128 v[174:177], v148 offset:51200
	ds_read_b128 v[178:181], v148 offset:52224
	ds_read_b128 v[182:185], v148 offset:53248
	ds_read_b128 v[186:189], v148 offset:54272
	ds_read_b128 v[190:193], v148 offset:55296
	ds_read_b128 v[194:197], v148 offset:56320
	global_load_lds_dwordx4 v134, s[0:1]
	s_mov_b32 m0, s37
	s_nop 0
	global_load_lds_dwordx4 v130, s[0:1]
	s_setprio 1
	s_barrier
	s_waitcnt lgkmcnt(0)
	v_mfma_f32_16x16x32_bf16 v[60:63], v[150:153], v[166:169], v[60:63]
	v_mfma_f32_16x16x32_bf16 v[56:59], v[158:161], v[166:169], v[56:59]
	v_mfma_f32_16x16x32_bf16 v[44:47], v[150:153], v[174:177], v[44:47]
	v_mfma_f32_16x16x32_bf16 v[40:43], v[158:161], v[174:177], v[40:43]
	v_mfma_f32_16x16x32_bf16 v[28:31], v[150:153], v[182:185], v[28:31]
	v_mfma_f32_16x16x32_bf16 v[24:27], v[158:161], v[182:185], v[24:27]
	v_mfma_f32_16x16x32_bf16 v[12:15], v[150:153], v[190:193], v[12:15]
	v_mfma_f32_16x16x32_bf16 v[8:11], v[158:161], v[190:193], v[8:11]
	v_mfma_f32_16x16x32_bf16 v[60:63], v[154:157], v[170:173], v[60:63]
	v_mfma_f32_16x16x32_bf16 v[56:59], v[162:165], v[170:173], v[56:59]
	v_mfma_f32_16x16x32_bf16 v[44:47], v[154:157], v[178:181], v[44:47]
	v_mfma_f32_16x16x32_bf16 v[40:43], v[162:165], v[178:181], v[40:43]
	v_mfma_f32_16x16x32_bf16 v[28:31], v[154:157], v[186:189], v[28:31]
	v_mfma_f32_16x16x32_bf16 v[24:27], v[162:165], v[186:189], v[24:27]
	v_mfma_f32_16x16x32_bf16 v[12:15], v[154:157], v[194:197], v[12:15]
	v_mfma_f32_16x16x32_bf16 v[8:11], v[162:165], v[194:197], v[8:11]
	s_barrier
	s_setprio 0
	s_add_u32 s16, s18, 0x40080
	s_addc_u32 s17, s19, 0
	s_add_i32 s18, s21, s25
	s_mov_b32 m0, s18
	s_nop 0
	global_load_lds_dwordx4 v132, s[16:17]
	s_add_i32 m0, s18, 0x2000
	s_nop 0
	global_load_lds_dwordx4 v128, s[16:17]
	s_waitcnt vmcnt(8)
	s_setprio 1
	s_barrier
	v_mfma_f32_16x16x32_bf16 v[52:55], v[202:205], v[166:169], v[52:55]
	v_mfma_f32_16x16x32_bf16 v[48:51], v[210:213], v[166:169], v[48:51]
	v_mfma_f32_16x16x32_bf16 v[36:39], v[202:205], v[174:177], v[36:39]
	v_mfma_f32_16x16x32_bf16 v[32:35], v[210:213], v[174:177], v[32:35]
	v_mfma_f32_16x16x32_bf16 v[20:23], v[202:205], v[182:185], v[20:23]
	v_mfma_f32_16x16x32_bf16 v[16:19], v[210:213], v[182:185], v[16:19]
	v_mfma_f32_16x16x32_bf16 v[4:7], v[202:205], v[190:193], v[4:7]
	v_mfma_f32_16x16x32_bf16 v[0:3], v[210:213], v[190:193], v[0:3]
	v_mfma_f32_16x16x32_bf16 v[52:55], v[206:209], v[170:173], v[52:55]
	v_mfma_f32_16x16x32_bf16 v[48:51], v[214:217], v[170:173], v[48:51]
	v_mfma_f32_16x16x32_bf16 v[36:39], v[206:209], v[178:181], v[36:39]
	v_mfma_f32_16x16x32_bf16 v[32:35], v[214:217], v[178:181], v[32:35]
	v_mfma_f32_16x16x32_bf16 v[20:23], v[206:209], v[186:189], v[20:23]
	v_mfma_f32_16x16x32_bf16 v[16:19], v[214:217], v[186:189], v[16:19]
	v_mfma_f32_16x16x32_bf16 v[4:7], v[206:209], v[194:197], v[4:7]
	v_mfma_f32_16x16x32_bf16 v[0:3], v[214:217], v[194:197], v[0:3]
	s_setprio 0
	s_add_i32 s48, s48, 2
	s_add_u32 s14, s14, 0x100
	s_addc_u32 s15, s15, 0
	s_add_u32 s46, s46, 0x100
	s_addc_u32 s47, s47, 0
	s_cmp_gt_u32 s48, 13
	s_cbranch_scc1 .Lconc_last_g0
	s_barrier
	s_branch .LBB0_235

; #define PG8_STAGE(bufoff, gbase, voff) do { _Pragma("unroll") for (int _i = 0; _i < 2; ++_i) \
;         __builtin_amdgcn_global_load_lds((const unsigned*)((const char*)(gbase) + (voff)[_i]), (LAS unsigned*)(lds + (bufoff) + ldsw + _i * 8192), 16, 0, 0); } while (0)
; #define PG8_WAIT_V(n) asm volatile("s_waitcnt vmcnt(" #n ")" ::: "memory")
; #define PG8_WAIT_L(n) asm volatile("s_waitcnt lgkmcnt(" #n ")" ::: "memory")
; template <class Epi, class Sched>
; __device__ __forceinline__ void gemm_phase(LAS unsigned char* lds, const Gemm g, const Sched& S, const Epi& E) {
;     ...
;         const bool has_next = S.next(ui + 1, nxt);
;         const char* nA = has_next ? (const char*)g.A + (size_t)nxt.pm * tstep : cA; const char* nB = has_next ? (const char*)g.Bt + (size_t)nxt.pn * tstep : cB;
;         for (int t = 0; t < nt; t += 2) {
;             const bool last = (t == nt - 2);
;             const char* a1 = cA + (size_t)(t + 1) * kstep;
;             const char* a2 = last ? nA : cA + (size_t)(t + 2) * kstep; const char* b2 = last ? nB : cB + (size_t)(t + 2) * kstep;
;             const char* a3 = a2 + kstep; const char* b3 = b2 + kstep;
;             PG8_LDB(B0, 0, 0); PG8_SCHED; PG8_LDA(At, 0, 0); PG8_STAGE(PG8_SA(1, 1), a1 + hstep, voffA);
;             PG8_WAIT_L(8); PG8_BAR; PG8_WAIT_L(0); PG8_MMA(0, 0, At, B0); PG8_BAR; PG8_SCHED;
;             PG8_LDB(B1, 0, 1); PG8_STAGE(PG8_SB(0, 0), b2, voffB);
;             PG8_BAR; PG8_WAIT_L(0); PG8_MMA(0, 1, At, B1); PG8_BAR;
;             PG8_LDA(At, 0, 1); PG8_STAGE(PG8_SA(0, 0), a2, voffA);
;             PG8_BAR; PG8_WAIT_L(0); PG8_MMA(1, 0, At, B0); PG8_BAR; PG8_SCHED;
;             PG8_STAGE(PG8_SB(0, 1), b2 + hstep, voffB);
;             PG8_WAIT_V(6); PG8_BAR; PG8_MMA(1, 1, At, B1); PG8_BAR;
;             PG8_LDB(B0, 1, 0); PG8_SCHED; PG8_LDA(At, 1, 0); PG8_STAGE(PG8_SA(0, 1), a2 + hstep, voffA);
;             PG8_WAIT_L(8); PG8_BAR; PG8_WAIT_L(0); PG8_MMA(0, 0, At, B0); PG8_BAR; PG8_SCHED;
;             PG8_LDB(B1, 1, 1); PG8_STAGE(PG8_SB(1, 0), b3, voffB);
;             PG8_BAR; PG8_WAIT_L(0); PG8_MMA(0, 1, At, B1); PG8_BAR;
;             PG8_LDA(At, 1, 1); PG8_STAGE(PG8_SA(1, 0), a3, voffA);
;             PG8_BAR; PG8_WAIT_L(0); PG8_MMA(1, 0, At, B0); PG8_BAR; PG8_SCHED;
;             PG8_STAGE(PG8_SB(1, 1), b3 + hstep, voffB);
;             PG8_WAIT_V(6); PG8_BAR; PG8_MMA(1, 1, At, B1); PG8_BAR;
.LBB0_304:
	s_add_u32 s0, s28, 0x100
	s_addc_u32 s67, s29, 0
	s_mov_b32 s68, -2
	ds_read_b128 v[144:147], v165
	ds_read_b128 v[148:151], v165 offset:1024
	ds_read_b128 v[152:155], v165 offset:2048
	ds_read_b128 v[156:159], v165 offset:3072
	s_add_u32 s28, s26, 0x100
	s_addc_u32 s29, s27, 0
	s_cmp_eq_u32 s68, 40
	s_cselect_b32 s37, s5, s29
	s_cselect_b32 s36, s4, s28
	s_cselect_b32 s35, s7, s67
	s_cselect_b32 s34, s6, s0
	v_lshl_add_u64 v[160:161], s[26:27], 0, v[136:137]
	s_add_i32 m0, s42, 0xc000
	ds_read_b128 v[168:171], v166
	ds_read_b128 v[172:175], v166 offset:1024
	ds_read_b128 v[176:179], v166 offset:2048
	ds_read_b128 v[180:183], v166 offset:3072
	ds_read_b128 v[184:187], v166 offset:4096
	ds_read_b128 v[188:191], v166 offset:5120
	ds_read_b128 v[192:195], v166 offset:6144
	ds_read_b128 v[196:199], v166 offset:7168
	global_load_lds_dwordx4 v[160:161], off
	v_lshl_add_u64 v[160:161], s[26:27], 0, v[138:139]
	s_add_i32 m0, s42, 0xe000
	s_nop 0
	global_load_lds_dwordx4 v[160:161], off
	s_waitcnt lgkmcnt(8)
	s_waitcnt vmcnt(8)
	s_setprio 1
	s_barrier
	s_waitcnt lgkmcnt(0)
	v_mfma_f32_16x16x32_bf16 v[124:127], v[144:147], v[168:171], 0
	v_mfma_f32_16x16x32_bf16 v[120:123], v[152:155], v[168:171], 0
	v_mfma_f32_16x16x32_bf16 v[116:119], v[144:147], v[176:179], 0
	v_mfma_f32_16x16x32_bf16 v[104:107], v[152:155], v[176:179], 0
	v_mfma_f32_16x16x32_bf16 v[96:99], v[144:147], v[184:187], 0
	v_mfma_f32_16x16x32_bf16 v[88:91], v[152:155], v[184:187], 0
	v_mfma_f32_16x16x32_bf16 v[80:83], v[144:147], v[192:195], 0
	v_mfma_f32_16x16x32_bf16 v[72:75], v[152:155], v[192:195], 0
	v_mfma_f32_16x16x32_bf16 v[124:127], v[148:151], v[172:175], v[124:127]
	v_mfma_f32_16x16x32_bf16 v[120:123], v[156:159], v[172:175], v[120:123]
	v_mfma_f32_16x16x32_bf16 v[116:119], v[148:151], v[180:183], v[116:119]
	v_mfma_f32_16x16x32_bf16 v[104:107], v[156:159], v[180:183], v[104:107]
	v_mfma_f32_16x16x32_bf16 v[96:99], v[148:151], v[188:191], v[96:99]
	v_mfma_f32_16x16x32_bf16 v[88:91], v[156:159], v[188:191], v[88:91]
	v_mfma_f32_16x16x32_bf16 v[80:83], v[148:151], v[196:199], v[80:83]
	v_mfma_f32_16x16x32_bf16 v[72:75], v[156:159], v[196:199], v[72:75]
	s_barrier
	s_setprio 0
	s_add_i32 s16, s58, s40
	s_mov_b32 m0, s16
	ds_read_b128 v[202:205], v167
	ds_read_b128 v[206:209], v167 offset:1024
	ds_read_b128 v[210:213], v167 offset:2048
	ds_read_b128 v[214:217], v167 offset:3072
	global_load_lds_dwordx4 v132, s[34:35]
	s_add_i32 m0, s16, 0x2000
	s_nop 0
	global_load_lds_dwordx4 v128, s[34:35]
	s_waitcnt vmcnt(8)
	s_setprio 1
	s_barrier
	s_waitcnt lgkmcnt(0)
	v_mfma_f32_16x16x32_bf16 v[112:115], v[202:205], v[168:171], 0
	v_mfma_f32_16x16x32_bf16 v[108:111], v[210:213], v[168:171], 0
	v_mfma_f32_16x16x32_bf16 v[100:103], v[202:205], v[176:179], 0
	v_mfma_f32_16x16x32_bf16 v[92:95], v[210:213], v[176:179], 0
	v_mfma_f32_16x16x32_bf16 v[84:87], v[202:205], v[184:187], 0
	v_mfma_f32_16x16x32_bf16 v[76:79], v[210:213], v[184:187], 0
	v_mfma_f32_16x16x32_bf16 v[68:71], v[202:205], v[192:195], 0
	v_mfma_f32_16x16x32_bf16 v[64:67], v[210:213], v[192:195], 0
	v_mfma_f32_16x16x32_bf16 v[112:115], v[206:209], v[172:175], v[112:115]
	v_mfma_f32_16x16x32_bf16 v[108:111], v[214:217], v[172:175], v[108:111]
	v_mfma_f32_16x16x32_bf16 v[100:103], v[206:209], v[180:183], v[100:103]
	v_mfma_f32_16x16x32_bf16 v[92:95], v[214:217], v[180:183], v[92:95]
	v_mfma_f32_16x16x32_bf16 v[84:87], v[206:209], v[188:191], v[84:87]
	v_mfma_f32_16x16x32_bf16 v[76:79], v[214:217], v[188:191], v[76:79]
	v_mfma_f32_16x16x32_bf16 v[68:71], v[206:209], v[196:199], v[68:71]
	v_mfma_f32_16x16x32_bf16 v[64:67], v[214:217], v[196:199], v[64:67]
	s_mov_b32 m0, s42
	s_barrier
	s_setprio 0
	ds_read_b128 v[168:171], v166 offset:16384
	ds_read_b128 v[172:175], v166 offset:17408
	ds_read_b128 v[176:179], v166 offset:18432
	ds_read_b128 v[180:183], v166 offset:19456
	ds_read_b128 v[184:187], v166 offset:20480
	ds_read_b128 v[188:191], v166 offset:21504
	ds_read_b128 v[192:195], v166 offset:22528
	ds_read_b128 v[196:199], v166 offset:23552
	global_load_lds_dwordx4 v134, s[36:37]
	s_mov_b32 m0, s43
	s_nop 0
	global_load_lds_dwordx4 v130, s[36:37]
	s_setprio 1
	s_barrier
	s_waitcnt lgkmcnt(0)
	v_mfma_f32_16x16x32_bf16 v[60:63], v[144:147], v[168:171], 0
	v_mfma_f32_16x16x32_bf16 v[56:59], v[152:155], v[168:171], 0
	v_mfma_f32_16x16x32_bf16 v[48:51], v[144:147], v[176:179], 0
	v_mfma_f32_16x16x32_bf16 v[40:43], v[152:155], v[176:179], 0
	v_mfma_f32_16x16x32_bf16 v[32:35], v[144:147], v[184:187], 0
	v_mfma_f32_16x16x32_bf16 v[24:27], v[152:155], v[184:187], 0
	v_mfma_f32_16x16x32_bf16 v[16:19], v[144:147], v[192:195], 0
	v_mfma_f32_16x16x32_bf16 v[8:11], v[152:155], v[192:195], 0
	v_mfma_f32_16x16x32_bf16 v[60:63], v[148:151], v[172:175], v[60:63]
	v_mfma_f32_16x16x32_bf16 v[56:59], v[156:159], v[172:175], v[56:59]
	v_mfma_f32_16x16x32_bf16 v[48:51], v[148:151], v[180:183], v[48:51]
	v_mfma_f32_16x16x32_bf16 v[40:43], v[156:159], v[180:183], v[40:43]
	v_mfma_f32_16x16x32_bf16 v[32:35], v[148:151], v[188:191], v[32:35]
	v_mfma_f32_16x16x32_bf16 v[24:27], v[156:159], v[188:191], v[24:27]
	v_mfma_f32_16x16x32_bf16 v[16:19], v[148:151], v[196:199], v[16:19]
	v_mfma_f32_16x16x32_bf16 v[8:11], v[156:159], v[196:199], v[8:11]
	s_barrier
	s_setprio 0
	s_add_u32 s16, s34, 0xb0000
	s_addc_u32 s17, s35, 0
	s_add_i32 s20, s59, s40
	s_mov_b32 m0, s20
	s_nop 0
	global_load_lds_dwordx4 v132, s[16:17]
	s_add_i32 m0, s20, 0x2000
	s_nop 0
	global_load_lds_dwordx4 v128, s[16:17]
	s_add_u32 s16, s36, 0xb0000
	s_addc_u32 s17, s37, 0
	s_mov_b32 m0, s44
	s_nop 0
	global_load_lds_dwordx4 v134, s[16:17]
	s_mov_b32 m0, s45
	s_nop 0
	global_load_lds_dwordx4 v130, s[16:17]
	s_waitcnt vmcnt(10)
	s_setprio 1
	s_barrier
; #define PG8_STAGE(bufoff, gbase, voff) do { _Pragma("unroll") for (int _i = 0; _i < 2; ++_i) \
;         __builtin_amdgcn_global_load_lds((const unsigned*)((const char*)(gbase) + (voff)[_i]), (LAS unsigned*)(lds + (bufoff) + ldsw + _i * 8192), 16, 0, 0); } while (0)
; #define PG8_LDA(dst, b, h) do { _Pragma("unroll") for (int m = 0; m < 4; ++m) _Pragma("unroll") for (int k = 0; k < 2; ++k) dst[m][k] = *(const LAS bf16x8*)(lds + PG8_SA(b, h) + aoff + m * 2048 + k * 1024); } while (0)
; #define PG8_LDB(dst, b, h) do { _Pragma("unroll") for (int n = 0; n < 2; ++n) _Pragma("unroll") for (int k = 0; k < 2; ++k) dst[n][k] = *(const LAS bf16x8*)(lds + PG8_SB(b, h) + boff + n * 2048 + k * 1024); } while (0)
; #define PG8_MMA(ai, bj, At, Bt) do { __builtin_amdgcn_s_setprio(1); _Pragma("unroll") for (int m = 0; m < 4; ++m) _Pragma("unroll") for (int n = 0; n < 2; ++n) _Pragma("unroll") for (int k = 0; k < 2; ++k) \
;         acc[ai][bj][m][n] = __builtin_amdgcn_mfma_f32_16x16x32_bf16(Bt[n][k], At[m][k], acc[ai][bj][m][n], 0, 0, 0); __builtin_amdgcn_s_setprio(0); } while (0)
; #define PG8_WAIT_V(n) asm volatile("s_waitcnt vmcnt(" #n ")" ::: "memory")
; #define PG8_WAIT_L(n) asm volatile("s_waitcnt lgkmcnt(" #n ")" ::: "memory")
; #define PG8_BAR __builtin_amdgcn_s_barrier()
; #define PG8_SCHED __builtin_amdgcn_sched_barrier(0)
; template <class Epi, class Sched>
; __device__ __forceinline__ void gemm_phase(LAS unsigned char* lds, const Gemm g, const Sched& S, const Epi& E) {
;     ...
;             PG8_WAIT_V(6); PG8_BAR; PG8_MMA(1, 1, At, B1); PG8_BAR;
;             PG8_LDB(B0, 1, 0); PG8_SCHED; PG8_LDA(At, 1, 0); PG8_STAGE(PG8_SA(0, 1), a2 + hstep, voffA);
;             PG8_WAIT_L(8); PG8_BAR; PG8_WAIT_L(0); PG8_MMA(0, 0, At, B0); PG8_BAR; PG8_SCHED;
;             PG8_LDB(B1, 1, 1); PG8_STAGE(PG8_SB(1, 0), b3, voffB);
;             PG8_BAR; PG8_WAIT_L(0); PG8_MMA(0, 1, At, B1); PG8_BAR;
;             PG8_LDA(At, 1, 1); PG8_STAGE(PG8_SA(1, 0), a3, voffA);
;             PG8_BAR; PG8_WAIT_L(0); PG8_MMA(1, 0, At, B0); PG8_BAR; PG8_SCHED;
	v_mfma_f32_16x16x32_bf16 v[52:55], v[202:205], v[168:171], 0
	v_mfma_f32_16x16x32_bf16 v[44:47], v[210:213], v[168:171], 0
	v_mfma_f32_16x16x32_bf16 v[36:39], v[202:205], v[176:179], 0
	v_mfma_f32_16x16x32_bf16 v[28:31], v[210:213], v[176:179], 0
	v_mfma_f32_16x16x32_bf16 v[20:23], v[202:205], v[184:187], 0
	v_mfma_f32_16x16x32_bf16 v[12:15], v[210:213], v[184:187], 0
	v_mfma_f32_16x16x32_bf16 v[4:7], v[202:205], v[192:195], 0
	v_mfma_f32_16x16x32_bf16 v[0:3], v[210:213], v[192:195], 0
	v_mfma_f32_16x16x32_bf16 v[52:55], v[206:209], v[172:175], v[52:55]
	v_mfma_f32_16x16x32_bf16 v[44:47], v[214:217], v[172:175], v[44:47]
	v_mfma_f32_16x16x32_bf16 v[36:39], v[206:209], v[180:183], v[36:39]
	v_mfma_f32_16x16x32_bf16 v[28:31], v[214:217], v[180:183], v[28:31]
	v_mfma_f32_16x16x32_bf16 v[20:23], v[206:209], v[188:191], v[20:23]
	v_mfma_f32_16x16x32_bf16 v[12:15], v[214:217], v[188:191], v[12:15]
	v_mfma_f32_16x16x32_bf16 v[4:7], v[206:209], v[196:199], v[4:7]
	v_mfma_f32_16x16x32_bf16 v[0:3], v[214:217], v[196:199], v[0:3]
	s_add_i32 s20, 0, 0x18000
	v_add_u32_e32 v156, s20, v164
	s_barrier
	s_setprio 0
	ds_read_b128 v[144:147], v156
	ds_read_b128 v[148:151], v156 offset:1024
	ds_read_b128 v[152:155], v156 offset:2048
	ds_read_b128 v[156:159], v156 offset:3072
	ds_read_b128 v[168:171], v166 offset:32768
	ds_read_b128 v[172:175], v166 offset:33792
	ds_read_b128 v[176:179], v166 offset:34816
	ds_read_b128 v[180:183], v166 offset:35840
	ds_read_b128 v[184:187], v166 offset:36864
	ds_read_b128 v[188:191], v166 offset:37888
	ds_read_b128 v[192:195], v166 offset:38912
	ds_read_b128 v[196:199], v166 offset:39936
	s_waitcnt lgkmcnt(8)
	s_waitcnt vmcnt(8)
	s_setprio 1
	s_barrier
	s_waitcnt lgkmcnt(0)
	v_mfma_f32_16x16x32_bf16 v[124:127], v[144:147], v[168:171], v[124:127]
	v_mfma_f32_16x16x32_bf16 v[120:123], v[152:155], v[168:171], v[120:123]
	v_mfma_f32_16x16x32_bf16 v[116:119], v[144:147], v[176:179], v[116:119]
	v_mfma_f32_16x16x32_bf16 v[104:107], v[152:155], v[176:179], v[104:107]
	v_mfma_f32_16x16x32_bf16 v[96:99], v[144:147], v[184:187], v[96:99]
	v_mfma_f32_16x16x32_bf16 v[88:91], v[152:155], v[184:187], v[88:91]
	v_mfma_f32_16x16x32_bf16 v[80:83], v[144:147], v[192:195], v[80:83]
	v_mfma_f32_16x16x32_bf16 v[72:75], v[152:155], v[192:195], v[72:75]
	v_mfma_f32_16x16x32_bf16 v[124:127], v[148:151], v[172:175], v[124:127]
	v_mfma_f32_16x16x32_bf16 v[120:123], v[156:159], v[172:175], v[120:123]
	v_mfma_f32_16x16x32_bf16 v[116:119], v[148:151], v[180:183], v[116:119]
	v_mfma_f32_16x16x32_bf16 v[104:107], v[156:159], v[180:183], v[104:107]
	v_mfma_f32_16x16x32_bf16 v[96:99], v[148:151], v[188:191], v[96:99]
	v_mfma_f32_16x16x32_bf16 v[88:91], v[156:159], v[188:191], v[88:91]
	v_mfma_f32_16x16x32_bf16 v[80:83], v[148:151], v[196:199], v[80:83]
	v_mfma_f32_16x16x32_bf16 v[72:75], v[156:159], v[196:199], v[72:75]
	s_barrier
	s_setprio 0
	s_add_i32 s21, 0, 0x1c000
	s_add_i32 s16, s20, s40
	v_add_u32_e32 v214, s21, v164
	s_add_u32 s8, s34, 0x80
	s_addc_u32 s9, s35, 0
	s_mov_b32 m0, s16
	ds_read_b128 v[202:205], v214
	ds_read_b128 v[206:209], v214 offset:1024
	ds_read_b128 v[210:213], v214 offset:2048
	ds_read_b128 v[214:217], v214 offset:3072
	global_load_lds_dwordx4 v132, s[8:9]
	s_add_i32 m0, s16, 0x2000
	s_nop 0
	global_load_lds_dwordx4 v128, s[8:9]
	s_waitcnt vmcnt(8)
	s_setprio 1
	s_barrier
	s_waitcnt lgkmcnt(0)
	v_mfma_f32_16x16x32_bf16 v[112:115], v[202:205], v[168:171], v[112:115]
	v_mfma_f32_16x16x32_bf16 v[108:111], v[210:213], v[168:171], v[108:111]
	v_mfma_f32_16x16x32_bf16 v[100:103], v[202:205], v[176:179], v[100:103]
	v_mfma_f32_16x16x32_bf16 v[92:95], v[210:213], v[176:179], v[92:95]
	v_mfma_f32_16x16x32_bf16 v[84:87], v[202:205], v[184:187], v[84:87]
	v_mfma_f32_16x16x32_bf16 v[76:79], v[210:213], v[184:187], v[76:79]
	v_mfma_f32_16x16x32_bf16 v[68:71], v[202:205], v[192:195], v[68:71]
	v_mfma_f32_16x16x32_bf16 v[64:67], v[210:213], v[192:195], v[64:67]
	v_mfma_f32_16x16x32_bf16 v[112:115], v[206:209], v[172:175], v[112:115]
	v_mfma_f32_16x16x32_bf16 v[108:111], v[214:217], v[172:175], v[108:111]
	v_mfma_f32_16x16x32_bf16 v[100:103], v[206:209], v[180:183], v[100:103]
	v_mfma_f32_16x16x32_bf16 v[92:95], v[214:217], v[180:183], v[92:95]
	v_mfma_f32_16x16x32_bf16 v[84:87], v[206:209], v[188:191], v[84:87]
	v_mfma_f32_16x16x32_bf16 v[76:79], v[214:217], v[188:191], v[76:79]
	v_mfma_f32_16x16x32_bf16 v[68:71], v[206:209], v[196:199], v[68:71]
	v_mfma_f32_16x16x32_bf16 v[64:67], v[214:217], v[196:199], v[64:67]
	s_mov_b32 m0, s52
	s_add_u32 s8, s36, 0x80
	s_addc_u32 s9, s37, 0
	s_barrier
	s_setprio 0
	ds_read_b128 v[168:171], v166 offset:49152
	ds_read_b128 v[172:175], v166 offset:50176
	ds_read_b128 v[176:179], v166 offset:51200
	ds_read_b128 v[180:183], v166 offset:52224
	ds_read_b128 v[184:187], v166 offset:53248
	ds_read_b128 v[188:191], v166 offset:54272
	ds_read_b128 v[192:195], v166 offset:55296
	ds_read_b128 v[196:199], v166 offset:56320
	global_load_lds_dwordx4 v134, s[8:9]
	s_mov_b32 m0, s53
	s_nop 0
	global_load_lds_dwordx4 v130, s[8:9]
	s_setprio 1
	s_barrier
	s_waitcnt lgkmcnt(0)
	v_mfma_f32_16x16x32_bf16 v[60:63], v[144:147], v[168:171], v[60:63]
	v_mfma_f32_16x16x32_bf16 v[56:59], v[152:155], v[168:171], v[56:59]
	v_mfma_f32_16x16x32_bf16 v[48:51], v[144:147], v[176:179], v[48:51]
	v_mfma_f32_16x16x32_bf16 v[40:43], v[152:155], v[176:179], v[40:43]
	v_mfma_f32_16x16x32_bf16 v[32:35], v[144:147], v[184:187], v[32:35]
	v_mfma_f32_16x16x32_bf16 v[24:27], v[152:155], v[184:187], v[24:27]
	v_mfma_f32_16x16x32_bf16 v[16:19], v[144:147], v[192:195], v[16:19]
	v_mfma_f32_16x16x32_bf16 v[8:11], v[152:155], v[192:195], v[8:11]
	v_mfma_f32_16x16x32_bf16 v[60:63], v[148:151], v[172:175], v[60:63]
	v_mfma_f32_16x16x32_bf16 v[56:59], v[156:159], v[172:175], v[56:59]
	v_mfma_f32_16x16x32_bf16 v[48:51], v[148:151], v[180:183], v[48:51]
	v_mfma_f32_16x16x32_bf16 v[40:43], v[156:159], v[180:183], v[40:43]
	v_mfma_f32_16x16x32_bf16 v[32:35], v[148:151], v[188:191], v[32:35]
	v_mfma_f32_16x16x32_bf16 v[24:27], v[156:159], v[188:191], v[24:27]
	v_mfma_f32_16x16x32_bf16 v[16:19], v[148:151], v[196:199], v[16:19]
	v_mfma_f32_16x16x32_bf16 v[8:11], v[156:159], v[196:199], v[8:11]
	s_barrier
; #define PG8_STAGE(bufoff, gbase, voff) do { _Pragma("unroll") for (int _i = 0; _i < 2; ++_i) \
;         __builtin_amdgcn_global_load_lds((const unsigned*)((const char*)(gbase) + (voff)[_i]), (LAS unsigned*)(lds + (bufoff) + ldsw + _i * 8192), 16, 0, 0); } while (0)
; #define PG8_LDA(dst, b, h) do { _Pragma("unroll") for (int m = 0; m < 4; ++m) _Pragma("unroll") for (int k = 0; k < 2; ++k) dst[m][k] = *(const LAS bf16x8*)(lds + PG8_SA(b, h) + aoff + m * 2048 + k * 1024); } while (0)
; #define PG8_LDB(dst, b, h) do { _Pragma("unroll") for (int n = 0; n < 2; ++n) _Pragma("unroll") for (int k = 0; k < 2; ++k) dst[n][k] = *(const LAS bf16x8*)(lds + PG8_SB(b, h) + boff + n * 2048 + k * 1024); } while (0)
; #define PG8_MMA(ai, bj, At, Bt) do { __builtin_amdgcn_s_setprio(1); _Pragma("unroll") for (int m = 0; m < 4; ++m) _Pragma("unroll") for (int n = 0; n < 2; ++n) _Pragma("unroll") for (int k = 0; k < 2; ++k) \
;         acc[ai][bj][m][n] = __builtin_amdgcn_mfma_f32_16x16x32_bf16(Bt[n][k], At[m][k], acc[ai][bj][m][n], 0, 0, 0); __builtin_amdgcn_s_setprio(0); } while (0)
; #define PG8_WAIT_V(n) asm volatile("s_waitcnt vmcnt(" #n ")" ::: "memory")
; #define PG8_WAIT_L(n) asm volatile("s_waitcnt lgkmcnt(" #n ")" ::: "memory")
; #define PG8_BAR __builtin_amdgcn_s_barrier()
; #define PG8_SCHED __builtin_amdgcn_sched_barrier(0)
; template <class Epi, class Sched>
; __device__ __forceinline__ void gemm_phase(LAS unsigned char* lds, const Gemm g, const Sched& S, const Epi& E) {
;     ...
;             PG8_LDB(B0, 0, 0); PG8_SCHED; PG8_LDA(At, 0, 0); PG8_STAGE(PG8_SA(1, 1), a1 + hstep, voffA);
;             PG8_WAIT_L(8); PG8_BAR; PG8_WAIT_L(0); PG8_MMA(0, 0, At, B0); PG8_BAR; PG8_SCHED;
;             PG8_LDB(B1, 0, 1); PG8_STAGE(PG8_SB(0, 0), b2, voffB);
;             PG8_BAR; PG8_WAIT_L(0); PG8_MMA(0, 1, At, B1); PG8_BAR;
;             PG8_LDA(At, 0, 1); PG8_STAGE(PG8_SA(0, 0), a2, voffA);
;             PG8_BAR; PG8_WAIT_L(0); PG8_MMA(1, 0, At, B0); PG8_BAR; PG8_SCHED;
;             PG8_STAGE(PG8_SB(0, 1), b2 + hstep, voffB);
;             PG8_WAIT_V(6); PG8_BAR; PG8_MMA(1, 1, At, B1); PG8_BAR;
;     ...
;             PG8_STAGE(PG8_SB(1, 1), b3 + hstep, voffB);
;             PG8_WAIT_V(6); PG8_BAR; PG8_MMA(1, 1, At, B1); PG8_BAR;
	s_setprio 0
	s_add_u32 s16, s34, 0xb0080
	s_addc_u32 s17, s35, 0
	s_add_i32 s20, s21, s40
	s_mov_b32 m0, s20
	s_nop 0
	global_load_lds_dwordx4 v132, s[16:17]
	s_add_i32 m0, s20, 0x2000
	s_nop 0
	global_load_lds_dwordx4 v128, s[16:17]
	s_waitcnt vmcnt(8)
	s_setprio 1
	s_barrier
	v_mfma_f32_16x16x32_bf16 v[52:55], v[202:205], v[168:171], v[52:55]
	v_mfma_f32_16x16x32_bf16 v[44:47], v[210:213], v[168:171], v[44:47]
	v_mfma_f32_16x16x32_bf16 v[36:39], v[202:205], v[176:179], v[36:39]
	v_mfma_f32_16x16x32_bf16 v[28:31], v[210:213], v[176:179], v[28:31]
	v_mfma_f32_16x16x32_bf16 v[20:23], v[202:205], v[184:187], v[20:23]
	v_mfma_f32_16x16x32_bf16 v[12:15], v[210:213], v[184:187], v[12:15]
	v_mfma_f32_16x16x32_bf16 v[4:7], v[202:205], v[192:195], v[4:7]
	v_mfma_f32_16x16x32_bf16 v[0:3], v[210:213], v[192:195], v[0:3]
	v_mfma_f32_16x16x32_bf16 v[52:55], v[206:209], v[172:175], v[52:55]
	v_mfma_f32_16x16x32_bf16 v[44:47], v[214:217], v[172:175], v[44:47]
	v_mfma_f32_16x16x32_bf16 v[36:39], v[206:209], v[180:183], v[36:39]
	v_mfma_f32_16x16x32_bf16 v[28:31], v[214:217], v[180:183], v[28:31]
	v_mfma_f32_16x16x32_bf16 v[20:23], v[206:209], v[188:191], v[20:23]
	v_mfma_f32_16x16x32_bf16 v[12:15], v[214:217], v[188:191], v[12:15]
	v_mfma_f32_16x16x32_bf16 v[4:7], v[206:209], v[196:199], v[4:7]
	v_mfma_f32_16x16x32_bf16 v[0:3], v[214:217], v[196:199], v[0:3]
	s_add_i32 s68, s68, 2
	s_add_u32 s0, s0, 0x100
	s_addc_u32 s67, s67, 0
	s_cmp_gt_u32 s68, 41
	s_mov_b64 s[26:27], s[28:29]
	s_barrier
	s_setprio 0
.LBB0_305:
	ds_read_b128 v[144:147], v165
	ds_read_b128 v[148:151], v165 offset:1024
	ds_read_b128 v[152:155], v165 offset:2048
	ds_read_b128 v[156:159], v165 offset:3072
	s_add_u32 s28, s26, 0x100
	s_addc_u32 s29, s27, 0
	s_cmp_eq_u32 s68, 40
	s_cselect_b32 s37, s5, s29
	s_cselect_b32 s36, s4, s28
	s_cselect_b32 s35, s7, s67
	s_cselect_b32 s34, s6, s0
	v_lshl_add_u64 v[160:161], s[26:27], 0, v[136:137]
	s_add_i32 m0, s42, 0xc000
	ds_read_b128 v[168:171], v166
	ds_read_b128 v[172:175], v166 offset:1024
	ds_read_b128 v[176:179], v166 offset:2048
	ds_read_b128 v[180:183], v166 offset:3072
	ds_read_b128 v[184:187], v166 offset:4096
	ds_read_b128 v[188:191], v166 offset:5120
	ds_read_b128 v[192:195], v166 offset:6144
	ds_read_b128 v[196:199], v166 offset:7168
	global_load_lds_dwordx4 v[160:161], off
	v_lshl_add_u64 v[160:161], s[26:27], 0, v[138:139]
	s_add_i32 m0, s42, 0xe000
	s_nop 0
	global_load_lds_dwordx4 v[160:161], off
	s_waitcnt lgkmcnt(8)
	s_waitcnt vmcnt(8)
	s_setprio 1
	s_barrier
	s_waitcnt lgkmcnt(0)
	v_mfma_f32_16x16x32_bf16 v[124:127], v[144:147], v[168:171], v[124:127]
	v_mfma_f32_16x16x32_bf16 v[120:123], v[152:155], v[168:171], v[120:123]
	v_mfma_f32_16x16x32_bf16 v[116:119], v[144:147], v[176:179], v[116:119]
	v_mfma_f32_16x16x32_bf16 v[104:107], v[152:155], v[176:179], v[104:107]
	v_mfma_f32_16x16x32_bf16 v[96:99], v[144:147], v[184:187], v[96:99]
	v_mfma_f32_16x16x32_bf16 v[88:91], v[152:155], v[184:187], v[88:91]
	v_mfma_f32_16x16x32_bf16 v[80:83], v[144:147], v[192:195], v[80:83]
	v_mfma_f32_16x16x32_bf16 v[72:75], v[152:155], v[192:195], v[72:75]
	v_mfma_f32_16x16x32_bf16 v[124:127], v[148:151], v[172:175], v[124:127]
	v_mfma_f32_16x16x32_bf16 v[120:123], v[156:159], v[172:175], v[120:123]
	v_mfma_f32_16x16x32_bf16 v[116:119], v[148:151], v[180:183], v[116:119]
	v_mfma_f32_16x16x32_bf16 v[104:107], v[156:159], v[180:183], v[104:107]
	v_mfma_f32_16x16x32_bf16 v[96:99], v[148:151], v[188:191], v[96:99]
	v_mfma_f32_16x16x32_bf16 v[88:91], v[156:159], v[188:191], v[88:91]
	v_mfma_f32_16x16x32_bf16 v[80:83], v[148:151], v[196:199], v[80:83]
	v_mfma_f32_16x16x32_bf16 v[72:75], v[156:159], v[196:199], v[72:75]
	s_barrier
	s_setprio 0
	s_add_i32 s16, s58, s40
	s_mov_b32 m0, s16
	ds_read_b128 v[202:205], v167
	ds_read_b128 v[206:209], v167 offset:1024
	ds_read_b128 v[210:213], v167 offset:2048
	ds_read_b128 v[214:217], v167 offset:3072
	global_load_lds_dwordx4 v132, s[34:35]
	s_add_i32 m0, s16, 0x2000
	s_nop 0
	global_load_lds_dwordx4 v128, s[34:35]
	s_waitcnt vmcnt(8)
	s_setprio 1
	s_barrier
	s_waitcnt lgkmcnt(0)
	v_mfma_f32_16x16x32_bf16 v[112:115], v[202:205], v[168:171], v[112:115]
	v_mfma_f32_16x16x32_bf16 v[108:111], v[210:213], v[168:171], v[108:111]
	v_mfma_f32_16x16x32_bf16 v[100:103], v[202:205], v[176:179], v[100:103]
	v_mfma_f32_16x16x32_bf16 v[92:95], v[210:213], v[176:179], v[92:95]
	v_mfma_f32_16x16x32_bf16 v[84:87], v[202:205], v[184:187], v[84:87]
	v_mfma_f32_16x16x32_bf16 v[76:79], v[210:213], v[184:187], v[76:79]
	v_mfma_f32_16x16x32_bf16 v[68:71], v[202:205], v[192:195], v[68:71]
	v_mfma_f32_16x16x32_bf16 v[64:67], v[210:213], v[192:195], v[64:67]
	v_mfma_f32_16x16x32_bf16 v[112:115], v[206:209], v[172:175], v[112:115]
	v_mfma_f32_16x16x32_bf16 v[108:111], v[214:217], v[172:175], v[108:111]
	v_mfma_f32_16x16x32_bf16 v[100:103], v[206:209], v[180:183], v[100:103]
	v_mfma_f32_16x16x32_bf16 v[92:95], v[214:217], v[180:183], v[92:95]
	v_mfma_f32_16x16x32_bf16 v[84:87], v[206:209], v[188:191], v[84:87]
	v_mfma_f32_16x16x32_bf16 v[76:79], v[214:217], v[188:191], v[76:79]
	v_mfma_f32_16x16x32_bf16 v[68:71], v[206:209], v[196:199], v[68:71]
	v_mfma_f32_16x16x32_bf16 v[64:67], v[214:217], v[196:199], v[64:67]
	s_mov_b32 m0, s42
	s_barrier
	s_setprio 0
	ds_read_b128 v[168:171], v166 offset:16384
	ds_read_b128 v[172:175], v166 offset:17408
	ds_read_b128 v[176:179], v166 offset:18432
	ds_read_b128 v[180:183], v166 offset:19456
	ds_read_b128 v[184:187], v166 offset:20480
	ds_read_b128 v[188:191], v166 offset:21504
	ds_read_b128 v[192:195], v166 offset:22528
	ds_read_b128 v[196:199], v166 offset:23552
	global_load_lds_dwordx4 v134, s[36:37]
	s_mov_b32 m0, s43
	s_nop 0
	global_load_lds_dwordx4 v130, s[36:37]
	s_setprio 1
	s_barrier
; #define PG8_STAGE(bufoff, gbase, voff) do { _Pragma("unroll") for (int _i = 0; _i < 2; ++_i) \
;         __builtin_amdgcn_global_load_lds((const unsigned*)((const char*)(gbase) + (voff)[_i]), (LAS unsigned*)(lds + (bufoff) + ldsw + _i * 8192), 16, 0, 0); } while (0)
; #define PG8_LDA(dst, b, h) do { _Pragma("unroll") for (int m = 0; m < 4; ++m) _Pragma("unroll") for (int k = 0; k < 2; ++k) dst[m][k] = *(const LAS bf16x8*)(lds + PG8_SA(b, h) + aoff + m * 2048 + k * 1024); } while (0)
; #define PG8_LDB(dst, b, h) do { _Pragma("unroll") for (int n = 0; n < 2; ++n) _Pragma("unroll") for (int k = 0; k < 2; ++k) dst[n][k] = *(const LAS bf16x8*)(lds + PG8_SB(b, h) + boff + n * 2048 + k * 1024); } while (0)
; #define PG8_MMA(ai, bj, At, Bt) do { __builtin_amdgcn_s_setprio(1); _Pragma("unroll") for (int m = 0; m < 4; ++m) _Pragma("unroll") for (int n = 0; n < 2; ++n) _Pragma("unroll") for (int k = 0; k < 2; ++k) \
;         acc[ai][bj][m][n] = __builtin_amdgcn_mfma_f32_16x16x32_bf16(Bt[n][k], At[m][k], acc[ai][bj][m][n], 0, 0, 0); __builtin_amdgcn_s_setprio(0); } while (0)
; #define PG8_WAIT_V(n) asm volatile("s_waitcnt vmcnt(" #n ")" ::: "memory")
; #define PG8_WAIT_L(n) asm volatile("s_waitcnt lgkmcnt(" #n ")" ::: "memory")
; #define PG8_BAR __builtin_amdgcn_s_barrier()
; #define PG8_SCHED __builtin_amdgcn_sched_barrier(0)
; template <class Epi, class Sched>
; __device__ __forceinline__ void gemm_phase(LAS unsigned char* lds, const Gemm g, const Sched& S, const Epi& E) {
;     ...
;             PG8_WAIT_V(6); PG8_BAR; PG8_MMA(1, 1, At, B1); PG8_BAR;
;             PG8_LDB(B0, 1, 0); PG8_SCHED; PG8_LDA(At, 1, 0); PG8_STAGE(PG8_SA(0, 1), a2 + hstep, voffA);
;             PG8_WAIT_L(8); PG8_BAR; PG8_WAIT_L(0); PG8_MMA(0, 0, At, B0); PG8_BAR; PG8_SCHED;
;             PG8_LDB(B1, 1, 1); PG8_STAGE(PG8_SB(1, 0), b3, voffB);
	s_waitcnt lgkmcnt(0)
	v_mfma_f32_16x16x32_bf16 v[60:63], v[144:147], v[168:171], v[60:63]
	v_mfma_f32_16x16x32_bf16 v[56:59], v[152:155], v[168:171], v[56:59]
	v_mfma_f32_16x16x32_bf16 v[48:51], v[144:147], v[176:179], v[48:51]
	v_mfma_f32_16x16x32_bf16 v[40:43], v[152:155], v[176:179], v[40:43]
	v_mfma_f32_16x16x32_bf16 v[32:35], v[144:147], v[184:187], v[32:35]
	v_mfma_f32_16x16x32_bf16 v[24:27], v[152:155], v[184:187], v[24:27]
	v_mfma_f32_16x16x32_bf16 v[16:19], v[144:147], v[192:195], v[16:19]
	v_mfma_f32_16x16x32_bf16 v[8:11], v[152:155], v[192:195], v[8:11]
	v_mfma_f32_16x16x32_bf16 v[60:63], v[148:151], v[172:175], v[60:63]
	v_mfma_f32_16x16x32_bf16 v[56:59], v[156:159], v[172:175], v[56:59]
	v_mfma_f32_16x16x32_bf16 v[48:51], v[148:151], v[180:183], v[48:51]
	v_mfma_f32_16x16x32_bf16 v[40:43], v[156:159], v[180:183], v[40:43]
	v_mfma_f32_16x16x32_bf16 v[32:35], v[148:151], v[188:191], v[32:35]
	v_mfma_f32_16x16x32_bf16 v[24:27], v[156:159], v[188:191], v[24:27]
	v_mfma_f32_16x16x32_bf16 v[16:19], v[148:151], v[196:199], v[16:19]
	v_mfma_f32_16x16x32_bf16 v[8:11], v[156:159], v[196:199], v[8:11]
	s_barrier
	s_setprio 0
	s_add_u32 s16, s34, 0xb0000
	s_addc_u32 s17, s35, 0
	s_add_i32 s20, s59, s40
	s_mov_b32 m0, s20
	s_nop 0
	global_load_lds_dwordx4 v132, s[16:17]
	s_add_i32 m0, s20, 0x2000
	s_nop 0
	global_load_lds_dwordx4 v128, s[16:17]
	s_add_u32 s16, s36, 0xb0000
	s_addc_u32 s17, s37, 0
	s_mov_b32 m0, s44
	s_nop 0
	global_load_lds_dwordx4 v134, s[16:17]
	s_mov_b32 m0, s45
	s_nop 0
	global_load_lds_dwordx4 v130, s[16:17]
	s_waitcnt vmcnt(10)
	s_setprio 1
	s_barrier
	v_mfma_f32_16x16x32_bf16 v[52:55], v[202:205], v[168:171], v[52:55]
	v_mfma_f32_16x16x32_bf16 v[44:47], v[210:213], v[168:171], v[44:47]
	v_mfma_f32_16x16x32_bf16 v[36:39], v[202:205], v[176:179], v[36:39]
	v_mfma_f32_16x16x32_bf16 v[28:31], v[210:213], v[176:179], v[28:31]
	v_mfma_f32_16x16x32_bf16 v[20:23], v[202:205], v[184:187], v[20:23]
	v_mfma_f32_16x16x32_bf16 v[12:15], v[210:213], v[184:187], v[12:15]
	v_mfma_f32_16x16x32_bf16 v[4:7], v[202:205], v[192:195], v[4:7]
	v_mfma_f32_16x16x32_bf16 v[0:3], v[210:213], v[192:195], v[0:3]
	v_mfma_f32_16x16x32_bf16 v[52:55], v[206:209], v[172:175], v[52:55]
	v_mfma_f32_16x16x32_bf16 v[44:47], v[214:217], v[172:175], v[44:47]
	v_mfma_f32_16x16x32_bf16 v[36:39], v[206:209], v[180:183], v[36:39]
	v_mfma_f32_16x16x32_bf16 v[28:31], v[214:217], v[180:183], v[28:31]
	v_mfma_f32_16x16x32_bf16 v[20:23], v[206:209], v[188:191], v[20:23]
	v_mfma_f32_16x16x32_bf16 v[12:15], v[214:217], v[188:191], v[12:15]
	v_mfma_f32_16x16x32_bf16 v[4:7], v[206:209], v[196:199], v[4:7]
	v_mfma_f32_16x16x32_bf16 v[0:3], v[214:217], v[196:199], v[0:3]
	s_add_i32 s20, 0, 0x18000
	v_add_u32_e32 v156, s20, v164
	s_barrier
	s_setprio 0
	ds_read_b128 v[144:147], v156
	ds_read_b128 v[148:151], v156 offset:1024
	ds_read_b128 v[152:155], v156 offset:2048
	ds_read_b128 v[156:159], v156 offset:3072
	ds_read_b128 v[168:171], v166 offset:32768
	ds_read_b128 v[172:175], v166 offset:33792
	ds_read_b128 v[176:179], v166 offset:34816
	ds_read_b128 v[180:183], v166 offset:35840
	ds_read_b128 v[184:187], v166 offset:36864
	ds_read_b128 v[188:191], v166 offset:37888
	ds_read_b128 v[192:195], v166 offset:38912
	ds_read_b128 v[196:199], v166 offset:39936
	s_waitcnt lgkmcnt(8)
	s_waitcnt vmcnt(8)
	s_setprio 1
	s_barrier
	s_waitcnt lgkmcnt(0)
	v_mfma_f32_16x16x32_bf16 v[124:127], v[144:147], v[168:171], v[124:127]
	v_mfma_f32_16x16x32_bf16 v[120:123], v[152:155], v[168:171], v[120:123]
	v_mfma_f32_16x16x32_bf16 v[116:119], v[144:147], v[176:179], v[116:119]
	v_mfma_f32_16x16x32_bf16 v[104:107], v[152:155], v[176:179], v[104:107]
	v_mfma_f32_16x16x32_bf16 v[96:99], v[144:147], v[184:187], v[96:99]
	v_mfma_f32_16x16x32_bf16 v[88:91], v[152:155], v[184:187], v[88:91]
	v_mfma_f32_16x16x32_bf16 v[80:83], v[144:147], v[192:195], v[80:83]
	v_mfma_f32_16x16x32_bf16 v[72:75], v[152:155], v[192:195], v[72:75]
	v_mfma_f32_16x16x32_bf16 v[124:127], v[148:151], v[172:175], v[124:127]
	v_mfma_f32_16x16x32_bf16 v[120:123], v[156:159], v[172:175], v[120:123]
	v_mfma_f32_16x16x32_bf16 v[116:119], v[148:151], v[180:183], v[116:119]
	v_mfma_f32_16x16x32_bf16 v[104:107], v[156:159], v[180:183], v[104:107]
	v_mfma_f32_16x16x32_bf16 v[96:99], v[148:151], v[188:191], v[96:99]
	v_mfma_f32_16x16x32_bf16 v[88:91], v[156:159], v[188:191], v[88:91]
	v_mfma_f32_16x16x32_bf16 v[80:83], v[148:151], v[196:199], v[80:83]
	v_mfma_f32_16x16x32_bf16 v[72:75], v[156:159], v[196:199], v[72:75]
	s_barrier
	s_setprio 0
	s_add_i32 s21, 0, 0x1c000
	s_add_i32 s16, s20, s40
	v_add_u32_e32 v214, s21, v164
	s_add_u32 s8, s34, 0x80
	s_addc_u32 s9, s35, 0
	s_mov_b32 m0, s16
	ds_read_b128 v[202:205], v214
	ds_read_b128 v[206:209], v214 offset:1024
	ds_read_b128 v[210:213], v214 offset:2048
	ds_read_b128 v[214:217], v214 offset:3072
	global_load_lds_dwordx4 v132, s[8:9]
	s_add_i32 m0, s16, 0x2000
	s_nop 0
	global_load_lds_dwordx4 v128, s[8:9]
	s_waitcnt vmcnt(8)
	s_setprio 1
	s_barrier
; #define PG8_STAGE(bufoff, gbase, voff) do { _Pragma("unroll") for (int _i = 0; _i < 2; ++_i) \
;         __builtin_amdgcn_global_load_lds((const unsigned*)((const char*)(gbase) + (voff)[_i]), (LAS unsigned*)(lds + (bufoff) + ldsw + _i * 8192), 16, 0, 0); } while (0)
; #define PG8_LDA(dst, b, h) do { _Pragma("unroll") for (int m = 0; m < 4; ++m) _Pragma("unroll") for (int k = 0; k < 2; ++k) dst[m][k] = *(const LAS bf16x8*)(lds + PG8_SA(b, h) + aoff + m * 2048 + k * 1024); } while (0)
; #define PG8_LDB(dst, b, h) do { _Pragma("unroll") for (int n = 0; n < 2; ++n) _Pragma("unroll") for (int k = 0; k < 2; ++k) dst[n][k] = *(const LAS bf16x8*)(lds + PG8_SB(b, h) + boff + n * 2048 + k * 1024); } while (0)
; #define PG8_MMA(ai, bj, At, Bt) do { __builtin_amdgcn_s_setprio(1); _Pragma("unroll") for (int m = 0; m < 4; ++m) _Pragma("unroll") for (int n = 0; n < 2; ++n) _Pragma("unroll") for (int k = 0; k < 2; ++k) \
;         acc[ai][bj][m][n] = __builtin_amdgcn_mfma_f32_16x16x32_bf16(Bt[n][k], At[m][k], acc[ai][bj][m][n], 0, 0, 0); __builtin_amdgcn_s_setprio(0); } while (0)
; #define PG8_WAIT_V(n) asm volatile("s_waitcnt vmcnt(" #n ")" ::: "memory")
; #define PG8_WAIT_L(n) asm volatile("s_waitcnt lgkmcnt(" #n ")" ::: "memory")
; #define PG8_BAR __builtin_amdgcn_s_barrier()
; template <class Epi, class Sched>
; __device__ __forceinline__ void gemm_phase(LAS unsigned char* lds, const Gemm g, const Sched& S, const Epi& E) {
;     ...
;     for (;;) {
;         const bool has_next = S.next(ui + 1, nxt);
;         const char* nA = has_next ? (const char*)g.A + (size_t)nxt.pm * tstep : cA; const char* nB = has_next ? (const char*)g.Bt + (size_t)nxt.pn * tstep : cB;
;     ...
;             PG8_WAIT_V(6); PG8_BAR; PG8_MMA(1, 1, At, B1); PG8_BAR;
;             PG8_LDB(B0, 1, 0); PG8_SCHED; PG8_LDA(At, 1, 0); PG8_STAGE(PG8_SA(0, 1), a2 + hstep, voffA);
;             PG8_WAIT_L(8); PG8_BAR; PG8_WAIT_L(0); PG8_MMA(0, 0, At, B0); PG8_BAR; PG8_SCHED;
;             PG8_LDB(B1, 1, 1); PG8_STAGE(PG8_SB(1, 0), b3, voffB);
;             PG8_BAR; PG8_WAIT_L(0); PG8_MMA(0, 1, At, B1); PG8_BAR;
;             PG8_LDA(At, 1, 1); PG8_STAGE(PG8_SA(1, 0), a3, voffA);
;             PG8_BAR; PG8_WAIT_L(0); PG8_MMA(1, 0, At, B0); PG8_BAR; PG8_SCHED;
;             PG8_STAGE(PG8_SB(1, 1), b3 + hstep, voffB);
;             PG8_WAIT_V(6); PG8_BAR; PG8_MMA(1, 1, At, B1); PG8_BAR;
	s_waitcnt lgkmcnt(0)
	v_mfma_f32_16x16x32_bf16 v[112:115], v[202:205], v[168:171], v[112:115]
	v_mfma_f32_16x16x32_bf16 v[108:111], v[210:213], v[168:171], v[108:111]
	v_mfma_f32_16x16x32_bf16 v[100:103], v[202:205], v[176:179], v[100:103]
	v_mfma_f32_16x16x32_bf16 v[92:95], v[210:213], v[176:179], v[92:95]
	v_mfma_f32_16x16x32_bf16 v[84:87], v[202:205], v[184:187], v[84:87]
	v_mfma_f32_16x16x32_bf16 v[76:79], v[210:213], v[184:187], v[76:79]
	v_mfma_f32_16x16x32_bf16 v[68:71], v[202:205], v[192:195], v[68:71]
	v_mfma_f32_16x16x32_bf16 v[64:67], v[210:213], v[192:195], v[64:67]
	v_mfma_f32_16x16x32_bf16 v[112:115], v[206:209], v[172:175], v[112:115]
	v_mfma_f32_16x16x32_bf16 v[108:111], v[214:217], v[172:175], v[108:111]
	v_mfma_f32_16x16x32_bf16 v[100:103], v[206:209], v[180:183], v[100:103]
	v_mfma_f32_16x16x32_bf16 v[92:95], v[214:217], v[180:183], v[92:95]
	v_mfma_f32_16x16x32_bf16 v[84:87], v[206:209], v[188:191], v[84:87]
	v_mfma_f32_16x16x32_bf16 v[76:79], v[214:217], v[188:191], v[76:79]
	v_mfma_f32_16x16x32_bf16 v[68:71], v[206:209], v[196:199], v[68:71]
	v_mfma_f32_16x16x32_bf16 v[64:67], v[214:217], v[196:199], v[64:67]
	s_mov_b32 m0, s52
	s_add_u32 s8, s36, 0x80
	s_addc_u32 s9, s37, 0
	s_barrier
	s_setprio 0
	ds_read_b128 v[168:171], v166 offset:49152
	ds_read_b128 v[172:175], v166 offset:50176
	ds_read_b128 v[176:179], v166 offset:51200
	ds_read_b128 v[180:183], v166 offset:52224
	ds_read_b128 v[184:187], v166 offset:53248
	ds_read_b128 v[188:191], v166 offset:54272
	ds_read_b128 v[192:195], v166 offset:55296
	ds_read_b128 v[196:199], v166 offset:56320
	global_load_lds_dwordx4 v134, s[8:9]
	s_mov_b32 m0, s53
	s_nop 0
	global_load_lds_dwordx4 v130, s[8:9]
	s_setprio 1
	s_barrier
	s_waitcnt lgkmcnt(0)
	v_mfma_f32_16x16x32_bf16 v[60:63], v[144:147], v[168:171], v[60:63]
	v_mfma_f32_16x16x32_bf16 v[56:59], v[152:155], v[168:171], v[56:59]
	v_mfma_f32_16x16x32_bf16 v[48:51], v[144:147], v[176:179], v[48:51]
	v_mfma_f32_16x16x32_bf16 v[40:43], v[152:155], v[176:179], v[40:43]
	v_mfma_f32_16x16x32_bf16 v[32:35], v[144:147], v[184:187], v[32:35]
	v_mfma_f32_16x16x32_bf16 v[24:27], v[152:155], v[184:187], v[24:27]
	v_mfma_f32_16x16x32_bf16 v[16:19], v[144:147], v[192:195], v[16:19]
	v_mfma_f32_16x16x32_bf16 v[8:11], v[152:155], v[192:195], v[8:11]
	v_mfma_f32_16x16x32_bf16 v[60:63], v[148:151], v[172:175], v[60:63]
	v_mfma_f32_16x16x32_bf16 v[56:59], v[156:159], v[172:175], v[56:59]
	v_mfma_f32_16x16x32_bf16 v[48:51], v[148:151], v[180:183], v[48:51]
	v_mfma_f32_16x16x32_bf16 v[40:43], v[156:159], v[180:183], v[40:43]
	v_mfma_f32_16x16x32_bf16 v[32:35], v[148:151], v[188:191], v[32:35]
	v_mfma_f32_16x16x32_bf16 v[24:27], v[156:159], v[188:191], v[24:27]
	v_mfma_f32_16x16x32_bf16 v[16:19], v[148:151], v[196:199], v[16:19]
	v_mfma_f32_16x16x32_bf16 v[8:11], v[156:159], v[196:199], v[8:11]
	s_barrier
	s_setprio 0
	s_add_u32 s16, s34, 0xb0080
	s_addc_u32 s17, s35, 0
	s_add_i32 s20, s21, s40
	s_mov_b32 m0, s20
	s_nop 0
	global_load_lds_dwordx4 v132, s[16:17]
	s_add_i32 m0, s20, 0x2000
	s_nop 0
	global_load_lds_dwordx4 v128, s[16:17]
	s_waitcnt vmcnt(8)
	s_setprio 1
	s_barrier
	v_mfma_f32_16x16x32_bf16 v[52:55], v[202:205], v[168:171], v[52:55]
	v_mfma_f32_16x16x32_bf16 v[44:47], v[210:213], v[168:171], v[44:47]
	v_mfma_f32_16x16x32_bf16 v[36:39], v[202:205], v[176:179], v[36:39]
	v_mfma_f32_16x16x32_bf16 v[28:31], v[210:213], v[176:179], v[28:31]
	v_mfma_f32_16x16x32_bf16 v[20:23], v[202:205], v[184:187], v[20:23]
	v_mfma_f32_16x16x32_bf16 v[12:15], v[210:213], v[184:187], v[12:15]
	v_mfma_f32_16x16x32_bf16 v[4:7], v[202:205], v[192:195], v[4:7]
	v_mfma_f32_16x16x32_bf16 v[0:3], v[210:213], v[192:195], v[0:3]
	v_mfma_f32_16x16x32_bf16 v[52:55], v[206:209], v[172:175], v[52:55]
	v_mfma_f32_16x16x32_bf16 v[44:47], v[214:217], v[172:175], v[44:47]
	v_mfma_f32_16x16x32_bf16 v[36:39], v[206:209], v[180:183], v[36:39]
	v_mfma_f32_16x16x32_bf16 v[28:31], v[214:217], v[180:183], v[28:31]
	v_mfma_f32_16x16x32_bf16 v[20:23], v[206:209], v[188:191], v[20:23]
	v_mfma_f32_16x16x32_bf16 v[12:15], v[214:217], v[188:191], v[12:15]
	v_mfma_f32_16x16x32_bf16 v[4:7], v[206:209], v[196:199], v[4:7]
	v_mfma_f32_16x16x32_bf16 v[0:3], v[214:217], v[196:199], v[0:3]
	s_add_i32 s68, s68, 2
	s_add_u32 s0, s0, 0x100
	s_addc_u32 s67, s67, 0
	s_cmp_gt_u32 s68, 41
	s_mov_b64 s[26:27], s[28:29]
	s_barrier
	s_setprio 0
	s_cbranch_scc0 .LBB0_305
	s_lshl_b32 s0, s66, 8
	v_mov_b32_e32 v145, v163
	v_mov_b32_e32 v144, v162
	s_cmpk_lt_i32 s66, 0x100
	s_cbranch_scc0 .LBB0_308
	s_ashr_i32 s29, s0, 31
	s_mov_b32 s28, s0
	s_lshl_b64 s[16:17], s[28:29], 12
	v_readlane_b32 s80, v254, 23
	v_readlane_b32 s81, v254, 24
	s_add_u32 s26, s80, s16
	v_readlane_b32 s82, v254, 25
	v_readlane_b32 s83, v254, 26
	v_readlane_b32 s84, v254, 27
	v_readlane_b32 s85, v254, 28
	v_readlane_b32 s86, v254, 29
	v_readlane_b32 s87, v254, 30
	v_readlane_b32 s88, v254, 31
	v_readlane_b32 s89, v254, 32
	v_readlane_b32 s90, v254, 33
	v_readlane_b32 s91, v254, 34
	v_readlane_b32 s92, v254, 35
	v_readlane_b32 s93, v254, 36
	v_readlane_b32 s94, v254, 37
	v_readlane_b32 s95, v254, 38
	s_addc_u32 s27, s81, s17
	s_cbranch_execnz .LBB0_297
	s_branch .LBB0_296

; #define PG8_STAGE(bufoff, gbase, voff) do { _Pragma("unroll") for (int _i = 0; _i < 2; ++_i) \
;         __builtin_amdgcn_global_load_lds((const unsigned*)((const char*)(gbase) + (voff)[_i]), (LAS unsigned*)(lds + (bufoff) + ldsw + _i * 8192), 16, 0, 0); } while (0)
; #define PG8_LDA(dst, b, h) do { _Pragma("unroll") for (int m = 0; m < 4; ++m) _Pragma("unroll") for (int k = 0; k < 2; ++k) dst[m][k] = *(const LAS bf16x8*)(lds + PG8_SA(b, h) + aoff + m * 2048 + k * 1024); } while (0)
; #define PG8_LDB(dst, b, h) do { _Pragma("unroll") for (int n = 0; n < 2; ++n) _Pragma("unroll") for (int k = 0; k < 2; ++k) dst[n][k] = *(const LAS bf16x8*)(lds + PG8_SB(b, h) + boff + n * 2048 + k * 1024); } while (0)
; #define PG8_MMA(ai, bj, At, Bt) do { __builtin_amdgcn_s_setprio(1); _Pragma("unroll") for (int m = 0; m < 4; ++m) _Pragma("unroll") for (int n = 0; n < 2; ++n) _Pragma("unroll") for (int k = 0; k < 2; ++k) \
;         acc[ai][bj][m][n] = __builtin_amdgcn_mfma_f32_16x16x32_bf16(Bt[n][k], At[m][k], acc[ai][bj][m][n], 0, 0, 0); __builtin_amdgcn_s_setprio(0); } while (0)
; #define PG8_WAIT_L(n) asm volatile("s_waitcnt lgkmcnt(" #n ")" ::: "memory")
; template <class Epi, class Sched>
; __device__ __forceinline__ void gemm_phase(LAS unsigned char* lds, const Gemm g, const Sched& S, const Epi& E) {
;     ...
;         const bool has_next = S.next(ui + 1, nxt);
;         const char* nA = has_next ? (const char*)g.A + (size_t)nxt.pm * tstep : cA; const char* nB = has_next ? (const char*)g.Bt + (size_t)nxt.pn * tstep : cB;
;         for (int t = 0; t < nt; t += 2) {
;             const bool last = (t == nt - 2);
;             const char* a1 = cA + (size_t)(t + 1) * kstep;
;             const char* a2 = last ? nA : cA + (size_t)(t + 2) * kstep; const char* b2 = last ? nB : cB + (size_t)(t + 2) * kstep;
;             const char* a3 = a2 + kstep; const char* b3 = b2 + kstep;
;             PG8_LDB(B0, 0, 0); PG8_SCHED; PG8_LDA(At, 0, 0); PG8_STAGE(PG8_SA(1, 1), a1 + hstep, voffA);
;             PG8_WAIT_L(8); PG8_BAR; PG8_WAIT_L(0); PG8_MMA(0, 0, At, B0); PG8_BAR; PG8_SCHED;
;             PG8_LDB(B1, 0, 1); PG8_STAGE(PG8_SB(0, 0), b2, voffB);
;             PG8_BAR; PG8_WAIT_L(0); PG8_MMA(0, 1, At, B1); PG8_BAR;
;             PG8_LDA(At, 0, 1); PG8_STAGE(PG8_SA(0, 0), a2, voffA);
;             PG8_BAR; PG8_WAIT_L(0); PG8_MMA(1, 0, At, B0); PG8_BAR; PG8_SCHED;
.LBB0_577:
	s_ashr_i32 s21, s20, 31
	v_cmp_lt_i64_e32 vcc, s[22:23], v[156:157]
	s_lshl_b64 s[22:23], s[20:21], 19
	s_add_u32 s22, s96, s22
	s_addc_u32 s23, s97, s23
	s_and_b64 s[24:25], vcc, exec
	s_cselect_b32 s5, s23, s7
	s_cselect_b32 s21, s22, s6
	s_ashr_i32 s19, s18, 31
	s_lshl_b64 s[24:25], s[18:19], 19
	s_add_u32 s24, s31, s24
	s_addc_u32 s25, s33, s25
	s_and_b64 s[28:29], vcc, exec
	s_cselect_b32 s19, s25, s27
	s_cselect_b32 s53, s24, s26
	s_add_u32 s6, s6, 0x40080
	s_addc_u32 s7, s7, 0
	s_add_u32 s54, s26, 0x100
	s_addc_u32 s55, s27, 0
	s_mov_b32 s56, -2
	s_waitcnt lgkmcnt(0)
	ds_read_b128 v[128:131], v167
	ds_read_b128 v[132:135], v167 offset:1024
	ds_read_b128 v[136:139], v167 offset:2048
	ds_read_b128 v[160:163], v167 offset:3072
	s_add_u32 s26, s6, 0xfffc0080
	s_addc_u32 s27, s7, -1
	s_cmp_eq_u32 s56, 12
	s_cselect_b32 s29, s5, s27
	s_cselect_b32 s28, s21, s26
	s_cselect_b32 s27, s19, s55
	s_cselect_b32 s26, s53, s54
	s_add_i32 m0, s37, 0xc000
	ds_read_b128 v[170:173], v168
	ds_read_b128 v[174:177], v168 offset:1024
	ds_read_b128 v[178:181], v168 offset:2048
	ds_read_b128 v[182:185], v168 offset:3072
	ds_read_b128 v[186:189], v168 offset:4096
	ds_read_b128 v[190:193], v168 offset:5120
	ds_read_b128 v[194:197], v168 offset:6144
	ds_read_b128 v[202:205], v168 offset:7168
	global_load_lds_dwordx4 v152, s[6:7]
	s_add_i32 m0, s37, 0xe000
	s_nop 0
	global_load_lds_dwordx4 v154, s[6:7]
	s_waitcnt lgkmcnt(8)
	s_waitcnt vmcnt(8)
	s_setprio 1
	s_barrier
	s_waitcnt lgkmcnt(0)
	v_mfma_f32_16x16x32_bf16 v[124:127], v[128:131], v[170:173], 0
	v_mfma_f32_16x16x32_bf16 v[120:123], v[136:139], v[170:173], 0
	v_mfma_f32_16x16x32_bf16 v[108:111], v[128:131], v[178:181], 0
	v_mfma_f32_16x16x32_bf16 v[104:107], v[136:139], v[178:181], 0
	v_mfma_f32_16x16x32_bf16 v[92:95], v[128:131], v[186:189], 0
	v_mfma_f32_16x16x32_bf16 v[88:91], v[136:139], v[186:189], 0
	v_mfma_f32_16x16x32_bf16 v[76:79], v[128:131], v[194:197], 0
	v_mfma_f32_16x16x32_bf16 v[72:75], v[136:139], v[194:197], 0
	v_mfma_f32_16x16x32_bf16 v[124:127], v[132:135], v[174:177], v[124:127]
	v_mfma_f32_16x16x32_bf16 v[120:123], v[160:163], v[174:177], v[120:123]
	v_mfma_f32_16x16x32_bf16 v[108:111], v[132:135], v[182:185], v[108:111]
	v_mfma_f32_16x16x32_bf16 v[104:107], v[160:163], v[182:185], v[104:107]
	v_mfma_f32_16x16x32_bf16 v[92:95], v[132:135], v[190:193], v[92:95]
	v_mfma_f32_16x16x32_bf16 v[88:91], v[160:163], v[190:193], v[88:91]
	v_mfma_f32_16x16x32_bf16 v[76:79], v[132:135], v[202:205], v[76:79]
	v_mfma_f32_16x16x32_bf16 v[72:75], v[160:163], v[202:205], v[72:75]
	s_barrier
	s_setprio 0
	s_add_i32 s57, s48, s34
	s_mov_b32 m0, s57
	ds_read_b128 v[206:209], v169
	ds_read_b128 v[210:213], v169 offset:1024
	ds_read_b128 v[214:217], v169 offset:2048
	ds_read_b128 v[218:221], v169 offset:3072
	global_load_lds_dwordx4 v146, s[26:27]
	s_add_i32 m0, s57, 0x2000
	s_nop 0
	global_load_lds_dwordx4 v142, s[26:27]
	s_waitcnt vmcnt(8)
	s_setprio 1
	s_barrier
	s_waitcnt lgkmcnt(0)
	v_mfma_f32_16x16x32_bf16 v[116:119], v[206:209], v[170:173], 0
	v_mfma_f32_16x16x32_bf16 v[112:115], v[214:217], v[170:173], 0
	v_mfma_f32_16x16x32_bf16 v[100:103], v[206:209], v[178:181], 0
	v_mfma_f32_16x16x32_bf16 v[96:99], v[214:217], v[178:181], 0
	v_mfma_f32_16x16x32_bf16 v[84:87], v[206:209], v[186:189], 0
	v_mfma_f32_16x16x32_bf16 v[80:83], v[214:217], v[186:189], 0
	v_mfma_f32_16x16x32_bf16 v[68:71], v[206:209], v[194:197], 0
	v_mfma_f32_16x16x32_bf16 v[64:67], v[214:217], v[194:197], 0
	v_mfma_f32_16x16x32_bf16 v[116:119], v[210:213], v[174:177], v[116:119]
	v_mfma_f32_16x16x32_bf16 v[112:115], v[218:221], v[174:177], v[112:115]
	v_mfma_f32_16x16x32_bf16 v[100:103], v[210:213], v[182:185], v[100:103]
	v_mfma_f32_16x16x32_bf16 v[96:99], v[218:221], v[182:185], v[96:99]
	v_mfma_f32_16x16x32_bf16 v[84:87], v[210:213], v[190:193], v[84:87]
	v_mfma_f32_16x16x32_bf16 v[80:83], v[218:221], v[190:193], v[80:83]
	v_mfma_f32_16x16x32_bf16 v[68:71], v[210:213], v[202:205], v[68:71]
	v_mfma_f32_16x16x32_bf16 v[64:67], v[218:221], v[202:205], v[64:67]
	s_mov_b32 m0, s37
	v_lshl_add_u64 v[222:223], s[28:29], 0, v[148:149]
	s_barrier
	s_setprio 0
	ds_read_b128 v[170:173], v168 offset:16384
	ds_read_b128 v[174:177], v168 offset:17408
	ds_read_b128 v[178:181], v168 offset:18432
	ds_read_b128 v[182:185], v168 offset:19456
	ds_read_b128 v[186:189], v168 offset:20480
	ds_read_b128 v[190:193], v168 offset:21504
	ds_read_b128 v[194:197], v168 offset:22528
	ds_read_b128 v[202:205], v168 offset:23552
	global_load_lds_dwordx4 v148, s[28:29]
	v_lshl_add_u64 v[224:225], s[28:29], 0, v[144:145]
	s_mov_b32 m0, s38
	s_nop 0
	global_load_lds_dwordx4 v144, s[28:29]
	s_setprio 1
	s_barrier
	s_waitcnt lgkmcnt(0)
	v_mfma_f32_16x16x32_bf16 v[60:63], v[128:131], v[170:173], 0
	v_mfma_f32_16x16x32_bf16 v[56:59], v[136:139], v[170:173], 0
	v_mfma_f32_16x16x32_bf16 v[44:47], v[128:131], v[178:181], 0
	v_mfma_f32_16x16x32_bf16 v[40:43], v[136:139], v[178:181], 0
	v_mfma_f32_16x16x32_bf16 v[28:31], v[128:131], v[186:189], 0
	v_mfma_f32_16x16x32_bf16 v[24:27], v[136:139], v[186:189], 0
	v_mfma_f32_16x16x32_bf16 v[12:15], v[128:131], v[194:197], 0
	v_mfma_f32_16x16x32_bf16 v[8:11], v[136:139], v[194:197], 0
	v_mfma_f32_16x16x32_bf16 v[60:63], v[132:135], v[174:177], v[60:63]
	v_mfma_f32_16x16x32_bf16 v[56:59], v[160:163], v[174:177], v[56:59]
	v_mfma_f32_16x16x32_bf16 v[44:47], v[132:135], v[182:185], v[44:47]
	v_mfma_f32_16x16x32_bf16 v[40:43], v[160:163], v[182:185], v[40:43]
	v_mfma_f32_16x16x32_bf16 v[28:31], v[132:135], v[190:193], v[28:31]
	v_mfma_f32_16x16x32_bf16 v[24:27], v[160:163], v[190:193], v[24:27]
	v_mfma_f32_16x16x32_bf16 v[12:15], v[132:135], v[202:205], v[12:15]
	v_mfma_f32_16x16x32_bf16 v[8:11], v[160:163], v[202:205], v[8:11]
	s_barrier
; #define PG8_STAGE(bufoff, gbase, voff) do { _Pragma("unroll") for (int _i = 0; _i < 2; ++_i) \
;         __builtin_amdgcn_global_load_lds((const unsigned*)((const char*)(gbase) + (voff)[_i]), (LAS unsigned*)(lds + (bufoff) + ldsw + _i * 8192), 16, 0, 0); } while (0)
; #define PG8_LDA(dst, b, h) do { _Pragma("unroll") for (int m = 0; m < 4; ++m) _Pragma("unroll") for (int k = 0; k < 2; ++k) dst[m][k] = *(const LAS bf16x8*)(lds + PG8_SA(b, h) + aoff + m * 2048 + k * 1024); } while (0)
; #define PG8_LDB(dst, b, h) do { _Pragma("unroll") for (int n = 0; n < 2; ++n) _Pragma("unroll") for (int k = 0; k < 2; ++k) dst[n][k] = *(const LAS bf16x8*)(lds + PG8_SB(b, h) + boff + n * 2048 + k * 1024); } while (0)
; #define PG8_MMA(ai, bj, At, Bt) do { __builtin_amdgcn_s_setprio(1); _Pragma("unroll") for (int m = 0; m < 4; ++m) _Pragma("unroll") for (int n = 0; n < 2; ++n) _Pragma("unroll") for (int k = 0; k < 2; ++k) \
;         acc[ai][bj][m][n] = __builtin_amdgcn_mfma_f32_16x16x32_bf16(Bt[n][k], At[m][k], acc[ai][bj][m][n], 0, 0, 0); __builtin_amdgcn_s_setprio(0); } while (0)
; #define PG8_WAIT_V(n) asm volatile("s_waitcnt vmcnt(" #n ")" ::: "memory")
; #define PG8_WAIT_L(n) asm volatile("s_waitcnt lgkmcnt(" #n ")" ::: "memory")
; #define PG8_BAR __builtin_amdgcn_s_barrier()
; #define PG8_SCHED __builtin_amdgcn_sched_barrier(0)
; template <class Epi, class Sched>
; __device__ __forceinline__ void gemm_phase(LAS unsigned char* lds, const Gemm g, const Sched& S, const Epi& E) {
;     ...
;             PG8_BAR; PG8_WAIT_L(0); PG8_MMA(1, 0, At, B0); PG8_BAR; PG8_SCHED;
;             PG8_STAGE(PG8_SB(0, 1), b2 + hstep, voffB);
;             PG8_WAIT_V(6); PG8_BAR; PG8_MMA(1, 1, At, B1); PG8_BAR;
;             PG8_LDB(B0, 1, 0); PG8_SCHED; PG8_LDA(At, 1, 0); PG8_STAGE(PG8_SA(0, 1), a2 + hstep, voffA);
;             PG8_WAIT_L(8); PG8_BAR; PG8_WAIT_L(0); PG8_MMA(0, 0, At, B0); PG8_BAR; PG8_SCHED;
;             PG8_LDB(B1, 1, 1); PG8_STAGE(PG8_SB(1, 0), b3, voffB);
;             PG8_BAR; PG8_WAIT_L(0); PG8_MMA(0, 1, At, B1); PG8_BAR;
;             PG8_LDA(At, 1, 1); PG8_STAGE(PG8_SA(1, 0), a3, voffA);
	s_setprio 0
	s_add_u32 s58, s26, 0x40000
	s_addc_u32 s59, s27, 0
	s_add_i32 s57, s49, s34
	s_mov_b32 m0, s57
	s_nop 0
	global_load_lds_dwordx4 v146, s[58:59]
	s_add_i32 m0, s57, 0x2000
	s_nop 0
	global_load_lds_dwordx4 v142, s[58:59]
	s_add_u32 s28, s28, 0x40000
	s_addc_u32 s29, s29, 0
	s_mov_b32 m0, s39
	s_nop 0
	global_load_lds_dwordx4 v148, s[28:29]
	s_mov_b32 m0, s40
	s_nop 0
	global_load_lds_dwordx4 v144, s[28:29]
	s_waitcnt vmcnt(10)
	s_setprio 1
	s_barrier
	v_mfma_f32_16x16x32_bf16 v[52:55], v[206:209], v[170:173], 0
	v_mfma_f32_16x16x32_bf16 v[48:51], v[214:217], v[170:173], 0
	v_mfma_f32_16x16x32_bf16 v[36:39], v[206:209], v[178:181], 0
	v_mfma_f32_16x16x32_bf16 v[32:35], v[214:217], v[178:181], 0
	v_mfma_f32_16x16x32_bf16 v[20:23], v[206:209], v[186:189], 0
	v_mfma_f32_16x16x32_bf16 v[16:19], v[214:217], v[186:189], 0
	v_mfma_f32_16x16x32_bf16 v[4:7], v[206:209], v[194:197], 0
	v_mfma_f32_16x16x32_bf16 v[0:3], v[214:217], v[194:197], 0
	v_mfma_f32_16x16x32_bf16 v[52:55], v[210:213], v[174:177], v[52:55]
	v_mfma_f32_16x16x32_bf16 v[48:51], v[218:221], v[174:177], v[48:51]
	v_mfma_f32_16x16x32_bf16 v[36:39], v[210:213], v[182:185], v[36:39]
	v_mfma_f32_16x16x32_bf16 v[32:35], v[218:221], v[182:185], v[32:35]
	v_mfma_f32_16x16x32_bf16 v[20:23], v[210:213], v[190:193], v[20:23]
	v_mfma_f32_16x16x32_bf16 v[16:19], v[218:221], v[190:193], v[16:19]
	v_mfma_f32_16x16x32_bf16 v[4:7], v[210:213], v[202:205], v[4:7]
	v_mfma_f32_16x16x32_bf16 v[0:3], v[218:221], v[202:205], v[0:3]
	s_add_i32 s57, 0, 0x18000
	v_add_u32_e32 v150, s57, v166
	s_barrier
	s_setprio 0
	ds_read_b128 v[128:131], v150
	ds_read_b128 v[132:135], v150 offset:1024
	ds_read_b128 v[136:139], v150 offset:2048
	ds_read_b128 v[160:163], v150 offset:3072
	ds_read_b128 v[170:173], v168 offset:32768
	ds_read_b128 v[174:177], v168 offset:33792
	ds_read_b128 v[178:181], v168 offset:34816
	ds_read_b128 v[182:185], v168 offset:35840
	ds_read_b128 v[186:189], v168 offset:36864
	ds_read_b128 v[190:193], v168 offset:37888
	ds_read_b128 v[194:197], v168 offset:38912
	ds_read_b128 v[202:205], v168 offset:39936
	s_waitcnt lgkmcnt(8)
	s_waitcnt vmcnt(8)
	s_setprio 1
	s_barrier
	s_waitcnt lgkmcnt(0)
	v_mfma_f32_16x16x32_bf16 v[124:127], v[128:131], v[170:173], v[124:127]
	v_mfma_f32_16x16x32_bf16 v[120:123], v[136:139], v[170:173], v[120:123]
	v_mfma_f32_16x16x32_bf16 v[108:111], v[128:131], v[178:181], v[108:111]
	v_mfma_f32_16x16x32_bf16 v[104:107], v[136:139], v[178:181], v[104:107]
	v_mfma_f32_16x16x32_bf16 v[92:95], v[128:131], v[186:189], v[92:95]
	v_mfma_f32_16x16x32_bf16 v[88:91], v[136:139], v[186:189], v[88:91]
	v_mfma_f32_16x16x32_bf16 v[76:79], v[128:131], v[194:197], v[76:79]
	v_mfma_f32_16x16x32_bf16 v[72:75], v[136:139], v[194:197], v[72:75]
	v_mfma_f32_16x16x32_bf16 v[124:127], v[132:135], v[174:177], v[124:127]
	v_mfma_f32_16x16x32_bf16 v[120:123], v[160:163], v[174:177], v[120:123]
	v_mfma_f32_16x16x32_bf16 v[108:111], v[132:135], v[182:185], v[108:111]
	v_mfma_f32_16x16x32_bf16 v[104:107], v[160:163], v[182:185], v[104:107]
	v_mfma_f32_16x16x32_bf16 v[92:95], v[132:135], v[190:193], v[92:95]
	v_mfma_f32_16x16x32_bf16 v[88:91], v[160:163], v[190:193], v[88:91]
	v_mfma_f32_16x16x32_bf16 v[76:79], v[132:135], v[202:205], v[76:79]
	v_mfma_f32_16x16x32_bf16 v[72:75], v[160:163], v[202:205], v[72:75]
	s_barrier
	s_setprio 0
	s_add_i32 s28, 0, 0x1c000
	s_add_i32 s29, s57, s34
	v_add_u32_e32 v150, s28, v166
	s_add_u32 s0, s26, 0x80
	s_addc_u32 s1, s27, 0
	s_mov_b32 m0, s29
	ds_read_b128 v[206:209], v150
	ds_read_b128 v[210:213], v150 offset:1024
	ds_read_b128 v[214:217], v150 offset:2048
	ds_read_b128 v[218:221], v150 offset:3072
	global_load_lds_dwordx4 v146, s[0:1]
	s_add_i32 m0, s29, 0x2000
	s_nop 0
	global_load_lds_dwordx4 v142, s[0:1]
	s_waitcnt vmcnt(8)
	s_setprio 1
	s_barrier
	s_waitcnt lgkmcnt(0)
	v_mfma_f32_16x16x32_bf16 v[116:119], v[206:209], v[170:173], v[116:119]
	v_mfma_f32_16x16x32_bf16 v[112:115], v[214:217], v[170:173], v[112:115]
	v_mfma_f32_16x16x32_bf16 v[100:103], v[206:209], v[178:181], v[100:103]
	v_mfma_f32_16x16x32_bf16 v[96:99], v[214:217], v[178:181], v[96:99]
	v_mfma_f32_16x16x32_bf16 v[84:87], v[206:209], v[186:189], v[84:87]
	v_mfma_f32_16x16x32_bf16 v[80:83], v[214:217], v[186:189], v[80:83]
	v_mfma_f32_16x16x32_bf16 v[68:71], v[206:209], v[194:197], v[68:71]
	v_mfma_f32_16x16x32_bf16 v[64:67], v[214:217], v[194:197], v[64:67]
	v_mfma_f32_16x16x32_bf16 v[116:119], v[210:213], v[174:177], v[116:119]
	v_mfma_f32_16x16x32_bf16 v[112:115], v[218:221], v[174:177], v[112:115]
	v_mfma_f32_16x16x32_bf16 v[100:103], v[210:213], v[182:185], v[100:103]
	v_mfma_f32_16x16x32_bf16 v[96:99], v[218:221], v[182:185], v[96:99]
	v_mfma_f32_16x16x32_bf16 v[84:87], v[210:213], v[190:193], v[84:87]
	v_mfma_f32_16x16x32_bf16 v[80:83], v[218:221], v[190:193], v[80:83]
	v_mfma_f32_16x16x32_bf16 v[68:71], v[210:213], v[202:205], v[68:71]
	v_mfma_f32_16x16x32_bf16 v[64:67], v[218:221], v[202:205], v[64:67]
	s_mov_b32 m0, s44
	s_mov_b64 s[0:1], 0x80
	v_lshl_add_u64 v[140:141], v[222:223], 0, s[0:1]
	s_barrier
	s_setprio 0
	ds_read_b128 v[170:173], v168 offset:49152
	ds_read_b128 v[174:177], v168 offset:50176
	ds_read_b128 v[178:181], v168 offset:51200
	ds_read_b128 v[182:185], v168 offset:52224
	ds_read_b128 v[186:189], v168 offset:53248
	ds_read_b128 v[190:193], v168 offset:54272
	ds_read_b128 v[194:197], v168 offset:55296
	ds_read_b128 v[202:205], v168 offset:56320
	global_load_lds_dwordx4 v[140:141], off
	v_lshl_add_u64 v[140:141], v[224:225], 0, s[0:1]
	s_mov_b32 m0, s45
	s_nop 0
	global_load_lds_dwordx4 v[140:141], off
	s_setprio 1
	s_barrier
; #define PG8_STAGE(bufoff, gbase, voff) do { _Pragma("unroll") for (int _i = 0; _i < 2; ++_i) \
;         __builtin_amdgcn_global_load_lds((const unsigned*)((const char*)(gbase) + (voff)[_i]), (LAS unsigned*)(lds + (bufoff) + ldsw + _i * 8192), 16, 0, 0); } while (0)
; #define PG8_LDA(dst, b, h) do { _Pragma("unroll") for (int m = 0; m < 4; ++m) _Pragma("unroll") for (int k = 0; k < 2; ++k) dst[m][k] = *(const LAS bf16x8*)(lds + PG8_SA(b, h) + aoff + m * 2048 + k * 1024); } while (0)
; #define PG8_LDB(dst, b, h) do { _Pragma("unroll") for (int n = 0; n < 2; ++n) _Pragma("unroll") for (int k = 0; k < 2; ++k) dst[n][k] = *(const LAS bf16x8*)(lds + PG8_SB(b, h) + boff + n * 2048 + k * 1024); } while (0)
; #define PG8_MMA(ai, bj, At, Bt) do { __builtin_amdgcn_s_setprio(1); _Pragma("unroll") for (int m = 0; m < 4; ++m) _Pragma("unroll") for (int n = 0; n < 2; ++n) _Pragma("unroll") for (int k = 0; k < 2; ++k) \
;         acc[ai][bj][m][n] = __builtin_amdgcn_mfma_f32_16x16x32_bf16(Bt[n][k], At[m][k], acc[ai][bj][m][n], 0, 0, 0); __builtin_amdgcn_s_setprio(0); } while (0)
; #define PG8_WAIT_V(n) asm volatile("s_waitcnt vmcnt(" #n ")" ::: "memory")
; #define PG8_WAIT_L(n) asm volatile("s_waitcnt lgkmcnt(" #n ")" ::: "memory")
; #define PG8_BAR __builtin_amdgcn_s_barrier()
; #define PG8_SCHED __builtin_amdgcn_sched_barrier(0)
; template <class Epi, class Sched>
; __device__ __forceinline__ void gemm_phase(LAS unsigned char* lds, const Gemm g, const Sched& S, const Epi& E) {
;     ...
;             PG8_LDB(B0, 0, 0); PG8_SCHED; PG8_LDA(At, 0, 0); PG8_STAGE(PG8_SA(1, 1), a1 + hstep, voffA);
;             PG8_WAIT_L(8); PG8_BAR; PG8_WAIT_L(0); PG8_MMA(0, 0, At, B0); PG8_BAR; PG8_SCHED;
;             PG8_LDB(B1, 0, 1); PG8_STAGE(PG8_SB(0, 0), b2, voffB);
;     ...
;             PG8_BAR; PG8_WAIT_L(0); PG8_MMA(1, 0, At, B0); PG8_BAR; PG8_SCHED;
;             PG8_STAGE(PG8_SB(1, 1), b3 + hstep, voffB);
;             PG8_WAIT_V(6); PG8_BAR; PG8_MMA(1, 1, At, B1); PG8_BAR;
	s_waitcnt lgkmcnt(0)
	v_mfma_f32_16x16x32_bf16 v[60:63], v[128:131], v[170:173], v[60:63]
	v_mfma_f32_16x16x32_bf16 v[56:59], v[136:139], v[170:173], v[56:59]
	v_mfma_f32_16x16x32_bf16 v[44:47], v[128:131], v[178:181], v[44:47]
	v_mfma_f32_16x16x32_bf16 v[40:43], v[136:139], v[178:181], v[40:43]
	v_mfma_f32_16x16x32_bf16 v[28:31], v[128:131], v[186:189], v[28:31]
	v_mfma_f32_16x16x32_bf16 v[24:27], v[136:139], v[186:189], v[24:27]
	v_mfma_f32_16x16x32_bf16 v[12:15], v[128:131], v[194:197], v[12:15]
	v_mfma_f32_16x16x32_bf16 v[8:11], v[136:139], v[194:197], v[8:11]
	v_mfma_f32_16x16x32_bf16 v[60:63], v[132:135], v[174:177], v[60:63]
	v_mfma_f32_16x16x32_bf16 v[56:59], v[160:163], v[174:177], v[56:59]
	v_mfma_f32_16x16x32_bf16 v[44:47], v[132:135], v[182:185], v[44:47]
	v_mfma_f32_16x16x32_bf16 v[40:43], v[160:163], v[182:185], v[40:43]
	v_mfma_f32_16x16x32_bf16 v[28:31], v[132:135], v[190:193], v[28:31]
	v_mfma_f32_16x16x32_bf16 v[24:27], v[160:163], v[190:193], v[24:27]
	v_mfma_f32_16x16x32_bf16 v[12:15], v[132:135], v[202:205], v[12:15]
	v_mfma_f32_16x16x32_bf16 v[8:11], v[160:163], v[202:205], v[8:11]
	s_barrier
	s_setprio 0
	s_add_u32 s26, s26, 0x40080
	s_addc_u32 s27, s27, 0
	s_add_i32 s28, s28, s34
	s_mov_b32 m0, s28
	s_nop 0
	global_load_lds_dwordx4 v146, s[26:27]
	s_add_i32 m0, s28, 0x2000
	s_nop 0
	global_load_lds_dwordx4 v142, s[26:27]
	s_waitcnt vmcnt(8)
	s_setprio 1
	s_barrier
	v_mfma_f32_16x16x32_bf16 v[52:55], v[206:209], v[170:173], v[52:55]
	v_mfma_f32_16x16x32_bf16 v[48:51], v[214:217], v[170:173], v[48:51]
	v_mfma_f32_16x16x32_bf16 v[36:39], v[206:209], v[178:181], v[36:39]
	v_mfma_f32_16x16x32_bf16 v[32:35], v[214:217], v[178:181], v[32:35]
	v_mfma_f32_16x16x32_bf16 v[20:23], v[206:209], v[186:189], v[20:23]
	v_mfma_f32_16x16x32_bf16 v[16:19], v[214:217], v[186:189], v[16:19]
	v_mfma_f32_16x16x32_bf16 v[4:7], v[206:209], v[194:197], v[4:7]
	v_mfma_f32_16x16x32_bf16 v[0:3], v[214:217], v[194:197], v[0:3]
	v_mfma_f32_16x16x32_bf16 v[52:55], v[210:213], v[174:177], v[52:55]
	v_mfma_f32_16x16x32_bf16 v[48:51], v[218:221], v[174:177], v[48:51]
	v_mfma_f32_16x16x32_bf16 v[36:39], v[210:213], v[182:185], v[36:39]
	v_mfma_f32_16x16x32_bf16 v[32:35], v[218:221], v[182:185], v[32:35]
	v_mfma_f32_16x16x32_bf16 v[20:23], v[210:213], v[190:193], v[20:23]
	v_mfma_f32_16x16x32_bf16 v[16:19], v[218:221], v[190:193], v[16:19]
	v_mfma_f32_16x16x32_bf16 v[4:7], v[210:213], v[202:205], v[4:7]
	v_mfma_f32_16x16x32_bf16 v[0:3], v[218:221], v[202:205], v[0:3]
	s_add_i32 s56, s56, 2
	s_add_u32 s6, s6, 0x100
	s_addc_u32 s7, s7, 0
	s_add_u32 s54, s54, 0x100
	s_addc_u32 s55, s55, 0
	s_cmp_gt_u32 s56, 13
	s_barrier
	s_setprio 0
.LBB0_578:
	ds_read_b128 v[128:131], v167
	ds_read_b128 v[132:135], v167 offset:1024
	ds_read_b128 v[136:139], v167 offset:2048
	ds_read_b128 v[160:163], v167 offset:3072
	s_add_u32 s26, s6, 0xfffc0080
	s_addc_u32 s27, s7, -1
	s_cmp_eq_u32 s56, 12
	s_cselect_b32 s29, s5, s27
	s_cselect_b32 s28, s21, s26
	s_cselect_b32 s27, s19, s55
	s_cselect_b32 s26, s53, s54
	s_add_i32 m0, s37, 0xc000
	ds_read_b128 v[170:173], v168
	ds_read_b128 v[174:177], v168 offset:1024
	ds_read_b128 v[178:181], v168 offset:2048
	ds_read_b128 v[182:185], v168 offset:3072
	ds_read_b128 v[186:189], v168 offset:4096
	ds_read_b128 v[190:193], v168 offset:5120
	ds_read_b128 v[194:197], v168 offset:6144
	ds_read_b128 v[202:205], v168 offset:7168
	global_load_lds_dwordx4 v152, s[6:7]
	s_add_i32 m0, s37, 0xe000
	s_nop 0
	global_load_lds_dwordx4 v154, s[6:7]
	s_waitcnt lgkmcnt(8)
	s_waitcnt vmcnt(8)
	s_setprio 1
	s_barrier
	s_waitcnt lgkmcnt(0)
	v_mfma_f32_16x16x32_bf16 v[124:127], v[128:131], v[170:173], v[124:127]
	v_mfma_f32_16x16x32_bf16 v[120:123], v[136:139], v[170:173], v[120:123]
	v_mfma_f32_16x16x32_bf16 v[108:111], v[128:131], v[178:181], v[108:111]
	v_mfma_f32_16x16x32_bf16 v[104:107], v[136:139], v[178:181], v[104:107]
	v_mfma_f32_16x16x32_bf16 v[92:95], v[128:131], v[186:189], v[92:95]
	v_mfma_f32_16x16x32_bf16 v[88:91], v[136:139], v[186:189], v[88:91]
	v_mfma_f32_16x16x32_bf16 v[76:79], v[128:131], v[194:197], v[76:79]
	v_mfma_f32_16x16x32_bf16 v[72:75], v[136:139], v[194:197], v[72:75]
	v_mfma_f32_16x16x32_bf16 v[124:127], v[132:135], v[174:177], v[124:127]
	v_mfma_f32_16x16x32_bf16 v[120:123], v[160:163], v[174:177], v[120:123]
	v_mfma_f32_16x16x32_bf16 v[108:111], v[132:135], v[182:185], v[108:111]
	v_mfma_f32_16x16x32_bf16 v[104:107], v[160:163], v[182:185], v[104:107]
	v_mfma_f32_16x16x32_bf16 v[92:95], v[132:135], v[190:193], v[92:95]
	v_mfma_f32_16x16x32_bf16 v[88:91], v[160:163], v[190:193], v[88:91]
	v_mfma_f32_16x16x32_bf16 v[76:79], v[132:135], v[202:205], v[76:79]
	v_mfma_f32_16x16x32_bf16 v[72:75], v[160:163], v[202:205], v[72:75]
	s_barrier
	s_setprio 0
	s_add_i32 s57, s48, s34
	s_mov_b32 m0, s57
	ds_read_b128 v[206:209], v169
	ds_read_b128 v[210:213], v169 offset:1024
	ds_read_b128 v[214:217], v169 offset:2048
	ds_read_b128 v[218:221], v169 offset:3072
	global_load_lds_dwordx4 v146, s[26:27]
	s_add_i32 m0, s57, 0x2000
	s_nop 0
	global_load_lds_dwordx4 v142, s[26:27]
	s_waitcnt vmcnt(8)
	s_setprio 1
	s_barrier
; #define PG8_STAGE(bufoff, gbase, voff) do { _Pragma("unroll") for (int _i = 0; _i < 2; ++_i) \
;         __builtin_amdgcn_global_load_lds((const unsigned*)((const char*)(gbase) + (voff)[_i]), (LAS unsigned*)(lds + (bufoff) + ldsw + _i * 8192), 16, 0, 0); } while (0)
; #define PG8_LDA(dst, b, h) do { _Pragma("unroll") for (int m = 0; m < 4; ++m) _Pragma("unroll") for (int k = 0; k < 2; ++k) dst[m][k] = *(const LAS bf16x8*)(lds + PG8_SA(b, h) + aoff + m * 2048 + k * 1024); } while (0)
; #define PG8_LDB(dst, b, h) do { _Pragma("unroll") for (int n = 0; n < 2; ++n) _Pragma("unroll") for (int k = 0; k < 2; ++k) dst[n][k] = *(const LAS bf16x8*)(lds + PG8_SB(b, h) + boff + n * 2048 + k * 1024); } while (0)
; #define PG8_MMA(ai, bj, At, Bt) do { __builtin_amdgcn_s_setprio(1); _Pragma("unroll") for (int m = 0; m < 4; ++m) _Pragma("unroll") for (int n = 0; n < 2; ++n) _Pragma("unroll") for (int k = 0; k < 2; ++k) \
;         acc[ai][bj][m][n] = __builtin_amdgcn_mfma_f32_16x16x32_bf16(Bt[n][k], At[m][k], acc[ai][bj][m][n], 0, 0, 0); __builtin_amdgcn_s_setprio(0); } while (0)
; #define PG8_WAIT_V(n) asm volatile("s_waitcnt vmcnt(" #n ")" ::: "memory")
; #define PG8_WAIT_L(n) asm volatile("s_waitcnt lgkmcnt(" #n ")" ::: "memory")
; #define PG8_BAR __builtin_amdgcn_s_barrier()
; #define PG8_SCHED __builtin_amdgcn_sched_barrier(0)
; template <class Epi, class Sched>
; __device__ __forceinline__ void gemm_phase(LAS unsigned char* lds, const Gemm g, const Sched& S, const Epi& E) {
;     ...
;             PG8_BAR; PG8_WAIT_L(0); PG8_MMA(0, 1, At, B1); PG8_BAR;
;             PG8_LDA(At, 0, 1); PG8_STAGE(PG8_SA(0, 0), a2, voffA);
;             PG8_BAR; PG8_WAIT_L(0); PG8_MMA(1, 0, At, B0); PG8_BAR; PG8_SCHED;
;             PG8_STAGE(PG8_SB(0, 1), b2 + hstep, voffB);
;             PG8_WAIT_V(6); PG8_BAR; PG8_MMA(1, 1, At, B1); PG8_BAR;
;             PG8_LDB(B0, 1, 0); PG8_SCHED; PG8_LDA(At, 1, 0); PG8_STAGE(PG8_SA(0, 1), a2 + hstep, voffA);
;             PG8_WAIT_L(8); PG8_BAR; PG8_WAIT_L(0); PG8_MMA(0, 0, At, B0); PG8_BAR; PG8_SCHED;
;             PG8_LDB(B1, 1, 1); PG8_STAGE(PG8_SB(1, 0), b3, voffB);
	s_waitcnt lgkmcnt(0)
	v_mfma_f32_16x16x32_bf16 v[116:119], v[206:209], v[170:173], v[116:119]
	v_mfma_f32_16x16x32_bf16 v[112:115], v[214:217], v[170:173], v[112:115]
	v_mfma_f32_16x16x32_bf16 v[100:103], v[206:209], v[178:181], v[100:103]
	v_mfma_f32_16x16x32_bf16 v[96:99], v[214:217], v[178:181], v[96:99]
	v_mfma_f32_16x16x32_bf16 v[84:87], v[206:209], v[186:189], v[84:87]
	v_mfma_f32_16x16x32_bf16 v[80:83], v[214:217], v[186:189], v[80:83]
	v_mfma_f32_16x16x32_bf16 v[68:71], v[206:209], v[194:197], v[68:71]
	v_mfma_f32_16x16x32_bf16 v[64:67], v[214:217], v[194:197], v[64:67]
	v_mfma_f32_16x16x32_bf16 v[116:119], v[210:213], v[174:177], v[116:119]
	v_mfma_f32_16x16x32_bf16 v[112:115], v[218:221], v[174:177], v[112:115]
	v_mfma_f32_16x16x32_bf16 v[100:103], v[210:213], v[182:185], v[100:103]
	v_mfma_f32_16x16x32_bf16 v[96:99], v[218:221], v[182:185], v[96:99]
	v_mfma_f32_16x16x32_bf16 v[84:87], v[210:213], v[190:193], v[84:87]
	v_mfma_f32_16x16x32_bf16 v[80:83], v[218:221], v[190:193], v[80:83]
	v_mfma_f32_16x16x32_bf16 v[68:71], v[210:213], v[202:205], v[68:71]
	v_mfma_f32_16x16x32_bf16 v[64:67], v[218:221], v[202:205], v[64:67]
	s_mov_b32 m0, s37
	v_lshl_add_u64 v[222:223], s[28:29], 0, v[148:149]
	s_barrier
	s_setprio 0
	ds_read_b128 v[170:173], v168 offset:16384
	ds_read_b128 v[174:177], v168 offset:17408
	ds_read_b128 v[178:181], v168 offset:18432
	ds_read_b128 v[182:185], v168 offset:19456
	ds_read_b128 v[186:189], v168 offset:20480
	ds_read_b128 v[190:193], v168 offset:21504
	ds_read_b128 v[194:197], v168 offset:22528
	ds_read_b128 v[202:205], v168 offset:23552
	global_load_lds_dwordx4 v148, s[28:29]
	v_lshl_add_u64 v[224:225], s[28:29], 0, v[144:145]
	s_mov_b32 m0, s38
	s_nop 0
	global_load_lds_dwordx4 v144, s[28:29]
	s_setprio 1
	s_barrier
	s_waitcnt lgkmcnt(0)
	v_mfma_f32_16x16x32_bf16 v[60:63], v[128:131], v[170:173], v[60:63]
	v_mfma_f32_16x16x32_bf16 v[56:59], v[136:139], v[170:173], v[56:59]
	v_mfma_f32_16x16x32_bf16 v[44:47], v[128:131], v[178:181], v[44:47]
	v_mfma_f32_16x16x32_bf16 v[40:43], v[136:139], v[178:181], v[40:43]
	v_mfma_f32_16x16x32_bf16 v[28:31], v[128:131], v[186:189], v[28:31]
	v_mfma_f32_16x16x32_bf16 v[24:27], v[136:139], v[186:189], v[24:27]
	v_mfma_f32_16x16x32_bf16 v[12:15], v[128:131], v[194:197], v[12:15]
	v_mfma_f32_16x16x32_bf16 v[8:11], v[136:139], v[194:197], v[8:11]
	v_mfma_f32_16x16x32_bf16 v[60:63], v[132:135], v[174:177], v[60:63]
	v_mfma_f32_16x16x32_bf16 v[56:59], v[160:163], v[174:177], v[56:59]
	v_mfma_f32_16x16x32_bf16 v[44:47], v[132:135], v[182:185], v[44:47]
	v_mfma_f32_16x16x32_bf16 v[40:43], v[160:163], v[182:185], v[40:43]
	v_mfma_f32_16x16x32_bf16 v[28:31], v[132:135], v[190:193], v[28:31]
	v_mfma_f32_16x16x32_bf16 v[24:27], v[160:163], v[190:193], v[24:27]
	v_mfma_f32_16x16x32_bf16 v[12:15], v[132:135], v[202:205], v[12:15]
	v_mfma_f32_16x16x32_bf16 v[8:11], v[160:163], v[202:205], v[8:11]
	s_barrier
	s_setprio 0
	s_add_u32 s58, s26, 0x40000
	s_addc_u32 s59, s27, 0
	s_add_i32 s57, s49, s34
	s_mov_b32 m0, s57
	s_nop 0
	global_load_lds_dwordx4 v146, s[58:59]
	s_add_i32 m0, s57, 0x2000
	s_nop 0
	global_load_lds_dwordx4 v142, s[58:59]
	s_add_u32 s28, s28, 0x40000
	s_addc_u32 s29, s29, 0
	s_mov_b32 m0, s39
	s_nop 0
	global_load_lds_dwordx4 v148, s[28:29]
	s_mov_b32 m0, s40
	s_nop 0
	global_load_lds_dwordx4 v144, s[28:29]
	s_waitcnt vmcnt(10)
	s_setprio 1
	s_barrier
	v_mfma_f32_16x16x32_bf16 v[52:55], v[206:209], v[170:173], v[52:55]
	v_mfma_f32_16x16x32_bf16 v[48:51], v[214:217], v[170:173], v[48:51]
	v_mfma_f32_16x16x32_bf16 v[36:39], v[206:209], v[178:181], v[36:39]
	v_mfma_f32_16x16x32_bf16 v[32:35], v[214:217], v[178:181], v[32:35]
	v_mfma_f32_16x16x32_bf16 v[20:23], v[206:209], v[186:189], v[20:23]
	v_mfma_f32_16x16x32_bf16 v[16:19], v[214:217], v[186:189], v[16:19]
	v_mfma_f32_16x16x32_bf16 v[4:7], v[206:209], v[194:197], v[4:7]
	v_mfma_f32_16x16x32_bf16 v[0:3], v[214:217], v[194:197], v[0:3]
	v_mfma_f32_16x16x32_bf16 v[52:55], v[210:213], v[174:177], v[52:55]
	v_mfma_f32_16x16x32_bf16 v[48:51], v[218:221], v[174:177], v[48:51]
	v_mfma_f32_16x16x32_bf16 v[36:39], v[210:213], v[182:185], v[36:39]
	v_mfma_f32_16x16x32_bf16 v[32:35], v[218:221], v[182:185], v[32:35]
	v_mfma_f32_16x16x32_bf16 v[20:23], v[210:213], v[190:193], v[20:23]
	v_mfma_f32_16x16x32_bf16 v[16:19], v[218:221], v[190:193], v[16:19]
	v_mfma_f32_16x16x32_bf16 v[4:7], v[210:213], v[202:205], v[4:7]
	v_mfma_f32_16x16x32_bf16 v[0:3], v[218:221], v[202:205], v[0:3]
	s_add_i32 s57, 0, 0x18000
	v_add_u32_e32 v150, s57, v166
	s_barrier
	s_setprio 0
	ds_read_b128 v[128:131], v150
	ds_read_b128 v[132:135], v150 offset:1024
	ds_read_b128 v[136:139], v150 offset:2048
	ds_read_b128 v[160:163], v150 offset:3072
	ds_read_b128 v[170:173], v168 offset:32768
	ds_read_b128 v[174:177], v168 offset:33792
	ds_read_b128 v[178:181], v168 offset:34816
	ds_read_b128 v[182:185], v168 offset:35840
	ds_read_b128 v[186:189], v168 offset:36864
	ds_read_b128 v[190:193], v168 offset:37888
	ds_read_b128 v[194:197], v168 offset:38912
	ds_read_b128 v[202:205], v168 offset:39936
	s_waitcnt lgkmcnt(8)
	s_waitcnt vmcnt(8)
	s_setprio 1
	s_barrier
; #define PG8_STAGE(bufoff, gbase, voff) do { _Pragma("unroll") for (int _i = 0; _i < 2; ++_i) \
;         __builtin_amdgcn_global_load_lds((const unsigned*)((const char*)(gbase) + (voff)[_i]), (LAS unsigned*)(lds + (bufoff) + ldsw + _i * 8192), 16, 0, 0); } while (0)
; #define PG8_LDA(dst, b, h) do { _Pragma("unroll") for (int m = 0; m < 4; ++m) _Pragma("unroll") for (int k = 0; k < 2; ++k) dst[m][k] = *(const LAS bf16x8*)(lds + PG8_SA(b, h) + aoff + m * 2048 + k * 1024); } while (0)
; #define PG8_LDB(dst, b, h) do { _Pragma("unroll") for (int n = 0; n < 2; ++n) _Pragma("unroll") for (int k = 0; k < 2; ++k) dst[n][k] = *(const LAS bf16x8*)(lds + PG8_SB(b, h) + boff + n * 2048 + k * 1024); } while (0)
; #define PG8_MMA(ai, bj, At, Bt) do { __builtin_amdgcn_s_setprio(1); _Pragma("unroll") for (int m = 0; m < 4; ++m) _Pragma("unroll") for (int n = 0; n < 2; ++n) _Pragma("unroll") for (int k = 0; k < 2; ++k) \
;         acc[ai][bj][m][n] = __builtin_amdgcn_mfma_f32_16x16x32_bf16(Bt[n][k], At[m][k], acc[ai][bj][m][n], 0, 0, 0); __builtin_amdgcn_s_setprio(0); } while (0)
; #define PG8_WAIT_L(n) asm volatile("s_waitcnt lgkmcnt(" #n ")" ::: "memory")
; #define PG8_BAR __builtin_amdgcn_s_barrier()
; #define PG8_SCHED __builtin_amdgcn_sched_barrier(0)
; template <class Epi, class Sched>
; __device__ __forceinline__ void gemm_phase(LAS unsigned char* lds, const Gemm g, const Sched& S, const Epi& E) {
;     ...
;             PG8_WAIT_L(8); PG8_BAR; PG8_WAIT_L(0); PG8_MMA(0, 0, At, B0); PG8_BAR; PG8_SCHED;
;             PG8_LDB(B1, 1, 1); PG8_STAGE(PG8_SB(1, 0), b3, voffB);
;             PG8_BAR; PG8_WAIT_L(0); PG8_MMA(0, 1, At, B1); PG8_BAR;
;             PG8_LDA(At, 1, 1); PG8_STAGE(PG8_SA(1, 0), a3, voffA);
	s_waitcnt lgkmcnt(0)
	v_mfma_f32_16x16x32_bf16 v[124:127], v[128:131], v[170:173], v[124:127]
	v_mfma_f32_16x16x32_bf16 v[120:123], v[136:139], v[170:173], v[120:123]
	v_mfma_f32_16x16x32_bf16 v[108:111], v[128:131], v[178:181], v[108:111]
	v_mfma_f32_16x16x32_bf16 v[104:107], v[136:139], v[178:181], v[104:107]
	v_mfma_f32_16x16x32_bf16 v[92:95], v[128:131], v[186:189], v[92:95]
	v_mfma_f32_16x16x32_bf16 v[88:91], v[136:139], v[186:189], v[88:91]
	v_mfma_f32_16x16x32_bf16 v[76:79], v[128:131], v[194:197], v[76:79]
	v_mfma_f32_16x16x32_bf16 v[72:75], v[136:139], v[194:197], v[72:75]
	v_mfma_f32_16x16x32_bf16 v[124:127], v[132:135], v[174:177], v[124:127]
	v_mfma_f32_16x16x32_bf16 v[120:123], v[160:163], v[174:177], v[120:123]
	v_mfma_f32_16x16x32_bf16 v[108:111], v[132:135], v[182:185], v[108:111]
	v_mfma_f32_16x16x32_bf16 v[104:107], v[160:163], v[182:185], v[104:107]
	v_mfma_f32_16x16x32_bf16 v[92:95], v[132:135], v[190:193], v[92:95]
	v_mfma_f32_16x16x32_bf16 v[88:91], v[160:163], v[190:193], v[88:91]
	v_mfma_f32_16x16x32_bf16 v[76:79], v[132:135], v[202:205], v[76:79]
	v_mfma_f32_16x16x32_bf16 v[72:75], v[160:163], v[202:205], v[72:75]
	s_barrier
	s_setprio 0
	s_add_i32 s28, 0, 0x1c000
	s_add_i32 s29, s57, s34
	v_add_u32_e32 v150, s28, v166
	s_add_u32 s0, s26, 0x80
	s_addc_u32 s1, s27, 0
	s_mov_b32 m0, s29
	ds_read_b128 v[206:209], v150
	ds_read_b128 v[210:213], v150 offset:1024
	ds_read_b128 v[214:217], v150 offset:2048
	ds_read_b128 v[218:221], v150 offset:3072
	global_load_lds_dwordx4 v146, s[0:1]
	s_add_i32 m0, s29, 0x2000
	s_nop 0
	global_load_lds_dwordx4 v142, s[0:1]
	s_waitcnt vmcnt(8)
	s_setprio 1
	s_barrier
	s_waitcnt lgkmcnt(0)
	v_mfma_f32_16x16x32_bf16 v[116:119], v[206:209], v[170:173], v[116:119]
	v_mfma_f32_16x16x32_bf16 v[112:115], v[214:217], v[170:173], v[112:115]
	v_mfma_f32_16x16x32_bf16 v[100:103], v[206:209], v[178:181], v[100:103]
	v_mfma_f32_16x16x32_bf16 v[96:99], v[214:217], v[178:181], v[96:99]
	v_mfma_f32_16x16x32_bf16 v[84:87], v[206:209], v[186:189], v[84:87]
	v_mfma_f32_16x16x32_bf16 v[80:83], v[214:217], v[186:189], v[80:83]
	v_mfma_f32_16x16x32_bf16 v[68:71], v[206:209], v[194:197], v[68:71]
	v_mfma_f32_16x16x32_bf16 v[64:67], v[214:217], v[194:197], v[64:67]
	v_mfma_f32_16x16x32_bf16 v[116:119], v[210:213], v[174:177], v[116:119]
	v_mfma_f32_16x16x32_bf16 v[112:115], v[218:221], v[174:177], v[112:115]
	v_mfma_f32_16x16x32_bf16 v[100:103], v[210:213], v[182:185], v[100:103]
	v_mfma_f32_16x16x32_bf16 v[96:99], v[218:221], v[182:185], v[96:99]
	v_mfma_f32_16x16x32_bf16 v[84:87], v[210:213], v[190:193], v[84:87]
	v_mfma_f32_16x16x32_bf16 v[80:83], v[218:221], v[190:193], v[80:83]
	v_mfma_f32_16x16x32_bf16 v[68:71], v[210:213], v[202:205], v[68:71]
	v_mfma_f32_16x16x32_bf16 v[64:67], v[218:221], v[202:205], v[64:67]
	s_mov_b32 m0, s44
	s_mov_b64 s[0:1], 0x80
	v_lshl_add_u64 v[140:141], v[222:223], 0, s[0:1]
	s_barrier
	s_setprio 0
	ds_read_b128 v[170:173], v168 offset:49152
	ds_read_b128 v[174:177], v168 offset:50176
	ds_read_b128 v[178:181], v168 offset:51200
	ds_read_b128 v[182:185], v168 offset:52224
	ds_read_b128 v[186:189], v168 offset:53248
	ds_read_b128 v[190:193], v168 offset:54272
	ds_read_b128 v[194:197], v168 offset:55296
	ds_read_b128 v[202:205], v168 offset:56320
	global_load_lds_dwordx4 v[140:141], off
	v_lshl_add_u64 v[140:141], v[224:225], 0, s[0:1]
	s_mov_b32 m0, s45
	s_nop 0
	global_load_lds_dwordx4 v[140:141], off
	s_setprio 1
	s_barrier
; #define PG8_STAGE(bufoff, gbase, voff) do { _Pragma("unroll") for (int _i = 0; _i < 2; ++_i) \
;         __builtin_amdgcn_global_load_lds((const unsigned*)((const char*)(gbase) + (voff)[_i]), (LAS unsigned*)(lds + (bufoff) + ldsw + _i * 8192), 16, 0, 0); } while (0)
; #define PG8_MMA(ai, bj, At, Bt) do { __builtin_amdgcn_s_setprio(1); _Pragma("unroll") for (int m = 0; m < 4; ++m) _Pragma("unroll") for (int n = 0; n < 2; ++n) _Pragma("unroll") for (int k = 0; k < 2; ++k) \
;         acc[ai][bj][m][n] = __builtin_amdgcn_mfma_f32_16x16x32_bf16(Bt[n][k], At[m][k], acc[ai][bj][m][n], 0, 0, 0); __builtin_amdgcn_s_setprio(0); } while (0)
; #define PG8_WAIT_V(n) asm volatile("s_waitcnt vmcnt(" #n ")" ::: "memory")
; #define PG8_WAIT_L(n) asm volatile("s_waitcnt lgkmcnt(" #n ")" ::: "memory")
; #define PG8_BAR __builtin_amdgcn_s_barrier()
; #define PG8_SCHED __builtin_amdgcn_sched_barrier(0)
; template <class Epi, class Sched>
; __device__ __forceinline__ void gemm_phase(LAS unsigned char* lds, const Gemm g, const Sched& S, const Epi& E) {
;     ...
;             PG8_BAR; PG8_WAIT_L(0); PG8_MMA(1, 0, At, B0); PG8_BAR; PG8_SCHED;
;             PG8_STAGE(PG8_SB(1, 1), b3 + hstep, voffB);
;             PG8_WAIT_V(6); PG8_BAR; PG8_MMA(1, 1, At, B1); PG8_BAR;
;     __device__ __forceinline__ void operator()(const AccT& acc, const Unit& u, int wr, int wc, int fr, int fq) const {
;     ...
;         const int row0 = u.pm * 256 + wr * 64 + fr, col0 = u.pn * 256 + wc * 32 + 8 * fq;
;         const bool rope = u.pn < 2;
;         const int i = 4 * (wc & 1) + fq;
; #pragma unroll
;         for (int ai = 0; ai < 2; ++ai)
; #pragma unroll
;             for (int m = 0; m < 4; ++m) {
;                 const int row = row0 + ai * 128 + m * 16;
;                 f32x4 cs = {1.f, 1.f, 1.f, 1.f}, sn = {0.f, 0.f, 0.f, 0.f};
;                 if (rope) { const int t = row & 2047; const int pos = (i < 4) ? (t >> 6) : (t & 63);
;                     cs = *(const f32x4*)(ropeA + pos * 16 + ((4 * i) & 15)); sn = *(const f32x4*)(ropeA + 1024 + pos * 16 + ((4 * i) & 15)); }
	s_waitcnt lgkmcnt(0)
	v_mfma_f32_16x16x32_bf16 v[60:63], v[128:131], v[170:173], v[60:63]
	v_mfma_f32_16x16x32_bf16 v[56:59], v[136:139], v[170:173], v[56:59]
	v_mfma_f32_16x16x32_bf16 v[44:47], v[128:131], v[178:181], v[44:47]
	v_mfma_f32_16x16x32_bf16 v[40:43], v[136:139], v[178:181], v[40:43]
	v_mfma_f32_16x16x32_bf16 v[28:31], v[128:131], v[186:189], v[28:31]
	v_mfma_f32_16x16x32_bf16 v[24:27], v[136:139], v[186:189], v[24:27]
	v_mfma_f32_16x16x32_bf16 v[12:15], v[128:131], v[194:197], v[12:15]
	v_mfma_f32_16x16x32_bf16 v[8:11], v[136:139], v[194:197], v[8:11]
	v_mfma_f32_16x16x32_bf16 v[60:63], v[132:135], v[174:177], v[60:63]
	v_mfma_f32_16x16x32_bf16 v[56:59], v[160:163], v[174:177], v[56:59]
	v_mfma_f32_16x16x32_bf16 v[44:47], v[132:135], v[182:185], v[44:47]
	v_mfma_f32_16x16x32_bf16 v[40:43], v[160:163], v[182:185], v[40:43]
	v_mfma_f32_16x16x32_bf16 v[28:31], v[132:135], v[190:193], v[28:31]
	v_mfma_f32_16x16x32_bf16 v[24:27], v[160:163], v[190:193], v[24:27]
	v_mfma_f32_16x16x32_bf16 v[12:15], v[132:135], v[202:205], v[12:15]
	v_mfma_f32_16x16x32_bf16 v[8:11], v[160:163], v[202:205], v[8:11]
	s_barrier
	s_setprio 0
	s_add_u32 s26, s26, 0x40080
	s_addc_u32 s27, s27, 0
	s_add_i32 s28, s28, s34
	s_mov_b32 m0, s28
	s_nop 0
	global_load_lds_dwordx4 v146, s[26:27]
	s_add_i32 m0, s28, 0x2000
	s_nop 0
	global_load_lds_dwordx4 v142, s[26:27]
	s_waitcnt vmcnt(8)
	s_setprio 1
	s_barrier
	v_mfma_f32_16x16x32_bf16 v[52:55], v[206:209], v[170:173], v[52:55]
	v_mfma_f32_16x16x32_bf16 v[48:51], v[214:217], v[170:173], v[48:51]
	v_mfma_f32_16x16x32_bf16 v[36:39], v[206:209], v[178:181], v[36:39]
	v_mfma_f32_16x16x32_bf16 v[32:35], v[214:217], v[178:181], v[32:35]
	v_mfma_f32_16x16x32_bf16 v[20:23], v[206:209], v[186:189], v[20:23]
	v_mfma_f32_16x16x32_bf16 v[16:19], v[214:217], v[186:189], v[16:19]
	v_mfma_f32_16x16x32_bf16 v[4:7], v[206:209], v[194:197], v[4:7]
	v_mfma_f32_16x16x32_bf16 v[0:3], v[214:217], v[194:197], v[0:3]
	v_mfma_f32_16x16x32_bf16 v[52:55], v[210:213], v[174:177], v[52:55]
	v_mfma_f32_16x16x32_bf16 v[48:51], v[218:221], v[174:177], v[48:51]
	v_mfma_f32_16x16x32_bf16 v[36:39], v[210:213], v[182:185], v[36:39]
	v_mfma_f32_16x16x32_bf16 v[32:35], v[218:221], v[182:185], v[32:35]
	v_mfma_f32_16x16x32_bf16 v[20:23], v[210:213], v[190:193], v[20:23]
	v_mfma_f32_16x16x32_bf16 v[16:19], v[218:221], v[190:193], v[16:19]
	v_mfma_f32_16x16x32_bf16 v[4:7], v[210:213], v[202:205], v[4:7]
	v_mfma_f32_16x16x32_bf16 v[0:3], v[218:221], v[202:205], v[0:3]
	s_add_i32 s56, s56, 2
	s_add_u32 s6, s6, 0x100
	s_addc_u32 s7, s7, 0
	s_add_u32 s54, s54, 0x100
	s_addc_u32 s55, s55, 0
	s_cmp_gt_u32 s56, 13
	s_barrier
	s_setprio 0
	s_cbranch_scc0 .LBB0_578
	v_mov_b32_e32 v129, v165
	v_mov_b32_e32 v173, v164
	s_lshl_b32 s4, s4, 8
	s_add_i32 s4, s4, s42
	v_add_u32_e32 v128, s46, v129
	v_add_u32_e32 v170, s4, v173
	v_cmp_gt_i32_e64 s[4:5], 4, v128
	v_lshlrev_b32_e32 v128, 2, v128
	s_cmp_lt_i32 s52, 2
	v_and_b32_e32 v130, 12, v128
	s_cselect_b64 s[26:27], -1, 0
	s_cmp_gt_i32 s52, 1
	v_and_b32_e32 v172, 63, v173
	v_mov_b32_e32 v128, 1.0
	v_mov_b32_e32 v132, 0
	v_lshlrev_b32_e32 v162, 2, v130
	v_mov_b32_e32 v134, 0
	v_mov_b32_e32 v135, 0
	v_mov_b32_e32 v136, 0
	v_mov_b32_e32 v137, 0
	v_mov_b32_e32 v138, 1.0
	v_mov_b32_e32 v139, 1.0
	v_mov_b32_e32 v140, 1.0
	v_mov_b32_e32 v141, 1.0
	s_cbranch_scc1 .LBB0_581
	v_bfe_u32 v130, v170, 6, 5
	v_cndmask_b32_e64 v130, v172, v130, s[4:5]
	v_lshlrev_b32_e32 v150, 6, v130
	v_lshl_add_u64 v[130:131], s[16:17], 0, v[150:151]
	v_mov_b32_e32 v163, v151
	v_lshl_add_u64 v[134:135], s[8:9], 0, v[150:151]
	v_lshl_add_u64 v[130:131], v[130:131], 0, v[162:163]
	v_lshl_add_u64 v[134:135], v[134:135], 0, v[162:163]
	global_load_dwordx4 v[138:141], v[130:131], off
	s_nop 0
	global_load_dwordx4 v[134:137], v[134:135], off
	s_waitcnt vmcnt(0)

; #define PG8_STAGE(bufoff, gbase, voff) do { _Pragma("unroll") for (int _i = 0; _i < 2; ++_i) \
;         __builtin_amdgcn_global_load_lds((const unsigned*)((const char*)(gbase) + (voff)[_i]), (LAS unsigned*)(lds + (bufoff) + ldsw + _i * 8192), 16, 0, 0); } while (0)
; #define PG8_LDA(dst, b, h) do { _Pragma("unroll") for (int m = 0; m < 4; ++m) _Pragma("unroll") for (int k = 0; k < 2; ++k) dst[m][k] = *(const LAS bf16x8*)(lds + PG8_SA(b, h) + aoff + m * 2048 + k * 1024); } while (0)
; #define PG8_LDB(dst, b, h) do { _Pragma("unroll") for (int n = 0; n < 2; ++n) _Pragma("unroll") for (int k = 0; k < 2; ++k) dst[n][k] = *(const LAS bf16x8*)(lds + PG8_SB(b, h) + boff + n * 2048 + k * 1024); } while (0)
; #define PG8_MMA(ai, bj, At, Bt) do { __builtin_amdgcn_s_setprio(1); _Pragma("unroll") for (int m = 0; m < 4; ++m) _Pragma("unroll") for (int n = 0; n < 2; ++n) _Pragma("unroll") for (int k = 0; k < 2; ++k) \
;         acc[ai][bj][m][n] = __builtin_amdgcn_mfma_f32_16x16x32_bf16(Bt[n][k], At[m][k], acc[ai][bj][m][n], 0, 0, 0); __builtin_amdgcn_s_setprio(0); } while (0)
; #define PG8_WAIT_L(n) asm volatile("s_waitcnt lgkmcnt(" #n ")" ::: "memory")
; template <class Epi, class Sched>
; __device__ __forceinline__ void gemm_phase(LAS unsigned char* lds, const Gemm g, const Sched& S, const Epi& E) {
;     ...
;         const bool has_next = S.next(ui + 1, nxt);
;         const char* nA = has_next ? (const char*)g.A + (size_t)nxt.pm * tstep : cA; const char* nB = has_next ? (const char*)g.Bt + (size_t)nxt.pn * tstep : cB;
;         for (int t = 0; t < nt; t += 2) {
;             const bool last = (t == nt - 2);
;             const char* a1 = cA + (size_t)(t + 1) * kstep;
;             const char* a2 = last ? nA : cA + (size_t)(t + 2) * kstep; const char* b2 = last ? nB : cB + (size_t)(t + 2) * kstep;
;             const char* a3 = a2 + kstep; const char* b3 = b2 + kstep;
;             PG8_LDB(B0, 0, 0); PG8_SCHED; PG8_LDA(At, 0, 0); PG8_STAGE(PG8_SA(1, 1), a1 + hstep, voffA);
;             PG8_WAIT_L(8); PG8_BAR; PG8_WAIT_L(0); PG8_MMA(0, 0, At, B0); PG8_BAR; PG8_SCHED;
;             PG8_LDB(B1, 0, 1); PG8_STAGE(PG8_SB(0, 0), b2, voffB);
;             PG8_BAR; PG8_WAIT_L(0); PG8_MMA(0, 1, At, B1); PG8_BAR;
;             PG8_LDA(At, 0, 1); PG8_STAGE(PG8_SA(0, 0), a2, voffA);
;             PG8_BAR; PG8_WAIT_L(0); PG8_MMA(1, 0, At, B0); PG8_BAR; PG8_SCHED;
.LBB0_612:
	s_ashr_i32 s35, s34, 31
	v_cmp_lt_i64_e32 vcc, s[6:7], v[142:143]
	s_lshl_b64 s[6:7], s[34:35], 19
	s_add_u32 s36, s40, s6
	s_addc_u32 s37, s41, s7
	s_and_b64 s[6:7], vcc, exec
	s_cselect_b32 s8, s37, s1
	s_cselect_b32 s9, s36, s0
	s_ashr_i32 s31, s30, 31
	s_lshl_b64 s[6:7], s[30:31], 19
	s_add_u32 s38, s96, s6
	s_addc_u32 s39, s97, s7
	s_and_b64 s[6:7], vcc, exec
	s_cselect_b32 s31, s39, s5
	s_cselect_b32 s35, s38, s4
	s_add_u32 s0, s0, 0x40080
	s_addc_u32 s1, s1, 0
	s_add_u32 s65, s4, 0x100
	s_addc_u32 s66, s5, 0
	s_mov_b32 s67, -2
	s_waitcnt lgkmcnt(0)
	ds_read_b128 v[146:149], v171
	ds_read_b128 v[150:153], v171 offset:1024
	ds_read_b128 v[154:157], v171 offset:2048
	ds_read_b128 v[158:161], v171 offset:3072
	s_add_u32 s4, s0, 0xfffc0080
	s_addc_u32 s5, s1, -1
	s_cmp_eq_u32 s67, 12
	s_cselect_b32 s7, s8, s5
	s_cselect_b32 s6, s9, s4
	s_cselect_b32 s5, s31, s66
	s_cselect_b32 s4, s35, s65
	s_add_i32 m0, s45, 0xc000
	ds_read_b128 v[162:165], v172
	ds_read_b128 v[178:181], v172 offset:1024
	ds_read_b128 v[182:185], v172 offset:2048
	ds_read_b128 v[186:189], v172 offset:3072
	ds_read_b128 v[190:193], v172 offset:4096
	ds_read_b128 v[194:197], v172 offset:5120
	ds_read_b128 v[202:205], v172 offset:6144
	ds_read_b128 v[206:209], v172 offset:7168
	global_load_lds_dwordx4 v138, s[0:1]
	s_add_i32 m0, s45, 0xe000
	s_nop 0
	global_load_lds_dwordx4 v140, s[0:1]
	s_waitcnt lgkmcnt(8)
	s_waitcnt vmcnt(8)
	s_setprio 1
	s_barrier
	s_waitcnt lgkmcnt(0)
	v_mfma_f32_16x16x32_bf16 v[124:127], v[146:149], v[162:165], 0
	v_mfma_f32_16x16x32_bf16 v[120:123], v[154:157], v[162:165], 0
	v_mfma_f32_16x16x32_bf16 v[108:111], v[146:149], v[182:185], 0
	v_mfma_f32_16x16x32_bf16 v[104:107], v[154:157], v[182:185], 0
	v_mfma_f32_16x16x32_bf16 v[92:95], v[146:149], v[190:193], 0
	v_mfma_f32_16x16x32_bf16 v[88:91], v[154:157], v[190:193], 0
	v_mfma_f32_16x16x32_bf16 v[76:79], v[146:149], v[202:205], 0
	v_mfma_f32_16x16x32_bf16 v[72:75], v[154:157], v[202:205], 0
	v_mfma_f32_16x16x32_bf16 v[124:127], v[150:153], v[178:181], v[124:127]
	v_mfma_f32_16x16x32_bf16 v[120:123], v[158:161], v[178:181], v[120:123]
	v_mfma_f32_16x16x32_bf16 v[108:111], v[150:153], v[186:189], v[108:111]
	v_mfma_f32_16x16x32_bf16 v[104:107], v[158:161], v[186:189], v[104:107]
	v_mfma_f32_16x16x32_bf16 v[92:95], v[150:153], v[194:197], v[92:95]
	v_mfma_f32_16x16x32_bf16 v[88:91], v[158:161], v[194:197], v[88:91]
	v_mfma_f32_16x16x32_bf16 v[76:79], v[150:153], v[206:209], v[76:79]
	v_mfma_f32_16x16x32_bf16 v[72:75], v[158:161], v[206:209], v[72:75]
	s_barrier
	s_setprio 0
	s_add_i32 s68, s57, s44
	s_mov_b32 m0, s68
	ds_read_b128 v[210:213], v173
	ds_read_b128 v[214:217], v173 offset:1024
	ds_read_b128 v[218:221], v173 offset:2048
	ds_read_b128 v[222:225], v173 offset:3072
	global_load_lds_dwordx4 v130, s[4:5]
	s_add_i32 m0, s68, 0x2000
	s_nop 0
	global_load_lds_dwordx4 v134, s[4:5]
	s_waitcnt vmcnt(8)
	s_setprio 1
	s_barrier
	s_waitcnt lgkmcnt(0)
	v_mfma_f32_16x16x32_bf16 v[116:119], v[210:213], v[162:165], 0
	v_mfma_f32_16x16x32_bf16 v[112:115], v[218:221], v[162:165], 0
	v_mfma_f32_16x16x32_bf16 v[100:103], v[210:213], v[182:185], 0
	v_mfma_f32_16x16x32_bf16 v[96:99], v[218:221], v[182:185], 0
	v_mfma_f32_16x16x32_bf16 v[84:87], v[210:213], v[190:193], 0
	v_mfma_f32_16x16x32_bf16 v[80:83], v[218:221], v[190:193], 0
	v_mfma_f32_16x16x32_bf16 v[68:71], v[210:213], v[202:205], 0
	v_mfma_f32_16x16x32_bf16 v[64:67], v[218:221], v[202:205], 0
	v_mfma_f32_16x16x32_bf16 v[116:119], v[214:217], v[178:181], v[116:119]
	v_mfma_f32_16x16x32_bf16 v[112:115], v[222:225], v[178:181], v[112:115]
	v_mfma_f32_16x16x32_bf16 v[100:103], v[214:217], v[186:189], v[100:103]
	v_mfma_f32_16x16x32_bf16 v[96:99], v[222:225], v[186:189], v[96:99]
	v_mfma_f32_16x16x32_bf16 v[84:87], v[214:217], v[194:197], v[84:87]
	v_mfma_f32_16x16x32_bf16 v[80:83], v[222:225], v[194:197], v[80:83]
	v_mfma_f32_16x16x32_bf16 v[68:71], v[214:217], v[206:209], v[68:71]
	v_mfma_f32_16x16x32_bf16 v[64:67], v[222:225], v[206:209], v[64:67]
	s_mov_b32 m0, s45
	v_lshl_add_u64 v[226:227], s[6:7], 0, v[128:129]
	s_barrier
	s_setprio 0
	ds_read_b128 v[162:165], v172 offset:16384
	ds_read_b128 v[178:181], v172 offset:17408
	ds_read_b128 v[182:185], v172 offset:18432
	ds_read_b128 v[186:189], v172 offset:19456
	ds_read_b128 v[190:193], v172 offset:20480
	ds_read_b128 v[194:197], v172 offset:21504
	ds_read_b128 v[202:205], v172 offset:22528
	ds_read_b128 v[206:209], v172 offset:23552
	global_load_lds_dwordx4 v128, s[6:7]
	v_lshl_add_u64 v[228:229], s[6:7], 0, v[132:133]
	s_mov_b32 m0, s46
	s_nop 0
	global_load_lds_dwordx4 v132, s[6:7]
	s_setprio 1
	s_barrier
	s_waitcnt lgkmcnt(0)
	v_mfma_f32_16x16x32_bf16 v[60:63], v[146:149], v[162:165], 0
	v_mfma_f32_16x16x32_bf16 v[56:59], v[154:157], v[162:165], 0
	v_mfma_f32_16x16x32_bf16 v[44:47], v[146:149], v[182:185], 0
	v_mfma_f32_16x16x32_bf16 v[40:43], v[154:157], v[182:185], 0
	v_mfma_f32_16x16x32_bf16 v[28:31], v[146:149], v[190:193], 0
	v_mfma_f32_16x16x32_bf16 v[24:27], v[154:157], v[190:193], 0
	v_mfma_f32_16x16x32_bf16 v[12:15], v[146:149], v[202:205], 0
	v_mfma_f32_16x16x32_bf16 v[8:11], v[154:157], v[202:205], 0
	v_mfma_f32_16x16x32_bf16 v[60:63], v[150:153], v[178:181], v[60:63]
	v_mfma_f32_16x16x32_bf16 v[56:59], v[158:161], v[178:181], v[56:59]
	v_mfma_f32_16x16x32_bf16 v[44:47], v[150:153], v[186:189], v[44:47]
	v_mfma_f32_16x16x32_bf16 v[40:43], v[158:161], v[186:189], v[40:43]
	v_mfma_f32_16x16x32_bf16 v[28:31], v[150:153], v[194:197], v[28:31]
	v_mfma_f32_16x16x32_bf16 v[24:27], v[158:161], v[194:197], v[24:27]
	v_mfma_f32_16x16x32_bf16 v[12:15], v[150:153], v[206:209], v[12:15]
	v_mfma_f32_16x16x32_bf16 v[8:11], v[158:161], v[206:209], v[8:11]
	s_barrier
; #define PG8_STAGE(bufoff, gbase, voff) do { _Pragma("unroll") for (int _i = 0; _i < 2; ++_i) \
;         __builtin_amdgcn_global_load_lds((const unsigned*)((const char*)(gbase) + (voff)[_i]), (LAS unsigned*)(lds + (bufoff) + ldsw + _i * 8192), 16, 0, 0); } while (0)
; #define PG8_LDA(dst, b, h) do { _Pragma("unroll") for (int m = 0; m < 4; ++m) _Pragma("unroll") for (int k = 0; k < 2; ++k) dst[m][k] = *(const LAS bf16x8*)(lds + PG8_SA(b, h) + aoff + m * 2048 + k * 1024); } while (0)
; #define PG8_LDB(dst, b, h) do { _Pragma("unroll") for (int n = 0; n < 2; ++n) _Pragma("unroll") for (int k = 0; k < 2; ++k) dst[n][k] = *(const LAS bf16x8*)(lds + PG8_SB(b, h) + boff + n * 2048 + k * 1024); } while (0)
; #define PG8_MMA(ai, bj, At, Bt) do { __builtin_amdgcn_s_setprio(1); _Pragma("unroll") for (int m = 0; m < 4; ++m) _Pragma("unroll") for (int n = 0; n < 2; ++n) _Pragma("unroll") for (int k = 0; k < 2; ++k) \
;         acc[ai][bj][m][n] = __builtin_amdgcn_mfma_f32_16x16x32_bf16(Bt[n][k], At[m][k], acc[ai][bj][m][n], 0, 0, 0); __builtin_amdgcn_s_setprio(0); } while (0)
; #define PG8_WAIT_V(n) asm volatile("s_waitcnt vmcnt(" #n ")" ::: "memory")
; #define PG8_WAIT_L(n) asm volatile("s_waitcnt lgkmcnt(" #n ")" ::: "memory")
; #define PG8_BAR __builtin_amdgcn_s_barrier()
; #define PG8_SCHED __builtin_amdgcn_sched_barrier(0)
; template <class Epi, class Sched>
; __device__ __forceinline__ void gemm_phase(LAS unsigned char* lds, const Gemm g, const Sched& S, const Epi& E) {
;     ...
;             PG8_BAR; PG8_WAIT_L(0); PG8_MMA(1, 0, At, B0); PG8_BAR; PG8_SCHED;
;             PG8_STAGE(PG8_SB(0, 1), b2 + hstep, voffB);
;             PG8_WAIT_V(6); PG8_BAR; PG8_MMA(1, 1, At, B1); PG8_BAR;
;             PG8_LDB(B0, 1, 0); PG8_SCHED; PG8_LDA(At, 1, 0); PG8_STAGE(PG8_SA(0, 1), a2 + hstep, voffA);
;             PG8_WAIT_L(8); PG8_BAR; PG8_WAIT_L(0); PG8_MMA(0, 0, At, B0); PG8_BAR; PG8_SCHED;
;             PG8_LDB(B1, 1, 1); PG8_STAGE(PG8_SB(1, 0), b3, voffB);
;             PG8_BAR; PG8_WAIT_L(0); PG8_MMA(0, 1, At, B1); PG8_BAR;
;             PG8_LDA(At, 1, 1); PG8_STAGE(PG8_SA(1, 0), a3, voffA);
	s_setprio 0
	s_add_u32 s68, s4, 0x40000
	s_addc_u32 s69, s5, 0
	s_add_i32 s70, s58, s44
	s_mov_b32 m0, s70
	s_nop 0
	global_load_lds_dwordx4 v130, s[68:69]
	s_add_i32 m0, s70, 0x2000
	s_nop 0
	global_load_lds_dwordx4 v134, s[68:69]
	s_add_u32 s6, s6, 0x40000
	s_addc_u32 s7, s7, 0
	s_mov_b32 m0, s47
	s_nop 0
	global_load_lds_dwordx4 v128, s[6:7]
	s_mov_b32 m0, s48
	s_nop 0
	global_load_lds_dwordx4 v132, s[6:7]
	s_waitcnt vmcnt(10)
	s_setprio 1
	s_barrier
	v_mfma_f32_16x16x32_bf16 v[52:55], v[210:213], v[162:165], 0
	v_mfma_f32_16x16x32_bf16 v[48:51], v[218:221], v[162:165], 0
	v_mfma_f32_16x16x32_bf16 v[36:39], v[210:213], v[182:185], 0
	v_mfma_f32_16x16x32_bf16 v[32:35], v[218:221], v[182:185], 0
	v_mfma_f32_16x16x32_bf16 v[20:23], v[210:213], v[190:193], 0
	v_mfma_f32_16x16x32_bf16 v[16:19], v[218:221], v[190:193], 0
	v_mfma_f32_16x16x32_bf16 v[4:7], v[210:213], v[202:205], 0
	v_mfma_f32_16x16x32_bf16 v[0:3], v[218:221], v[202:205], 0
	v_mfma_f32_16x16x32_bf16 v[52:55], v[214:217], v[178:181], v[52:55]
	v_mfma_f32_16x16x32_bf16 v[48:51], v[222:225], v[178:181], v[48:51]
	v_mfma_f32_16x16x32_bf16 v[36:39], v[214:217], v[186:189], v[36:39]
	v_mfma_f32_16x16x32_bf16 v[32:35], v[222:225], v[186:189], v[32:35]
	v_mfma_f32_16x16x32_bf16 v[20:23], v[214:217], v[194:197], v[20:23]
	v_mfma_f32_16x16x32_bf16 v[16:19], v[222:225], v[194:197], v[16:19]
	v_mfma_f32_16x16x32_bf16 v[4:7], v[214:217], v[206:209], v[4:7]
	v_mfma_f32_16x16x32_bf16 v[0:3], v[222:225], v[206:209], v[0:3]
	s_add_i32 s68, 0, 0x18000
	v_add_u32_e32 v136, s68, v170
	s_barrier
	s_setprio 0
	ds_read_b128 v[146:149], v136
	ds_read_b128 v[150:153], v136 offset:1024
	ds_read_b128 v[154:157], v136 offset:2048
	ds_read_b128 v[158:161], v136 offset:3072
	ds_read_b128 v[162:165], v172 offset:32768
	ds_read_b128 v[178:181], v172 offset:33792
	ds_read_b128 v[182:185], v172 offset:34816
	ds_read_b128 v[186:189], v172 offset:35840
	ds_read_b128 v[190:193], v172 offset:36864
	ds_read_b128 v[194:197], v172 offset:37888
	ds_read_b128 v[202:205], v172 offset:38912
	ds_read_b128 v[206:209], v172 offset:39936
	s_waitcnt lgkmcnt(8)
	s_waitcnt vmcnt(8)
	s_setprio 1
	s_barrier
	s_waitcnt lgkmcnt(0)
	v_mfma_f32_16x16x32_bf16 v[124:127], v[146:149], v[162:165], v[124:127]
	v_mfma_f32_16x16x32_bf16 v[120:123], v[154:157], v[162:165], v[120:123]
	v_mfma_f32_16x16x32_bf16 v[108:111], v[146:149], v[182:185], v[108:111]
	v_mfma_f32_16x16x32_bf16 v[104:107], v[154:157], v[182:185], v[104:107]
	v_mfma_f32_16x16x32_bf16 v[92:95], v[146:149], v[190:193], v[92:95]
	v_mfma_f32_16x16x32_bf16 v[88:91], v[154:157], v[190:193], v[88:91]
	v_mfma_f32_16x16x32_bf16 v[76:79], v[146:149], v[202:205], v[76:79]
	v_mfma_f32_16x16x32_bf16 v[72:75], v[154:157], v[202:205], v[72:75]
	v_mfma_f32_16x16x32_bf16 v[124:127], v[150:153], v[178:181], v[124:127]
	v_mfma_f32_16x16x32_bf16 v[120:123], v[158:161], v[178:181], v[120:123]
	v_mfma_f32_16x16x32_bf16 v[108:111], v[150:153], v[186:189], v[108:111]
	v_mfma_f32_16x16x32_bf16 v[104:107], v[158:161], v[186:189], v[104:107]
	v_mfma_f32_16x16x32_bf16 v[92:95], v[150:153], v[194:197], v[92:95]
	v_mfma_f32_16x16x32_bf16 v[88:91], v[158:161], v[194:197], v[88:91]
	v_mfma_f32_16x16x32_bf16 v[76:79], v[150:153], v[206:209], v[76:79]
	v_mfma_f32_16x16x32_bf16 v[72:75], v[158:161], v[206:209], v[72:75]
	s_barrier
	s_setprio 0
	s_add_i32 s6, 0, 0x1c000
	s_add_i32 s7, s68, s44
	v_add_u32_e32 v136, s6, v170
	s_add_u32 s20, s4, 0x80
	s_addc_u32 s21, s5, 0
	s_mov_b32 m0, s7
	ds_read_b128 v[210:213], v136
	ds_read_b128 v[214:217], v136 offset:1024
	ds_read_b128 v[218:221], v136 offset:2048
	ds_read_b128 v[222:225], v136 offset:3072
	global_load_lds_dwordx4 v130, s[20:21]
	s_add_i32 m0, s7, 0x2000
	s_nop 0
	global_load_lds_dwordx4 v134, s[20:21]
	s_waitcnt vmcnt(8)
	s_setprio 1
	s_barrier
	s_waitcnt lgkmcnt(0)
	v_mfma_f32_16x16x32_bf16 v[116:119], v[210:213], v[162:165], v[116:119]
	v_mfma_f32_16x16x32_bf16 v[112:115], v[218:221], v[162:165], v[112:115]
	v_mfma_f32_16x16x32_bf16 v[100:103], v[210:213], v[182:185], v[100:103]
	v_mfma_f32_16x16x32_bf16 v[96:99], v[218:221], v[182:185], v[96:99]
	v_mfma_f32_16x16x32_bf16 v[84:87], v[210:213], v[190:193], v[84:87]
	v_mfma_f32_16x16x32_bf16 v[80:83], v[218:221], v[190:193], v[80:83]
	v_mfma_f32_16x16x32_bf16 v[68:71], v[210:213], v[202:205], v[68:71]
	v_mfma_f32_16x16x32_bf16 v[64:67], v[218:221], v[202:205], v[64:67]
	v_mfma_f32_16x16x32_bf16 v[116:119], v[214:217], v[178:181], v[116:119]
	v_mfma_f32_16x16x32_bf16 v[112:115], v[222:225], v[178:181], v[112:115]
	v_mfma_f32_16x16x32_bf16 v[100:103], v[214:217], v[186:189], v[100:103]
	v_mfma_f32_16x16x32_bf16 v[96:99], v[222:225], v[186:189], v[96:99]
	v_mfma_f32_16x16x32_bf16 v[84:87], v[214:217], v[194:197], v[84:87]
	v_mfma_f32_16x16x32_bf16 v[80:83], v[222:225], v[194:197], v[80:83]
	v_mfma_f32_16x16x32_bf16 v[68:71], v[214:217], v[206:209], v[68:71]
	v_mfma_f32_16x16x32_bf16 v[64:67], v[222:225], v[206:209], v[64:67]
	s_mov_b32 m0, s54
	s_mov_b64 s[20:21], 0x80
	v_lshl_add_u64 v[166:167], v[226:227], 0, s[20:21]
	s_barrier
	s_setprio 0
	ds_read_b128 v[162:165], v172 offset:49152
	ds_read_b128 v[178:181], v172 offset:50176
	ds_read_b128 v[182:185], v172 offset:51200
	ds_read_b128 v[186:189], v172 offset:52224
	ds_read_b128 v[190:193], v172 offset:53248
	ds_read_b128 v[194:197], v172 offset:54272
	ds_read_b128 v[202:205], v172 offset:55296
	ds_read_b128 v[206:209], v172 offset:56320
	global_load_lds_dwordx4 v[166:167], off
	v_lshl_add_u64 v[166:167], v[228:229], 0, s[20:21]
	s_mov_b32 m0, s55
	s_nop 0
	global_load_lds_dwordx4 v[166:167], off
	s_setprio 1
	s_barrier
; #define PG8_STAGE(bufoff, gbase, voff) do { _Pragma("unroll") for (int _i = 0; _i < 2; ++_i) \
;         __builtin_amdgcn_global_load_lds((const unsigned*)((const char*)(gbase) + (voff)[_i]), (LAS unsigned*)(lds + (bufoff) + ldsw + _i * 8192), 16, 0, 0); } while (0)
; #define PG8_LDA(dst, b, h) do { _Pragma("unroll") for (int m = 0; m < 4; ++m) _Pragma("unroll") for (int k = 0; k < 2; ++k) dst[m][k] = *(const LAS bf16x8*)(lds + PG8_SA(b, h) + aoff + m * 2048 + k * 1024); } while (0)
; #define PG8_LDB(dst, b, h) do { _Pragma("unroll") for (int n = 0; n < 2; ++n) _Pragma("unroll") for (int k = 0; k < 2; ++k) dst[n][k] = *(const LAS bf16x8*)(lds + PG8_SB(b, h) + boff + n * 2048 + k * 1024); } while (0)
; #define PG8_MMA(ai, bj, At, Bt) do { __builtin_amdgcn_s_setprio(1); _Pragma("unroll") for (int m = 0; m < 4; ++m) _Pragma("unroll") for (int n = 0; n < 2; ++n) _Pragma("unroll") for (int k = 0; k < 2; ++k) \
;         acc[ai][bj][m][n] = __builtin_amdgcn_mfma_f32_16x16x32_bf16(Bt[n][k], At[m][k], acc[ai][bj][m][n], 0, 0, 0); __builtin_amdgcn_s_setprio(0); } while (0)
; #define PG8_WAIT_V(n) asm volatile("s_waitcnt vmcnt(" #n ")" ::: "memory")
; #define PG8_WAIT_L(n) asm volatile("s_waitcnt lgkmcnt(" #n ")" ::: "memory")
; #define PG8_BAR __builtin_amdgcn_s_barrier()
; #define PG8_SCHED __builtin_amdgcn_sched_barrier(0)
; template <class Epi, class Sched>
; __device__ __forceinline__ void gemm_phase(LAS unsigned char* lds, const Gemm g, const Sched& S, const Epi& E) {
;     ...
;             PG8_LDB(B0, 0, 0); PG8_SCHED; PG8_LDA(At, 0, 0); PG8_STAGE(PG8_SA(1, 1), a1 + hstep, voffA);
;             PG8_WAIT_L(8); PG8_BAR; PG8_WAIT_L(0); PG8_MMA(0, 0, At, B0); PG8_BAR; PG8_SCHED;
;             PG8_LDB(B1, 0, 1); PG8_STAGE(PG8_SB(0, 0), b2, voffB);
;     ...
;             PG8_LDA(At, 1, 1); PG8_STAGE(PG8_SA(1, 0), a3, voffA);
;             PG8_BAR; PG8_WAIT_L(0); PG8_MMA(1, 0, At, B0); PG8_BAR; PG8_SCHED;
;             PG8_STAGE(PG8_SB(1, 1), b3 + hstep, voffB);
;             PG8_WAIT_V(6); PG8_BAR; PG8_MMA(1, 1, At, B1); PG8_BAR;
	s_waitcnt lgkmcnt(0)
	v_mfma_f32_16x16x32_bf16 v[60:63], v[146:149], v[162:165], v[60:63]
	v_mfma_f32_16x16x32_bf16 v[56:59], v[154:157], v[162:165], v[56:59]
	v_mfma_f32_16x16x32_bf16 v[44:47], v[146:149], v[182:185], v[44:47]
	v_mfma_f32_16x16x32_bf16 v[40:43], v[154:157], v[182:185], v[40:43]
	v_mfma_f32_16x16x32_bf16 v[28:31], v[146:149], v[190:193], v[28:31]
	v_mfma_f32_16x16x32_bf16 v[24:27], v[154:157], v[190:193], v[24:27]
	v_mfma_f32_16x16x32_bf16 v[12:15], v[146:149], v[202:205], v[12:15]
	v_mfma_f32_16x16x32_bf16 v[8:11], v[154:157], v[202:205], v[8:11]
	v_mfma_f32_16x16x32_bf16 v[60:63], v[150:153], v[178:181], v[60:63]
	v_mfma_f32_16x16x32_bf16 v[56:59], v[158:161], v[178:181], v[56:59]
	v_mfma_f32_16x16x32_bf16 v[44:47], v[150:153], v[186:189], v[44:47]
	v_mfma_f32_16x16x32_bf16 v[40:43], v[158:161], v[186:189], v[40:43]
	v_mfma_f32_16x16x32_bf16 v[28:31], v[150:153], v[194:197], v[28:31]
	v_mfma_f32_16x16x32_bf16 v[24:27], v[158:161], v[194:197], v[24:27]
	v_mfma_f32_16x16x32_bf16 v[12:15], v[150:153], v[206:209], v[12:15]
	v_mfma_f32_16x16x32_bf16 v[8:11], v[158:161], v[206:209], v[8:11]
	s_barrier
	s_setprio 0
	s_add_u32 s4, s4, 0x40080
	s_addc_u32 s5, s5, 0
	s_add_i32 s6, s6, s44
	s_mov_b32 m0, s6
	s_nop 0
	global_load_lds_dwordx4 v130, s[4:5]
	s_add_i32 m0, s6, 0x2000
	s_nop 0
	global_load_lds_dwordx4 v134, s[4:5]
	s_waitcnt vmcnt(8)
	s_setprio 1
	s_barrier
	v_mfma_f32_16x16x32_bf16 v[52:55], v[210:213], v[162:165], v[52:55]
	v_mfma_f32_16x16x32_bf16 v[48:51], v[218:221], v[162:165], v[48:51]
	v_mfma_f32_16x16x32_bf16 v[36:39], v[210:213], v[182:185], v[36:39]
	v_mfma_f32_16x16x32_bf16 v[32:35], v[218:221], v[182:185], v[32:35]
	v_mfma_f32_16x16x32_bf16 v[20:23], v[210:213], v[190:193], v[20:23]
	v_mfma_f32_16x16x32_bf16 v[16:19], v[218:221], v[190:193], v[16:19]
	v_mfma_f32_16x16x32_bf16 v[4:7], v[210:213], v[202:205], v[4:7]
	v_mfma_f32_16x16x32_bf16 v[0:3], v[218:221], v[202:205], v[0:3]
	v_mfma_f32_16x16x32_bf16 v[52:55], v[214:217], v[178:181], v[52:55]
	v_mfma_f32_16x16x32_bf16 v[48:51], v[222:225], v[178:181], v[48:51]
	v_mfma_f32_16x16x32_bf16 v[36:39], v[214:217], v[186:189], v[36:39]
	v_mfma_f32_16x16x32_bf16 v[32:35], v[222:225], v[186:189], v[32:35]
	v_mfma_f32_16x16x32_bf16 v[20:23], v[214:217], v[194:197], v[20:23]
	v_mfma_f32_16x16x32_bf16 v[16:19], v[222:225], v[194:197], v[16:19]
	v_mfma_f32_16x16x32_bf16 v[4:7], v[214:217], v[206:209], v[4:7]
	v_mfma_f32_16x16x32_bf16 v[0:3], v[222:225], v[206:209], v[0:3]
	s_add_i32 s67, s67, 2
	s_add_u32 s0, s0, 0x100
	s_addc_u32 s1, s1, 0
	s_add_u32 s65, s65, 0x100
	s_addc_u32 s66, s66, 0
	s_cmp_gt_u32 s67, 13
	s_barrier
	s_setprio 0
.LBB0_613:
	ds_read_b128 v[146:149], v171
	ds_read_b128 v[150:153], v171 offset:1024
	ds_read_b128 v[154:157], v171 offset:2048
	ds_read_b128 v[158:161], v171 offset:3072
	s_add_u32 s4, s0, 0xfffc0080
	s_addc_u32 s5, s1, -1
	s_cmp_eq_u32 s67, 12
	s_cselect_b32 s7, s8, s5
	s_cselect_b32 s6, s9, s4
	s_cselect_b32 s5, s31, s66
	s_cselect_b32 s4, s35, s65
	s_add_i32 m0, s45, 0xc000
	ds_read_b128 v[162:165], v172
	ds_read_b128 v[178:181], v172 offset:1024
	ds_read_b128 v[182:185], v172 offset:2048
	ds_read_b128 v[186:189], v172 offset:3072
	ds_read_b128 v[190:193], v172 offset:4096
	ds_read_b128 v[194:197], v172 offset:5120
	ds_read_b128 v[202:205], v172 offset:6144
	ds_read_b128 v[206:209], v172 offset:7168
	global_load_lds_dwordx4 v138, s[0:1]
	s_add_i32 m0, s45, 0xe000
	s_nop 0
	global_load_lds_dwordx4 v140, s[0:1]
	s_waitcnt lgkmcnt(8)
	s_waitcnt vmcnt(8)
	s_setprio 1
	s_barrier
	s_waitcnt lgkmcnt(0)
	v_mfma_f32_16x16x32_bf16 v[124:127], v[146:149], v[162:165], v[124:127]
	v_mfma_f32_16x16x32_bf16 v[120:123], v[154:157], v[162:165], v[120:123]
	v_mfma_f32_16x16x32_bf16 v[108:111], v[146:149], v[182:185], v[108:111]
	v_mfma_f32_16x16x32_bf16 v[104:107], v[154:157], v[182:185], v[104:107]
	v_mfma_f32_16x16x32_bf16 v[92:95], v[146:149], v[190:193], v[92:95]
	v_mfma_f32_16x16x32_bf16 v[88:91], v[154:157], v[190:193], v[88:91]
	v_mfma_f32_16x16x32_bf16 v[76:79], v[146:149], v[202:205], v[76:79]
	v_mfma_f32_16x16x32_bf16 v[72:75], v[154:157], v[202:205], v[72:75]
	v_mfma_f32_16x16x32_bf16 v[124:127], v[150:153], v[178:181], v[124:127]
	v_mfma_f32_16x16x32_bf16 v[120:123], v[158:161], v[178:181], v[120:123]
	v_mfma_f32_16x16x32_bf16 v[108:111], v[150:153], v[186:189], v[108:111]
	v_mfma_f32_16x16x32_bf16 v[104:107], v[158:161], v[186:189], v[104:107]
	v_mfma_f32_16x16x32_bf16 v[92:95], v[150:153], v[194:197], v[92:95]
	v_mfma_f32_16x16x32_bf16 v[88:91], v[158:161], v[194:197], v[88:91]
	v_mfma_f32_16x16x32_bf16 v[76:79], v[150:153], v[206:209], v[76:79]
	v_mfma_f32_16x16x32_bf16 v[72:75], v[158:161], v[206:209], v[72:75]
	s_barrier
	s_setprio 0
	s_add_i32 s68, s57, s44
	s_mov_b32 m0, s68
	ds_read_b128 v[210:213], v173
	ds_read_b128 v[214:217], v173 offset:1024
	ds_read_b128 v[218:221], v173 offset:2048
	ds_read_b128 v[222:225], v173 offset:3072
	global_load_lds_dwordx4 v130, s[4:5]
	s_add_i32 m0, s68, 0x2000
	s_nop 0
	global_load_lds_dwordx4 v134, s[4:5]
	s_waitcnt vmcnt(8)
	s_setprio 1
	s_barrier
; #define PG8_STAGE(bufoff, gbase, voff) do { _Pragma("unroll") for (int _i = 0; _i < 2; ++_i) \
;         __builtin_amdgcn_global_load_lds((const unsigned*)((const char*)(gbase) + (voff)[_i]), (LAS unsigned*)(lds + (bufoff) + ldsw + _i * 8192), 16, 0, 0); } while (0)
; #define PG8_LDA(dst, b, h) do { _Pragma("unroll") for (int m = 0; m < 4; ++m) _Pragma("unroll") for (int k = 0; k < 2; ++k) dst[m][k] = *(const LAS bf16x8*)(lds + PG8_SA(b, h) + aoff + m * 2048 + k * 1024); } while (0)
; #define PG8_LDB(dst, b, h) do { _Pragma("unroll") for (int n = 0; n < 2; ++n) _Pragma("unroll") for (int k = 0; k < 2; ++k) dst[n][k] = *(const LAS bf16x8*)(lds + PG8_SB(b, h) + boff + n * 2048 + k * 1024); } while (0)
; #define PG8_MMA(ai, bj, At, Bt) do { __builtin_amdgcn_s_setprio(1); _Pragma("unroll") for (int m = 0; m < 4; ++m) _Pragma("unroll") for (int n = 0; n < 2; ++n) _Pragma("unroll") for (int k = 0; k < 2; ++k) \
;         acc[ai][bj][m][n] = __builtin_amdgcn_mfma_f32_16x16x32_bf16(Bt[n][k], At[m][k], acc[ai][bj][m][n], 0, 0, 0); __builtin_amdgcn_s_setprio(0); } while (0)
; #define PG8_WAIT_V(n) asm volatile("s_waitcnt vmcnt(" #n ")" ::: "memory")
; #define PG8_WAIT_L(n) asm volatile("s_waitcnt lgkmcnt(" #n ")" ::: "memory")
; #define PG8_BAR __builtin_amdgcn_s_barrier()
; #define PG8_SCHED __builtin_amdgcn_sched_barrier(0)
; template <class Epi, class Sched>
; __device__ __forceinline__ void gemm_phase(LAS unsigned char* lds, const Gemm g, const Sched& S, const Epi& E) {
;     ...
;             PG8_BAR; PG8_WAIT_L(0); PG8_MMA(0, 1, At, B1); PG8_BAR;
;             PG8_LDA(At, 0, 1); PG8_STAGE(PG8_SA(0, 0), a2, voffA);
;             PG8_BAR; PG8_WAIT_L(0); PG8_MMA(1, 0, At, B0); PG8_BAR; PG8_SCHED;
;             PG8_STAGE(PG8_SB(0, 1), b2 + hstep, voffB);
;             PG8_WAIT_V(6); PG8_BAR; PG8_MMA(1, 1, At, B1); PG8_BAR;
;             PG8_LDB(B0, 1, 0); PG8_SCHED; PG8_LDA(At, 1, 0); PG8_STAGE(PG8_SA(0, 1), a2 + hstep, voffA);
;             PG8_WAIT_L(8); PG8_BAR; PG8_WAIT_L(0); PG8_MMA(0, 0, At, B0); PG8_BAR; PG8_SCHED;
;             PG8_LDB(B1, 1, 1); PG8_STAGE(PG8_SB(1, 0), b3, voffB);
	s_waitcnt lgkmcnt(0)
	v_mfma_f32_16x16x32_bf16 v[116:119], v[210:213], v[162:165], v[116:119]
	v_mfma_f32_16x16x32_bf16 v[112:115], v[218:221], v[162:165], v[112:115]
	v_mfma_f32_16x16x32_bf16 v[100:103], v[210:213], v[182:185], v[100:103]
	v_mfma_f32_16x16x32_bf16 v[96:99], v[218:221], v[182:185], v[96:99]
	v_mfma_f32_16x16x32_bf16 v[84:87], v[210:213], v[190:193], v[84:87]
	v_mfma_f32_16x16x32_bf16 v[80:83], v[218:221], v[190:193], v[80:83]
	v_mfma_f32_16x16x32_bf16 v[68:71], v[210:213], v[202:205], v[68:71]
	v_mfma_f32_16x16x32_bf16 v[64:67], v[218:221], v[202:205], v[64:67]
	v_mfma_f32_16x16x32_bf16 v[116:119], v[214:217], v[178:181], v[116:119]
	v_mfma_f32_16x16x32_bf16 v[112:115], v[222:225], v[178:181], v[112:115]
	v_mfma_f32_16x16x32_bf16 v[100:103], v[214:217], v[186:189], v[100:103]
	v_mfma_f32_16x16x32_bf16 v[96:99], v[222:225], v[186:189], v[96:99]
	v_mfma_f32_16x16x32_bf16 v[84:87], v[214:217], v[194:197], v[84:87]
	v_mfma_f32_16x16x32_bf16 v[80:83], v[222:225], v[194:197], v[80:83]
	v_mfma_f32_16x16x32_bf16 v[68:71], v[214:217], v[206:209], v[68:71]
	v_mfma_f32_16x16x32_bf16 v[64:67], v[222:225], v[206:209], v[64:67]
	s_mov_b32 m0, s45
	v_lshl_add_u64 v[226:227], s[6:7], 0, v[128:129]
	s_barrier
	s_setprio 0
	ds_read_b128 v[162:165], v172 offset:16384
	ds_read_b128 v[178:181], v172 offset:17408
	ds_read_b128 v[182:185], v172 offset:18432
	ds_read_b128 v[186:189], v172 offset:19456
	ds_read_b128 v[190:193], v172 offset:20480
	ds_read_b128 v[194:197], v172 offset:21504
	ds_read_b128 v[202:205], v172 offset:22528
	ds_read_b128 v[206:209], v172 offset:23552
	global_load_lds_dwordx4 v128, s[6:7]
	v_lshl_add_u64 v[228:229], s[6:7], 0, v[132:133]
	s_mov_b32 m0, s46
	s_nop 0
	global_load_lds_dwordx4 v132, s[6:7]
	s_setprio 1
	s_barrier
	s_waitcnt lgkmcnt(0)
	v_mfma_f32_16x16x32_bf16 v[60:63], v[146:149], v[162:165], v[60:63]
	v_mfma_f32_16x16x32_bf16 v[56:59], v[154:157], v[162:165], v[56:59]
	v_mfma_f32_16x16x32_bf16 v[44:47], v[146:149], v[182:185], v[44:47]
	v_mfma_f32_16x16x32_bf16 v[40:43], v[154:157], v[182:185], v[40:43]
	v_mfma_f32_16x16x32_bf16 v[28:31], v[146:149], v[190:193], v[28:31]
	v_mfma_f32_16x16x32_bf16 v[24:27], v[154:157], v[190:193], v[24:27]
	v_mfma_f32_16x16x32_bf16 v[12:15], v[146:149], v[202:205], v[12:15]
	v_mfma_f32_16x16x32_bf16 v[8:11], v[154:157], v[202:205], v[8:11]
	v_mfma_f32_16x16x32_bf16 v[60:63], v[150:153], v[178:181], v[60:63]
	v_mfma_f32_16x16x32_bf16 v[56:59], v[158:161], v[178:181], v[56:59]
	v_mfma_f32_16x16x32_bf16 v[44:47], v[150:153], v[186:189], v[44:47]
	v_mfma_f32_16x16x32_bf16 v[40:43], v[158:161], v[186:189], v[40:43]
	v_mfma_f32_16x16x32_bf16 v[28:31], v[150:153], v[194:197], v[28:31]
	v_mfma_f32_16x16x32_bf16 v[24:27], v[158:161], v[194:197], v[24:27]
	v_mfma_f32_16x16x32_bf16 v[12:15], v[150:153], v[206:209], v[12:15]
	v_mfma_f32_16x16x32_bf16 v[8:11], v[158:161], v[206:209], v[8:11]
	s_barrier
	s_setprio 0
	s_add_u32 s68, s4, 0x40000
	s_addc_u32 s69, s5, 0
	s_add_i32 s70, s58, s44
	s_mov_b32 m0, s70
	s_nop 0
	global_load_lds_dwordx4 v130, s[68:69]
	s_add_i32 m0, s70, 0x2000
	s_nop 0
	global_load_lds_dwordx4 v134, s[68:69]
	s_add_u32 s6, s6, 0x40000
	s_addc_u32 s7, s7, 0
	s_mov_b32 m0, s47
	s_nop 0
	global_load_lds_dwordx4 v128, s[6:7]
	s_mov_b32 m0, s48
	s_nop 0
	global_load_lds_dwordx4 v132, s[6:7]
	s_waitcnt vmcnt(10)
	s_setprio 1
	s_barrier
	v_mfma_f32_16x16x32_bf16 v[52:55], v[210:213], v[162:165], v[52:55]
	v_mfma_f32_16x16x32_bf16 v[48:51], v[218:221], v[162:165], v[48:51]
	v_mfma_f32_16x16x32_bf16 v[36:39], v[210:213], v[182:185], v[36:39]
	v_mfma_f32_16x16x32_bf16 v[32:35], v[218:221], v[182:185], v[32:35]
	v_mfma_f32_16x16x32_bf16 v[20:23], v[210:213], v[190:193], v[20:23]
	v_mfma_f32_16x16x32_bf16 v[16:19], v[218:221], v[190:193], v[16:19]
	v_mfma_f32_16x16x32_bf16 v[4:7], v[210:213], v[202:205], v[4:7]
	v_mfma_f32_16x16x32_bf16 v[0:3], v[218:221], v[202:205], v[0:3]
	v_mfma_f32_16x16x32_bf16 v[52:55], v[214:217], v[178:181], v[52:55]
	v_mfma_f32_16x16x32_bf16 v[48:51], v[222:225], v[178:181], v[48:51]
	v_mfma_f32_16x16x32_bf16 v[36:39], v[214:217], v[186:189], v[36:39]
	v_mfma_f32_16x16x32_bf16 v[32:35], v[222:225], v[186:189], v[32:35]
	v_mfma_f32_16x16x32_bf16 v[20:23], v[214:217], v[194:197], v[20:23]
	v_mfma_f32_16x16x32_bf16 v[16:19], v[222:225], v[194:197], v[16:19]
	v_mfma_f32_16x16x32_bf16 v[4:7], v[214:217], v[206:209], v[4:7]
	v_mfma_f32_16x16x32_bf16 v[0:3], v[222:225], v[206:209], v[0:3]
	s_add_i32 s68, 0, 0x18000
	v_add_u32_e32 v136, s68, v170
	s_barrier
	s_setprio 0
	ds_read_b128 v[146:149], v136
	ds_read_b128 v[150:153], v136 offset:1024
	ds_read_b128 v[154:157], v136 offset:2048
	ds_read_b128 v[158:161], v136 offset:3072
	ds_read_b128 v[162:165], v172 offset:32768
	ds_read_b128 v[178:181], v172 offset:33792
	ds_read_b128 v[182:185], v172 offset:34816
	ds_read_b128 v[186:189], v172 offset:35840
	ds_read_b128 v[190:193], v172 offset:36864
	ds_read_b128 v[194:197], v172 offset:37888
	ds_read_b128 v[202:205], v172 offset:38912
	ds_read_b128 v[206:209], v172 offset:39936
	s_waitcnt lgkmcnt(8)
	s_waitcnt vmcnt(8)
	s_setprio 1
	s_barrier
; #define PG8_STAGE(bufoff, gbase, voff) do { _Pragma("unroll") for (int _i = 0; _i < 2; ++_i) \
;         __builtin_amdgcn_global_load_lds((const unsigned*)((const char*)(gbase) + (voff)[_i]), (LAS unsigned*)(lds + (bufoff) + ldsw + _i * 8192), 16, 0, 0); } while (0)
; #define PG8_LDA(dst, b, h) do { _Pragma("unroll") for (int m = 0; m < 4; ++m) _Pragma("unroll") for (int k = 0; k < 2; ++k) dst[m][k] = *(const LAS bf16x8*)(lds + PG8_SA(b, h) + aoff + m * 2048 + k * 1024); } while (0)
; #define PG8_LDB(dst, b, h) do { _Pragma("unroll") for (int n = 0; n < 2; ++n) _Pragma("unroll") for (int k = 0; k < 2; ++k) dst[n][k] = *(const LAS bf16x8*)(lds + PG8_SB(b, h) + boff + n * 2048 + k * 1024); } while (0)
; #define PG8_MMA(ai, bj, At, Bt) do { __builtin_amdgcn_s_setprio(1); _Pragma("unroll") for (int m = 0; m < 4; ++m) _Pragma("unroll") for (int n = 0; n < 2; ++n) _Pragma("unroll") for (int k = 0; k < 2; ++k) \
;         acc[ai][bj][m][n] = __builtin_amdgcn_mfma_f32_16x16x32_bf16(Bt[n][k], At[m][k], acc[ai][bj][m][n], 0, 0, 0); __builtin_amdgcn_s_setprio(0); } while (0)
; #define PG8_WAIT_V(n) asm volatile("s_waitcnt vmcnt(" #n ")" ::: "memory")
; #define PG8_WAIT_L(n) asm volatile("s_waitcnt lgkmcnt(" #n ")" ::: "memory")
; #define PG8_BAR __builtin_amdgcn_s_barrier()
; #define PG8_SCHED __builtin_amdgcn_sched_barrier(0)
; template <class Epi, class Sched>
; __device__ __forceinline__ void gemm_phase(LAS unsigned char* lds, const Gemm g, const Sched& S, const Epi& E) {
;     ...
;             PG8_WAIT_L(8); PG8_BAR; PG8_WAIT_L(0); PG8_MMA(0, 0, At, B0); PG8_BAR; PG8_SCHED;
;             PG8_LDB(B1, 1, 1); PG8_STAGE(PG8_SB(1, 0), b3, voffB);
;             PG8_BAR; PG8_WAIT_L(0); PG8_MMA(0, 1, At, B1); PG8_BAR;
;             PG8_LDA(At, 1, 1); PG8_STAGE(PG8_SA(1, 0), a3, voffA);
;             PG8_BAR; PG8_WAIT_L(0); PG8_MMA(1, 0, At, B0); PG8_BAR; PG8_SCHED;
;             PG8_STAGE(PG8_SB(1, 1), b3 + hstep, voffB);
;             PG8_WAIT_V(6); PG8_BAR; PG8_MMA(1, 1, At, B1); PG8_BAR;
;         }
	s_waitcnt lgkmcnt(0)
	v_mfma_f32_16x16x32_bf16 v[124:127], v[146:149], v[162:165], v[124:127]
	v_mfma_f32_16x16x32_bf16 v[120:123], v[154:157], v[162:165], v[120:123]
	v_mfma_f32_16x16x32_bf16 v[108:111], v[146:149], v[182:185], v[108:111]
	v_mfma_f32_16x16x32_bf16 v[104:107], v[154:157], v[182:185], v[104:107]
	v_mfma_f32_16x16x32_bf16 v[92:95], v[146:149], v[190:193], v[92:95]
	v_mfma_f32_16x16x32_bf16 v[88:91], v[154:157], v[190:193], v[88:91]
	v_mfma_f32_16x16x32_bf16 v[76:79], v[146:149], v[202:205], v[76:79]
	v_mfma_f32_16x16x32_bf16 v[72:75], v[154:157], v[202:205], v[72:75]
	v_mfma_f32_16x16x32_bf16 v[124:127], v[150:153], v[178:181], v[124:127]
	v_mfma_f32_16x16x32_bf16 v[120:123], v[158:161], v[178:181], v[120:123]
	v_mfma_f32_16x16x32_bf16 v[108:111], v[150:153], v[186:189], v[108:111]
	v_mfma_f32_16x16x32_bf16 v[104:107], v[158:161], v[186:189], v[104:107]
	v_mfma_f32_16x16x32_bf16 v[92:95], v[150:153], v[194:197], v[92:95]
	v_mfma_f32_16x16x32_bf16 v[88:91], v[158:161], v[194:197], v[88:91]
	v_mfma_f32_16x16x32_bf16 v[76:79], v[150:153], v[206:209], v[76:79]
	v_mfma_f32_16x16x32_bf16 v[72:75], v[158:161], v[206:209], v[72:75]
	s_barrier
	s_setprio 0
	s_add_i32 s6, 0, 0x1c000
	s_add_i32 s7, s68, s44
	v_add_u32_e32 v136, s6, v170
	s_add_u32 s20, s4, 0x80
	s_addc_u32 s21, s5, 0
	s_mov_b32 m0, s7
	ds_read_b128 v[210:213], v136
	ds_read_b128 v[214:217], v136 offset:1024
	ds_read_b128 v[218:221], v136 offset:2048
	ds_read_b128 v[222:225], v136 offset:3072
	global_load_lds_dwordx4 v130, s[20:21]
	s_add_i32 m0, s7, 0x2000
	s_nop 0
	global_load_lds_dwordx4 v134, s[20:21]
	s_waitcnt vmcnt(8)
	s_setprio 1
	s_barrier
	s_waitcnt lgkmcnt(0)
	v_mfma_f32_16x16x32_bf16 v[116:119], v[210:213], v[162:165], v[116:119]
	v_mfma_f32_16x16x32_bf16 v[112:115], v[218:221], v[162:165], v[112:115]
	v_mfma_f32_16x16x32_bf16 v[100:103], v[210:213], v[182:185], v[100:103]
	v_mfma_f32_16x16x32_bf16 v[96:99], v[218:221], v[182:185], v[96:99]
	v_mfma_f32_16x16x32_bf16 v[84:87], v[210:213], v[190:193], v[84:87]
	v_mfma_f32_16x16x32_bf16 v[80:83], v[218:221], v[190:193], v[80:83]
	v_mfma_f32_16x16x32_bf16 v[68:71], v[210:213], v[202:205], v[68:71]
	v_mfma_f32_16x16x32_bf16 v[64:67], v[218:221], v[202:205], v[64:67]
	v_mfma_f32_16x16x32_bf16 v[116:119], v[214:217], v[178:181], v[116:119]
	v_mfma_f32_16x16x32_bf16 v[112:115], v[222:225], v[178:181], v[112:115]
	v_mfma_f32_16x16x32_bf16 v[100:103], v[214:217], v[186:189], v[100:103]
	v_mfma_f32_16x16x32_bf16 v[96:99], v[222:225], v[186:189], v[96:99]
	v_mfma_f32_16x16x32_bf16 v[84:87], v[214:217], v[194:197], v[84:87]
	v_mfma_f32_16x16x32_bf16 v[80:83], v[222:225], v[194:197], v[80:83]
	v_mfma_f32_16x16x32_bf16 v[68:71], v[214:217], v[206:209], v[68:71]
	v_mfma_f32_16x16x32_bf16 v[64:67], v[222:225], v[206:209], v[64:67]
	s_mov_b32 m0, s54
	s_mov_b64 s[20:21], 0x80
	v_lshl_add_u64 v[166:167], v[226:227], 0, s[20:21]
	s_barrier
	s_setprio 0
	ds_read_b128 v[162:165], v172 offset:49152
	ds_read_b128 v[178:181], v172 offset:50176
	ds_read_b128 v[182:185], v172 offset:51200
	ds_read_b128 v[186:189], v172 offset:52224
	ds_read_b128 v[190:193], v172 offset:53248
	ds_read_b128 v[194:197], v172 offset:54272
	ds_read_b128 v[202:205], v172 offset:55296
	ds_read_b128 v[206:209], v172 offset:56320
	global_load_lds_dwordx4 v[166:167], off
	v_lshl_add_u64 v[166:167], v[228:229], 0, s[20:21]
	s_mov_b32 m0, s55
	s_nop 0
	global_load_lds_dwordx4 v[166:167], off
	s_setprio 1
	s_barrier
	s_waitcnt lgkmcnt(0)
	v_mfma_f32_16x16x32_bf16 v[60:63], v[146:149], v[162:165], v[60:63]
	v_mfma_f32_16x16x32_bf16 v[56:59], v[154:157], v[162:165], v[56:59]
	v_mfma_f32_16x16x32_bf16 v[44:47], v[146:149], v[182:185], v[44:47]
	v_mfma_f32_16x16x32_bf16 v[40:43], v[154:157], v[182:185], v[40:43]
	v_mfma_f32_16x16x32_bf16 v[28:31], v[146:149], v[190:193], v[28:31]
	v_mfma_f32_16x16x32_bf16 v[24:27], v[154:157], v[190:193], v[24:27]
	v_mfma_f32_16x16x32_bf16 v[12:15], v[146:149], v[202:205], v[12:15]
	v_mfma_f32_16x16x32_bf16 v[8:11], v[154:157], v[202:205], v[8:11]
	v_mfma_f32_16x16x32_bf16 v[60:63], v[150:153], v[178:181], v[60:63]
	v_mfma_f32_16x16x32_bf16 v[56:59], v[158:161], v[178:181], v[56:59]
	v_mfma_f32_16x16x32_bf16 v[44:47], v[150:153], v[186:189], v[44:47]
	v_mfma_f32_16x16x32_bf16 v[40:43], v[158:161], v[186:189], v[40:43]
	v_mfma_f32_16x16x32_bf16 v[28:31], v[150:153], v[194:197], v[28:31]
	v_mfma_f32_16x16x32_bf16 v[24:27], v[158:161], v[194:197], v[24:27]
	v_mfma_f32_16x16x32_bf16 v[12:15], v[150:153], v[206:209], v[12:15]
	v_mfma_f32_16x16x32_bf16 v[8:11], v[158:161], v[206:209], v[8:11]
	s_barrier
	s_setprio 0
	s_add_u32 s4, s4, 0x40080
	s_addc_u32 s5, s5, 0
	s_add_i32 s6, s6, s44
	s_mov_b32 m0, s6
	s_nop 0
	global_load_lds_dwordx4 v130, s[4:5]
	s_add_i32 m0, s6, 0x2000
	s_nop 0
	global_load_lds_dwordx4 v134, s[4:5]
	s_waitcnt vmcnt(8)
	s_setprio 1
	s_barrier
	v_mfma_f32_16x16x32_bf16 v[52:55], v[210:213], v[162:165], v[52:55]
	v_mfma_f32_16x16x32_bf16 v[48:51], v[218:221], v[162:165], v[48:51]
	v_mfma_f32_16x16x32_bf16 v[36:39], v[210:213], v[182:185], v[36:39]
	v_mfma_f32_16x16x32_bf16 v[32:35], v[218:221], v[182:185], v[32:35]
	v_mfma_f32_16x16x32_bf16 v[20:23], v[210:213], v[190:193], v[20:23]
	v_mfma_f32_16x16x32_bf16 v[16:19], v[218:221], v[190:193], v[16:19]
	v_mfma_f32_16x16x32_bf16 v[4:7], v[210:213], v[202:205], v[4:7]
	v_mfma_f32_16x16x32_bf16 v[0:3], v[218:221], v[202:205], v[0:3]
	v_mfma_f32_16x16x32_bf16 v[52:55], v[214:217], v[178:181], v[52:55]
	v_mfma_f32_16x16x32_bf16 v[48:51], v[222:225], v[178:181], v[48:51]
	v_mfma_f32_16x16x32_bf16 v[36:39], v[214:217], v[186:189], v[36:39]
	v_mfma_f32_16x16x32_bf16 v[32:35], v[222:225], v[186:189], v[32:35]
	v_mfma_f32_16x16x32_bf16 v[20:23], v[214:217], v[194:197], v[20:23]
	v_mfma_f32_16x16x32_bf16 v[16:19], v[222:225], v[194:197], v[16:19]
	v_mfma_f32_16x16x32_bf16 v[4:7], v[214:217], v[206:209], v[4:7]
	v_mfma_f32_16x16x32_bf16 v[0:3], v[222:225], v[206:209], v[0:3]
	s_add_i32 s67, s67, 2
	s_add_u32 s0, s0, 0x100
	s_addc_u32 s1, s1, 0
	s_add_u32 s65, s65, 0x100
	s_addc_u32 s66, s66, 0
	s_cmp_gt_u32 s67, 13
	s_barrier
;     __device__ __forceinline__ void operator()(const AccT& acc, const Unit& u, int wr, int wc, int fr, int fq) const {
;     ...
;         const int rbase = wr * 64 + fr;
;         const int tb = u.pn * 256 + wc * 32 + 8 * fq;
;         const int o0 = wc * 32 + 8 * fq;
;         const int j = fr & 3; const float sgn = ((fr >> 2) & 1) ? 1.0f : -1.0f;
; #pragma unroll
;         for (int ai = 0; ai < 2; ++ai) {
;             const int hh = 2 * ai + wr;
;             const float l2f = lgd[hh] * 1.4426950408889634f, l2b = lgd[4 + hh] * 1.4426950408889634f;
;             const float zf0 = exp2f((float)(127 - o0) * l2f), zfs = exp2f(-l2f), zb0 = exp2f((float)o0 * l2b), zbs = exp2f(l2b);
; #pragma unroll
;             for (int m = 0; m < 4; ++m) {
;                 const int r = rbase + ai * 128 + m * 16;
;                 const int d = 4 * (2 * m + (fr >> 3)) + j;
; #pragma unroll
;                 for (int bj = 0; bj < 2; ++bj) {
;                     const int t0 = tb + bj * 128;
;                     float v[8];
; #pragma unroll
;                     for (int jj = 0; jj < 4; ++jj) { v[jj] = acc[ai][bj][m][0][jj]; v[4 + jj] = acc[ai][bj][m][1][jj]; }
;                     if constexpr (ROPE) {
;                         const int t = t0 & 2047;
; #pragma unroll
;                         for (int hf = 0; hf < 2; ++hf) {
;                             f32x4 cs, sn;
;                             if (m < 2) { const float c1 = ropeA[(t >> 6) * 16 + d], s1 = ropeA[1024 + (t >> 6) * 16 + d]; cs = (f32x4){c1, c1, c1, c1}; sn = (f32x4){s1, s1, s1, s1}; }
;                             else { const float* cb = ropeA + 2048 + (d - 16) * 64 + (t & 63) + 4 * hf; cs = *(const f32x4*)(cb); sn = *(const f32x4*)(cb + 1024); }
; #pragma unroll
;                             for (int jj = 0; jj < 4; ++jj) { const float pr = __shfl_xor(v[4 * hf + jj], 4); v[4 * hf + jj] = v[4 * hf + jj] * cs[jj] + sgn * pr * sn[jj]; }
;                             __builtin_amdgcn_sched_barrier(0);
;                         }
;                     }
;                     float zf[8], zb[8]; zf[0] = zf0; zb[0] = zb0;
; #pragma unroll
;                     for (int jj = 1; jj < 8; ++jj) { zf[jj] = zf[jj - 1] * zfs; zb[jj] = zb[jj - 1] * zbs; }
;                     u32x4 wf, wb;
	s_setprio 0
	s_cbranch_scc0 .LBB0_613
	v_mov_b32_e32 v136, v169
	v_mov_b32_e32 v150, v168
	s_lshl_b32 s0, s33, 8
	global_load_dword v154, v137, s[22:23]
	global_load_dword v155, v137, s[22:23] offset:16
	s_or_b32 s0, s0, s53
	v_lshlrev_b32_e32 v151, 3, v136
	v_ashrrev_i32_e32 v136, 1, v150
	v_add_u32_e32 v162, s0, v151
	v_bfi_b32 v136, -4, v136, v150
	v_lshrrev_b32_e32 v146, 2, v162
	v_add_u32_e32 v192, 0x400, v136
	v_and_b32_e32 v187, 0x1f0, v146
	v_add_u32_e32 v146, v192, v187
	v_add_u32_e32 v148, v187, v136
	v_ashrrev_i32_e32 v147, 31, v146
	v_ashrrev_i32_e32 v149, 31, v148
	v_lshl_add_u64 v[146:147], v[146:147], 2, s[16:17]
	v_lshl_add_u64 v[148:149], v[148:149], 2, s[16:17]
	global_load_dword v153, v[146:147], off
	global_load_dword v166, v[148:149], off
	v_and_b32_e32 v157, 64, v174
	v_xor_b32_e32 v156, 4, v174
	v_add_u32_e32 v157, 64, v157
	v_cmp_lt_i32_e32 vcc, v156, v157
	v_mov_b32_e32 v152, v124
	v_add_u32_e32 v151, s53, v151
	v_cndmask_b32_e32 v156, v174, v156, vcc
	v_lshlrev_b32_e32 v177, 2, v156
	ds_bpermute_b32 v124, v177, v124
	v_sub_u32_e32 v156, 0x7f, v151
	v_add_u32_e32 v164, s52, v150
	v_and_b32_e32 v150, 4, v150
	v_cvt_f32_i32_e32 v179, v156
	v_cvt_f32_i32_e32 v178, v151
	v_cmp_eq_u32_e32 vcc, 0, v150
	ds_bpermute_b32 v157, v177, v125
	ds_bpermute_b32 v158, v177, v127
	s_waitcnt lgkmcnt(0)
	v_cndmask_b32_e64 v167, v124, -v124, vcc
	ds_bpermute_b32 v151, v177, v126
	v_ashrrev_i32_e32 v165, 31, v164
	v_and_b32_e32 v186, 56, v162
	s_waitcnt lgkmcnt(0)
	v_cndmask_b32_e64 v151, v151, -v151, vcc
	s_waitcnt vmcnt(0)
	v_mul_f32_e32 v124, 0x3fb8aa3b, v154
	v_mul_f32_e32 v150, 0x3fb8aa3b, v155
	v_cmp_lt_f32_e64 s[4:5], s60, v124
	v_mul_f32_e32 v156, v124, v179
	v_cmp_gt_f32_e64 s[6:7], s59, v150
	v_cndmask_b32_e64 v159, 0, v176, s[4:5]
	v_mul_f32_e32 v160, v150, v178
	v_cndmask_b32_e64 v161, 0, v176, s[6:7]
	v_cmp_gt_f32_e64 s[8:9], s59, v156
	v_fmac_f32_e32 v159, 0xbfb8aa3b, v154
	s_and_b64 s[0:1], s[4:5], exec
	v_cmp_gt_f32_e64 s[4:5], s59, v160
	v_fmac_f32_e32 v161, 0x3fb8aa3b, v155
	v_cndmask_b32_e64 v154, 0, v176, s[8:9]
	v_exp_f32_e32 v155, v159
	v_cndmask_b32_e64 v159, 0, v176, s[4:5]
	v_fmac_f32_e32 v154, v124, v179
	v_fmac_f32_e32 v159, v150, v178
	v_exp_f32_e32 v150, v154
	v_cndmask_b32_e64 v156, 0, v175, s[8:9]
	s_cselect_b32 s8, 0xffffffc0, 0
	v_exp_f32_e32 v161, v161
	v_exp_f32_e32 v159, v159
	v_ldexp_f32 v163, v155, s8
	v_pk_mul_f32 v[154:155], v[152:153], v[166:167]
	v_cndmask_b32_e64 v167, v157, -v157, vcc
	v_mov_b32_e32 v152, v125
	s_and_b64 s[0:1], s[6:7], exec
	v_add_f32_e32 v190, v154, v155
	v_pk_mul_f32 v[154:155], v[152:153], v[166:167]
	v_cndmask_b32_e64 v167, v158, -v158, vcc
	v_mov_b32_e32 v152, v127
	v_cndmask_b32_e64 v160, 0, v175, s[4:5]
	s_cselect_b32 s0, 0xffffffc0, 0
	v_ldexp_f32 v180, v150, v156
	v_add_f32_e32 v191, v154, v155
	v_pk_mul_f32 v[154:155], v[152:153], v[166:167]
	v_ldexp_f32 v124, v161, s0
	v_mul_f32_e32 v161, v126, v166
	v_ldexp_f32 v150, v159, v160
	v_mul_f32_e32 v181, v163, v180
	v_add_f32_e32 v193, v154, v155
	global_load_dword v188, v[148:149], off
	global_load_dword v157, v[146:147], off
	ds_bpermute_b32 v127, v177, v121
	v_mov_b32_e32 v156, v121
	ds_bpermute_b32 v121, v177, v123
	ds_bpermute_b32 v125, v177, v120
	ds_bpermute_b32 v152, v177, v122
	s_waitcnt lgkmcnt(3)
	v_cndmask_b32_e64 v189, v127, -v127, vcc
	s_waitcnt lgkmcnt(1)
	v_cndmask_b32_e64 v158, v125, -v125, vcc
	s_waitcnt lgkmcnt(0)
	v_cndmask_b32_e64 v127, v152, -v152, vcc
	s_waitcnt vmcnt(1)
	v_mul_f32_e32 v159, v120, v188
	s_waitcnt vmcnt(0)
	v_pk_mul_f32 v[154:155], v[156:157], v[188:189]
	v_cndmask_b32_e64 v189, v121, -v121, vcc
	v_mov_b32_e32 v156, v123
	v_add_f32_e32 v121, v154, v155
	v_pk_mul_f32 v[154:155], v[156:157], v[188:189]
	s_nop 0
	v_add_f32_e32 v123, v154, v155
	v_mov_b32_e32 v125, v153
	v_pk_mul_f32 v[152:153], v[124:125], v[150:151]
	v_mov_b32_e32 v125, v161
	v_pk_mul_f32 v[154:155], v[124:125], v[152:153]
	v_mov_b32_e32 v125, v157
	v_mov_b32_e32 v155, v158
	v_pk_mul_f32 v[156:157], v[124:125], v[154:155]
	v_mov_b32_e32 v158, v124
	v_pk_mul_f32 v[158:159], v[158:159], v[156:157]
	v_mul_f32_e32 v167, v163, v181
	v_mov_b32_e32 v159, v127
	v_mul_f32_e32 v183, v163, v167
	v_pk_mul_f32 v[160:161], v[124:125], v[158:159]
	v_mul_f32_e32 v182, v163, v183
	v_mul_f32_e32 v151, v124, v160
	v_mul_f32_e32 v185, v163, v182
	v_mul_f32_e32 v155, v124, v151
	v_mul_f32_e32 v124, v180, v190
	v_mul_f32_e32 v125, v181, v191
	v_fma_f32 v153, v126, v166, v153
	v_mul_f32_e32 v184, v163, v185
	v_cvt_pk_bf16_f32 v124, v124, v125
	v_mul_f32_e32 v125, v167, v153
	v_mul_f32_e32 v126, v183, v193
	v_fma_f32 v120, v120, v188, v157
	v_mul_f32_e32 v159, v163, v184
	v_cvt_pk_bf16_f32 v125, v125, v126
	v_mul_f32_e32 v126, v182, v120
	v_mul_f32_e32 v127, v185, v121
	v_fma_f32 v122, v122, v188, v161
	v_cvt_pk_bf16_f32 v126, v126, v127
	v_mul_f32_e32 v127, v184, v122
	v_mul_f32_e32 v157, v159, v123
	v_cvt_pk_bf16_f32 v127, v127, v157
	v_mul_f32_e32 v157, v150, v190
	v_mul_f32_e32 v120, v158, v120
	v_mul_f32_e32 v121, v160, v121
	v_mul_f32_e32 v161, v152, v191
	v_cvt_pk_bf16_f32 v188, v157, v161
	v_mul_f32_e32 v153, v154, v153
	v_mul_f32_e32 v157, v156, v193
	v_cvt_pk_bf16_f32 v189, v153, v157
	v_cvt_pk_bf16_f32 v190, v120, v121
	v_mul_f32_e32 v120, v151, v122
	v_mul_f32_e32 v121, v155, v123
	v_cvt_pk_bf16_f32 v191, v120, v121
	v_lshlrev_b64 v[120:121], 17, v[164:165]
	v_lshl_add_u64 v[120:121], s[80:81], 0, v[120:121]
	v_ashrrev_i32_e32 v163, 31, v162
	v_lshl_add_u64 v[120:121], v[162:163], 1, v[120:121]
	s_mov_b64 s[0:1], 0x2000000
	global_store_dwordx4 v[120:121], v[124:127], off
	s_nop 1
	v_lshl_add_u64 v[126:127], v[120:121], 0, s[0:1]
	s_brev_b32 s0, 64
	v_add_co_u32_e64 v122, s[4:5], s0, v120
	s_nop 1
	v_addc_co_u32_e64 v123, s[4:5], 0, v121, s[4:5]
	global_store_dwordx4 v[122:123], v[188:191], off
	v_add_u32_e32 v122, 0x80, v162
	v_lshrrev_b32_e32 v122, 2, v122
	v_and_b32_e32 v153, 0x1f0, v122
	v_add_u32_e32 v122, v153, v192
	v_add_u32_e32 v124, v153, v136
	v_ashrrev_i32_e32 v123, 31, v122
	v_ashrrev_i32_e32 v125, 31, v124
	v_lshl_add_u64 v[122:123], v[122:123], 2, s[16:17]
	v_lshl_add_u64 v[124:125], v[124:125], 2, s[16:17]
	global_load_dword v163, v[122:123], off
	global_load_dword v164, v[124:125], off
	ds_bpermute_b32 v157, v177, v116
	v_mov_b32_e32 v162, v116
	ds_bpermute_b32 v116, v177, v117
	ds_bpermute_b32 v161, v177, v118
	ds_bpermute_b32 v166, v177, v119
	s_waitcnt lgkmcnt(3)
;     __device__ __forceinline__ void operator()(const AccT& acc, const Unit& u, int wr, int wc, int fr, int fq) const {
;     ...
;             for (int m = 0; m < 4; ++m) {
;                 const int r = rbase + ai * 128 + m * 16;
;                 const int d = 4 * (2 * m + (fr >> 3)) + j;
; #pragma unroll
;                 for (int bj = 0; bj < 2; ++bj) {
;                     const int t0 = tb + bj * 128;
;                     float v[8];
; #pragma unroll
;                     for (int jj = 0; jj < 4; ++jj) { v[jj] = acc[ai][bj][m][0][jj]; v[4 + jj] = acc[ai][bj][m][1][jj]; }
;                     if constexpr (ROPE) {
;                         const int t = t0 & 2047;
; #pragma unroll
;                         for (int hf = 0; hf < 2; ++hf) {
;                             f32x4 cs, sn;
;                             if (m < 2) { const float c1 = ropeA[(t >> 6) * 16 + d], s1 = ropeA[1024 + (t >> 6) * 16 + d]; cs = (f32x4){c1, c1, c1, c1}; sn = (f32x4){s1, s1, s1, s1}; }
;                             else { const float* cb = ropeA + 2048 + (d - 16) * 64 + (t & 63) + 4 * hf; cs = *(const f32x4*)(cb); sn = *(const f32x4*)(cb + 1024); }
; #pragma unroll
;                             for (int jj = 0; jj < 4; ++jj) { const float pr = __shfl_xor(v[4 * hf + jj], 4); v[4 * hf + jj] = v[4 * hf + jj] * cs[jj] + sgn * pr * sn[jj]; }
;                             __builtin_amdgcn_sched_barrier(0);
;                         }
;                     }
;                     float zf[8], zb[8]; zf[0] = zf0; zb[0] = zb0;
; #pragma unroll
;                     for (int jj = 1; jj < 8; ++jj) { zf[jj] = zf[jj - 1] * zfs; zb[jj] = zb[jj - 1] * zbs; }
;                     u32x4 wf, wb;
;                     wf.x = cvt_pk_bf16(v[0] * zf[0], v[1] * zf[1]); wf.y = cvt_pk_bf16(v[2] * zf[2], v[3] * zf[3]); wf.z = cvt_pk_bf16(v[4] * zf[4], v[5] * zf[5]); wf.w = cvt_pk_bf16(v[6] * zf[6], v[7] * zf[7]);
;                     wb.x = cvt_pk_bf16(v[0] * zb[0], v[1] * zb[1]); wb.y = cvt_pk_bf16(v[2] * zb[2], v[3] * zb[3]); wb.z = cvt_pk_bf16(v[4] * zb[4], v[5] * zb[5]); wb.w = cvt_pk_bf16(v[6] * zb[6], v[7] * zb[7]);
;                     *(u32x4*)(KTZ + (size_t)r * NT + t0) = wf;
;                     *(u32x4*)(KTZ + (size_t)(256 + r) * NT + t0) = wb;
;                     __builtin_amdgcn_sched_barrier(0);
	v_cndmask_b32_e64 v165, v157, -v157, vcc
	s_waitcnt vmcnt(0)
	v_pk_mul_f32 v[188:189], v[162:163], v[164:165]
	s_waitcnt lgkmcnt(2)
	v_cndmask_b32_e64 v165, v116, -v116, vcc
	v_mov_b32_e32 v162, v117
	v_pk_mul_f32 v[116:117], v[162:163], v[164:165]
	s_waitcnt lgkmcnt(1)
	v_cndmask_b32_e64 v165, v161, -v161, vcc
	v_mov_b32_e32 v162, v118
	v_add_f32_e32 v161, v116, v117
	v_pk_mul_f32 v[116:117], v[162:163], v[164:165]
	s_waitcnt lgkmcnt(0)
	v_cndmask_b32_e64 v165, v166, -v166, vcc
	v_mov_b32_e32 v162, v119
	v_add_f32_e32 v166, v116, v117
	v_pk_mul_f32 v[116:117], v[162:163], v[164:165]
	v_add_f32_e32 v157, v188, v189
	v_add_f32_e32 v164, v116, v117
	global_load_dword v117, v[122:123], off
	global_load_dword v118, v[124:125], off
	ds_bpermute_b32 v119, v177, v112
	v_mov_b32_e32 v116, v112
	ds_bpermute_b32 v112, v177, v113
	ds_bpermute_b32 v165, v177, v114
	ds_bpermute_b32 v188, v177, v115
	s_waitcnt lgkmcnt(3)
	v_cndmask_b32_e64 v119, v119, -v119, vcc
	s_waitcnt vmcnt(0)
	v_pk_mul_f32 v[162:163], v[116:117], v[118:119]
	s_waitcnt lgkmcnt(2)
	v_cndmask_b32_e64 v119, v112, -v112, vcc
	v_mov_b32_e32 v116, v113
	v_pk_mul_f32 v[112:113], v[116:117], v[118:119]
	s_waitcnt lgkmcnt(1)
	v_cndmask_b32_e64 v119, v165, -v165, vcc
	v_mov_b32_e32 v116, v114
	v_add_f32_e32 v162, v162, v163
	v_add_f32_e32 v163, v112, v113
	v_pk_mul_f32 v[112:113], v[116:117], v[118:119]
	s_waitcnt lgkmcnt(0)
	v_cndmask_b32_e64 v119, v188, -v188, vcc
	v_mov_b32_e32 v116, v115
	v_add_f32_e32 v165, v112, v113
	v_pk_mul_f32 v[112:113], v[116:117], v[118:119]
	s_nop 0
	v_add_f32_e32 v119, v112, v113
	v_mul_f32_e32 v112, v180, v157
	v_mul_f32_e32 v113, v181, v161
	v_cvt_pk_bf16_f32 v112, v112, v113
	v_mul_f32_e32 v113, v167, v166
	v_mul_f32_e32 v114, v183, v164
	v_cvt_pk_bf16_f32 v113, v113, v114
	v_mul_f32_e32 v114, v182, v162
	v_mul_f32_e32 v115, v185, v163
	v_cvt_pk_bf16_f32 v114, v114, v115
	v_mul_f32_e32 v115, v184, v165
	v_mul_f32_e32 v116, v159, v119
	v_cvt_pk_bf16_f32 v115, v115, v116
	v_mul_f32_e32 v116, v150, v157
	v_mul_f32_e32 v117, v152, v161
	v_cvt_pk_bf16_f32 v116, v116, v117
	v_mul_f32_e32 v117, v154, v166
	v_mul_f32_e32 v118, v156, v164
	v_cvt_pk_bf16_f32 v117, v117, v118
	v_mul_f32_e32 v118, v158, v162
	v_mul_f32_e32 v157, v160, v163
	v_mul_f32_e32 v119, v155, v119
	v_cvt_pk_bf16_f32 v118, v118, v157
	v_mul_f32_e32 v157, v151, v165
	v_cvt_pk_bf16_f32 v119, v157, v119
	global_store_dwordx4 v[120:121], v[112:115], off offset:256
	global_store_dwordx4 v[126:127], v[116:119], off offset:256
	v_add_u32_e32 v161, 0x408, v136
	v_add_u32_e32 v157, 8, v136
	v_add_u32_e32 v112, v161, v187
	v_add_u32_e32 v114, v187, v157
	v_ashrrev_i32_e32 v113, 31, v112
	v_ashrrev_i32_e32 v115, 31, v114
	v_lshl_add_u64 v[112:113], v[112:113], 2, s[16:17]
	v_lshl_add_u64 v[114:115], v[114:115], 2, s[16:17]
	global_load_dword v117, v[112:113], off
	global_load_dword v118, v[114:115], off
	ds_bpermute_b32 v119, v177, v108
	v_mov_b32_e32 v116, v108
	ds_bpermute_b32 v108, v177, v109
	ds_bpermute_b32 v162, v177, v110
	ds_bpermute_b32 v163, v177, v111
	s_waitcnt lgkmcnt(3)
	v_cndmask_b32_e64 v119, v119, -v119, vcc
	s_waitcnt vmcnt(0)
	v_pk_mul_f32 v[126:127], v[116:117], v[118:119]
	s_waitcnt lgkmcnt(2)
	v_cndmask_b32_e64 v119, v108, -v108, vcc
	v_mov_b32_e32 v116, v109
	v_pk_mul_f32 v[108:109], v[116:117], v[118:119]
	s_waitcnt lgkmcnt(1)
	v_cndmask_b32_e64 v119, v162, -v162, vcc
	v_mov_b32_e32 v116, v110
	v_add_f32_e32 v126, v126, v127
	v_add_f32_e32 v127, v108, v109
	v_pk_mul_f32 v[108:109], v[116:117], v[118:119]
	s_waitcnt lgkmcnt(0)
	v_cndmask_b32_e64 v119, v163, -v163, vcc
	v_mov_b32_e32 v116, v111
	v_add_f32_e32 v162, v108, v109
	v_pk_mul_f32 v[108:109], v[116:117], v[118:119]
	s_nop 0
	v_add_f32_e32 v118, v108, v109
	global_load_dword v109, v[112:113], off
	global_load_dword v110, v[114:115], off
	ds_bpermute_b32 v111, v177, v104
	v_mov_b32_e32 v108, v104
	ds_bpermute_b32 v104, v177, v105
	ds_bpermute_b32 v119, v177, v106
	ds_bpermute_b32 v163, v177, v107
	s_waitcnt lgkmcnt(3)
	v_cndmask_b32_e64 v111, v111, -v111, vcc
	s_waitcnt vmcnt(0)
	v_pk_mul_f32 v[116:117], v[108:109], v[110:111]
	s_waitcnt lgkmcnt(2)
	v_cndmask_b32_e64 v111, v104, -v104, vcc
	v_mov_b32_e32 v108, v105
	v_pk_mul_f32 v[104:105], v[108:109], v[110:111]
	s_waitcnt lgkmcnt(1)
	v_cndmask_b32_e64 v111, v119, -v119, vcc
	v_mov_b32_e32 v108, v106
	v_add_f32_e32 v119, v104, v105
	v_pk_mul_f32 v[104:105], v[108:109], v[110:111]
	s_waitcnt lgkmcnt(0)
	v_cndmask_b32_e64 v111, v163, -v163, vcc
	v_mov_b32_e32 v108, v107
	v_add_f32_e32 v163, v104, v105
	v_pk_mul_f32 v[104:105], v[108:109], v[110:111]
	v_add_f32_e32 v164, v116, v117
	v_add_f32_e32 v108, v104, v105
	v_mul_f32_e32 v104, v180, v126
	v_mul_f32_e32 v105, v181, v127
	v_cvt_pk_bf16_f32 v104, v104, v105
	v_mul_f32_e32 v105, v167, v162
	v_mul_f32_e32 v106, v183, v118
	v_cvt_pk_bf16_f32 v105, v105, v106
	v_mul_f32_e32 v106, v182, v164
	v_mul_f32_e32 v107, v185, v119
	v_cvt_pk_bf16_f32 v106, v106, v107
	v_mul_f32_e32 v107, v184, v163
	v_mul_f32_e32 v109, v159, v108
	v_cvt_pk_bf16_f32 v107, v107, v109
	v_mul_f32_e32 v109, v150, v126
	v_mul_f32_e32 v110, v152, v127
	v_cvt_pk_bf16_f32 v116, v109, v110
	v_mul_f32_e32 v109, v154, v162
	v_mul_f32_e32 v110, v156, v118
	v_cvt_pk_bf16_f32 v117, v109, v110
	v_mul_f32_e32 v109, v158, v164
	v_mul_f32_e32 v110, v160, v119
	v_cvt_pk_bf16_f32 v118, v109, v110
	v_mul_f32_e32 v109, v151, v163
	v_mul_f32_e32 v108, v155, v108
	s_mov_b64 s[0:1], 0x200000
	v_cvt_pk_bf16_f32 v119, v109, v108
	v_lshl_add_u64 v[108:109], v[120:121], 0, s[0:1]
	s_mov_b32 s0, 0x200000
	v_add_co_u32_e64 v110, s[4:5], s0, v120
	s_mov_b64 s[0:1], 0x2200000
	s_nop 0
	v_addc_co_u32_e64 v111, s[4:5], 0, v121, s[4:5]
	global_store_dwordx4 v[110:111], v[104:107], off
	v_lshl_add_u64 v[110:111], v[120:121], 0, s[0:1]
	s_mov_b32 s0, 0x2200000
	v_add_co_u32_e64 v104, s[4:5], s0, v120
	s_nop 1
	v_addc_co_u32_e64 v105, s[4:5], 0, v121, s[4:5]
	global_store_dwordx4 v[104:105], v[116:119], off
	v_add_u32_e32 v104, v153, v161
	v_add_u32_e32 v106, v153, v157
	v_ashrrev_i32_e32 v105, 31, v104
	v_ashrrev_i32_e32 v107, 31, v106
	v_lshl_add_u64 v[104:105], v[104:105], 2, s[16:17]
	v_lshl_add_u64 v[106:107], v[106:107], 2, s[16:17]
	global_load_dword v117, v[104:105], off
	global_load_dword v118, v[106:107], off
	ds_bpermute_b32 v119, v177, v100
	v_mov_b32_e32 v116, v100
	ds_bpermute_b32 v100, v177, v101
	ds_bpermute_b32 v153, v177, v102
	ds_bpermute_b32 v157, v177, v103
	s_waitcnt lgkmcnt(3)
;     __device__ __forceinline__ void operator()(const AccT& acc, const Unit& u, int wr, int wc, int fr, int fq) const {
;     ...
;             for (int m = 0; m < 4; ++m) {
;                 const int r = rbase + ai * 128 + m * 16;
;                 const int d = 4 * (2 * m + (fr >> 3)) + j;
; #pragma unroll
;                 for (int bj = 0; bj < 2; ++bj) {
;                     const int t0 = tb + bj * 128;
;                     float v[8];
; #pragma unroll
;                     for (int jj = 0; jj < 4; ++jj) { v[jj] = acc[ai][bj][m][0][jj]; v[4 + jj] = acc[ai][bj][m][1][jj]; }
;                     if constexpr (ROPE) {
;                         const int t = t0 & 2047;
; #pragma unroll
;                         for (int hf = 0; hf < 2; ++hf) {
;                             f32x4 cs, sn;
;                             if (m < 2) { const float c1 = ropeA[(t >> 6) * 16 + d], s1 = ropeA[1024 + (t >> 6) * 16 + d]; cs = (f32x4){c1, c1, c1, c1}; sn = (f32x4){s1, s1, s1, s1}; }
;                             else { const float* cb = ropeA + 2048 + (d - 16) * 64 + (t & 63) + 4 * hf; cs = *(const f32x4*)(cb); sn = *(const f32x4*)(cb + 1024); }
; #pragma unroll
;                             for (int jj = 0; jj < 4; ++jj) { const float pr = __shfl_xor(v[4 * hf + jj], 4); v[4 * hf + jj] = v[4 * hf + jj] * cs[jj] + sgn * pr * sn[jj]; }
;                             __builtin_amdgcn_sched_barrier(0);
;                         }
;                     }
;                     float zf[8], zb[8]; zf[0] = zf0; zb[0] = zb0;
; #pragma unroll
;                     for (int jj = 1; jj < 8; ++jj) { zf[jj] = zf[jj - 1] * zfs; zb[jj] = zb[jj - 1] * zbs; }
;                     u32x4 wf, wb;
;                     wf.x = cvt_pk_bf16(v[0] * zf[0], v[1] * zf[1]); wf.y = cvt_pk_bf16(v[2] * zf[2], v[3] * zf[3]); wf.z = cvt_pk_bf16(v[4] * zf[4], v[5] * zf[5]); wf.w = cvt_pk_bf16(v[6] * zf[6], v[7] * zf[7]);
;                     wb.x = cvt_pk_bf16(v[0] * zb[0], v[1] * zb[1]); wb.y = cvt_pk_bf16(v[2] * zb[2], v[3] * zb[3]); wb.z = cvt_pk_bf16(v[4] * zb[4], v[5] * zb[5]); wb.w = cvt_pk_bf16(v[6] * zb[6], v[7] * zb[7]);
;                     *(u32x4*)(KTZ + (size_t)r * NT + t0) = wf;
;                     *(u32x4*)(KTZ + (size_t)(256 + r) * NT + t0) = wb;
;                     __builtin_amdgcn_sched_barrier(0);
	v_cndmask_b32_e64 v119, v119, -v119, vcc
	s_waitcnt vmcnt(0)
	v_pk_mul_f32 v[126:127], v[116:117], v[118:119]
	s_waitcnt lgkmcnt(2)
	v_cndmask_b32_e64 v119, v100, -v100, vcc
	v_mov_b32_e32 v116, v101
	v_pk_mul_f32 v[100:101], v[116:117], v[118:119]
	s_waitcnt lgkmcnt(1)
	v_cndmask_b32_e64 v119, v153, -v153, vcc
	v_mov_b32_e32 v116, v102
	v_add_f32_e32 v126, v126, v127
	v_add_f32_e32 v127, v100, v101
	v_pk_mul_f32 v[100:101], v[116:117], v[118:119]
	s_waitcnt lgkmcnt(0)
	v_cndmask_b32_e64 v119, v157, -v157, vcc
	v_mov_b32_e32 v116, v103
	v_add_f32_e32 v153, v100, v101
	v_pk_mul_f32 v[100:101], v[116:117], v[118:119]
	s_nop 0
	v_add_f32_e32 v118, v100, v101
	global_load_dword v101, v[104:105], off
	global_load_dword v102, v[106:107], off
	ds_bpermute_b32 v103, v177, v96
	v_mov_b32_e32 v100, v96
	ds_bpermute_b32 v96, v177, v97
	ds_bpermute_b32 v119, v177, v98
	ds_bpermute_b32 v157, v177, v99
	s_waitcnt lgkmcnt(3)
	v_cndmask_b32_e64 v103, v103, -v103, vcc
	s_waitcnt vmcnt(0)
	v_pk_mul_f32 v[116:117], v[100:101], v[102:103]
	s_waitcnt lgkmcnt(2)
	v_cndmask_b32_e64 v103, v96, -v96, vcc
	v_mov_b32_e32 v100, v97
	v_pk_mul_f32 v[96:97], v[100:101], v[102:103]
	s_waitcnt lgkmcnt(1)
	v_cndmask_b32_e64 v103, v119, -v119, vcc
	v_mov_b32_e32 v100, v98
	v_add_f32_e32 v116, v116, v117
	v_add_f32_e32 v117, v96, v97
	v_pk_mul_f32 v[96:97], v[100:101], v[102:103]
	s_waitcnt lgkmcnt(0)
	v_cndmask_b32_e64 v103, v157, -v157, vcc
	v_mov_b32_e32 v100, v99
	v_add_f32_e32 v119, v96, v97
	v_pk_mul_f32 v[96:97], v[100:101], v[102:103]
	s_nop 0
	v_add_f32_e32 v103, v96, v97
	v_mul_f32_e32 v96, v180, v126
	v_mul_f32_e32 v97, v181, v127
	v_cvt_pk_bf16_f32 v96, v96, v97
	v_mul_f32_e32 v97, v167, v153
	v_mul_f32_e32 v98, v183, v118
	v_cvt_pk_bf16_f32 v97, v97, v98
	v_mul_f32_e32 v98, v182, v116
	v_mul_f32_e32 v99, v185, v117
	v_cvt_pk_bf16_f32 v98, v98, v99
	v_mul_f32_e32 v99, v184, v119
	v_mul_f32_e32 v100, v159, v103
	v_cvt_pk_bf16_f32 v99, v99, v100
	v_mul_f32_e32 v100, v150, v126
	v_mul_f32_e32 v101, v152, v127
	v_cvt_pk_bf16_f32 v100, v100, v101
	v_mul_f32_e32 v101, v154, v153
	v_mul_f32_e32 v102, v156, v118
	v_cvt_pk_bf16_f32 v101, v101, v102
	v_mul_f32_e32 v102, v158, v116
	v_mul_f32_e32 v116, v160, v117
	v_mul_f32_e32 v103, v155, v103
	v_cvt_pk_bf16_f32 v102, v102, v116
	v_mul_f32_e32 v116, v151, v119
	v_cvt_pk_bf16_f32 v103, v116, v103
	global_store_dwordx4 v[108:109], v[96:99], off offset:256
	global_store_dwordx4 v[110:111], v[100:103], off offset:256
	s_nop 1
	v_lshlrev_b32_e32 v100, 6, v136
	v_ashrrev_i32_e32 v101, 31, v100
	v_lshlrev_b64 v[102:103], 2, v[100:101]
	v_lshl_add_u64 v[96:97], s[24:25], 0, v[102:103]
	v_lshlrev_b32_e32 v136, 2, v186
	v_lshl_add_u64 v[96:97], v[96:97], 0, v[136:137]
	v_add_co_u32_e64 v98, s[4:5], s61, v96
	ds_bpermute_b32 v101, v177, v92
	s_nop 0
	v_addc_co_u32_e64 v99, s[4:5], 0, v97, s[4:5]
	global_load_dwordx4 v[108:111], v[98:99], off
	global_load_dwordx4 v[116:119], v[96:97], off
	ds_bpermute_b32 v127, v177, v93
	ds_bpermute_b32 v153, v177, v94
	ds_bpermute_b32 v157, v177, v95
	v_mov_b32_e32 v126, v92
	v_mov_b32_e32 v92, v94
	s_waitcnt lgkmcnt(3)
	v_cndmask_b32_e64 v163, v101, -v101, vcc
	s_waitcnt lgkmcnt(2)
	v_cndmask_b32_e64 v165, v127, -v127, vcc
	s_waitcnt lgkmcnt(1)
	v_cndmask_b32_e64 v187, v153, -v153, vcc
	s_waitcnt lgkmcnt(0)
	v_cndmask_b32_e64 v189, v157, -v157, vcc
	s_waitcnt vmcnt(1)
	v_mov_b32_e32 v127, v108
	s_waitcnt vmcnt(0)
	v_mov_b32_e32 v162, v116
	v_mov_b32_e32 v108, v93
	v_mov_b32_e32 v164, v117
	v_mov_b32_e32 v93, v110
	v_mov_b32_e32 v186, v118
	v_mov_b32_e32 v110, v95
	v_mov_b32_e32 v188, v119
	v_pk_mul_f32 v[94:95], v[126:127], v[162:163]
	v_pk_mul_f32 v[108:109], v[108:109], v[164:165]
	v_pk_mul_f32 v[92:93], v[92:93], v[186:187]
	v_pk_mul_f32 v[110:111], v[110:111], v[188:189]
	v_add_f32_e32 v101, v94, v95
	v_add_f32_e32 v153, v108, v109
	v_add_f32_e32 v157, v92, v93
	v_add_f32_e32 v161, v110, v111
	v_lshl_add_u64 v[92:93], s[16:17], 0, v[102:103]
	v_lshl_add_u64 v[94:95], v[92:93], 0, v[136:137]
	v_add_co_u32_e64 v92, s[4:5], s62, v94
	ds_bpermute_b32 v103, v177, v88
	s_nop 0
	v_addc_co_u32_e64 v93, s[4:5], 0, v95, s[4:5]
	v_add_co_u32_e64 v94, s[4:5], s49, v94
	ds_bpermute_b32 v126, v177, v89
	s_nop 0
	v_addc_co_u32_e64 v95, s[4:5], 0, v95, s[4:5]
	global_load_dwordx4 v[108:111], v[92:93], off offset:16
	global_load_dwordx4 v[116:119], v[94:95], off offset:16
	ds_bpermute_b32 v162, v177, v90
	ds_bpermute_b32 v164, v177, v91
	v_mov_b32_e32 v102, v88
	v_mov_b32_e32 v88, v90
	s_waitcnt lgkmcnt(3)
	v_cndmask_b32_e64 v127, v103, -v103, vcc
	s_waitcnt lgkmcnt(2)
	v_cndmask_b32_e64 v163, v126, -v126, vcc
	s_waitcnt lgkmcnt(1)
	v_cndmask_b32_e64 v165, v162, -v162, vcc
	s_waitcnt lgkmcnt(0)
	v_cndmask_b32_e64 v187, v164, -v164, vcc
	s_waitcnt vmcnt(1)
	v_mov_b32_e32 v103, v108
	s_waitcnt vmcnt(0)
;     __device__ __forceinline__ void operator()(const AccT& acc, const Unit& u, int wr, int wc, int fr, int fq) const {
;     ...
;             for (int m = 0; m < 4; ++m) {
;                 const int r = rbase + ai * 128 + m * 16;
;                 const int d = 4 * (2 * m + (fr >> 3)) + j;
; #pragma unroll
;                 for (int bj = 0; bj < 2; ++bj) {
;                     const int t0 = tb + bj * 128;
;                     float v[8];
; #pragma unroll
;                     for (int jj = 0; jj < 4; ++jj) { v[jj] = acc[ai][bj][m][0][jj]; v[4 + jj] = acc[ai][bj][m][1][jj]; }
;                     if constexpr (ROPE) {
;                         const int t = t0 & 2047;
; #pragma unroll
;                         for (int hf = 0; hf < 2; ++hf) {
;                             f32x4 cs, sn;
;                             if (m < 2) { const float c1 = ropeA[(t >> 6) * 16 + d], s1 = ropeA[1024 + (t >> 6) * 16 + d]; cs = (f32x4){c1, c1, c1, c1}; sn = (f32x4){s1, s1, s1, s1}; }
;                             else { const float* cb = ropeA + 2048 + (d - 16) * 64 + (t & 63) + 4 * hf; cs = *(const f32x4*)(cb); sn = *(const f32x4*)(cb + 1024); }
; #pragma unroll
;                             for (int jj = 0; jj < 4; ++jj) { const float pr = __shfl_xor(v[4 * hf + jj], 4); v[4 * hf + jj] = v[4 * hf + jj] * cs[jj] + sgn * pr * sn[jj]; }
;                             __builtin_amdgcn_sched_barrier(0);
;                         }
;                     }
;                     float zf[8], zb[8]; zf[0] = zf0; zb[0] = zb0;
; #pragma unroll
;                     for (int jj = 1; jj < 8; ++jj) { zf[jj] = zf[jj - 1] * zfs; zb[jj] = zb[jj - 1] * zbs; }
;                     u32x4 wf, wb;
;                     wf.x = cvt_pk_bf16(v[0] * zf[0], v[1] * zf[1]); wf.y = cvt_pk_bf16(v[2] * zf[2], v[3] * zf[3]); wf.z = cvt_pk_bf16(v[4] * zf[4], v[5] * zf[5]); wf.w = cvt_pk_bf16(v[6] * zf[6], v[7] * zf[7]);
;                     wb.x = cvt_pk_bf16(v[0] * zb[0], v[1] * zb[1]); wb.y = cvt_pk_bf16(v[2] * zb[2], v[3] * zb[3]); wb.z = cvt_pk_bf16(v[4] * zb[4], v[5] * zb[5]); wb.w = cvt_pk_bf16(v[6] * zb[6], v[7] * zb[7]);
;                     *(u32x4*)(KTZ + (size_t)r * NT + t0) = wf;
;                     *(u32x4*)(KTZ + (size_t)(256 + r) * NT + t0) = wb;
;                     __builtin_amdgcn_sched_barrier(0);
	v_mov_b32_e32 v126, v116
	v_mov_b32_e32 v108, v89
	v_mov_b32_e32 v162, v117
	v_mov_b32_e32 v89, v110
	v_mov_b32_e32 v164, v118
	v_mov_b32_e32 v110, v91
	v_mov_b32_e32 v186, v119
	v_pk_mul_f32 v[90:91], v[102:103], v[126:127]
	v_pk_mul_f32 v[102:103], v[108:109], v[162:163]
	v_pk_mul_f32 v[88:89], v[88:89], v[164:165]
	v_pk_mul_f32 v[108:109], v[110:111], v[186:187]
	v_add_f32_e32 v90, v90, v91
	v_add_f32_e32 v91, v102, v103
	v_add_f32_e32 v88, v88, v89
	v_add_f32_e32 v89, v108, v109
	v_mul_f32_e32 v102, v180, v101
	v_mul_f32_e32 v103, v181, v153
	v_cvt_pk_bf16_f32 v108, v102, v103
	v_mul_f32_e32 v102, v167, v157
	v_mul_f32_e32 v103, v183, v161
	v_cvt_pk_bf16_f32 v109, v102, v103
	v_mul_f32_e32 v102, v182, v90
	v_mul_f32_e32 v103, v185, v91
	v_cvt_pk_bf16_f32 v110, v102, v103
	v_mul_f32_e32 v102, v184, v88
	v_mul_f32_e32 v103, v159, v89
	v_cvt_pk_bf16_f32 v111, v102, v103
	v_mul_f32_e32 v101, v150, v101
	v_mul_f32_e32 v102, v152, v153
	v_mul_f32_e32 v88, v151, v88
	v_mul_f32_e32 v89, v155, v89
	s_mov_b64 s[0:1], 0x400000
	v_cvt_pk_bf16_f32 v116, v101, v102
	v_mul_f32_e32 v101, v154, v157
	v_mul_f32_e32 v102, v156, v161
	v_cvt_pk_bf16_f32 v117, v101, v102
	v_mul_f32_e32 v90, v158, v90
	v_mul_f32_e32 v91, v160, v91
	v_cvt_pk_bf16_f32 v118, v90, v91
	v_cvt_pk_bf16_f32 v119, v88, v89
	v_lshl_add_u64 v[88:89], v[120:121], 0, s[0:1]
	s_mov_b32 s0, 0x400000
	v_add_co_u32_e64 v90, s[4:5], s0, v120
	s_mov_b64 s[0:1], 0x2400000
	s_nop 0
	v_addc_co_u32_e64 v91, s[4:5], 0, v121, s[4:5]
	global_store_dwordx4 v[90:91], v[108:111], off
	v_lshl_add_u64 v[90:91], v[120:121], 0, s[0:1]
	s_mov_b32 s0, 0x2400000
	v_add_co_u32_e64 v102, s[4:5], s0, v120
	s_nop 1
	v_addc_co_u32_e64 v103, s[4:5], 0, v121, s[4:5]
	global_store_dwordx4 v[102:103], v[116:119], off
	global_load_dwordx4 v[108:111], v[98:99], off
	s_nop 0
	global_load_dwordx4 v[116:119], v[96:97], off
	ds_bpermute_b32 v101, v177, v84
	ds_bpermute_b32 v103, v177, v85
	ds_bpermute_b32 v126, v177, v86
	ds_bpermute_b32 v153, v177, v87
	v_mov_b32_e32 v102, v84
	v_mov_b32_e32 v84, v86
	s_waitcnt lgkmcnt(3)
	v_cndmask_b32_e64 v127, v101, -v101, vcc
	s_waitcnt lgkmcnt(2)
	v_cndmask_b32_e64 v163, v103, -v103, vcc
	s_waitcnt lgkmcnt(1)
	v_cndmask_b32_e64 v165, v126, -v126, vcc
	s_waitcnt lgkmcnt(0)
	v_cndmask_b32_e64 v187, v153, -v153, vcc
	s_waitcnt vmcnt(1)
	v_mov_b32_e32 v103, v108
	s_waitcnt vmcnt(0)
	v_mov_b32_e32 v126, v116
	v_mov_b32_e32 v108, v85
	v_mov_b32_e32 v162, v117
	v_mov_b32_e32 v85, v110
	v_mov_b32_e32 v164, v118
	v_mov_b32_e32 v110, v87
	v_mov_b32_e32 v186, v119
	v_pk_mul_f32 v[86:87], v[102:103], v[126:127]
	v_pk_mul_f32 v[102:103], v[108:109], v[162:163]
	v_pk_mul_f32 v[84:85], v[84:85], v[164:165]
	v_pk_mul_f32 v[108:109], v[110:111], v[186:187]
	v_add_f32_e32 v101, v86, v87
	v_add_f32_e32 v153, v102, v103
	v_add_f32_e32 v157, v84, v85
	v_add_f32_e32 v161, v108, v109
	global_load_dwordx4 v[84:87], v[92:93], off offset:16
	global_load_dwordx4 v[108:111], v[94:95], off offset:16
	ds_bpermute_b32 v103, v177, v80
	ds_bpermute_b32 v116, v177, v81
	ds_bpermute_b32 v118, v177, v82
	ds_bpermute_b32 v126, v177, v83
	v_mov_b32_e32 v102, v80
	v_mov_b32_e32 v80, v82
	s_waitcnt lgkmcnt(3)
	v_cndmask_b32_e64 v117, v103, -v103, vcc
	s_waitcnt lgkmcnt(2)
	v_cndmask_b32_e64 v119, v116, -v116, vcc
	s_waitcnt lgkmcnt(1)
	v_cndmask_b32_e64 v127, v118, -v118, vcc
	s_waitcnt lgkmcnt(0)
	v_cndmask_b32_e64 v163, v126, -v126, vcc
	s_waitcnt vmcnt(1)
	v_mov_b32_e32 v103, v84
	s_waitcnt vmcnt(0)
	v_mov_b32_e32 v116, v108
	v_mov_b32_e32 v84, v81
	v_mov_b32_e32 v118, v109
	v_mov_b32_e32 v81, v86
	v_mov_b32_e32 v126, v110
	v_mov_b32_e32 v86, v83
	v_mov_b32_e32 v162, v111
	v_pk_mul_f32 v[82:83], v[102:103], v[116:117]
	v_pk_mul_f32 v[84:85], v[84:85], v[118:119]
	v_pk_mul_f32 v[80:81], v[80:81], v[126:127]
	v_pk_mul_f32 v[86:87], v[86:87], v[162:163]
	v_add_f32_e32 v102, v82, v83
	v_add_f32_e32 v103, v84, v85
	v_add_f32_e32 v108, v80, v81
	v_add_f32_e32 v87, v86, v87
	v_mul_f32_e32 v80, v180, v101
	v_mul_f32_e32 v81, v181, v153
	v_cvt_pk_bf16_f32 v80, v80, v81
	v_mul_f32_e32 v81, v167, v157
	v_mul_f32_e32 v82, v183, v161
	v_cvt_pk_bf16_f32 v81, v81, v82
	v_mul_f32_e32 v82, v182, v102
	v_mul_f32_e32 v83, v185, v103
	v_cvt_pk_bf16_f32 v82, v82, v83
	v_mul_f32_e32 v83, v184, v108
	v_mul_f32_e32 v84, v159, v87
	v_cvt_pk_bf16_f32 v83, v83, v84
	v_mul_f32_e32 v84, v150, v101
	v_mul_f32_e32 v85, v152, v153
	v_cvt_pk_bf16_f32 v84, v84, v85
	v_mul_f32_e32 v85, v154, v157
	v_mul_f32_e32 v86, v156, v161
	v_cvt_pk_bf16_f32 v85, v85, v86
	v_mul_f32_e32 v86, v158, v102
	v_mul_f32_e32 v101, v160, v103
	v_mul_f32_e32 v87, v155, v87
	v_cvt_pk_bf16_f32 v86, v86, v101
	v_mul_f32_e32 v101, v151, v108
	v_cvt_pk_bf16_f32 v87, v101, v87
	global_store_dwordx4 v[88:89], v[80:83], off offset:256
	global_store_dwordx4 v[90:91], v[84:87], off offset:256
	s_nop 0
	v_add_u32_e32 v80, 0x200, v100
	v_ashrrev_i32_e32 v81, 31, v80
	v_lshl_add_u64 v[82:83], s[24:25], 0, v[136:137]
	v_lshlrev_b64 v[100:101], 2, v[80:81]
	v_lshl_add_u64 v[80:81], v[82:83], 0, v[100:101]
	v_add_co_u32_e64 v82, s[4:5], s61, v80
	ds_bpermute_b32 v103, v177, v76
	s_nop 0
	v_addc_co_u32_e64 v83, s[4:5], 0, v81, s[4:5]
	global_load_dwordx4 v[84:87], v[82:83], off
	global_load_dwordx4 v[88:91], v[80:81], off
	ds_bpermute_b32 v108, v177, v77
	ds_bpermute_b32 v110, v177, v78
	ds_bpermute_b32 v116, v177, v79
	v_mov_b32_e32 v102, v76
	v_mov_b32_e32 v76, v78
	s_waitcnt lgkmcnt(3)
	v_cndmask_b32_e64 v109, v103, -v103, vcc
	s_waitcnt lgkmcnt(2)
	v_cndmask_b32_e64 v111, v108, -v108, vcc
	s_waitcnt lgkmcnt(1)
	v_cndmask_b32_e64 v117, v110, -v110, vcc
	s_waitcnt lgkmcnt(0)
;     __device__ __forceinline__ void operator()(const AccT& acc, const Unit& u, int wr, int wc, int fr, int fq) const {
;     ...
;             for (int m = 0; m < 4; ++m) {
;                 const int r = rbase + ai * 128 + m * 16;
;                 const int d = 4 * (2 * m + (fr >> 3)) + j;
; #pragma unroll
;                 for (int bj = 0; bj < 2; ++bj) {
;                     const int t0 = tb + bj * 128;
;                     float v[8];
; #pragma unroll
;                     for (int jj = 0; jj < 4; ++jj) { v[jj] = acc[ai][bj][m][0][jj]; v[4 + jj] = acc[ai][bj][m][1][jj]; }
;                     if constexpr (ROPE) {
;                         const int t = t0 & 2047;
; #pragma unroll
;                         for (int hf = 0; hf < 2; ++hf) {
;                             f32x4 cs, sn;
;                             if (m < 2) { const float c1 = ropeA[(t >> 6) * 16 + d], s1 = ropeA[1024 + (t >> 6) * 16 + d]; cs = (f32x4){c1, c1, c1, c1}; sn = (f32x4){s1, s1, s1, s1}; }
;                             else { const float* cb = ropeA + 2048 + (d - 16) * 64 + (t & 63) + 4 * hf; cs = *(const f32x4*)(cb); sn = *(const f32x4*)(cb + 1024); }
; #pragma unroll
;                             for (int jj = 0; jj < 4; ++jj) { const float pr = __shfl_xor(v[4 * hf + jj], 4); v[4 * hf + jj] = v[4 * hf + jj] * cs[jj] + sgn * pr * sn[jj]; }
;                             __builtin_amdgcn_sched_barrier(0);
;                         }
;                     }
;                     float zf[8], zb[8]; zf[0] = zf0; zb[0] = zb0;
; #pragma unroll
;                     for (int jj = 1; jj < 8; ++jj) { zf[jj] = zf[jj - 1] * zfs; zb[jj] = zb[jj - 1] * zbs; }
;                     u32x4 wf, wb;
;                     wf.x = cvt_pk_bf16(v[0] * zf[0], v[1] * zf[1]); wf.y = cvt_pk_bf16(v[2] * zf[2], v[3] * zf[3]); wf.z = cvt_pk_bf16(v[4] * zf[4], v[5] * zf[5]); wf.w = cvt_pk_bf16(v[6] * zf[6], v[7] * zf[7]);
;                     wb.x = cvt_pk_bf16(v[0] * zb[0], v[1] * zb[1]); wb.y = cvt_pk_bf16(v[2] * zb[2], v[3] * zb[3]); wb.z = cvt_pk_bf16(v[4] * zb[4], v[5] * zb[5]); wb.w = cvt_pk_bf16(v[6] * zb[6], v[7] * zb[7]);
;                     *(u32x4*)(KTZ + (size_t)r * NT + t0) = wf;
;                     *(u32x4*)(KTZ + (size_t)(256 + r) * NT + t0) = wb;
;                     __builtin_amdgcn_sched_barrier(0);
	v_cndmask_b32_e64 v119, v116, -v116, vcc
	s_waitcnt vmcnt(1)
	v_mov_b32_e32 v103, v84
	s_waitcnt vmcnt(0)
	v_mov_b32_e32 v108, v88
	v_mov_b32_e32 v84, v77
	v_mov_b32_e32 v110, v89
	v_mov_b32_e32 v77, v86
	v_mov_b32_e32 v116, v90
	v_mov_b32_e32 v86, v79
	v_mov_b32_e32 v118, v91
	v_pk_mul_f32 v[78:79], v[102:103], v[108:109]
	v_pk_mul_f32 v[84:85], v[84:85], v[110:111]
	v_pk_mul_f32 v[76:77], v[76:77], v[116:117]
	v_pk_mul_f32 v[86:87], v[86:87], v[118:119]
	v_add_f32_e32 v118, v78, v79
	v_add_f32_e32 v119, v84, v85
	v_add_f32_e32 v126, v76, v77
	v_add_f32_e32 v127, v86, v87
	v_lshl_add_u64 v[76:77], s[16:17], 0, v[100:101]
	v_lshl_add_u64 v[78:79], v[76:77], 0, v[136:137]
	v_add_co_u32_e64 v76, s[4:5], s62, v78
	ds_bpermute_b32 v101, v177, v72
	s_nop 0
	v_addc_co_u32_e64 v77, s[4:5], 0, v79, s[4:5]
	v_add_co_u32_e64 v78, s[4:5], s49, v78
	ds_bpermute_b32 v102, v177, v73
	s_nop 0
	v_addc_co_u32_e64 v79, s[4:5], 0, v79, s[4:5]
	global_load_dwordx4 v[84:87], v[76:77], off offset:16
	global_load_dwordx4 v[88:91], v[78:79], off offset:16
	ds_bpermute_b32 v108, v177, v74
	ds_bpermute_b32 v110, v177, v75
	v_mov_b32_e32 v100, v72
	v_mov_b32_e32 v72, v74
	s_waitcnt lgkmcnt(3)
	v_cndmask_b32_e64 v103, v101, -v101, vcc
	s_waitcnt lgkmcnt(2)
	v_cndmask_b32_e64 v109, v102, -v102, vcc
	s_waitcnt lgkmcnt(1)
	v_cndmask_b32_e64 v111, v108, -v108, vcc
	s_waitcnt lgkmcnt(0)
	v_cndmask_b32_e64 v117, v110, -v110, vcc
	s_waitcnt vmcnt(1)
	v_mov_b32_e32 v101, v84
	s_waitcnt vmcnt(0)
	v_mov_b32_e32 v102, v88
	v_mov_b32_e32 v84, v73
	v_mov_b32_e32 v108, v89
	v_mov_b32_e32 v73, v86
	v_mov_b32_e32 v110, v90
	v_mov_b32_e32 v86, v75
	v_mov_b32_e32 v116, v91
	v_pk_mul_f32 v[74:75], v[100:101], v[102:103]
	v_pk_mul_f32 v[84:85], v[84:85], v[108:109]
	v_pk_mul_f32 v[72:73], v[72:73], v[110:111]
	v_pk_mul_f32 v[86:87], v[86:87], v[116:117]
	v_add_f32_e32 v74, v74, v75
	v_add_f32_e32 v75, v84, v85
	v_add_f32_e32 v72, v72, v73
	v_add_f32_e32 v73, v86, v87
	v_mul_f32_e32 v84, v180, v118
	v_mul_f32_e32 v85, v181, v119
	v_cvt_pk_bf16_f32 v84, v84, v85
	v_mul_f32_e32 v85, v167, v126
	v_mul_f32_e32 v86, v183, v127
	v_cvt_pk_bf16_f32 v85, v85, v86
	v_mul_f32_e32 v86, v182, v74
	v_mul_f32_e32 v87, v185, v75
	v_cvt_pk_bf16_f32 v86, v86, v87
	v_mul_f32_e32 v87, v184, v72
	v_mul_f32_e32 v88, v159, v73
	v_cvt_pk_bf16_f32 v87, v87, v88
	v_mul_f32_e32 v88, v150, v118
	v_mul_f32_e32 v89, v152, v119
	v_cvt_pk_bf16_f32 v88, v88, v89
	v_mul_f32_e32 v89, v154, v126
	v_mul_f32_e32 v90, v156, v127
	v_mul_f32_e32 v72, v151, v72
	v_mul_f32_e32 v73, v155, v73
	s_mov_b64 s[0:1], 0x600000
	v_cvt_pk_bf16_f32 v89, v89, v90
	v_mul_f32_e32 v74, v158, v74
	v_mul_f32_e32 v75, v160, v75
	v_cvt_pk_bf16_f32 v90, v74, v75
	v_cvt_pk_bf16_f32 v91, v72, v73
	v_lshl_add_u64 v[72:73], v[120:121], 0, s[0:1]
	s_mov_b32 s0, 0x600000
	v_add_co_u32_e64 v74, s[4:5], s0, v120
	s_mov_b64 s[0:1], 0x2600000
	s_nop 0
	v_addc_co_u32_e64 v75, s[4:5], 0, v121, s[4:5]
	global_store_dwordx4 v[74:75], v[84:87], off
	v_lshl_add_u64 v[74:75], v[120:121], 0, s[0:1]
	s_mov_b32 s0, 0x2600000
	v_add_co_u32_e64 v84, s[4:5], s0, v120
	s_nop 1
	v_addc_co_u32_e64 v85, s[4:5], 0, v121, s[4:5]
	global_store_dwordx4 v[84:85], v[88:91], off
	global_load_dwordx4 v[84:87], v[82:83], off
	s_nop 0
	global_load_dwordx4 v[88:91], v[80:81], off
	ds_bpermute_b32 v101, v177, v68
	ds_bpermute_b32 v102, v177, v69
	ds_bpermute_b32 v108, v177, v70
	ds_bpermute_b32 v110, v177, v71
	v_mov_b32_e32 v100, v68
	v_mov_b32_e32 v68, v70
	s_waitcnt lgkmcnt(3)
	v_cndmask_b32_e64 v103, v101, -v101, vcc
	s_waitcnt lgkmcnt(2)
	v_cndmask_b32_e64 v109, v102, -v102, vcc
	s_waitcnt lgkmcnt(1)
	v_cndmask_b32_e64 v111, v108, -v108, vcc
	s_waitcnt lgkmcnt(0)
	v_cndmask_b32_e64 v117, v110, -v110, vcc
	s_waitcnt vmcnt(1)
	v_mov_b32_e32 v101, v84
	s_waitcnt vmcnt(0)
	v_mov_b32_e32 v102, v88
	v_mov_b32_e32 v84, v69
	v_mov_b32_e32 v108, v89
	v_mov_b32_e32 v69, v86
	v_mov_b32_e32 v110, v90
	v_mov_b32_e32 v86, v71
	v_mov_b32_e32 v116, v91
	v_pk_mul_f32 v[70:71], v[100:101], v[102:103]
	v_pk_mul_f32 v[84:85], v[84:85], v[108:109]
	v_pk_mul_f32 v[68:69], v[68:69], v[110:111]
	v_pk_mul_f32 v[86:87], v[86:87], v[116:117]
	v_add_f32_e32 v110, v70, v71
	v_add_f32_e32 v111, v84, v85
	v_add_f32_e32 v116, v68, v69
	v_add_f32_e32 v117, v86, v87
	global_load_dwordx4 v[68:71], v[76:77], off offset:16
	global_load_dwordx4 v[84:87], v[78:79], off offset:16
	ds_bpermute_b32 v89, v177, v64
	ds_bpermute_b32 v90, v177, v65
	ds_bpermute_b32 v100, v177, v66
	ds_bpermute_b32 v102, v177, v67
	v_mov_b32_e32 v88, v64
	v_mov_b32_e32 v64, v66
	s_waitcnt lgkmcnt(3)
	v_cndmask_b32_e64 v91, v89, -v89, vcc
	s_waitcnt lgkmcnt(2)
	v_cndmask_b32_e64 v101, v90, -v90, vcc
	s_waitcnt lgkmcnt(1)
	v_cndmask_b32_e64 v103, v100, -v100, vcc
	s_waitcnt lgkmcnt(0)
	v_cndmask_b32_e64 v109, v102, -v102, vcc
	s_waitcnt vmcnt(1)
	v_mov_b32_e32 v89, v68
	s_waitcnt vmcnt(0)
;     __device__ __forceinline__ void operator()(const AccT& acc, const Unit& u, int wr, int wc, int fr, int fq) const {
;     ...
;         for (int ai = 0; ai < 2; ++ai) {
;             const int hh = 2 * ai + wr;
;             const float l2f = lgd[hh] * 1.4426950408889634f, l2b = lgd[4 + hh] * 1.4426950408889634f;
;             const float zf0 = exp2f((float)(127 - o0) * l2f), zfs = exp2f(-l2f), zb0 = exp2f((float)o0 * l2b), zbs = exp2f(l2b);
; #pragma unroll
;             for (int m = 0; m < 4; ++m) {
;                 const int r = rbase + ai * 128 + m * 16;
;                 const int d = 4 * (2 * m + (fr >> 3)) + j;
; #pragma unroll
;                 for (int bj = 0; bj < 2; ++bj) {
;                     const int t0 = tb + bj * 128;
;                     float v[8];
; #pragma unroll
;                     for (int jj = 0; jj < 4; ++jj) { v[jj] = acc[ai][bj][m][0][jj]; v[4 + jj] = acc[ai][bj][m][1][jj]; }
;                     if constexpr (ROPE) {
;                         const int t = t0 & 2047;
; #pragma unroll
;                         for (int hf = 0; hf < 2; ++hf) {
;                             f32x4 cs, sn;
;                             if (m < 2) { const float c1 = ropeA[(t >> 6) * 16 + d], s1 = ropeA[1024 + (t >> 6) * 16 + d]; cs = (f32x4){c1, c1, c1, c1}; sn = (f32x4){s1, s1, s1, s1}; }
;                             else { const float* cb = ropeA + 2048 + (d - 16) * 64 + (t & 63) + 4 * hf; cs = *(const f32x4*)(cb); sn = *(const f32x4*)(cb + 1024); }
; #pragma unroll
;                             for (int jj = 0; jj < 4; ++jj) { const float pr = __shfl_xor(v[4 * hf + jj], 4); v[4 * hf + jj] = v[4 * hf + jj] * cs[jj] + sgn * pr * sn[jj]; }
;                             __builtin_amdgcn_sched_barrier(0);
;                         }
;                     }
;                     float zf[8], zb[8]; zf[0] = zf0; zb[0] = zb0;
; #pragma unroll
;                     for (int jj = 1; jj < 8; ++jj) { zf[jj] = zf[jj - 1] * zfs; zb[jj] = zb[jj - 1] * zbs; }
;                     u32x4 wf, wb;
;                     wf.x = cvt_pk_bf16(v[0] * zf[0], v[1] * zf[1]); wf.y = cvt_pk_bf16(v[2] * zf[2], v[3] * zf[3]); wf.z = cvt_pk_bf16(v[4] * zf[4], v[5] * zf[5]); wf.w = cvt_pk_bf16(v[6] * zf[6], v[7] * zf[7]);
	v_mov_b32_e32 v90, v84
	v_mov_b32_e32 v68, v65
	v_mov_b32_e32 v100, v85
	v_mov_b32_e32 v65, v70
	v_mov_b32_e32 v102, v86
	v_mov_b32_e32 v70, v67
	v_mov_b32_e32 v108, v87
	v_pk_mul_f32 v[66:67], v[88:89], v[90:91]
	v_pk_mul_f32 v[68:69], v[68:69], v[100:101]
	v_pk_mul_f32 v[64:65], v[64:65], v[102:103]
	v_pk_mul_f32 v[70:71], v[70:71], v[108:109]
	v_add_f32_e32 v84, v66, v67
	v_add_f32_e32 v85, v68, v69
	v_add_f32_e32 v86, v64, v65
	v_add_f32_e32 v71, v70, v71
	v_mul_f32_e32 v64, v180, v110
	v_mul_f32_e32 v65, v181, v111
	v_cvt_pk_bf16_f32 v64, v64, v65
	v_mul_f32_e32 v65, v167, v116
	v_mul_f32_e32 v66, v183, v117
	v_cvt_pk_bf16_f32 v65, v65, v66
	v_mul_f32_e32 v66, v182, v84
	v_mul_f32_e32 v67, v185, v85
	v_cvt_pk_bf16_f32 v66, v66, v67
	v_mul_f32_e32 v67, v184, v86
	v_mul_f32_e32 v68, v159, v71
	v_cvt_pk_bf16_f32 v67, v67, v68
	v_mul_f32_e32 v68, v150, v110
	v_mul_f32_e32 v69, v152, v111
	v_cvt_pk_bf16_f32 v68, v68, v69
	v_mul_f32_e32 v69, v154, v116
	v_mul_f32_e32 v70, v156, v117
	v_cvt_pk_bf16_f32 v69, v69, v70
	v_mul_f32_e32 v70, v158, v84
	v_mul_f32_e32 v84, v160, v85
	v_mul_f32_e32 v71, v155, v71
	v_cvt_pk_bf16_f32 v70, v70, v84
	v_mul_f32_e32 v84, v151, v86
	v_cvt_pk_bf16_f32 v71, v84, v71
	global_store_dwordx4 v[72:73], v[64:67], off offset:256
	global_store_dwordx4 v[74:75], v[68:71], off offset:256
	global_load_dword v64, v137, s[22:23] offset:8
	s_nop 0
	global_load_dword v70, v137, s[22:23] offset:24
	global_load_dword v67, v[146:147], off
	global_load_dword v74, v[148:149], off
	ds_bpermute_b32 v65, v177, v60
	ds_bpermute_b32 v68, v177, v62
	v_mov_b32_e32 v66, v60
	ds_bpermute_b32 v60, v177, v61
	ds_bpermute_b32 v71, v177, v63
	s_waitcnt lgkmcnt(3)
	v_cndmask_b32_e64 v75, v65, -v65, vcc
	s_waitcnt lgkmcnt(2)
	v_cndmask_b32_e64 v65, v68, -v68, vcc
	s_waitcnt vmcnt(3)
	v_mul_f32_e32 v72, 0x3fb8aa3b, v64
	s_waitcnt vmcnt(2)
	v_mul_f32_e32 v73, 0x3fb8aa3b, v70
	v_mul_f32_e32 v84, v72, v179
	s_waitcnt vmcnt(0)
	v_pk_mul_f32 v[68:69], v[66:67], v[74:75]
	s_waitcnt lgkmcnt(1)
	v_cndmask_b32_e64 v75, v60, -v60, vcc
	v_mov_b32_e32 v66, v61
	v_cmp_lt_f32_e64 s[4:5], s60, v72
	v_mul_f32_e32 v87, v73, v178
	v_pk_mul_f32 v[60:61], v[66:67], v[74:75]
	s_waitcnt lgkmcnt(0)
	v_cndmask_b32_e64 v75, v71, -v71, vcc
	v_mov_b32_e32 v66, v63
	v_cmp_gt_f32_e64 s[8:9], s59, v84
	v_cndmask_b32_e64 v86, 0, v176, s[4:5]
	v_cmp_gt_f32_e64 s[6:7], s59, v73
	s_and_b64 s[0:1], s[4:5], exec
	v_cmp_gt_f32_e64 s[4:5], s59, v87
	v_add_f32_e32 v110, v60, v61
	v_pk_mul_f32 v[60:61], v[66:67], v[74:75]
	v_cndmask_b32_e64 v66, 0, v176, s[8:9]
	v_cndmask_b32_e64 v88, 0, v176, s[6:7]
	v_add_f32_e32 v89, v68, v69
	v_fmac_f32_e32 v86, 0xbfb8aa3b, v64
	v_cndmask_b32_e64 v69, 0, v176, s[4:5]
	v_fmac_f32_e32 v66, v72, v179
	v_fmac_f32_e32 v88, 0x3fb8aa3b, v70
	v_exp_f32_e32 v68, v86
	v_fmac_f32_e32 v69, v73, v178
	v_exp_f32_e32 v66, v66
	v_exp_f32_e32 v70, v88
	v_exp_f32_e32 v69, v69
	v_cndmask_b32_e64 v63, 0, v175, s[8:9]
	s_cselect_b32 s8, 0xffffffc0, 0
	s_and_b64 s[0:1], s[6:7], exec
	v_cndmask_b32_e64 v64, 0, v175, s[4:5]
	s_cselect_b32 s0, 0xffffffc0, 0
	v_ldexp_f32 v100, v68, s8
	v_ldexp_f32 v63, v66, v63
	v_mul_f32_e32 v85, v62, v74
	v_ldexp_f32 v90, v70, s0
	v_ldexp_f32 v64, v69, v64
	v_mul_f32_e32 v75, v100, v63
	v_add_f32_e32 v111, v60, v61
	global_load_dword v108, v[148:149], off
	global_load_dword v69, v[146:147], off
	ds_bpermute_b32 v61, v177, v57
	ds_bpermute_b32 v60, v177, v56
	v_mov_b32_e32 v68, v57
	ds_bpermute_b32 v57, v177, v59
	ds_bpermute_b32 v66, v177, v58
	s_waitcnt lgkmcnt(3)
	v_cndmask_b32_e64 v109, v61, -v61, vcc
	s_waitcnt lgkmcnt(2)
	v_cndmask_b32_e64 v70, v60, -v60, vcc
	s_waitcnt lgkmcnt(0)
	v_cndmask_b32_e64 v72, v66, -v66, vcc
	s_waitcnt vmcnt(1)
	v_mul_f32_e32 v71, v56, v108
	s_waitcnt vmcnt(0)
	v_pk_mul_f32 v[60:61], v[68:69], v[108:109]
	v_cndmask_b32_e64 v109, v57, -v57, vcc
	v_mov_b32_e32 v68, v59
	v_add_f32_e32 v57, v60, v61
	v_pk_mul_f32 v[60:61], v[68:69], v[108:109]
	s_nop 0
	v_add_f32_e32 v59, v60, v61
	v_mov_b32_e32 v91, v67
	v_pk_mul_f32 v[60:61], v[90:91], v[64:65]
	v_mov_b32_e32 v91, v85
	v_pk_mul_f32 v[66:67], v[90:91], v[60:61]
	v_mov_b32_e32 v91, v69
	v_mov_b32_e32 v67, v70
	v_mul_f32_e32 v84, v100, v75
	v_pk_mul_f32 v[68:69], v[90:91], v[66:67]
	v_mov_b32_e32 v70, v90
	v_mul_f32_e32 v86, v100, v84
	v_pk_mul_f32 v[70:71], v[70:71], v[68:69]
	v_mul_f32_e32 v85, v100, v86
	v_mov_b32_e32 v71, v72
	v_mul_f32_e32 v88, v100, v85
	v_pk_mul_f32 v[72:73], v[90:91], v[70:71]
	v_fma_f32 v61, v62, v74, v61
	v_mul_f32_e32 v87, v100, v88
	v_mul_f32_e32 v65, v90, v72
	v_mul_f32_e32 v62, v84, v61
	v_fma_f32 v56, v56, v108, v69
	v_mul_f32_e32 v71, v100, v87
	v_mul_f32_e32 v67, v90, v65
	v_mul_f32_e32 v90, v63, v89
	v_mul_f32_e32 v91, v75, v110
	v_cvt_pk_bf16_f32 v100, v90, v91
	v_mul_f32_e32 v74, v86, v111
	v_cvt_pk_bf16_f32 v101, v62, v74
	v_mul_f32_e32 v62, v85, v56
	v_fma_f32 v58, v58, v108, v73
	v_mul_f32_e32 v69, v88, v57
	v_cvt_pk_bf16_f32 v102, v62, v69
	v_mul_f32_e32 v62, v87, v58
	v_mul_f32_e32 v69, v71, v59
	v_cvt_pk_bf16_f32 v103, v62, v69
	v_mul_f32_e32 v62, v64, v89
	v_mul_f32_e32 v56, v70, v56
	v_mul_f32_e32 v57, v72, v57
	v_mul_f32_e32 v69, v60, v110
	v_cvt_pk_bf16_f32 v108, v62, v69
	v_mul_f32_e32 v61, v66, v61
	v_mul_f32_e32 v62, v68, v111
	v_cvt_pk_bf16_f32 v109, v61, v62
	v_cvt_pk_bf16_f32 v110, v56, v57
	v_mul_f32_e32 v56, v65, v58
	v_mul_f32_e32 v57, v67, v59
	s_mov_b64 s[0:1], 0x1000000
	v_cvt_pk_bf16_f32 v111, v56, v57
	v_lshl_add_u64 v[56:57], v[120:121], 0, s[0:1]
	s_mov_b32 s0, 0x1000000
	v_add_co_u32_e64 v58, s[4:5], s0, v120
	s_mov_b64 s[0:1], 0x3000000
	s_nop 0
	v_addc_co_u32_e64 v59, s[4:5], 0, v121, s[4:5]
	global_store_dwordx4 v[58:59], v[100:103], off
	v_lshl_add_u64 v[58:59], v[120:121], 0, s[0:1]
	s_mov_b32 s0, 0x3000000
	v_add_co_u32_e64 v90, s[4:5], s0, v120
	s_nop 1
	v_addc_co_u32_e64 v91, s[4:5], 0, v121, s[4:5]
	global_store_dwordx4 v[90:91], v[108:111], off
	global_load_dword v91, v[122:123], off
	s_nop 0
	global_load_dword v100, v[124:125], off
	ds_bpermute_b32 v61, v177, v52
	v_mov_b32_e32 v90, v52
	ds_bpermute_b32 v52, v177, v53
	ds_bpermute_b32 v62, v177, v54
	ds_bpermute_b32 v69, v177, v55
	s_waitcnt lgkmcnt(3)
;     __device__ __forceinline__ void operator()(const AccT& acc, const Unit& u, int wr, int wc, int fr, int fq) const {
;     ...
;             for (int m = 0; m < 4; ++m) {
;                 const int r = rbase + ai * 128 + m * 16;
;                 const int d = 4 * (2 * m + (fr >> 3)) + j;
; #pragma unroll
;                 for (int bj = 0; bj < 2; ++bj) {
;                     const int t0 = tb + bj * 128;
;                     float v[8];
; #pragma unroll
;                     for (int jj = 0; jj < 4; ++jj) { v[jj] = acc[ai][bj][m][0][jj]; v[4 + jj] = acc[ai][bj][m][1][jj]; }
;                     if constexpr (ROPE) {
;                         const int t = t0 & 2047;
; #pragma unroll
;                         for (int hf = 0; hf < 2; ++hf) {
;                             f32x4 cs, sn;
;                             if (m < 2) { const float c1 = ropeA[(t >> 6) * 16 + d], s1 = ropeA[1024 + (t >> 6) * 16 + d]; cs = (f32x4){c1, c1, c1, c1}; sn = (f32x4){s1, s1, s1, s1}; }
;                             else { const float* cb = ropeA + 2048 + (d - 16) * 64 + (t & 63) + 4 * hf; cs = *(const f32x4*)(cb); sn = *(const f32x4*)(cb + 1024); }
; #pragma unroll
;                             for (int jj = 0; jj < 4; ++jj) { const float pr = __shfl_xor(v[4 * hf + jj], 4); v[4 * hf + jj] = v[4 * hf + jj] * cs[jj] + sgn * pr * sn[jj]; }
;                             __builtin_amdgcn_sched_barrier(0);
;                         }
;                     }
;                     float zf[8], zb[8]; zf[0] = zf0; zb[0] = zb0;
; #pragma unroll
;                     for (int jj = 1; jj < 8; ++jj) { zf[jj] = zf[jj - 1] * zfs; zb[jj] = zb[jj - 1] * zbs; }
;                     u32x4 wf, wb;
;                     wf.x = cvt_pk_bf16(v[0] * zf[0], v[1] * zf[1]); wf.y = cvt_pk_bf16(v[2] * zf[2], v[3] * zf[3]); wf.z = cvt_pk_bf16(v[4] * zf[4], v[5] * zf[5]); wf.w = cvt_pk_bf16(v[6] * zf[6], v[7] * zf[7]);
;                     wb.x = cvt_pk_bf16(v[0] * zb[0], v[1] * zb[1]); wb.y = cvt_pk_bf16(v[2] * zb[2], v[3] * zb[3]); wb.z = cvt_pk_bf16(v[4] * zb[4], v[5] * zb[5]); wb.w = cvt_pk_bf16(v[6] * zb[6], v[7] * zb[7]);
;                     *(u32x4*)(KTZ + (size_t)r * NT + t0) = wf;
;                     *(u32x4*)(KTZ + (size_t)(256 + r) * NT + t0) = wb;
;                     __builtin_amdgcn_sched_barrier(0);
	v_cndmask_b32_e64 v101, v61, -v61, vcc
	s_waitcnt vmcnt(0)
	v_pk_mul_f32 v[102:103], v[90:91], v[100:101]
	s_waitcnt lgkmcnt(2)
	v_cndmask_b32_e64 v101, v52, -v52, vcc
	v_mov_b32_e32 v90, v53
	v_pk_mul_f32 v[52:53], v[90:91], v[100:101]
	s_waitcnt lgkmcnt(1)
	v_cndmask_b32_e64 v101, v62, -v62, vcc
	v_mov_b32_e32 v90, v54
	v_add_f32_e32 v62, v52, v53
	v_pk_mul_f32 v[52:53], v[90:91], v[100:101]
	s_waitcnt lgkmcnt(0)
	v_cndmask_b32_e64 v101, v69, -v69, vcc
	v_mov_b32_e32 v90, v55
	v_add_f32_e32 v69, v52, v53
	v_pk_mul_f32 v[52:53], v[90:91], v[100:101]
	v_add_f32_e32 v61, v102, v103
	v_add_f32_e32 v73, v52, v53
	global_load_dword v53, v[122:123], off
	global_load_dword v54, v[124:125], off
	ds_bpermute_b32 v55, v177, v48
	v_mov_b32_e32 v52, v48
	ds_bpermute_b32 v48, v177, v49
	ds_bpermute_b32 v74, v177, v50
	ds_bpermute_b32 v89, v177, v51
	s_waitcnt lgkmcnt(3)
	v_cndmask_b32_e64 v55, v55, -v55, vcc
	s_waitcnt vmcnt(0)
	v_pk_mul_f32 v[90:91], v[52:53], v[54:55]
	s_waitcnt lgkmcnt(2)
	v_cndmask_b32_e64 v55, v48, -v48, vcc
	v_mov_b32_e32 v52, v49
	v_pk_mul_f32 v[48:49], v[52:53], v[54:55]
	s_waitcnt lgkmcnt(1)
	v_cndmask_b32_e64 v55, v74, -v74, vcc
	v_mov_b32_e32 v52, v50
	v_add_f32_e32 v74, v48, v49
	v_pk_mul_f32 v[48:49], v[52:53], v[54:55]
	s_waitcnt lgkmcnt(0)
	v_cndmask_b32_e64 v55, v89, -v89, vcc
	v_mov_b32_e32 v52, v51
	v_add_f32_e32 v89, v48, v49
	v_pk_mul_f32 v[48:49], v[52:53], v[54:55]
	v_add_f32_e32 v90, v90, v91
	v_add_f32_e32 v55, v48, v49
	v_mul_f32_e32 v48, v63, v61
	v_mul_f32_e32 v49, v75, v62
	v_cvt_pk_bf16_f32 v48, v48, v49
	v_mul_f32_e32 v49, v84, v69
	v_mul_f32_e32 v50, v86, v73
	v_cvt_pk_bf16_f32 v49, v49, v50
	v_mul_f32_e32 v50, v85, v90
	v_mul_f32_e32 v51, v88, v74
	v_cvt_pk_bf16_f32 v50, v50, v51
	v_mul_f32_e32 v51, v87, v89
	v_mul_f32_e32 v52, v71, v55
	v_cvt_pk_bf16_f32 v51, v51, v52
	v_mul_f32_e32 v52, v64, v61
	v_mul_f32_e32 v53, v60, v62
	v_cvt_pk_bf16_f32 v52, v52, v53
	v_mul_f32_e32 v53, v66, v69
	v_mul_f32_e32 v54, v68, v73
	v_cvt_pk_bf16_f32 v53, v53, v54
	v_mul_f32_e32 v54, v70, v90
	v_mul_f32_e32 v61, v72, v74
	v_mul_f32_e32 v55, v67, v55
	v_cvt_pk_bf16_f32 v54, v54, v61
	v_mul_f32_e32 v61, v65, v89
	v_cvt_pk_bf16_f32 v55, v61, v55
	global_store_dwordx4 v[56:57], v[48:51], off offset:256
	global_store_dwordx4 v[58:59], v[52:55], off offset:256
	global_load_dword v49, v[112:113], off
	s_nop 0
	global_load_dword v50, v[114:115], off
	ds_bpermute_b32 v51, v177, v44
	v_mov_b32_e32 v48, v44
	ds_bpermute_b32 v44, v177, v45
	ds_bpermute_b32 v54, v177, v46
	ds_bpermute_b32 v55, v177, v47
	s_waitcnt lgkmcnt(3)
	v_cndmask_b32_e64 v51, v51, -v51, vcc
	s_waitcnt vmcnt(0)
	v_pk_mul_f32 v[52:53], v[48:49], v[50:51]
	s_waitcnt lgkmcnt(2)
	v_cndmask_b32_e64 v51, v44, -v44, vcc
	v_mov_b32_e32 v48, v45
	v_pk_mul_f32 v[44:45], v[48:49], v[50:51]
	s_waitcnt lgkmcnt(1)
	v_cndmask_b32_e64 v51, v54, -v54, vcc
	v_mov_b32_e32 v48, v46
	v_add_f32_e32 v52, v52, v53
	v_add_f32_e32 v53, v44, v45
	v_pk_mul_f32 v[44:45], v[48:49], v[50:51]
	s_waitcnt lgkmcnt(0)
	v_cndmask_b32_e64 v51, v55, -v55, vcc
	v_mov_b32_e32 v48, v47
	v_add_f32_e32 v54, v44, v45
	v_pk_mul_f32 v[44:45], v[48:49], v[50:51]
	s_nop 0
	v_add_f32_e32 v50, v44, v45
	global_load_dword v45, v[112:113], off
	global_load_dword v46, v[114:115], off
	ds_bpermute_b32 v47, v177, v40
	v_mov_b32_e32 v44, v40
	ds_bpermute_b32 v40, v177, v41
	ds_bpermute_b32 v51, v177, v42
	ds_bpermute_b32 v55, v177, v43
	s_waitcnt lgkmcnt(3)
	v_cndmask_b32_e64 v47, v47, -v47, vcc
	s_waitcnt vmcnt(0)
	v_pk_mul_f32 v[48:49], v[44:45], v[46:47]
	s_waitcnt lgkmcnt(2)
	v_cndmask_b32_e64 v47, v40, -v40, vcc
	v_mov_b32_e32 v44, v41
	v_pk_mul_f32 v[40:41], v[44:45], v[46:47]
	s_waitcnt lgkmcnt(1)
	v_cndmask_b32_e64 v47, v51, -v51, vcc
	v_mov_b32_e32 v44, v42
	v_add_f32_e32 v48, v48, v49
	v_add_f32_e32 v49, v40, v41
	v_pk_mul_f32 v[40:41], v[44:45], v[46:47]
	s_waitcnt lgkmcnt(0)
	v_cndmask_b32_e64 v47, v55, -v55, vcc
	v_mov_b32_e32 v44, v43
	v_add_f32_e32 v51, v40, v41
	v_pk_mul_f32 v[40:41], v[44:45], v[46:47]
	s_nop 0
	v_add_f32_e32 v40, v40, v41
	v_mul_f32_e32 v41, v63, v52
	v_mul_f32_e32 v42, v75, v53
	v_cvt_pk_bf16_f32 v42, v41, v42
	v_mul_f32_e32 v41, v84, v54
	v_mul_f32_e32 v43, v86, v50
	v_cvt_pk_bf16_f32 v43, v41, v43
	v_mul_f32_e32 v41, v85, v48
	v_mul_f32_e32 v44, v88, v49
	v_cvt_pk_bf16_f32 v44, v41, v44
	v_mul_f32_e32 v41, v87, v51
	v_mul_f32_e32 v45, v71, v40
	v_cvt_pk_bf16_f32 v45, v41, v45
	v_mul_f32_e32 v41, v64, v52
	v_mul_f32_e32 v46, v60, v53
	v_cvt_pk_bf16_f32 v46, v41, v46
	v_mul_f32_e32 v41, v66, v54
	v_mul_f32_e32 v47, v68, v50
	v_cvt_pk_bf16_f32 v47, v41, v47
	v_mul_f32_e32 v41, v70, v48
	v_mul_f32_e32 v48, v72, v49
	v_cvt_pk_bf16_f32 v48, v41, v48
	v_mul_f32_e32 v41, v65, v51
	v_mul_f32_e32 v40, v67, v40
	s_mov_b64 s[0:1], 0x1200000
	v_cvt_pk_bf16_f32 v49, v41, v40
	v_lshl_add_u64 v[40:41], v[120:121], 0, s[0:1]
	s_mov_b32 s0, 0x1200000
	v_add_co_u32_e64 v50, s[4:5], s0, v120
	s_mov_b64 s[0:1], 0x3200000
	s_nop 0
	v_addc_co_u32_e64 v51, s[4:5], 0, v121, s[4:5]
	global_store_dwordx4 v[50:51], v[42:45], off
	s_nop 1
	v_lshl_add_u64 v[42:43], v[120:121], 0, s[0:1]
	s_mov_b32 s0, 0x3200000
	v_add_co_u32_e64 v44, s[4:5], s0, v120
	s_nop 1
	v_addc_co_u32_e64 v45, s[4:5], 0, v121, s[4:5]
	global_store_dwordx4 v[44:45], v[46:49], off
	global_load_dword v45, v[104:105], off
	s_nop 0
	global_load_dword v46, v[106:107], off
	ds_bpermute_b32 v47, v177, v36
	v_mov_b32_e32 v44, v36
	ds_bpermute_b32 v36, v177, v37
	ds_bpermute_b32 v50, v177, v38
	ds_bpermute_b32 v51, v177, v39
	s_waitcnt lgkmcnt(3)
	v_cndmask_b32_e64 v47, v47, -v47, vcc
	s_waitcnt vmcnt(0)
	v_pk_mul_f32 v[48:49], v[44:45], v[46:47]
	s_waitcnt lgkmcnt(2)
;     __device__ __forceinline__ void operator()(const AccT& acc, const Unit& u, int wr, int wc, int fr, int fq) const {
;     ...
;             for (int m = 0; m < 4; ++m) {
;                 const int r = rbase + ai * 128 + m * 16;
;                 const int d = 4 * (2 * m + (fr >> 3)) + j;
; #pragma unroll
;                 for (int bj = 0; bj < 2; ++bj) {
;                     const int t0 = tb + bj * 128;
;                     float v[8];
; #pragma unroll
;                     for (int jj = 0; jj < 4; ++jj) { v[jj] = acc[ai][bj][m][0][jj]; v[4 + jj] = acc[ai][bj][m][1][jj]; }
;                     if constexpr (ROPE) {
;                         const int t = t0 & 2047;
; #pragma unroll
;                         for (int hf = 0; hf < 2; ++hf) {
;                             f32x4 cs, sn;
;                             if (m < 2) { const float c1 = ropeA[(t >> 6) * 16 + d], s1 = ropeA[1024 + (t >> 6) * 16 + d]; cs = (f32x4){c1, c1, c1, c1}; sn = (f32x4){s1, s1, s1, s1}; }
;                             else { const float* cb = ropeA + 2048 + (d - 16) * 64 + (t & 63) + 4 * hf; cs = *(const f32x4*)(cb); sn = *(const f32x4*)(cb + 1024); }
; #pragma unroll
;                             for (int jj = 0; jj < 4; ++jj) { const float pr = __shfl_xor(v[4 * hf + jj], 4); v[4 * hf + jj] = v[4 * hf + jj] * cs[jj] + sgn * pr * sn[jj]; }
;                             __builtin_amdgcn_sched_barrier(0);
;                         }
;                     }
;                     float zf[8], zb[8]; zf[0] = zf0; zb[0] = zb0;
; #pragma unroll
;                     for (int jj = 1; jj < 8; ++jj) { zf[jj] = zf[jj - 1] * zfs; zb[jj] = zb[jj - 1] * zbs; }
;                     u32x4 wf, wb;
;                     wf.x = cvt_pk_bf16(v[0] * zf[0], v[1] * zf[1]); wf.y = cvt_pk_bf16(v[2] * zf[2], v[3] * zf[3]); wf.z = cvt_pk_bf16(v[4] * zf[4], v[5] * zf[5]); wf.w = cvt_pk_bf16(v[6] * zf[6], v[7] * zf[7]);
;                     wb.x = cvt_pk_bf16(v[0] * zb[0], v[1] * zb[1]); wb.y = cvt_pk_bf16(v[2] * zb[2], v[3] * zb[3]); wb.z = cvt_pk_bf16(v[4] * zb[4], v[5] * zb[5]); wb.w = cvt_pk_bf16(v[6] * zb[6], v[7] * zb[7]);
;                     *(u32x4*)(KTZ + (size_t)r * NT + t0) = wf;
;                     *(u32x4*)(KTZ + (size_t)(256 + r) * NT + t0) = wb;
;                     __builtin_amdgcn_sched_barrier(0);
	v_cndmask_b32_e64 v47, v36, -v36, vcc
	v_mov_b32_e32 v44, v37
	v_pk_mul_f32 v[36:37], v[44:45], v[46:47]
	s_waitcnt lgkmcnt(1)
	v_cndmask_b32_e64 v47, v50, -v50, vcc
	v_mov_b32_e32 v44, v38
	v_add_f32_e32 v48, v48, v49
	v_add_f32_e32 v49, v36, v37
	v_pk_mul_f32 v[36:37], v[44:45], v[46:47]
	s_waitcnt lgkmcnt(0)
	v_cndmask_b32_e64 v47, v51, -v51, vcc
	v_mov_b32_e32 v44, v39
	v_add_f32_e32 v50, v36, v37
	v_pk_mul_f32 v[36:37], v[44:45], v[46:47]
	s_nop 0
	v_add_f32_e32 v46, v36, v37
	global_load_dword v37, v[104:105], off
	global_load_dword v38, v[106:107], off
	ds_bpermute_b32 v39, v177, v32
	v_mov_b32_e32 v36, v32
	ds_bpermute_b32 v32, v177, v33
	ds_bpermute_b32 v47, v177, v34
	ds_bpermute_b32 v51, v177, v35
	s_waitcnt lgkmcnt(3)
	v_cndmask_b32_e64 v39, v39, -v39, vcc
	s_waitcnt vmcnt(0)
	v_pk_mul_f32 v[44:45], v[36:37], v[38:39]
	s_waitcnt lgkmcnt(2)
	v_cndmask_b32_e64 v39, v32, -v32, vcc
	v_mov_b32_e32 v36, v33
	v_pk_mul_f32 v[32:33], v[36:37], v[38:39]
	s_waitcnt lgkmcnt(1)
	v_cndmask_b32_e64 v39, v47, -v47, vcc
	v_mov_b32_e32 v36, v34
	v_add_f32_e32 v44, v44, v45
	v_add_f32_e32 v45, v32, v33
	v_pk_mul_f32 v[32:33], v[36:37], v[38:39]
	s_waitcnt lgkmcnt(0)
	v_cndmask_b32_e64 v39, v51, -v51, vcc
	v_mov_b32_e32 v36, v35
	v_add_f32_e32 v47, v32, v33
	v_pk_mul_f32 v[32:33], v[36:37], v[38:39]
	s_nop 0
	v_add_f32_e32 v39, v32, v33
	v_mul_f32_e32 v32, v63, v48
	v_mul_f32_e32 v33, v75, v49
	v_cvt_pk_bf16_f32 v32, v32, v33
	v_mul_f32_e32 v33, v84, v50
	v_mul_f32_e32 v34, v86, v46
	v_cvt_pk_bf16_f32 v33, v33, v34
	v_mul_f32_e32 v34, v85, v44
	v_mul_f32_e32 v35, v88, v45
	v_cvt_pk_bf16_f32 v34, v34, v35
	v_mul_f32_e32 v35, v87, v47
	v_mul_f32_e32 v36, v71, v39
	v_cvt_pk_bf16_f32 v35, v35, v36
	v_mul_f32_e32 v36, v64, v48
	v_mul_f32_e32 v37, v60, v49
	v_cvt_pk_bf16_f32 v36, v36, v37
	v_mul_f32_e32 v37, v66, v50
	v_mul_f32_e32 v38, v68, v46
	v_cvt_pk_bf16_f32 v37, v37, v38
	v_mul_f32_e32 v38, v70, v44
	v_mul_f32_e32 v44, v72, v45
	v_mul_f32_e32 v39, v67, v39
	v_cvt_pk_bf16_f32 v38, v38, v44
	v_mul_f32_e32 v44, v65, v47
	v_cvt_pk_bf16_f32 v39, v44, v39
	global_store_dwordx4 v[40:41], v[32:35], off offset:256
	global_store_dwordx4 v[42:43], v[36:39], off offset:256
	global_load_dwordx4 v[32:35], v[98:99], off
	s_nop 0
	global_load_dwordx4 v[36:39], v[96:97], off
	ds_bpermute_b32 v41, v177, v28
	ds_bpermute_b32 v42, v177, v29
	ds_bpermute_b32 v44, v177, v30
	ds_bpermute_b32 v46, v177, v31
	v_mov_b32_e32 v40, v28
	v_mov_b32_e32 v28, v30
	s_waitcnt lgkmcnt(3)
	v_cndmask_b32_e64 v43, v41, -v41, vcc
	s_waitcnt lgkmcnt(2)
	v_cndmask_b32_e64 v45, v42, -v42, vcc
	s_waitcnt lgkmcnt(1)
	v_cndmask_b32_e64 v47, v44, -v44, vcc
	s_waitcnt lgkmcnt(0)
	v_cndmask_b32_e64 v49, v46, -v46, vcc
	s_waitcnt vmcnt(1)
	v_mov_b32_e32 v41, v32
	s_waitcnt vmcnt(0)
	v_mov_b32_e32 v42, v36
	v_mov_b32_e32 v32, v29
	v_mov_b32_e32 v44, v37
	v_mov_b32_e32 v29, v34
	v_mov_b32_e32 v46, v38
	v_mov_b32_e32 v34, v31
	v_mov_b32_e32 v48, v39
	v_pk_mul_f32 v[30:31], v[40:41], v[42:43]
	v_pk_mul_f32 v[32:33], v[32:33], v[44:45]
	v_pk_mul_f32 v[28:29], v[28:29], v[46:47]
	v_pk_mul_f32 v[34:35], v[34:35], v[48:49]
	v_add_f32_e32 v46, v30, v31
	v_add_f32_e32 v47, v32, v33
	v_add_f32_e32 v48, v28, v29
	v_add_f32_e32 v49, v34, v35
	global_load_dwordx4 v[28:31], v[92:93], off offset:16
	global_load_dwordx4 v[32:35], v[94:95], off offset:16
	ds_bpermute_b32 v37, v177, v24
	ds_bpermute_b32 v38, v177, v25
	ds_bpermute_b32 v40, v177, v26
	ds_bpermute_b32 v42, v177, v27
	v_mov_b32_e32 v36, v24
	v_mov_b32_e32 v24, v26
	s_waitcnt lgkmcnt(3)
	v_cndmask_b32_e64 v39, v37, -v37, vcc
	s_waitcnt lgkmcnt(2)
	v_cndmask_b32_e64 v41, v38, -v38, vcc
	s_waitcnt lgkmcnt(1)
	v_cndmask_b32_e64 v43, v40, -v40, vcc
	s_waitcnt lgkmcnt(0)
	v_cndmask_b32_e64 v45, v42, -v42, vcc
	s_waitcnt vmcnt(1)
	v_mov_b32_e32 v37, v28
	s_waitcnt vmcnt(0)
	v_mov_b32_e32 v38, v32
	v_mov_b32_e32 v28, v25
	v_mov_b32_e32 v40, v33
	v_mov_b32_e32 v25, v30
	v_mov_b32_e32 v42, v34
	v_mov_b32_e32 v30, v27
	v_mov_b32_e32 v44, v35
	v_pk_mul_f32 v[26:27], v[36:37], v[38:39]
	v_pk_mul_f32 v[28:29], v[28:29], v[40:41]
	v_pk_mul_f32 v[24:25], v[24:25], v[42:43]
	v_pk_mul_f32 v[30:31], v[30:31], v[44:45]
	v_add_f32_e32 v32, v26, v27
	v_add_f32_e32 v33, v28, v29
	v_add_f32_e32 v24, v24, v25
	v_add_f32_e32 v25, v30, v31
	v_mul_f32_e32 v26, v63, v46
	v_mul_f32_e32 v27, v75, v47
	v_cvt_pk_bf16_f32 v26, v26, v27
	v_mul_f32_e32 v27, v84, v48
	v_mul_f32_e32 v28, v86, v49
	v_cvt_pk_bf16_f32 v27, v27, v28
	v_mul_f32_e32 v28, v85, v32
	v_mul_f32_e32 v29, v88, v33
	v_cvt_pk_bf16_f32 v28, v28, v29
	v_mul_f32_e32 v29, v87, v24
	v_mul_f32_e32 v30, v71, v25
	v_cvt_pk_bf16_f32 v29, v29, v30
	v_mul_f32_e32 v30, v64, v46
	v_mul_f32_e32 v31, v60, v47
	v_cvt_pk_bf16_f32 v30, v30, v31
	v_mul_f32_e32 v31, v66, v48
	v_mul_f32_e32 v32, v70, v32
	v_mul_f32_e32 v33, v72, v33
	v_mul_f32_e32 v24, v65, v24
	v_mul_f32_e32 v25, v67, v25
	s_mov_b64 s[0:1], 0x1400000
	v_mul_f32_e32 v34, v68, v49
	v_cvt_pk_bf16_f32 v31, v31, v34
	v_cvt_pk_bf16_f32 v32, v32, v33
	v_cvt_pk_bf16_f32 v33, v24, v25
	v_lshl_add_u64 v[24:25], v[120:121], 0, s[0:1]
	s_mov_b32 s0, 0x1400000
	v_add_co_u32_e64 v34, s[4:5], s0, v120
	s_mov_b64 s[0:1], 0x3400000
	s_nop 0
	v_addc_co_u32_e64 v35, s[4:5], 0, v121, s[4:5]
	global_store_dwordx4 v[34:35], v[26:29], off
	s_nop 1
	v_lshl_add_u64 v[26:27], v[120:121], 0, s[0:1]
	s_mov_b32 s0, 0x3400000
	v_add_co_u32_e64 v28, s[4:5], s0, v120
	s_nop 1
	v_addc_co_u32_e64 v29, s[4:5], 0, v121, s[4:5]
	global_store_dwordx4 v[28:29], v[30:33], off
	global_load_dwordx4 v[28:31], v[98:99], off
	s_nop 0
	global_load_dwordx4 v[32:35], v[96:97], off
	ds_bpermute_b32 v37, v177, v20
	ds_bpermute_b32 v38, v177, v21
	ds_bpermute_b32 v40, v177, v22
	ds_bpermute_b32 v42, v177, v23
	v_mov_b32_e32 v36, v20
	v_mov_b32_e32 v20, v22
	s_waitcnt lgkmcnt(3)
;     __device__ __forceinline__ void operator()(const AccT& acc, const Unit& u, int wr, int wc, int fr, int fq) const {
;     ...
;             for (int m = 0; m < 4; ++m) {
;                 const int r = rbase + ai * 128 + m * 16;
;                 const int d = 4 * (2 * m + (fr >> 3)) + j;
; #pragma unroll
;                 for (int bj = 0; bj < 2; ++bj) {
;                     const int t0 = tb + bj * 128;
;                     float v[8];
; #pragma unroll
;                     for (int jj = 0; jj < 4; ++jj) { v[jj] = acc[ai][bj][m][0][jj]; v[4 + jj] = acc[ai][bj][m][1][jj]; }
;                     if constexpr (ROPE) {
;                         const int t = t0 & 2047;
; #pragma unroll
;                         for (int hf = 0; hf < 2; ++hf) {
;                             f32x4 cs, sn;
;                             if (m < 2) { const float c1 = ropeA[(t >> 6) * 16 + d], s1 = ropeA[1024 + (t >> 6) * 16 + d]; cs = (f32x4){c1, c1, c1, c1}; sn = (f32x4){s1, s1, s1, s1}; }
;                             else { const float* cb = ropeA + 2048 + (d - 16) * 64 + (t & 63) + 4 * hf; cs = *(const f32x4*)(cb); sn = *(const f32x4*)(cb + 1024); }
; #pragma unroll
;                             for (int jj = 0; jj < 4; ++jj) { const float pr = __shfl_xor(v[4 * hf + jj], 4); v[4 * hf + jj] = v[4 * hf + jj] * cs[jj] + sgn * pr * sn[jj]; }
;                             __builtin_amdgcn_sched_barrier(0);
;                         }
;                     }
;                     float zf[8], zb[8]; zf[0] = zf0; zb[0] = zb0;
; #pragma unroll
;                     for (int jj = 1; jj < 8; ++jj) { zf[jj] = zf[jj - 1] * zfs; zb[jj] = zb[jj - 1] * zbs; }
;                     u32x4 wf, wb;
;                     wf.x = cvt_pk_bf16(v[0] * zf[0], v[1] * zf[1]); wf.y = cvt_pk_bf16(v[2] * zf[2], v[3] * zf[3]); wf.z = cvt_pk_bf16(v[4] * zf[4], v[5] * zf[5]); wf.w = cvt_pk_bf16(v[6] * zf[6], v[7] * zf[7]);
;                     wb.x = cvt_pk_bf16(v[0] * zb[0], v[1] * zb[1]); wb.y = cvt_pk_bf16(v[2] * zb[2], v[3] * zb[3]); wb.z = cvt_pk_bf16(v[4] * zb[4], v[5] * zb[5]); wb.w = cvt_pk_bf16(v[6] * zb[6], v[7] * zb[7]);
;                     *(u32x4*)(KTZ + (size_t)r * NT + t0) = wf;
;                     *(u32x4*)(KTZ + (size_t)(256 + r) * NT + t0) = wb;
;                     __builtin_amdgcn_sched_barrier(0);
	v_cndmask_b32_e64 v39, v37, -v37, vcc
	s_waitcnt lgkmcnt(2)
	v_cndmask_b32_e64 v41, v38, -v38, vcc
	s_waitcnt lgkmcnt(1)
	v_cndmask_b32_e64 v43, v40, -v40, vcc
	s_waitcnt lgkmcnt(0)
	v_cndmask_b32_e64 v45, v42, -v42, vcc
	s_waitcnt vmcnt(1)
	v_mov_b32_e32 v37, v28
	s_waitcnt vmcnt(0)
	v_mov_b32_e32 v38, v32
	v_mov_b32_e32 v28, v21
	v_mov_b32_e32 v40, v33
	v_mov_b32_e32 v21, v30
	v_mov_b32_e32 v42, v34
	v_mov_b32_e32 v30, v23
	v_mov_b32_e32 v44, v35
	v_pk_mul_f32 v[22:23], v[36:37], v[38:39]
	v_pk_mul_f32 v[28:29], v[28:29], v[40:41]
	v_pk_mul_f32 v[20:21], v[20:21], v[42:43]
	v_pk_mul_f32 v[30:31], v[30:31], v[44:45]
	v_add_f32_e32 v42, v22, v23
	v_add_f32_e32 v43, v28, v29
	v_add_f32_e32 v44, v20, v21
	v_add_f32_e32 v45, v30, v31
	global_load_dwordx4 v[20:23], v[92:93], off offset:16
	global_load_dwordx4 v[28:31], v[94:95], off offset:16
	ds_bpermute_b32 v33, v177, v16
	ds_bpermute_b32 v34, v177, v17
	ds_bpermute_b32 v36, v177, v18
	ds_bpermute_b32 v38, v177, v19
	v_mov_b32_e32 v32, v16
	v_mov_b32_e32 v16, v18
	s_waitcnt lgkmcnt(3)
	v_cndmask_b32_e64 v35, v33, -v33, vcc
	s_waitcnt lgkmcnt(2)
	v_cndmask_b32_e64 v37, v34, -v34, vcc
	s_waitcnt lgkmcnt(1)
	v_cndmask_b32_e64 v39, v36, -v36, vcc
	s_waitcnt lgkmcnt(0)
	v_cndmask_b32_e64 v41, v38, -v38, vcc
	s_waitcnt vmcnt(1)
	v_mov_b32_e32 v33, v20
	s_waitcnt vmcnt(0)
	v_mov_b32_e32 v34, v28
	v_mov_b32_e32 v20, v17
	v_mov_b32_e32 v36, v29
	v_mov_b32_e32 v17, v22
	v_mov_b32_e32 v38, v30
	v_mov_b32_e32 v22, v19
	v_mov_b32_e32 v40, v31
	v_pk_mul_f32 v[18:19], v[32:33], v[34:35]
	v_pk_mul_f32 v[20:21], v[20:21], v[36:37]
	v_pk_mul_f32 v[16:17], v[16:17], v[38:39]
	v_pk_mul_f32 v[22:23], v[22:23], v[40:41]
	v_add_f32_e32 v28, v18, v19
	v_add_f32_e32 v29, v20, v21
	v_add_f32_e32 v30, v16, v17
	v_add_f32_e32 v23, v22, v23
	v_mul_f32_e32 v16, v63, v42
	v_mul_f32_e32 v17, v75, v43
	v_cvt_pk_bf16_f32 v16, v16, v17
	v_mul_f32_e32 v17, v84, v44
	v_mul_f32_e32 v18, v86, v45
	v_cvt_pk_bf16_f32 v17, v17, v18
	v_mul_f32_e32 v18, v85, v28
	v_mul_f32_e32 v19, v88, v29
	v_cvt_pk_bf16_f32 v18, v18, v19
	v_mul_f32_e32 v19, v87, v30
	v_mul_f32_e32 v20, v71, v23
	v_cvt_pk_bf16_f32 v19, v19, v20
	v_mul_f32_e32 v20, v64, v42
	v_mul_f32_e32 v21, v60, v43
	v_cvt_pk_bf16_f32 v20, v20, v21
	v_mul_f32_e32 v21, v66, v44
	v_mul_f32_e32 v22, v68, v45
	v_cvt_pk_bf16_f32 v21, v21, v22
	v_mul_f32_e32 v22, v70, v28
	v_mul_f32_e32 v28, v72, v29
	v_mul_f32_e32 v23, v67, v23
	v_cvt_pk_bf16_f32 v22, v22, v28
	v_mul_f32_e32 v28, v65, v30
	v_cvt_pk_bf16_f32 v23, v28, v23
	global_store_dwordx4 v[24:25], v[16:19], off offset:256
	global_store_dwordx4 v[26:27], v[20:23], off offset:256
	global_load_dwordx4 v[16:19], v[82:83], off
	s_nop 0
	global_load_dwordx4 v[20:23], v[80:81], off
	ds_bpermute_b32 v25, v177, v12
	ds_bpermute_b32 v26, v177, v13
	ds_bpermute_b32 v28, v177, v14
	ds_bpermute_b32 v30, v177, v15
	v_mov_b32_e32 v24, v12
	v_mov_b32_e32 v12, v14
	s_waitcnt lgkmcnt(3)
	v_cndmask_b32_e64 v27, v25, -v25, vcc
	s_waitcnt lgkmcnt(2)
	v_cndmask_b32_e64 v29, v26, -v26, vcc
	s_waitcnt lgkmcnt(1)
	v_cndmask_b32_e64 v31, v28, -v28, vcc
	s_waitcnt lgkmcnt(0)
	v_cndmask_b32_e64 v33, v30, -v30, vcc
	s_waitcnt vmcnt(1)
	v_mov_b32_e32 v25, v16
	s_waitcnt vmcnt(0)
	v_mov_b32_e32 v26, v20
	v_mov_b32_e32 v16, v13
	v_mov_b32_e32 v28, v21
	v_mov_b32_e32 v13, v18
	v_mov_b32_e32 v30, v22
	v_mov_b32_e32 v18, v15
	v_mov_b32_e32 v32, v23
	v_pk_mul_f32 v[14:15], v[24:25], v[26:27]
	v_pk_mul_f32 v[16:17], v[16:17], v[28:29]
	v_pk_mul_f32 v[12:13], v[12:13], v[30:31]
	v_pk_mul_f32 v[18:19], v[18:19], v[32:33]
	v_add_f32_e32 v30, v14, v15
	v_add_f32_e32 v31, v16, v17
	v_add_f32_e32 v32, v12, v13
	v_add_f32_e32 v33, v18, v19
	global_load_dwordx4 v[12:15], v[76:77], off offset:16
	global_load_dwordx4 v[16:19], v[78:79], off offset:16
	ds_bpermute_b32 v21, v177, v8
	ds_bpermute_b32 v22, v177, v9
	ds_bpermute_b32 v24, v177, v10
	ds_bpermute_b32 v26, v177, v11
	v_mov_b32_e32 v20, v8
	v_mov_b32_e32 v8, v10
	s_waitcnt lgkmcnt(3)
	v_cndmask_b32_e64 v23, v21, -v21, vcc
	s_waitcnt lgkmcnt(2)
	v_cndmask_b32_e64 v25, v22, -v22, vcc
	s_waitcnt lgkmcnt(1)
	v_cndmask_b32_e64 v27, v24, -v24, vcc
	s_waitcnt lgkmcnt(0)
	v_cndmask_b32_e64 v29, v26, -v26, vcc
	s_waitcnt vmcnt(1)
	v_mov_b32_e32 v21, v12
	s_waitcnt vmcnt(0)
; #define PG8_BAR __builtin_amdgcn_s_barrier()
; template <class Epi, class Sched>
; __device__ __forceinline__ void gemm_phase(LAS unsigned char* lds, const Gemm g, const Sched& S, const Epi& E) {
;     ...
;     PG8_WAIT_V(0);
;     if (wr == 0) PG8_BAR;
;     PG8_BAR;
;     __device__ __forceinline__ void operator()(const AccT& acc, const Unit& u, int wr, int wc, int fr, int fq) const {
;     ...
;                 for (int bj = 0; bj < 2; ++bj) {
;                     const int t0 = tb + bj * 128;
;                     float v[8];
; #pragma unroll
;                     for (int jj = 0; jj < 4; ++jj) { v[jj] = acc[ai][bj][m][0][jj]; v[4 + jj] = acc[ai][bj][m][1][jj]; }
;                     if constexpr (ROPE) {
;                         const int t = t0 & 2047;
; #pragma unroll
;                         for (int hf = 0; hf < 2; ++hf) {
;                             f32x4 cs, sn;
;                             if (m < 2) { const float c1 = ropeA[(t >> 6) * 16 + d], s1 = ropeA[1024 + (t >> 6) * 16 + d]; cs = (f32x4){c1, c1, c1, c1}; sn = (f32x4){s1, s1, s1, s1}; }
;                             else { const float* cb = ropeA + 2048 + (d - 16) * 64 + (t & 63) + 4 * hf; cs = *(const f32x4*)(cb); sn = *(const f32x4*)(cb + 1024); }
; #pragma unroll
;                             for (int jj = 0; jj < 4; ++jj) { const float pr = __shfl_xor(v[4 * hf + jj], 4); v[4 * hf + jj] = v[4 * hf + jj] * cs[jj] + sgn * pr * sn[jj]; }
;                             __builtin_amdgcn_sched_barrier(0);
;                         }
;                     }
;                     float zf[8], zb[8]; zf[0] = zf0; zb[0] = zb0;
; #pragma unroll
;                     for (int jj = 1; jj < 8; ++jj) { zf[jj] = zf[jj - 1] * zfs; zb[jj] = zb[jj - 1] * zbs; }
;                     u32x4 wf, wb;
;                     wf.x = cvt_pk_bf16(v[0] * zf[0], v[1] * zf[1]); wf.y = cvt_pk_bf16(v[2] * zf[2], v[3] * zf[3]); wf.z = cvt_pk_bf16(v[4] * zf[4], v[5] * zf[5]); wf.w = cvt_pk_bf16(v[6] * zf[6], v[7] * zf[7]);
;                     wb.x = cvt_pk_bf16(v[0] * zb[0], v[1] * zb[1]); wb.y = cvt_pk_bf16(v[2] * zb[2], v[3] * zb[3]); wb.z = cvt_pk_bf16(v[4] * zb[4], v[5] * zb[5]); wb.w = cvt_pk_bf16(v[6] * zb[6], v[7] * zb[7]);
;                     *(u32x4*)(KTZ + (size_t)r * NT + t0) = wf;
;                     *(u32x4*)(KTZ + (size_t)(256 + r) * NT + t0) = wb;
;                     __builtin_amdgcn_sched_barrier(0);
	v_mov_b32_e32 v22, v16
	v_mov_b32_e32 v12, v9
	v_mov_b32_e32 v24, v17
	v_mov_b32_e32 v9, v14
	v_mov_b32_e32 v26, v18
	v_mov_b32_e32 v14, v11
	v_mov_b32_e32 v28, v19
	v_pk_mul_f32 v[10:11], v[20:21], v[22:23]
	v_pk_mul_f32 v[12:13], v[12:13], v[24:25]
	v_pk_mul_f32 v[8:9], v[8:9], v[26:27]
	v_pk_mul_f32 v[14:15], v[14:15], v[28:29]
	v_add_f32_e32 v16, v10, v11
	v_add_f32_e32 v17, v12, v13
	v_add_f32_e32 v8, v8, v9
	v_add_f32_e32 v9, v14, v15
	v_mul_f32_e32 v10, v63, v30
	v_mul_f32_e32 v11, v75, v31
	v_cvt_pk_bf16_f32 v10, v10, v11
	v_mul_f32_e32 v11, v84, v32
	v_mul_f32_e32 v12, v86, v33
	v_cvt_pk_bf16_f32 v11, v11, v12
	v_mul_f32_e32 v12, v85, v16
	v_mul_f32_e32 v13, v88, v17
	v_cvt_pk_bf16_f32 v12, v12, v13
	v_mul_f32_e32 v13, v87, v8
	v_mul_f32_e32 v14, v71, v9
	v_cvt_pk_bf16_f32 v13, v13, v14
	v_mul_f32_e32 v14, v64, v30
	v_mul_f32_e32 v15, v60, v31
	v_cvt_pk_bf16_f32 v14, v14, v15
	v_mul_f32_e32 v15, v66, v32
	v_mul_f32_e32 v18, v68, v33
	v_cvt_pk_bf16_f32 v15, v15, v18
	v_add_co_u32_e64 v18, s[4:5], s63, v120
	v_mul_f32_e32 v16, v70, v16
	v_mul_f32_e32 v17, v72, v17
	v_addc_co_u32_e64 v19, s[4:5], 0, v121, s[4:5]
	v_cvt_pk_bf16_f32 v16, v16, v17
	v_mul_f32_e32 v8, v65, v8
	v_mul_f32_e32 v9, v67, v9
	v_cvt_pk_bf16_f32 v17, v8, v9
	global_store_dwordx4 v[18:19], v[10:13], off
	v_lshl_add_u64 v[8:9], v[120:121], 0, s[26:27]
	s_nop 0
	v_add_co_u32_e64 v12, s[4:5], s64, v120
	v_lshl_add_u64 v[10:11], v[120:121], 0, s[28:29]
	s_nop 0
	v_addc_co_u32_e64 v13, s[4:5], 0, v121, s[4:5]
	global_store_dwordx4 v[12:13], v[14:17], off
	global_load_dwordx4 v[12:15], v[82:83], off
	s_nop 0
	global_load_dwordx4 v[16:19], v[80:81], off
	ds_bpermute_b32 v34, v177, v4
	ds_bpermute_b32 v32, v177, v5
	ds_bpermute_b32 v33, v177, v6
	ds_bpermute_b32 v28, v177, v7
	global_load_dwordx4 v[20:23], v[76:77], off offset:16
	global_load_dwordx4 v[24:27], v[78:79], off offset:16
	s_waitcnt lgkmcnt(0)
	v_cndmask_b32_e64 v29, v28, -v28, vcc
	v_mov_b32_e32 v30, v7
	s_waitcnt vmcnt(3)
	v_mov_b32_e32 v31, v15
	s_waitcnt vmcnt(2)
	v_mov_b32_e32 v28, v19
	v_cndmask_b32_e64 v19, v33, -v33, vcc
	v_mov_b32_e32 v7, v14
	v_cndmask_b32_e64 v15, v32, -v32, vcc
	v_mov_b32_e32 v32, v5
	v_mov_b32_e32 v33, v13
	v_mov_b32_e32 v14, v17
	v_cndmask_b32_e64 v17, v34, -v34, vcc
	v_mov_b32_e32 v5, v12
	ds_bpermute_b32 v13, v177, v0
	v_mov_b32_e32 v12, v0
	ds_bpermute_b32 v34, v177, v1
	ds_bpermute_b32 v35, v177, v2
	v_mov_b32_e32 v0, v2
	ds_bpermute_b32 v2, v177, v3
	v_pk_mul_f32 v[28:29], v[30:31], v[28:29]
	v_pk_mul_f32 v[6:7], v[6:7], v[18:19]
	v_pk_mul_f32 v[14:15], v[32:33], v[14:15]
	v_pk_mul_f32 v[4:5], v[4:5], v[16:17]
	v_add_f32_e32 v18, v28, v29
	v_add_f32_e32 v19, v6, v7
	v_add_f32_e32 v28, v14, v15
	v_add_f32_e32 v29, v4, v5
	s_waitcnt lgkmcnt(3)
	v_cndmask_b32_e64 v5, v13, -v13, vcc
	s_waitcnt lgkmcnt(2)
	v_cndmask_b32_e64 v7, v34, -v34, vcc
	s_waitcnt lgkmcnt(1)
	v_cndmask_b32_e64 v15, v35, -v35, vcc
	s_waitcnt lgkmcnt(0)
	v_cndmask_b32_e64 v17, v2, -v2, vcc
	s_waitcnt vmcnt(1)
	v_mov_b32_e32 v13, v20
	s_waitcnt vmcnt(0)
	v_mov_b32_e32 v4, v24
	v_mov_b32_e32 v20, v1
	v_mov_b32_e32 v6, v25
	v_mov_b32_e32 v1, v22
	v_mov_b32_e32 v14, v26
	v_mov_b32_e32 v22, v3
	v_mov_b32_e32 v16, v27
	v_pk_mul_f32 v[2:3], v[12:13], v[4:5]
	v_pk_mul_f32 v[4:5], v[20:21], v[6:7]
	v_pk_mul_f32 v[0:1], v[0:1], v[14:15]
	v_pk_mul_f32 v[6:7], v[22:23], v[16:17]
	v_add_f32_e32 v12, v2, v3
	v_add_f32_e32 v13, v4, v5
	v_add_f32_e32 v14, v0, v1
	v_add_f32_e32 v7, v6, v7
	v_mul_f32_e32 v0, v63, v29
	v_mul_f32_e32 v1, v75, v28
	v_cvt_pk_bf16_f32 v0, v0, v1
	v_mul_f32_e32 v1, v84, v19
	v_mul_f32_e32 v2, v86, v18
	v_cvt_pk_bf16_f32 v1, v1, v2
	v_mul_f32_e32 v2, v85, v12
	v_mul_f32_e32 v3, v88, v13
	v_cvt_pk_bf16_f32 v2, v2, v3
	v_mul_f32_e32 v3, v87, v14
	v_mul_f32_e32 v4, v71, v7
	v_cvt_pk_bf16_f32 v3, v3, v4
	v_mul_f32_e32 v4, v64, v29
	v_mul_f32_e32 v5, v60, v28
	v_cvt_pk_bf16_f32 v4, v4, v5
	v_mul_f32_e32 v5, v66, v19
	v_mul_f32_e32 v6, v68, v18
	v_cvt_pk_bf16_f32 v5, v5, v6
	v_mul_f32_e32 v6, v70, v12
	v_mul_f32_e32 v12, v72, v13
	v_mul_f32_e32 v7, v67, v7
	v_cvt_pk_bf16_f32 v6, v6, v12
	v_mul_f32_e32 v12, v65, v14
	v_cvt_pk_bf16_f32 v7, v12, v7
	global_store_dwordx4 v[8:9], v[0:3], off offset:256
	global_store_dwordx4 v[10:11], v[4:7], off offset:256
	s_and_b64 vcc, exec, s[2:3]
	s_mov_b32 s33, s30
	s_mov_b64 s[4:5], s[38:39]
	s_mov_b64 s[0:1], s[36:37]
	s_cbranch_vccz .LBB0_606
	s_waitcnt vmcnt(0)
	s_cmpk_gt_u32 s42, 0xff
	s_cbranch_scc1 .LBB0_617
	s_barrier

; #define PG8_STAGE(bufoff, gbase, voff) do { _Pragma("unroll") for (int _i = 0; _i < 2; ++_i) \
;         __builtin_amdgcn_global_load_lds((const unsigned*)((const char*)(gbase) + (voff)[_i]), (LAS unsigned*)(lds + (bufoff) + ldsw + _i * 8192), 16, 0, 0); } while (0)
; #define PG8_LDA(dst, b, h) do { _Pragma("unroll") for (int m = 0; m < 4; ++m) _Pragma("unroll") for (int k = 0; k < 2; ++k) dst[m][k] = *(const LAS bf16x8*)(lds + PG8_SA(b, h) + aoff + m * 2048 + k * 1024); } while (0)
; #define PG8_LDB(dst, b, h) do { _Pragma("unroll") for (int n = 0; n < 2; ++n) _Pragma("unroll") for (int k = 0; k < 2; ++k) dst[n][k] = *(const LAS bf16x8*)(lds + PG8_SB(b, h) + boff + n * 2048 + k * 1024); } while (0)
; #define PG8_MMA(ai, bj, At, Bt) do { __builtin_amdgcn_s_setprio(1); _Pragma("unroll") for (int m = 0; m < 4; ++m) _Pragma("unroll") for (int n = 0; n < 2; ++n) _Pragma("unroll") for (int k = 0; k < 2; ++k) \
;         acc[ai][bj][m][n] = __builtin_amdgcn_mfma_f32_16x16x32_bf16(Bt[n][k], At[m][k], acc[ai][bj][m][n], 0, 0, 0); __builtin_amdgcn_s_setprio(0); } while (0)
; #define PG8_WAIT_L(n) asm volatile("s_waitcnt lgkmcnt(" #n ")" ::: "memory")
; template <class Epi, class Sched>
; __device__ __forceinline__ void gemm_phase(LAS unsigned char* lds, const Gemm g, const Sched& S, const Epi& E) {
;     ...
;         const bool has_next = S.next(ui + 1, nxt);
;         const char* nA = has_next ? (const char*)g.A + (size_t)nxt.pm * tstep : cA; const char* nB = has_next ? (const char*)g.Bt + (size_t)nxt.pn * tstep : cB;
;         for (int t = 0; t < nt; t += 2) {
;             const bool last = (t == nt - 2);
;             const char* a1 = cA + (size_t)(t + 1) * kstep;
;             const char* a2 = last ? nA : cA + (size_t)(t + 2) * kstep; const char* b2 = last ? nB : cB + (size_t)(t + 2) * kstep;
;             const char* a3 = a2 + kstep; const char* b3 = b2 + kstep;
;             PG8_LDB(B0, 0, 0); PG8_SCHED; PG8_LDA(At, 0, 0); PG8_STAGE(PG8_SA(1, 1), a1 + hstep, voffA);
;             PG8_WAIT_L(8); PG8_BAR; PG8_WAIT_L(0); PG8_MMA(0, 0, At, B0); PG8_BAR; PG8_SCHED;
;             PG8_LDB(B1, 0, 1); PG8_STAGE(PG8_SB(0, 0), b2, voffB);
;             PG8_BAR; PG8_WAIT_L(0); PG8_MMA(0, 1, At, B1); PG8_BAR;
;             PG8_LDA(At, 0, 1); PG8_STAGE(PG8_SA(0, 0), a2, voffA);
;             PG8_BAR; PG8_WAIT_L(0); PG8_MMA(1, 0, At, B0); PG8_BAR; PG8_SCHED;
.LBB0_632:
	s_ashr_i32 s23, s22, 31
	v_cmp_lt_i64_e32 vcc, s[24:25], v[140:141]
	s_lshl_b64 s[24:25], s[22:23], 19
	s_add_u32 s24, s38, s24
	s_addc_u32 s25, s39, s25
	s_and_b64 s[26:27], vcc, exec
	s_cselect_b32 s23, s25, s31
	s_cselect_b32 s61, s24, s30
	s_ashr_i32 s21, s20, 31
	s_lshl_b64 s[26:27], s[20:21], 19
	s_add_u32 s26, s96, s26
	s_addc_u32 s27, s97, s27
	s_and_b64 s[36:37], vcc, exec
	s_cselect_b32 s21, s27, s35
	s_cselect_b32 s62, s26, s34
	s_add_u32 s30, s30, 0x40080
	s_addc_u32 s31, s31, 0
	s_add_u32 s63, s34, 0x100
	s_addc_u32 s64, s35, 0
	s_mov_b32 s65, -2
	s_waitcnt lgkmcnt(0)
	ds_read_b128 v[150:153], v147
	ds_read_b128 v[154:157], v147 offset:1024
	ds_read_b128 v[158:161], v147 offset:2048
	ds_read_b128 v[162:165], v147 offset:3072
	s_add_u32 s34, s30, 0xfffc0080
	s_addc_u32 s35, s31, -1
	s_cmp_eq_u32 s65, 12
	s_cselect_b32 s37, s23, s35
	s_cselect_b32 s36, s61, s34
	s_cselect_b32 s35, s21, s64
	s_cselect_b32 s34, s62, s63
	s_add_i32 m0, s29, 0xc000
	ds_read_b128 v[166:169], v148
	ds_read_b128 v[170:173], v148 offset:1024
	ds_read_b128 v[174:177], v148 offset:2048
	ds_read_b128 v[178:181], v148 offset:3072
	ds_read_b128 v[182:185], v148 offset:4096
	ds_read_b128 v[186:189], v148 offset:5120
	ds_read_b128 v[190:193], v148 offset:6144
	ds_read_b128 v[194:197], v148 offset:7168
	global_load_lds_dwordx4 v136, s[30:31]
	s_add_i32 m0, s29, 0xe000
	s_nop 0
	global_load_lds_dwordx4 v138, s[30:31]
	s_waitcnt lgkmcnt(8)
	s_waitcnt vmcnt(8)
	s_setprio 1
	s_barrier
	s_waitcnt lgkmcnt(0)
	v_mfma_f32_16x16x32_bf16 v[124:127], v[150:153], v[166:169], 0
	v_mfma_f32_16x16x32_bf16 v[120:123], v[158:161], v[166:169], 0
	v_mfma_f32_16x16x32_bf16 v[116:119], v[150:153], v[174:177], 0
	v_mfma_f32_16x16x32_bf16 v[108:111], v[158:161], v[174:177], 0
	v_mfma_f32_16x16x32_bf16 v[100:103], v[150:153], v[182:185], 0
	v_mfma_f32_16x16x32_bf16 v[92:95], v[158:161], v[182:185], 0
	v_mfma_f32_16x16x32_bf16 v[84:87], v[150:153], v[190:193], 0
	v_mfma_f32_16x16x32_bf16 v[76:79], v[158:161], v[190:193], 0
	v_mfma_f32_16x16x32_bf16 v[124:127], v[154:157], v[170:173], v[124:127]
	v_mfma_f32_16x16x32_bf16 v[120:123], v[162:165], v[170:173], v[120:123]
	v_mfma_f32_16x16x32_bf16 v[116:119], v[154:157], v[178:181], v[116:119]
	v_mfma_f32_16x16x32_bf16 v[108:111], v[162:165], v[178:181], v[108:111]
	v_mfma_f32_16x16x32_bf16 v[100:103], v[154:157], v[186:189], v[100:103]
	v_mfma_f32_16x16x32_bf16 v[92:95], v[162:165], v[186:189], v[92:95]
	v_mfma_f32_16x16x32_bf16 v[84:87], v[154:157], v[194:197], v[84:87]
	v_mfma_f32_16x16x32_bf16 v[76:79], v[162:165], v[194:197], v[76:79]
	s_barrier
	s_setprio 0
	s_add_i32 s66, s54, s43
	s_mov_b32 m0, s66
	ds_read_b128 v[202:205], v149
	ds_read_b128 v[206:209], v149 offset:1024
	ds_read_b128 v[210:213], v149 offset:2048
	ds_read_b128 v[214:217], v149 offset:3072
	global_load_lds_dwordx4 v130, s[34:35]
	s_add_i32 m0, s66, 0x2000
	s_nop 0
	global_load_lds_dwordx4 v134, s[34:35]
	s_waitcnt vmcnt(8)
	s_setprio 1
	s_barrier
	s_waitcnt lgkmcnt(0)
	v_mfma_f32_16x16x32_bf16 v[112:115], v[202:205], v[166:169], 0
	v_mfma_f32_16x16x32_bf16 v[104:107], v[210:213], v[166:169], 0
	v_mfma_f32_16x16x32_bf16 v[96:99], v[202:205], v[174:177], 0
	v_mfma_f32_16x16x32_bf16 v[88:91], v[210:213], v[174:177], 0
	v_mfma_f32_16x16x32_bf16 v[80:83], v[202:205], v[182:185], 0
	v_mfma_f32_16x16x32_bf16 v[72:75], v[210:213], v[182:185], 0
	v_mfma_f32_16x16x32_bf16 v[68:71], v[202:205], v[190:193], 0
	v_mfma_f32_16x16x32_bf16 v[64:67], v[210:213], v[190:193], 0
	v_mfma_f32_16x16x32_bf16 v[112:115], v[206:209], v[170:173], v[112:115]
	v_mfma_f32_16x16x32_bf16 v[104:107], v[214:217], v[170:173], v[104:107]
	v_mfma_f32_16x16x32_bf16 v[96:99], v[206:209], v[178:181], v[96:99]
	v_mfma_f32_16x16x32_bf16 v[88:91], v[214:217], v[178:181], v[88:91]
	v_mfma_f32_16x16x32_bf16 v[80:83], v[206:209], v[186:189], v[80:83]
	v_mfma_f32_16x16x32_bf16 v[72:75], v[214:217], v[186:189], v[72:75]
	v_mfma_f32_16x16x32_bf16 v[68:71], v[206:209], v[194:197], v[68:71]
	v_mfma_f32_16x16x32_bf16 v[64:67], v[214:217], v[194:197], v[64:67]
	s_mov_b32 m0, s29
	v_lshl_add_u64 v[220:221], s[36:37], 0, v[128:129]
	s_barrier
	s_setprio 0
	ds_read_b128 v[166:169], v148 offset:16384
	ds_read_b128 v[170:173], v148 offset:17408
	ds_read_b128 v[174:177], v148 offset:18432
	ds_read_b128 v[178:181], v148 offset:19456
	ds_read_b128 v[182:185], v148 offset:20480
	ds_read_b128 v[186:189], v148 offset:21504
	ds_read_b128 v[190:193], v148 offset:22528
	ds_read_b128 v[194:197], v148 offset:23552
	global_load_lds_dwordx4 v128, s[36:37]
	v_lshl_add_u64 v[222:223], s[36:37], 0, v[132:133]
	s_mov_b32 m0, s44
	s_nop 0
	global_load_lds_dwordx4 v132, s[36:37]
	s_setprio 1
	s_barrier
	s_waitcnt lgkmcnt(0)
	v_mfma_f32_16x16x32_bf16 v[60:63], v[150:153], v[166:169], 0
	v_mfma_f32_16x16x32_bf16 v[56:59], v[158:161], v[166:169], 0
	v_mfma_f32_16x16x32_bf16 v[52:55], v[150:153], v[174:177], 0
	v_mfma_f32_16x16x32_bf16 v[44:47], v[158:161], v[174:177], 0
	v_mfma_f32_16x16x32_bf16 v[36:39], v[150:153], v[182:185], 0
	v_mfma_f32_16x16x32_bf16 v[28:31], v[158:161], v[182:185], 0
	v_mfma_f32_16x16x32_bf16 v[20:23], v[150:153], v[190:193], 0
	v_mfma_f32_16x16x32_bf16 v[12:15], v[158:161], v[190:193], 0
	v_mfma_f32_16x16x32_bf16 v[60:63], v[154:157], v[170:173], v[60:63]
	v_mfma_f32_16x16x32_bf16 v[56:59], v[162:165], v[170:173], v[56:59]
	v_mfma_f32_16x16x32_bf16 v[52:55], v[154:157], v[178:181], v[52:55]
	v_mfma_f32_16x16x32_bf16 v[44:47], v[162:165], v[178:181], v[44:47]
	v_mfma_f32_16x16x32_bf16 v[36:39], v[154:157], v[186:189], v[36:39]
	v_mfma_f32_16x16x32_bf16 v[28:31], v[162:165], v[186:189], v[28:31]
	v_mfma_f32_16x16x32_bf16 v[20:23], v[154:157], v[194:197], v[20:23]
	v_mfma_f32_16x16x32_bf16 v[12:15], v[162:165], v[194:197], v[12:15]
	s_barrier
; #define PG8_STAGE(bufoff, gbase, voff) do { _Pragma("unroll") for (int _i = 0; _i < 2; ++_i) \
;         __builtin_amdgcn_global_load_lds((const unsigned*)((const char*)(gbase) + (voff)[_i]), (LAS unsigned*)(lds + (bufoff) + ldsw + _i * 8192), 16, 0, 0); } while (0)
; #define PG8_LDA(dst, b, h) do { _Pragma("unroll") for (int m = 0; m < 4; ++m) _Pragma("unroll") for (int k = 0; k < 2; ++k) dst[m][k] = *(const LAS bf16x8*)(lds + PG8_SA(b, h) + aoff + m * 2048 + k * 1024); } while (0)
; #define PG8_LDB(dst, b, h) do { _Pragma("unroll") for (int n = 0; n < 2; ++n) _Pragma("unroll") for (int k = 0; k < 2; ++k) dst[n][k] = *(const LAS bf16x8*)(lds + PG8_SB(b, h) + boff + n * 2048 + k * 1024); } while (0)
; #define PG8_MMA(ai, bj, At, Bt) do { __builtin_amdgcn_s_setprio(1); _Pragma("unroll") for (int m = 0; m < 4; ++m) _Pragma("unroll") for (int n = 0; n < 2; ++n) _Pragma("unroll") for (int k = 0; k < 2; ++k) \
;         acc[ai][bj][m][n] = __builtin_amdgcn_mfma_f32_16x16x32_bf16(Bt[n][k], At[m][k], acc[ai][bj][m][n], 0, 0, 0); __builtin_amdgcn_s_setprio(0); } while (0)
; #define PG8_WAIT_V(n) asm volatile("s_waitcnt vmcnt(" #n ")" ::: "memory")
; #define PG8_WAIT_L(n) asm volatile("s_waitcnt lgkmcnt(" #n ")" ::: "memory")
; #define PG8_BAR __builtin_amdgcn_s_barrier()
; #define PG8_SCHED __builtin_amdgcn_sched_barrier(0)
; template <class Epi, class Sched>
; __device__ __forceinline__ void gemm_phase(LAS unsigned char* lds, const Gemm g, const Sched& S, const Epi& E) {
;     ...
;             PG8_STAGE(PG8_SB(0, 1), b2 + hstep, voffB);
;             PG8_WAIT_V(6); PG8_BAR; PG8_MMA(1, 1, At, B1); PG8_BAR;
;             PG8_LDB(B0, 1, 0); PG8_SCHED; PG8_LDA(At, 1, 0); PG8_STAGE(PG8_SA(0, 1), a2 + hstep, voffA);
;             PG8_WAIT_L(8); PG8_BAR; PG8_WAIT_L(0); PG8_MMA(0, 0, At, B0); PG8_BAR; PG8_SCHED;
;             PG8_LDB(B1, 1, 1); PG8_STAGE(PG8_SB(1, 0), b3, voffB);
;             PG8_BAR; PG8_WAIT_L(0); PG8_MMA(0, 1, At, B1); PG8_BAR;
;             PG8_LDA(At, 1, 1); PG8_STAGE(PG8_SA(1, 0), a3, voffA);
;             PG8_BAR; PG8_WAIT_L(0); PG8_MMA(1, 0, At, B0); PG8_BAR; PG8_SCHED;
	s_setprio 0
	s_add_u32 s66, s34, 0x40000
	s_addc_u32 s67, s35, 0
	s_add_i32 s68, s55, s43
	s_mov_b32 m0, s68
	s_nop 0
	global_load_lds_dwordx4 v130, s[66:67]
	s_add_i32 m0, s68, 0x2000
	s_nop 0
	global_load_lds_dwordx4 v134, s[66:67]
	s_add_u32 s36, s36, 0x40000
	s_addc_u32 s37, s37, 0
	s_mov_b32 m0, s45
	s_nop 0
	global_load_lds_dwordx4 v128, s[36:37]
	s_mov_b32 m0, s46
	s_nop 0
	global_load_lds_dwordx4 v132, s[36:37]
	s_waitcnt vmcnt(10)
	s_setprio 1
	s_barrier
	v_mfma_f32_16x16x32_bf16 v[48:51], v[202:205], v[166:169], 0
	v_mfma_f32_16x16x32_bf16 v[40:43], v[210:213], v[166:169], 0
	v_mfma_f32_16x16x32_bf16 v[32:35], v[202:205], v[174:177], 0
	v_mfma_f32_16x16x32_bf16 v[24:27], v[210:213], v[174:177], 0
	v_mfma_f32_16x16x32_bf16 v[16:19], v[202:205], v[182:185], 0
	v_mfma_f32_16x16x32_bf16 v[8:11], v[210:213], v[182:185], 0
	v_mfma_f32_16x16x32_bf16 v[4:7], v[202:205], v[190:193], 0
	v_mfma_f32_16x16x32_bf16 v[0:3], v[210:213], v[190:193], 0
	v_mfma_f32_16x16x32_bf16 v[48:51], v[206:209], v[170:173], v[48:51]
	v_mfma_f32_16x16x32_bf16 v[40:43], v[214:217], v[170:173], v[40:43]
	v_mfma_f32_16x16x32_bf16 v[32:35], v[206:209], v[178:181], v[32:35]
	v_mfma_f32_16x16x32_bf16 v[24:27], v[214:217], v[178:181], v[24:27]
	v_mfma_f32_16x16x32_bf16 v[16:19], v[206:209], v[186:189], v[16:19]
	v_mfma_f32_16x16x32_bf16 v[8:11], v[214:217], v[186:189], v[8:11]
	v_mfma_f32_16x16x32_bf16 v[4:7], v[206:209], v[194:197], v[4:7]
	v_mfma_f32_16x16x32_bf16 v[0:3], v[214:217], v[194:197], v[0:3]
	s_add_i32 s66, 0, 0x18000
	v_add_u32_e32 v162, s66, v146
	s_barrier
	s_setprio 0
	ds_read_b128 v[150:153], v162
	ds_read_b128 v[154:157], v162 offset:1024
	ds_read_b128 v[158:161], v162 offset:2048
	ds_read_b128 v[162:165], v162 offset:3072
	ds_read_b128 v[166:169], v148 offset:32768
	ds_read_b128 v[170:173], v148 offset:33792
	ds_read_b128 v[174:177], v148 offset:34816
	ds_read_b128 v[178:181], v148 offset:35840
	ds_read_b128 v[182:185], v148 offset:36864
	ds_read_b128 v[186:189], v148 offset:37888
	ds_read_b128 v[190:193], v148 offset:38912
	ds_read_b128 v[194:197], v148 offset:39936
	s_waitcnt lgkmcnt(8)
	s_waitcnt vmcnt(8)
	s_setprio 1
	s_barrier
	s_waitcnt lgkmcnt(0)
	v_mfma_f32_16x16x32_bf16 v[124:127], v[150:153], v[166:169], v[124:127]
	v_mfma_f32_16x16x32_bf16 v[120:123], v[158:161], v[166:169], v[120:123]
	v_mfma_f32_16x16x32_bf16 v[116:119], v[150:153], v[174:177], v[116:119]
	v_mfma_f32_16x16x32_bf16 v[108:111], v[158:161], v[174:177], v[108:111]
	v_mfma_f32_16x16x32_bf16 v[100:103], v[150:153], v[182:185], v[100:103]
	v_mfma_f32_16x16x32_bf16 v[92:95], v[158:161], v[182:185], v[92:95]
	v_mfma_f32_16x16x32_bf16 v[84:87], v[150:153], v[190:193], v[84:87]
	v_mfma_f32_16x16x32_bf16 v[76:79], v[158:161], v[190:193], v[76:79]
	v_mfma_f32_16x16x32_bf16 v[124:127], v[154:157], v[170:173], v[124:127]
	v_mfma_f32_16x16x32_bf16 v[120:123], v[162:165], v[170:173], v[120:123]
	v_mfma_f32_16x16x32_bf16 v[116:119], v[154:157], v[178:181], v[116:119]
	v_mfma_f32_16x16x32_bf16 v[108:111], v[162:165], v[178:181], v[108:111]
	v_mfma_f32_16x16x32_bf16 v[100:103], v[154:157], v[186:189], v[100:103]
	v_mfma_f32_16x16x32_bf16 v[92:95], v[162:165], v[186:189], v[92:95]
	v_mfma_f32_16x16x32_bf16 v[84:87], v[154:157], v[194:197], v[84:87]
	v_mfma_f32_16x16x32_bf16 v[76:79], v[162:165], v[194:197], v[76:79]
	s_barrier
	s_setprio 0
	s_add_i32 s36, 0, 0x1c000
	s_add_i32 s37, s66, s43
	v_add_u32_e32 v214, s36, v146
	s_add_u32 s4, s34, 0x80
	s_addc_u32 s5, s35, 0
	s_mov_b32 m0, s37
	ds_read_b128 v[202:205], v214
	ds_read_b128 v[206:209], v214 offset:1024
	ds_read_b128 v[210:213], v214 offset:2048
	ds_read_b128 v[214:217], v214 offset:3072
	global_load_lds_dwordx4 v130, s[4:5]
	s_add_i32 m0, s37, 0x2000
	s_nop 0
	global_load_lds_dwordx4 v134, s[4:5]
	s_waitcnt vmcnt(8)
	s_setprio 1
	s_barrier
	s_waitcnt lgkmcnt(0)
	v_mfma_f32_16x16x32_bf16 v[112:115], v[202:205], v[166:169], v[112:115]
	v_mfma_f32_16x16x32_bf16 v[104:107], v[210:213], v[166:169], v[104:107]
	v_mfma_f32_16x16x32_bf16 v[96:99], v[202:205], v[174:177], v[96:99]
	v_mfma_f32_16x16x32_bf16 v[88:91], v[210:213], v[174:177], v[88:91]
	v_mfma_f32_16x16x32_bf16 v[80:83], v[202:205], v[182:185], v[80:83]
	v_mfma_f32_16x16x32_bf16 v[72:75], v[210:213], v[182:185], v[72:75]
	v_mfma_f32_16x16x32_bf16 v[68:71], v[202:205], v[190:193], v[68:71]
	v_mfma_f32_16x16x32_bf16 v[64:67], v[210:213], v[190:193], v[64:67]
	v_mfma_f32_16x16x32_bf16 v[112:115], v[206:209], v[170:173], v[112:115]
	v_mfma_f32_16x16x32_bf16 v[104:107], v[214:217], v[170:173], v[104:107]
	v_mfma_f32_16x16x32_bf16 v[96:99], v[206:209], v[178:181], v[96:99]
	v_mfma_f32_16x16x32_bf16 v[88:91], v[214:217], v[178:181], v[88:91]
	v_mfma_f32_16x16x32_bf16 v[80:83], v[206:209], v[186:189], v[80:83]
	v_mfma_f32_16x16x32_bf16 v[72:75], v[214:217], v[186:189], v[72:75]
	v_mfma_f32_16x16x32_bf16 v[68:71], v[206:209], v[194:197], v[68:71]
	v_mfma_f32_16x16x32_bf16 v[64:67], v[214:217], v[194:197], v[64:67]
	s_mov_b32 m0, s51
	s_mov_b64 s[4:5], 0x80
	v_lshl_add_u64 v[198:199], v[220:221], 0, s[4:5]
	s_barrier
	s_setprio 0
	ds_read_b128 v[166:169], v148 offset:49152
	ds_read_b128 v[170:173], v148 offset:50176
	ds_read_b128 v[174:177], v148 offset:51200
	ds_read_b128 v[178:181], v148 offset:52224
	ds_read_b128 v[182:185], v148 offset:53248
	ds_read_b128 v[186:189], v148 offset:54272
	ds_read_b128 v[190:193], v148 offset:55296
	ds_read_b128 v[194:197], v148 offset:56320
	global_load_lds_dwordx4 v[198:199], off
	v_lshl_add_u64 v[198:199], v[222:223], 0, s[4:5]
	s_mov_b32 m0, s52
	s_nop 0
	global_load_lds_dwordx4 v[198:199], off
	s_setprio 1
	s_barrier
; #define PG8_STAGE(bufoff, gbase, voff) do { _Pragma("unroll") for (int _i = 0; _i < 2; ++_i) \
;         __builtin_amdgcn_global_load_lds((const unsigned*)((const char*)(gbase) + (voff)[_i]), (LAS unsigned*)(lds + (bufoff) + ldsw + _i * 8192), 16, 0, 0); } while (0)
; #define PG8_LDA(dst, b, h) do { _Pragma("unroll") for (int m = 0; m < 4; ++m) _Pragma("unroll") for (int k = 0; k < 2; ++k) dst[m][k] = *(const LAS bf16x8*)(lds + PG8_SA(b, h) + aoff + m * 2048 + k * 1024); } while (0)
; #define PG8_LDB(dst, b, h) do { _Pragma("unroll") for (int n = 0; n < 2; ++n) _Pragma("unroll") for (int k = 0; k < 2; ++k) dst[n][k] = *(const LAS bf16x8*)(lds + PG8_SB(b, h) + boff + n * 2048 + k * 1024); } while (0)
; #define PG8_WAIT_V(n) asm volatile("s_waitcnt vmcnt(" #n ")" ::: "memory")
; #define PG8_WAIT_L(n) asm volatile("s_waitcnt lgkmcnt(" #n ")" ::: "memory")
; #define PG8_BAR __builtin_amdgcn_s_barrier()
; #define PG8_SCHED __builtin_amdgcn_sched_barrier(0)
; template <class Epi, class Sched>
; __device__ __forceinline__ void gemm_phase(LAS unsigned char* lds, const Gemm g, const Sched& S, const Epi& E) {
;     ...
;             PG8_LDB(B0, 0, 0); PG8_SCHED; PG8_LDA(At, 0, 0); PG8_STAGE(PG8_SA(1, 1), a1 + hstep, voffA);
;             PG8_WAIT_L(8); PG8_BAR; PG8_WAIT_L(0); PG8_MMA(0, 0, At, B0); PG8_BAR; PG8_SCHED;
;             PG8_LDB(B1, 0, 1); PG8_STAGE(PG8_SB(0, 0), b2, voffB);
;             PG8_BAR; PG8_WAIT_L(0); PG8_MMA(0, 1, At, B1); PG8_BAR;
;             PG8_LDA(At, 0, 1); PG8_STAGE(PG8_SA(0, 0), a2, voffA);
;             PG8_BAR; PG8_WAIT_L(0); PG8_MMA(1, 0, At, B0); PG8_BAR; PG8_SCHED;
;             PG8_STAGE(PG8_SB(0, 1), b2 + hstep, voffB);
;             PG8_WAIT_V(6); PG8_BAR; PG8_MMA(1, 1, At, B1); PG8_BAR;
;             PG8_LDB(B0, 1, 0); PG8_SCHED; PG8_LDA(At, 1, 0); PG8_STAGE(PG8_SA(0, 1), a2 + hstep, voffA);
;             PG8_WAIT_L(8); PG8_BAR; PG8_WAIT_L(0); PG8_MMA(0, 0, At, B0); PG8_BAR; PG8_SCHED;
;             PG8_LDB(B1, 1, 1); PG8_STAGE(PG8_SB(1, 0), b3, voffB);
;             PG8_BAR; PG8_WAIT_L(0); PG8_MMA(0, 1, At, B1); PG8_BAR;
;             PG8_LDA(At, 1, 1); PG8_STAGE(PG8_SA(1, 0), a3, voffA);
;             PG8_BAR; PG8_WAIT_L(0); PG8_MMA(1, 0, At, B0); PG8_BAR; PG8_SCHED;
;             PG8_STAGE(PG8_SB(1, 1), b3 + hstep, voffB);
;             PG8_WAIT_V(6); PG8_BAR; PG8_MMA(1, 1, At, B1); PG8_BAR;
	s_waitcnt lgkmcnt(0)
	v_mfma_f32_16x16x32_bf16 v[60:63], v[150:153], v[166:169], v[60:63]
	v_mfma_f32_16x16x32_bf16 v[56:59], v[158:161], v[166:169], v[56:59]
	v_mfma_f32_16x16x32_bf16 v[52:55], v[150:153], v[174:177], v[52:55]
	v_mfma_f32_16x16x32_bf16 v[44:47], v[158:161], v[174:177], v[44:47]
	v_mfma_f32_16x16x32_bf16 v[36:39], v[150:153], v[182:185], v[36:39]
	v_mfma_f32_16x16x32_bf16 v[28:31], v[158:161], v[182:185], v[28:31]
	v_mfma_f32_16x16x32_bf16 v[20:23], v[150:153], v[190:193], v[20:23]
	v_mfma_f32_16x16x32_bf16 v[12:15], v[158:161], v[190:193], v[12:15]
	v_mfma_f32_16x16x32_bf16 v[60:63], v[154:157], v[170:173], v[60:63]
	v_mfma_f32_16x16x32_bf16 v[56:59], v[162:165], v[170:173], v[56:59]
	v_mfma_f32_16x16x32_bf16 v[52:55], v[154:157], v[178:181], v[52:55]
	v_mfma_f32_16x16x32_bf16 v[44:47], v[162:165], v[178:181], v[44:47]
	v_mfma_f32_16x16x32_bf16 v[36:39], v[154:157], v[186:189], v[36:39]
	v_mfma_f32_16x16x32_bf16 v[28:31], v[162:165], v[186:189], v[28:31]
	v_mfma_f32_16x16x32_bf16 v[20:23], v[154:157], v[194:197], v[20:23]
	v_mfma_f32_16x16x32_bf16 v[12:15], v[162:165], v[194:197], v[12:15]
	s_barrier
	s_setprio 0
	s_add_u32 s34, s34, 0x40080
	s_addc_u32 s35, s35, 0
	s_add_i32 s36, s36, s43
	s_mov_b32 m0, s36
	s_nop 0
	global_load_lds_dwordx4 v130, s[34:35]
	s_add_i32 m0, s36, 0x2000
	s_nop 0
	global_load_lds_dwordx4 v134, s[34:35]
	s_waitcnt vmcnt(8)
	s_setprio 1
	s_barrier
	v_mfma_f32_16x16x32_bf16 v[48:51], v[202:205], v[166:169], v[48:51]
	v_mfma_f32_16x16x32_bf16 v[40:43], v[210:213], v[166:169], v[40:43]
	v_mfma_f32_16x16x32_bf16 v[32:35], v[202:205], v[174:177], v[32:35]
	v_mfma_f32_16x16x32_bf16 v[24:27], v[210:213], v[174:177], v[24:27]
	v_mfma_f32_16x16x32_bf16 v[16:19], v[202:205], v[182:185], v[16:19]
	v_mfma_f32_16x16x32_bf16 v[8:11], v[210:213], v[182:185], v[8:11]
	v_mfma_f32_16x16x32_bf16 v[4:7], v[202:205], v[190:193], v[4:7]
	v_mfma_f32_16x16x32_bf16 v[0:3], v[210:213], v[190:193], v[0:3]
	v_mfma_f32_16x16x32_bf16 v[48:51], v[206:209], v[170:173], v[48:51]
	v_mfma_f32_16x16x32_bf16 v[40:43], v[214:217], v[170:173], v[40:43]
	v_mfma_f32_16x16x32_bf16 v[32:35], v[206:209], v[178:181], v[32:35]
	v_mfma_f32_16x16x32_bf16 v[24:27], v[214:217], v[178:181], v[24:27]
	v_mfma_f32_16x16x32_bf16 v[16:19], v[206:209], v[186:189], v[16:19]
	v_mfma_f32_16x16x32_bf16 v[8:11], v[214:217], v[186:189], v[8:11]
	v_mfma_f32_16x16x32_bf16 v[4:7], v[206:209], v[194:197], v[4:7]
	v_mfma_f32_16x16x32_bf16 v[0:3], v[214:217], v[194:197], v[0:3]
	s_add_i32 s65, s65, 2
	s_add_u32 s30, s30, 0x100
	s_addc_u32 s31, s31, 0
	s_add_u32 s63, s63, 0x100
	s_addc_u32 s64, s64, 0
	s_cmp_gt_u32 s65, 13
	s_barrier
	s_setprio 0
.LBB0_633:
	ds_read_b128 v[150:153], v147
	ds_read_b128 v[154:157], v147 offset:1024
	ds_read_b128 v[158:161], v147 offset:2048
	ds_read_b128 v[162:165], v147 offset:3072
	s_add_u32 s34, s30, 0xfffc0080
	s_addc_u32 s35, s31, -1
	s_cmp_eq_u32 s65, 12
	s_cselect_b32 s37, s23, s35
	s_cselect_b32 s36, s61, s34
	s_cselect_b32 s35, s21, s64
	s_cselect_b32 s34, s62, s63
	s_add_i32 m0, s29, 0xc000
	ds_read_b128 v[166:169], v148
	ds_read_b128 v[170:173], v148 offset:1024
	ds_read_b128 v[174:177], v148 offset:2048
	ds_read_b128 v[178:181], v148 offset:3072
	ds_read_b128 v[182:185], v148 offset:4096
	ds_read_b128 v[186:189], v148 offset:5120
	ds_read_b128 v[190:193], v148 offset:6144
	ds_read_b128 v[194:197], v148 offset:7168
	global_load_lds_dwordx4 v136, s[30:31]
	s_add_i32 m0, s29, 0xe000
	s_nop 0
	global_load_lds_dwordx4 v138, s[30:31]
	s_waitcnt lgkmcnt(8)
	s_waitcnt vmcnt(8)
	s_setprio 1
	s_barrier
	s_waitcnt lgkmcnt(0)
	v_mfma_f32_16x16x32_bf16 v[124:127], v[150:153], v[166:169], v[124:127]
	v_mfma_f32_16x16x32_bf16 v[120:123], v[158:161], v[166:169], v[120:123]
	v_mfma_f32_16x16x32_bf16 v[116:119], v[150:153], v[174:177], v[116:119]
	v_mfma_f32_16x16x32_bf16 v[108:111], v[158:161], v[174:177], v[108:111]
	v_mfma_f32_16x16x32_bf16 v[100:103], v[150:153], v[182:185], v[100:103]
	v_mfma_f32_16x16x32_bf16 v[92:95], v[158:161], v[182:185], v[92:95]
	v_mfma_f32_16x16x32_bf16 v[84:87], v[150:153], v[190:193], v[84:87]
	v_mfma_f32_16x16x32_bf16 v[76:79], v[158:161], v[190:193], v[76:79]
	v_mfma_f32_16x16x32_bf16 v[124:127], v[154:157], v[170:173], v[124:127]
	v_mfma_f32_16x16x32_bf16 v[120:123], v[162:165], v[170:173], v[120:123]
	v_mfma_f32_16x16x32_bf16 v[116:119], v[154:157], v[178:181], v[116:119]
	v_mfma_f32_16x16x32_bf16 v[108:111], v[162:165], v[178:181], v[108:111]
	v_mfma_f32_16x16x32_bf16 v[100:103], v[154:157], v[186:189], v[100:103]
	v_mfma_f32_16x16x32_bf16 v[92:95], v[162:165], v[186:189], v[92:95]
	v_mfma_f32_16x16x32_bf16 v[84:87], v[154:157], v[194:197], v[84:87]
	v_mfma_f32_16x16x32_bf16 v[76:79], v[162:165], v[194:197], v[76:79]
	s_barrier
	s_setprio 0
	s_add_i32 s66, s54, s43
	s_mov_b32 m0, s66
	ds_read_b128 v[202:205], v149
	ds_read_b128 v[206:209], v149 offset:1024
	ds_read_b128 v[210:213], v149 offset:2048
	ds_read_b128 v[214:217], v149 offset:3072
	global_load_lds_dwordx4 v130, s[34:35]
	s_add_i32 m0, s66, 0x2000
	s_nop 0
	global_load_lds_dwordx4 v134, s[34:35]
	s_waitcnt vmcnt(8)
	s_setprio 1
	s_barrier
; #define PG8_STAGE(bufoff, gbase, voff) do { _Pragma("unroll") for (int _i = 0; _i < 2; ++_i) \
;         __builtin_amdgcn_global_load_lds((const unsigned*)((const char*)(gbase) + (voff)[_i]), (LAS unsigned*)(lds + (bufoff) + ldsw + _i * 8192), 16, 0, 0); } while (0)
; #define PG8_LDA(dst, b, h) do { _Pragma("unroll") for (int m = 0; m < 4; ++m) _Pragma("unroll") for (int k = 0; k < 2; ++k) dst[m][k] = *(const LAS bf16x8*)(lds + PG8_SA(b, h) + aoff + m * 2048 + k * 1024); } while (0)
; #define PG8_LDB(dst, b, h) do { _Pragma("unroll") for (int n = 0; n < 2; ++n) _Pragma("unroll") for (int k = 0; k < 2; ++k) dst[n][k] = *(const LAS bf16x8*)(lds + PG8_SB(b, h) + boff + n * 2048 + k * 1024); } while (0)
; #define PG8_MMA(ai, bj, At, Bt) do { __builtin_amdgcn_s_setprio(1); _Pragma("unroll") for (int m = 0; m < 4; ++m) _Pragma("unroll") for (int n = 0; n < 2; ++n) _Pragma("unroll") for (int k = 0; k < 2; ++k) \
;         acc[ai][bj][m][n] = __builtin_amdgcn_mfma_f32_16x16x32_bf16(Bt[n][k], At[m][k], acc[ai][bj][m][n], 0, 0, 0); __builtin_amdgcn_s_setprio(0); } while (0)
; #define PG8_WAIT_V(n) asm volatile("s_waitcnt vmcnt(" #n ")" ::: "memory")
; #define PG8_WAIT_L(n) asm volatile("s_waitcnt lgkmcnt(" #n ")" ::: "memory")
; #define PG8_BAR __builtin_amdgcn_s_barrier()
; #define PG8_SCHED __builtin_amdgcn_sched_barrier(0)
; template <class Epi, class Sched>
; __device__ __forceinline__ void gemm_phase(LAS unsigned char* lds, const Gemm g, const Sched& S, const Epi& E) {
;     ...
;             PG8_BAR; PG8_WAIT_L(0); PG8_MMA(0, 1, At, B1); PG8_BAR;
;             PG8_LDA(At, 0, 1); PG8_STAGE(PG8_SA(0, 0), a2, voffA);
;             PG8_BAR; PG8_WAIT_L(0); PG8_MMA(1, 0, At, B0); PG8_BAR; PG8_SCHED;
;             PG8_STAGE(PG8_SB(0, 1), b2 + hstep, voffB);
;             PG8_WAIT_V(6); PG8_BAR; PG8_MMA(1, 1, At, B1); PG8_BAR;
;             PG8_LDB(B0, 1, 0); PG8_SCHED; PG8_LDA(At, 1, 0); PG8_STAGE(PG8_SA(0, 1), a2 + hstep, voffA);
	s_waitcnt lgkmcnt(0)
	v_mfma_f32_16x16x32_bf16 v[112:115], v[202:205], v[166:169], v[112:115]
	v_mfma_f32_16x16x32_bf16 v[104:107], v[210:213], v[166:169], v[104:107]
	v_mfma_f32_16x16x32_bf16 v[96:99], v[202:205], v[174:177], v[96:99]
	v_mfma_f32_16x16x32_bf16 v[88:91], v[210:213], v[174:177], v[88:91]
	v_mfma_f32_16x16x32_bf16 v[80:83], v[202:205], v[182:185], v[80:83]
	v_mfma_f32_16x16x32_bf16 v[72:75], v[210:213], v[182:185], v[72:75]
	v_mfma_f32_16x16x32_bf16 v[68:71], v[202:205], v[190:193], v[68:71]
	v_mfma_f32_16x16x32_bf16 v[64:67], v[210:213], v[190:193], v[64:67]
	v_mfma_f32_16x16x32_bf16 v[112:115], v[206:209], v[170:173], v[112:115]
	v_mfma_f32_16x16x32_bf16 v[104:107], v[214:217], v[170:173], v[104:107]
	v_mfma_f32_16x16x32_bf16 v[96:99], v[206:209], v[178:181], v[96:99]
	v_mfma_f32_16x16x32_bf16 v[88:91], v[214:217], v[178:181], v[88:91]
	v_mfma_f32_16x16x32_bf16 v[80:83], v[206:209], v[186:189], v[80:83]
	v_mfma_f32_16x16x32_bf16 v[72:75], v[214:217], v[186:189], v[72:75]
	v_mfma_f32_16x16x32_bf16 v[68:71], v[206:209], v[194:197], v[68:71]
	v_mfma_f32_16x16x32_bf16 v[64:67], v[214:217], v[194:197], v[64:67]
	s_mov_b32 m0, s29
	v_lshl_add_u64 v[220:221], s[36:37], 0, v[128:129]
	s_barrier
	s_setprio 0
	ds_read_b128 v[166:169], v148 offset:16384
	ds_read_b128 v[170:173], v148 offset:17408
	ds_read_b128 v[174:177], v148 offset:18432
	ds_read_b128 v[178:181], v148 offset:19456
	ds_read_b128 v[182:185], v148 offset:20480
	ds_read_b128 v[186:189], v148 offset:21504
	ds_read_b128 v[190:193], v148 offset:22528
	ds_read_b128 v[194:197], v148 offset:23552
	global_load_lds_dwordx4 v128, s[36:37]
	v_lshl_add_u64 v[222:223], s[36:37], 0, v[132:133]
	s_mov_b32 m0, s44
	s_nop 0
	global_load_lds_dwordx4 v132, s[36:37]
	s_setprio 1
	s_barrier
	s_waitcnt lgkmcnt(0)
	v_mfma_f32_16x16x32_bf16 v[60:63], v[150:153], v[166:169], v[60:63]
	v_mfma_f32_16x16x32_bf16 v[56:59], v[158:161], v[166:169], v[56:59]
	v_mfma_f32_16x16x32_bf16 v[52:55], v[150:153], v[174:177], v[52:55]
	v_mfma_f32_16x16x32_bf16 v[44:47], v[158:161], v[174:177], v[44:47]
	v_mfma_f32_16x16x32_bf16 v[36:39], v[150:153], v[182:185], v[36:39]
	v_mfma_f32_16x16x32_bf16 v[28:31], v[158:161], v[182:185], v[28:31]
	v_mfma_f32_16x16x32_bf16 v[20:23], v[150:153], v[190:193], v[20:23]
	v_mfma_f32_16x16x32_bf16 v[12:15], v[158:161], v[190:193], v[12:15]
	v_mfma_f32_16x16x32_bf16 v[60:63], v[154:157], v[170:173], v[60:63]
	v_mfma_f32_16x16x32_bf16 v[56:59], v[162:165], v[170:173], v[56:59]
	v_mfma_f32_16x16x32_bf16 v[52:55], v[154:157], v[178:181], v[52:55]
	v_mfma_f32_16x16x32_bf16 v[44:47], v[162:165], v[178:181], v[44:47]
	v_mfma_f32_16x16x32_bf16 v[36:39], v[154:157], v[186:189], v[36:39]
	v_mfma_f32_16x16x32_bf16 v[28:31], v[162:165], v[186:189], v[28:31]
	v_mfma_f32_16x16x32_bf16 v[20:23], v[154:157], v[194:197], v[20:23]
	v_mfma_f32_16x16x32_bf16 v[12:15], v[162:165], v[194:197], v[12:15]
	s_barrier
	s_setprio 0
	s_add_u32 s66, s34, 0x40000
	s_addc_u32 s67, s35, 0
	s_add_i32 s68, s55, s43
	s_mov_b32 m0, s68
	s_nop 0
	global_load_lds_dwordx4 v130, s[66:67]
	s_add_i32 m0, s68, 0x2000
	s_nop 0
	global_load_lds_dwordx4 v134, s[66:67]
	s_add_u32 s36, s36, 0x40000
	s_addc_u32 s37, s37, 0
	s_mov_b32 m0, s45
	s_nop 0
	global_load_lds_dwordx4 v128, s[36:37]
	s_mov_b32 m0, s46
	s_nop 0
	global_load_lds_dwordx4 v132, s[36:37]
	s_waitcnt vmcnt(10)
	s_setprio 1
	s_barrier
	v_mfma_f32_16x16x32_bf16 v[48:51], v[202:205], v[166:169], v[48:51]
	v_mfma_f32_16x16x32_bf16 v[40:43], v[210:213], v[166:169], v[40:43]
	v_mfma_f32_16x16x32_bf16 v[32:35], v[202:205], v[174:177], v[32:35]
	v_mfma_f32_16x16x32_bf16 v[24:27], v[210:213], v[174:177], v[24:27]
	v_mfma_f32_16x16x32_bf16 v[16:19], v[202:205], v[182:185], v[16:19]
	v_mfma_f32_16x16x32_bf16 v[8:11], v[210:213], v[182:185], v[8:11]
	v_mfma_f32_16x16x32_bf16 v[4:7], v[202:205], v[190:193], v[4:7]
	v_mfma_f32_16x16x32_bf16 v[0:3], v[210:213], v[190:193], v[0:3]
	v_mfma_f32_16x16x32_bf16 v[48:51], v[206:209], v[170:173], v[48:51]
	v_mfma_f32_16x16x32_bf16 v[40:43], v[214:217], v[170:173], v[40:43]
	v_mfma_f32_16x16x32_bf16 v[32:35], v[206:209], v[178:181], v[32:35]
	v_mfma_f32_16x16x32_bf16 v[24:27], v[214:217], v[178:181], v[24:27]
	v_mfma_f32_16x16x32_bf16 v[16:19], v[206:209], v[186:189], v[16:19]
	v_mfma_f32_16x16x32_bf16 v[8:11], v[214:217], v[186:189], v[8:11]
	v_mfma_f32_16x16x32_bf16 v[4:7], v[206:209], v[194:197], v[4:7]
	v_mfma_f32_16x16x32_bf16 v[0:3], v[214:217], v[194:197], v[0:3]
	s_add_i32 s66, 0, 0x18000
	v_add_u32_e32 v162, s66, v146
	s_barrier
	s_setprio 0
	ds_read_b128 v[150:153], v162
	ds_read_b128 v[154:157], v162 offset:1024
	ds_read_b128 v[158:161], v162 offset:2048
	ds_read_b128 v[162:165], v162 offset:3072
	ds_read_b128 v[166:169], v148 offset:32768
	ds_read_b128 v[170:173], v148 offset:33792
	ds_read_b128 v[174:177], v148 offset:34816
	ds_read_b128 v[178:181], v148 offset:35840
	ds_read_b128 v[182:185], v148 offset:36864
	ds_read_b128 v[186:189], v148 offset:37888
	ds_read_b128 v[190:193], v148 offset:38912
	ds_read_b128 v[194:197], v148 offset:39936
	s_waitcnt lgkmcnt(8)
	s_waitcnt vmcnt(8)
	s_setprio 1
	s_barrier
; #define PG8_STAGE(bufoff, gbase, voff) do { _Pragma("unroll") for (int _i = 0; _i < 2; ++_i) \
;         __builtin_amdgcn_global_load_lds((const unsigned*)((const char*)(gbase) + (voff)[_i]), (LAS unsigned*)(lds + (bufoff) + ldsw + _i * 8192), 16, 0, 0); } while (0)
; #define PG8_LDA(dst, b, h) do { _Pragma("unroll") for (int m = 0; m < 4; ++m) _Pragma("unroll") for (int k = 0; k < 2; ++k) dst[m][k] = *(const LAS bf16x8*)(lds + PG8_SA(b, h) + aoff + m * 2048 + k * 1024); } while (0)
; #define PG8_LDB(dst, b, h) do { _Pragma("unroll") for (int n = 0; n < 2; ++n) _Pragma("unroll") for (int k = 0; k < 2; ++k) dst[n][k] = *(const LAS bf16x8*)(lds + PG8_SB(b, h) + boff + n * 2048 + k * 1024); } while (0)
; #define PG8_MMA(ai, bj, At, Bt) do { __builtin_amdgcn_s_setprio(1); _Pragma("unroll") for (int m = 0; m < 4; ++m) _Pragma("unroll") for (int n = 0; n < 2; ++n) _Pragma("unroll") for (int k = 0; k < 2; ++k) \
;         acc[ai][bj][m][n] = __builtin_amdgcn_mfma_f32_16x16x32_bf16(Bt[n][k], At[m][k], acc[ai][bj][m][n], 0, 0, 0); __builtin_amdgcn_s_setprio(0); } while (0)
; #define PG8_WAIT_L(n) asm volatile("s_waitcnt lgkmcnt(" #n ")" ::: "memory")
; #define PG8_BAR __builtin_amdgcn_s_barrier()
; #define PG8_SCHED __builtin_amdgcn_sched_barrier(0)
; template <class Epi, class Sched>
; __device__ __forceinline__ void gemm_phase(LAS unsigned char* lds, const Gemm g, const Sched& S, const Epi& E) {
;     ...
;             PG8_WAIT_L(8); PG8_BAR; PG8_WAIT_L(0); PG8_MMA(0, 0, At, B0); PG8_BAR; PG8_SCHED;
;             PG8_LDB(B1, 1, 1); PG8_STAGE(PG8_SB(1, 0), b3, voffB);
;             PG8_BAR; PG8_WAIT_L(0); PG8_MMA(0, 1, At, B1); PG8_BAR;
;             PG8_LDA(At, 1, 1); PG8_STAGE(PG8_SA(1, 0), a3, voffA);
;             PG8_BAR; PG8_WAIT_L(0); PG8_MMA(1, 0, At, B0); PG8_BAR; PG8_SCHED;
;             PG8_STAGE(PG8_SB(1, 1), b3 + hstep, voffB);
	s_waitcnt lgkmcnt(0)
	v_mfma_f32_16x16x32_bf16 v[124:127], v[150:153], v[166:169], v[124:127]
	v_mfma_f32_16x16x32_bf16 v[120:123], v[158:161], v[166:169], v[120:123]
	v_mfma_f32_16x16x32_bf16 v[116:119], v[150:153], v[174:177], v[116:119]
	v_mfma_f32_16x16x32_bf16 v[108:111], v[158:161], v[174:177], v[108:111]
	v_mfma_f32_16x16x32_bf16 v[100:103], v[150:153], v[182:185], v[100:103]
	v_mfma_f32_16x16x32_bf16 v[92:95], v[158:161], v[182:185], v[92:95]
	v_mfma_f32_16x16x32_bf16 v[84:87], v[150:153], v[190:193], v[84:87]
	v_mfma_f32_16x16x32_bf16 v[76:79], v[158:161], v[190:193], v[76:79]
	v_mfma_f32_16x16x32_bf16 v[124:127], v[154:157], v[170:173], v[124:127]
	v_mfma_f32_16x16x32_bf16 v[120:123], v[162:165], v[170:173], v[120:123]
	v_mfma_f32_16x16x32_bf16 v[116:119], v[154:157], v[178:181], v[116:119]
	v_mfma_f32_16x16x32_bf16 v[108:111], v[162:165], v[178:181], v[108:111]
	v_mfma_f32_16x16x32_bf16 v[100:103], v[154:157], v[186:189], v[100:103]
	v_mfma_f32_16x16x32_bf16 v[92:95], v[162:165], v[186:189], v[92:95]
	v_mfma_f32_16x16x32_bf16 v[84:87], v[154:157], v[194:197], v[84:87]
	v_mfma_f32_16x16x32_bf16 v[76:79], v[162:165], v[194:197], v[76:79]
	s_barrier
	s_setprio 0
	s_add_i32 s36, 0, 0x1c000
	s_add_i32 s37, s66, s43
	v_add_u32_e32 v214, s36, v146
	s_add_u32 s4, s34, 0x80
	s_addc_u32 s5, s35, 0
	s_mov_b32 m0, s37
	ds_read_b128 v[202:205], v214
	ds_read_b128 v[206:209], v214 offset:1024
	ds_read_b128 v[210:213], v214 offset:2048
	ds_read_b128 v[214:217], v214 offset:3072
	global_load_lds_dwordx4 v130, s[4:5]
	s_add_i32 m0, s37, 0x2000
	s_nop 0
	global_load_lds_dwordx4 v134, s[4:5]
	s_waitcnt vmcnt(8)
	s_setprio 1
	s_barrier
	s_waitcnt lgkmcnt(0)
	v_mfma_f32_16x16x32_bf16 v[112:115], v[202:205], v[166:169], v[112:115]
	v_mfma_f32_16x16x32_bf16 v[104:107], v[210:213], v[166:169], v[104:107]
	v_mfma_f32_16x16x32_bf16 v[96:99], v[202:205], v[174:177], v[96:99]
	v_mfma_f32_16x16x32_bf16 v[88:91], v[210:213], v[174:177], v[88:91]
	v_mfma_f32_16x16x32_bf16 v[80:83], v[202:205], v[182:185], v[80:83]
	v_mfma_f32_16x16x32_bf16 v[72:75], v[210:213], v[182:185], v[72:75]
	v_mfma_f32_16x16x32_bf16 v[68:71], v[202:205], v[190:193], v[68:71]
	v_mfma_f32_16x16x32_bf16 v[64:67], v[210:213], v[190:193], v[64:67]
	v_mfma_f32_16x16x32_bf16 v[112:115], v[206:209], v[170:173], v[112:115]
	v_mfma_f32_16x16x32_bf16 v[104:107], v[214:217], v[170:173], v[104:107]
	v_mfma_f32_16x16x32_bf16 v[96:99], v[206:209], v[178:181], v[96:99]
	v_mfma_f32_16x16x32_bf16 v[88:91], v[214:217], v[178:181], v[88:91]
	v_mfma_f32_16x16x32_bf16 v[80:83], v[206:209], v[186:189], v[80:83]
	v_mfma_f32_16x16x32_bf16 v[72:75], v[214:217], v[186:189], v[72:75]
	v_mfma_f32_16x16x32_bf16 v[68:71], v[206:209], v[194:197], v[68:71]
	v_mfma_f32_16x16x32_bf16 v[64:67], v[214:217], v[194:197], v[64:67]
	s_mov_b32 m0, s51
	s_mov_b64 s[4:5], 0x80
	v_lshl_add_u64 v[198:199], v[220:221], 0, s[4:5]
	s_barrier
	s_setprio 0
	ds_read_b128 v[166:169], v148 offset:49152
	ds_read_b128 v[170:173], v148 offset:50176
	ds_read_b128 v[174:177], v148 offset:51200
	ds_read_b128 v[178:181], v148 offset:52224
	ds_read_b128 v[182:185], v148 offset:53248
	ds_read_b128 v[186:189], v148 offset:54272
	ds_read_b128 v[190:193], v148 offset:55296
	ds_read_b128 v[194:197], v148 offset:56320
	global_load_lds_dwordx4 v[198:199], off
	v_lshl_add_u64 v[198:199], v[222:223], 0, s[4:5]
	s_mov_b32 m0, s52
	s_nop 0
	global_load_lds_dwordx4 v[198:199], off
	s_setprio 1
	s_barrier
	s_waitcnt lgkmcnt(0)
	v_mfma_f32_16x16x32_bf16 v[60:63], v[150:153], v[166:169], v[60:63]
	v_mfma_f32_16x16x32_bf16 v[56:59], v[158:161], v[166:169], v[56:59]
	v_mfma_f32_16x16x32_bf16 v[52:55], v[150:153], v[174:177], v[52:55]
	v_mfma_f32_16x16x32_bf16 v[44:47], v[158:161], v[174:177], v[44:47]
	v_mfma_f32_16x16x32_bf16 v[36:39], v[150:153], v[182:185], v[36:39]
	v_mfma_f32_16x16x32_bf16 v[28:31], v[158:161], v[182:185], v[28:31]
	v_mfma_f32_16x16x32_bf16 v[20:23], v[150:153], v[190:193], v[20:23]
	v_mfma_f32_16x16x32_bf16 v[12:15], v[158:161], v[190:193], v[12:15]
	v_mfma_f32_16x16x32_bf16 v[60:63], v[154:157], v[170:173], v[60:63]
	v_mfma_f32_16x16x32_bf16 v[56:59], v[162:165], v[170:173], v[56:59]
	v_mfma_f32_16x16x32_bf16 v[52:55], v[154:157], v[178:181], v[52:55]
	v_mfma_f32_16x16x32_bf16 v[44:47], v[162:165], v[178:181], v[44:47]
	v_mfma_f32_16x16x32_bf16 v[36:39], v[154:157], v[186:189], v[36:39]
	v_mfma_f32_16x16x32_bf16 v[28:31], v[162:165], v[186:189], v[28:31]
	v_mfma_f32_16x16x32_bf16 v[20:23], v[154:157], v[194:197], v[20:23]
	v_mfma_f32_16x16x32_bf16 v[12:15], v[162:165], v[194:197], v[12:15]
	s_barrier
	s_setprio 0
	s_add_u32 s34, s34, 0x40080
	s_addc_u32 s35, s35, 0
	s_add_i32 s36, s36, s43
	s_mov_b32 m0, s36
	s_nop 0
	global_load_lds_dwordx4 v130, s[34:35]
	s_add_i32 m0, s36, 0x2000
	s_nop 0
	global_load_lds_dwordx4 v134, s[34:35]
	s_waitcnt vmcnt(8)
	s_setprio 1
	s_barrier
; __device__ __forceinline__ unsigned cvt_pk_bf16(float lo, float hi) { unsigned r; asm volatile("v_cvt_pk_bf16_f32 %0, %1, %2" : "=v"(r) : "v"(lo), "v"(hi)); return r; }
; #define PG8_MMA(ai, bj, At, Bt) do { __builtin_amdgcn_s_setprio(1); _Pragma("unroll") for (int m = 0; m < 4; ++m) _Pragma("unroll") for (int n = 0; n < 2; ++n) _Pragma("unroll") for (int k = 0; k < 2; ++k) \
;         acc[ai][bj][m][n] = __builtin_amdgcn_mfma_f32_16x16x32_bf16(Bt[n][k], At[m][k], acc[ai][bj][m][n], 0, 0, 0); __builtin_amdgcn_s_setprio(0); } while (0)
; #define PG8_WAIT_V(n) asm volatile("s_waitcnt vmcnt(" #n ")" ::: "memory")
; #define PG8_BAR __builtin_amdgcn_s_barrier()
; template <class Epi, class Sched>
; __device__ __forceinline__ void gemm_phase(LAS unsigned char* lds, const Gemm g, const Sched& S, const Epi& E) {
;     ...
;             PG8_WAIT_V(6); PG8_BAR; PG8_MMA(1, 1, At, B1); PG8_BAR;
;         }
;         E(acc, cur, wr, wc, fr, fq);
;         if (!has_next) break;
;     __device__ __forceinline__ void operator()(const AccT& acc, const Unit& u, int wr, int wc, int fr, int fq) const {
;     ...
;         const int rbase = u.pm * 256 + wr * 64 + fr;
;         const int tb = u.pn * 256 + wc * 32 + 8 * fq;
; #pragma unroll
;         for (int ai = 0; ai < 2; ++ai)
; #pragma unroll
;             for (int m = 0; m < 4; ++m) {
;                 const int r = rbase + ai * 128 + m * 16;
; #pragma unroll
;                 for (int bj = 0; bj < 2; ++bj) {
;                     const int t0 = tb + bj * 128;
;                     const f32x4 v0 = acc[ai][bj][m][0], v1 = acc[ai][bj][m][1];
;                     u32x4 w; w.x = cvt_pk_bf16(v0[0], v0[1]); w.y = cvt_pk_bf16(v0[2], v0[3]); w.z = cvt_pk_bf16(v1[0], v1[1]); w.w = cvt_pk_bf16(v1[2], v1[3]);
;                     *(u32x4*)(VT + (size_t)r * NT + t0) = w;
;                 }
;             }
	v_mfma_f32_16x16x32_bf16 v[48:51], v[202:205], v[166:169], v[48:51]
	v_mfma_f32_16x16x32_bf16 v[40:43], v[210:213], v[166:169], v[40:43]
	v_mfma_f32_16x16x32_bf16 v[32:35], v[202:205], v[174:177], v[32:35]
	v_mfma_f32_16x16x32_bf16 v[24:27], v[210:213], v[174:177], v[24:27]
	v_mfma_f32_16x16x32_bf16 v[16:19], v[202:205], v[182:185], v[16:19]
	v_mfma_f32_16x16x32_bf16 v[8:11], v[210:213], v[182:185], v[8:11]
	v_mfma_f32_16x16x32_bf16 v[4:7], v[202:205], v[190:193], v[4:7]
	v_mfma_f32_16x16x32_bf16 v[0:3], v[210:213], v[190:193], v[0:3]
	v_mfma_f32_16x16x32_bf16 v[48:51], v[206:209], v[170:173], v[48:51]
	v_mfma_f32_16x16x32_bf16 v[40:43], v[214:217], v[170:173], v[40:43]
	v_mfma_f32_16x16x32_bf16 v[32:35], v[206:209], v[178:181], v[32:35]
	v_mfma_f32_16x16x32_bf16 v[24:27], v[214:217], v[178:181], v[24:27]
	v_mfma_f32_16x16x32_bf16 v[16:19], v[206:209], v[186:189], v[16:19]
	v_mfma_f32_16x16x32_bf16 v[8:11], v[214:217], v[186:189], v[8:11]
	v_mfma_f32_16x16x32_bf16 v[4:7], v[206:209], v[194:197], v[4:7]
	v_mfma_f32_16x16x32_bf16 v[0:3], v[214:217], v[194:197], v[0:3]
	s_add_i32 s65, s65, 2
	s_add_u32 s30, s30, 0x100
	s_addc_u32 s31, s31, 0
	s_add_u32 s63, s63, 0x100
	s_addc_u32 s64, s64, 0
	s_cmp_gt_u32 s65, 13
	s_barrier
	s_setprio 0
	s_cbranch_scc0 .LBB0_633
	v_mov_b32_e32 v150, v144
	v_mov_b32_e32 v151, v145
	s_lshl_b32 s21, s28, 8
	s_add_i32 s21, s21, s48
	v_add_u32_e32 v150, s21, v150
	s_lshl_b32 s21, s60, 8
	s_or_b32 s21, s21, s49
	v_lshl_add_u32 v152, v151, 3, s21
	v_ashrrev_i32_e32 v151, 31, v150
	v_cvt_pk_bf16_f32 v124, v124, v125
	v_cvt_pk_bf16_f32 v125, v126, v127
	v_cvt_pk_bf16_f32 v126, v120, v121
	v_lshlrev_b64 v[120:121], 17, v[150:151]
	v_lshl_add_u64 v[120:121], s[0:1], 0, v[120:121]
	v_ashrrev_i32_e32 v153, 31, v152
	v_lshl_add_u64 v[120:121], v[152:153], 1, v[120:121]
	s_mov_b32 s21, 0x200000
	v_cvt_pk_bf16_f32 v127, v122, v123
	global_store_dwordx4 v[120:121], v[124:127], off
	v_cvt_pk_bf16_f32 v112, v112, v113
	v_cvt_pk_bf16_f32 v113, v114, v115
	v_cvt_pk_bf16_f32 v114, v104, v105
	v_cvt_pk_bf16_f32 v115, v106, v107
	global_store_dwordx4 v[120:121], v[112:115], off offset:256
	v_cvt_pk_bf16_f32 v104, v116, v117
	v_cvt_pk_bf16_f32 v105, v118, v119
	v_cvt_pk_bf16_f32 v106, v108, v109
	v_cvt_pk_bf16_f32 v107, v110, v111
	s_mov_b64 s[30:31], 0x200000
	v_add_co_u32_e32 v110, vcc, s21, v120
	v_lshl_add_u64 v[108:109], v[120:121], 0, s[30:31]
	s_nop 0
	v_addc_co_u32_e32 v111, vcc, 0, v121, vcc
	s_mov_b32 s21, 0x400000
	global_store_dwordx4 v[110:111], v[104:107], off
	v_cvt_pk_bf16_f32 v96, v96, v97
	v_cvt_pk_bf16_f32 v97, v98, v99
	v_cvt_pk_bf16_f32 v98, v88, v89
	v_cvt_pk_bf16_f32 v99, v90, v91
	global_store_dwordx4 v[108:109], v[96:99], off offset:256
	v_cvt_pk_bf16_f32 v88, v100, v101
	v_cvt_pk_bf16_f32 v89, v102, v103
	v_cvt_pk_bf16_f32 v90, v92, v93
	v_cvt_pk_bf16_f32 v91, v94, v95
	s_mov_b64 s[30:31], 0x400000
	v_add_co_u32_e32 v94, vcc, s21, v120
	v_lshl_add_u64 v[92:93], v[120:121], 0, s[30:31]
	s_nop 0
	v_addc_co_u32_e32 v95, vcc, 0, v121, vcc
	s_mov_b32 s21, 0x600000
	global_store_dwordx4 v[94:95], v[88:91], off
	v_cvt_pk_bf16_f32 v80, v80, v81
	v_cvt_pk_bf16_f32 v81, v82, v83
	v_cvt_pk_bf16_f32 v82, v72, v73
	v_cvt_pk_bf16_f32 v83, v74, v75
	global_store_dwordx4 v[92:93], v[80:83], off offset:256
	v_cvt_pk_bf16_f32 v72, v84, v85
	v_cvt_pk_bf16_f32 v73, v86, v87
	v_cvt_pk_bf16_f32 v74, v76, v77
	v_cvt_pk_bf16_f32 v75, v78, v79
	s_mov_b64 s[30:31], 0x600000
	v_add_co_u32_e32 v78, vcc, s21, v120
	v_lshl_add_u64 v[76:77], v[120:121], 0, s[30:31]
	s_nop 0
	v_addc_co_u32_e32 v79, vcc, 0, v121, vcc
	global_store_dwordx4 v[78:79], v[72:75], off
	v_cvt_pk_bf16_f32 v68, v68, v69
	v_cvt_pk_bf16_f32 v69, v70, v71
	v_cvt_pk_bf16_f32 v70, v64, v65
	v_cvt_pk_bf16_f32 v71, v66, v67
	global_store_dwordx4 v[76:77], v[68:71], off offset:256
	v_cvt_pk_bf16_f32 v60, v60, v61
	v_cvt_pk_bf16_f32 v61, v62, v63
	v_cvt_pk_bf16_f32 v62, v56, v57
	v_cvt_pk_bf16_f32 v63, v58, v59
	s_mov_b64 s[30:31], 0x1000000
	v_add_co_u32_e32 v58, vcc, s56, v120
	v_lshl_add_u64 v[56:57], v[120:121], 0, s[30:31]
	s_nop 0
	v_addc_co_u32_e32 v59, vcc, 0, v121, vcc
	global_store_dwordx4 v[58:59], v[60:63], off
	v_cvt_pk_bf16_f32 v48, v48, v49
	v_cvt_pk_bf16_f32 v49, v50, v51
	v_cvt_pk_bf16_f32 v50, v40, v41
	v_cvt_pk_bf16_f32 v51, v42, v43
	global_store_dwordx4 v[56:57], v[48:51], off offset:256
	v_cvt_pk_bf16_f32 v40, v52, v53
	v_cvt_pk_bf16_f32 v41, v54, v55
	v_cvt_pk_bf16_f32 v42, v44, v45
	v_cvt_pk_bf16_f32 v43, v46, v47
	v_add_co_u32_e32 v46, vcc, s57, v120
	v_lshl_add_u64 v[44:45], v[120:121], 0, s[6:7]
	s_nop 0
	v_addc_co_u32_e32 v47, vcc, 0, v121, vcc
	global_store_dwordx4 v[46:47], v[40:43], off
	v_cvt_pk_bf16_f32 v32, v32, v33
	v_cvt_pk_bf16_f32 v33, v34, v35
	v_cvt_pk_bf16_f32 v34, v24, v25
	v_cvt_pk_bf16_f32 v35, v26, v27
	global_store_dwordx4 v[44:45], v[32:35], off offset:256
	v_cvt_pk_bf16_f32 v24, v36, v37
	v_cvt_pk_bf16_f32 v25, v38, v39
	v_cvt_pk_bf16_f32 v26, v28, v29
	v_cvt_pk_bf16_f32 v27, v30, v31
	v_add_co_u32_e32 v30, vcc, s58, v120
	v_lshl_add_u64 v[28:29], v[120:121], 0, s[8:9]
	s_nop 0
	v_addc_co_u32_e32 v31, vcc, 0, v121, vcc
	global_store_dwordx4 v[30:31], v[24:27], off
	v_cvt_pk_bf16_f32 v16, v16, v17
	v_cvt_pk_bf16_f32 v17, v18, v19
	v_cvt_pk_bf16_f32 v18, v8, v9
	v_cvt_pk_bf16_f32 v19, v10, v11
	global_store_dwordx4 v[28:29], v[16:19], off offset:256
	v_cvt_pk_bf16_f32 v8, v20, v21
	v_cvt_pk_bf16_f32 v9, v22, v23
	v_cvt_pk_bf16_f32 v10, v12, v13
	v_cvt_pk_bf16_f32 v11, v14, v15
	v_add_co_u32_e32 v14, vcc, s59, v120
	v_lshl_add_u64 v[12:13], v[120:121], 0, s[16:17]
	s_nop 0
	v_addc_co_u32_e32 v15, vcc, 0, v121, vcc
	s_and_b64 vcc, exec, s[2:3]
	s_mov_b32 s60, s20
	s_mov_b32 s28, s22
	s_mov_b64 s[34:35], s[26:27]
	s_mov_b64 s[30:31], s[24:25]
	global_store_dwordx4 v[14:15], v[8:11], off
	v_cvt_pk_bf16_f32 v4, v4, v5
	v_cvt_pk_bf16_f32 v5, v6, v7
	v_cvt_pk_bf16_f32 v6, v0, v1
	v_cvt_pk_bf16_f32 v7, v2, v3
	global_store_dwordx4 v[12:13], v[4:7], off offset:256
	s_cbranch_vccz .LBB0_626
	s_waitcnt vmcnt(0)
	s_cmpk_gt_u32 s33, 0xff
	s_cbranch_scc1 .LBB0_637
	s_barrier

; #define PG8_STAGE(bufoff, gbase, voff) do { _Pragma("unroll") for (int _i = 0; _i < 2; ++_i) \
;         __builtin_amdgcn_global_load_lds((const unsigned*)((const char*)(gbase) + (voff)[_i]), (LAS unsigned*)(lds + (bufoff) + ldsw + _i * 8192), 16, 0, 0); } while (0)
; #define PG8_LDA(dst, b, h) do { _Pragma("unroll") for (int m = 0; m < 4; ++m) _Pragma("unroll") for (int k = 0; k < 2; ++k) dst[m][k] = *(const LAS bf16x8*)(lds + PG8_SA(b, h) + aoff + m * 2048 + k * 1024); } while (0)
; #define PG8_LDB(dst, b, h) do { _Pragma("unroll") for (int n = 0; n < 2; ++n) _Pragma("unroll") for (int k = 0; k < 2; ++k) dst[n][k] = *(const LAS bf16x8*)(lds + PG8_SB(b, h) + boff + n * 2048 + k * 1024); } while (0)
; #define PG8_MMA(ai, bj, At, Bt) do { __builtin_amdgcn_s_setprio(1); _Pragma("unroll") for (int m = 0; m < 4; ++m) _Pragma("unroll") for (int n = 0; n < 2; ++n) _Pragma("unroll") for (int k = 0; k < 2; ++k) \
;         acc[ai][bj][m][n] = __builtin_amdgcn_mfma_f32_16x16x32_bf16(Bt[n][k], At[m][k], acc[ai][bj][m][n], 0, 0, 0); __builtin_amdgcn_s_setprio(0); } while (0)
; #define PG8_WAIT_L(n) asm volatile("s_waitcnt lgkmcnt(" #n ")" ::: "memory")
; template <class Epi, class Sched>
; __device__ __forceinline__ void gemm_phase(LAS unsigned char* lds, const Gemm g, const Sched& S, const Epi& E) {
;     ...
;         const bool has_next = S.next(ui + 1, nxt);
;         const char* nA = has_next ? (const char*)g.A + (size_t)nxt.pm * tstep : cA; const char* nB = has_next ? (const char*)g.Bt + (size_t)nxt.pn * tstep : cB;
;         for (int t = 0; t < nt; t += 2) {
;             const bool last = (t == nt - 2);
;             const char* a1 = cA + (size_t)(t + 1) * kstep;
;             const char* a2 = last ? nA : cA + (size_t)(t + 2) * kstep; const char* b2 = last ? nB : cB + (size_t)(t + 2) * kstep;
;             const char* a3 = a2 + kstep; const char* b3 = b2 + kstep;
;             PG8_LDB(B0, 0, 0); PG8_SCHED; PG8_LDA(At, 0, 0); PG8_STAGE(PG8_SA(1, 1), a1 + hstep, voffA);
;             PG8_WAIT_L(8); PG8_BAR; PG8_WAIT_L(0); PG8_MMA(0, 0, At, B0); PG8_BAR; PG8_SCHED;
;             PG8_LDB(B1, 0, 1); PG8_STAGE(PG8_SB(0, 0), b2, voffB);
;             PG8_BAR; PG8_WAIT_L(0); PG8_MMA(0, 1, At, B1); PG8_BAR;
;             PG8_LDA(At, 0, 1); PG8_STAGE(PG8_SA(0, 0), a2, voffA);
;             PG8_BAR; PG8_WAIT_L(0); PG8_MMA(1, 0, At, B0); PG8_BAR; PG8_SCHED;
.LBB0_652:
	s_ashr_i32 s9, s8, 31
	v_cmp_lt_i64_e32 vcc, s[16:17], v[142:143]
	s_lshl_b64 s[16:17], s[8:9], 19
	s_add_u32 s16, s14, s16
	s_addc_u32 s17, s15, s17
	s_and_b64 s[18:19], vcc, exec
	s_cselect_b32 s9, s17, s23
	s_cselect_b32 s48, s16, s22
	s_ashr_i32 s7, s6, 31
	s_lshl_b64 s[18:19], s[6:7], 19
	s_add_u32 s18, s12, s18
	s_addc_u32 s19, s13, s19
	s_and_b64 s[26:27], vcc, exec
	s_cselect_b32 s7, s19, s25
	s_cselect_b32 s49, s18, s24
	s_add_u32 s22, s22, 0x40080
	s_addc_u32 s23, s23, 0
	s_add_u32 s51, s24, 0x100
	s_addc_u32 s52, s25, 0
	s_mov_b32 s53, -2
	s_waitcnt lgkmcnt(0)
	ds_read_b128 v[152:155], v149
	ds_read_b128 v[156:159], v149 offset:1024
	ds_read_b128 v[160:163], v149 offset:2048
	ds_read_b128 v[164:167], v149 offset:3072
	s_add_u32 s24, s22, 0xfffc0080
	s_addc_u32 s25, s23, -1
	s_cmp_eq_u32 s53, 12
	s_cselect_b32 s27, s9, s25
	s_cselect_b32 s26, s48, s24
	s_cselect_b32 s25, s7, s52
	s_cselect_b32 s24, s49, s51
	s_add_i32 m0, s21, 0xc000
	ds_read_b128 v[168:171], v150
	ds_read_b128 v[172:175], v150 offset:1024
	ds_read_b128 v[176:179], v150 offset:2048
	ds_read_b128 v[180:183], v150 offset:3072
	ds_read_b128 v[184:187], v150 offset:4096
	ds_read_b128 v[188:191], v150 offset:5120
	ds_read_b128 v[192:195], v150 offset:6144
	ds_read_b128 v[196:199], v150 offset:7168
	global_load_lds_dwordx4 v138, s[22:23]
	s_add_i32 m0, s21, 0xe000
	s_nop 0
	global_load_lds_dwordx4 v140, s[22:23]
	s_waitcnt lgkmcnt(8)
	s_waitcnt vmcnt(8)
	s_setprio 1
	s_barrier
	s_waitcnt lgkmcnt(0)
	v_mfma_f32_16x16x32_bf16 v[124:127], v[152:155], v[168:171], 0
	v_mfma_f32_16x16x32_bf16 v[120:123], v[160:163], v[168:171], 0
	v_mfma_f32_16x16x32_bf16 v[112:115], v[152:155], v[176:179], 0
	v_mfma_f32_16x16x32_bf16 v[104:107], v[160:163], v[176:179], 0
	v_mfma_f32_16x16x32_bf16 v[96:99], v[152:155], v[184:187], 0
	v_mfma_f32_16x16x32_bf16 v[88:91], v[160:163], v[184:187], 0
	v_mfma_f32_16x16x32_bf16 v[80:83], v[152:155], v[192:195], 0
	v_mfma_f32_16x16x32_bf16 v[72:75], v[160:163], v[192:195], 0
	v_mfma_f32_16x16x32_bf16 v[124:127], v[156:159], v[172:175], v[124:127]
	v_mfma_f32_16x16x32_bf16 v[120:123], v[164:167], v[172:175], v[120:123]
	v_mfma_f32_16x16x32_bf16 v[112:115], v[156:159], v[180:183], v[112:115]
	v_mfma_f32_16x16x32_bf16 v[104:107], v[164:167], v[180:183], v[104:107]
	v_mfma_f32_16x16x32_bf16 v[96:99], v[156:159], v[188:191], v[96:99]
	v_mfma_f32_16x16x32_bf16 v[88:91], v[164:167], v[188:191], v[88:91]
	v_mfma_f32_16x16x32_bf16 v[80:83], v[156:159], v[196:199], v[80:83]
	v_mfma_f32_16x16x32_bf16 v[72:75], v[164:167], v[196:199], v[72:75]
	s_barrier
	s_setprio 0
	s_add_i32 s54, s45, s30
	s_mov_b32 m0, s54
	ds_read_b128 v[202:205], v151
	ds_read_b128 v[206:209], v151 offset:1024
	ds_read_b128 v[210:213], v151 offset:2048
	ds_read_b128 v[214:217], v151 offset:3072
	global_load_lds_dwordx4 v130, s[24:25]
	s_add_i32 m0, s54, 0x2000
	s_nop 0
	global_load_lds_dwordx4 v134, s[24:25]
	s_waitcnt vmcnt(8)
	s_setprio 1
	s_barrier
	s_waitcnt lgkmcnt(0)
	v_mfma_f32_16x16x32_bf16 v[116:119], v[202:205], v[168:171], 0
	v_mfma_f32_16x16x32_bf16 v[108:111], v[210:213], v[168:171], 0
	v_mfma_f32_16x16x32_bf16 v[100:103], v[202:205], v[176:179], 0
	v_mfma_f32_16x16x32_bf16 v[92:95], v[210:213], v[176:179], 0
	v_mfma_f32_16x16x32_bf16 v[84:87], v[202:205], v[184:187], 0
	v_mfma_f32_16x16x32_bf16 v[76:79], v[210:213], v[184:187], 0
	v_mfma_f32_16x16x32_bf16 v[68:71], v[202:205], v[192:195], 0
	v_mfma_f32_16x16x32_bf16 v[64:67], v[210:213], v[192:195], 0
	v_mfma_f32_16x16x32_bf16 v[116:119], v[206:209], v[172:175], v[116:119]
	v_mfma_f32_16x16x32_bf16 v[108:111], v[214:217], v[172:175], v[108:111]
	v_mfma_f32_16x16x32_bf16 v[100:103], v[206:209], v[180:183], v[100:103]
	v_mfma_f32_16x16x32_bf16 v[92:95], v[214:217], v[180:183], v[92:95]
	v_mfma_f32_16x16x32_bf16 v[84:87], v[206:209], v[188:191], v[84:87]
	v_mfma_f32_16x16x32_bf16 v[76:79], v[214:217], v[188:191], v[76:79]
	v_mfma_f32_16x16x32_bf16 v[68:71], v[206:209], v[196:199], v[68:71]
	v_mfma_f32_16x16x32_bf16 v[64:67], v[214:217], v[196:199], v[64:67]
	s_mov_b32 m0, s21
	v_lshl_add_u64 v[222:223], s[26:27], 0, v[128:129]
	s_barrier
	s_setprio 0
	ds_read_b128 v[168:171], v150 offset:16384
	ds_read_b128 v[172:175], v150 offset:17408
	ds_read_b128 v[176:179], v150 offset:18432
	ds_read_b128 v[180:183], v150 offset:19456
	ds_read_b128 v[184:187], v150 offset:20480
	ds_read_b128 v[188:191], v150 offset:21504
	ds_read_b128 v[192:195], v150 offset:22528
	ds_read_b128 v[196:199], v150 offset:23552
	global_load_lds_dwordx4 v128, s[26:27]
	v_lshl_add_u64 v[224:225], s[26:27], 0, v[132:133]
	s_mov_b32 m0, s31
	s_nop 0
	global_load_lds_dwordx4 v132, s[26:27]
	s_setprio 1
	s_barrier
	s_waitcnt lgkmcnt(0)
	v_mfma_f32_16x16x32_bf16 v[60:63], v[152:155], v[168:171], 0
	v_mfma_f32_16x16x32_bf16 v[56:59], v[160:163], v[168:171], 0
	v_mfma_f32_16x16x32_bf16 v[48:51], v[152:155], v[176:179], 0
	v_mfma_f32_16x16x32_bf16 v[40:43], v[160:163], v[176:179], 0
	v_mfma_f32_16x16x32_bf16 v[32:35], v[152:155], v[184:187], 0
	v_mfma_f32_16x16x32_bf16 v[24:27], v[160:163], v[184:187], 0
	v_mfma_f32_16x16x32_bf16 v[16:19], v[152:155], v[192:195], 0
	v_mfma_f32_16x16x32_bf16 v[8:11], v[160:163], v[192:195], 0
	v_mfma_f32_16x16x32_bf16 v[60:63], v[156:159], v[172:175], v[60:63]
	v_mfma_f32_16x16x32_bf16 v[56:59], v[164:167], v[172:175], v[56:59]
	v_mfma_f32_16x16x32_bf16 v[48:51], v[156:159], v[180:183], v[48:51]
	v_mfma_f32_16x16x32_bf16 v[40:43], v[164:167], v[180:183], v[40:43]
	v_mfma_f32_16x16x32_bf16 v[32:35], v[156:159], v[188:191], v[32:35]
	v_mfma_f32_16x16x32_bf16 v[24:27], v[164:167], v[188:191], v[24:27]
	v_mfma_f32_16x16x32_bf16 v[16:19], v[156:159], v[196:199], v[16:19]
	v_mfma_f32_16x16x32_bf16 v[8:11], v[164:167], v[196:199], v[8:11]
	s_barrier
; #define PG8_STAGE(bufoff, gbase, voff) do { _Pragma("unroll") for (int _i = 0; _i < 2; ++_i) \
;         __builtin_amdgcn_global_load_lds((const unsigned*)((const char*)(gbase) + (voff)[_i]), (LAS unsigned*)(lds + (bufoff) + ldsw + _i * 8192), 16, 0, 0); } while (0)
; #define PG8_LDA(dst, b, h) do { _Pragma("unroll") for (int m = 0; m < 4; ++m) _Pragma("unroll") for (int k = 0; k < 2; ++k) dst[m][k] = *(const LAS bf16x8*)(lds + PG8_SA(b, h) + aoff + m * 2048 + k * 1024); } while (0)
; #define PG8_LDB(dst, b, h) do { _Pragma("unroll") for (int n = 0; n < 2; ++n) _Pragma("unroll") for (int k = 0; k < 2; ++k) dst[n][k] = *(const LAS bf16x8*)(lds + PG8_SB(b, h) + boff + n * 2048 + k * 1024); } while (0)
; #define PG8_MMA(ai, bj, At, Bt) do { __builtin_amdgcn_s_setprio(1); _Pragma("unroll") for (int m = 0; m < 4; ++m) _Pragma("unroll") for (int n = 0; n < 2; ++n) _Pragma("unroll") for (int k = 0; k < 2; ++k) \
;         acc[ai][bj][m][n] = __builtin_amdgcn_mfma_f32_16x16x32_bf16(Bt[n][k], At[m][k], acc[ai][bj][m][n], 0, 0, 0); __builtin_amdgcn_s_setprio(0); } while (0)
; #define PG8_WAIT_V(n) asm volatile("s_waitcnt vmcnt(" #n ")" ::: "memory")
; #define PG8_WAIT_L(n) asm volatile("s_waitcnt lgkmcnt(" #n ")" ::: "memory")
; #define PG8_BAR __builtin_amdgcn_s_barrier()
; #define PG8_SCHED __builtin_amdgcn_sched_barrier(0)
; template <class Epi, class Sched>
; __device__ __forceinline__ void gemm_phase(LAS unsigned char* lds, const Gemm g, const Sched& S, const Epi& E) {
;     ...
;             PG8_STAGE(PG8_SB(0, 1), b2 + hstep, voffB);
;             PG8_WAIT_V(6); PG8_BAR; PG8_MMA(1, 1, At, B1); PG8_BAR;
;             PG8_LDB(B0, 1, 0); PG8_SCHED; PG8_LDA(At, 1, 0); PG8_STAGE(PG8_SA(0, 1), a2 + hstep, voffA);
;             PG8_WAIT_L(8); PG8_BAR; PG8_WAIT_L(0); PG8_MMA(0, 0, At, B0); PG8_BAR; PG8_SCHED;
;             PG8_LDB(B1, 1, 1); PG8_STAGE(PG8_SB(1, 0), b3, voffB);
;             PG8_BAR; PG8_WAIT_L(0); PG8_MMA(0, 1, At, B1); PG8_BAR;
;             PG8_LDA(At, 1, 1); PG8_STAGE(PG8_SA(1, 0), a3, voffA);
;             PG8_BAR; PG8_WAIT_L(0); PG8_MMA(1, 0, At, B0); PG8_BAR; PG8_SCHED;
	s_setprio 0
	s_add_u32 s54, s24, 0x40000
	s_addc_u32 s55, s25, 0
	s_add_i32 s56, s46, s30
	s_mov_b32 m0, s56
	s_nop 0
	global_load_lds_dwordx4 v130, s[54:55]
	s_add_i32 m0, s56, 0x2000
	s_nop 0
	global_load_lds_dwordx4 v134, s[54:55]
	s_add_u32 s26, s26, 0x40000
	s_addc_u32 s27, s27, 0
	s_mov_b32 m0, s33
	s_nop 0
	global_load_lds_dwordx4 v128, s[26:27]
	s_mov_b32 m0, s34
	s_nop 0
	global_load_lds_dwordx4 v132, s[26:27]
	s_waitcnt vmcnt(10)
	s_setprio 1
	s_barrier
	v_mfma_f32_16x16x32_bf16 v[52:55], v[202:205], v[168:171], 0
	v_mfma_f32_16x16x32_bf16 v[44:47], v[210:213], v[168:171], 0
	v_mfma_f32_16x16x32_bf16 v[36:39], v[202:205], v[176:179], 0
	v_mfma_f32_16x16x32_bf16 v[28:31], v[210:213], v[176:179], 0
	v_mfma_f32_16x16x32_bf16 v[20:23], v[202:205], v[184:187], 0
	v_mfma_f32_16x16x32_bf16 v[12:15], v[210:213], v[184:187], 0
	v_mfma_f32_16x16x32_bf16 v[4:7], v[202:205], v[192:195], 0
	v_mfma_f32_16x16x32_bf16 v[0:3], v[210:213], v[192:195], 0
	v_mfma_f32_16x16x32_bf16 v[52:55], v[206:209], v[172:175], v[52:55]
	v_mfma_f32_16x16x32_bf16 v[44:47], v[214:217], v[172:175], v[44:47]
	v_mfma_f32_16x16x32_bf16 v[36:39], v[206:209], v[180:183], v[36:39]
	v_mfma_f32_16x16x32_bf16 v[28:31], v[214:217], v[180:183], v[28:31]
	v_mfma_f32_16x16x32_bf16 v[20:23], v[206:209], v[188:191], v[20:23]
	v_mfma_f32_16x16x32_bf16 v[12:15], v[214:217], v[188:191], v[12:15]
	v_mfma_f32_16x16x32_bf16 v[4:7], v[206:209], v[196:199], v[4:7]
	v_mfma_f32_16x16x32_bf16 v[0:3], v[214:217], v[196:199], v[0:3]
	s_add_i32 s54, 0, 0x18000
	v_add_u32_e32 v136, s54, v148
	s_barrier
	s_setprio 0
	ds_read_b128 v[152:155], v136
	ds_read_b128 v[156:159], v136 offset:1024
	ds_read_b128 v[160:163], v136 offset:2048
	ds_read_b128 v[164:167], v136 offset:3072
	ds_read_b128 v[168:171], v150 offset:32768
	ds_read_b128 v[172:175], v150 offset:33792
	ds_read_b128 v[176:179], v150 offset:34816
	ds_read_b128 v[180:183], v150 offset:35840
	ds_read_b128 v[184:187], v150 offset:36864
	ds_read_b128 v[188:191], v150 offset:37888
	ds_read_b128 v[192:195], v150 offset:38912
	ds_read_b128 v[196:199], v150 offset:39936
	s_waitcnt lgkmcnt(8)
	s_waitcnt vmcnt(8)
	s_setprio 1
	s_barrier
	s_waitcnt lgkmcnt(0)
	v_mfma_f32_16x16x32_bf16 v[124:127], v[152:155], v[168:171], v[124:127]
	v_mfma_f32_16x16x32_bf16 v[120:123], v[160:163], v[168:171], v[120:123]
	v_mfma_f32_16x16x32_bf16 v[112:115], v[152:155], v[176:179], v[112:115]
	v_mfma_f32_16x16x32_bf16 v[104:107], v[160:163], v[176:179], v[104:107]
	v_mfma_f32_16x16x32_bf16 v[96:99], v[152:155], v[184:187], v[96:99]
	v_mfma_f32_16x16x32_bf16 v[88:91], v[160:163], v[184:187], v[88:91]
	v_mfma_f32_16x16x32_bf16 v[80:83], v[152:155], v[192:195], v[80:83]
	v_mfma_f32_16x16x32_bf16 v[72:75], v[160:163], v[192:195], v[72:75]
	v_mfma_f32_16x16x32_bf16 v[124:127], v[156:159], v[172:175], v[124:127]
	v_mfma_f32_16x16x32_bf16 v[120:123], v[164:167], v[172:175], v[120:123]
	v_mfma_f32_16x16x32_bf16 v[112:115], v[156:159], v[180:183], v[112:115]
	v_mfma_f32_16x16x32_bf16 v[104:107], v[164:167], v[180:183], v[104:107]
	v_mfma_f32_16x16x32_bf16 v[96:99], v[156:159], v[188:191], v[96:99]
	v_mfma_f32_16x16x32_bf16 v[88:91], v[164:167], v[188:191], v[88:91]
	v_mfma_f32_16x16x32_bf16 v[80:83], v[156:159], v[196:199], v[80:83]
	v_mfma_f32_16x16x32_bf16 v[72:75], v[164:167], v[196:199], v[72:75]
	s_barrier
	s_setprio 0
	s_add_i32 s26, 0, 0x1c000
	s_add_i32 s27, s54, s30
	v_add_u32_e32 v136, s26, v148
	s_add_u32 s0, s24, 0x80
	s_addc_u32 s1, s25, 0
	s_mov_b32 m0, s27
	ds_read_b128 v[202:205], v136
	ds_read_b128 v[206:209], v136 offset:1024
	ds_read_b128 v[210:213], v136 offset:2048
	ds_read_b128 v[214:217], v136 offset:3072
	global_load_lds_dwordx4 v130, s[0:1]
	s_add_i32 m0, s27, 0x2000
	s_nop 0
	global_load_lds_dwordx4 v134, s[0:1]
	s_waitcnt vmcnt(8)
	s_setprio 1
	s_barrier
	s_waitcnt lgkmcnt(0)
	v_mfma_f32_16x16x32_bf16 v[116:119], v[202:205], v[168:171], v[116:119]
	v_mfma_f32_16x16x32_bf16 v[108:111], v[210:213], v[168:171], v[108:111]
	v_mfma_f32_16x16x32_bf16 v[100:103], v[202:205], v[176:179], v[100:103]
	v_mfma_f32_16x16x32_bf16 v[92:95], v[210:213], v[176:179], v[92:95]
	v_mfma_f32_16x16x32_bf16 v[84:87], v[202:205], v[184:187], v[84:87]
	v_mfma_f32_16x16x32_bf16 v[76:79], v[210:213], v[184:187], v[76:79]
	v_mfma_f32_16x16x32_bf16 v[68:71], v[202:205], v[192:195], v[68:71]
	v_mfma_f32_16x16x32_bf16 v[64:67], v[210:213], v[192:195], v[64:67]
	v_mfma_f32_16x16x32_bf16 v[116:119], v[206:209], v[172:175], v[116:119]
	v_mfma_f32_16x16x32_bf16 v[108:111], v[214:217], v[172:175], v[108:111]
	v_mfma_f32_16x16x32_bf16 v[100:103], v[206:209], v[180:183], v[100:103]
	v_mfma_f32_16x16x32_bf16 v[92:95], v[214:217], v[180:183], v[92:95]
	v_mfma_f32_16x16x32_bf16 v[84:87], v[206:209], v[188:191], v[84:87]
	v_mfma_f32_16x16x32_bf16 v[76:79], v[214:217], v[188:191], v[76:79]
	v_mfma_f32_16x16x32_bf16 v[68:71], v[206:209], v[196:199], v[68:71]
	v_mfma_f32_16x16x32_bf16 v[64:67], v[214:217], v[196:199], v[64:67]
	s_mov_b32 m0, s42
	s_mov_b64 s[0:1], 0x80
	v_lshl_add_u64 v[218:219], v[222:223], 0, s[0:1]
	s_barrier
	s_setprio 0
	ds_read_b128 v[168:171], v150 offset:49152
	ds_read_b128 v[172:175], v150 offset:50176
	ds_read_b128 v[176:179], v150 offset:51200
	ds_read_b128 v[180:183], v150 offset:52224
	ds_read_b128 v[184:187], v150 offset:53248
	ds_read_b128 v[188:191], v150 offset:54272
	ds_read_b128 v[192:195], v150 offset:55296
	ds_read_b128 v[196:199], v150 offset:56320
	global_load_lds_dwordx4 v[218:219], off
	v_lshl_add_u64 v[218:219], v[224:225], 0, s[0:1]
	s_mov_b32 m0, s43
	s_nop 0
	global_load_lds_dwordx4 v[218:219], off
	s_setprio 1
	s_barrier
; #define PG8_STAGE(bufoff, gbase, voff) do { _Pragma("unroll") for (int _i = 0; _i < 2; ++_i) \
;         __builtin_amdgcn_global_load_lds((const unsigned*)((const char*)(gbase) + (voff)[_i]), (LAS unsigned*)(lds + (bufoff) + ldsw + _i * 8192), 16, 0, 0); } while (0)
; #define PG8_LDA(dst, b, h) do { _Pragma("unroll") for (int m = 0; m < 4; ++m) _Pragma("unroll") for (int k = 0; k < 2; ++k) dst[m][k] = *(const LAS bf16x8*)(lds + PG8_SA(b, h) + aoff + m * 2048 + k * 1024); } while (0)
; #define PG8_LDB(dst, b, h) do { _Pragma("unroll") for (int n = 0; n < 2; ++n) _Pragma("unroll") for (int k = 0; k < 2; ++k) dst[n][k] = *(const LAS bf16x8*)(lds + PG8_SB(b, h) + boff + n * 2048 + k * 1024); } while (0)
; #define PG8_WAIT_V(n) asm volatile("s_waitcnt vmcnt(" #n ")" ::: "memory")
; #define PG8_WAIT_L(n) asm volatile("s_waitcnt lgkmcnt(" #n ")" ::: "memory")
; #define PG8_BAR __builtin_amdgcn_s_barrier()
; #define PG8_SCHED __builtin_amdgcn_sched_barrier(0)
; template <class Epi, class Sched>
; __device__ __forceinline__ void gemm_phase(LAS unsigned char* lds, const Gemm g, const Sched& S, const Epi& E) {
;     ...
;             PG8_LDB(B0, 0, 0); PG8_SCHED; PG8_LDA(At, 0, 0); PG8_STAGE(PG8_SA(1, 1), a1 + hstep, voffA);
;             PG8_WAIT_L(8); PG8_BAR; PG8_WAIT_L(0); PG8_MMA(0, 0, At, B0); PG8_BAR; PG8_SCHED;
;             PG8_LDB(B1, 0, 1); PG8_STAGE(PG8_SB(0, 0), b2, voffB);
;             PG8_BAR; PG8_WAIT_L(0); PG8_MMA(0, 1, At, B1); PG8_BAR;
;             PG8_LDA(At, 0, 1); PG8_STAGE(PG8_SA(0, 0), a2, voffA);
;             PG8_BAR; PG8_WAIT_L(0); PG8_MMA(1, 0, At, B0); PG8_BAR; PG8_SCHED;
;             PG8_STAGE(PG8_SB(0, 1), b2 + hstep, voffB);
;             PG8_WAIT_V(6); PG8_BAR; PG8_MMA(1, 1, At, B1); PG8_BAR;
;             PG8_LDB(B0, 1, 0); PG8_SCHED; PG8_LDA(At, 1, 0); PG8_STAGE(PG8_SA(0, 1), a2 + hstep, voffA);
;             PG8_WAIT_L(8); PG8_BAR; PG8_WAIT_L(0); PG8_MMA(0, 0, At, B0); PG8_BAR; PG8_SCHED;
;             PG8_LDB(B1, 1, 1); PG8_STAGE(PG8_SB(1, 0), b3, voffB);
;             PG8_BAR; PG8_WAIT_L(0); PG8_MMA(0, 1, At, B1); PG8_BAR;
;             PG8_LDA(At, 1, 1); PG8_STAGE(PG8_SA(1, 0), a3, voffA);
;             PG8_BAR; PG8_WAIT_L(0); PG8_MMA(1, 0, At, B0); PG8_BAR; PG8_SCHED;
;             PG8_STAGE(PG8_SB(1, 1), b3 + hstep, voffB);
;             PG8_WAIT_V(6); PG8_BAR; PG8_MMA(1, 1, At, B1); PG8_BAR;
	s_waitcnt lgkmcnt(0)
	v_mfma_f32_16x16x32_bf16 v[60:63], v[152:155], v[168:171], v[60:63]
	v_mfma_f32_16x16x32_bf16 v[56:59], v[160:163], v[168:171], v[56:59]
	v_mfma_f32_16x16x32_bf16 v[48:51], v[152:155], v[176:179], v[48:51]
	v_mfma_f32_16x16x32_bf16 v[40:43], v[160:163], v[176:179], v[40:43]
	v_mfma_f32_16x16x32_bf16 v[32:35], v[152:155], v[184:187], v[32:35]
	v_mfma_f32_16x16x32_bf16 v[24:27], v[160:163], v[184:187], v[24:27]
	v_mfma_f32_16x16x32_bf16 v[16:19], v[152:155], v[192:195], v[16:19]
	v_mfma_f32_16x16x32_bf16 v[8:11], v[160:163], v[192:195], v[8:11]
	v_mfma_f32_16x16x32_bf16 v[60:63], v[156:159], v[172:175], v[60:63]
	v_mfma_f32_16x16x32_bf16 v[56:59], v[164:167], v[172:175], v[56:59]
	v_mfma_f32_16x16x32_bf16 v[48:51], v[156:159], v[180:183], v[48:51]
	v_mfma_f32_16x16x32_bf16 v[40:43], v[164:167], v[180:183], v[40:43]
	v_mfma_f32_16x16x32_bf16 v[32:35], v[156:159], v[188:191], v[32:35]
	v_mfma_f32_16x16x32_bf16 v[24:27], v[164:167], v[188:191], v[24:27]
	v_mfma_f32_16x16x32_bf16 v[16:19], v[156:159], v[196:199], v[16:19]
	v_mfma_f32_16x16x32_bf16 v[8:11], v[164:167], v[196:199], v[8:11]
	s_barrier
	s_setprio 0
	s_add_u32 s24, s24, 0x40080
	s_addc_u32 s25, s25, 0
	s_add_i32 s26, s26, s30
	s_mov_b32 m0, s26
	s_nop 0
	global_load_lds_dwordx4 v130, s[24:25]
	s_add_i32 m0, s26, 0x2000
	s_nop 0
	global_load_lds_dwordx4 v134, s[24:25]
	s_waitcnt vmcnt(8)
	s_setprio 1
	s_barrier
	v_mfma_f32_16x16x32_bf16 v[52:55], v[202:205], v[168:171], v[52:55]
	v_mfma_f32_16x16x32_bf16 v[44:47], v[210:213], v[168:171], v[44:47]
	v_mfma_f32_16x16x32_bf16 v[36:39], v[202:205], v[176:179], v[36:39]
	v_mfma_f32_16x16x32_bf16 v[28:31], v[210:213], v[176:179], v[28:31]
	v_mfma_f32_16x16x32_bf16 v[20:23], v[202:205], v[184:187], v[20:23]
	v_mfma_f32_16x16x32_bf16 v[12:15], v[210:213], v[184:187], v[12:15]
	v_mfma_f32_16x16x32_bf16 v[4:7], v[202:205], v[192:195], v[4:7]
	v_mfma_f32_16x16x32_bf16 v[0:3], v[210:213], v[192:195], v[0:3]
	v_mfma_f32_16x16x32_bf16 v[52:55], v[206:209], v[172:175], v[52:55]
	v_mfma_f32_16x16x32_bf16 v[44:47], v[214:217], v[172:175], v[44:47]
	v_mfma_f32_16x16x32_bf16 v[36:39], v[206:209], v[180:183], v[36:39]
	v_mfma_f32_16x16x32_bf16 v[28:31], v[214:217], v[180:183], v[28:31]
	v_mfma_f32_16x16x32_bf16 v[20:23], v[206:209], v[188:191], v[20:23]
	v_mfma_f32_16x16x32_bf16 v[12:15], v[214:217], v[188:191], v[12:15]
	v_mfma_f32_16x16x32_bf16 v[4:7], v[206:209], v[196:199], v[4:7]
	v_mfma_f32_16x16x32_bf16 v[0:3], v[214:217], v[196:199], v[0:3]
	s_add_i32 s53, s53, 2
	s_add_u32 s22, s22, 0x100
	s_addc_u32 s23, s23, 0
	s_add_u32 s51, s51, 0x100
	s_addc_u32 s52, s52, 0
	s_cmp_gt_u32 s53, 13
	s_barrier
	s_setprio 0
.LBB0_653:
	ds_read_b128 v[152:155], v149
	ds_read_b128 v[156:159], v149 offset:1024
	ds_read_b128 v[160:163], v149 offset:2048
	ds_read_b128 v[164:167], v149 offset:3072
	s_add_u32 s24, s22, 0xfffc0080
	s_addc_u32 s25, s23, -1
	s_cmp_eq_u32 s53, 12
	s_cselect_b32 s27, s9, s25
	s_cselect_b32 s26, s48, s24
	s_cselect_b32 s25, s7, s52
	s_cselect_b32 s24, s49, s51
	s_add_i32 m0, s21, 0xc000
	ds_read_b128 v[168:171], v150
	ds_read_b128 v[172:175], v150 offset:1024
	ds_read_b128 v[176:179], v150 offset:2048
	ds_read_b128 v[180:183], v150 offset:3072
	ds_read_b128 v[184:187], v150 offset:4096
	ds_read_b128 v[188:191], v150 offset:5120
	ds_read_b128 v[192:195], v150 offset:6144
	ds_read_b128 v[196:199], v150 offset:7168
	global_load_lds_dwordx4 v138, s[22:23]
	s_add_i32 m0, s21, 0xe000
	s_nop 0
	global_load_lds_dwordx4 v140, s[22:23]
	s_waitcnt lgkmcnt(8)
	s_waitcnt vmcnt(8)
	s_setprio 1
	s_barrier
	s_waitcnt lgkmcnt(0)
	v_mfma_f32_16x16x32_bf16 v[124:127], v[152:155], v[168:171], v[124:127]
	v_mfma_f32_16x16x32_bf16 v[120:123], v[160:163], v[168:171], v[120:123]
	v_mfma_f32_16x16x32_bf16 v[112:115], v[152:155], v[176:179], v[112:115]
	v_mfma_f32_16x16x32_bf16 v[104:107], v[160:163], v[176:179], v[104:107]
	v_mfma_f32_16x16x32_bf16 v[96:99], v[152:155], v[184:187], v[96:99]
	v_mfma_f32_16x16x32_bf16 v[88:91], v[160:163], v[184:187], v[88:91]
	v_mfma_f32_16x16x32_bf16 v[80:83], v[152:155], v[192:195], v[80:83]
	v_mfma_f32_16x16x32_bf16 v[72:75], v[160:163], v[192:195], v[72:75]
	v_mfma_f32_16x16x32_bf16 v[124:127], v[156:159], v[172:175], v[124:127]
	v_mfma_f32_16x16x32_bf16 v[120:123], v[164:167], v[172:175], v[120:123]
	v_mfma_f32_16x16x32_bf16 v[112:115], v[156:159], v[180:183], v[112:115]
	v_mfma_f32_16x16x32_bf16 v[104:107], v[164:167], v[180:183], v[104:107]
	v_mfma_f32_16x16x32_bf16 v[96:99], v[156:159], v[188:191], v[96:99]
	v_mfma_f32_16x16x32_bf16 v[88:91], v[164:167], v[188:191], v[88:91]
	v_mfma_f32_16x16x32_bf16 v[80:83], v[156:159], v[196:199], v[80:83]
	v_mfma_f32_16x16x32_bf16 v[72:75], v[164:167], v[196:199], v[72:75]
	s_barrier
	s_setprio 0
	s_add_i32 s54, s45, s30
	s_mov_b32 m0, s54
	ds_read_b128 v[202:205], v151
	ds_read_b128 v[206:209], v151 offset:1024
	ds_read_b128 v[210:213], v151 offset:2048
	ds_read_b128 v[214:217], v151 offset:3072
	global_load_lds_dwordx4 v130, s[24:25]
	s_add_i32 m0, s54, 0x2000
	s_nop 0
	global_load_lds_dwordx4 v134, s[24:25]
	s_waitcnt vmcnt(8)
	s_setprio 1
	s_barrier
; #define PG8_STAGE(bufoff, gbase, voff) do { _Pragma("unroll") for (int _i = 0; _i < 2; ++_i) \
;         __builtin_amdgcn_global_load_lds((const unsigned*)((const char*)(gbase) + (voff)[_i]), (LAS unsigned*)(lds + (bufoff) + ldsw + _i * 8192), 16, 0, 0); } while (0)
; #define PG8_LDA(dst, b, h) do { _Pragma("unroll") for (int m = 0; m < 4; ++m) _Pragma("unroll") for (int k = 0; k < 2; ++k) dst[m][k] = *(const LAS bf16x8*)(lds + PG8_SA(b, h) + aoff + m * 2048 + k * 1024); } while (0)
; #define PG8_LDB(dst, b, h) do { _Pragma("unroll") for (int n = 0; n < 2; ++n) _Pragma("unroll") for (int k = 0; k < 2; ++k) dst[n][k] = *(const LAS bf16x8*)(lds + PG8_SB(b, h) + boff + n * 2048 + k * 1024); } while (0)
; #define PG8_MMA(ai, bj, At, Bt) do { __builtin_amdgcn_s_setprio(1); _Pragma("unroll") for (int m = 0; m < 4; ++m) _Pragma("unroll") for (int n = 0; n < 2; ++n) _Pragma("unroll") for (int k = 0; k < 2; ++k) \
;         acc[ai][bj][m][n] = __builtin_amdgcn_mfma_f32_16x16x32_bf16(Bt[n][k], At[m][k], acc[ai][bj][m][n], 0, 0, 0); __builtin_amdgcn_s_setprio(0); } while (0)
; #define PG8_WAIT_V(n) asm volatile("s_waitcnt vmcnt(" #n ")" ::: "memory")
; #define PG8_WAIT_L(n) asm volatile("s_waitcnt lgkmcnt(" #n ")" ::: "memory")
; #define PG8_BAR __builtin_amdgcn_s_barrier()
; #define PG8_SCHED __builtin_amdgcn_sched_barrier(0)
; template <class Epi, class Sched>
; __device__ __forceinline__ void gemm_phase(LAS unsigned char* lds, const Gemm g, const Sched& S, const Epi& E) {
;     ...
;             PG8_BAR; PG8_WAIT_L(0); PG8_MMA(0, 1, At, B1); PG8_BAR;
;             PG8_LDA(At, 0, 1); PG8_STAGE(PG8_SA(0, 0), a2, voffA);
;             PG8_BAR; PG8_WAIT_L(0); PG8_MMA(1, 0, At, B0); PG8_BAR; PG8_SCHED;
;             PG8_STAGE(PG8_SB(0, 1), b2 + hstep, voffB);
;             PG8_WAIT_V(6); PG8_BAR; PG8_MMA(1, 1, At, B1); PG8_BAR;
;             PG8_LDB(B0, 1, 0); PG8_SCHED; PG8_LDA(At, 1, 0); PG8_STAGE(PG8_SA(0, 1), a2 + hstep, voffA);
	s_waitcnt lgkmcnt(0)
	v_mfma_f32_16x16x32_bf16 v[116:119], v[202:205], v[168:171], v[116:119]
	v_mfma_f32_16x16x32_bf16 v[108:111], v[210:213], v[168:171], v[108:111]
	v_mfma_f32_16x16x32_bf16 v[100:103], v[202:205], v[176:179], v[100:103]
	v_mfma_f32_16x16x32_bf16 v[92:95], v[210:213], v[176:179], v[92:95]
	v_mfma_f32_16x16x32_bf16 v[84:87], v[202:205], v[184:187], v[84:87]
	v_mfma_f32_16x16x32_bf16 v[76:79], v[210:213], v[184:187], v[76:79]
	v_mfma_f32_16x16x32_bf16 v[68:71], v[202:205], v[192:195], v[68:71]
	v_mfma_f32_16x16x32_bf16 v[64:67], v[210:213], v[192:195], v[64:67]
	v_mfma_f32_16x16x32_bf16 v[116:119], v[206:209], v[172:175], v[116:119]
	v_mfma_f32_16x16x32_bf16 v[108:111], v[214:217], v[172:175], v[108:111]
	v_mfma_f32_16x16x32_bf16 v[100:103], v[206:209], v[180:183], v[100:103]
	v_mfma_f32_16x16x32_bf16 v[92:95], v[214:217], v[180:183], v[92:95]
	v_mfma_f32_16x16x32_bf16 v[84:87], v[206:209], v[188:191], v[84:87]
	v_mfma_f32_16x16x32_bf16 v[76:79], v[214:217], v[188:191], v[76:79]
	v_mfma_f32_16x16x32_bf16 v[68:71], v[206:209], v[196:199], v[68:71]
	v_mfma_f32_16x16x32_bf16 v[64:67], v[214:217], v[196:199], v[64:67]
	s_mov_b32 m0, s21
	v_lshl_add_u64 v[222:223], s[26:27], 0, v[128:129]
	s_barrier
	s_setprio 0
	ds_read_b128 v[168:171], v150 offset:16384
	ds_read_b128 v[172:175], v150 offset:17408
	ds_read_b128 v[176:179], v150 offset:18432
	ds_read_b128 v[180:183], v150 offset:19456
	ds_read_b128 v[184:187], v150 offset:20480
	ds_read_b128 v[188:191], v150 offset:21504
	ds_read_b128 v[192:195], v150 offset:22528
	ds_read_b128 v[196:199], v150 offset:23552
	global_load_lds_dwordx4 v128, s[26:27]
	v_lshl_add_u64 v[224:225], s[26:27], 0, v[132:133]
	s_mov_b32 m0, s31
	s_nop 0
	global_load_lds_dwordx4 v132, s[26:27]
	s_setprio 1
	s_barrier
	s_waitcnt lgkmcnt(0)
	v_mfma_f32_16x16x32_bf16 v[60:63], v[152:155], v[168:171], v[60:63]
	v_mfma_f32_16x16x32_bf16 v[56:59], v[160:163], v[168:171], v[56:59]
	v_mfma_f32_16x16x32_bf16 v[48:51], v[152:155], v[176:179], v[48:51]
	v_mfma_f32_16x16x32_bf16 v[40:43], v[160:163], v[176:179], v[40:43]
	v_mfma_f32_16x16x32_bf16 v[32:35], v[152:155], v[184:187], v[32:35]
	v_mfma_f32_16x16x32_bf16 v[24:27], v[160:163], v[184:187], v[24:27]
	v_mfma_f32_16x16x32_bf16 v[16:19], v[152:155], v[192:195], v[16:19]
	v_mfma_f32_16x16x32_bf16 v[8:11], v[160:163], v[192:195], v[8:11]
	v_mfma_f32_16x16x32_bf16 v[60:63], v[156:159], v[172:175], v[60:63]
	v_mfma_f32_16x16x32_bf16 v[56:59], v[164:167], v[172:175], v[56:59]
	v_mfma_f32_16x16x32_bf16 v[48:51], v[156:159], v[180:183], v[48:51]
	v_mfma_f32_16x16x32_bf16 v[40:43], v[164:167], v[180:183], v[40:43]
	v_mfma_f32_16x16x32_bf16 v[32:35], v[156:159], v[188:191], v[32:35]
	v_mfma_f32_16x16x32_bf16 v[24:27], v[164:167], v[188:191], v[24:27]
	v_mfma_f32_16x16x32_bf16 v[16:19], v[156:159], v[196:199], v[16:19]
	v_mfma_f32_16x16x32_bf16 v[8:11], v[164:167], v[196:199], v[8:11]
	s_barrier
	s_setprio 0
	s_add_u32 s54, s24, 0x40000
	s_addc_u32 s55, s25, 0
	s_add_i32 s56, s46, s30
	s_mov_b32 m0, s56
	s_nop 0
	global_load_lds_dwordx4 v130, s[54:55]
	s_add_i32 m0, s56, 0x2000
	s_nop 0
	global_load_lds_dwordx4 v134, s[54:55]
	s_add_u32 s26, s26, 0x40000
	s_addc_u32 s27, s27, 0
	s_mov_b32 m0, s33
	s_nop 0
	global_load_lds_dwordx4 v128, s[26:27]
	s_mov_b32 m0, s34
	s_nop 0
	global_load_lds_dwordx4 v132, s[26:27]
	s_waitcnt vmcnt(10)
	s_setprio 1
	s_barrier
	v_mfma_f32_16x16x32_bf16 v[52:55], v[202:205], v[168:171], v[52:55]
	v_mfma_f32_16x16x32_bf16 v[44:47], v[210:213], v[168:171], v[44:47]
	v_mfma_f32_16x16x32_bf16 v[36:39], v[202:205], v[176:179], v[36:39]
	v_mfma_f32_16x16x32_bf16 v[28:31], v[210:213], v[176:179], v[28:31]
	v_mfma_f32_16x16x32_bf16 v[20:23], v[202:205], v[184:187], v[20:23]
	v_mfma_f32_16x16x32_bf16 v[12:15], v[210:213], v[184:187], v[12:15]
	v_mfma_f32_16x16x32_bf16 v[4:7], v[202:205], v[192:195], v[4:7]
	v_mfma_f32_16x16x32_bf16 v[0:3], v[210:213], v[192:195], v[0:3]
	v_mfma_f32_16x16x32_bf16 v[52:55], v[206:209], v[172:175], v[52:55]
	v_mfma_f32_16x16x32_bf16 v[44:47], v[214:217], v[172:175], v[44:47]
	v_mfma_f32_16x16x32_bf16 v[36:39], v[206:209], v[180:183], v[36:39]
	v_mfma_f32_16x16x32_bf16 v[28:31], v[214:217], v[180:183], v[28:31]
	v_mfma_f32_16x16x32_bf16 v[20:23], v[206:209], v[188:191], v[20:23]
	v_mfma_f32_16x16x32_bf16 v[12:15], v[214:217], v[188:191], v[12:15]
	v_mfma_f32_16x16x32_bf16 v[4:7], v[206:209], v[196:199], v[4:7]
	v_mfma_f32_16x16x32_bf16 v[0:3], v[214:217], v[196:199], v[0:3]
	s_add_i32 s54, 0, 0x18000
	v_add_u32_e32 v136, s54, v148
	s_barrier
	s_setprio 0
	ds_read_b128 v[152:155], v136
	ds_read_b128 v[156:159], v136 offset:1024
	ds_read_b128 v[160:163], v136 offset:2048
	ds_read_b128 v[164:167], v136 offset:3072
	ds_read_b128 v[168:171], v150 offset:32768
	ds_read_b128 v[172:175], v150 offset:33792
	ds_read_b128 v[176:179], v150 offset:34816
	ds_read_b128 v[180:183], v150 offset:35840
	ds_read_b128 v[184:187], v150 offset:36864
	ds_read_b128 v[188:191], v150 offset:37888
	ds_read_b128 v[192:195], v150 offset:38912
	ds_read_b128 v[196:199], v150 offset:39936
	s_waitcnt lgkmcnt(8)
	s_waitcnt vmcnt(8)
	s_setprio 1
	s_barrier
; #define PG8_STAGE(bufoff, gbase, voff) do { _Pragma("unroll") for (int _i = 0; _i < 2; ++_i) \
;         __builtin_amdgcn_global_load_lds((const unsigned*)((const char*)(gbase) + (voff)[_i]), (LAS unsigned*)(lds + (bufoff) + ldsw + _i * 8192), 16, 0, 0); } while (0)
; #define PG8_LDA(dst, b, h) do { _Pragma("unroll") for (int m = 0; m < 4; ++m) _Pragma("unroll") for (int k = 0; k < 2; ++k) dst[m][k] = *(const LAS bf16x8*)(lds + PG8_SA(b, h) + aoff + m * 2048 + k * 1024); } while (0)
; #define PG8_LDB(dst, b, h) do { _Pragma("unroll") for (int n = 0; n < 2; ++n) _Pragma("unroll") for (int k = 0; k < 2; ++k) dst[n][k] = *(const LAS bf16x8*)(lds + PG8_SB(b, h) + boff + n * 2048 + k * 1024); } while (0)
; #define PG8_MMA(ai, bj, At, Bt) do { __builtin_amdgcn_s_setprio(1); _Pragma("unroll") for (int m = 0; m < 4; ++m) _Pragma("unroll") for (int n = 0; n < 2; ++n) _Pragma("unroll") for (int k = 0; k < 2; ++k) \
;         acc[ai][bj][m][n] = __builtin_amdgcn_mfma_f32_16x16x32_bf16(Bt[n][k], At[m][k], acc[ai][bj][m][n], 0, 0, 0); __builtin_amdgcn_s_setprio(0); } while (0)
; #define PG8_WAIT_V(n) asm volatile("s_waitcnt vmcnt(" #n ")" ::: "memory")
; #define PG8_WAIT_L(n) asm volatile("s_waitcnt lgkmcnt(" #n ")" ::: "memory")
; #define PG8_BAR __builtin_amdgcn_s_barrier()
; #define PG8_SCHED __builtin_amdgcn_sched_barrier(0)
; template <class Epi, class Sched>
; __device__ __forceinline__ void gemm_phase(LAS unsigned char* lds, const Gemm g, const Sched& S, const Epi& E) {
;     ...
;             PG8_WAIT_L(8); PG8_BAR; PG8_WAIT_L(0); PG8_MMA(0, 0, At, B0); PG8_BAR; PG8_SCHED;
;             PG8_LDB(B1, 1, 1); PG8_STAGE(PG8_SB(1, 0), b3, voffB);
;             PG8_BAR; PG8_WAIT_L(0); PG8_MMA(0, 1, At, B1); PG8_BAR;
;             PG8_LDA(At, 1, 1); PG8_STAGE(PG8_SA(1, 0), a3, voffA);
;             PG8_BAR; PG8_WAIT_L(0); PG8_MMA(1, 0, At, B0); PG8_BAR; PG8_SCHED;
;             PG8_STAGE(PG8_SB(1, 1), b3 + hstep, voffB);
;             PG8_WAIT_V(6); PG8_BAR; PG8_MMA(1, 1, At, B1); PG8_BAR;
	s_waitcnt lgkmcnt(0)
	v_mfma_f32_16x16x32_bf16 v[124:127], v[152:155], v[168:171], v[124:127]
	v_mfma_f32_16x16x32_bf16 v[120:123], v[160:163], v[168:171], v[120:123]
	v_mfma_f32_16x16x32_bf16 v[112:115], v[152:155], v[176:179], v[112:115]
	v_mfma_f32_16x16x32_bf16 v[104:107], v[160:163], v[176:179], v[104:107]
	v_mfma_f32_16x16x32_bf16 v[96:99], v[152:155], v[184:187], v[96:99]
	v_mfma_f32_16x16x32_bf16 v[88:91], v[160:163], v[184:187], v[88:91]
	v_mfma_f32_16x16x32_bf16 v[80:83], v[152:155], v[192:195], v[80:83]
	v_mfma_f32_16x16x32_bf16 v[72:75], v[160:163], v[192:195], v[72:75]
	v_mfma_f32_16x16x32_bf16 v[124:127], v[156:159], v[172:175], v[124:127]
	v_mfma_f32_16x16x32_bf16 v[120:123], v[164:167], v[172:175], v[120:123]
	v_mfma_f32_16x16x32_bf16 v[112:115], v[156:159], v[180:183], v[112:115]
	v_mfma_f32_16x16x32_bf16 v[104:107], v[164:167], v[180:183], v[104:107]
	v_mfma_f32_16x16x32_bf16 v[96:99], v[156:159], v[188:191], v[96:99]
	v_mfma_f32_16x16x32_bf16 v[88:91], v[164:167], v[188:191], v[88:91]
	v_mfma_f32_16x16x32_bf16 v[80:83], v[156:159], v[196:199], v[80:83]
	v_mfma_f32_16x16x32_bf16 v[72:75], v[164:167], v[196:199], v[72:75]
	s_barrier
	s_setprio 0
	s_add_i32 s26, 0, 0x1c000
	s_add_i32 s27, s54, s30
	v_add_u32_e32 v136, s26, v148
	s_add_u32 s0, s24, 0x80
	s_addc_u32 s1, s25, 0
	s_mov_b32 m0, s27
	ds_read_b128 v[202:205], v136
	ds_read_b128 v[206:209], v136 offset:1024
	ds_read_b128 v[210:213], v136 offset:2048
	ds_read_b128 v[214:217], v136 offset:3072
	global_load_lds_dwordx4 v130, s[0:1]
	s_add_i32 m0, s27, 0x2000
	s_nop 0
	global_load_lds_dwordx4 v134, s[0:1]
	s_waitcnt vmcnt(8)
	s_setprio 1
	s_barrier
	s_waitcnt lgkmcnt(0)
	v_mfma_f32_16x16x32_bf16 v[116:119], v[202:205], v[168:171], v[116:119]
	v_mfma_f32_16x16x32_bf16 v[108:111], v[210:213], v[168:171], v[108:111]
	v_mfma_f32_16x16x32_bf16 v[100:103], v[202:205], v[176:179], v[100:103]
	v_mfma_f32_16x16x32_bf16 v[92:95], v[210:213], v[176:179], v[92:95]
	v_mfma_f32_16x16x32_bf16 v[84:87], v[202:205], v[184:187], v[84:87]
	v_mfma_f32_16x16x32_bf16 v[76:79], v[210:213], v[184:187], v[76:79]
	v_mfma_f32_16x16x32_bf16 v[68:71], v[202:205], v[192:195], v[68:71]
	v_mfma_f32_16x16x32_bf16 v[64:67], v[210:213], v[192:195], v[64:67]
	v_mfma_f32_16x16x32_bf16 v[116:119], v[206:209], v[172:175], v[116:119]
	v_mfma_f32_16x16x32_bf16 v[108:111], v[214:217], v[172:175], v[108:111]
	v_mfma_f32_16x16x32_bf16 v[100:103], v[206:209], v[180:183], v[100:103]
	v_mfma_f32_16x16x32_bf16 v[92:95], v[214:217], v[180:183], v[92:95]
	v_mfma_f32_16x16x32_bf16 v[84:87], v[206:209], v[188:191], v[84:87]
	v_mfma_f32_16x16x32_bf16 v[76:79], v[214:217], v[188:191], v[76:79]
	v_mfma_f32_16x16x32_bf16 v[68:71], v[206:209], v[196:199], v[68:71]
	v_mfma_f32_16x16x32_bf16 v[64:67], v[214:217], v[196:199], v[64:67]
	s_mov_b32 m0, s42
	s_mov_b64 s[0:1], 0x80
	v_lshl_add_u64 v[218:219], v[222:223], 0, s[0:1]
	s_barrier
	s_setprio 0
	ds_read_b128 v[168:171], v150 offset:49152
	ds_read_b128 v[172:175], v150 offset:50176
	ds_read_b128 v[176:179], v150 offset:51200
	ds_read_b128 v[180:183], v150 offset:52224
	ds_read_b128 v[184:187], v150 offset:53248
	ds_read_b128 v[188:191], v150 offset:54272
	ds_read_b128 v[192:195], v150 offset:55296
	ds_read_b128 v[196:199], v150 offset:56320
	global_load_lds_dwordx4 v[218:219], off
	v_lshl_add_u64 v[218:219], v[224:225], 0, s[0:1]
	s_mov_b32 m0, s43
	s_nop 0
	global_load_lds_dwordx4 v[218:219], off
	s_setprio 1
	s_barrier
	s_waitcnt lgkmcnt(0)
	v_mfma_f32_16x16x32_bf16 v[60:63], v[152:155], v[168:171], v[60:63]
	v_mfma_f32_16x16x32_bf16 v[56:59], v[160:163], v[168:171], v[56:59]
	v_mfma_f32_16x16x32_bf16 v[48:51], v[152:155], v[176:179], v[48:51]
	v_mfma_f32_16x16x32_bf16 v[40:43], v[160:163], v[176:179], v[40:43]
	v_mfma_f32_16x16x32_bf16 v[32:35], v[152:155], v[184:187], v[32:35]
	v_mfma_f32_16x16x32_bf16 v[24:27], v[160:163], v[184:187], v[24:27]
	v_mfma_f32_16x16x32_bf16 v[16:19], v[152:155], v[192:195], v[16:19]
	v_mfma_f32_16x16x32_bf16 v[8:11], v[160:163], v[192:195], v[8:11]
	v_mfma_f32_16x16x32_bf16 v[60:63], v[156:159], v[172:175], v[60:63]
	v_mfma_f32_16x16x32_bf16 v[56:59], v[164:167], v[172:175], v[56:59]
	v_mfma_f32_16x16x32_bf16 v[48:51], v[156:159], v[180:183], v[48:51]
	v_mfma_f32_16x16x32_bf16 v[40:43], v[164:167], v[180:183], v[40:43]
	v_mfma_f32_16x16x32_bf16 v[32:35], v[156:159], v[188:191], v[32:35]
	v_mfma_f32_16x16x32_bf16 v[24:27], v[164:167], v[188:191], v[24:27]
	v_mfma_f32_16x16x32_bf16 v[16:19], v[156:159], v[196:199], v[16:19]
	v_mfma_f32_16x16x32_bf16 v[8:11], v[164:167], v[196:199], v[8:11]
	s_barrier
	s_setprio 0
	s_add_u32 s24, s24, 0x40080
	s_addc_u32 s25, s25, 0
	s_add_i32 s26, s26, s30
	s_mov_b32 m0, s26
	s_nop 0
	global_load_lds_dwordx4 v130, s[24:25]
	s_add_i32 m0, s26, 0x2000
	s_nop 0
	global_load_lds_dwordx4 v134, s[24:25]
	s_waitcnt vmcnt(8)
	s_setprio 1
	s_barrier
	v_mfma_f32_16x16x32_bf16 v[52:55], v[202:205], v[168:171], v[52:55]
	v_mfma_f32_16x16x32_bf16 v[44:47], v[210:213], v[168:171], v[44:47]
	v_mfma_f32_16x16x32_bf16 v[36:39], v[202:205], v[176:179], v[36:39]
	v_mfma_f32_16x16x32_bf16 v[28:31], v[210:213], v[176:179], v[28:31]
	v_mfma_f32_16x16x32_bf16 v[20:23], v[202:205], v[184:187], v[20:23]
	v_mfma_f32_16x16x32_bf16 v[12:15], v[210:213], v[184:187], v[12:15]
	v_mfma_f32_16x16x32_bf16 v[4:7], v[202:205], v[192:195], v[4:7]
	v_mfma_f32_16x16x32_bf16 v[0:3], v[210:213], v[192:195], v[0:3]
	v_mfma_f32_16x16x32_bf16 v[52:55], v[206:209], v[172:175], v[52:55]
	v_mfma_f32_16x16x32_bf16 v[44:47], v[214:217], v[172:175], v[44:47]
	v_mfma_f32_16x16x32_bf16 v[36:39], v[206:209], v[180:183], v[36:39]
	v_mfma_f32_16x16x32_bf16 v[28:31], v[214:217], v[180:183], v[28:31]
	v_mfma_f32_16x16x32_bf16 v[20:23], v[206:209], v[188:191], v[20:23]
	v_mfma_f32_16x16x32_bf16 v[12:15], v[214:217], v[188:191], v[12:15]
	v_mfma_f32_16x16x32_bf16 v[4:7], v[206:209], v[196:199], v[4:7]
	v_mfma_f32_16x16x32_bf16 v[0:3], v[214:217], v[196:199], v[0:3]
	s_add_i32 s53, s53, 2
	s_add_u32 s22, s22, 0x100
	s_addc_u32 s23, s23, 0
	s_add_u32 s51, s51, 0x100
	s_addc_u32 s52, s52, 0
	s_cmp_gt_u32 s53, 13
	s_barrier
; __device__ __forceinline__ unsigned cvt_pk_bf16(float lo, float hi) { unsigned r; asm volatile("v_cvt_pk_bf16_f32 %0, %1, %2" : "=v"(r) : "v"(lo), "v"(hi)); return r; }
; #define PG8_MMA(ai, bj, At, Bt) do { __builtin_amdgcn_s_setprio(1); _Pragma("unroll") for (int m = 0; m < 4; ++m) _Pragma("unroll") for (int n = 0; n < 2; ++n) _Pragma("unroll") for (int k = 0; k < 2; ++k) \
;         acc[ai][bj][m][n] = __builtin_amdgcn_mfma_f32_16x16x32_bf16(Bt[n][k], At[m][k], acc[ai][bj][m][n], 0, 0, 0); __builtin_amdgcn_s_setprio(0); } while (0)
; #define PG8_WAIT_V(n) asm volatile("s_waitcnt vmcnt(" #n ")" ::: "memory")
; #define PG8_BAR __builtin_amdgcn_s_barrier()
; template <class Epi, class Sched>
; __device__ __forceinline__ void gemm_phase(LAS unsigned char* lds, const Gemm g, const Sched& S, const Epi& E) {
;     ...
;             PG8_WAIT_V(6); PG8_BAR; PG8_MMA(1, 1, At, B1); PG8_BAR;
;         }
;         E(acc, cur, wr, wc, fr, fq);
;         if (!has_next) break;
;     __device__ __forceinline__ void operator()(const AccT& acc, const Unit& u, int wr, int wc, int fr, int fq) const {
;     ...
;         const int rbase = u.pm * 256 + wr * 64 + fr;
;         const int tb = u.pn * 256 + wc * 32 + 8 * fq;
; #pragma unroll
;         for (int ai = 0; ai < 2; ++ai)
; #pragma unroll
;             for (int m = 0; m < 4; ++m) {
;                 const int gm = rbase + ai * 128 + m * 16;
; #pragma unroll
;                 for (int bj = 0; bj < 2; ++bj) {
;                     const int t0 = tb + bj * 128;
;                     const f32x4 v0 = acc[ai][bj][m][0], v1 = acc[ai][bj][m][1];
;                     u32x4 w; w.x = cvt_pk_bf16(v0[0], v0[1]); w.y = cvt_pk_bf16(v0[2], v0[3]); w.z = cvt_pk_bf16(v1[0], v1[1]); w.w = cvt_pk_bf16(v1[2], v1[3]);
;                     *(u32x4*)(YT + ((size_t)((t0 >> 10) * 512 + gm)) * 2048 + part * 1024 + (t0 & 1023)) = w;
;                 }
	s_setprio 0
	s_cbranch_scc0 .LBB0_653
	v_mov_b32_e32 v136, v147
	v_mov_b32_e32 v152, v146
	s_lshl_b32 s7, s20, 8
	s_add_i32 s7, s7, s36
	v_add_u32_e32 v152, s7, v152
	s_lshl_b32 s7, s47, 8
	s_or_b32 s7, s7, s37
	v_lshl_add_u32 v153, v136, 3, s7
	v_cvt_pk_bf16_f32 v124, v124, v125
	v_cvt_pk_bf16_f32 v125, v126, v127
	v_cvt_pk_bf16_f32 v126, v120, v121
	v_ashrrev_i32_e32 v120, 1, v153
	v_cvt_pk_bf16_f32 v127, v122, v123
	v_and_b32_e32 v122, 0xfffffe00, v120
	v_add_u32_e32 v120, v122, v152
	v_ashrrev_i32_e32 v121, 31, v120
	v_lshlrev_b64 v[120:121], 12, v[120:121]
	v_and_b32_e32 v123, 0x3f8, v153
	v_lshl_add_u64 v[120:121], s[68:69], 0, v[120:121]
	v_lshlrev_b32_e32 v136, 1, v123
	v_lshl_add_u64 v[120:121], v[120:121], 0, v[136:137]
	global_store_dwordx4 v[120:121], v[124:127], off
	v_add_u32_e32 v120, 0x80, v153
	v_cvt_pk_bf16_f32 v116, v116, v117
	v_cvt_pk_bf16_f32 v117, v118, v119
	v_cvt_pk_bf16_f32 v118, v108, v109
	v_ashrrev_i32_e32 v108, 1, v120
	v_and_b32_e32 v121, 0xfffffe00, v108
	v_add_u32_e32 v108, v121, v152
	v_ashrrev_i32_e32 v109, 31, v108
	v_lshlrev_b64 v[108:109], 12, v[108:109]
	v_cvt_pk_bf16_f32 v119, v110, v111
	v_lshl_add_u64 v[110:111], s[68:69], 0, v[108:109]
	v_and_b32_e32 v108, 0x3f8, v120
	v_lshlrev_b32_e32 v108, 1, v108
	v_mov_b32_e32 v109, v137
	v_lshl_add_u64 v[110:111], v[110:111], 0, v[108:109]
	global_store_dwordx4 v[110:111], v[116:119], off
	v_cvt_pk_bf16_f32 v110, v112, v113
	v_cvt_pk_bf16_f32 v111, v114, v115
	v_cvt_pk_bf16_f32 v112, v104, v105
	v_cvt_pk_bf16_f32 v113, v106, v107
	s_and_b64 vcc, exec, s[4:5]
	s_nop 0
	v_add_u32_e32 v116, 16, v152
	v_add_u32_e32 v104, v122, v116
	v_ashrrev_i32_e32 v105, 31, v104
	v_lshlrev_b64 v[104:105], 12, v[104:105]
	v_lshl_add_u64 v[104:105], s[68:69], 0, v[104:105]
	v_lshl_add_u64 v[104:105], v[104:105], 0, v[136:137]
	global_store_dwordx4 v[104:105], v[110:113], off
	v_cvt_pk_bf16_f32 v100, v100, v101
	v_cvt_pk_bf16_f32 v101, v102, v103
	v_cvt_pk_bf16_f32 v102, v92, v93
	v_add_u32_e32 v92, v121, v116
	v_ashrrev_i32_e32 v93, 31, v92
	v_lshlrev_b64 v[92:93], 12, v[92:93]
	v_lshl_add_u64 v[92:93], s[68:69], 0, v[92:93]
	v_lshl_add_u64 v[92:93], v[92:93], 0, v[108:109]
	v_cvt_pk_bf16_f32 v103, v94, v95
	global_store_dwordx4 v[92:93], v[100:103], off
	v_cvt_pk_bf16_f32 v92, v96, v97
	v_cvt_pk_bf16_f32 v93, v98, v99
	v_cvt_pk_bf16_f32 v94, v88, v89
	v_cvt_pk_bf16_f32 v95, v90, v91
	s_mov_b32 s47, s6
	s_nop 0
	v_add_u32_e32 v100, 32, v152
	v_add_u32_e32 v88, v122, v100
	v_ashrrev_i32_e32 v89, 31, v88
	v_lshlrev_b64 v[88:89], 12, v[88:89]
	v_lshl_add_u64 v[88:89], s[68:69], 0, v[88:89]
	v_lshl_add_u64 v[88:89], v[88:89], 0, v[136:137]
	global_store_dwordx4 v[88:89], v[92:95], off
	v_cvt_pk_bf16_f32 v84, v84, v85
	v_cvt_pk_bf16_f32 v85, v86, v87
	v_cvt_pk_bf16_f32 v86, v76, v77
	v_add_u32_e32 v76, v121, v100
	v_ashrrev_i32_e32 v77, 31, v76
	v_lshlrev_b64 v[76:77], 12, v[76:77]
	v_lshl_add_u64 v[76:77], s[68:69], 0, v[76:77]
	v_lshl_add_u64 v[76:77], v[76:77], 0, v[108:109]
	v_cvt_pk_bf16_f32 v87, v78, v79
	global_store_dwordx4 v[76:77], v[84:87], off
	v_cvt_pk_bf16_f32 v76, v80, v81
	v_cvt_pk_bf16_f32 v77, v82, v83
	v_cvt_pk_bf16_f32 v78, v72, v73
	v_cvt_pk_bf16_f32 v79, v74, v75
	s_mov_b32 s20, s8
	s_nop 0
	v_add_u32_e32 v84, 48, v152
	v_add_u32_e32 v72, v122, v84
	v_ashrrev_i32_e32 v73, 31, v72
	v_lshlrev_b64 v[72:73], 12, v[72:73]
	v_lshl_add_u64 v[72:73], s[68:69], 0, v[72:73]
	v_lshl_add_u64 v[72:73], v[72:73], 0, v[136:137]
	global_store_dwordx4 v[72:73], v[76:79], off
	v_cvt_pk_bf16_f32 v68, v68, v69
	v_cvt_pk_bf16_f32 v69, v70, v71
; __device__ __forceinline__ unsigned cvt_pk_bf16(float lo, float hi) { unsigned r; asm volatile("v_cvt_pk_bf16_f32 %0, %1, %2" : "=v"(r) : "v"(lo), "v"(hi)); return r; }
; #define PG8_WAIT_V(n) asm volatile("s_waitcnt vmcnt(" #n ")" ::: "memory")
; #define PG8_BAR __builtin_amdgcn_s_barrier()
; template <class Epi, class Sched>
; __device__ __forceinline__ void gemm_phase(LAS unsigned char* lds, const Gemm g, const Sched& S, const Epi& E) {
;     ...
;     PG8_WAIT_V(0);
;     if (wr == 0) PG8_BAR;
;     __device__ __forceinline__ void operator()(const AccT& acc, const Unit& u, int wr, int wc, int fr, int fq) const {
;     ...
;                 const int gm = rbase + ai * 128 + m * 16;
; #pragma unroll
;                 for (int bj = 0; bj < 2; ++bj) {
;                     const int t0 = tb + bj * 128;
;                     const f32x4 v0 = acc[ai][bj][m][0], v1 = acc[ai][bj][m][1];
;                     u32x4 w; w.x = cvt_pk_bf16(v0[0], v0[1]); w.y = cvt_pk_bf16(v0[2], v0[3]); w.z = cvt_pk_bf16(v1[0], v1[1]); w.w = cvt_pk_bf16(v1[2], v1[3]);
;                     *(u32x4*)(YT + ((size_t)((t0 >> 10) * 512 + gm)) * 2048 + part * 1024 + (t0 & 1023)) = w;
;                 }
	v_cvt_pk_bf16_f32 v70, v64, v65
	v_add_u32_e32 v64, v121, v84
	v_ashrrev_i32_e32 v65, 31, v64
	v_lshlrev_b64 v[64:65], 12, v[64:65]
	v_lshl_add_u64 v[64:65], s[68:69], 0, v[64:65]
	v_lshl_add_u64 v[64:65], v[64:65], 0, v[108:109]
	v_cvt_pk_bf16_f32 v71, v66, v67
	global_store_dwordx4 v[64:65], v[68:71], off
	v_add_u32_e32 v64, 0x80, v152
	v_cvt_pk_bf16_f32 v60, v60, v61
	v_cvt_pk_bf16_f32 v61, v62, v63
	v_cvt_pk_bf16_f32 v62, v56, v57
	v_add_u32_e32 v56, v122, v64
	v_ashrrev_i32_e32 v57, 31, v56
	v_lshlrev_b64 v[56:57], 12, v[56:57]
	v_lshl_add_u64 v[56:57], s[68:69], 0, v[56:57]
	v_lshl_add_u64 v[56:57], v[56:57], 0, v[136:137]
	v_cvt_pk_bf16_f32 v63, v58, v59
	global_store_dwordx4 v[56:57], v[60:63], off
	v_cvt_pk_bf16_f32 v52, v52, v53
	v_cvt_pk_bf16_f32 v53, v54, v55
	v_cvt_pk_bf16_f32 v54, v44, v45
	v_add_u32_e32 v44, v121, v64
	v_ashrrev_i32_e32 v45, 31, v44
	v_lshlrev_b64 v[44:45], 12, v[44:45]
	v_lshl_add_u64 v[44:45], s[68:69], 0, v[44:45]
	v_lshl_add_u64 v[44:45], v[44:45], 0, v[108:109]
	v_cvt_pk_bf16_f32 v55, v46, v47
	global_store_dwordx4 v[44:45], v[52:55], off
	v_cvt_pk_bf16_f32 v44, v48, v49
	v_cvt_pk_bf16_f32 v45, v50, v51
	v_cvt_pk_bf16_f32 v46, v40, v41
	v_cvt_pk_bf16_f32 v47, v42, v43
	s_mov_b64 s[24:25], s[18:19]
	s_nop 0
	v_add_u32_e32 v52, 0x90, v152
	v_add_u32_e32 v40, v122, v52
	v_ashrrev_i32_e32 v41, 31, v40
	v_lshlrev_b64 v[40:41], 12, v[40:41]
	v_lshl_add_u64 v[40:41], s[68:69], 0, v[40:41]
	v_lshl_add_u64 v[40:41], v[40:41], 0, v[136:137]
	global_store_dwordx4 v[40:41], v[44:47], off
	v_cvt_pk_bf16_f32 v36, v36, v37
	v_cvt_pk_bf16_f32 v37, v38, v39
	v_cvt_pk_bf16_f32 v38, v28, v29
	v_add_u32_e32 v28, v121, v52
	v_ashrrev_i32_e32 v29, 31, v28
	v_lshlrev_b64 v[28:29], 12, v[28:29]
	v_lshl_add_u64 v[28:29], s[68:69], 0, v[28:29]
	v_lshl_add_u64 v[28:29], v[28:29], 0, v[108:109]
	v_cvt_pk_bf16_f32 v39, v30, v31
	global_store_dwordx4 v[28:29], v[36:39], off
	v_cvt_pk_bf16_f32 v28, v32, v33
	v_cvt_pk_bf16_f32 v29, v34, v35
	v_cvt_pk_bf16_f32 v30, v24, v25
	v_cvt_pk_bf16_f32 v31, v26, v27
	s_mov_b64 s[22:23], s[16:17]
	s_nop 0
	v_add_u32_e32 v36, 0xa0, v152
	v_add_u32_e32 v24, v122, v36
	v_ashrrev_i32_e32 v25, 31, v24
	v_lshlrev_b64 v[24:25], 12, v[24:25]
	v_lshl_add_u64 v[24:25], s[68:69], 0, v[24:25]
	v_lshl_add_u64 v[24:25], v[24:25], 0, v[136:137]
	global_store_dwordx4 v[24:25], v[28:31], off
	v_cvt_pk_bf16_f32 v20, v20, v21
	v_cvt_pk_bf16_f32 v21, v22, v23
	v_cvt_pk_bf16_f32 v22, v12, v13
	v_add_u32_e32 v12, v121, v36
	v_ashrrev_i32_e32 v13, 31, v12
	v_lshlrev_b64 v[12:13], 12, v[12:13]
	v_lshl_add_u64 v[12:13], s[68:69], 0, v[12:13]
	v_lshl_add_u64 v[12:13], v[12:13], 0, v[108:109]
	v_cvt_pk_bf16_f32 v23, v14, v15
	global_store_dwordx4 v[12:13], v[20:23], off
	v_cvt_pk_bf16_f32 v12, v16, v17
	v_cvt_pk_bf16_f32 v13, v18, v19
	v_cvt_pk_bf16_f32 v14, v8, v9
	v_cvt_pk_bf16_f32 v15, v10, v11
	s_nop 1
	v_add_u32_e32 v20, 0xb0, v152
	v_add_u32_e32 v8, v122, v20
	v_ashrrev_i32_e32 v9, 31, v8
	v_lshlrev_b64 v[8:9], 12, v[8:9]
	v_lshl_add_u64 v[8:9], s[68:69], 0, v[8:9]
	v_lshl_add_u64 v[8:9], v[8:9], 0, v[136:137]
	global_store_dwordx4 v[8:9], v[12:15], off
	v_cvt_pk_bf16_f32 v4, v4, v5
	v_cvt_pk_bf16_f32 v5, v6, v7
	v_cvt_pk_bf16_f32 v6, v0, v1
	v_add_u32_e32 v0, v121, v20
	v_ashrrev_i32_e32 v1, 31, v0
	v_lshlrev_b64 v[0:1], 12, v[0:1]
	v_lshl_add_u64 v[0:1], s[68:69], 0, v[0:1]
	v_lshl_add_u64 v[0:1], v[0:1], 0, v[108:109]
	v_cvt_pk_bf16_f32 v7, v2, v3
	global_store_dwordx4 v[0:1], v[4:7], off
	s_cbranch_vccz .LBB0_646
	s_waitcnt vmcnt(0)
	s_cmpk_gt_u32 s28, 0xff
	s_cbranch_scc1 .LBB0_657
	s_barrier

; #define PG8_STAGE(bufoff, gbase, voff) do { _Pragma("unroll") for (int _i = 0; _i < 2; ++_i) \
;         __builtin_amdgcn_global_load_lds((const unsigned*)((const char*)(gbase) + (voff)[_i]), (LAS unsigned*)(lds + (bufoff) + ldsw + _i * 8192), 16, 0, 0); } while (0)
; #define PG8_LDA(dst, b, h) do { _Pragma("unroll") for (int m = 0; m < 4; ++m) _Pragma("unroll") for (int k = 0; k < 2; ++k) dst[m][k] = *(const LAS bf16x8*)(lds + PG8_SA(b, h) + aoff + m * 2048 + k * 1024); } while (0)
; #define PG8_LDB(dst, b, h) do { _Pragma("unroll") for (int n = 0; n < 2; ++n) _Pragma("unroll") for (int k = 0; k < 2; ++k) dst[n][k] = *(const LAS bf16x8*)(lds + PG8_SB(b, h) + boff + n * 2048 + k * 1024); } while (0)
; #define PG8_MMA(ai, bj, At, Bt) do { __builtin_amdgcn_s_setprio(1); _Pragma("unroll") for (int m = 0; m < 4; ++m) _Pragma("unroll") for (int n = 0; n < 2; ++n) _Pragma("unroll") for (int k = 0; k < 2; ++k) \
;         acc[ai][bj][m][n] = __builtin_amdgcn_mfma_f32_16x16x32_bf16(Bt[n][k], At[m][k], acc[ai][bj][m][n], 0, 0, 0); __builtin_amdgcn_s_setprio(0); } while (0)
; #define PG8_WAIT_L(n) asm volatile("s_waitcnt lgkmcnt(" #n ")" ::: "memory")
; template <class Epi, class Sched>
; __device__ __forceinline__ void gemm_phase(LAS unsigned char* lds, const Gemm g, const Sched& S, const Epi& E) {
;     ...
;         const bool has_next = S.next(ui + 1, nxt);
;         const char* nA = has_next ? (const char*)g.A + (size_t)nxt.pm * tstep : cA; const char* nB = has_next ? (const char*)g.Bt + (size_t)nxt.pn * tstep : cB;
;         for (int t = 0; t < nt; t += 2) {
;             const bool last = (t == nt - 2);
;             const char* a1 = cA + (size_t)(t + 1) * kstep;
;             const char* a2 = last ? nA : cA + (size_t)(t + 2) * kstep; const char* b2 = last ? nB : cB + (size_t)(t + 2) * kstep;
;             const char* a3 = a2 + kstep; const char* b3 = b2 + kstep;
;             PG8_LDB(B0, 0, 0); PG8_SCHED; PG8_LDA(At, 0, 0); PG8_STAGE(PG8_SA(1, 1), a1 + hstep, voffA);
;             PG8_WAIT_L(8); PG8_BAR; PG8_WAIT_L(0); PG8_MMA(0, 0, At, B0); PG8_BAR; PG8_SCHED;
;             PG8_LDB(B1, 0, 1); PG8_STAGE(PG8_SB(0, 0), b2, voffB);
;             PG8_BAR; PG8_WAIT_L(0); PG8_MMA(0, 1, At, B1); PG8_BAR;
;             PG8_LDA(At, 0, 1); PG8_STAGE(PG8_SA(0, 0), a2, voffA);
;             PG8_BAR; PG8_WAIT_L(0); PG8_MMA(1, 0, At, B0); PG8_BAR; PG8_SCHED;
.LBB0_672:
	s_ashr_i32 s9, s8, 31
	v_cmp_lt_i64_e32 vcc, s[12:13], v[142:143]
	s_lshl_b64 s[12:13], s[8:9], 19
	s_add_u32 s12, s26, s12
	s_addc_u32 s13, s27, s13
	s_and_b64 s[14:15], vcc, exec
	s_cselect_b32 s9, s13, s19
	s_cselect_b32 s46, s12, s18
	s_ashr_i32 s7, s6, 31
	s_lshl_b64 s[14:15], s[6:7], 19
	s_add_u32 s14, s10, s14
	s_addc_u32 s15, s11, s15
	s_and_b64 s[22:23], vcc, exec
	s_cselect_b32 s7, s15, s21
	s_cselect_b32 s47, s14, s20
	s_add_u32 s18, s18, 0x40080
	s_addc_u32 s19, s19, 0
	s_add_u32 s48, s20, 0x100
	s_addc_u32 s49, s21, 0
	s_mov_b32 s51, -2
	s_waitcnt lgkmcnt(0)
	ds_read_b128 v[152:155], v149
	ds_read_b128 v[156:159], v149 offset:1024
	ds_read_b128 v[160:163], v149 offset:2048
	ds_read_b128 v[164:167], v149 offset:3072
	s_add_u32 s20, s18, 0xfffc0080
	s_addc_u32 s21, s19, -1
	s_cmp_eq_u32 s51, 12
	s_cselect_b32 s23, s9, s21
	s_cselect_b32 s22, s46, s20
	s_cselect_b32 s21, s7, s49
	s_cselect_b32 s20, s47, s48
	s_add_i32 m0, s17, 0xc000
	ds_read_b128 v[168:171], v150
	ds_read_b128 v[172:175], v150 offset:1024
	ds_read_b128 v[176:179], v150 offset:2048
	ds_read_b128 v[180:183], v150 offset:3072
	ds_read_b128 v[184:187], v150 offset:4096
	ds_read_b128 v[188:191], v150 offset:5120
	ds_read_b128 v[192:195], v150 offset:6144
	ds_read_b128 v[196:199], v150 offset:7168
	global_load_lds_dwordx4 v138, s[18:19]
	s_add_i32 m0, s17, 0xe000
	s_nop 0
	global_load_lds_dwordx4 v140, s[18:19]
	s_waitcnt lgkmcnt(8)
	s_waitcnt vmcnt(8)
	s_setprio 1
	s_barrier
	s_waitcnt lgkmcnt(0)
	v_mfma_f32_16x16x32_bf16 v[124:127], v[152:155], v[168:171], 0
	v_mfma_f32_16x16x32_bf16 v[120:123], v[160:163], v[168:171], 0
	v_mfma_f32_16x16x32_bf16 v[112:115], v[152:155], v[176:179], 0
	v_mfma_f32_16x16x32_bf16 v[104:107], v[160:163], v[176:179], 0
	v_mfma_f32_16x16x32_bf16 v[96:99], v[152:155], v[184:187], 0
	v_mfma_f32_16x16x32_bf16 v[88:91], v[160:163], v[184:187], 0
	v_mfma_f32_16x16x32_bf16 v[80:83], v[152:155], v[192:195], 0
	v_mfma_f32_16x16x32_bf16 v[72:75], v[160:163], v[192:195], 0
	v_mfma_f32_16x16x32_bf16 v[124:127], v[156:159], v[172:175], v[124:127]
	v_mfma_f32_16x16x32_bf16 v[120:123], v[164:167], v[172:175], v[120:123]
	v_mfma_f32_16x16x32_bf16 v[112:115], v[156:159], v[180:183], v[112:115]
	v_mfma_f32_16x16x32_bf16 v[104:107], v[164:167], v[180:183], v[104:107]
	v_mfma_f32_16x16x32_bf16 v[96:99], v[156:159], v[188:191], v[96:99]
	v_mfma_f32_16x16x32_bf16 v[88:91], v[164:167], v[188:191], v[88:91]
	v_mfma_f32_16x16x32_bf16 v[80:83], v[156:159], v[196:199], v[80:83]
	v_mfma_f32_16x16x32_bf16 v[72:75], v[164:167], v[196:199], v[72:75]
	s_barrier
	s_setprio 0
	s_add_i32 s52, s43, s28
	s_mov_b32 m0, s52
	ds_read_b128 v[202:205], v151
	ds_read_b128 v[206:209], v151 offset:1024
	ds_read_b128 v[210:213], v151 offset:2048
	ds_read_b128 v[214:217], v151 offset:3072
	global_load_lds_dwordx4 v130, s[20:21]
	s_add_i32 m0, s52, 0x2000
	s_nop 0
	global_load_lds_dwordx4 v134, s[20:21]
	s_waitcnt vmcnt(8)
	s_setprio 1
	s_barrier
	s_waitcnt lgkmcnt(0)
	v_mfma_f32_16x16x32_bf16 v[116:119], v[202:205], v[168:171], 0
	v_mfma_f32_16x16x32_bf16 v[108:111], v[210:213], v[168:171], 0
	v_mfma_f32_16x16x32_bf16 v[100:103], v[202:205], v[176:179], 0
	v_mfma_f32_16x16x32_bf16 v[92:95], v[210:213], v[176:179], 0
	v_mfma_f32_16x16x32_bf16 v[84:87], v[202:205], v[184:187], 0
	v_mfma_f32_16x16x32_bf16 v[76:79], v[210:213], v[184:187], 0
	v_mfma_f32_16x16x32_bf16 v[68:71], v[202:205], v[192:195], 0
	v_mfma_f32_16x16x32_bf16 v[64:67], v[210:213], v[192:195], 0
	v_mfma_f32_16x16x32_bf16 v[116:119], v[206:209], v[172:175], v[116:119]
	v_mfma_f32_16x16x32_bf16 v[108:111], v[214:217], v[172:175], v[108:111]
	v_mfma_f32_16x16x32_bf16 v[100:103], v[206:209], v[180:183], v[100:103]
	v_mfma_f32_16x16x32_bf16 v[92:95], v[214:217], v[180:183], v[92:95]
	v_mfma_f32_16x16x32_bf16 v[84:87], v[206:209], v[188:191], v[84:87]
	v_mfma_f32_16x16x32_bf16 v[76:79], v[214:217], v[188:191], v[76:79]
	v_mfma_f32_16x16x32_bf16 v[68:71], v[206:209], v[196:199], v[68:71]
	v_mfma_f32_16x16x32_bf16 v[64:67], v[214:217], v[196:199], v[64:67]
	s_mov_b32 m0, s17
	v_lshl_add_u64 v[222:223], s[22:23], 0, v[128:129]
	s_barrier
	s_setprio 0
	ds_read_b128 v[168:171], v150 offset:16384
	ds_read_b128 v[172:175], v150 offset:17408
	ds_read_b128 v[176:179], v150 offset:18432
	ds_read_b128 v[180:183], v150 offset:19456
	ds_read_b128 v[184:187], v150 offset:20480
	ds_read_b128 v[188:191], v150 offset:21504
	ds_read_b128 v[192:195], v150 offset:22528
	ds_read_b128 v[196:199], v150 offset:23552
	global_load_lds_dwordx4 v128, s[22:23]
	v_lshl_add_u64 v[224:225], s[22:23], 0, v[132:133]
	s_mov_b32 m0, s29
	s_nop 0
	global_load_lds_dwordx4 v132, s[22:23]
	s_setprio 1
	s_barrier
	s_waitcnt lgkmcnt(0)
	v_mfma_f32_16x16x32_bf16 v[60:63], v[152:155], v[168:171], 0
	v_mfma_f32_16x16x32_bf16 v[56:59], v[160:163], v[168:171], 0
	v_mfma_f32_16x16x32_bf16 v[48:51], v[152:155], v[176:179], 0
	v_mfma_f32_16x16x32_bf16 v[40:43], v[160:163], v[176:179], 0
	v_mfma_f32_16x16x32_bf16 v[32:35], v[152:155], v[184:187], 0
	v_mfma_f32_16x16x32_bf16 v[24:27], v[160:163], v[184:187], 0
	v_mfma_f32_16x16x32_bf16 v[16:19], v[152:155], v[192:195], 0
	v_mfma_f32_16x16x32_bf16 v[8:11], v[160:163], v[192:195], 0
	v_mfma_f32_16x16x32_bf16 v[60:63], v[156:159], v[172:175], v[60:63]
	v_mfma_f32_16x16x32_bf16 v[56:59], v[164:167], v[172:175], v[56:59]
	v_mfma_f32_16x16x32_bf16 v[48:51], v[156:159], v[180:183], v[48:51]
	v_mfma_f32_16x16x32_bf16 v[40:43], v[164:167], v[180:183], v[40:43]
	v_mfma_f32_16x16x32_bf16 v[32:35], v[156:159], v[188:191], v[32:35]
	v_mfma_f32_16x16x32_bf16 v[24:27], v[164:167], v[188:191], v[24:27]
	v_mfma_f32_16x16x32_bf16 v[16:19], v[156:159], v[196:199], v[16:19]
	v_mfma_f32_16x16x32_bf16 v[8:11], v[164:167], v[196:199], v[8:11]
	s_barrier
; #define PG8_STAGE(bufoff, gbase, voff) do { _Pragma("unroll") for (int _i = 0; _i < 2; ++_i) \
;         __builtin_amdgcn_global_load_lds((const unsigned*)((const char*)(gbase) + (voff)[_i]), (LAS unsigned*)(lds + (bufoff) + ldsw + _i * 8192), 16, 0, 0); } while (0)
; #define PG8_LDA(dst, b, h) do { _Pragma("unroll") for (int m = 0; m < 4; ++m) _Pragma("unroll") for (int k = 0; k < 2; ++k) dst[m][k] = *(const LAS bf16x8*)(lds + PG8_SA(b, h) + aoff + m * 2048 + k * 1024); } while (0)
; #define PG8_LDB(dst, b, h) do { _Pragma("unroll") for (int n = 0; n < 2; ++n) _Pragma("unroll") for (int k = 0; k < 2; ++k) dst[n][k] = *(const LAS bf16x8*)(lds + PG8_SB(b, h) + boff + n * 2048 + k * 1024); } while (0)
; #define PG8_MMA(ai, bj, At, Bt) do { __builtin_amdgcn_s_setprio(1); _Pragma("unroll") for (int m = 0; m < 4; ++m) _Pragma("unroll") for (int n = 0; n < 2; ++n) _Pragma("unroll") for (int k = 0; k < 2; ++k) \
;         acc[ai][bj][m][n] = __builtin_amdgcn_mfma_f32_16x16x32_bf16(Bt[n][k], At[m][k], acc[ai][bj][m][n], 0, 0, 0); __builtin_amdgcn_s_setprio(0); } while (0)
; #define PG8_WAIT_V(n) asm volatile("s_waitcnt vmcnt(" #n ")" ::: "memory")
; #define PG8_WAIT_L(n) asm volatile("s_waitcnt lgkmcnt(" #n ")" ::: "memory")
; #define PG8_BAR __builtin_amdgcn_s_barrier()
; #define PG8_SCHED __builtin_amdgcn_sched_barrier(0)
; template <class Epi, class Sched>
; __device__ __forceinline__ void gemm_phase(LAS unsigned char* lds, const Gemm g, const Sched& S, const Epi& E) {
;     ...
;             PG8_STAGE(PG8_SB(0, 1), b2 + hstep, voffB);
;             PG8_WAIT_V(6); PG8_BAR; PG8_MMA(1, 1, At, B1); PG8_BAR;
;             PG8_LDB(B0, 1, 0); PG8_SCHED; PG8_LDA(At, 1, 0); PG8_STAGE(PG8_SA(0, 1), a2 + hstep, voffA);
;             PG8_WAIT_L(8); PG8_BAR; PG8_WAIT_L(0); PG8_MMA(0, 0, At, B0); PG8_BAR; PG8_SCHED;
;             PG8_LDB(B1, 1, 1); PG8_STAGE(PG8_SB(1, 0), b3, voffB);
;             PG8_BAR; PG8_WAIT_L(0); PG8_MMA(0, 1, At, B1); PG8_BAR;
;             PG8_LDA(At, 1, 1); PG8_STAGE(PG8_SA(1, 0), a3, voffA);
;             PG8_BAR; PG8_WAIT_L(0); PG8_MMA(1, 0, At, B0); PG8_BAR; PG8_SCHED;
	s_setprio 0
	s_add_u32 s52, s20, 0x40000
	s_addc_u32 s53, s21, 0
	s_add_i32 s54, s44, s28
	s_mov_b32 m0, s54
	s_nop 0
	global_load_lds_dwordx4 v130, s[52:53]
	s_add_i32 m0, s54, 0x2000
	s_nop 0
	global_load_lds_dwordx4 v134, s[52:53]
	s_add_u32 s22, s22, 0x40000
	s_addc_u32 s23, s23, 0
	s_mov_b32 m0, s30
	s_nop 0
	global_load_lds_dwordx4 v128, s[22:23]
	s_mov_b32 m0, s31
	s_nop 0
	global_load_lds_dwordx4 v132, s[22:23]
	s_waitcnt vmcnt(10)
	s_setprio 1
	s_barrier
	v_mfma_f32_16x16x32_bf16 v[52:55], v[202:205], v[168:171], 0
	v_mfma_f32_16x16x32_bf16 v[44:47], v[210:213], v[168:171], 0
	v_mfma_f32_16x16x32_bf16 v[36:39], v[202:205], v[176:179], 0
	v_mfma_f32_16x16x32_bf16 v[28:31], v[210:213], v[176:179], 0
	v_mfma_f32_16x16x32_bf16 v[20:23], v[202:205], v[184:187], 0
	v_mfma_f32_16x16x32_bf16 v[12:15], v[210:213], v[184:187], 0
	v_mfma_f32_16x16x32_bf16 v[4:7], v[202:205], v[192:195], 0
	v_mfma_f32_16x16x32_bf16 v[0:3], v[210:213], v[192:195], 0
	v_mfma_f32_16x16x32_bf16 v[52:55], v[206:209], v[172:175], v[52:55]
	v_mfma_f32_16x16x32_bf16 v[44:47], v[214:217], v[172:175], v[44:47]
	v_mfma_f32_16x16x32_bf16 v[36:39], v[206:209], v[180:183], v[36:39]
	v_mfma_f32_16x16x32_bf16 v[28:31], v[214:217], v[180:183], v[28:31]
	v_mfma_f32_16x16x32_bf16 v[20:23], v[206:209], v[188:191], v[20:23]
	v_mfma_f32_16x16x32_bf16 v[12:15], v[214:217], v[188:191], v[12:15]
	v_mfma_f32_16x16x32_bf16 v[4:7], v[206:209], v[196:199], v[4:7]
	v_mfma_f32_16x16x32_bf16 v[0:3], v[214:217], v[196:199], v[0:3]
	s_add_i32 s52, 0, 0x18000
	v_add_u32_e32 v136, s52, v148
	s_barrier
	s_setprio 0
	ds_read_b128 v[152:155], v136
	ds_read_b128 v[156:159], v136 offset:1024
	ds_read_b128 v[160:163], v136 offset:2048
	ds_read_b128 v[164:167], v136 offset:3072
	ds_read_b128 v[168:171], v150 offset:32768
	ds_read_b128 v[172:175], v150 offset:33792
	ds_read_b128 v[176:179], v150 offset:34816
	ds_read_b128 v[180:183], v150 offset:35840
	ds_read_b128 v[184:187], v150 offset:36864
	ds_read_b128 v[188:191], v150 offset:37888
	ds_read_b128 v[192:195], v150 offset:38912
	ds_read_b128 v[196:199], v150 offset:39936
	s_waitcnt lgkmcnt(8)
	s_waitcnt vmcnt(8)
	s_setprio 1
	s_barrier
	s_waitcnt lgkmcnt(0)
	v_mfma_f32_16x16x32_bf16 v[124:127], v[152:155], v[168:171], v[124:127]
	v_mfma_f32_16x16x32_bf16 v[120:123], v[160:163], v[168:171], v[120:123]
	v_mfma_f32_16x16x32_bf16 v[112:115], v[152:155], v[176:179], v[112:115]
	v_mfma_f32_16x16x32_bf16 v[104:107], v[160:163], v[176:179], v[104:107]
	v_mfma_f32_16x16x32_bf16 v[96:99], v[152:155], v[184:187], v[96:99]
	v_mfma_f32_16x16x32_bf16 v[88:91], v[160:163], v[184:187], v[88:91]
	v_mfma_f32_16x16x32_bf16 v[80:83], v[152:155], v[192:195], v[80:83]
	v_mfma_f32_16x16x32_bf16 v[72:75], v[160:163], v[192:195], v[72:75]
	v_mfma_f32_16x16x32_bf16 v[124:127], v[156:159], v[172:175], v[124:127]
	v_mfma_f32_16x16x32_bf16 v[120:123], v[164:167], v[172:175], v[120:123]
	v_mfma_f32_16x16x32_bf16 v[112:115], v[156:159], v[180:183], v[112:115]
	v_mfma_f32_16x16x32_bf16 v[104:107], v[164:167], v[180:183], v[104:107]
	v_mfma_f32_16x16x32_bf16 v[96:99], v[156:159], v[188:191], v[96:99]
	v_mfma_f32_16x16x32_bf16 v[88:91], v[164:167], v[188:191], v[88:91]
	v_mfma_f32_16x16x32_bf16 v[80:83], v[156:159], v[196:199], v[80:83]
	v_mfma_f32_16x16x32_bf16 v[72:75], v[164:167], v[196:199], v[72:75]
	s_barrier
	s_setprio 0
	s_add_i32 s22, 0, 0x1c000
	s_add_i32 s23, s52, s28
	v_add_u32_e32 v136, s22, v148
	s_add_u32 s0, s20, 0x80
	s_addc_u32 s1, s21, 0
	s_mov_b32 m0, s23
	ds_read_b128 v[202:205], v136
	ds_read_b128 v[206:209], v136 offset:1024
	ds_read_b128 v[210:213], v136 offset:2048
	ds_read_b128 v[214:217], v136 offset:3072
	global_load_lds_dwordx4 v130, s[0:1]
	s_add_i32 m0, s23, 0x2000
	s_nop 0
	global_load_lds_dwordx4 v134, s[0:1]
	s_waitcnt vmcnt(8)
	s_setprio 1
	s_barrier
	s_waitcnt lgkmcnt(0)
	v_mfma_f32_16x16x32_bf16 v[116:119], v[202:205], v[168:171], v[116:119]
	v_mfma_f32_16x16x32_bf16 v[108:111], v[210:213], v[168:171], v[108:111]
	v_mfma_f32_16x16x32_bf16 v[100:103], v[202:205], v[176:179], v[100:103]
	v_mfma_f32_16x16x32_bf16 v[92:95], v[210:213], v[176:179], v[92:95]
	v_mfma_f32_16x16x32_bf16 v[84:87], v[202:205], v[184:187], v[84:87]
	v_mfma_f32_16x16x32_bf16 v[76:79], v[210:213], v[184:187], v[76:79]
	v_mfma_f32_16x16x32_bf16 v[68:71], v[202:205], v[192:195], v[68:71]
	v_mfma_f32_16x16x32_bf16 v[64:67], v[210:213], v[192:195], v[64:67]
	v_mfma_f32_16x16x32_bf16 v[116:119], v[206:209], v[172:175], v[116:119]
	v_mfma_f32_16x16x32_bf16 v[108:111], v[214:217], v[172:175], v[108:111]
	v_mfma_f32_16x16x32_bf16 v[100:103], v[206:209], v[180:183], v[100:103]
	v_mfma_f32_16x16x32_bf16 v[92:95], v[214:217], v[180:183], v[92:95]
	v_mfma_f32_16x16x32_bf16 v[84:87], v[206:209], v[188:191], v[84:87]
	v_mfma_f32_16x16x32_bf16 v[76:79], v[214:217], v[188:191], v[76:79]
	v_mfma_f32_16x16x32_bf16 v[68:71], v[206:209], v[196:199], v[68:71]
	v_mfma_f32_16x16x32_bf16 v[64:67], v[214:217], v[196:199], v[64:67]
	s_mov_b32 m0, s36
	s_mov_b64 s[0:1], 0x80
	v_lshl_add_u64 v[218:219], v[222:223], 0, s[0:1]
	s_barrier
	s_setprio 0
	ds_read_b128 v[168:171], v150 offset:49152
	ds_read_b128 v[172:175], v150 offset:50176
	ds_read_b128 v[176:179], v150 offset:51200
	ds_read_b128 v[180:183], v150 offset:52224
	ds_read_b128 v[184:187], v150 offset:53248
	ds_read_b128 v[188:191], v150 offset:54272
	ds_read_b128 v[192:195], v150 offset:55296
	ds_read_b128 v[196:199], v150 offset:56320
	global_load_lds_dwordx4 v[218:219], off
	v_lshl_add_u64 v[218:219], v[224:225], 0, s[0:1]
	s_mov_b32 m0, s37
	s_nop 0
	global_load_lds_dwordx4 v[218:219], off
	s_setprio 1
	s_barrier
; #define PG8_STAGE(bufoff, gbase, voff) do { _Pragma("unroll") for (int _i = 0; _i < 2; ++_i) \
;         __builtin_amdgcn_global_load_lds((const unsigned*)((const char*)(gbase) + (voff)[_i]), (LAS unsigned*)(lds + (bufoff) + ldsw + _i * 8192), 16, 0, 0); } while (0)
; #define PG8_LDA(dst, b, h) do { _Pragma("unroll") for (int m = 0; m < 4; ++m) _Pragma("unroll") for (int k = 0; k < 2; ++k) dst[m][k] = *(const LAS bf16x8*)(lds + PG8_SA(b, h) + aoff + m * 2048 + k * 1024); } while (0)
; #define PG8_LDB(dst, b, h) do { _Pragma("unroll") for (int n = 0; n < 2; ++n) _Pragma("unroll") for (int k = 0; k < 2; ++k) dst[n][k] = *(const LAS bf16x8*)(lds + PG8_SB(b, h) + boff + n * 2048 + k * 1024); } while (0)
; #define PG8_WAIT_V(n) asm volatile("s_waitcnt vmcnt(" #n ")" ::: "memory")
; #define PG8_WAIT_L(n) asm volatile("s_waitcnt lgkmcnt(" #n ")" ::: "memory")
; #define PG8_BAR __builtin_amdgcn_s_barrier()
; #define PG8_SCHED __builtin_amdgcn_sched_barrier(0)
; template <class Epi, class Sched>
; __device__ __forceinline__ void gemm_phase(LAS unsigned char* lds, const Gemm g, const Sched& S, const Epi& E) {
;     ...
;             PG8_LDB(B0, 0, 0); PG8_SCHED; PG8_LDA(At, 0, 0); PG8_STAGE(PG8_SA(1, 1), a1 + hstep, voffA);
;             PG8_WAIT_L(8); PG8_BAR; PG8_WAIT_L(0); PG8_MMA(0, 0, At, B0); PG8_BAR; PG8_SCHED;
;             PG8_LDB(B1, 0, 1); PG8_STAGE(PG8_SB(0, 0), b2, voffB);
;             PG8_BAR; PG8_WAIT_L(0); PG8_MMA(0, 1, At, B1); PG8_BAR;
;             PG8_LDA(At, 0, 1); PG8_STAGE(PG8_SA(0, 0), a2, voffA);
;             PG8_BAR; PG8_WAIT_L(0); PG8_MMA(1, 0, At, B0); PG8_BAR; PG8_SCHED;
;             PG8_STAGE(PG8_SB(0, 1), b2 + hstep, voffB);
;             PG8_WAIT_V(6); PG8_BAR; PG8_MMA(1, 1, At, B1); PG8_BAR;
;             PG8_LDB(B0, 1, 0); PG8_SCHED; PG8_LDA(At, 1, 0); PG8_STAGE(PG8_SA(0, 1), a2 + hstep, voffA);
;             PG8_WAIT_L(8); PG8_BAR; PG8_WAIT_L(0); PG8_MMA(0, 0, At, B0); PG8_BAR; PG8_SCHED;
;             PG8_LDB(B1, 1, 1); PG8_STAGE(PG8_SB(1, 0), b3, voffB);
;             PG8_BAR; PG8_WAIT_L(0); PG8_MMA(0, 1, At, B1); PG8_BAR;
;             PG8_LDA(At, 1, 1); PG8_STAGE(PG8_SA(1, 0), a3, voffA);
;             PG8_BAR; PG8_WAIT_L(0); PG8_MMA(1, 0, At, B0); PG8_BAR; PG8_SCHED;
;             PG8_STAGE(PG8_SB(1, 1), b3 + hstep, voffB);
;             PG8_WAIT_V(6); PG8_BAR; PG8_MMA(1, 1, At, B1); PG8_BAR;
	s_waitcnt lgkmcnt(0)
	v_mfma_f32_16x16x32_bf16 v[60:63], v[152:155], v[168:171], v[60:63]
	v_mfma_f32_16x16x32_bf16 v[56:59], v[160:163], v[168:171], v[56:59]
	v_mfma_f32_16x16x32_bf16 v[48:51], v[152:155], v[176:179], v[48:51]
	v_mfma_f32_16x16x32_bf16 v[40:43], v[160:163], v[176:179], v[40:43]
	v_mfma_f32_16x16x32_bf16 v[32:35], v[152:155], v[184:187], v[32:35]
	v_mfma_f32_16x16x32_bf16 v[24:27], v[160:163], v[184:187], v[24:27]
	v_mfma_f32_16x16x32_bf16 v[16:19], v[152:155], v[192:195], v[16:19]
	v_mfma_f32_16x16x32_bf16 v[8:11], v[160:163], v[192:195], v[8:11]
	v_mfma_f32_16x16x32_bf16 v[60:63], v[156:159], v[172:175], v[60:63]
	v_mfma_f32_16x16x32_bf16 v[56:59], v[164:167], v[172:175], v[56:59]
	v_mfma_f32_16x16x32_bf16 v[48:51], v[156:159], v[180:183], v[48:51]
	v_mfma_f32_16x16x32_bf16 v[40:43], v[164:167], v[180:183], v[40:43]
	v_mfma_f32_16x16x32_bf16 v[32:35], v[156:159], v[188:191], v[32:35]
	v_mfma_f32_16x16x32_bf16 v[24:27], v[164:167], v[188:191], v[24:27]
	v_mfma_f32_16x16x32_bf16 v[16:19], v[156:159], v[196:199], v[16:19]
	v_mfma_f32_16x16x32_bf16 v[8:11], v[164:167], v[196:199], v[8:11]
	s_barrier
	s_setprio 0
	s_add_u32 s20, s20, 0x40080
	s_addc_u32 s21, s21, 0
	s_add_i32 s22, s22, s28
	s_mov_b32 m0, s22
	s_nop 0
	global_load_lds_dwordx4 v130, s[20:21]
	s_add_i32 m0, s22, 0x2000
	s_nop 0
	global_load_lds_dwordx4 v134, s[20:21]
	s_waitcnt vmcnt(8)
	s_setprio 1
	s_barrier
	v_mfma_f32_16x16x32_bf16 v[52:55], v[202:205], v[168:171], v[52:55]
	v_mfma_f32_16x16x32_bf16 v[44:47], v[210:213], v[168:171], v[44:47]
	v_mfma_f32_16x16x32_bf16 v[36:39], v[202:205], v[176:179], v[36:39]
	v_mfma_f32_16x16x32_bf16 v[28:31], v[210:213], v[176:179], v[28:31]
	v_mfma_f32_16x16x32_bf16 v[20:23], v[202:205], v[184:187], v[20:23]
	v_mfma_f32_16x16x32_bf16 v[12:15], v[210:213], v[184:187], v[12:15]
	v_mfma_f32_16x16x32_bf16 v[4:7], v[202:205], v[192:195], v[4:7]
	v_mfma_f32_16x16x32_bf16 v[0:3], v[210:213], v[192:195], v[0:3]
	v_mfma_f32_16x16x32_bf16 v[52:55], v[206:209], v[172:175], v[52:55]
	v_mfma_f32_16x16x32_bf16 v[44:47], v[214:217], v[172:175], v[44:47]
	v_mfma_f32_16x16x32_bf16 v[36:39], v[206:209], v[180:183], v[36:39]
	v_mfma_f32_16x16x32_bf16 v[28:31], v[214:217], v[180:183], v[28:31]
	v_mfma_f32_16x16x32_bf16 v[20:23], v[206:209], v[188:191], v[20:23]
	v_mfma_f32_16x16x32_bf16 v[12:15], v[214:217], v[188:191], v[12:15]
	v_mfma_f32_16x16x32_bf16 v[4:7], v[206:209], v[196:199], v[4:7]
	v_mfma_f32_16x16x32_bf16 v[0:3], v[214:217], v[196:199], v[0:3]
	s_add_i32 s51, s51, 2
	s_add_u32 s18, s18, 0x100
	s_addc_u32 s19, s19, 0
	s_add_u32 s48, s48, 0x100
	s_addc_u32 s49, s49, 0
	s_cmp_gt_u32 s51, 13
	s_barrier
	s_setprio 0
.LBB0_673:
	ds_read_b128 v[152:155], v149
	ds_read_b128 v[156:159], v149 offset:1024
	ds_read_b128 v[160:163], v149 offset:2048
	ds_read_b128 v[164:167], v149 offset:3072
	s_add_u32 s20, s18, 0xfffc0080
	s_addc_u32 s21, s19, -1
	s_cmp_eq_u32 s51, 12
	s_cselect_b32 s23, s9, s21
	s_cselect_b32 s22, s46, s20
	s_cselect_b32 s21, s7, s49
	s_cselect_b32 s20, s47, s48
	s_add_i32 m0, s17, 0xc000
	ds_read_b128 v[168:171], v150
	ds_read_b128 v[172:175], v150 offset:1024
	ds_read_b128 v[176:179], v150 offset:2048
	ds_read_b128 v[180:183], v150 offset:3072
	ds_read_b128 v[184:187], v150 offset:4096
	ds_read_b128 v[188:191], v150 offset:5120
	ds_read_b128 v[192:195], v150 offset:6144
	ds_read_b128 v[196:199], v150 offset:7168
	global_load_lds_dwordx4 v138, s[18:19]
	s_add_i32 m0, s17, 0xe000
	s_nop 0
	global_load_lds_dwordx4 v140, s[18:19]
	s_waitcnt lgkmcnt(8)
	s_waitcnt vmcnt(8)
	s_setprio 1
	s_barrier
	s_waitcnt lgkmcnt(0)
	v_mfma_f32_16x16x32_bf16 v[124:127], v[152:155], v[168:171], v[124:127]
	v_mfma_f32_16x16x32_bf16 v[120:123], v[160:163], v[168:171], v[120:123]
	v_mfma_f32_16x16x32_bf16 v[112:115], v[152:155], v[176:179], v[112:115]
	v_mfma_f32_16x16x32_bf16 v[104:107], v[160:163], v[176:179], v[104:107]
	v_mfma_f32_16x16x32_bf16 v[96:99], v[152:155], v[184:187], v[96:99]
	v_mfma_f32_16x16x32_bf16 v[88:91], v[160:163], v[184:187], v[88:91]
	v_mfma_f32_16x16x32_bf16 v[80:83], v[152:155], v[192:195], v[80:83]
	v_mfma_f32_16x16x32_bf16 v[72:75], v[160:163], v[192:195], v[72:75]
	v_mfma_f32_16x16x32_bf16 v[124:127], v[156:159], v[172:175], v[124:127]
	v_mfma_f32_16x16x32_bf16 v[120:123], v[164:167], v[172:175], v[120:123]
	v_mfma_f32_16x16x32_bf16 v[112:115], v[156:159], v[180:183], v[112:115]
	v_mfma_f32_16x16x32_bf16 v[104:107], v[164:167], v[180:183], v[104:107]
	v_mfma_f32_16x16x32_bf16 v[96:99], v[156:159], v[188:191], v[96:99]
	v_mfma_f32_16x16x32_bf16 v[88:91], v[164:167], v[188:191], v[88:91]
	v_mfma_f32_16x16x32_bf16 v[80:83], v[156:159], v[196:199], v[80:83]
	v_mfma_f32_16x16x32_bf16 v[72:75], v[164:167], v[196:199], v[72:75]
	s_barrier
	s_setprio 0
	s_add_i32 s52, s43, s28
	s_mov_b32 m0, s52
	ds_read_b128 v[202:205], v151
	ds_read_b128 v[206:209], v151 offset:1024
	ds_read_b128 v[210:213], v151 offset:2048
	ds_read_b128 v[214:217], v151 offset:3072
	global_load_lds_dwordx4 v130, s[20:21]
	s_add_i32 m0, s52, 0x2000
	s_nop 0
	global_load_lds_dwordx4 v134, s[20:21]
	s_waitcnt vmcnt(8)
	s_setprio 1
	s_barrier
; #define PG8_STAGE(bufoff, gbase, voff) do { _Pragma("unroll") for (int _i = 0; _i < 2; ++_i) \
;         __builtin_amdgcn_global_load_lds((const unsigned*)((const char*)(gbase) + (voff)[_i]), (LAS unsigned*)(lds + (bufoff) + ldsw + _i * 8192), 16, 0, 0); } while (0)
; #define PG8_LDA(dst, b, h) do { _Pragma("unroll") for (int m = 0; m < 4; ++m) _Pragma("unroll") for (int k = 0; k < 2; ++k) dst[m][k] = *(const LAS bf16x8*)(lds + PG8_SA(b, h) + aoff + m * 2048 + k * 1024); } while (0)
; #define PG8_LDB(dst, b, h) do { _Pragma("unroll") for (int n = 0; n < 2; ++n) _Pragma("unroll") for (int k = 0; k < 2; ++k) dst[n][k] = *(const LAS bf16x8*)(lds + PG8_SB(b, h) + boff + n * 2048 + k * 1024); } while (0)
; #define PG8_MMA(ai, bj, At, Bt) do { __builtin_amdgcn_s_setprio(1); _Pragma("unroll") for (int m = 0; m < 4; ++m) _Pragma("unroll") for (int n = 0; n < 2; ++n) _Pragma("unroll") for (int k = 0; k < 2; ++k) \
;         acc[ai][bj][m][n] = __builtin_amdgcn_mfma_f32_16x16x32_bf16(Bt[n][k], At[m][k], acc[ai][bj][m][n], 0, 0, 0); __builtin_amdgcn_s_setprio(0); } while (0)
; #define PG8_WAIT_V(n) asm volatile("s_waitcnt vmcnt(" #n ")" ::: "memory")
; #define PG8_WAIT_L(n) asm volatile("s_waitcnt lgkmcnt(" #n ")" ::: "memory")
; #define PG8_BAR __builtin_amdgcn_s_barrier()
; #define PG8_SCHED __builtin_amdgcn_sched_barrier(0)
; template <class Epi, class Sched>
; __device__ __forceinline__ void gemm_phase(LAS unsigned char* lds, const Gemm g, const Sched& S, const Epi& E) {
;     ...
;             PG8_BAR; PG8_WAIT_L(0); PG8_MMA(0, 1, At, B1); PG8_BAR;
;             PG8_LDA(At, 0, 1); PG8_STAGE(PG8_SA(0, 0), a2, voffA);
;             PG8_BAR; PG8_WAIT_L(0); PG8_MMA(1, 0, At, B0); PG8_BAR; PG8_SCHED;
;             PG8_STAGE(PG8_SB(0, 1), b2 + hstep, voffB);
;             PG8_WAIT_V(6); PG8_BAR; PG8_MMA(1, 1, At, B1); PG8_BAR;
;             PG8_LDB(B0, 1, 0); PG8_SCHED; PG8_LDA(At, 1, 0); PG8_STAGE(PG8_SA(0, 1), a2 + hstep, voffA);
	s_waitcnt lgkmcnt(0)
	v_mfma_f32_16x16x32_bf16 v[116:119], v[202:205], v[168:171], v[116:119]
	v_mfma_f32_16x16x32_bf16 v[108:111], v[210:213], v[168:171], v[108:111]
	v_mfma_f32_16x16x32_bf16 v[100:103], v[202:205], v[176:179], v[100:103]
	v_mfma_f32_16x16x32_bf16 v[92:95], v[210:213], v[176:179], v[92:95]
	v_mfma_f32_16x16x32_bf16 v[84:87], v[202:205], v[184:187], v[84:87]
	v_mfma_f32_16x16x32_bf16 v[76:79], v[210:213], v[184:187], v[76:79]
	v_mfma_f32_16x16x32_bf16 v[68:71], v[202:205], v[192:195], v[68:71]
	v_mfma_f32_16x16x32_bf16 v[64:67], v[210:213], v[192:195], v[64:67]
	v_mfma_f32_16x16x32_bf16 v[116:119], v[206:209], v[172:175], v[116:119]
	v_mfma_f32_16x16x32_bf16 v[108:111], v[214:217], v[172:175], v[108:111]
	v_mfma_f32_16x16x32_bf16 v[100:103], v[206:209], v[180:183], v[100:103]
	v_mfma_f32_16x16x32_bf16 v[92:95], v[214:217], v[180:183], v[92:95]
	v_mfma_f32_16x16x32_bf16 v[84:87], v[206:209], v[188:191], v[84:87]
	v_mfma_f32_16x16x32_bf16 v[76:79], v[214:217], v[188:191], v[76:79]
	v_mfma_f32_16x16x32_bf16 v[68:71], v[206:209], v[196:199], v[68:71]
	v_mfma_f32_16x16x32_bf16 v[64:67], v[214:217], v[196:199], v[64:67]
	s_mov_b32 m0, s17
	v_lshl_add_u64 v[222:223], s[22:23], 0, v[128:129]
	s_barrier
	s_setprio 0
	ds_read_b128 v[168:171], v150 offset:16384
	ds_read_b128 v[172:175], v150 offset:17408
	ds_read_b128 v[176:179], v150 offset:18432
	ds_read_b128 v[180:183], v150 offset:19456
	ds_read_b128 v[184:187], v150 offset:20480
	ds_read_b128 v[188:191], v150 offset:21504
	ds_read_b128 v[192:195], v150 offset:22528
	ds_read_b128 v[196:199], v150 offset:23552
	global_load_lds_dwordx4 v128, s[22:23]
	v_lshl_add_u64 v[224:225], s[22:23], 0, v[132:133]
	s_mov_b32 m0, s29
	s_nop 0
	global_load_lds_dwordx4 v132, s[22:23]
	s_setprio 1
	s_barrier
	s_waitcnt lgkmcnt(0)
	v_mfma_f32_16x16x32_bf16 v[60:63], v[152:155], v[168:171], v[60:63]
	v_mfma_f32_16x16x32_bf16 v[56:59], v[160:163], v[168:171], v[56:59]
	v_mfma_f32_16x16x32_bf16 v[48:51], v[152:155], v[176:179], v[48:51]
	v_mfma_f32_16x16x32_bf16 v[40:43], v[160:163], v[176:179], v[40:43]
	v_mfma_f32_16x16x32_bf16 v[32:35], v[152:155], v[184:187], v[32:35]
	v_mfma_f32_16x16x32_bf16 v[24:27], v[160:163], v[184:187], v[24:27]
	v_mfma_f32_16x16x32_bf16 v[16:19], v[152:155], v[192:195], v[16:19]
	v_mfma_f32_16x16x32_bf16 v[8:11], v[160:163], v[192:195], v[8:11]
	v_mfma_f32_16x16x32_bf16 v[60:63], v[156:159], v[172:175], v[60:63]
	v_mfma_f32_16x16x32_bf16 v[56:59], v[164:167], v[172:175], v[56:59]
	v_mfma_f32_16x16x32_bf16 v[48:51], v[156:159], v[180:183], v[48:51]
	v_mfma_f32_16x16x32_bf16 v[40:43], v[164:167], v[180:183], v[40:43]
	v_mfma_f32_16x16x32_bf16 v[32:35], v[156:159], v[188:191], v[32:35]
	v_mfma_f32_16x16x32_bf16 v[24:27], v[164:167], v[188:191], v[24:27]
	v_mfma_f32_16x16x32_bf16 v[16:19], v[156:159], v[196:199], v[16:19]
	v_mfma_f32_16x16x32_bf16 v[8:11], v[164:167], v[196:199], v[8:11]
	s_barrier
	s_setprio 0
	s_add_u32 s52, s20, 0x40000
	s_addc_u32 s53, s21, 0
	s_add_i32 s54, s44, s28
	s_mov_b32 m0, s54
	s_nop 0
	global_load_lds_dwordx4 v130, s[52:53]
	s_add_i32 m0, s54, 0x2000
	s_nop 0
	global_load_lds_dwordx4 v134, s[52:53]
	s_add_u32 s22, s22, 0x40000
	s_addc_u32 s23, s23, 0
	s_mov_b32 m0, s30
	s_nop 0
	global_load_lds_dwordx4 v128, s[22:23]
	s_mov_b32 m0, s31
	s_nop 0
	global_load_lds_dwordx4 v132, s[22:23]
	s_waitcnt vmcnt(10)
	s_setprio 1
	s_barrier
	v_mfma_f32_16x16x32_bf16 v[52:55], v[202:205], v[168:171], v[52:55]
	v_mfma_f32_16x16x32_bf16 v[44:47], v[210:213], v[168:171], v[44:47]
	v_mfma_f32_16x16x32_bf16 v[36:39], v[202:205], v[176:179], v[36:39]
	v_mfma_f32_16x16x32_bf16 v[28:31], v[210:213], v[176:179], v[28:31]
	v_mfma_f32_16x16x32_bf16 v[20:23], v[202:205], v[184:187], v[20:23]
	v_mfma_f32_16x16x32_bf16 v[12:15], v[210:213], v[184:187], v[12:15]
	v_mfma_f32_16x16x32_bf16 v[4:7], v[202:205], v[192:195], v[4:7]
	v_mfma_f32_16x16x32_bf16 v[0:3], v[210:213], v[192:195], v[0:3]
	v_mfma_f32_16x16x32_bf16 v[52:55], v[206:209], v[172:175], v[52:55]
	v_mfma_f32_16x16x32_bf16 v[44:47], v[214:217], v[172:175], v[44:47]
	v_mfma_f32_16x16x32_bf16 v[36:39], v[206:209], v[180:183], v[36:39]
	v_mfma_f32_16x16x32_bf16 v[28:31], v[214:217], v[180:183], v[28:31]
	v_mfma_f32_16x16x32_bf16 v[20:23], v[206:209], v[188:191], v[20:23]
	v_mfma_f32_16x16x32_bf16 v[12:15], v[214:217], v[188:191], v[12:15]
	v_mfma_f32_16x16x32_bf16 v[4:7], v[206:209], v[196:199], v[4:7]
	v_mfma_f32_16x16x32_bf16 v[0:3], v[214:217], v[196:199], v[0:3]
	s_add_i32 s52, 0, 0x18000
	v_add_u32_e32 v136, s52, v148
	s_barrier
	s_setprio 0
	ds_read_b128 v[152:155], v136
	ds_read_b128 v[156:159], v136 offset:1024
	ds_read_b128 v[160:163], v136 offset:2048
	ds_read_b128 v[164:167], v136 offset:3072
	ds_read_b128 v[168:171], v150 offset:32768
	ds_read_b128 v[172:175], v150 offset:33792
	ds_read_b128 v[176:179], v150 offset:34816
	ds_read_b128 v[180:183], v150 offset:35840
	ds_read_b128 v[184:187], v150 offset:36864
	ds_read_b128 v[188:191], v150 offset:37888
	ds_read_b128 v[192:195], v150 offset:38912
	ds_read_b128 v[196:199], v150 offset:39936
	s_waitcnt lgkmcnt(8)
	s_waitcnt vmcnt(8)
	s_setprio 1
	s_barrier
; #define PG8_STAGE(bufoff, gbase, voff) do { _Pragma("unroll") for (int _i = 0; _i < 2; ++_i) \
;         __builtin_amdgcn_global_load_lds((const unsigned*)((const char*)(gbase) + (voff)[_i]), (LAS unsigned*)(lds + (bufoff) + ldsw + _i * 8192), 16, 0, 0); } while (0)
; #define PG8_LDA(dst, b, h) do { _Pragma("unroll") for (int m = 0; m < 4; ++m) _Pragma("unroll") for (int k = 0; k < 2; ++k) dst[m][k] = *(const LAS bf16x8*)(lds + PG8_SA(b, h) + aoff + m * 2048 + k * 1024); } while (0)
; #define PG8_LDB(dst, b, h) do { _Pragma("unroll") for (int n = 0; n < 2; ++n) _Pragma("unroll") for (int k = 0; k < 2; ++k) dst[n][k] = *(const LAS bf16x8*)(lds + PG8_SB(b, h) + boff + n * 2048 + k * 1024); } while (0)
; #define PG8_MMA(ai, bj, At, Bt) do { __builtin_amdgcn_s_setprio(1); _Pragma("unroll") for (int m = 0; m < 4; ++m) _Pragma("unroll") for (int n = 0; n < 2; ++n) _Pragma("unroll") for (int k = 0; k < 2; ++k) \
;         acc[ai][bj][m][n] = __builtin_amdgcn_mfma_f32_16x16x32_bf16(Bt[n][k], At[m][k], acc[ai][bj][m][n], 0, 0, 0); __builtin_amdgcn_s_setprio(0); } while (0)
; #define PG8_WAIT_V(n) asm volatile("s_waitcnt vmcnt(" #n ")" ::: "memory")
; #define PG8_WAIT_L(n) asm volatile("s_waitcnt lgkmcnt(" #n ")" ::: "memory")
; #define PG8_BAR __builtin_amdgcn_s_barrier()
; #define PG8_SCHED __builtin_amdgcn_sched_barrier(0)
; template <class Epi, class Sched>
; __device__ __forceinline__ void gemm_phase(LAS unsigned char* lds, const Gemm g, const Sched& S, const Epi& E) {
;     ...
;             PG8_WAIT_L(8); PG8_BAR; PG8_WAIT_L(0); PG8_MMA(0, 0, At, B0); PG8_BAR; PG8_SCHED;
;             PG8_LDB(B1, 1, 1); PG8_STAGE(PG8_SB(1, 0), b3, voffB);
;             PG8_BAR; PG8_WAIT_L(0); PG8_MMA(0, 1, At, B1); PG8_BAR;
;             PG8_LDA(At, 1, 1); PG8_STAGE(PG8_SA(1, 0), a3, voffA);
;             PG8_BAR; PG8_WAIT_L(0); PG8_MMA(1, 0, At, B0); PG8_BAR; PG8_SCHED;
;             PG8_STAGE(PG8_SB(1, 1), b3 + hstep, voffB);
;             PG8_WAIT_V(6); PG8_BAR; PG8_MMA(1, 1, At, B1); PG8_BAR;
	s_waitcnt lgkmcnt(0)
	v_mfma_f32_16x16x32_bf16 v[124:127], v[152:155], v[168:171], v[124:127]
	v_mfma_f32_16x16x32_bf16 v[120:123], v[160:163], v[168:171], v[120:123]
	v_mfma_f32_16x16x32_bf16 v[112:115], v[152:155], v[176:179], v[112:115]
	v_mfma_f32_16x16x32_bf16 v[104:107], v[160:163], v[176:179], v[104:107]
	v_mfma_f32_16x16x32_bf16 v[96:99], v[152:155], v[184:187], v[96:99]
	v_mfma_f32_16x16x32_bf16 v[88:91], v[160:163], v[184:187], v[88:91]
	v_mfma_f32_16x16x32_bf16 v[80:83], v[152:155], v[192:195], v[80:83]
	v_mfma_f32_16x16x32_bf16 v[72:75], v[160:163], v[192:195], v[72:75]
	v_mfma_f32_16x16x32_bf16 v[124:127], v[156:159], v[172:175], v[124:127]
	v_mfma_f32_16x16x32_bf16 v[120:123], v[164:167], v[172:175], v[120:123]
	v_mfma_f32_16x16x32_bf16 v[112:115], v[156:159], v[180:183], v[112:115]
	v_mfma_f32_16x16x32_bf16 v[104:107], v[164:167], v[180:183], v[104:107]
	v_mfma_f32_16x16x32_bf16 v[96:99], v[156:159], v[188:191], v[96:99]
	v_mfma_f32_16x16x32_bf16 v[88:91], v[164:167], v[188:191], v[88:91]
	v_mfma_f32_16x16x32_bf16 v[80:83], v[156:159], v[196:199], v[80:83]
	v_mfma_f32_16x16x32_bf16 v[72:75], v[164:167], v[196:199], v[72:75]
	s_barrier
	s_setprio 0
	s_add_i32 s22, 0, 0x1c000
	s_add_i32 s23, s52, s28
	v_add_u32_e32 v136, s22, v148
	s_add_u32 s0, s20, 0x80
	s_addc_u32 s1, s21, 0
	s_mov_b32 m0, s23
	ds_read_b128 v[202:205], v136
	ds_read_b128 v[206:209], v136 offset:1024
	ds_read_b128 v[210:213], v136 offset:2048
	ds_read_b128 v[214:217], v136 offset:3072
	global_load_lds_dwordx4 v130, s[0:1]
	s_add_i32 m0, s23, 0x2000
	s_nop 0
	global_load_lds_dwordx4 v134, s[0:1]
	s_waitcnt vmcnt(8)
	s_setprio 1
	s_barrier
	s_waitcnt lgkmcnt(0)
	v_mfma_f32_16x16x32_bf16 v[116:119], v[202:205], v[168:171], v[116:119]
	v_mfma_f32_16x16x32_bf16 v[108:111], v[210:213], v[168:171], v[108:111]
	v_mfma_f32_16x16x32_bf16 v[100:103], v[202:205], v[176:179], v[100:103]
	v_mfma_f32_16x16x32_bf16 v[92:95], v[210:213], v[176:179], v[92:95]
	v_mfma_f32_16x16x32_bf16 v[84:87], v[202:205], v[184:187], v[84:87]
	v_mfma_f32_16x16x32_bf16 v[76:79], v[210:213], v[184:187], v[76:79]
	v_mfma_f32_16x16x32_bf16 v[68:71], v[202:205], v[192:195], v[68:71]
	v_mfma_f32_16x16x32_bf16 v[64:67], v[210:213], v[192:195], v[64:67]
	v_mfma_f32_16x16x32_bf16 v[116:119], v[206:209], v[172:175], v[116:119]
	v_mfma_f32_16x16x32_bf16 v[108:111], v[214:217], v[172:175], v[108:111]
	v_mfma_f32_16x16x32_bf16 v[100:103], v[206:209], v[180:183], v[100:103]
	v_mfma_f32_16x16x32_bf16 v[92:95], v[214:217], v[180:183], v[92:95]
	v_mfma_f32_16x16x32_bf16 v[84:87], v[206:209], v[188:191], v[84:87]
	v_mfma_f32_16x16x32_bf16 v[76:79], v[214:217], v[188:191], v[76:79]
	v_mfma_f32_16x16x32_bf16 v[68:71], v[206:209], v[196:199], v[68:71]
	v_mfma_f32_16x16x32_bf16 v[64:67], v[214:217], v[196:199], v[64:67]
	s_mov_b32 m0, s36
	s_mov_b64 s[0:1], 0x80
	v_lshl_add_u64 v[218:219], v[222:223], 0, s[0:1]
	s_barrier
	s_setprio 0
	ds_read_b128 v[168:171], v150 offset:49152
	ds_read_b128 v[172:175], v150 offset:50176
	ds_read_b128 v[176:179], v150 offset:51200
	ds_read_b128 v[180:183], v150 offset:52224
	ds_read_b128 v[184:187], v150 offset:53248
	ds_read_b128 v[188:191], v150 offset:54272
	ds_read_b128 v[192:195], v150 offset:55296
	ds_read_b128 v[196:199], v150 offset:56320
	global_load_lds_dwordx4 v[218:219], off
	v_lshl_add_u64 v[218:219], v[224:225], 0, s[0:1]
	s_mov_b32 m0, s37
	s_nop 0
	global_load_lds_dwordx4 v[218:219], off
	s_setprio 1
	s_barrier
	s_waitcnt lgkmcnt(0)
	v_mfma_f32_16x16x32_bf16 v[60:63], v[152:155], v[168:171], v[60:63]
	v_mfma_f32_16x16x32_bf16 v[56:59], v[160:163], v[168:171], v[56:59]
	v_mfma_f32_16x16x32_bf16 v[48:51], v[152:155], v[176:179], v[48:51]
	v_mfma_f32_16x16x32_bf16 v[40:43], v[160:163], v[176:179], v[40:43]
	v_mfma_f32_16x16x32_bf16 v[32:35], v[152:155], v[184:187], v[32:35]
	v_mfma_f32_16x16x32_bf16 v[24:27], v[160:163], v[184:187], v[24:27]
	v_mfma_f32_16x16x32_bf16 v[16:19], v[152:155], v[192:195], v[16:19]
	v_mfma_f32_16x16x32_bf16 v[8:11], v[160:163], v[192:195], v[8:11]
	v_mfma_f32_16x16x32_bf16 v[60:63], v[156:159], v[172:175], v[60:63]
	v_mfma_f32_16x16x32_bf16 v[56:59], v[164:167], v[172:175], v[56:59]
	v_mfma_f32_16x16x32_bf16 v[48:51], v[156:159], v[180:183], v[48:51]
	v_mfma_f32_16x16x32_bf16 v[40:43], v[164:167], v[180:183], v[40:43]
	v_mfma_f32_16x16x32_bf16 v[32:35], v[156:159], v[188:191], v[32:35]
	v_mfma_f32_16x16x32_bf16 v[24:27], v[164:167], v[188:191], v[24:27]
	v_mfma_f32_16x16x32_bf16 v[16:19], v[156:159], v[196:199], v[16:19]
	v_mfma_f32_16x16x32_bf16 v[8:11], v[164:167], v[196:199], v[8:11]
	s_barrier
	s_setprio 0
	s_add_u32 s20, s20, 0x40080
	s_addc_u32 s21, s21, 0
	s_add_i32 s22, s22, s28
	s_mov_b32 m0, s22
	s_nop 0
	global_load_lds_dwordx4 v130, s[20:21]
	s_add_i32 m0, s22, 0x2000
	s_nop 0
	global_load_lds_dwordx4 v134, s[20:21]
	s_waitcnt vmcnt(8)
	s_setprio 1
	s_barrier
	v_mfma_f32_16x16x32_bf16 v[52:55], v[202:205], v[168:171], v[52:55]
	v_mfma_f32_16x16x32_bf16 v[44:47], v[210:213], v[168:171], v[44:47]
	v_mfma_f32_16x16x32_bf16 v[36:39], v[202:205], v[176:179], v[36:39]
	v_mfma_f32_16x16x32_bf16 v[28:31], v[210:213], v[176:179], v[28:31]
	v_mfma_f32_16x16x32_bf16 v[20:23], v[202:205], v[184:187], v[20:23]
	v_mfma_f32_16x16x32_bf16 v[12:15], v[210:213], v[184:187], v[12:15]
	v_mfma_f32_16x16x32_bf16 v[4:7], v[202:205], v[192:195], v[4:7]
	v_mfma_f32_16x16x32_bf16 v[0:3], v[210:213], v[192:195], v[0:3]
	v_mfma_f32_16x16x32_bf16 v[52:55], v[206:209], v[172:175], v[52:55]
	v_mfma_f32_16x16x32_bf16 v[44:47], v[214:217], v[172:175], v[44:47]
	v_mfma_f32_16x16x32_bf16 v[36:39], v[206:209], v[180:183], v[36:39]
	v_mfma_f32_16x16x32_bf16 v[28:31], v[214:217], v[180:183], v[28:31]
	v_mfma_f32_16x16x32_bf16 v[20:23], v[206:209], v[188:191], v[20:23]
	v_mfma_f32_16x16x32_bf16 v[12:15], v[214:217], v[188:191], v[12:15]
	v_mfma_f32_16x16x32_bf16 v[4:7], v[206:209], v[196:199], v[4:7]
	v_mfma_f32_16x16x32_bf16 v[0:3], v[214:217], v[196:199], v[0:3]
	s_add_i32 s51, s51, 2
	s_add_u32 s18, s18, 0x100
	s_addc_u32 s19, s19, 0
	s_add_u32 s48, s48, 0x100
	s_addc_u32 s49, s49, 0
	s_cmp_gt_u32 s51, 13
	s_barrier
; __device__ __forceinline__ unsigned cvt_pk_bf16(float lo, float hi) { unsigned r; asm volatile("v_cvt_pk_bf16_f32 %0, %1, %2" : "=v"(r) : "v"(lo), "v"(hi)); return r; }
; #define PG8_MMA(ai, bj, At, Bt) do { __builtin_amdgcn_s_setprio(1); _Pragma("unroll") for (int m = 0; m < 4; ++m) _Pragma("unroll") for (int n = 0; n < 2; ++n) _Pragma("unroll") for (int k = 0; k < 2; ++k) \
;         acc[ai][bj][m][n] = __builtin_amdgcn_mfma_f32_16x16x32_bf16(Bt[n][k], At[m][k], acc[ai][bj][m][n], 0, 0, 0); __builtin_amdgcn_s_setprio(0); } while (0)
; #define PG8_WAIT_V(n) asm volatile("s_waitcnt vmcnt(" #n ")" ::: "memory")
; #define PG8_BAR __builtin_amdgcn_s_barrier()
; template <class Epi, class Sched>
; __device__ __forceinline__ void gemm_phase(LAS unsigned char* lds, const Gemm g, const Sched& S, const Epi& E) {
;     ...
;             PG8_WAIT_V(6); PG8_BAR; PG8_MMA(1, 1, At, B1); PG8_BAR;
;         }
;         E(acc, cur, wr, wc, fr, fq);
;         if (!has_next) break;
;     __device__ __forceinline__ void operator()(const AccT& acc, const Unit& u, int wr, int wc, int fr, int fq) const {
;     ...
;         const int rbase = u.pm * 256 + wr * 64 + fr;
;         const int tb = u.pn * 256 + wc * 32 + 8 * fq;
; #pragma unroll
;         for (int ai = 0; ai < 2; ++ai)
; #pragma unroll
;             for (int m = 0; m < 4; ++m) {
;                 const int gm = rbase + ai * 128 + m * 16;
; #pragma unroll
;                 for (int bj = 0; bj < 2; ++bj) {
;                     const int t0 = tb + bj * 128;
;                     const f32x4 v0 = acc[ai][bj][m][0], v1 = acc[ai][bj][m][1];
;                     u32x4 w; w.x = cvt_pk_bf16(v0[0], v0[1]); w.y = cvt_pk_bf16(v0[2], v0[3]); w.z = cvt_pk_bf16(v1[0], v1[1]); w.w = cvt_pk_bf16(v1[2], v1[3]);
;                     *(u32x4*)(YT + ((size_t)((t0 >> 10) * 512 + gm)) * 2048 + part * 1024 + (t0 & 1023)) = w;
;                 }
	s_setprio 0
	s_cbranch_scc0 .LBB0_673
	v_mov_b32_e32 v136, v147
	v_mov_b32_e32 v152, v146
	s_lshl_b32 s7, s16, 8
	s_add_i32 s7, s7, s34
	v_add_u32_e32 v152, s7, v152
	s_lshl_b32 s7, s45, 8
	s_or_b32 s7, s7, s35
	v_lshl_add_u32 v153, v136, 3, s7
	v_cvt_pk_bf16_f32 v124, v124, v125
	v_cvt_pk_bf16_f32 v125, v126, v127
	v_cvt_pk_bf16_f32 v126, v120, v121
	v_ashrrev_i32_e32 v120, 1, v153
	v_cvt_pk_bf16_f32 v127, v122, v123
	v_and_b32_e32 v122, 0xfffffe00, v120
	v_add_u32_e32 v120, v122, v152
	v_ashrrev_i32_e32 v121, 31, v120
	v_lshlrev_b64 v[120:121], 12, v[120:121]
	v_and_b32_e32 v123, 0x3f8, v153
	v_lshl_add_u64 v[120:121], s[4:5], 0, v[120:121]
	v_lshlrev_b32_e32 v136, 1, v123
	v_lshl_add_u64 v[120:121], v[120:121], 0, v[136:137]
	global_store_dwordx4 v[120:121], v[124:127], off
	v_add_u32_e32 v120, 0x80, v153
	v_cvt_pk_bf16_f32 v116, v116, v117
	v_cvt_pk_bf16_f32 v117, v118, v119
	v_cvt_pk_bf16_f32 v118, v108, v109
	v_ashrrev_i32_e32 v108, 1, v120
	v_and_b32_e32 v121, 0xfffffe00, v108
	v_add_u32_e32 v108, v121, v152
	v_ashrrev_i32_e32 v109, 31, v108
	v_lshlrev_b64 v[108:109], 12, v[108:109]
	v_cvt_pk_bf16_f32 v119, v110, v111
	v_lshl_add_u64 v[110:111], s[4:5], 0, v[108:109]
	v_and_b32_e32 v108, 0x3f8, v120
	v_lshlrev_b32_e32 v108, 1, v108
	v_mov_b32_e32 v109, v137
	v_lshl_add_u64 v[110:111], v[110:111], 0, v[108:109]
	global_store_dwordx4 v[110:111], v[116:119], off
	v_cvt_pk_bf16_f32 v110, v112, v113
	v_cvt_pk_bf16_f32 v111, v114, v115
	v_cvt_pk_bf16_f32 v112, v104, v105
	v_cvt_pk_bf16_f32 v113, v106, v107
	s_and_b64 vcc, exec, s[2:3]
	s_nop 0
	v_add_u32_e32 v116, 16, v152
	v_add_u32_e32 v104, v122, v116
	v_ashrrev_i32_e32 v105, 31, v104
	v_lshlrev_b64 v[104:105], 12, v[104:105]
	v_lshl_add_u64 v[104:105], s[4:5], 0, v[104:105]
	v_lshl_add_u64 v[104:105], v[104:105], 0, v[136:137]
	global_store_dwordx4 v[104:105], v[110:113], off
	v_cvt_pk_bf16_f32 v100, v100, v101
	v_cvt_pk_bf16_f32 v101, v102, v103
	v_cvt_pk_bf16_f32 v102, v92, v93
	v_add_u32_e32 v92, v121, v116
	v_ashrrev_i32_e32 v93, 31, v92
	v_lshlrev_b64 v[92:93], 12, v[92:93]
	v_lshl_add_u64 v[92:93], s[4:5], 0, v[92:93]
	v_lshl_add_u64 v[92:93], v[92:93], 0, v[108:109]
	v_cvt_pk_bf16_f32 v103, v94, v95
	global_store_dwordx4 v[92:93], v[100:103], off
	v_cvt_pk_bf16_f32 v92, v96, v97
	v_cvt_pk_bf16_f32 v93, v98, v99
	v_cvt_pk_bf16_f32 v94, v88, v89
	v_cvt_pk_bf16_f32 v95, v90, v91
	s_mov_b32 s45, s6
	s_nop 0
	v_add_u32_e32 v100, 32, v152
	v_add_u32_e32 v88, v122, v100
	v_ashrrev_i32_e32 v89, 31, v88
	v_lshlrev_b64 v[88:89], 12, v[88:89]
	v_lshl_add_u64 v[88:89], s[4:5], 0, v[88:89]
	v_lshl_add_u64 v[88:89], v[88:89], 0, v[136:137]
	global_store_dwordx4 v[88:89], v[92:95], off
	v_cvt_pk_bf16_f32 v84, v84, v85
	v_cvt_pk_bf16_f32 v85, v86, v87
	v_cvt_pk_bf16_f32 v86, v76, v77
	v_add_u32_e32 v76, v121, v100
	v_ashrrev_i32_e32 v77, 31, v76
	v_lshlrev_b64 v[76:77], 12, v[76:77]
	v_lshl_add_u64 v[76:77], s[4:5], 0, v[76:77]
	v_lshl_add_u64 v[76:77], v[76:77], 0, v[108:109]
	v_cvt_pk_bf16_f32 v87, v78, v79
	global_store_dwordx4 v[76:77], v[84:87], off
	v_cvt_pk_bf16_f32 v76, v80, v81
	v_cvt_pk_bf16_f32 v77, v82, v83
	v_cvt_pk_bf16_f32 v78, v72, v73
	v_cvt_pk_bf16_f32 v79, v74, v75
	s_mov_b32 s16, s8
	s_nop 0
	v_add_u32_e32 v84, 48, v152
	v_add_u32_e32 v72, v122, v84
	v_ashrrev_i32_e32 v73, 31, v72
	v_lshlrev_b64 v[72:73], 12, v[72:73]
	v_lshl_add_u64 v[72:73], s[4:5], 0, v[72:73]
	v_lshl_add_u64 v[72:73], v[72:73], 0, v[136:137]
	global_store_dwordx4 v[72:73], v[76:79], off
	v_cvt_pk_bf16_f32 v68, v68, v69
	v_cvt_pk_bf16_f32 v69, v70, v71
	v_cvt_pk_bf16_f32 v70, v64, v65
	v_add_u32_e32 v64, v121, v84
	v_ashrrev_i32_e32 v65, 31, v64
	v_lshlrev_b64 v[64:65], 12, v[64:65]
	v_lshl_add_u64 v[64:65], s[4:5], 0, v[64:65]
	v_lshl_add_u64 v[64:65], v[64:65], 0, v[108:109]
	v_cvt_pk_bf16_f32 v71, v66, v67
	global_store_dwordx4 v[64:65], v[68:71], off
	v_add_u32_e32 v64, 0x80, v152
	v_cvt_pk_bf16_f32 v60, v60, v61
	v_cvt_pk_bf16_f32 v61, v62, v63
	v_cvt_pk_bf16_f32 v62, v56, v57
	v_add_u32_e32 v56, v122, v64
	v_ashrrev_i32_e32 v57, 31, v56
	v_lshlrev_b64 v[56:57], 12, v[56:57]
	v_lshl_add_u64 v[56:57], s[4:5], 0, v[56:57]
	v_lshl_add_u64 v[56:57], v[56:57], 0, v[136:137]
	v_cvt_pk_bf16_f32 v63, v58, v59
	global_store_dwordx4 v[56:57], v[60:63], off
	v_cvt_pk_bf16_f32 v52, v52, v53
	v_cvt_pk_bf16_f32 v53, v54, v55
	v_cvt_pk_bf16_f32 v54, v44, v45
	v_add_u32_e32 v44, v121, v64
	v_ashrrev_i32_e32 v45, 31, v44
	v_lshlrev_b64 v[44:45], 12, v[44:45]
	v_lshl_add_u64 v[44:45], s[4:5], 0, v[44:45]
	v_lshl_add_u64 v[44:45], v[44:45], 0, v[108:109]
	v_cvt_pk_bf16_f32 v55, v46, v47
	global_store_dwordx4 v[44:45], v[52:55], off
	v_cvt_pk_bf16_f32 v44, v48, v49
	v_cvt_pk_bf16_f32 v45, v50, v51
	v_cvt_pk_bf16_f32 v46, v40, v41
	v_cvt_pk_bf16_f32 v47, v42, v43
	s_mov_b64 s[20:21], s[14:15]
	s_nop 0
	v_add_u32_e32 v52, 0x90, v152
	v_add_u32_e32 v40, v122, v52
	v_ashrrev_i32_e32 v41, 31, v40
	v_lshlrev_b64 v[40:41], 12, v[40:41]
	v_lshl_add_u64 v[40:41], s[4:5], 0, v[40:41]
	v_lshl_add_u64 v[40:41], v[40:41], 0, v[136:137]
	global_store_dwordx4 v[40:41], v[44:47], off
	v_cvt_pk_bf16_f32 v36, v36, v37
	v_cvt_pk_bf16_f32 v37, v38, v39
	v_cvt_pk_bf16_f32 v38, v28, v29
	v_add_u32_e32 v28, v121, v52
	v_ashrrev_i32_e32 v29, 31, v28
	v_lshlrev_b64 v[28:29], 12, v[28:29]
	v_lshl_add_u64 v[28:29], s[4:5], 0, v[28:29]
	v_lshl_add_u64 v[28:29], v[28:29], 0, v[108:109]
	v_cvt_pk_bf16_f32 v39, v30, v31
	global_store_dwordx4 v[28:29], v[36:39], off
	v_cvt_pk_bf16_f32 v28, v32, v33
	v_cvt_pk_bf16_f32 v29, v34, v35
	v_cvt_pk_bf16_f32 v30, v24, v25
	v_cvt_pk_bf16_f32 v31, v26, v27
	s_mov_b64 s[18:19], s[12:13]
	s_nop 0
	v_add_u32_e32 v36, 0xa0, v152
	v_add_u32_e32 v24, v122, v36
	v_ashrrev_i32_e32 v25, 31, v24
	v_lshlrev_b64 v[24:25], 12, v[24:25]
	v_lshl_add_u64 v[24:25], s[4:5], 0, v[24:25]
	v_lshl_add_u64 v[24:25], v[24:25], 0, v[136:137]
	global_store_dwordx4 v[24:25], v[28:31], off
	v_cvt_pk_bf16_f32 v20, v20, v21
	v_cvt_pk_bf16_f32 v21, v22, v23
	v_cvt_pk_bf16_f32 v22, v12, v13
	v_add_u32_e32 v12, v121, v36
	v_ashrrev_i32_e32 v13, 31, v12
	v_lshlrev_b64 v[12:13], 12, v[12:13]
	v_lshl_add_u64 v[12:13], s[4:5], 0, v[12:13]
	v_lshl_add_u64 v[12:13], v[12:13], 0, v[108:109]
	v_cvt_pk_bf16_f32 v23, v14, v15
	global_store_dwordx4 v[12:13], v[20:23], off
	v_cvt_pk_bf16_f32 v12, v16, v17
	v_cvt_pk_bf16_f32 v13, v18, v19
	v_cvt_pk_bf16_f32 v14, v8, v9
	v_cvt_pk_bf16_f32 v15, v10, v11
	s_nop 1
	v_add_u32_e32 v20, 0xb0, v152
	v_add_u32_e32 v8, v122, v20
	v_ashrrev_i32_e32 v9, 31, v8
	v_lshlrev_b64 v[8:9], 12, v[8:9]
	v_lshl_add_u64 v[8:9], s[4:5], 0, v[8:9]
	v_lshl_add_u64 v[8:9], v[8:9], 0, v[136:137]
	global_store_dwordx4 v[8:9], v[12:15], off
	v_cvt_pk_bf16_f32 v4, v4, v5
	v_cvt_pk_bf16_f32 v5, v6, v7
	v_cvt_pk_bf16_f32 v6, v0, v1
	v_add_u32_e32 v0, v121, v20
	v_ashrrev_i32_e32 v1, 31, v0
	v_lshlrev_b64 v[0:1], 12, v[0:1]
	v_lshl_add_u64 v[0:1], s[4:5], 0, v[0:1]
	v_lshl_add_u64 v[0:1], v[0:1], 0, v[108:109]
	v_cvt_pk_bf16_f32 v7, v2, v3
	global_store_dwordx4 v[0:1], v[4:7], off
	s_cbranch_vccz .LBB0_666
; #define PG8_WAIT_V(n) asm volatile("s_waitcnt vmcnt(" #n ")" ::: "memory")
; #define PG8_BAR __builtin_amdgcn_s_barrier()
; template <class Epi, class Sched>
; __device__ __forceinline__ void gemm_phase(LAS unsigned char* lds, const Gemm g, const Sched& S, const Epi& E) {
;     ...
;     PG8_WAIT_V(0);
;     if (wr == 0) PG8_BAR;
	s_waitcnt vmcnt(0)
	s_cmpk_gt_u32 s24, 0xff
	s_cbranch_scc1 .LBB0_677
	s_barrier

; #define PG8_STAGE(bufoff, gbase, voff) do { _Pragma("unroll") for (int _i = 0; _i < 2; ++_i) \
;         __builtin_amdgcn_global_load_lds((const unsigned*)((const char*)(gbase) + (voff)[_i]), (LAS unsigned*)(lds + (bufoff) + ldsw + _i * 8192), 16, 0, 0); } while (0)
; #define PG8_LDA(dst, b, h) do { _Pragma("unroll") for (int m = 0; m < 4; ++m) _Pragma("unroll") for (int k = 0; k < 2; ++k) dst[m][k] = *(const LAS bf16x8*)(lds + PG8_SA(b, h) + aoff + m * 2048 + k * 1024); } while (0)
; #define PG8_LDB(dst, b, h) do { _Pragma("unroll") for (int n = 0; n < 2; ++n) _Pragma("unroll") for (int k = 0; k < 2; ++k) dst[n][k] = *(const LAS bf16x8*)(lds + PG8_SB(b, h) + boff + n * 2048 + k * 1024); } while (0)
; #define PG8_MMA(ai, bj, At, Bt) do { __builtin_amdgcn_s_setprio(1); _Pragma("unroll") for (int m = 0; m < 4; ++m) _Pragma("unroll") for (int n = 0; n < 2; ++n) _Pragma("unroll") for (int k = 0; k < 2; ++k) \
;         acc[ai][bj][m][n] = __builtin_amdgcn_mfma_f32_16x16x32_bf16(Bt[n][k], At[m][k], acc[ai][bj][m][n], 0, 0, 0); __builtin_amdgcn_s_setprio(0); } while (0)
; #define PG8_WAIT_L(n) asm volatile("s_waitcnt lgkmcnt(" #n ")" ::: "memory")
; template <class Epi, class Sched>
; __device__ __forceinline__ void gemm_phase(LAS unsigned char* lds, const Gemm g, const Sched& S, const Epi& E) {
;     ...
;         const bool has_next = S.next(ui + 1, nxt);
;         const char* nA = has_next ? (const char*)g.A + (size_t)nxt.pm * tstep : cA; const char* nB = has_next ? (const char*)g.Bt + (size_t)nxt.pn * tstep : cB;
;         for (int t = 0; t < nt; t += 2) {
;             const bool last = (t == nt - 2);
;             const char* a1 = cA + (size_t)(t + 1) * kstep;
;             const char* a2 = last ? nA : cA + (size_t)(t + 2) * kstep; const char* b2 = last ? nB : cB + (size_t)(t + 2) * kstep;
;             const char* a3 = a2 + kstep; const char* b3 = b2 + kstep;
;             PG8_LDB(B0, 0, 0); PG8_SCHED; PG8_LDA(At, 0, 0); PG8_STAGE(PG8_SA(1, 1), a1 + hstep, voffA);
;             PG8_WAIT_L(8); PG8_BAR; PG8_WAIT_L(0); PG8_MMA(0, 0, At, B0); PG8_BAR; PG8_SCHED;
;             PG8_LDB(B1, 0, 1); PG8_STAGE(PG8_SB(0, 0), b2, voffB);
;             PG8_BAR; PG8_WAIT_L(0); PG8_MMA(0, 1, At, B1); PG8_BAR;
;             PG8_LDA(At, 0, 1); PG8_STAGE(PG8_SA(0, 0), a2, voffA);
;             PG8_BAR; PG8_WAIT_L(0); PG8_MMA(1, 0, At, B0); PG8_BAR; PG8_SCHED;
.LBB0_692:
	s_ashr_i32 s19, s18, 31
	v_cmp_lt_i64_e64 s[24:25], s[20:21], 32
	s_lshl_b64 s[20:21], s[18:19], 19
	s_add_u32 s20, s40, s20
	s_addc_u32 s21, s41, s21
	s_and_b64 s[22:23], s[24:25], exec
	s_cselect_b32 s19, s21, s3
	s_cselect_b32 s57, s20, s2
	s_ashr_i32 s17, s16, 31
	s_lshl_b64 s[22:23], s[16:17], 19
	s_add_u32 s22, s28, s22
	s_addc_u32 s23, s29, s23
	s_and_b64 s[24:25], s[24:25], exec
	s_cselect_b32 s17, s23, s5
	s_cselect_b32 s58, s22, s4
	s_add_u32 s2, s2, 0x40080
	s_addc_u32 s3, s3, 0
	s_add_u32 s59, s4, 0x100
	s_addc_u32 s60, s5, 0
	s_mov_b32 s61, -2
	s_waitcnt lgkmcnt(0)
	ds_read_b128 v[140:143], v149
	ds_read_b128 v[154:157], v149 offset:1024
	ds_read_b128 v[158:161], v149 offset:2048
	ds_read_b128 v[162:165], v149 offset:3072
	s_add_u32 s4, s2, 0xfffc0080
	s_addc_u32 s5, s3, -1
	s_cmp_eq_u32 s61, 12
	s_cselect_b32 s25, s19, s5
	s_cselect_b32 s24, s57, s4
	s_cselect_b32 s5, s17, s60
	s_cselect_b32 s4, s58, s59
	s_add_i32 m0, s33, 0xc000
	ds_read_b128 v[166:169], v150
	ds_read_b128 v[170:173], v150 offset:1024
	ds_read_b128 v[174:177], v150 offset:2048
	ds_read_b128 v[178:181], v150 offset:3072
	ds_read_b128 v[182:185], v150 offset:4096
	ds_read_b128 v[186:189], v150 offset:5120
	ds_read_b128 v[190:193], v150 offset:6144
	ds_read_b128 v[194:197], v150 offset:7168
	global_load_lds_dwordx4 v136, s[2:3]
	s_add_i32 m0, s33, 0xe000
	s_nop 0
	global_load_lds_dwordx4 v138, s[2:3]
	s_waitcnt lgkmcnt(8)
	s_waitcnt vmcnt(8)
	s_setprio 1
	s_barrier
	s_waitcnt lgkmcnt(0)
	v_mfma_f32_16x16x32_bf16 v[124:127], v[140:143], v[166:169], 0
	v_mfma_f32_16x16x32_bf16 v[120:123], v[158:161], v[166:169], 0
	v_mfma_f32_16x16x32_bf16 v[108:111], v[140:143], v[174:177], 0
	v_mfma_f32_16x16x32_bf16 v[104:107], v[158:161], v[174:177], 0
	v_mfma_f32_16x16x32_bf16 v[92:95], v[140:143], v[182:185], 0
	v_mfma_f32_16x16x32_bf16 v[88:91], v[158:161], v[182:185], 0
	v_mfma_f32_16x16x32_bf16 v[76:79], v[140:143], v[190:193], 0
	v_mfma_f32_16x16x32_bf16 v[72:75], v[158:161], v[190:193], 0
	v_mfma_f32_16x16x32_bf16 v[124:127], v[154:157], v[170:173], v[124:127]
	v_mfma_f32_16x16x32_bf16 v[120:123], v[162:165], v[170:173], v[120:123]
	v_mfma_f32_16x16x32_bf16 v[108:111], v[154:157], v[178:181], v[108:111]
	v_mfma_f32_16x16x32_bf16 v[104:107], v[162:165], v[178:181], v[104:107]
	v_mfma_f32_16x16x32_bf16 v[92:95], v[154:157], v[186:189], v[92:95]
	v_mfma_f32_16x16x32_bf16 v[88:91], v[162:165], v[186:189], v[88:91]
	v_mfma_f32_16x16x32_bf16 v[76:79], v[154:157], v[194:197], v[76:79]
	v_mfma_f32_16x16x32_bf16 v[72:75], v[162:165], v[194:197], v[72:75]
	s_barrier
	s_setprio 0
	s_add_i32 s62, s47, s31
	s_mov_b32 m0, s62
	ds_read_b128 v[202:205], v151
	ds_read_b128 v[206:209], v151 offset:1024
	ds_read_b128 v[210:213], v151 offset:2048
	ds_read_b128 v[214:217], v151 offset:3072
	global_load_lds_dwordx4 v130, s[4:5]
	s_add_i32 m0, s62, 0x2000
	s_nop 0
	global_load_lds_dwordx4 v134, s[4:5]
	s_waitcnt vmcnt(8)
	s_setprio 1
	s_barrier
	s_waitcnt lgkmcnt(0)
	v_mfma_f32_16x16x32_bf16 v[116:119], v[202:205], v[166:169], 0
	v_mfma_f32_16x16x32_bf16 v[112:115], v[210:213], v[166:169], 0
	v_mfma_f32_16x16x32_bf16 v[100:103], v[202:205], v[174:177], 0
	v_mfma_f32_16x16x32_bf16 v[96:99], v[210:213], v[174:177], 0
	v_mfma_f32_16x16x32_bf16 v[84:87], v[202:205], v[182:185], 0
	v_mfma_f32_16x16x32_bf16 v[80:83], v[210:213], v[182:185], 0
	v_mfma_f32_16x16x32_bf16 v[68:71], v[202:205], v[190:193], 0
	v_mfma_f32_16x16x32_bf16 v[64:67], v[210:213], v[190:193], 0
	v_mfma_f32_16x16x32_bf16 v[116:119], v[206:209], v[170:173], v[116:119]
	v_mfma_f32_16x16x32_bf16 v[112:115], v[214:217], v[170:173], v[112:115]
	v_mfma_f32_16x16x32_bf16 v[100:103], v[206:209], v[178:181], v[100:103]
	v_mfma_f32_16x16x32_bf16 v[96:99], v[214:217], v[178:181], v[96:99]
	v_mfma_f32_16x16x32_bf16 v[84:87], v[206:209], v[186:189], v[84:87]
	v_mfma_f32_16x16x32_bf16 v[80:83], v[214:217], v[186:189], v[80:83]
	v_mfma_f32_16x16x32_bf16 v[68:71], v[206:209], v[194:197], v[68:71]
	v_mfma_f32_16x16x32_bf16 v[64:67], v[214:217], v[194:197], v[64:67]
	s_mov_b32 m0, s33
	v_lshl_add_u64 v[218:219], s[24:25], 0, v[128:129]
	s_barrier
	s_setprio 0
	ds_read_b128 v[166:169], v150 offset:16384
	ds_read_b128 v[170:173], v150 offset:17408
	ds_read_b128 v[174:177], v150 offset:18432
	ds_read_b128 v[178:181], v150 offset:19456
	ds_read_b128 v[182:185], v150 offset:20480
	ds_read_b128 v[186:189], v150 offset:21504
	ds_read_b128 v[190:193], v150 offset:22528
	ds_read_b128 v[194:197], v150 offset:23552
	global_load_lds_dwordx4 v128, s[24:25]
	v_lshl_add_u64 v[220:221], s[24:25], 0, v[132:133]
	s_mov_b32 m0, s34
	s_nop 0
	global_load_lds_dwordx4 v132, s[24:25]
	s_setprio 1
	s_barrier
	s_waitcnt lgkmcnt(0)
	v_mfma_f32_16x16x32_bf16 v[60:63], v[140:143], v[166:169], 0
	v_mfma_f32_16x16x32_bf16 v[56:59], v[158:161], v[166:169], 0
	v_mfma_f32_16x16x32_bf16 v[44:47], v[140:143], v[174:177], 0
	v_mfma_f32_16x16x32_bf16 v[40:43], v[158:161], v[174:177], 0
	v_mfma_f32_16x16x32_bf16 v[28:31], v[140:143], v[182:185], 0
	v_mfma_f32_16x16x32_bf16 v[24:27], v[158:161], v[182:185], 0
	v_mfma_f32_16x16x32_bf16 v[12:15], v[140:143], v[190:193], 0
	v_mfma_f32_16x16x32_bf16 v[8:11], v[158:161], v[190:193], 0
	v_mfma_f32_16x16x32_bf16 v[60:63], v[154:157], v[170:173], v[60:63]
	v_mfma_f32_16x16x32_bf16 v[56:59], v[162:165], v[170:173], v[56:59]
	v_mfma_f32_16x16x32_bf16 v[44:47], v[154:157], v[178:181], v[44:47]
	v_mfma_f32_16x16x32_bf16 v[40:43], v[162:165], v[178:181], v[40:43]
	v_mfma_f32_16x16x32_bf16 v[28:31], v[154:157], v[186:189], v[28:31]
	v_mfma_f32_16x16x32_bf16 v[24:27], v[162:165], v[186:189], v[24:27]
	v_mfma_f32_16x16x32_bf16 v[12:15], v[154:157], v[194:197], v[12:15]
	v_mfma_f32_16x16x32_bf16 v[8:11], v[162:165], v[194:197], v[8:11]
	s_barrier
; #define PG8_STAGE(bufoff, gbase, voff) do { _Pragma("unroll") for (int _i = 0; _i < 2; ++_i) \
;         __builtin_amdgcn_global_load_lds((const unsigned*)((const char*)(gbase) + (voff)[_i]), (LAS unsigned*)(lds + (bufoff) + ldsw + _i * 8192), 16, 0, 0); } while (0)
; #define PG8_LDA(dst, b, h) do { _Pragma("unroll") for (int m = 0; m < 4; ++m) _Pragma("unroll") for (int k = 0; k < 2; ++k) dst[m][k] = *(const LAS bf16x8*)(lds + PG8_SA(b, h) + aoff + m * 2048 + k * 1024); } while (0)
; #define PG8_LDB(dst, b, h) do { _Pragma("unroll") for (int n = 0; n < 2; ++n) _Pragma("unroll") for (int k = 0; k < 2; ++k) dst[n][k] = *(const LAS bf16x8*)(lds + PG8_SB(b, h) + boff + n * 2048 + k * 1024); } while (0)
; #define PG8_MMA(ai, bj, At, Bt) do { __builtin_amdgcn_s_setprio(1); _Pragma("unroll") for (int m = 0; m < 4; ++m) _Pragma("unroll") for (int n = 0; n < 2; ++n) _Pragma("unroll") for (int k = 0; k < 2; ++k) \
;         acc[ai][bj][m][n] = __builtin_amdgcn_mfma_f32_16x16x32_bf16(Bt[n][k], At[m][k], acc[ai][bj][m][n], 0, 0, 0); __builtin_amdgcn_s_setprio(0); } while (0)
; #define PG8_WAIT_V(n) asm volatile("s_waitcnt vmcnt(" #n ")" ::: "memory")
; #define PG8_WAIT_L(n) asm volatile("s_waitcnt lgkmcnt(" #n ")" ::: "memory")
; #define PG8_BAR __builtin_amdgcn_s_barrier()
; #define PG8_SCHED __builtin_amdgcn_sched_barrier(0)
; template <class Epi, class Sched>
; __device__ __forceinline__ void gemm_phase(LAS unsigned char* lds, const Gemm g, const Sched& S, const Epi& E) {
;     ...
;             PG8_STAGE(PG8_SB(0, 1), b2 + hstep, voffB);
;             PG8_WAIT_V(6); PG8_BAR; PG8_MMA(1, 1, At, B1); PG8_BAR;
;             PG8_LDB(B0, 1, 0); PG8_SCHED; PG8_LDA(At, 1, 0); PG8_STAGE(PG8_SA(0, 1), a2 + hstep, voffA);
;             PG8_WAIT_L(8); PG8_BAR; PG8_WAIT_L(0); PG8_MMA(0, 0, At, B0); PG8_BAR; PG8_SCHED;
;             PG8_LDB(B1, 1, 1); PG8_STAGE(PG8_SB(1, 0), b3, voffB);
;             PG8_BAR; PG8_WAIT_L(0); PG8_MMA(0, 1, At, B1); PG8_BAR;
;             PG8_LDA(At, 1, 1); PG8_STAGE(PG8_SA(1, 0), a3, voffA);
;             PG8_BAR; PG8_WAIT_L(0); PG8_MMA(1, 0, At, B0); PG8_BAR; PG8_SCHED;
	s_setprio 0
	s_add_u32 s62, s4, 0x40000
	s_addc_u32 s63, s5, 0
	s_add_i32 s64, s48, s31
	s_mov_b32 m0, s64
	s_nop 0
	global_load_lds_dwordx4 v130, s[62:63]
	s_add_i32 m0, s64, 0x2000
	s_nop 0
	global_load_lds_dwordx4 v134, s[62:63]
	s_add_u32 s24, s24, 0x40000
	s_addc_u32 s25, s25, 0
	s_mov_b32 m0, s35
	s_nop 0
	global_load_lds_dwordx4 v128, s[24:25]
	s_mov_b32 m0, s36
	s_nop 0
	global_load_lds_dwordx4 v132, s[24:25]
	s_waitcnt vmcnt(10)
	s_setprio 1
	s_barrier
	v_mfma_f32_16x16x32_bf16 v[52:55], v[202:205], v[166:169], 0
	v_mfma_f32_16x16x32_bf16 v[48:51], v[210:213], v[166:169], 0
	v_mfma_f32_16x16x32_bf16 v[36:39], v[202:205], v[174:177], 0
	v_mfma_f32_16x16x32_bf16 v[32:35], v[210:213], v[174:177], 0
	v_mfma_f32_16x16x32_bf16 v[20:23], v[202:205], v[182:185], 0
	v_mfma_f32_16x16x32_bf16 v[16:19], v[210:213], v[182:185], 0
	v_mfma_f32_16x16x32_bf16 v[4:7], v[202:205], v[190:193], 0
	v_mfma_f32_16x16x32_bf16 v[0:3], v[210:213], v[190:193], 0
	v_mfma_f32_16x16x32_bf16 v[52:55], v[206:209], v[170:173], v[52:55]
	v_mfma_f32_16x16x32_bf16 v[48:51], v[214:217], v[170:173], v[48:51]
	v_mfma_f32_16x16x32_bf16 v[36:39], v[206:209], v[178:181], v[36:39]
	v_mfma_f32_16x16x32_bf16 v[32:35], v[214:217], v[178:181], v[32:35]
	v_mfma_f32_16x16x32_bf16 v[20:23], v[206:209], v[186:189], v[20:23]
	v_mfma_f32_16x16x32_bf16 v[16:19], v[214:217], v[186:189], v[16:19]
	v_mfma_f32_16x16x32_bf16 v[4:7], v[206:209], v[194:197], v[4:7]
	v_mfma_f32_16x16x32_bf16 v[0:3], v[214:217], v[194:197], v[0:3]
	s_add_i32 s62, 0, 0x18000
	v_add_u32_e32 v162, s62, v148
	s_barrier
	s_setprio 0
	ds_read_b128 v[140:143], v162
	ds_read_b128 v[154:157], v162 offset:1024
	ds_read_b128 v[158:161], v162 offset:2048
	ds_read_b128 v[162:165], v162 offset:3072
	ds_read_b128 v[166:169], v150 offset:32768
	ds_read_b128 v[170:173], v150 offset:33792
	ds_read_b128 v[174:177], v150 offset:34816
	ds_read_b128 v[178:181], v150 offset:35840
	ds_read_b128 v[182:185], v150 offset:36864
	ds_read_b128 v[186:189], v150 offset:37888
	ds_read_b128 v[190:193], v150 offset:38912
	ds_read_b128 v[194:197], v150 offset:39936
	s_waitcnt lgkmcnt(8)
	s_waitcnt vmcnt(8)
	s_setprio 1
	s_barrier
	s_waitcnt lgkmcnt(0)
	v_mfma_f32_16x16x32_bf16 v[124:127], v[140:143], v[166:169], v[124:127]
	v_mfma_f32_16x16x32_bf16 v[120:123], v[158:161], v[166:169], v[120:123]
	v_mfma_f32_16x16x32_bf16 v[108:111], v[140:143], v[174:177], v[108:111]
	v_mfma_f32_16x16x32_bf16 v[104:107], v[158:161], v[174:177], v[104:107]
	v_mfma_f32_16x16x32_bf16 v[92:95], v[140:143], v[182:185], v[92:95]
	v_mfma_f32_16x16x32_bf16 v[88:91], v[158:161], v[182:185], v[88:91]
	v_mfma_f32_16x16x32_bf16 v[76:79], v[140:143], v[190:193], v[76:79]
	v_mfma_f32_16x16x32_bf16 v[72:75], v[158:161], v[190:193], v[72:75]
	v_mfma_f32_16x16x32_bf16 v[124:127], v[154:157], v[170:173], v[124:127]
	v_mfma_f32_16x16x32_bf16 v[120:123], v[162:165], v[170:173], v[120:123]
	v_mfma_f32_16x16x32_bf16 v[108:111], v[154:157], v[178:181], v[108:111]
	v_mfma_f32_16x16x32_bf16 v[104:107], v[162:165], v[178:181], v[104:107]
	v_mfma_f32_16x16x32_bf16 v[92:95], v[154:157], v[186:189], v[92:95]
	v_mfma_f32_16x16x32_bf16 v[88:91], v[162:165], v[186:189], v[88:91]
	v_mfma_f32_16x16x32_bf16 v[76:79], v[154:157], v[194:197], v[76:79]
	v_mfma_f32_16x16x32_bf16 v[72:75], v[162:165], v[194:197], v[72:75]
	s_barrier
	s_setprio 0
	s_add_i32 s24, 0, 0x1c000
	s_add_i32 s25, s62, s31
	v_add_u32_e32 v214, s24, v148
	s_add_u32 s0, s4, 0x80
	s_addc_u32 s1, s5, 0
	s_mov_b32 m0, s25
	ds_read_b128 v[202:205], v214
	ds_read_b128 v[206:209], v214 offset:1024
	ds_read_b128 v[210:213], v214 offset:2048
	ds_read_b128 v[214:217], v214 offset:3072
	global_load_lds_dwordx4 v130, s[0:1]
	s_add_i32 m0, s25, 0x2000
	s_nop 0
	global_load_lds_dwordx4 v134, s[0:1]
	s_waitcnt vmcnt(8)
	s_setprio 1
	s_barrier
	s_waitcnt lgkmcnt(0)
	v_mfma_f32_16x16x32_bf16 v[116:119], v[202:205], v[166:169], v[116:119]
	v_mfma_f32_16x16x32_bf16 v[112:115], v[210:213], v[166:169], v[112:115]
	v_mfma_f32_16x16x32_bf16 v[100:103], v[202:205], v[174:177], v[100:103]
	v_mfma_f32_16x16x32_bf16 v[96:99], v[210:213], v[174:177], v[96:99]
	v_mfma_f32_16x16x32_bf16 v[84:87], v[202:205], v[182:185], v[84:87]
	v_mfma_f32_16x16x32_bf16 v[80:83], v[210:213], v[182:185], v[80:83]
	v_mfma_f32_16x16x32_bf16 v[68:71], v[202:205], v[190:193], v[68:71]
	v_mfma_f32_16x16x32_bf16 v[64:67], v[210:213], v[190:193], v[64:67]
	v_mfma_f32_16x16x32_bf16 v[116:119], v[206:209], v[170:173], v[116:119]
	v_mfma_f32_16x16x32_bf16 v[112:115], v[214:217], v[170:173], v[112:115]
	v_mfma_f32_16x16x32_bf16 v[100:103], v[206:209], v[178:181], v[100:103]
	v_mfma_f32_16x16x32_bf16 v[96:99], v[214:217], v[178:181], v[96:99]
	v_mfma_f32_16x16x32_bf16 v[84:87], v[206:209], v[186:189], v[84:87]
	v_mfma_f32_16x16x32_bf16 v[80:83], v[214:217], v[186:189], v[80:83]
	v_mfma_f32_16x16x32_bf16 v[68:71], v[206:209], v[194:197], v[68:71]
	v_mfma_f32_16x16x32_bf16 v[64:67], v[214:217], v[194:197], v[64:67]
	s_mov_b32 m0, s44
	s_mov_b64 s[0:1], 0x80
	v_lshl_add_u64 v[144:145], v[218:219], 0, s[0:1]
	s_barrier
	s_setprio 0
	ds_read_b128 v[166:169], v150 offset:49152
	ds_read_b128 v[170:173], v150 offset:50176
	ds_read_b128 v[174:177], v150 offset:51200
	ds_read_b128 v[178:181], v150 offset:52224
	ds_read_b128 v[182:185], v150 offset:53248
	ds_read_b128 v[186:189], v150 offset:54272
	ds_read_b128 v[190:193], v150 offset:55296
	ds_read_b128 v[194:197], v150 offset:56320
	global_load_lds_dwordx4 v[144:145], off
	v_lshl_add_u64 v[144:145], v[220:221], 0, s[0:1]
	s_mov_b32 m0, s45
	s_nop 0
	global_load_lds_dwordx4 v[144:145], off
	s_setprio 1
	s_barrier
; #define PG8_STAGE(bufoff, gbase, voff) do { _Pragma("unroll") for (int _i = 0; _i < 2; ++_i) \
;         __builtin_amdgcn_global_load_lds((const unsigned*)((const char*)(gbase) + (voff)[_i]), (LAS unsigned*)(lds + (bufoff) + ldsw + _i * 8192), 16, 0, 0); } while (0)
; #define PG8_LDA(dst, b, h) do { _Pragma("unroll") for (int m = 0; m < 4; ++m) _Pragma("unroll") for (int k = 0; k < 2; ++k) dst[m][k] = *(const LAS bf16x8*)(lds + PG8_SA(b, h) + aoff + m * 2048 + k * 1024); } while (0)
; #define PG8_LDB(dst, b, h) do { _Pragma("unroll") for (int n = 0; n < 2; ++n) _Pragma("unroll") for (int k = 0; k < 2; ++k) dst[n][k] = *(const LAS bf16x8*)(lds + PG8_SB(b, h) + boff + n * 2048 + k * 1024); } while (0)
; #define PG8_WAIT_V(n) asm volatile("s_waitcnt vmcnt(" #n ")" ::: "memory")
; #define PG8_WAIT_L(n) asm volatile("s_waitcnt lgkmcnt(" #n ")" ::: "memory")
; #define PG8_BAR __builtin_amdgcn_s_barrier()
; #define PG8_SCHED __builtin_amdgcn_sched_barrier(0)
; template <class Epi, class Sched>
; __device__ __forceinline__ void gemm_phase(LAS unsigned char* lds, const Gemm g, const Sched& S, const Epi& E) {
;     ...
;             PG8_LDB(B0, 0, 0); PG8_SCHED; PG8_LDA(At, 0, 0); PG8_STAGE(PG8_SA(1, 1), a1 + hstep, voffA);
;             PG8_WAIT_L(8); PG8_BAR; PG8_WAIT_L(0); PG8_MMA(0, 0, At, B0); PG8_BAR; PG8_SCHED;
;             PG8_LDB(B1, 0, 1); PG8_STAGE(PG8_SB(0, 0), b2, voffB);
;             PG8_BAR; PG8_WAIT_L(0); PG8_MMA(0, 1, At, B1); PG8_BAR;
;             PG8_LDA(At, 0, 1); PG8_STAGE(PG8_SA(0, 0), a2, voffA);
;             PG8_BAR; PG8_WAIT_L(0); PG8_MMA(1, 0, At, B0); PG8_BAR; PG8_SCHED;
;             PG8_STAGE(PG8_SB(0, 1), b2 + hstep, voffB);
;             PG8_WAIT_V(6); PG8_BAR; PG8_MMA(1, 1, At, B1); PG8_BAR;
;             PG8_LDB(B0, 1, 0); PG8_SCHED; PG8_LDA(At, 1, 0); PG8_STAGE(PG8_SA(0, 1), a2 + hstep, voffA);
;             PG8_WAIT_L(8); PG8_BAR; PG8_WAIT_L(0); PG8_MMA(0, 0, At, B0); PG8_BAR; PG8_SCHED;
;             PG8_LDB(B1, 1, 1); PG8_STAGE(PG8_SB(1, 0), b3, voffB);
;             PG8_BAR; PG8_WAIT_L(0); PG8_MMA(0, 1, At, B1); PG8_BAR;
;             PG8_LDA(At, 1, 1); PG8_STAGE(PG8_SA(1, 0), a3, voffA);
;             PG8_BAR; PG8_WAIT_L(0); PG8_MMA(1, 0, At, B0); PG8_BAR; PG8_SCHED;
;             PG8_STAGE(PG8_SB(1, 1), b3 + hstep, voffB);
;             PG8_WAIT_V(6); PG8_BAR; PG8_MMA(1, 1, At, B1); PG8_BAR;
	s_waitcnt lgkmcnt(0)
	v_mfma_f32_16x16x32_bf16 v[60:63], v[140:143], v[166:169], v[60:63]
	v_mfma_f32_16x16x32_bf16 v[56:59], v[158:161], v[166:169], v[56:59]
	v_mfma_f32_16x16x32_bf16 v[44:47], v[140:143], v[174:177], v[44:47]
	v_mfma_f32_16x16x32_bf16 v[40:43], v[158:161], v[174:177], v[40:43]
	v_mfma_f32_16x16x32_bf16 v[28:31], v[140:143], v[182:185], v[28:31]
	v_mfma_f32_16x16x32_bf16 v[24:27], v[158:161], v[182:185], v[24:27]
	v_mfma_f32_16x16x32_bf16 v[12:15], v[140:143], v[190:193], v[12:15]
	v_mfma_f32_16x16x32_bf16 v[8:11], v[158:161], v[190:193], v[8:11]
	v_mfma_f32_16x16x32_bf16 v[60:63], v[154:157], v[170:173], v[60:63]
	v_mfma_f32_16x16x32_bf16 v[56:59], v[162:165], v[170:173], v[56:59]
	v_mfma_f32_16x16x32_bf16 v[44:47], v[154:157], v[178:181], v[44:47]
	v_mfma_f32_16x16x32_bf16 v[40:43], v[162:165], v[178:181], v[40:43]
	v_mfma_f32_16x16x32_bf16 v[28:31], v[154:157], v[186:189], v[28:31]
	v_mfma_f32_16x16x32_bf16 v[24:27], v[162:165], v[186:189], v[24:27]
	v_mfma_f32_16x16x32_bf16 v[12:15], v[154:157], v[194:197], v[12:15]
	v_mfma_f32_16x16x32_bf16 v[8:11], v[162:165], v[194:197], v[8:11]
	s_barrier
	s_setprio 0
	s_add_u32 s4, s4, 0x40080
	s_addc_u32 s5, s5, 0
	s_add_i32 s24, s24, s31
	s_mov_b32 m0, s24
	s_nop 0
	global_load_lds_dwordx4 v130, s[4:5]
	s_add_i32 m0, s24, 0x2000
	s_nop 0
	global_load_lds_dwordx4 v134, s[4:5]
	s_waitcnt vmcnt(8)
	s_setprio 1
	s_barrier
	v_mfma_f32_16x16x32_bf16 v[52:55], v[202:205], v[166:169], v[52:55]
	v_mfma_f32_16x16x32_bf16 v[48:51], v[210:213], v[166:169], v[48:51]
	v_mfma_f32_16x16x32_bf16 v[36:39], v[202:205], v[174:177], v[36:39]
	v_mfma_f32_16x16x32_bf16 v[32:35], v[210:213], v[174:177], v[32:35]
	v_mfma_f32_16x16x32_bf16 v[20:23], v[202:205], v[182:185], v[20:23]
	v_mfma_f32_16x16x32_bf16 v[16:19], v[210:213], v[182:185], v[16:19]
	v_mfma_f32_16x16x32_bf16 v[4:7], v[202:205], v[190:193], v[4:7]
	v_mfma_f32_16x16x32_bf16 v[0:3], v[210:213], v[190:193], v[0:3]
	v_mfma_f32_16x16x32_bf16 v[52:55], v[206:209], v[170:173], v[52:55]
	v_mfma_f32_16x16x32_bf16 v[48:51], v[214:217], v[170:173], v[48:51]
	v_mfma_f32_16x16x32_bf16 v[36:39], v[206:209], v[178:181], v[36:39]
	v_mfma_f32_16x16x32_bf16 v[32:35], v[214:217], v[178:181], v[32:35]
	v_mfma_f32_16x16x32_bf16 v[20:23], v[206:209], v[186:189], v[20:23]
	v_mfma_f32_16x16x32_bf16 v[16:19], v[214:217], v[186:189], v[16:19]
	v_mfma_f32_16x16x32_bf16 v[4:7], v[206:209], v[194:197], v[4:7]
	v_mfma_f32_16x16x32_bf16 v[0:3], v[214:217], v[194:197], v[0:3]
	s_add_i32 s61, s61, 2
	s_add_u32 s2, s2, 0x100
	s_addc_u32 s3, s3, 0
	s_add_u32 s59, s59, 0x100
	s_addc_u32 s60, s60, 0
	s_cmp_gt_u32 s61, 13
	s_barrier
	s_setprio 0
.LBB0_693:
	ds_read_b128 v[140:143], v149
	ds_read_b128 v[154:157], v149 offset:1024
	ds_read_b128 v[158:161], v149 offset:2048
	ds_read_b128 v[162:165], v149 offset:3072
	s_add_u32 s4, s2, 0xfffc0080
	s_addc_u32 s5, s3, -1
	s_cmp_eq_u32 s61, 12
	s_cselect_b32 s25, s19, s5
	s_cselect_b32 s24, s57, s4
	s_cselect_b32 s5, s17, s60
	s_cselect_b32 s4, s58, s59
	s_add_i32 m0, s33, 0xc000
	ds_read_b128 v[166:169], v150
	ds_read_b128 v[170:173], v150 offset:1024
	ds_read_b128 v[174:177], v150 offset:2048
	ds_read_b128 v[178:181], v150 offset:3072
	ds_read_b128 v[182:185], v150 offset:4096
	ds_read_b128 v[186:189], v150 offset:5120
	ds_read_b128 v[190:193], v150 offset:6144
	ds_read_b128 v[194:197], v150 offset:7168
	global_load_lds_dwordx4 v136, s[2:3]
	s_add_i32 m0, s33, 0xe000
	s_nop 0
	global_load_lds_dwordx4 v138, s[2:3]
	s_waitcnt lgkmcnt(8)
	s_waitcnt vmcnt(8)
	s_setprio 1
	s_barrier
	s_waitcnt lgkmcnt(0)
	v_mfma_f32_16x16x32_bf16 v[124:127], v[140:143], v[166:169], v[124:127]
	v_mfma_f32_16x16x32_bf16 v[120:123], v[158:161], v[166:169], v[120:123]
	v_mfma_f32_16x16x32_bf16 v[108:111], v[140:143], v[174:177], v[108:111]
	v_mfma_f32_16x16x32_bf16 v[104:107], v[158:161], v[174:177], v[104:107]
	v_mfma_f32_16x16x32_bf16 v[92:95], v[140:143], v[182:185], v[92:95]
	v_mfma_f32_16x16x32_bf16 v[88:91], v[158:161], v[182:185], v[88:91]
	v_mfma_f32_16x16x32_bf16 v[76:79], v[140:143], v[190:193], v[76:79]
	v_mfma_f32_16x16x32_bf16 v[72:75], v[158:161], v[190:193], v[72:75]
	v_mfma_f32_16x16x32_bf16 v[124:127], v[154:157], v[170:173], v[124:127]
	v_mfma_f32_16x16x32_bf16 v[120:123], v[162:165], v[170:173], v[120:123]
	v_mfma_f32_16x16x32_bf16 v[108:111], v[154:157], v[178:181], v[108:111]
	v_mfma_f32_16x16x32_bf16 v[104:107], v[162:165], v[178:181], v[104:107]
	v_mfma_f32_16x16x32_bf16 v[92:95], v[154:157], v[186:189], v[92:95]
	v_mfma_f32_16x16x32_bf16 v[88:91], v[162:165], v[186:189], v[88:91]
	v_mfma_f32_16x16x32_bf16 v[76:79], v[154:157], v[194:197], v[76:79]
	v_mfma_f32_16x16x32_bf16 v[72:75], v[162:165], v[194:197], v[72:75]
	s_barrier
	s_setprio 0
	s_add_i32 s62, s47, s31
	s_mov_b32 m0, s62
	ds_read_b128 v[202:205], v151
	ds_read_b128 v[206:209], v151 offset:1024
	ds_read_b128 v[210:213], v151 offset:2048
	ds_read_b128 v[214:217], v151 offset:3072
	global_load_lds_dwordx4 v130, s[4:5]
	s_add_i32 m0, s62, 0x2000
	s_nop 0
	global_load_lds_dwordx4 v134, s[4:5]
	s_waitcnt vmcnt(8)
	s_setprio 1
	s_barrier
; #define PG8_STAGE(bufoff, gbase, voff) do { _Pragma("unroll") for (int _i = 0; _i < 2; ++_i) \
;         __builtin_amdgcn_global_load_lds((const unsigned*)((const char*)(gbase) + (voff)[_i]), (LAS unsigned*)(lds + (bufoff) + ldsw + _i * 8192), 16, 0, 0); } while (0)
; #define PG8_LDA(dst, b, h) do { _Pragma("unroll") for (int m = 0; m < 4; ++m) _Pragma("unroll") for (int k = 0; k < 2; ++k) dst[m][k] = *(const LAS bf16x8*)(lds + PG8_SA(b, h) + aoff + m * 2048 + k * 1024); } while (0)
; #define PG8_LDB(dst, b, h) do { _Pragma("unroll") for (int n = 0; n < 2; ++n) _Pragma("unroll") for (int k = 0; k < 2; ++k) dst[n][k] = *(const LAS bf16x8*)(lds + PG8_SB(b, h) + boff + n * 2048 + k * 1024); } while (0)
; #define PG8_MMA(ai, bj, At, Bt) do { __builtin_amdgcn_s_setprio(1); _Pragma("unroll") for (int m = 0; m < 4; ++m) _Pragma("unroll") for (int n = 0; n < 2; ++n) _Pragma("unroll") for (int k = 0; k < 2; ++k) \
;         acc[ai][bj][m][n] = __builtin_amdgcn_mfma_f32_16x16x32_bf16(Bt[n][k], At[m][k], acc[ai][bj][m][n], 0, 0, 0); __builtin_amdgcn_s_setprio(0); } while (0)
; #define PG8_WAIT_V(n) asm volatile("s_waitcnt vmcnt(" #n ")" ::: "memory")
; #define PG8_WAIT_L(n) asm volatile("s_waitcnt lgkmcnt(" #n ")" ::: "memory")
; #define PG8_BAR __builtin_amdgcn_s_barrier()
; #define PG8_SCHED __builtin_amdgcn_sched_barrier(0)
; template <class Epi, class Sched>
; __device__ __forceinline__ void gemm_phase(LAS unsigned char* lds, const Gemm g, const Sched& S, const Epi& E) {
;     ...
;             PG8_BAR; PG8_WAIT_L(0); PG8_MMA(0, 1, At, B1); PG8_BAR;
;             PG8_LDA(At, 0, 1); PG8_STAGE(PG8_SA(0, 0), a2, voffA);
;             PG8_BAR; PG8_WAIT_L(0); PG8_MMA(1, 0, At, B0); PG8_BAR; PG8_SCHED;
;             PG8_STAGE(PG8_SB(0, 1), b2 + hstep, voffB);
;             PG8_WAIT_V(6); PG8_BAR; PG8_MMA(1, 1, At, B1); PG8_BAR;
;             PG8_LDB(B0, 1, 0); PG8_SCHED; PG8_LDA(At, 1, 0); PG8_STAGE(PG8_SA(0, 1), a2 + hstep, voffA);
	s_waitcnt lgkmcnt(0)
	v_mfma_f32_16x16x32_bf16 v[116:119], v[202:205], v[166:169], v[116:119]
	v_mfma_f32_16x16x32_bf16 v[112:115], v[210:213], v[166:169], v[112:115]
	v_mfma_f32_16x16x32_bf16 v[100:103], v[202:205], v[174:177], v[100:103]
	v_mfma_f32_16x16x32_bf16 v[96:99], v[210:213], v[174:177], v[96:99]
	v_mfma_f32_16x16x32_bf16 v[84:87], v[202:205], v[182:185], v[84:87]
	v_mfma_f32_16x16x32_bf16 v[80:83], v[210:213], v[182:185], v[80:83]
	v_mfma_f32_16x16x32_bf16 v[68:71], v[202:205], v[190:193], v[68:71]
	v_mfma_f32_16x16x32_bf16 v[64:67], v[210:213], v[190:193], v[64:67]
	v_mfma_f32_16x16x32_bf16 v[116:119], v[206:209], v[170:173], v[116:119]
	v_mfma_f32_16x16x32_bf16 v[112:115], v[214:217], v[170:173], v[112:115]
	v_mfma_f32_16x16x32_bf16 v[100:103], v[206:209], v[178:181], v[100:103]
	v_mfma_f32_16x16x32_bf16 v[96:99], v[214:217], v[178:181], v[96:99]
	v_mfma_f32_16x16x32_bf16 v[84:87], v[206:209], v[186:189], v[84:87]
	v_mfma_f32_16x16x32_bf16 v[80:83], v[214:217], v[186:189], v[80:83]
	v_mfma_f32_16x16x32_bf16 v[68:71], v[206:209], v[194:197], v[68:71]
	v_mfma_f32_16x16x32_bf16 v[64:67], v[214:217], v[194:197], v[64:67]
	s_mov_b32 m0, s33
	v_lshl_add_u64 v[218:219], s[24:25], 0, v[128:129]
	s_barrier
	s_setprio 0
	ds_read_b128 v[166:169], v150 offset:16384
	ds_read_b128 v[170:173], v150 offset:17408
	ds_read_b128 v[174:177], v150 offset:18432
	ds_read_b128 v[178:181], v150 offset:19456
	ds_read_b128 v[182:185], v150 offset:20480
	ds_read_b128 v[186:189], v150 offset:21504
	ds_read_b128 v[190:193], v150 offset:22528
	ds_read_b128 v[194:197], v150 offset:23552
	global_load_lds_dwordx4 v128, s[24:25]
	v_lshl_add_u64 v[220:221], s[24:25], 0, v[132:133]
	s_mov_b32 m0, s34
	s_nop 0
	global_load_lds_dwordx4 v132, s[24:25]
	s_setprio 1
	s_barrier
	s_waitcnt lgkmcnt(0)
	v_mfma_f32_16x16x32_bf16 v[60:63], v[140:143], v[166:169], v[60:63]
	v_mfma_f32_16x16x32_bf16 v[56:59], v[158:161], v[166:169], v[56:59]
	v_mfma_f32_16x16x32_bf16 v[44:47], v[140:143], v[174:177], v[44:47]
	v_mfma_f32_16x16x32_bf16 v[40:43], v[158:161], v[174:177], v[40:43]
	v_mfma_f32_16x16x32_bf16 v[28:31], v[140:143], v[182:185], v[28:31]
	v_mfma_f32_16x16x32_bf16 v[24:27], v[158:161], v[182:185], v[24:27]
	v_mfma_f32_16x16x32_bf16 v[12:15], v[140:143], v[190:193], v[12:15]
	v_mfma_f32_16x16x32_bf16 v[8:11], v[158:161], v[190:193], v[8:11]
	v_mfma_f32_16x16x32_bf16 v[60:63], v[154:157], v[170:173], v[60:63]
	v_mfma_f32_16x16x32_bf16 v[56:59], v[162:165], v[170:173], v[56:59]
	v_mfma_f32_16x16x32_bf16 v[44:47], v[154:157], v[178:181], v[44:47]
	v_mfma_f32_16x16x32_bf16 v[40:43], v[162:165], v[178:181], v[40:43]
	v_mfma_f32_16x16x32_bf16 v[28:31], v[154:157], v[186:189], v[28:31]
	v_mfma_f32_16x16x32_bf16 v[24:27], v[162:165], v[186:189], v[24:27]
	v_mfma_f32_16x16x32_bf16 v[12:15], v[154:157], v[194:197], v[12:15]
	v_mfma_f32_16x16x32_bf16 v[8:11], v[162:165], v[194:197], v[8:11]
	s_barrier
	s_setprio 0
	s_add_u32 s62, s4, 0x40000
	s_addc_u32 s63, s5, 0
	s_add_i32 s64, s48, s31
	s_mov_b32 m0, s64
	s_nop 0
	global_load_lds_dwordx4 v130, s[62:63]
	s_add_i32 m0, s64, 0x2000
	s_nop 0
	global_load_lds_dwordx4 v134, s[62:63]
	s_add_u32 s24, s24, 0x40000
	s_addc_u32 s25, s25, 0
	s_mov_b32 m0, s35
	s_nop 0
	global_load_lds_dwordx4 v128, s[24:25]
	s_mov_b32 m0, s36
	s_nop 0
	global_load_lds_dwordx4 v132, s[24:25]
	s_waitcnt vmcnt(10)
	s_setprio 1
	s_barrier
	v_mfma_f32_16x16x32_bf16 v[52:55], v[202:205], v[166:169], v[52:55]
	v_mfma_f32_16x16x32_bf16 v[48:51], v[210:213], v[166:169], v[48:51]
	v_mfma_f32_16x16x32_bf16 v[36:39], v[202:205], v[174:177], v[36:39]
	v_mfma_f32_16x16x32_bf16 v[32:35], v[210:213], v[174:177], v[32:35]
	v_mfma_f32_16x16x32_bf16 v[20:23], v[202:205], v[182:185], v[20:23]
	v_mfma_f32_16x16x32_bf16 v[16:19], v[210:213], v[182:185], v[16:19]
	v_mfma_f32_16x16x32_bf16 v[4:7], v[202:205], v[190:193], v[4:7]
	v_mfma_f32_16x16x32_bf16 v[0:3], v[210:213], v[190:193], v[0:3]
	v_mfma_f32_16x16x32_bf16 v[52:55], v[206:209], v[170:173], v[52:55]
	v_mfma_f32_16x16x32_bf16 v[48:51], v[214:217], v[170:173], v[48:51]
	v_mfma_f32_16x16x32_bf16 v[36:39], v[206:209], v[178:181], v[36:39]
	v_mfma_f32_16x16x32_bf16 v[32:35], v[214:217], v[178:181], v[32:35]
	v_mfma_f32_16x16x32_bf16 v[20:23], v[206:209], v[186:189], v[20:23]
	v_mfma_f32_16x16x32_bf16 v[16:19], v[214:217], v[186:189], v[16:19]
	v_mfma_f32_16x16x32_bf16 v[4:7], v[206:209], v[194:197], v[4:7]
	v_mfma_f32_16x16x32_bf16 v[0:3], v[214:217], v[194:197], v[0:3]
	s_add_i32 s62, 0, 0x18000
	v_add_u32_e32 v162, s62, v148
	s_barrier
	s_setprio 0
	ds_read_b128 v[140:143], v162
	ds_read_b128 v[154:157], v162 offset:1024
	ds_read_b128 v[158:161], v162 offset:2048
	ds_read_b128 v[162:165], v162 offset:3072
	ds_read_b128 v[166:169], v150 offset:32768
	ds_read_b128 v[170:173], v150 offset:33792
	ds_read_b128 v[174:177], v150 offset:34816
	ds_read_b128 v[178:181], v150 offset:35840
	ds_read_b128 v[182:185], v150 offset:36864
	ds_read_b128 v[186:189], v150 offset:37888
	ds_read_b128 v[190:193], v150 offset:38912
	ds_read_b128 v[194:197], v150 offset:39936
	s_waitcnt lgkmcnt(8)
	s_waitcnt vmcnt(8)
	s_setprio 1
	s_barrier
; #define PG8_STAGE(bufoff, gbase, voff) do { _Pragma("unroll") for (int _i = 0; _i < 2; ++_i) \
;         __builtin_amdgcn_global_load_lds((const unsigned*)((const char*)(gbase) + (voff)[_i]), (LAS unsigned*)(lds + (bufoff) + ldsw + _i * 8192), 16, 0, 0); } while (0)
; #define PG8_LDA(dst, b, h) do { _Pragma("unroll") for (int m = 0; m < 4; ++m) _Pragma("unroll") for (int k = 0; k < 2; ++k) dst[m][k] = *(const LAS bf16x8*)(lds + PG8_SA(b, h) + aoff + m * 2048 + k * 1024); } while (0)
; #define PG8_LDB(dst, b, h) do { _Pragma("unroll") for (int n = 0; n < 2; ++n) _Pragma("unroll") for (int k = 0; k < 2; ++k) dst[n][k] = *(const LAS bf16x8*)(lds + PG8_SB(b, h) + boff + n * 2048 + k * 1024); } while (0)
; #define PG8_MMA(ai, bj, At, Bt) do { __builtin_amdgcn_s_setprio(1); _Pragma("unroll") for (int m = 0; m < 4; ++m) _Pragma("unroll") for (int n = 0; n < 2; ++n) _Pragma("unroll") for (int k = 0; k < 2; ++k) \
;         acc[ai][bj][m][n] = __builtin_amdgcn_mfma_f32_16x16x32_bf16(Bt[n][k], At[m][k], acc[ai][bj][m][n], 0, 0, 0); __builtin_amdgcn_s_setprio(0); } while (0)
; #define PG8_WAIT_V(n) asm volatile("s_waitcnt vmcnt(" #n ")" ::: "memory")
; #define PG8_WAIT_L(n) asm volatile("s_waitcnt lgkmcnt(" #n ")" ::: "memory")
; #define PG8_BAR __builtin_amdgcn_s_barrier()
; #define PG8_SCHED __builtin_amdgcn_sched_barrier(0)
; template <class Epi, class Sched>
; __device__ __forceinline__ void gemm_phase(LAS unsigned char* lds, const Gemm g, const Sched& S, const Epi& E) {
;     ...
;             PG8_WAIT_L(8); PG8_BAR; PG8_WAIT_L(0); PG8_MMA(0, 0, At, B0); PG8_BAR; PG8_SCHED;
;             PG8_LDB(B1, 1, 1); PG8_STAGE(PG8_SB(1, 0), b3, voffB);
;             PG8_BAR; PG8_WAIT_L(0); PG8_MMA(0, 1, At, B1); PG8_BAR;
;             PG8_LDA(At, 1, 1); PG8_STAGE(PG8_SA(1, 0), a3, voffA);
;             PG8_BAR; PG8_WAIT_L(0); PG8_MMA(1, 0, At, B0); PG8_BAR; PG8_SCHED;
;             PG8_STAGE(PG8_SB(1, 1), b3 + hstep, voffB);
;             PG8_WAIT_V(6); PG8_BAR; PG8_MMA(1, 1, At, B1); PG8_BAR;
	s_waitcnt lgkmcnt(0)
	v_mfma_f32_16x16x32_bf16 v[124:127], v[140:143], v[166:169], v[124:127]
	v_mfma_f32_16x16x32_bf16 v[120:123], v[158:161], v[166:169], v[120:123]
	v_mfma_f32_16x16x32_bf16 v[108:111], v[140:143], v[174:177], v[108:111]
	v_mfma_f32_16x16x32_bf16 v[104:107], v[158:161], v[174:177], v[104:107]
	v_mfma_f32_16x16x32_bf16 v[92:95], v[140:143], v[182:185], v[92:95]
	v_mfma_f32_16x16x32_bf16 v[88:91], v[158:161], v[182:185], v[88:91]
	v_mfma_f32_16x16x32_bf16 v[76:79], v[140:143], v[190:193], v[76:79]
	v_mfma_f32_16x16x32_bf16 v[72:75], v[158:161], v[190:193], v[72:75]
	v_mfma_f32_16x16x32_bf16 v[124:127], v[154:157], v[170:173], v[124:127]
	v_mfma_f32_16x16x32_bf16 v[120:123], v[162:165], v[170:173], v[120:123]
	v_mfma_f32_16x16x32_bf16 v[108:111], v[154:157], v[178:181], v[108:111]
	v_mfma_f32_16x16x32_bf16 v[104:107], v[162:165], v[178:181], v[104:107]
	v_mfma_f32_16x16x32_bf16 v[92:95], v[154:157], v[186:189], v[92:95]
	v_mfma_f32_16x16x32_bf16 v[88:91], v[162:165], v[186:189], v[88:91]
	v_mfma_f32_16x16x32_bf16 v[76:79], v[154:157], v[194:197], v[76:79]
	v_mfma_f32_16x16x32_bf16 v[72:75], v[162:165], v[194:197], v[72:75]
	s_barrier
	s_setprio 0
	s_add_i32 s24, 0, 0x1c000
	s_add_i32 s25, s62, s31
	v_add_u32_e32 v214, s24, v148
	s_add_u32 s0, s4, 0x80
	s_addc_u32 s1, s5, 0
	s_mov_b32 m0, s25
	ds_read_b128 v[202:205], v214
	ds_read_b128 v[206:209], v214 offset:1024
	ds_read_b128 v[210:213], v214 offset:2048
	ds_read_b128 v[214:217], v214 offset:3072
	global_load_lds_dwordx4 v130, s[0:1]
	s_add_i32 m0, s25, 0x2000
	s_nop 0
	global_load_lds_dwordx4 v134, s[0:1]
	s_waitcnt vmcnt(8)
	s_setprio 1
	s_barrier
	s_waitcnt lgkmcnt(0)
	v_mfma_f32_16x16x32_bf16 v[116:119], v[202:205], v[166:169], v[116:119]
	v_mfma_f32_16x16x32_bf16 v[112:115], v[210:213], v[166:169], v[112:115]
	v_mfma_f32_16x16x32_bf16 v[100:103], v[202:205], v[174:177], v[100:103]
	v_mfma_f32_16x16x32_bf16 v[96:99], v[210:213], v[174:177], v[96:99]
	v_mfma_f32_16x16x32_bf16 v[84:87], v[202:205], v[182:185], v[84:87]
	v_mfma_f32_16x16x32_bf16 v[80:83], v[210:213], v[182:185], v[80:83]
	v_mfma_f32_16x16x32_bf16 v[68:71], v[202:205], v[190:193], v[68:71]
	v_mfma_f32_16x16x32_bf16 v[64:67], v[210:213], v[190:193], v[64:67]
	v_mfma_f32_16x16x32_bf16 v[116:119], v[206:209], v[170:173], v[116:119]
	v_mfma_f32_16x16x32_bf16 v[112:115], v[214:217], v[170:173], v[112:115]
	v_mfma_f32_16x16x32_bf16 v[100:103], v[206:209], v[178:181], v[100:103]
	v_mfma_f32_16x16x32_bf16 v[96:99], v[214:217], v[178:181], v[96:99]
	v_mfma_f32_16x16x32_bf16 v[84:87], v[206:209], v[186:189], v[84:87]
	v_mfma_f32_16x16x32_bf16 v[80:83], v[214:217], v[186:189], v[80:83]
	v_mfma_f32_16x16x32_bf16 v[68:71], v[206:209], v[194:197], v[68:71]
	v_mfma_f32_16x16x32_bf16 v[64:67], v[214:217], v[194:197], v[64:67]
	s_mov_b32 m0, s44
	s_mov_b64 s[0:1], 0x80
	v_lshl_add_u64 v[144:145], v[218:219], 0, s[0:1]
	s_barrier
	s_setprio 0
	ds_read_b128 v[166:169], v150 offset:49152
	ds_read_b128 v[170:173], v150 offset:50176
	ds_read_b128 v[174:177], v150 offset:51200
	ds_read_b128 v[178:181], v150 offset:52224
	ds_read_b128 v[182:185], v150 offset:53248
	ds_read_b128 v[186:189], v150 offset:54272
	ds_read_b128 v[190:193], v150 offset:55296
	ds_read_b128 v[194:197], v150 offset:56320
	global_load_lds_dwordx4 v[144:145], off
	v_lshl_add_u64 v[144:145], v[220:221], 0, s[0:1]
	s_mov_b32 m0, s45
	s_nop 0
	global_load_lds_dwordx4 v[144:145], off
	s_setprio 1
	s_barrier
	s_waitcnt lgkmcnt(0)
	v_mfma_f32_16x16x32_bf16 v[60:63], v[140:143], v[166:169], v[60:63]
	v_mfma_f32_16x16x32_bf16 v[56:59], v[158:161], v[166:169], v[56:59]
	v_mfma_f32_16x16x32_bf16 v[44:47], v[140:143], v[174:177], v[44:47]
	v_mfma_f32_16x16x32_bf16 v[40:43], v[158:161], v[174:177], v[40:43]
	v_mfma_f32_16x16x32_bf16 v[28:31], v[140:143], v[182:185], v[28:31]
	v_mfma_f32_16x16x32_bf16 v[24:27], v[158:161], v[182:185], v[24:27]
	v_mfma_f32_16x16x32_bf16 v[12:15], v[140:143], v[190:193], v[12:15]
	v_mfma_f32_16x16x32_bf16 v[8:11], v[158:161], v[190:193], v[8:11]
	v_mfma_f32_16x16x32_bf16 v[60:63], v[154:157], v[170:173], v[60:63]
	v_mfma_f32_16x16x32_bf16 v[56:59], v[162:165], v[170:173], v[56:59]
	v_mfma_f32_16x16x32_bf16 v[44:47], v[154:157], v[178:181], v[44:47]
	v_mfma_f32_16x16x32_bf16 v[40:43], v[162:165], v[178:181], v[40:43]
	v_mfma_f32_16x16x32_bf16 v[28:31], v[154:157], v[186:189], v[28:31]
	v_mfma_f32_16x16x32_bf16 v[24:27], v[162:165], v[186:189], v[24:27]
	v_mfma_f32_16x16x32_bf16 v[12:15], v[154:157], v[194:197], v[12:15]
	v_mfma_f32_16x16x32_bf16 v[8:11], v[162:165], v[194:197], v[8:11]
	s_barrier
	s_setprio 0
	s_add_u32 s4, s4, 0x40080
	s_addc_u32 s5, s5, 0
	s_add_i32 s24, s24, s31
	s_mov_b32 m0, s24
	s_nop 0
	global_load_lds_dwordx4 v130, s[4:5]
	s_add_i32 m0, s24, 0x2000
	s_nop 0
	global_load_lds_dwordx4 v134, s[4:5]
	s_waitcnt vmcnt(8)
	s_setprio 1
	s_barrier
	v_mfma_f32_16x16x32_bf16 v[52:55], v[202:205], v[166:169], v[52:55]
	v_mfma_f32_16x16x32_bf16 v[48:51], v[210:213], v[166:169], v[48:51]
	v_mfma_f32_16x16x32_bf16 v[36:39], v[202:205], v[174:177], v[36:39]
	v_mfma_f32_16x16x32_bf16 v[32:35], v[210:213], v[174:177], v[32:35]
	v_mfma_f32_16x16x32_bf16 v[20:23], v[202:205], v[182:185], v[20:23]
	v_mfma_f32_16x16x32_bf16 v[16:19], v[210:213], v[182:185], v[16:19]
	v_mfma_f32_16x16x32_bf16 v[4:7], v[202:205], v[190:193], v[4:7]
	v_mfma_f32_16x16x32_bf16 v[0:3], v[210:213], v[190:193], v[0:3]
	v_mfma_f32_16x16x32_bf16 v[52:55], v[206:209], v[170:173], v[52:55]
	v_mfma_f32_16x16x32_bf16 v[48:51], v[214:217], v[170:173], v[48:51]
	v_mfma_f32_16x16x32_bf16 v[36:39], v[206:209], v[178:181], v[36:39]
	v_mfma_f32_16x16x32_bf16 v[32:35], v[214:217], v[178:181], v[32:35]
	v_mfma_f32_16x16x32_bf16 v[20:23], v[206:209], v[186:189], v[20:23]
	v_mfma_f32_16x16x32_bf16 v[16:19], v[214:217], v[186:189], v[16:19]
	v_mfma_f32_16x16x32_bf16 v[4:7], v[206:209], v[194:197], v[4:7]
	v_mfma_f32_16x16x32_bf16 v[0:3], v[214:217], v[194:197], v[0:3]
	s_add_i32 s61, s61, 2
	s_add_u32 s2, s2, 0x100
	s_addc_u32 s3, s3, 0
	s_add_u32 s59, s59, 0x100
	s_addc_u32 s60, s60, 0
	s_cmp_gt_u32 s61, 13
	s_barrier
; template <class Epi, class Sched>
; __device__ __forceinline__ void gemm_phase(LAS unsigned char* lds, const Gemm g, const Sched& S, const Epi& E) {
;     ...
;         const bool has_next = S.next(ui + 1, nxt);
;     __device__ __forceinline__ void operator()(const AccT& acc, const Unit& u, int wr, int wc, int fr, int fq) const {
;     ...
;         const int rbase = wr * 64 + fr;
;         const int tb = u.pn * 256 + wc * 32 + 8 * fq;
;         const int o0 = wc * 32 + 8 * fq;
;         const int j = fr & 3; const float sgn = ((fr >> 2) & 1) ? 1.0f : -1.0f;
; #pragma unroll
;         for (int ai = 0; ai < 2; ++ai) {
;             const int hh = 2 * ai + wr;
;             const float l2f = lgd[hh] * 1.4426950408889634f, l2b = lgd[4 + hh] * 1.4426950408889634f;
;             const float zf0 = exp2f((float)(127 - o0) * l2f), zfs = exp2f(-l2f), zb0 = exp2f((float)o0 * l2b), zbs = exp2f(l2b);
; #pragma unroll
;             for (int m = 0; m < 4; ++m) {
;                 const int r = rbase + ai * 128 + m * 16;
;                 const int d = 4 * (2 * m + (fr >> 3)) + j;
; #pragma unroll
;                 for (int bj = 0; bj < 2; ++bj) {
;                     const int t0 = tb + bj * 128;
;                     float v[8];
; #pragma unroll
;                     for (int jj = 0; jj < 4; ++jj) { v[jj] = acc[ai][bj][m][0][jj]; v[4 + jj] = acc[ai][bj][m][1][jj]; }
;                     if constexpr (ROPE) {
;                         const int t = t0 & 2047;
; #pragma unroll
;                         for (int hf = 0; hf < 2; ++hf) {
;                             f32x4 cs, sn;
;                             if (m < 2) { const float c1 = ropeA[(t >> 6) * 16 + d], s1 = ropeA[1024 + (t >> 6) * 16 + d]; cs = (f32x4){c1, c1, c1, c1}; sn = (f32x4){s1, s1, s1, s1}; }
;                             else { const float* cb = ropeA + 2048 + (d - 16) * 64 + (t & 63) + 4 * hf; cs = *(const f32x4*)(cb); sn = *(const f32x4*)(cb + 1024); }
; #pragma unroll
;                             for (int jj = 0; jj < 4; ++jj) { const float pr = __shfl_xor(v[4 * hf + jj], 4); v[4 * hf + jj] = v[4 * hf + jj] * cs[jj] + sgn * pr * sn[jj]; }
;                             __builtin_amdgcn_sched_barrier(0);
;                         }
;                     }
;                     float zf[8], zb[8]; zf[0] = zf0; zb[0] = zb0;
; #pragma unroll
	s_setprio 0
	s_cbranch_scc0 .LBB0_693
	v_mov_b32_e32 v141, v147
	v_mov_b32_e32 v140, v146
	global_load_dword v156, v131, s[6:7]
	global_load_dword v157, v131, s[6:7] offset:16
	s_lshl_b32 s2, s56, 8
	s_or_b32 s2, s2, s43
	v_add_u32_e32 v140, s42, v140
	v_lshlrev_b32_e32 v141, 3, v141
	v_add_u32_e32 v142, s2, v141
	v_add_u32_e32 v143, s43, v141
	v_ashrrev_i32_e32 v141, 31, v140
	v_sub_u32_e32 v144, 0x7f, v143
	v_lshlrev_b64 v[140:141], 14, v[140:141]
	v_cvt_f32_i32_e32 v154, v143
	v_ashrrev_i32_e32 v143, 31, v142
	v_cvt_f32_i32_e32 v155, v144
	v_lshl_add_u64 v[140:141], s[70:71], 0, v[140:141]
	s_mov_b32 s3, 0x400000
	v_lshl_add_u64 v[140:141], v[142:143], 1, v[140:141]
	v_add_co_u32_e32 v144, vcc, s3, v140
	s_mov_b64 s[4:5], 0x400000
	s_nop 0
	v_addc_co_u32_e32 v145, vcc, 0, v141, vcc
	v_lshl_add_u64 v[142:143], v[140:141], 0, s[4:5]
	s_waitcnt vmcnt(0)
	v_mul_f32_e32 v158, 0x3fb8aa3b, v156
	v_mul_f32_e32 v159, 0x3fb8aa3b, v157
	v_mul_f32_e32 v160, v158, v155
	v_cmp_lt_f32_e32 vcc, s51, v158
	v_mul_f32_e32 v162, v159, v154
	v_cmp_gt_f32_e64 s[2:3], s49, v159
	v_cndmask_b32_e32 v161, 0, v153, vcc
	v_cmp_gt_f32_e64 s[4:5], s49, v160
	v_cndmask_b32_e64 v163, 0, v153, s[2:3]
	s_and_b64 s[24:25], vcc, exec
	v_cmp_gt_f32_e32 vcc, s49, v162
	v_fmac_f32_e32 v163, 0x3fb8aa3b, v157
	v_cndmask_b32_e64 v157, 0, v153, s[4:5]
	v_cndmask_b32_e32 v162, 0, v153, vcc
	v_fmac_f32_e32 v161, 0xbfb8aa3b, v156
	v_fmac_f32_e32 v157, v158, v155
	v_fmac_f32_e32 v162, v159, v154
	v_exp_f32_e32 v161, v161
	v_exp_f32_e32 v163, v163
	v_exp_f32_e32 v157, v157
	v_exp_f32_e32 v158, v162
	v_cndmask_b32_e64 v160, 0, v152, s[4:5]
	s_cselect_b32 s4, 0xffffffc0, 0
	s_and_b64 s[2:3], s[2:3], exec
	v_cndmask_b32_e32 v156, 0, v152, vcc
	s_cselect_b32 s2, 0xffffffc0, 0
	v_ldexp_f32 v161, v161, s4
	v_ldexp_f32 v162, v163, s2
	v_ldexp_f32 v163, v157, v160
	v_ldexp_f32 v156, v158, v156
	v_mul_f32_e32 v164, v161, v163
	v_mul_f32_e32 v157, v162, v156
	v_mul_f32_e32 v158, v124, v163
	v_mul_f32_e32 v165, v124, v156
	v_mul_f32_e32 v166, v161, v164
	v_mul_f32_e32 v124, v162, v157
	v_mul_f32_e32 v159, v125, v164
	v_mul_f32_e32 v167, v125, v157
	v_mul_f32_e32 v168, v161, v166
	v_mul_f32_e32 v125, v162, v124
	v_cvt_pk_bf16_f32 v158, v158, v159
	v_mul_f32_e32 v159, v126, v166
	v_mul_f32_e32 v169, v126, v124
	v_mul_f32_e32 v170, v161, v168
	v_mul_f32_e32 v126, v162, v125
	v_mul_f32_e32 v171, v161, v170
	v_mul_f32_e32 v172, v162, v126
	v_mul_f32_e32 v160, v127, v168
	v_mul_f32_e32 v174, v161, v171
	v_mul_f32_e32 v175, v162, v172
	v_cvt_pk_bf16_f32 v159, v159, v160
	v_mul_f32_e32 v160, v120, v170
	v_mul_f32_e32 v173, v120, v126
	v_mul_f32_e32 v120, v121, v171
	v_mul_f32_e32 v177, v161, v174
	v_mul_f32_e32 v162, v162, v175
	v_mul_f32_e32 v176, v121, v172
	v_cvt_pk_bf16_f32 v160, v160, v120
	v_mul_f32_e32 v120, v122, v174
	v_mul_f32_e32 v121, v123, v177
	v_mul_f32_e32 v123, v123, v162
	v_cvt_pk_bf16_f32 v161, v120, v121
	v_mul_f32_e32 v127, v127, v125
	v_mul_f32_e32 v178, v122, v175
	v_cvt_pk_bf16_f32 v120, v165, v167
	v_cvt_pk_bf16_f32 v121, v169, v127
	v_cvt_pk_bf16_f32 v122, v173, v176
	v_cvt_pk_bf16_f32 v123, v178, v123
	global_store_dwordx4 v[140:141], v[158:161], off
	global_store_dwordx4 v[144:145], v[120:123], off
	s_nop 1
	v_mul_f32_e32 v120, v116, v163
	v_mul_f32_e32 v121, v117, v164
	v_cvt_pk_bf16_f32 v120, v120, v121
	v_mul_f32_e32 v121, v118, v166
	v_mul_f32_e32 v122, v119, v168
	v_cvt_pk_bf16_f32 v121, v121, v122
	v_mul_f32_e32 v122, v112, v170
	v_mul_f32_e32 v123, v113, v171
	v_cvt_pk_bf16_f32 v122, v122, v123
	v_mul_f32_e32 v123, v114, v174
	v_mul_f32_e32 v116, v116, v156
	v_mul_f32_e32 v117, v117, v157
	v_mul_f32_e32 v127, v115, v177
	v_cvt_pk_bf16_f32 v123, v123, v127
	v_cvt_pk_bf16_f32 v116, v116, v117
	v_mul_f32_e32 v117, v118, v124
	v_mul_f32_e32 v118, v119, v125
	v_mul_f32_e32 v112, v112, v126
	v_mul_f32_e32 v113, v113, v172
	v_cvt_pk_bf16_f32 v117, v117, v118
	v_cvt_pk_bf16_f32 v118, v112, v113
	v_mul_f32_e32 v112, v114, v175
	v_mul_f32_e32 v113, v115, v162
	v_cvt_pk_bf16_f32 v119, v112, v113
	global_store_dwordx4 v[140:141], v[120:123], off offset:256
	global_store_dwordx4 v[142:143], v[116:119], off offset:256
	v_mul_f32_e32 v112, v108, v163
	v_mul_f32_e32 v113, v109, v164
	v_cvt_pk_bf16_f32 v112, v112, v113
	v_mul_f32_e32 v113, v110, v166
	v_mul_f32_e32 v114, v111, v168
	v_cvt_pk_bf16_f32 v113, v113, v114
	v_mul_f32_e32 v114, v104, v170
	v_mul_f32_e32 v115, v105, v171
	v_cvt_pk_bf16_f32 v114, v114, v115
	v_mul_f32_e32 v115, v106, v174
	v_mul_f32_e32 v108, v108, v156
	v_mul_f32_e32 v109, v109, v157
	v_mul_f32_e32 v116, v107, v177
	v_cvt_pk_bf16_f32 v115, v115, v116
	v_cvt_pk_bf16_f32 v108, v108, v109
	v_mul_f32_e32 v109, v110, v124
	v_mul_f32_e32 v110, v111, v125
	v_mul_f32_e32 v104, v104, v126
	s_mov_b64 s[2:3], 0x40000
	v_cvt_pk_bf16_f32 v109, v109, v110
	v_mul_f32_e32 v105, v105, v172
	v_cvt_pk_bf16_f32 v110, v104, v105
	v_mul_f32_e32 v104, v106, v175
	v_lshl_add_u64 v[116:117], v[140:141], 0, s[2:3]
	s_mov_b32 s2, 0x40000
	v_mul_f32_e32 v105, v107, v162
	v_cvt_pk_bf16_f32 v111, v104, v105
	v_add_co_u32_e32 v104, vcc, s2, v140
	s_mov_b64 s[2:3], 0x440000
	s_nop 0
	v_addc_co_u32_e32 v105, vcc, 0, v141, vcc
	global_store_dwordx4 v[104:105], v[112:115], off
	s_nop 1
	v_lshl_add_u64 v[112:113], v[140:141], 0, s[2:3]
	s_mov_b32 s2, 0x440000
	v_add_co_u32_e32 v104, vcc, s2, v140
	s_nop 1
	v_addc_co_u32_e32 v105, vcc, 0, v141, vcc
	global_store_dwordx4 v[104:105], v[108:111], off
	v_mul_f32_e32 v104, v100, v163
	v_mul_f32_e32 v105, v101, v164
	v_cvt_pk_bf16_f32 v104, v104, v105
	v_mul_f32_e32 v105, v102, v166
	v_mul_f32_e32 v106, v103, v168
	v_cvt_pk_bf16_f32 v105, v105, v106
;     __device__ __forceinline__ void operator()(const AccT& acc, const Unit& u, int wr, int wc, int fr, int fq) const {
;     ...
;             for (int m = 0; m < 4; ++m) {
;                 const int r = rbase + ai * 128 + m * 16;
;                 const int d = 4 * (2 * m + (fr >> 3)) + j;
; #pragma unroll
;                 for (int bj = 0; bj < 2; ++bj) {
;                     const int t0 = tb + bj * 128;
;                     float v[8];
; #pragma unroll
;                     for (int jj = 0; jj < 4; ++jj) { v[jj] = acc[ai][bj][m][0][jj]; v[4 + jj] = acc[ai][bj][m][1][jj]; }
;                     if constexpr (ROPE) {
;                         const int t = t0 & 2047;
; #pragma unroll
;                         for (int hf = 0; hf < 2; ++hf) {
;                             f32x4 cs, sn;
;                             if (m < 2) { const float c1 = ropeA[(t >> 6) * 16 + d], s1 = ropeA[1024 + (t >> 6) * 16 + d]; cs = (f32x4){c1, c1, c1, c1}; sn = (f32x4){s1, s1, s1, s1}; }
;                             else { const float* cb = ropeA + 2048 + (d - 16) * 64 + (t & 63) + 4 * hf; cs = *(const f32x4*)(cb); sn = *(const f32x4*)(cb + 1024); }
; #pragma unroll
;                             for (int jj = 0; jj < 4; ++jj) { const float pr = __shfl_xor(v[4 * hf + jj], 4); v[4 * hf + jj] = v[4 * hf + jj] * cs[jj] + sgn * pr * sn[jj]; }
;                             __builtin_amdgcn_sched_barrier(0);
;                         }
;                     }
;                     float zf[8], zb[8]; zf[0] = zf0; zb[0] = zb0;
; #pragma unroll
;                     for (int jj = 1; jj < 8; ++jj) { zf[jj] = zf[jj - 1] * zfs; zb[jj] = zb[jj - 1] * zbs; }
;                     u32x4 wf, wb;
;                     wf.x = cvt_pk_bf16(v[0] * zf[0], v[1] * zf[1]); wf.y = cvt_pk_bf16(v[2] * zf[2], v[3] * zf[3]); wf.z = cvt_pk_bf16(v[4] * zf[4], v[5] * zf[5]); wf.w = cvt_pk_bf16(v[6] * zf[6], v[7] * zf[7]);
;                     wb.x = cvt_pk_bf16(v[0] * zb[0], v[1] * zb[1]); wb.y = cvt_pk_bf16(v[2] * zb[2], v[3] * zb[3]); wb.z = cvt_pk_bf16(v[4] * zb[4], v[5] * zb[5]); wb.w = cvt_pk_bf16(v[6] * zb[6], v[7] * zb[7]);
;                     *(u32x4*)(KTZ + (size_t)r * NT + t0) = wf;
;                     *(u32x4*)(KTZ + (size_t)(256 + r) * NT + t0) = wb;
	v_mul_f32_e32 v106, v96, v170
	v_mul_f32_e32 v107, v97, v171
	v_cvt_pk_bf16_f32 v106, v106, v107
	v_mul_f32_e32 v107, v98, v174
	v_mul_f32_e32 v100, v100, v156
	v_mul_f32_e32 v101, v101, v157
	v_mul_f32_e32 v108, v99, v177
	v_cvt_pk_bf16_f32 v107, v107, v108
	v_cvt_pk_bf16_f32 v100, v100, v101
	v_mul_f32_e32 v101, v102, v124
	v_mul_f32_e32 v102, v103, v125
	v_mul_f32_e32 v96, v96, v126
	v_mul_f32_e32 v97, v97, v172
	v_cvt_pk_bf16_f32 v101, v101, v102
	v_cvt_pk_bf16_f32 v102, v96, v97
	v_mul_f32_e32 v96, v98, v175
	v_mul_f32_e32 v97, v99, v162
	v_cvt_pk_bf16_f32 v103, v96, v97
	global_store_dwordx4 v[116:117], v[104:107], off offset:256
	global_store_dwordx4 v[112:113], v[100:103], off offset:256
	v_mul_f32_e32 v96, v92, v163
	v_mul_f32_e32 v97, v93, v164
	v_cvt_pk_bf16_f32 v96, v96, v97
	v_mul_f32_e32 v97, v94, v166
	v_mul_f32_e32 v98, v95, v168
	v_cvt_pk_bf16_f32 v97, v97, v98
	v_mul_f32_e32 v98, v88, v170
	v_mul_f32_e32 v99, v89, v171
	v_cvt_pk_bf16_f32 v98, v98, v99
	v_mul_f32_e32 v99, v90, v174
	v_mul_f32_e32 v92, v92, v156
	v_mul_f32_e32 v93, v93, v157
	v_mul_f32_e32 v100, v91, v177
	v_cvt_pk_bf16_f32 v99, v99, v100
	v_cvt_pk_bf16_f32 v92, v92, v93
	v_mul_f32_e32 v93, v94, v124
	v_mul_f32_e32 v94, v95, v125
	v_mul_f32_e32 v88, v88, v126
	s_mov_b64 s[2:3], 0x80000
	v_cvt_pk_bf16_f32 v93, v93, v94
	v_mul_f32_e32 v89, v89, v172
	v_cvt_pk_bf16_f32 v94, v88, v89
	v_mul_f32_e32 v88, v90, v175
	v_lshl_add_u64 v[100:101], v[140:141], 0, s[2:3]
	s_mov_b32 s2, 0x80000
	v_mul_f32_e32 v89, v91, v162
	v_cvt_pk_bf16_f32 v95, v88, v89
	v_add_co_u32_e32 v88, vcc, s2, v140
	s_mov_b64 s[2:3], 0x480000
	s_nop 0
	v_addc_co_u32_e32 v89, vcc, 0, v141, vcc
	global_store_dwordx4 v[88:89], v[96:99], off
	s_nop 1
	v_lshl_add_u64 v[96:97], v[140:141], 0, s[2:3]
	s_mov_b32 s2, 0x480000
	v_add_co_u32_e32 v88, vcc, s2, v140
	s_nop 1
	v_addc_co_u32_e32 v89, vcc, 0, v141, vcc
	global_store_dwordx4 v[88:89], v[92:95], off
	v_mul_f32_e32 v88, v84, v163
	v_mul_f32_e32 v89, v85, v164
	v_cvt_pk_bf16_f32 v88, v88, v89
	v_mul_f32_e32 v89, v86, v166
	v_mul_f32_e32 v90, v87, v168
	v_cvt_pk_bf16_f32 v89, v89, v90
	v_mul_f32_e32 v90, v80, v170
	v_mul_f32_e32 v91, v81, v171
	v_cvt_pk_bf16_f32 v90, v90, v91
	v_mul_f32_e32 v91, v82, v174
	v_mul_f32_e32 v84, v84, v156
	v_mul_f32_e32 v85, v85, v157
	v_mul_f32_e32 v92, v83, v177
	v_cvt_pk_bf16_f32 v91, v91, v92
	v_cvt_pk_bf16_f32 v84, v84, v85
	v_mul_f32_e32 v85, v86, v124
	v_mul_f32_e32 v86, v87, v125
	v_mul_f32_e32 v80, v80, v126
	v_mul_f32_e32 v81, v81, v172
	v_cvt_pk_bf16_f32 v85, v85, v86
	v_cvt_pk_bf16_f32 v86, v80, v81
	v_mul_f32_e32 v80, v82, v175
	v_mul_f32_e32 v81, v83, v162
	v_cvt_pk_bf16_f32 v87, v80, v81
	global_store_dwordx4 v[100:101], v[88:91], off offset:256
	global_store_dwordx4 v[96:97], v[84:87], off offset:256
	v_mul_f32_e32 v80, v76, v163
	v_mul_f32_e32 v81, v77, v164
	v_cvt_pk_bf16_f32 v80, v80, v81
	v_mul_f32_e32 v81, v78, v166
	v_mul_f32_e32 v82, v79, v168
	v_cvt_pk_bf16_f32 v81, v81, v82
	v_mul_f32_e32 v82, v72, v170
	v_mul_f32_e32 v83, v73, v171
	v_cvt_pk_bf16_f32 v82, v82, v83
	v_mul_f32_e32 v83, v74, v174
	v_mul_f32_e32 v76, v76, v156
	v_mul_f32_e32 v77, v77, v157
	v_mul_f32_e32 v84, v75, v177
	v_cvt_pk_bf16_f32 v83, v83, v84
	v_cvt_pk_bf16_f32 v76, v76, v77
	v_mul_f32_e32 v77, v78, v124
	v_mul_f32_e32 v78, v79, v125
	v_mul_f32_e32 v72, v72, v126
	s_mov_b64 s[2:3], 0xc0000
	v_cvt_pk_bf16_f32 v77, v77, v78
	v_mul_f32_e32 v73, v73, v172
	v_cvt_pk_bf16_f32 v78, v72, v73
	v_mul_f32_e32 v72, v74, v175
	v_lshl_add_u64 v[84:85], v[140:141], 0, s[2:3]
	s_mov_b32 s2, 0xc0000
	v_mul_f32_e32 v73, v75, v162
	v_cvt_pk_bf16_f32 v79, v72, v73
	v_add_co_u32_e32 v72, vcc, s2, v140
	s_mov_b64 s[2:3], 0x4c0000
	s_nop 0
	v_addc_co_u32_e32 v73, vcc, 0, v141, vcc
	global_store_dwordx4 v[72:73], v[80:83], off
	s_nop 1
	v_lshl_add_u64 v[80:81], v[140:141], 0, s[2:3]
	s_mov_b32 s2, 0x4c0000
	v_add_co_u32_e32 v72, vcc, s2, v140
	s_nop 1
	v_addc_co_u32_e32 v73, vcc, 0, v141, vcc
	global_store_dwordx4 v[72:73], v[76:79], off
	v_mul_f32_e32 v72, v68, v163
	v_mul_f32_e32 v73, v69, v164
	v_cvt_pk_bf16_f32 v72, v72, v73
	v_mul_f32_e32 v73, v70, v166
	v_mul_f32_e32 v74, v71, v168
	v_cvt_pk_bf16_f32 v73, v73, v74
	v_mul_f32_e32 v74, v64, v170
	v_mul_f32_e32 v75, v65, v171
	v_cvt_pk_bf16_f32 v74, v74, v75
	v_mul_f32_e32 v75, v66, v174
	v_mul_f32_e32 v68, v68, v156
	v_mul_f32_e32 v69, v69, v157
	v_mul_f32_e32 v76, v67, v177
	v_cvt_pk_bf16_f32 v75, v75, v76
	v_cvt_pk_bf16_f32 v68, v68, v69
	v_mul_f32_e32 v69, v70, v124
	v_mul_f32_e32 v70, v71, v125
	v_mul_f32_e32 v64, v64, v126
	v_mul_f32_e32 v65, v65, v172
	v_cvt_pk_bf16_f32 v69, v69, v70
	v_cvt_pk_bf16_f32 v70, v64, v65
	v_mul_f32_e32 v64, v66, v175
	v_mul_f32_e32 v65, v67, v162
	v_cvt_pk_bf16_f32 v71, v64, v65
	global_store_dwordx4 v[84:85], v[72:75], off offset:256
	global_store_dwordx4 v[80:81], v[68:71], off offset:256
	global_load_dword v70, v131, s[6:7] offset:8
	s_nop 0
	global_load_dword v71, v131, s[6:7] offset:24
	s_mov_b32 s17, 0x200000
	v_add_co_u32_e32 v76, vcc, s17, v140
	s_mov_b32 s19, 0x600000
	s_nop 0
	v_addc_co_u32_e32 v77, vcc, 0, v141, vcc
	v_add_co_u32_e32 v68, vcc, s19, v140
	s_mov_b64 s[2:3], 0x200000
	s_nop 0
	v_addc_co_u32_e32 v69, vcc, 0, v141, vcc
	s_mov_b64 s[4:5], 0x600000
	v_lshl_add_u64 v[64:65], v[140:141], 0, s[2:3]
	v_lshl_add_u64 v[66:67], v[140:141], 0, s[4:5]
	s_waitcnt vmcnt(0)
;     __device__ __forceinline__ void operator()(const AccT& acc, const Unit& u, int wr, int wc, int fr, int fq) const {
;     ...
;         for (int ai = 0; ai < 2; ++ai) {
;             const int hh = 2 * ai + wr;
;             const float l2f = lgd[hh] * 1.4426950408889634f, l2b = lgd[4 + hh] * 1.4426950408889634f;
;             const float zf0 = exp2f((float)(127 - o0) * l2f), zfs = exp2f(-l2f), zb0 = exp2f((float)o0 * l2b), zbs = exp2f(l2b);
; #pragma unroll
;             for (int m = 0; m < 4; ++m) {
;                 const int r = rbase + ai * 128 + m * 16;
;                 const int d = 4 * (2 * m + (fr >> 3)) + j;
; #pragma unroll
;                 for (int bj = 0; bj < 2; ++bj) {
;                     const int t0 = tb + bj * 128;
;                     float v[8];
; #pragma unroll
;                     for (int jj = 0; jj < 4; ++jj) { v[jj] = acc[ai][bj][m][0][jj]; v[4 + jj] = acc[ai][bj][m][1][jj]; }
;                     if constexpr (ROPE) {
;                         const int t = t0 & 2047;
; #pragma unroll
;                         for (int hf = 0; hf < 2; ++hf) {
;                             f32x4 cs, sn;
;                             if (m < 2) { const float c1 = ropeA[(t >> 6) * 16 + d], s1 = ropeA[1024 + (t >> 6) * 16 + d]; cs = (f32x4){c1, c1, c1, c1}; sn = (f32x4){s1, s1, s1, s1}; }
;                             else { const float* cb = ropeA + 2048 + (d - 16) * 64 + (t & 63) + 4 * hf; cs = *(const f32x4*)(cb); sn = *(const f32x4*)(cb + 1024); }
; #pragma unroll
;                             for (int jj = 0; jj < 4; ++jj) { const float pr = __shfl_xor(v[4 * hf + jj], 4); v[4 * hf + jj] = v[4 * hf + jj] * cs[jj] + sgn * pr * sn[jj]; }
;                             __builtin_amdgcn_sched_barrier(0);
;                         }
;                     }
;                     float zf[8], zb[8]; zf[0] = zf0; zb[0] = zb0;
; #pragma unroll
;                     for (int jj = 1; jj < 8; ++jj) { zf[jj] = zf[jj - 1] * zfs; zb[jj] = zb[jj - 1] * zbs; }
;                     u32x4 wf, wb;
;                     wf.x = cvt_pk_bf16(v[0] * zf[0], v[1] * zf[1]); wf.y = cvt_pk_bf16(v[2] * zf[2], v[3] * zf[3]); wf.z = cvt_pk_bf16(v[4] * zf[4], v[5] * zf[5]); wf.w = cvt_pk_bf16(v[6] * zf[6], v[7] * zf[7]);
	v_mul_f32_e32 v72, 0x3fb8aa3b, v70
	v_mul_f32_e32 v73, 0x3fb8aa3b, v71
	v_mul_f32_e32 v74, v72, v155
	v_cmp_lt_f32_e32 vcc, s51, v72
	v_mul_f32_e32 v78, v73, v154
	v_cmp_gt_f32_e64 s[2:3], s49, v73
	v_cndmask_b32_e32 v75, 0, v153, vcc
	v_cmp_gt_f32_e64 s[4:5], s49, v74
	v_cndmask_b32_e64 v79, 0, v153, s[2:3]
	s_and_b64 s[24:25], vcc, exec
	v_cmp_gt_f32_e32 vcc, s49, v78
	v_fmac_f32_e32 v79, 0x3fb8aa3b, v71
	v_cndmask_b32_e64 v71, 0, v153, s[4:5]
	v_cndmask_b32_e32 v78, 0, v153, vcc
	v_fmac_f32_e32 v75, 0xbfb8aa3b, v70
	v_fmac_f32_e32 v71, v72, v155
	v_fmac_f32_e32 v78, v73, v154
	v_exp_f32_e32 v75, v75
	v_exp_f32_e32 v79, v79
	v_exp_f32_e32 v71, v71
	v_exp_f32_e32 v72, v78
	v_cndmask_b32_e64 v74, 0, v152, s[4:5]
	s_cselect_b32 s4, 0xffffffc0, 0
	s_and_b64 s[2:3], s[2:3], exec
	v_cndmask_b32_e32 v70, 0, v152, vcc
	s_cselect_b32 s2, 0xffffffc0, 0
	v_ldexp_f32 v75, v75, s4
	v_ldexp_f32 v78, v79, s2
	v_ldexp_f32 v79, v71, v74
	v_ldexp_f32 v70, v72, v70
	v_mul_f32_e32 v80, v75, v79
	v_mul_f32_e32 v71, v78, v70
	v_mul_f32_e32 v72, v60, v79
	v_mul_f32_e32 v81, v60, v70
	v_mul_f32_e32 v82, v75, v80
	v_mul_f32_e32 v60, v78, v71
	v_mul_f32_e32 v83, v75, v82
	v_mul_f32_e32 v84, v78, v60
	v_mul_f32_e32 v85, v75, v83
	v_mul_f32_e32 v86, v78, v84
	v_mul_f32_e32 v73, v61, v80
	v_mul_f32_e32 v87, v75, v85
	v_mul_f32_e32 v88, v78, v86
	v_cvt_pk_bf16_f32 v72, v72, v73
	v_mul_f32_e32 v73, v62, v82
	v_mul_f32_e32 v74, v63, v83
	v_mul_f32_e32 v90, v75, v87
	v_mul_f32_e32 v91, v78, v88
	v_cvt_pk_bf16_f32 v73, v73, v74
	v_mul_f32_e32 v74, v56, v85
	v_mul_f32_e32 v89, v56, v86
	v_mul_f32_e32 v56, v57, v87
	v_mul_f32_e32 v93, v75, v90
	v_mul_f32_e32 v78, v78, v91
	v_mul_f32_e32 v92, v57, v88
	v_cvt_pk_bf16_f32 v74, v74, v56
	v_mul_f32_e32 v56, v58, v90
	v_mul_f32_e32 v57, v59, v93
	v_mul_f32_e32 v59, v59, v78
	v_cvt_pk_bf16_f32 v75, v56, v57
	v_mul_f32_e32 v61, v61, v71
	v_mul_f32_e32 v62, v62, v60
	v_mul_f32_e32 v63, v63, v84
	v_mul_f32_e32 v94, v58, v91
	v_cvt_pk_bf16_f32 v56, v81, v61
	v_cvt_pk_bf16_f32 v57, v62, v63
	v_cvt_pk_bf16_f32 v58, v89, v92
	v_cvt_pk_bf16_f32 v59, v94, v59
	global_store_dwordx4 v[76:77], v[72:75], off
	global_store_dwordx4 v[68:69], v[56:59], off
	s_nop 1
	v_mul_f32_e32 v56, v52, v79
	v_mul_f32_e32 v57, v53, v80
	v_cvt_pk_bf16_f32 v56, v56, v57
	v_mul_f32_e32 v57, v54, v82
	v_mul_f32_e32 v58, v55, v83
	v_cvt_pk_bf16_f32 v57, v57, v58
	v_mul_f32_e32 v58, v48, v85
	v_mul_f32_e32 v59, v49, v87
	v_cvt_pk_bf16_f32 v58, v58, v59
	v_mul_f32_e32 v59, v50, v90
	v_mul_f32_e32 v52, v52, v70
	v_mul_f32_e32 v53, v53, v71
	v_mul_f32_e32 v61, v51, v93
	v_cvt_pk_bf16_f32 v59, v59, v61
	v_cvt_pk_bf16_f32 v52, v52, v53
	v_mul_f32_e32 v53, v54, v60
	v_mul_f32_e32 v54, v55, v84
	v_mul_f32_e32 v48, v48, v86
	v_mul_f32_e32 v49, v49, v88
	v_cvt_pk_bf16_f32 v53, v53, v54
	v_cvt_pk_bf16_f32 v54, v48, v49
	v_mul_f32_e32 v48, v50, v91
	v_mul_f32_e32 v49, v51, v78
	v_cvt_pk_bf16_f32 v55, v48, v49
	global_store_dwordx4 v[64:65], v[56:59], off offset:256
	global_store_dwordx4 v[66:67], v[52:55], off offset:256
	v_mul_f32_e32 v48, v44, v79
	v_mul_f32_e32 v49, v45, v80
	v_cvt_pk_bf16_f32 v48, v48, v49
	v_mul_f32_e32 v49, v46, v82
	v_mul_f32_e32 v50, v47, v83
	v_cvt_pk_bf16_f32 v49, v49, v50
	v_mul_f32_e32 v50, v40, v85
	v_mul_f32_e32 v51, v41, v87
	v_cvt_pk_bf16_f32 v50, v50, v51
	v_mul_f32_e32 v51, v42, v90
	v_mul_f32_e32 v44, v44, v70
	v_mul_f32_e32 v45, v45, v71
	v_mul_f32_e32 v52, v43, v93
	v_cvt_pk_bf16_f32 v51, v51, v52
	v_cvt_pk_bf16_f32 v44, v44, v45
	v_mul_f32_e32 v45, v46, v60
	v_mul_f32_e32 v46, v47, v84
	v_mul_f32_e32 v40, v40, v86
	s_mov_b64 s[2:3], 0x240000
	v_cvt_pk_bf16_f32 v45, v45, v46
	v_mul_f32_e32 v41, v41, v88
	v_cvt_pk_bf16_f32 v46, v40, v41
	v_mul_f32_e32 v40, v42, v91
	v_lshl_add_u64 v[52:53], v[140:141], 0, s[2:3]
	s_mov_b32 s2, 0x240000
	v_mul_f32_e32 v41, v43, v78
	v_cvt_pk_bf16_f32 v47, v40, v41
	v_add_co_u32_e32 v40, vcc, s2, v140
	s_mov_b64 s[2:3], 0x640000
	s_nop 0
	v_addc_co_u32_e32 v41, vcc, 0, v141, vcc
	global_store_dwordx4 v[40:41], v[48:51], off
	s_nop 1
	v_lshl_add_u64 v[48:49], v[140:141], 0, s[2:3]
	s_mov_b32 s2, 0x640000
	v_add_co_u32_e32 v40, vcc, s2, v140
	s_nop 1
	v_addc_co_u32_e32 v41, vcc, 0, v141, vcc
	global_store_dwordx4 v[40:41], v[44:47], off
	v_mul_f32_e32 v40, v36, v79
	v_mul_f32_e32 v41, v37, v80
	v_cvt_pk_bf16_f32 v40, v40, v41
	v_mul_f32_e32 v41, v38, v82
	v_mul_f32_e32 v42, v39, v83
	v_cvt_pk_bf16_f32 v41, v41, v42
	v_mul_f32_e32 v42, v32, v85
	v_mul_f32_e32 v43, v33, v87
	v_cvt_pk_bf16_f32 v42, v42, v43
	v_mul_f32_e32 v43, v34, v90
	v_mul_f32_e32 v36, v36, v70
; template <class Epi, class Sched>
; __device__ __forceinline__ void gemm_phase(LAS unsigned char* lds, const Gemm g, const Sched& S, const Epi& E) {
;     ...
;         E(acc, cur, wr, wc, fr, fq);
;         if (!has_next) break;
; #pragma unroll
;         for (int a = 0; a < 2; ++a)
; #pragma unroll
;     __device__ __forceinline__ void operator()(const AccT& acc, const Unit& u, int wr, int wc, int fr, int fq) const {
;     ...
;                 for (int bj = 0; bj < 2; ++bj) {
;                     const int t0 = tb + bj * 128;
;                     float v[8];
; #pragma unroll
;                     for (int jj = 0; jj < 4; ++jj) { v[jj] = acc[ai][bj][m][0][jj]; v[4 + jj] = acc[ai][bj][m][1][jj]; }
;                     if constexpr (ROPE) {
;                         const int t = t0 & 2047;
; #pragma unroll
;                         for (int hf = 0; hf < 2; ++hf) {
;                             f32x4 cs, sn;
;                             if (m < 2) { const float c1 = ropeA[(t >> 6) * 16 + d], s1 = ropeA[1024 + (t >> 6) * 16 + d]; cs = (f32x4){c1, c1, c1, c1}; sn = (f32x4){s1, s1, s1, s1}; }
;                             else { const float* cb = ropeA + 2048 + (d - 16) * 64 + (t & 63) + 4 * hf; cs = *(const f32x4*)(cb); sn = *(const f32x4*)(cb + 1024); }
; #pragma unroll
;                             for (int jj = 0; jj < 4; ++jj) { const float pr = __shfl_xor(v[4 * hf + jj], 4); v[4 * hf + jj] = v[4 * hf + jj] * cs[jj] + sgn * pr * sn[jj]; }
;                             __builtin_amdgcn_sched_barrier(0);
;                         }
;                     }
;                     float zf[8], zb[8]; zf[0] = zf0; zb[0] = zb0;
; #pragma unroll
;                     for (int jj = 1; jj < 8; ++jj) { zf[jj] = zf[jj - 1] * zfs; zb[jj] = zb[jj - 1] * zbs; }
;                     u32x4 wf, wb;
;                     wf.x = cvt_pk_bf16(v[0] * zf[0], v[1] * zf[1]); wf.y = cvt_pk_bf16(v[2] * zf[2], v[3] * zf[3]); wf.z = cvt_pk_bf16(v[4] * zf[4], v[5] * zf[5]); wf.w = cvt_pk_bf16(v[6] * zf[6], v[7] * zf[7]);
;                     wb.x = cvt_pk_bf16(v[0] * zb[0], v[1] * zb[1]); wb.y = cvt_pk_bf16(v[2] * zb[2], v[3] * zb[3]); wb.z = cvt_pk_bf16(v[4] * zb[4], v[5] * zb[5]); wb.w = cvt_pk_bf16(v[6] * zb[6], v[7] * zb[7]);
;                     *(u32x4*)(KTZ + (size_t)r * NT + t0) = wf;
;                     *(u32x4*)(KTZ + (size_t)(256 + r) * NT + t0) = wb;
	v_mul_f32_e32 v37, v37, v71
	v_mul_f32_e32 v44, v35, v93
	v_cvt_pk_bf16_f32 v43, v43, v44
	v_cvt_pk_bf16_f32 v36, v36, v37
	v_mul_f32_e32 v37, v38, v60
	v_mul_f32_e32 v38, v39, v84
	v_mul_f32_e32 v32, v32, v86
	v_mul_f32_e32 v33, v33, v88
	v_cvt_pk_bf16_f32 v37, v37, v38
	v_cvt_pk_bf16_f32 v38, v32, v33
	v_mul_f32_e32 v32, v34, v91
	v_mul_f32_e32 v33, v35, v78
	v_cvt_pk_bf16_f32 v39, v32, v33
	global_store_dwordx4 v[52:53], v[40:43], off offset:256
	global_store_dwordx4 v[48:49], v[36:39], off offset:256
	v_mul_f32_e32 v32, v28, v79
	v_mul_f32_e32 v33, v29, v80
	v_cvt_pk_bf16_f32 v32, v32, v33
	v_mul_f32_e32 v33, v30, v82
	v_mul_f32_e32 v34, v31, v83
	v_cvt_pk_bf16_f32 v33, v33, v34
	v_mul_f32_e32 v34, v24, v85
	v_mul_f32_e32 v35, v25, v87
	v_cvt_pk_bf16_f32 v34, v34, v35
	v_mul_f32_e32 v35, v26, v90
	v_mul_f32_e32 v28, v28, v70
	v_mul_f32_e32 v29, v29, v71
	v_mul_f32_e32 v36, v27, v93
	v_cvt_pk_bf16_f32 v35, v35, v36
	v_cvt_pk_bf16_f32 v28, v28, v29
	v_mul_f32_e32 v29, v30, v60
	v_mul_f32_e32 v30, v31, v84
	v_mul_f32_e32 v24, v24, v86
	v_cvt_pk_bf16_f32 v29, v29, v30
	v_mul_f32_e32 v25, v25, v88
	v_cvt_pk_bf16_f32 v30, v24, v25
	v_mul_f32_e32 v24, v26, v91
	v_mul_f32_e32 v25, v27, v78
	v_cvt_pk_bf16_f32 v31, v24, v25
	v_add_co_u32_e32 v24, vcc, s52, v140
	s_mov_b64 s[2:3], 0x280000
	s_nop 0
	v_addc_co_u32_e32 v25, vcc, 0, v141, vcc
	global_store_dwordx4 v[24:25], v[32:35], off
	v_add_co_u32_e32 v24, vcc, s53, v140
	v_lshl_add_u64 v[36:37], v[140:141], 0, s[2:3]
	s_nop 0
	v_addc_co_u32_e32 v25, vcc, 0, v141, vcc
	v_lshl_add_u64 v[32:33], v[140:141], 0, s[8:9]
	global_store_dwordx4 v[24:25], v[28:31], off
	v_mul_f32_e32 v24, v20, v79
	v_mul_f32_e32 v25, v21, v80
	v_cvt_pk_bf16_f32 v24, v24, v25
	v_mul_f32_e32 v25, v22, v82
	v_mul_f32_e32 v26, v23, v83
	v_cvt_pk_bf16_f32 v25, v25, v26
	v_mul_f32_e32 v26, v16, v85
	v_mul_f32_e32 v27, v17, v87
	v_cvt_pk_bf16_f32 v26, v26, v27
	v_mul_f32_e32 v27, v18, v90
	v_mul_f32_e32 v20, v20, v70
	v_mul_f32_e32 v21, v21, v71
	v_mul_f32_e32 v28, v19, v93
	v_cvt_pk_bf16_f32 v27, v27, v28
	v_cvt_pk_bf16_f32 v20, v20, v21
	v_mul_f32_e32 v21, v22, v60
	v_mul_f32_e32 v22, v23, v84
	v_mul_f32_e32 v16, v16, v86
	v_mul_f32_e32 v17, v17, v88
	v_cvt_pk_bf16_f32 v21, v21, v22
	v_cvt_pk_bf16_f32 v22, v16, v17
	v_mul_f32_e32 v16, v18, v91
	v_mul_f32_e32 v17, v19, v78
	v_cvt_pk_bf16_f32 v23, v16, v17
	global_store_dwordx4 v[36:37], v[24:27], off offset:256
	global_store_dwordx4 v[32:33], v[20:23], off offset:256
	v_mul_f32_e32 v16, v12, v79
	v_mul_f32_e32 v17, v13, v80
	v_cvt_pk_bf16_f32 v16, v16, v17
	v_mul_f32_e32 v17, v14, v82
	v_mul_f32_e32 v18, v15, v83
	v_cvt_pk_bf16_f32 v17, v17, v18
	v_mul_f32_e32 v18, v8, v85
	v_mul_f32_e32 v19, v9, v87
	v_cvt_pk_bf16_f32 v18, v18, v19
	v_mul_f32_e32 v19, v10, v90
	v_mul_f32_e32 v12, v12, v70
	v_mul_f32_e32 v13, v13, v71
	v_mul_f32_e32 v20, v11, v93
	v_cvt_pk_bf16_f32 v19, v19, v20
	v_cvt_pk_bf16_f32 v12, v12, v13
	v_mul_f32_e32 v13, v14, v60
	v_mul_f32_e32 v14, v15, v84
	v_mul_f32_e32 v8, v8, v86
	v_cvt_pk_bf16_f32 v13, v13, v14
	v_mul_f32_e32 v9, v9, v88
	v_cvt_pk_bf16_f32 v14, v8, v9
	v_mul_f32_e32 v8, v10, v91
	v_mul_f32_e32 v9, v11, v78
	v_cvt_pk_bf16_f32 v15, v8, v9
	v_add_co_u32_e32 v8, vcc, s54, v140
	v_lshl_add_u64 v[20:21], v[140:141], 0, s[10:11]
	s_nop 0
	v_addc_co_u32_e32 v9, vcc, 0, v141, vcc
	global_store_dwordx4 v[8:9], v[16:19], off
	v_add_co_u32_e32 v8, vcc, s55, v140
	s_nop 0
	v_lshl_add_u64 v[16:17], v[140:141], 0, s[12:13]
	v_addc_co_u32_e32 v9, vcc, 0, v141, vcc
	global_store_dwordx4 v[8:9], v[12:15], off
	v_mul_f32_e32 v8, v4, v79
	v_mul_f32_e32 v9, v5, v80
	v_cvt_pk_bf16_f32 v8, v8, v9
	v_mul_f32_e32 v9, v6, v82
	v_mul_f32_e32 v10, v7, v83
	v_cvt_pk_bf16_f32 v9, v9, v10
	v_mul_f32_e32 v10, v0, v85
	v_mul_f32_e32 v11, v1, v87
	v_cvt_pk_bf16_f32 v10, v10, v11
	v_mul_f32_e32 v11, v2, v90
	v_mul_f32_e32 v4, v4, v70
	v_mul_f32_e32 v5, v5, v71
	v_mul_f32_e32 v12, v3, v93
	v_cvt_pk_bf16_f32 v11, v11, v12
	v_cvt_pk_bf16_f32 v4, v4, v5
	v_mul_f32_e32 v5, v6, v60
	v_mul_f32_e32 v6, v7, v84
	v_mul_f32_e32 v0, v0, v86
	v_mul_f32_e32 v1, v1, v88
	v_cvt_pk_bf16_f32 v5, v5, v6
	v_cvt_pk_bf16_f32 v6, v0, v1
	v_mul_f32_e32 v0, v2, v91
	v_mul_f32_e32 v1, v3, v78
	v_cvt_pk_bf16_f32 v7, v0, v1
	global_store_dwordx4 v[20:21], v[8:11], off offset:256
	global_store_dwordx4 v[16:17], v[4:7], off offset:256
	s_and_b64 vcc, exec, s[14:15]
	s_mov_b32 s56, s16
	s_mov_b64 s[4:5], s[22:23]
	s_mov_b64 s[2:3], s[20:21]
	s_cbranch_vccz .LBB0_686
	s_waitcnt vmcnt(0)
	s_cmpk_gt_u32 s27, 0xff
	s_cbranch_scc1 .LBB0_697
	s_barrier

; #define PG8_STAGE(bufoff, gbase, voff) do { _Pragma("unroll") for (int _i = 0; _i < 2; ++_i) \
;         __builtin_amdgcn_global_load_lds((const unsigned*)((const char*)(gbase) + (voff)[_i]), (LAS unsigned*)(lds + (bufoff) + ldsw + _i * 8192), 16, 0, 0); } while (0)
; #define PG8_LDA(dst, b, h) do { _Pragma("unroll") for (int m = 0; m < 4; ++m) _Pragma("unroll") for (int k = 0; k < 2; ++k) dst[m][k] = *(const LAS bf16x8*)(lds + PG8_SA(b, h) + aoff + m * 2048 + k * 1024); } while (0)
; #define PG8_LDB(dst, b, h) do { _Pragma("unroll") for (int n = 0; n < 2; ++n) _Pragma("unroll") for (int k = 0; k < 2; ++k) dst[n][k] = *(const LAS bf16x8*)(lds + PG8_SB(b, h) + boff + n * 2048 + k * 1024); } while (0)
; #define PG8_MMA(ai, bj, At, Bt) do { __builtin_amdgcn_s_setprio(1); _Pragma("unroll") for (int m = 0; m < 4; ++m) _Pragma("unroll") for (int n = 0; n < 2; ++n) _Pragma("unroll") for (int k = 0; k < 2; ++k) \
;         acc[ai][bj][m][n] = __builtin_amdgcn_mfma_f32_16x16x32_bf16(Bt[n][k], At[m][k], acc[ai][bj][m][n], 0, 0, 0); __builtin_amdgcn_s_setprio(0); } while (0)
; template <class Epi, class Sched>
; __device__ __forceinline__ void gemm_phase(LAS unsigned char* lds, const Gemm g, const Sched& S, const Epi& E) {
;     ...
;         const char* nA = has_next ? (const char*)g.A + (size_t)nxt.pm * tstep : cA; const char* nB = has_next ? (const char*)g.Bt + (size_t)nxt.pn * tstep : cB;
;         for (int t = 0; t < nt; t += 2) {
;             const bool last = (t == nt - 2);
;             const char* a1 = cA + (size_t)(t + 1) * kstep;
;             const char* a2 = last ? nA : cA + (size_t)(t + 2) * kstep; const char* b2 = last ? nB : cB + (size_t)(t + 2) * kstep;
;             const char* a3 = a2 + kstep; const char* b3 = b2 + kstep;
;             PG8_LDB(B0, 0, 0); PG8_SCHED; PG8_LDA(At, 0, 0); PG8_STAGE(PG8_SA(1, 1), a1 + hstep, voffA);
;             PG8_WAIT_L(8); PG8_BAR; PG8_WAIT_L(0); PG8_MMA(0, 0, At, B0); PG8_BAR; PG8_SCHED;
;             PG8_LDB(B1, 0, 1); PG8_STAGE(PG8_SB(0, 0), b2, voffB);
;             PG8_BAR; PG8_WAIT_L(0); PG8_MMA(0, 1, At, B1); PG8_BAR;
;             PG8_LDA(At, 0, 1); PG8_STAGE(PG8_SA(0, 0), a2, voffA);
;             PG8_BAR; PG8_WAIT_L(0); PG8_MMA(1, 0, At, B0); PG8_BAR; PG8_SCHED;
;             PG8_STAGE(PG8_SB(0, 1), b2 + hstep, voffB);
;             PG8_WAIT_V(6); PG8_BAR; PG8_MMA(1, 1, At, B1); PG8_BAR;
.LBB0_712:
	s_ashr_i32 s15, s14, 31
	v_cmp_lt_i64_e64 s[26:27], s[16:17], 64
	s_lshl_b64 s[16:17], s[14:15], 19
	s_add_u32 s16, s38, s16
	s_addc_u32 s17, s39, s17
	s_and_b64 s[18:19], s[26:27], exec
	s_cselect_b32 s15, s17, s23
	s_cselect_b32 s54, s16, s22
	s_ashr_i32 s13, s12, 31
	s_lshl_b64 s[18:19], s[12:13], 19
	s_add_u32 s18, s28, s18
	s_addc_u32 s19, s29, s19
	s_and_b64 s[26:27], s[26:27], exec
	s_cselect_b32 s13, s19, s25
	s_cselect_b32 s55, s18, s24
	s_add_u32 s22, s22, 0x40080
	s_addc_u32 s23, s23, 0
	s_add_u32 s56, s24, 0x100
	s_addc_u32 s57, s25, 0
	s_mov_b32 s58, -2
	s_waitcnt lgkmcnt(0)
	ds_read_b128 v[146:149], v143
	ds_read_b128 v[150:153], v143 offset:1024
	ds_read_b128 v[154:157], v143 offset:2048
	ds_read_b128 v[158:161], v143 offset:3072
	s_add_u32 s24, s22, 0xfffc0080
	s_addc_u32 s25, s23, -1
	s_cmp_eq_u32 s58, 12
	s_cselect_b32 s27, s15, s25
	s_cselect_b32 s26, s54, s24
	s_cselect_b32 s25, s13, s57
	s_cselect_b32 s24, s55, s56
	s_add_i32 m0, s21, 0xc000
	ds_read_b128 v[162:165], v144
	ds_read_b128 v[166:169], v144 offset:1024
	ds_read_b128 v[170:173], v144 offset:2048
	ds_read_b128 v[174:177], v144 offset:3072
	ds_read_b128 v[178:181], v144 offset:4096
	ds_read_b128 v[182:185], v144 offset:5120
	ds_read_b128 v[186:189], v144 offset:6144
	ds_read_b128 v[190:193], v144 offset:7168
	global_load_lds_dwordx4 v136, s[22:23]
	s_add_i32 m0, s21, 0xe000
	s_nop 0
	global_load_lds_dwordx4 v138, s[22:23]
	s_waitcnt lgkmcnt(8)
	s_waitcnt vmcnt(8)
	s_setprio 1
	s_barrier
	s_waitcnt lgkmcnt(0)
	v_mfma_f32_16x16x32_bf16 v[124:127], v[146:149], v[162:165], 0
	v_mfma_f32_16x16x32_bf16 v[120:123], v[154:157], v[162:165], 0
	v_mfma_f32_16x16x32_bf16 v[116:119], v[146:149], v[170:173], 0
	v_mfma_f32_16x16x32_bf16 v[108:111], v[154:157], v[170:173], 0
	v_mfma_f32_16x16x32_bf16 v[100:103], v[146:149], v[178:181], 0
	v_mfma_f32_16x16x32_bf16 v[92:95], v[154:157], v[178:181], 0
	v_mfma_f32_16x16x32_bf16 v[84:87], v[146:149], v[186:189], 0
	v_mfma_f32_16x16x32_bf16 v[76:79], v[154:157], v[186:189], 0
	v_mfma_f32_16x16x32_bf16 v[124:127], v[150:153], v[166:169], v[124:127]
	v_mfma_f32_16x16x32_bf16 v[120:123], v[158:161], v[166:169], v[120:123]
	v_mfma_f32_16x16x32_bf16 v[116:119], v[150:153], v[174:177], v[116:119]
	v_mfma_f32_16x16x32_bf16 v[108:111], v[158:161], v[174:177], v[108:111]
	v_mfma_f32_16x16x32_bf16 v[100:103], v[150:153], v[182:185], v[100:103]
	v_mfma_f32_16x16x32_bf16 v[92:95], v[158:161], v[182:185], v[92:95]
	v_mfma_f32_16x16x32_bf16 v[84:87], v[150:153], v[190:193], v[84:87]
	v_mfma_f32_16x16x32_bf16 v[76:79], v[158:161], v[190:193], v[76:79]
	s_barrier
	s_setprio 0
	s_add_i32 s59, s46, s34
	s_mov_b32 m0, s59
	ds_read_b128 v[194:197], v145
	ds_read_b128 v[202:205], v145 offset:1024
	ds_read_b128 v[206:209], v145 offset:2048
	ds_read_b128 v[210:213], v145 offset:3072
	global_load_lds_dwordx4 v130, s[24:25]
	s_add_i32 m0, s59, 0x2000
	s_nop 0
	global_load_lds_dwordx4 v134, s[24:25]
	s_waitcnt vmcnt(8)
	s_setprio 1
	s_barrier
	s_waitcnt lgkmcnt(0)
	v_mfma_f32_16x16x32_bf16 v[112:115], v[194:197], v[162:165], 0
	v_mfma_f32_16x16x32_bf16 v[104:107], v[206:209], v[162:165], 0
	v_mfma_f32_16x16x32_bf16 v[96:99], v[194:197], v[170:173], 0
	v_mfma_f32_16x16x32_bf16 v[88:91], v[206:209], v[170:173], 0
	v_mfma_f32_16x16x32_bf16 v[80:83], v[194:197], v[178:181], 0
	v_mfma_f32_16x16x32_bf16 v[72:75], v[206:209], v[178:181], 0
	v_mfma_f32_16x16x32_bf16 v[68:71], v[194:197], v[186:189], 0
	v_mfma_f32_16x16x32_bf16 v[64:67], v[206:209], v[186:189], 0
	v_mfma_f32_16x16x32_bf16 v[112:115], v[202:205], v[166:169], v[112:115]
	v_mfma_f32_16x16x32_bf16 v[104:107], v[210:213], v[166:169], v[104:107]
	v_mfma_f32_16x16x32_bf16 v[96:99], v[202:205], v[174:177], v[96:99]
	v_mfma_f32_16x16x32_bf16 v[88:91], v[210:213], v[174:177], v[88:91]
	v_mfma_f32_16x16x32_bf16 v[80:83], v[202:205], v[182:185], v[80:83]
	v_mfma_f32_16x16x32_bf16 v[72:75], v[210:213], v[182:185], v[72:75]
	v_mfma_f32_16x16x32_bf16 v[68:71], v[202:205], v[190:193], v[68:71]
	v_mfma_f32_16x16x32_bf16 v[64:67], v[210:213], v[190:193], v[64:67]
	s_mov_b32 m0, s21
	v_lshl_add_u64 v[216:217], s[26:27], 0, v[128:129]
	s_barrier
	s_setprio 0
	ds_read_b128 v[162:165], v144 offset:16384
	ds_read_b128 v[166:169], v144 offset:17408
	ds_read_b128 v[170:173], v144 offset:18432
	ds_read_b128 v[174:177], v144 offset:19456
	ds_read_b128 v[178:181], v144 offset:20480
	ds_read_b128 v[182:185], v144 offset:21504
	ds_read_b128 v[186:189], v144 offset:22528
	ds_read_b128 v[190:193], v144 offset:23552
	global_load_lds_dwordx4 v128, s[26:27]
	v_lshl_add_u64 v[218:219], s[26:27], 0, v[132:133]
	s_mov_b32 m0, s35
	s_nop 0
	global_load_lds_dwordx4 v132, s[26:27]
	s_setprio 1
	s_barrier
	s_waitcnt lgkmcnt(0)
	v_mfma_f32_16x16x32_bf16 v[60:63], v[146:149], v[162:165], 0
	v_mfma_f32_16x16x32_bf16 v[56:59], v[154:157], v[162:165], 0
	v_mfma_f32_16x16x32_bf16 v[52:55], v[146:149], v[170:173], 0
	v_mfma_f32_16x16x32_bf16 v[44:47], v[154:157], v[170:173], 0
	v_mfma_f32_16x16x32_bf16 v[36:39], v[146:149], v[178:181], 0
	v_mfma_f32_16x16x32_bf16 v[28:31], v[154:157], v[178:181], 0
	v_mfma_f32_16x16x32_bf16 v[20:23], v[146:149], v[186:189], 0
	v_mfma_f32_16x16x32_bf16 v[12:15], v[154:157], v[186:189], 0
	v_mfma_f32_16x16x32_bf16 v[60:63], v[150:153], v[166:169], v[60:63]
	v_mfma_f32_16x16x32_bf16 v[56:59], v[158:161], v[166:169], v[56:59]
	v_mfma_f32_16x16x32_bf16 v[52:55], v[150:153], v[174:177], v[52:55]
	v_mfma_f32_16x16x32_bf16 v[44:47], v[158:161], v[174:177], v[44:47]
	v_mfma_f32_16x16x32_bf16 v[36:39], v[150:153], v[182:185], v[36:39]
	v_mfma_f32_16x16x32_bf16 v[28:31], v[158:161], v[182:185], v[28:31]
	v_mfma_f32_16x16x32_bf16 v[20:23], v[150:153], v[190:193], v[20:23]
	v_mfma_f32_16x16x32_bf16 v[12:15], v[158:161], v[190:193], v[12:15]
	s_barrier
; #define PG8_STAGE(bufoff, gbase, voff) do { _Pragma("unroll") for (int _i = 0; _i < 2; ++_i) \
;         __builtin_amdgcn_global_load_lds((const unsigned*)((const char*)(gbase) + (voff)[_i]), (LAS unsigned*)(lds + (bufoff) + ldsw + _i * 8192), 16, 0, 0); } while (0)
; #define PG8_LDA(dst, b, h) do { _Pragma("unroll") for (int m = 0; m < 4; ++m) _Pragma("unroll") for (int k = 0; k < 2; ++k) dst[m][k] = *(const LAS bf16x8*)(lds + PG8_SA(b, h) + aoff + m * 2048 + k * 1024); } while (0)
; #define PG8_LDB(dst, b, h) do { _Pragma("unroll") for (int n = 0; n < 2; ++n) _Pragma("unroll") for (int k = 0; k < 2; ++k) dst[n][k] = *(const LAS bf16x8*)(lds + PG8_SB(b, h) + boff + n * 2048 + k * 1024); } while (0)
; #define PG8_MMA(ai, bj, At, Bt) do { __builtin_amdgcn_s_setprio(1); _Pragma("unroll") for (int m = 0; m < 4; ++m) _Pragma("unroll") for (int n = 0; n < 2; ++n) _Pragma("unroll") for (int k = 0; k < 2; ++k) \
;         acc[ai][bj][m][n] = __builtin_amdgcn_mfma_f32_16x16x32_bf16(Bt[n][k], At[m][k], acc[ai][bj][m][n], 0, 0, 0); __builtin_amdgcn_s_setprio(0); } while (0)
; #define PG8_WAIT_V(n) asm volatile("s_waitcnt vmcnt(" #n ")" ::: "memory")
; #define PG8_WAIT_L(n) asm volatile("s_waitcnt lgkmcnt(" #n ")" ::: "memory")
; #define PG8_BAR __builtin_amdgcn_s_barrier()
; #define PG8_SCHED __builtin_amdgcn_sched_barrier(0)
; template <class Epi, class Sched>
; __device__ __forceinline__ void gemm_phase(LAS unsigned char* lds, const Gemm g, const Sched& S, const Epi& E) {
;     ...
;             PG8_BAR; PG8_WAIT_L(0); PG8_MMA(1, 0, At, B0); PG8_BAR; PG8_SCHED;
;             PG8_STAGE(PG8_SB(0, 1), b2 + hstep, voffB);
;             PG8_WAIT_V(6); PG8_BAR; PG8_MMA(1, 1, At, B1); PG8_BAR;
;             PG8_LDB(B0, 1, 0); PG8_SCHED; PG8_LDA(At, 1, 0); PG8_STAGE(PG8_SA(0, 1), a2 + hstep, voffA);
;             PG8_WAIT_L(8); PG8_BAR; PG8_WAIT_L(0); PG8_MMA(0, 0, At, B0); PG8_BAR; PG8_SCHED;
;             PG8_LDB(B1, 1, 1); PG8_STAGE(PG8_SB(1, 0), b3, voffB);
;             PG8_BAR; PG8_WAIT_L(0); PG8_MMA(0, 1, At, B1); PG8_BAR;
;             PG8_LDA(At, 1, 1); PG8_STAGE(PG8_SA(1, 0), a3, voffA);
;             PG8_BAR; PG8_WAIT_L(0); PG8_MMA(1, 0, At, B0); PG8_BAR; PG8_SCHED;
	s_setprio 0
	s_add_u32 s60, s24, 0x40000
	s_addc_u32 s61, s25, 0
	s_add_i32 s59, s47, s34
	s_mov_b32 m0, s59
	s_nop 0
	global_load_lds_dwordx4 v130, s[60:61]
	s_add_i32 m0, s59, 0x2000
	s_nop 0
	global_load_lds_dwordx4 v134, s[60:61]
	s_add_u32 s26, s26, 0x40000
	s_addc_u32 s27, s27, 0
	s_mov_b32 m0, s36
	s_nop 0
	global_load_lds_dwordx4 v128, s[26:27]
	s_mov_b32 m0, s37
	s_nop 0
	global_load_lds_dwordx4 v132, s[26:27]
	s_waitcnt vmcnt(10)
	s_setprio 1
	s_barrier
	v_mfma_f32_16x16x32_bf16 v[48:51], v[194:197], v[162:165], 0
	v_mfma_f32_16x16x32_bf16 v[40:43], v[206:209], v[162:165], 0
	v_mfma_f32_16x16x32_bf16 v[32:35], v[194:197], v[170:173], 0
	v_mfma_f32_16x16x32_bf16 v[24:27], v[206:209], v[170:173], 0
	v_mfma_f32_16x16x32_bf16 v[16:19], v[194:197], v[178:181], 0
	v_mfma_f32_16x16x32_bf16 v[8:11], v[206:209], v[178:181], 0
	v_mfma_f32_16x16x32_bf16 v[4:7], v[194:197], v[186:189], 0
	v_mfma_f32_16x16x32_bf16 v[0:3], v[206:209], v[186:189], 0
	v_mfma_f32_16x16x32_bf16 v[48:51], v[202:205], v[166:169], v[48:51]
	v_mfma_f32_16x16x32_bf16 v[40:43], v[210:213], v[166:169], v[40:43]
	v_mfma_f32_16x16x32_bf16 v[32:35], v[202:205], v[174:177], v[32:35]
	v_mfma_f32_16x16x32_bf16 v[24:27], v[210:213], v[174:177], v[24:27]
	v_mfma_f32_16x16x32_bf16 v[16:19], v[202:205], v[182:185], v[16:19]
	v_mfma_f32_16x16x32_bf16 v[8:11], v[210:213], v[182:185], v[8:11]
	v_mfma_f32_16x16x32_bf16 v[4:7], v[202:205], v[190:193], v[4:7]
	v_mfma_f32_16x16x32_bf16 v[0:3], v[210:213], v[190:193], v[0:3]
	s_add_i32 s59, 0, 0x18000
	v_add_u32_e32 v158, s59, v142
	s_barrier
	s_setprio 0
	ds_read_b128 v[146:149], v158
	ds_read_b128 v[150:153], v158 offset:1024
	ds_read_b128 v[154:157], v158 offset:2048
	ds_read_b128 v[158:161], v158 offset:3072
	ds_read_b128 v[162:165], v144 offset:32768
	ds_read_b128 v[166:169], v144 offset:33792
	ds_read_b128 v[170:173], v144 offset:34816
	ds_read_b128 v[174:177], v144 offset:35840
	ds_read_b128 v[178:181], v144 offset:36864
	ds_read_b128 v[182:185], v144 offset:37888
	ds_read_b128 v[186:189], v144 offset:38912
	ds_read_b128 v[190:193], v144 offset:39936
	s_waitcnt lgkmcnt(8)
	s_waitcnt vmcnt(8)
	s_setprio 1
	s_barrier
	s_waitcnt lgkmcnt(0)
	v_mfma_f32_16x16x32_bf16 v[124:127], v[146:149], v[162:165], v[124:127]
	v_mfma_f32_16x16x32_bf16 v[120:123], v[154:157], v[162:165], v[120:123]
	v_mfma_f32_16x16x32_bf16 v[116:119], v[146:149], v[170:173], v[116:119]
	v_mfma_f32_16x16x32_bf16 v[108:111], v[154:157], v[170:173], v[108:111]
	v_mfma_f32_16x16x32_bf16 v[100:103], v[146:149], v[178:181], v[100:103]
	v_mfma_f32_16x16x32_bf16 v[92:95], v[154:157], v[178:181], v[92:95]
	v_mfma_f32_16x16x32_bf16 v[84:87], v[146:149], v[186:189], v[84:87]
	v_mfma_f32_16x16x32_bf16 v[76:79], v[154:157], v[186:189], v[76:79]
	v_mfma_f32_16x16x32_bf16 v[124:127], v[150:153], v[166:169], v[124:127]
	v_mfma_f32_16x16x32_bf16 v[120:123], v[158:161], v[166:169], v[120:123]
	v_mfma_f32_16x16x32_bf16 v[116:119], v[150:153], v[174:177], v[116:119]
	v_mfma_f32_16x16x32_bf16 v[108:111], v[158:161], v[174:177], v[108:111]
	v_mfma_f32_16x16x32_bf16 v[100:103], v[150:153], v[182:185], v[100:103]
	v_mfma_f32_16x16x32_bf16 v[92:95], v[158:161], v[182:185], v[92:95]
	v_mfma_f32_16x16x32_bf16 v[84:87], v[150:153], v[190:193], v[84:87]
	v_mfma_f32_16x16x32_bf16 v[76:79], v[158:161], v[190:193], v[76:79]
	s_barrier
	s_setprio 0
	s_add_i32 s26, 0, 0x1c000
	s_add_i32 s27, s59, s34
	v_add_u32_e32 v210, s26, v142
	s_add_u32 s0, s24, 0x80
	s_addc_u32 s1, s25, 0
	s_mov_b32 m0, s27
	ds_read_b128 v[194:197], v210
	ds_read_b128 v[202:205], v210 offset:1024
	ds_read_b128 v[206:209], v210 offset:2048
	ds_read_b128 v[210:213], v210 offset:3072
	global_load_lds_dwordx4 v130, s[0:1]
	s_add_i32 m0, s27, 0x2000
	s_nop 0
	global_load_lds_dwordx4 v134, s[0:1]
	s_waitcnt vmcnt(8)
	s_setprio 1
	s_barrier
	s_waitcnt lgkmcnt(0)
	v_mfma_f32_16x16x32_bf16 v[112:115], v[194:197], v[162:165], v[112:115]
	v_mfma_f32_16x16x32_bf16 v[104:107], v[206:209], v[162:165], v[104:107]
	v_mfma_f32_16x16x32_bf16 v[96:99], v[194:197], v[170:173], v[96:99]
	v_mfma_f32_16x16x32_bf16 v[88:91], v[206:209], v[170:173], v[88:91]
	v_mfma_f32_16x16x32_bf16 v[80:83], v[194:197], v[178:181], v[80:83]
	v_mfma_f32_16x16x32_bf16 v[72:75], v[206:209], v[178:181], v[72:75]
	v_mfma_f32_16x16x32_bf16 v[68:71], v[194:197], v[186:189], v[68:71]
	v_mfma_f32_16x16x32_bf16 v[64:67], v[206:209], v[186:189], v[64:67]
	v_mfma_f32_16x16x32_bf16 v[112:115], v[202:205], v[166:169], v[112:115]
	v_mfma_f32_16x16x32_bf16 v[104:107], v[210:213], v[166:169], v[104:107]
	v_mfma_f32_16x16x32_bf16 v[96:99], v[202:205], v[174:177], v[96:99]
	v_mfma_f32_16x16x32_bf16 v[88:91], v[210:213], v[174:177], v[88:91]
	v_mfma_f32_16x16x32_bf16 v[80:83], v[202:205], v[182:185], v[80:83]
	v_mfma_f32_16x16x32_bf16 v[72:75], v[210:213], v[182:185], v[72:75]
	v_mfma_f32_16x16x32_bf16 v[68:71], v[202:205], v[190:193], v[68:71]
	v_mfma_f32_16x16x32_bf16 v[64:67], v[210:213], v[190:193], v[64:67]
	s_mov_b32 m0, s43
	s_mov_b64 s[0:1], 0x80
	v_lshl_add_u64 v[198:199], v[216:217], 0, s[0:1]
	s_barrier
	s_setprio 0
	ds_read_b128 v[162:165], v144 offset:49152
	ds_read_b128 v[166:169], v144 offset:50176
	ds_read_b128 v[170:173], v144 offset:51200
	ds_read_b128 v[174:177], v144 offset:52224
	ds_read_b128 v[178:181], v144 offset:53248
	ds_read_b128 v[182:185], v144 offset:54272
	ds_read_b128 v[186:189], v144 offset:55296
	ds_read_b128 v[190:193], v144 offset:56320
	global_load_lds_dwordx4 v[198:199], off
	v_lshl_add_u64 v[198:199], v[218:219], 0, s[0:1]
	s_mov_b32 m0, s44
	s_nop 0
	global_load_lds_dwordx4 v[198:199], off
	s_setprio 1
	s_barrier
; #define PG8_STAGE(bufoff, gbase, voff) do { _Pragma("unroll") for (int _i = 0; _i < 2; ++_i) \
;         __builtin_amdgcn_global_load_lds((const unsigned*)((const char*)(gbase) + (voff)[_i]), (LAS unsigned*)(lds + (bufoff) + ldsw + _i * 8192), 16, 0, 0); } while (0)
; #define PG8_LDA(dst, b, h) do { _Pragma("unroll") for (int m = 0; m < 4; ++m) _Pragma("unroll") for (int k = 0; k < 2; ++k) dst[m][k] = *(const LAS bf16x8*)(lds + PG8_SA(b, h) + aoff + m * 2048 + k * 1024); } while (0)
; #define PG8_LDB(dst, b, h) do { _Pragma("unroll") for (int n = 0; n < 2; ++n) _Pragma("unroll") for (int k = 0; k < 2; ++k) dst[n][k] = *(const LAS bf16x8*)(lds + PG8_SB(b, h) + boff + n * 2048 + k * 1024); } while (0)
; #define PG8_MMA(ai, bj, At, Bt) do { __builtin_amdgcn_s_setprio(1); _Pragma("unroll") for (int m = 0; m < 4; ++m) _Pragma("unroll") for (int n = 0; n < 2; ++n) _Pragma("unroll") for (int k = 0; k < 2; ++k) \
;         acc[ai][bj][m][n] = __builtin_amdgcn_mfma_f32_16x16x32_bf16(Bt[n][k], At[m][k], acc[ai][bj][m][n], 0, 0, 0); __builtin_amdgcn_s_setprio(0); } while (0)
; #define PG8_WAIT_V(n) asm volatile("s_waitcnt vmcnt(" #n ")" ::: "memory")
; #define PG8_WAIT_L(n) asm volatile("s_waitcnt lgkmcnt(" #n ")" ::: "memory")
; #define PG8_BAR __builtin_amdgcn_s_barrier()
; #define PG8_SCHED __builtin_amdgcn_sched_barrier(0)
; template <class Epi, class Sched>
; __device__ __forceinline__ void gemm_phase(LAS unsigned char* lds, const Gemm g, const Sched& S, const Epi& E) {
;     ...
;             PG8_LDB(B0, 0, 0); PG8_SCHED; PG8_LDA(At, 0, 0); PG8_STAGE(PG8_SA(1, 1), a1 + hstep, voffA);
;             PG8_WAIT_L(8); PG8_BAR; PG8_WAIT_L(0); PG8_MMA(0, 0, At, B0); PG8_BAR; PG8_SCHED;
;             PG8_LDB(B1, 0, 1); PG8_STAGE(PG8_SB(0, 0), b2, voffB);
;             PG8_BAR; PG8_WAIT_L(0); PG8_MMA(0, 1, At, B1); PG8_BAR;
;     ...
;             PG8_BAR; PG8_WAIT_L(0); PG8_MMA(1, 0, At, B0); PG8_BAR; PG8_SCHED;
;             PG8_STAGE(PG8_SB(1, 1), b3 + hstep, voffB);
;             PG8_WAIT_V(6); PG8_BAR; PG8_MMA(1, 1, At, B1); PG8_BAR;
	s_waitcnt lgkmcnt(0)
	v_mfma_f32_16x16x32_bf16 v[60:63], v[146:149], v[162:165], v[60:63]
	v_mfma_f32_16x16x32_bf16 v[56:59], v[154:157], v[162:165], v[56:59]
	v_mfma_f32_16x16x32_bf16 v[52:55], v[146:149], v[170:173], v[52:55]
	v_mfma_f32_16x16x32_bf16 v[44:47], v[154:157], v[170:173], v[44:47]
	v_mfma_f32_16x16x32_bf16 v[36:39], v[146:149], v[178:181], v[36:39]
	v_mfma_f32_16x16x32_bf16 v[28:31], v[154:157], v[178:181], v[28:31]
	v_mfma_f32_16x16x32_bf16 v[20:23], v[146:149], v[186:189], v[20:23]
	v_mfma_f32_16x16x32_bf16 v[12:15], v[154:157], v[186:189], v[12:15]
	v_mfma_f32_16x16x32_bf16 v[60:63], v[150:153], v[166:169], v[60:63]
	v_mfma_f32_16x16x32_bf16 v[56:59], v[158:161], v[166:169], v[56:59]
	v_mfma_f32_16x16x32_bf16 v[52:55], v[150:153], v[174:177], v[52:55]
	v_mfma_f32_16x16x32_bf16 v[44:47], v[158:161], v[174:177], v[44:47]
	v_mfma_f32_16x16x32_bf16 v[36:39], v[150:153], v[182:185], v[36:39]
	v_mfma_f32_16x16x32_bf16 v[28:31], v[158:161], v[182:185], v[28:31]
	v_mfma_f32_16x16x32_bf16 v[20:23], v[150:153], v[190:193], v[20:23]
	v_mfma_f32_16x16x32_bf16 v[12:15], v[158:161], v[190:193], v[12:15]
	s_barrier
	s_setprio 0
	s_add_u32 s24, s24, 0x40080
	s_addc_u32 s25, s25, 0
	s_add_i32 s26, s26, s34
	s_mov_b32 m0, s26
	s_nop 0
	global_load_lds_dwordx4 v130, s[24:25]
	s_add_i32 m0, s26, 0x2000
	s_nop 0
	global_load_lds_dwordx4 v134, s[24:25]
	s_waitcnt vmcnt(8)
	s_setprio 1
	s_barrier
	v_mfma_f32_16x16x32_bf16 v[48:51], v[194:197], v[162:165], v[48:51]
	v_mfma_f32_16x16x32_bf16 v[40:43], v[206:209], v[162:165], v[40:43]
	v_mfma_f32_16x16x32_bf16 v[32:35], v[194:197], v[170:173], v[32:35]
	v_mfma_f32_16x16x32_bf16 v[24:27], v[206:209], v[170:173], v[24:27]
	v_mfma_f32_16x16x32_bf16 v[16:19], v[194:197], v[178:181], v[16:19]
	v_mfma_f32_16x16x32_bf16 v[8:11], v[206:209], v[178:181], v[8:11]
	v_mfma_f32_16x16x32_bf16 v[4:7], v[194:197], v[186:189], v[4:7]
	v_mfma_f32_16x16x32_bf16 v[0:3], v[206:209], v[186:189], v[0:3]
	v_mfma_f32_16x16x32_bf16 v[48:51], v[202:205], v[166:169], v[48:51]
	v_mfma_f32_16x16x32_bf16 v[40:43], v[210:213], v[166:169], v[40:43]
	v_mfma_f32_16x16x32_bf16 v[32:35], v[202:205], v[174:177], v[32:35]
	v_mfma_f32_16x16x32_bf16 v[24:27], v[210:213], v[174:177], v[24:27]
	v_mfma_f32_16x16x32_bf16 v[16:19], v[202:205], v[182:185], v[16:19]
	v_mfma_f32_16x16x32_bf16 v[8:11], v[210:213], v[182:185], v[8:11]
	v_mfma_f32_16x16x32_bf16 v[4:7], v[202:205], v[190:193], v[4:7]
	v_mfma_f32_16x16x32_bf16 v[0:3], v[210:213], v[190:193], v[0:3]
	s_add_i32 s58, s58, 2
	s_add_u32 s22, s22, 0x100
	s_addc_u32 s23, s23, 0
	s_add_u32 s56, s56, 0x100
	s_addc_u32 s57, s57, 0
	s_cmp_gt_u32 s58, 13
	s_barrier
	s_setprio 0
.LBB0_713:
	ds_read_b128 v[146:149], v143
	ds_read_b128 v[150:153], v143 offset:1024
	ds_read_b128 v[154:157], v143 offset:2048
	ds_read_b128 v[158:161], v143 offset:3072
	s_add_u32 s24, s22, 0xfffc0080
	s_addc_u32 s25, s23, -1
	s_cmp_eq_u32 s58, 12
	s_cselect_b32 s27, s15, s25
	s_cselect_b32 s26, s54, s24
	s_cselect_b32 s25, s13, s57
	s_cselect_b32 s24, s55, s56
	s_add_i32 m0, s21, 0xc000
	ds_read_b128 v[162:165], v144
	ds_read_b128 v[166:169], v144 offset:1024
	ds_read_b128 v[170:173], v144 offset:2048
	ds_read_b128 v[174:177], v144 offset:3072
	ds_read_b128 v[178:181], v144 offset:4096
	ds_read_b128 v[182:185], v144 offset:5120
	ds_read_b128 v[186:189], v144 offset:6144
	ds_read_b128 v[190:193], v144 offset:7168
	global_load_lds_dwordx4 v136, s[22:23]
	s_add_i32 m0, s21, 0xe000
	s_nop 0
	global_load_lds_dwordx4 v138, s[22:23]
	s_waitcnt lgkmcnt(8)
	s_waitcnt vmcnt(8)
	s_setprio 1
	s_barrier
	s_waitcnt lgkmcnt(0)
	v_mfma_f32_16x16x32_bf16 v[124:127], v[146:149], v[162:165], v[124:127]
	v_mfma_f32_16x16x32_bf16 v[120:123], v[154:157], v[162:165], v[120:123]
	v_mfma_f32_16x16x32_bf16 v[116:119], v[146:149], v[170:173], v[116:119]
	v_mfma_f32_16x16x32_bf16 v[108:111], v[154:157], v[170:173], v[108:111]
	v_mfma_f32_16x16x32_bf16 v[100:103], v[146:149], v[178:181], v[100:103]
	v_mfma_f32_16x16x32_bf16 v[92:95], v[154:157], v[178:181], v[92:95]
	v_mfma_f32_16x16x32_bf16 v[84:87], v[146:149], v[186:189], v[84:87]
	v_mfma_f32_16x16x32_bf16 v[76:79], v[154:157], v[186:189], v[76:79]
	v_mfma_f32_16x16x32_bf16 v[124:127], v[150:153], v[166:169], v[124:127]
	v_mfma_f32_16x16x32_bf16 v[120:123], v[158:161], v[166:169], v[120:123]
	v_mfma_f32_16x16x32_bf16 v[116:119], v[150:153], v[174:177], v[116:119]
	v_mfma_f32_16x16x32_bf16 v[108:111], v[158:161], v[174:177], v[108:111]
	v_mfma_f32_16x16x32_bf16 v[100:103], v[150:153], v[182:185], v[100:103]
	v_mfma_f32_16x16x32_bf16 v[92:95], v[158:161], v[182:185], v[92:95]
	v_mfma_f32_16x16x32_bf16 v[84:87], v[150:153], v[190:193], v[84:87]
	v_mfma_f32_16x16x32_bf16 v[76:79], v[158:161], v[190:193], v[76:79]
	s_barrier
	s_setprio 0
	s_add_i32 s59, s46, s34
	s_mov_b32 m0, s59
	ds_read_b128 v[194:197], v145
	ds_read_b128 v[202:205], v145 offset:1024
	ds_read_b128 v[206:209], v145 offset:2048
	ds_read_b128 v[210:213], v145 offset:3072
	global_load_lds_dwordx4 v130, s[24:25]
	s_add_i32 m0, s59, 0x2000
	s_nop 0
	global_load_lds_dwordx4 v134, s[24:25]
	s_waitcnt vmcnt(8)
	s_setprio 1
	s_barrier
; #define PG8_STAGE(bufoff, gbase, voff) do { _Pragma("unroll") for (int _i = 0; _i < 2; ++_i) \
;         __builtin_amdgcn_global_load_lds((const unsigned*)((const char*)(gbase) + (voff)[_i]), (LAS unsigned*)(lds + (bufoff) + ldsw + _i * 8192), 16, 0, 0); } while (0)
; #define PG8_LDA(dst, b, h) do { _Pragma("unroll") for (int m = 0; m < 4; ++m) _Pragma("unroll") for (int k = 0; k < 2; ++k) dst[m][k] = *(const LAS bf16x8*)(lds + PG8_SA(b, h) + aoff + m * 2048 + k * 1024); } while (0)
; #define PG8_LDB(dst, b, h) do { _Pragma("unroll") for (int n = 0; n < 2; ++n) _Pragma("unroll") for (int k = 0; k < 2; ++k) dst[n][k] = *(const LAS bf16x8*)(lds + PG8_SB(b, h) + boff + n * 2048 + k * 1024); } while (0)
; #define PG8_MMA(ai, bj, At, Bt) do { __builtin_amdgcn_s_setprio(1); _Pragma("unroll") for (int m = 0; m < 4; ++m) _Pragma("unroll") for (int n = 0; n < 2; ++n) _Pragma("unroll") for (int k = 0; k < 2; ++k) \
;         acc[ai][bj][m][n] = __builtin_amdgcn_mfma_f32_16x16x32_bf16(Bt[n][k], At[m][k], acc[ai][bj][m][n], 0, 0, 0); __builtin_amdgcn_s_setprio(0); } while (0)
; #define PG8_WAIT_V(n) asm volatile("s_waitcnt vmcnt(" #n ")" ::: "memory")
; #define PG8_WAIT_L(n) asm volatile("s_waitcnt lgkmcnt(" #n ")" ::: "memory")
; #define PG8_BAR __builtin_amdgcn_s_barrier()
; #define PG8_SCHED __builtin_amdgcn_sched_barrier(0)
; template <class Epi, class Sched>
; __device__ __forceinline__ void gemm_phase(LAS unsigned char* lds, const Gemm g, const Sched& S, const Epi& E) {
;     ...
;             PG8_BAR; PG8_WAIT_L(0); PG8_MMA(0, 1, At, B1); PG8_BAR;
;             PG8_LDA(At, 0, 1); PG8_STAGE(PG8_SA(0, 0), a2, voffA);
;             PG8_BAR; PG8_WAIT_L(0); PG8_MMA(1, 0, At, B0); PG8_BAR; PG8_SCHED;
;             PG8_STAGE(PG8_SB(0, 1), b2 + hstep, voffB);
;             PG8_WAIT_V(6); PG8_BAR; PG8_MMA(1, 1, At, B1); PG8_BAR;
;             PG8_LDB(B0, 1, 0); PG8_SCHED; PG8_LDA(At, 1, 0); PG8_STAGE(PG8_SA(0, 1), a2 + hstep, voffA);
;             PG8_WAIT_L(8); PG8_BAR; PG8_WAIT_L(0); PG8_MMA(0, 0, At, B0); PG8_BAR; PG8_SCHED;
	s_waitcnt lgkmcnt(0)
	v_mfma_f32_16x16x32_bf16 v[112:115], v[194:197], v[162:165], v[112:115]
	v_mfma_f32_16x16x32_bf16 v[104:107], v[206:209], v[162:165], v[104:107]
	v_mfma_f32_16x16x32_bf16 v[96:99], v[194:197], v[170:173], v[96:99]
	v_mfma_f32_16x16x32_bf16 v[88:91], v[206:209], v[170:173], v[88:91]
	v_mfma_f32_16x16x32_bf16 v[80:83], v[194:197], v[178:181], v[80:83]
	v_mfma_f32_16x16x32_bf16 v[72:75], v[206:209], v[178:181], v[72:75]
	v_mfma_f32_16x16x32_bf16 v[68:71], v[194:197], v[186:189], v[68:71]
	v_mfma_f32_16x16x32_bf16 v[64:67], v[206:209], v[186:189], v[64:67]
	v_mfma_f32_16x16x32_bf16 v[112:115], v[202:205], v[166:169], v[112:115]
	v_mfma_f32_16x16x32_bf16 v[104:107], v[210:213], v[166:169], v[104:107]
	v_mfma_f32_16x16x32_bf16 v[96:99], v[202:205], v[174:177], v[96:99]
	v_mfma_f32_16x16x32_bf16 v[88:91], v[210:213], v[174:177], v[88:91]
	v_mfma_f32_16x16x32_bf16 v[80:83], v[202:205], v[182:185], v[80:83]
	v_mfma_f32_16x16x32_bf16 v[72:75], v[210:213], v[182:185], v[72:75]
	v_mfma_f32_16x16x32_bf16 v[68:71], v[202:205], v[190:193], v[68:71]
	v_mfma_f32_16x16x32_bf16 v[64:67], v[210:213], v[190:193], v[64:67]
	s_mov_b32 m0, s21
	v_lshl_add_u64 v[216:217], s[26:27], 0, v[128:129]
	s_barrier
	s_setprio 0
	ds_read_b128 v[162:165], v144 offset:16384
	ds_read_b128 v[166:169], v144 offset:17408
	ds_read_b128 v[170:173], v144 offset:18432
	ds_read_b128 v[174:177], v144 offset:19456
	ds_read_b128 v[178:181], v144 offset:20480
	ds_read_b128 v[182:185], v144 offset:21504
	ds_read_b128 v[186:189], v144 offset:22528
	ds_read_b128 v[190:193], v144 offset:23552
	global_load_lds_dwordx4 v128, s[26:27]
	v_lshl_add_u64 v[218:219], s[26:27], 0, v[132:133]
	s_mov_b32 m0, s35
	s_nop 0
	global_load_lds_dwordx4 v132, s[26:27]
	s_setprio 1
	s_barrier
	s_waitcnt lgkmcnt(0)
	v_mfma_f32_16x16x32_bf16 v[60:63], v[146:149], v[162:165], v[60:63]
	v_mfma_f32_16x16x32_bf16 v[56:59], v[154:157], v[162:165], v[56:59]
	v_mfma_f32_16x16x32_bf16 v[52:55], v[146:149], v[170:173], v[52:55]
	v_mfma_f32_16x16x32_bf16 v[44:47], v[154:157], v[170:173], v[44:47]
	v_mfma_f32_16x16x32_bf16 v[36:39], v[146:149], v[178:181], v[36:39]
	v_mfma_f32_16x16x32_bf16 v[28:31], v[154:157], v[178:181], v[28:31]
	v_mfma_f32_16x16x32_bf16 v[20:23], v[146:149], v[186:189], v[20:23]
	v_mfma_f32_16x16x32_bf16 v[12:15], v[154:157], v[186:189], v[12:15]
	v_mfma_f32_16x16x32_bf16 v[60:63], v[150:153], v[166:169], v[60:63]
	v_mfma_f32_16x16x32_bf16 v[56:59], v[158:161], v[166:169], v[56:59]
	v_mfma_f32_16x16x32_bf16 v[52:55], v[150:153], v[174:177], v[52:55]
	v_mfma_f32_16x16x32_bf16 v[44:47], v[158:161], v[174:177], v[44:47]
	v_mfma_f32_16x16x32_bf16 v[36:39], v[150:153], v[182:185], v[36:39]
	v_mfma_f32_16x16x32_bf16 v[28:31], v[158:161], v[182:185], v[28:31]
	v_mfma_f32_16x16x32_bf16 v[20:23], v[150:153], v[190:193], v[20:23]
	v_mfma_f32_16x16x32_bf16 v[12:15], v[158:161], v[190:193], v[12:15]
	s_barrier
	s_setprio 0
	s_add_u32 s60, s24, 0x40000
	s_addc_u32 s61, s25, 0
	s_add_i32 s59, s47, s34
	s_mov_b32 m0, s59
	s_nop 0
	global_load_lds_dwordx4 v130, s[60:61]
	s_add_i32 m0, s59, 0x2000
	s_nop 0
	global_load_lds_dwordx4 v134, s[60:61]
	s_add_u32 s26, s26, 0x40000
	s_addc_u32 s27, s27, 0
	s_mov_b32 m0, s36
	s_nop 0
	global_load_lds_dwordx4 v128, s[26:27]
	s_mov_b32 m0, s37
	s_nop 0
	global_load_lds_dwordx4 v132, s[26:27]
	s_waitcnt vmcnt(10)
	s_setprio 1
	s_barrier
	v_mfma_f32_16x16x32_bf16 v[48:51], v[194:197], v[162:165], v[48:51]
	v_mfma_f32_16x16x32_bf16 v[40:43], v[206:209], v[162:165], v[40:43]
	v_mfma_f32_16x16x32_bf16 v[32:35], v[194:197], v[170:173], v[32:35]
	v_mfma_f32_16x16x32_bf16 v[24:27], v[206:209], v[170:173], v[24:27]
	v_mfma_f32_16x16x32_bf16 v[16:19], v[194:197], v[178:181], v[16:19]
	v_mfma_f32_16x16x32_bf16 v[8:11], v[206:209], v[178:181], v[8:11]
	v_mfma_f32_16x16x32_bf16 v[4:7], v[194:197], v[186:189], v[4:7]
	v_mfma_f32_16x16x32_bf16 v[0:3], v[206:209], v[186:189], v[0:3]
	v_mfma_f32_16x16x32_bf16 v[48:51], v[202:205], v[166:169], v[48:51]
	v_mfma_f32_16x16x32_bf16 v[40:43], v[210:213], v[166:169], v[40:43]
	v_mfma_f32_16x16x32_bf16 v[32:35], v[202:205], v[174:177], v[32:35]
	v_mfma_f32_16x16x32_bf16 v[24:27], v[210:213], v[174:177], v[24:27]
	v_mfma_f32_16x16x32_bf16 v[16:19], v[202:205], v[182:185], v[16:19]
	v_mfma_f32_16x16x32_bf16 v[8:11], v[210:213], v[182:185], v[8:11]
	v_mfma_f32_16x16x32_bf16 v[4:7], v[202:205], v[190:193], v[4:7]
	v_mfma_f32_16x16x32_bf16 v[0:3], v[210:213], v[190:193], v[0:3]
	s_add_i32 s59, 0, 0x18000
	v_add_u32_e32 v158, s59, v142
	s_barrier
	s_setprio 0
	ds_read_b128 v[146:149], v158
	ds_read_b128 v[150:153], v158 offset:1024
	ds_read_b128 v[154:157], v158 offset:2048
	ds_read_b128 v[158:161], v158 offset:3072
	ds_read_b128 v[162:165], v144 offset:32768
	ds_read_b128 v[166:169], v144 offset:33792
	ds_read_b128 v[170:173], v144 offset:34816
	ds_read_b128 v[174:177], v144 offset:35840
	ds_read_b128 v[178:181], v144 offset:36864
	ds_read_b128 v[182:185], v144 offset:37888
	ds_read_b128 v[186:189], v144 offset:38912
	ds_read_b128 v[190:193], v144 offset:39936
	s_waitcnt lgkmcnt(8)
	s_waitcnt vmcnt(8)
	s_setprio 1
	s_barrier
; #define PG8_STAGE(bufoff, gbase, voff) do { _Pragma("unroll") for (int _i = 0; _i < 2; ++_i) \
;         __builtin_amdgcn_global_load_lds((const unsigned*)((const char*)(gbase) + (voff)[_i]), (LAS unsigned*)(lds + (bufoff) + ldsw + _i * 8192), 16, 0, 0); } while (0)
; #define PG8_LDA(dst, b, h) do { _Pragma("unroll") for (int m = 0; m < 4; ++m) _Pragma("unroll") for (int k = 0; k < 2; ++k) dst[m][k] = *(const LAS bf16x8*)(lds + PG8_SA(b, h) + aoff + m * 2048 + k * 1024); } while (0)
; #define PG8_LDB(dst, b, h) do { _Pragma("unroll") for (int n = 0; n < 2; ++n) _Pragma("unroll") for (int k = 0; k < 2; ++k) dst[n][k] = *(const LAS bf16x8*)(lds + PG8_SB(b, h) + boff + n * 2048 + k * 1024); } while (0)
; #define PG8_MMA(ai, bj, At, Bt) do { __builtin_amdgcn_s_setprio(1); _Pragma("unroll") for (int m = 0; m < 4; ++m) _Pragma("unroll") for (int n = 0; n < 2; ++n) _Pragma("unroll") for (int k = 0; k < 2; ++k) \
;         acc[ai][bj][m][n] = __builtin_amdgcn_mfma_f32_16x16x32_bf16(Bt[n][k], At[m][k], acc[ai][bj][m][n], 0, 0, 0); __builtin_amdgcn_s_setprio(0); } while (0)
; #define PG8_WAIT_L(n) asm volatile("s_waitcnt lgkmcnt(" #n ")" ::: "memory")
; #define PG8_BAR __builtin_amdgcn_s_barrier()
; #define PG8_SCHED __builtin_amdgcn_sched_barrier(0)
; template <class Epi, class Sched>
; __device__ __forceinline__ void gemm_phase(LAS unsigned char* lds, const Gemm g, const Sched& S, const Epi& E) {
;     ...
;             PG8_WAIT_L(8); PG8_BAR; PG8_WAIT_L(0); PG8_MMA(0, 0, At, B0); PG8_BAR; PG8_SCHED;
;             PG8_LDB(B1, 1, 1); PG8_STAGE(PG8_SB(1, 0), b3, voffB);
;             PG8_BAR; PG8_WAIT_L(0); PG8_MMA(0, 1, At, B1); PG8_BAR;
;             PG8_LDA(At, 1, 1); PG8_STAGE(PG8_SA(1, 0), a3, voffA);
;             PG8_BAR; PG8_WAIT_L(0); PG8_MMA(1, 0, At, B0); PG8_BAR; PG8_SCHED;
;             PG8_STAGE(PG8_SB(1, 1), b3 + hstep, voffB);
	s_waitcnt lgkmcnt(0)
	v_mfma_f32_16x16x32_bf16 v[124:127], v[146:149], v[162:165], v[124:127]
	v_mfma_f32_16x16x32_bf16 v[120:123], v[154:157], v[162:165], v[120:123]
	v_mfma_f32_16x16x32_bf16 v[116:119], v[146:149], v[170:173], v[116:119]
	v_mfma_f32_16x16x32_bf16 v[108:111], v[154:157], v[170:173], v[108:111]
	v_mfma_f32_16x16x32_bf16 v[100:103], v[146:149], v[178:181], v[100:103]
	v_mfma_f32_16x16x32_bf16 v[92:95], v[154:157], v[178:181], v[92:95]
	v_mfma_f32_16x16x32_bf16 v[84:87], v[146:149], v[186:189], v[84:87]
	v_mfma_f32_16x16x32_bf16 v[76:79], v[154:157], v[186:189], v[76:79]
	v_mfma_f32_16x16x32_bf16 v[124:127], v[150:153], v[166:169], v[124:127]
	v_mfma_f32_16x16x32_bf16 v[120:123], v[158:161], v[166:169], v[120:123]
	v_mfma_f32_16x16x32_bf16 v[116:119], v[150:153], v[174:177], v[116:119]
	v_mfma_f32_16x16x32_bf16 v[108:111], v[158:161], v[174:177], v[108:111]
	v_mfma_f32_16x16x32_bf16 v[100:103], v[150:153], v[182:185], v[100:103]
	v_mfma_f32_16x16x32_bf16 v[92:95], v[158:161], v[182:185], v[92:95]
	v_mfma_f32_16x16x32_bf16 v[84:87], v[150:153], v[190:193], v[84:87]
	v_mfma_f32_16x16x32_bf16 v[76:79], v[158:161], v[190:193], v[76:79]
	s_barrier
	s_setprio 0
	s_add_i32 s26, 0, 0x1c000
	s_add_i32 s27, s59, s34
	v_add_u32_e32 v210, s26, v142
	s_add_u32 s0, s24, 0x80
	s_addc_u32 s1, s25, 0
	s_mov_b32 m0, s27
	ds_read_b128 v[194:197], v210
	ds_read_b128 v[202:205], v210 offset:1024
	ds_read_b128 v[206:209], v210 offset:2048
	ds_read_b128 v[210:213], v210 offset:3072
	global_load_lds_dwordx4 v130, s[0:1]
	s_add_i32 m0, s27, 0x2000
	s_nop 0
	global_load_lds_dwordx4 v134, s[0:1]
	s_waitcnt vmcnt(8)
	s_setprio 1
	s_barrier
	s_waitcnt lgkmcnt(0)
	v_mfma_f32_16x16x32_bf16 v[112:115], v[194:197], v[162:165], v[112:115]
	v_mfma_f32_16x16x32_bf16 v[104:107], v[206:209], v[162:165], v[104:107]
	v_mfma_f32_16x16x32_bf16 v[96:99], v[194:197], v[170:173], v[96:99]
	v_mfma_f32_16x16x32_bf16 v[88:91], v[206:209], v[170:173], v[88:91]
	v_mfma_f32_16x16x32_bf16 v[80:83], v[194:197], v[178:181], v[80:83]
	v_mfma_f32_16x16x32_bf16 v[72:75], v[206:209], v[178:181], v[72:75]
	v_mfma_f32_16x16x32_bf16 v[68:71], v[194:197], v[186:189], v[68:71]
	v_mfma_f32_16x16x32_bf16 v[64:67], v[206:209], v[186:189], v[64:67]
	v_mfma_f32_16x16x32_bf16 v[112:115], v[202:205], v[166:169], v[112:115]
	v_mfma_f32_16x16x32_bf16 v[104:107], v[210:213], v[166:169], v[104:107]
	v_mfma_f32_16x16x32_bf16 v[96:99], v[202:205], v[174:177], v[96:99]
	v_mfma_f32_16x16x32_bf16 v[88:91], v[210:213], v[174:177], v[88:91]
	v_mfma_f32_16x16x32_bf16 v[80:83], v[202:205], v[182:185], v[80:83]
	v_mfma_f32_16x16x32_bf16 v[72:75], v[210:213], v[182:185], v[72:75]
	v_mfma_f32_16x16x32_bf16 v[68:71], v[202:205], v[190:193], v[68:71]
	v_mfma_f32_16x16x32_bf16 v[64:67], v[210:213], v[190:193], v[64:67]
	s_mov_b32 m0, s43
	s_mov_b64 s[0:1], 0x80
	v_lshl_add_u64 v[198:199], v[216:217], 0, s[0:1]
	s_barrier
	s_setprio 0
	ds_read_b128 v[162:165], v144 offset:49152
	ds_read_b128 v[166:169], v144 offset:50176
	ds_read_b128 v[170:173], v144 offset:51200
	ds_read_b128 v[174:177], v144 offset:52224
	ds_read_b128 v[178:181], v144 offset:53248
	ds_read_b128 v[182:185], v144 offset:54272
	ds_read_b128 v[186:189], v144 offset:55296
	ds_read_b128 v[190:193], v144 offset:56320
	global_load_lds_dwordx4 v[198:199], off
	v_lshl_add_u64 v[198:199], v[218:219], 0, s[0:1]
	s_mov_b32 m0, s44
	s_nop 0
	global_load_lds_dwordx4 v[198:199], off
	s_setprio 1
	s_barrier
	s_waitcnt lgkmcnt(0)
	v_mfma_f32_16x16x32_bf16 v[60:63], v[146:149], v[162:165], v[60:63]
	v_mfma_f32_16x16x32_bf16 v[56:59], v[154:157], v[162:165], v[56:59]
	v_mfma_f32_16x16x32_bf16 v[52:55], v[146:149], v[170:173], v[52:55]
	v_mfma_f32_16x16x32_bf16 v[44:47], v[154:157], v[170:173], v[44:47]
	v_mfma_f32_16x16x32_bf16 v[36:39], v[146:149], v[178:181], v[36:39]
	v_mfma_f32_16x16x32_bf16 v[28:31], v[154:157], v[178:181], v[28:31]
	v_mfma_f32_16x16x32_bf16 v[20:23], v[146:149], v[186:189], v[20:23]
	v_mfma_f32_16x16x32_bf16 v[12:15], v[154:157], v[186:189], v[12:15]
	v_mfma_f32_16x16x32_bf16 v[60:63], v[150:153], v[166:169], v[60:63]
	v_mfma_f32_16x16x32_bf16 v[56:59], v[158:161], v[166:169], v[56:59]
	v_mfma_f32_16x16x32_bf16 v[52:55], v[150:153], v[174:177], v[52:55]
	v_mfma_f32_16x16x32_bf16 v[44:47], v[158:161], v[174:177], v[44:47]
	v_mfma_f32_16x16x32_bf16 v[36:39], v[150:153], v[182:185], v[36:39]
	v_mfma_f32_16x16x32_bf16 v[28:31], v[158:161], v[182:185], v[28:31]
	v_mfma_f32_16x16x32_bf16 v[20:23], v[150:153], v[190:193], v[20:23]
	v_mfma_f32_16x16x32_bf16 v[12:15], v[158:161], v[190:193], v[12:15]
	s_barrier
	s_setprio 0
	s_add_u32 s24, s24, 0x40080
	s_addc_u32 s25, s25, 0
	s_add_i32 s26, s26, s34
	s_mov_b32 m0, s26
	s_nop 0
	global_load_lds_dwordx4 v130, s[24:25]
	s_add_i32 m0, s26, 0x2000
	s_nop 0
	global_load_lds_dwordx4 v134, s[24:25]
	s_waitcnt vmcnt(8)
	s_setprio 1
	s_barrier
; __device__ __forceinline__ unsigned cvt_pk_bf16(float lo, float hi) { unsigned r; asm volatile("v_cvt_pk_bf16_f32 %0, %1, %2" : "=v"(r) : "v"(lo), "v"(hi)); return r; }
; #define PG8_MMA(ai, bj, At, Bt) do { __builtin_amdgcn_s_setprio(1); _Pragma("unroll") for (int m = 0; m < 4; ++m) _Pragma("unroll") for (int n = 0; n < 2; ++n) _Pragma("unroll") for (int k = 0; k < 2; ++k) \
;         acc[ai][bj][m][n] = __builtin_amdgcn_mfma_f32_16x16x32_bf16(Bt[n][k], At[m][k], acc[ai][bj][m][n], 0, 0, 0); __builtin_amdgcn_s_setprio(0); } while (0)
; #define PG8_WAIT_V(n) asm volatile("s_waitcnt vmcnt(" #n ")" ::: "memory")
; #define PG8_BAR __builtin_amdgcn_s_barrier()
; template <class Epi, class Sched>
; __device__ __forceinline__ void gemm_phase(LAS unsigned char* lds, const Gemm g, const Sched& S, const Epi& E) {
;     ...
;             PG8_WAIT_V(6); PG8_BAR; PG8_MMA(1, 1, At, B1); PG8_BAR;
;         }
;         E(acc, cur, wr, wc, fr, fq);
;         if (!has_next) break;
;     __device__ __forceinline__ void operator()(const AccT& acc, const Unit& u, int wr, int wc, int fr, int fq) const {
;     ...
;         const int rbase = u.pm * 256 + wr * 64 + fr;
;         const int tb = u.pn * 256 + wc * 32 + 8 * fq;
; #pragma unroll
;         for (int ai = 0; ai < 2; ++ai)
; #pragma unroll
;             for (int m = 0; m < 4; ++m) {
;                 const int r = rbase + ai * 128 + m * 16;
; #pragma unroll
;                 for (int bj = 0; bj < 2; ++bj) {
;                     const int t0 = tb + bj * 128;
;                     const f32x4 v0 = acc[ai][bj][m][0], v1 = acc[ai][bj][m][1];
;                     u32x4 w; w.x = cvt_pk_bf16(v0[0], v0[1]); w.y = cvt_pk_bf16(v0[2], v0[3]); w.z = cvt_pk_bf16(v1[0], v1[1]); w.w = cvt_pk_bf16(v1[2], v1[3]);
;                     *(u32x4*)(VT + (size_t)r * NT + t0) = w;
;                 }
	v_mfma_f32_16x16x32_bf16 v[48:51], v[194:197], v[162:165], v[48:51]
	v_mfma_f32_16x16x32_bf16 v[40:43], v[206:209], v[162:165], v[40:43]
	v_mfma_f32_16x16x32_bf16 v[32:35], v[194:197], v[170:173], v[32:35]
	v_mfma_f32_16x16x32_bf16 v[24:27], v[206:209], v[170:173], v[24:27]
	v_mfma_f32_16x16x32_bf16 v[16:19], v[194:197], v[178:181], v[16:19]
	v_mfma_f32_16x16x32_bf16 v[8:11], v[206:209], v[178:181], v[8:11]
	v_mfma_f32_16x16x32_bf16 v[4:7], v[194:197], v[186:189], v[4:7]
	v_mfma_f32_16x16x32_bf16 v[0:3], v[206:209], v[186:189], v[0:3]
	v_mfma_f32_16x16x32_bf16 v[48:51], v[202:205], v[166:169], v[48:51]
	v_mfma_f32_16x16x32_bf16 v[40:43], v[210:213], v[166:169], v[40:43]
	v_mfma_f32_16x16x32_bf16 v[32:35], v[202:205], v[174:177], v[32:35]
	v_mfma_f32_16x16x32_bf16 v[24:27], v[210:213], v[174:177], v[24:27]
	v_mfma_f32_16x16x32_bf16 v[16:19], v[202:205], v[182:185], v[16:19]
	v_mfma_f32_16x16x32_bf16 v[8:11], v[210:213], v[182:185], v[8:11]
	v_mfma_f32_16x16x32_bf16 v[4:7], v[202:205], v[190:193], v[4:7]
	v_mfma_f32_16x16x32_bf16 v[0:3], v[210:213], v[190:193], v[0:3]
	s_add_i32 s58, s58, 2
	s_add_u32 s22, s22, 0x100
	s_addc_u32 s23, s23, 0
	s_add_u32 s56, s56, 0x100
	s_addc_u32 s57, s57, 0
	s_cmp_gt_u32 s58, 13
	s_barrier
	s_setprio 0
	s_cbranch_scc0 .LBB0_713
	v_mov_b32_e32 v146, v140
	v_mov_b32_e32 v147, v141
	s_lshl_b32 s13, s20, 8
	s_add_i32 s13, s13, s41
	v_add_u32_e32 v146, s13, v146
	s_lshl_b32 s13, s53, 8
	s_or_b32 s13, s13, s42
	v_lshl_add_u32 v148, v147, 3, s13
	v_ashrrev_i32_e32 v147, 31, v146
	v_cvt_pk_bf16_f32 v124, v124, v125
	v_cvt_pk_bf16_f32 v125, v126, v127
	v_cvt_pk_bf16_f32 v126, v120, v121
	v_lshlrev_b64 v[120:121], 14, v[146:147]
	v_lshl_add_u64 v[120:121], s[62:63], 0, v[120:121]
	v_ashrrev_i32_e32 v149, 31, v148
	v_lshl_add_u64 v[120:121], v[148:149], 1, v[120:121]
	s_mov_b32 s13, 0x40000
	v_cvt_pk_bf16_f32 v127, v122, v123
	global_store_dwordx4 v[120:121], v[124:127], off
	v_cvt_pk_bf16_f32 v112, v112, v113
	v_cvt_pk_bf16_f32 v113, v114, v115
	v_cvt_pk_bf16_f32 v114, v104, v105
	v_cvt_pk_bf16_f32 v115, v106, v107
	global_store_dwordx4 v[120:121], v[112:115], off offset:256
	v_cvt_pk_bf16_f32 v104, v116, v117
	v_cvt_pk_bf16_f32 v105, v118, v119
	v_cvt_pk_bf16_f32 v106, v108, v109
	v_cvt_pk_bf16_f32 v107, v110, v111
	s_mov_b64 s[22:23], 0x40000
	v_add_co_u32_e32 v110, vcc, s13, v120
	v_lshl_add_u64 v[108:109], v[120:121], 0, s[22:23]
	s_nop 0
	v_addc_co_u32_e32 v111, vcc, 0, v121, vcc
	s_mov_b32 s13, 0x80000
	global_store_dwordx4 v[110:111], v[104:107], off
	v_cvt_pk_bf16_f32 v96, v96, v97
	v_cvt_pk_bf16_f32 v97, v98, v99
	v_cvt_pk_bf16_f32 v98, v88, v89
	v_cvt_pk_bf16_f32 v99, v90, v91
	global_store_dwordx4 v[108:109], v[96:99], off offset:256
	v_cvt_pk_bf16_f32 v88, v100, v101
	v_cvt_pk_bf16_f32 v89, v102, v103
	v_cvt_pk_bf16_f32 v90, v92, v93
	v_cvt_pk_bf16_f32 v91, v94, v95
	s_mov_b64 s[22:23], 0x80000
	v_add_co_u32_e32 v94, vcc, s13, v120
	v_lshl_add_u64 v[92:93], v[120:121], 0, s[22:23]
	s_nop 0
	v_addc_co_u32_e32 v95, vcc, 0, v121, vcc
	global_store_dwordx4 v[94:95], v[88:91], off
	v_cvt_pk_bf16_f32 v80, v80, v81
	v_cvt_pk_bf16_f32 v81, v82, v83
	v_cvt_pk_bf16_f32 v82, v72, v73
	v_cvt_pk_bf16_f32 v83, v74, v75
	global_store_dwordx4 v[92:93], v[80:83], off offset:256
	v_cvt_pk_bf16_f32 v72, v84, v85
	v_cvt_pk_bf16_f32 v73, v86, v87
	v_cvt_pk_bf16_f32 v74, v76, v77
	v_cvt_pk_bf16_f32 v75, v78, v79
	s_mov_b64 s[22:23], 0xc0000
	v_add_co_u32_e32 v78, vcc, s48, v120
	v_lshl_add_u64 v[76:77], v[120:121], 0, s[22:23]
	s_nop 0
	v_addc_co_u32_e32 v79, vcc, 0, v121, vcc
	global_store_dwordx4 v[78:79], v[72:75], off
	v_cvt_pk_bf16_f32 v68, v68, v69
	v_cvt_pk_bf16_f32 v69, v70, v71
	v_cvt_pk_bf16_f32 v70, v64, v65
	v_cvt_pk_bf16_f32 v71, v66, v67
	global_store_dwordx4 v[76:77], v[68:71], off offset:256
	v_cvt_pk_bf16_f32 v60, v60, v61
	v_cvt_pk_bf16_f32 v61, v62, v63
	v_cvt_pk_bf16_f32 v62, v56, v57
	v_cvt_pk_bf16_f32 v63, v58, v59
	v_add_co_u32_e32 v58, vcc, s49, v120
	v_lshl_add_u64 v[56:57], v[120:121], 0, s[2:3]
	s_nop 0
	v_addc_co_u32_e32 v59, vcc, 0, v121, vcc
	global_store_dwordx4 v[58:59], v[60:63], off
	v_cvt_pk_bf16_f32 v48, v48, v49
	v_cvt_pk_bf16_f32 v49, v50, v51
	v_cvt_pk_bf16_f32 v50, v40, v41
	v_cvt_pk_bf16_f32 v51, v42, v43
	global_store_dwordx4 v[56:57], v[48:51], off offset:256
	v_cvt_pk_bf16_f32 v40, v52, v53
	v_cvt_pk_bf16_f32 v41, v54, v55
	v_cvt_pk_bf16_f32 v42, v44, v45
	v_cvt_pk_bf16_f32 v43, v46, v47
	v_add_co_u32_e32 v46, vcc, s50, v120
	v_lshl_add_u64 v[44:45], v[120:121], 0, s[4:5]
	s_nop 0
	v_addc_co_u32_e32 v47, vcc, 0, v121, vcc
	global_store_dwordx4 v[46:47], v[40:43], off
	v_cvt_pk_bf16_f32 v32, v32, v33
	v_cvt_pk_bf16_f32 v33, v34, v35
	v_cvt_pk_bf16_f32 v34, v24, v25
	v_cvt_pk_bf16_f32 v35, v26, v27
	global_store_dwordx4 v[44:45], v[32:35], off offset:256
	v_cvt_pk_bf16_f32 v24, v36, v37
	v_cvt_pk_bf16_f32 v25, v38, v39
	v_cvt_pk_bf16_f32 v26, v28, v29
	v_cvt_pk_bf16_f32 v27, v30, v31
	v_add_co_u32_e32 v30, vcc, s51, v120
	v_lshl_add_u64 v[28:29], v[120:121], 0, s[6:7]
	s_nop 0
	v_addc_co_u32_e32 v31, vcc, 0, v121, vcc
	global_store_dwordx4 v[30:31], v[24:27], off
	v_cvt_pk_bf16_f32 v16, v16, v17
	v_cvt_pk_bf16_f32 v17, v18, v19
	v_cvt_pk_bf16_f32 v18, v8, v9
	v_cvt_pk_bf16_f32 v19, v10, v11
	global_store_dwordx4 v[28:29], v[16:19], off offset:256
	v_cvt_pk_bf16_f32 v8, v20, v21
	v_cvt_pk_bf16_f32 v9, v22, v23
	v_cvt_pk_bf16_f32 v10, v12, v13
	v_cvt_pk_bf16_f32 v11, v14, v15
	v_add_co_u32_e32 v14, vcc, s52, v120
	v_lshl_add_u64 v[12:13], v[120:121], 0, s[8:9]
	s_nop 0
	v_addc_co_u32_e32 v15, vcc, 0, v121, vcc
	s_and_b64 vcc, exec, s[10:11]
	s_mov_b32 s53, s12
	s_mov_b32 s20, s14
	s_mov_b64 s[24:25], s[18:19]
	s_mov_b64 s[22:23], s[16:17]
	global_store_dwordx4 v[14:15], v[8:11], off
	v_cvt_pk_bf16_f32 v4, v4, v5
	v_cvt_pk_bf16_f32 v5, v6, v7
	v_cvt_pk_bf16_f32 v6, v0, v1
	v_cvt_pk_bf16_f32 v7, v2, v3
	global_store_dwordx4 v[12:13], v[4:7], off offset:256
	s_cbranch_vccz .LBB0_706
	s_waitcnt vmcnt(0)
	s_cmpk_gt_u32 s31, 0xff
	s_cbranch_scc1 .LBB0_717
	s_barrier

; #define PG8_STAGE(bufoff, gbase, voff) do { _Pragma("unroll") for (int _i = 0; _i < 2; ++_i) \
;         __builtin_amdgcn_global_load_lds((const unsigned*)((const char*)(gbase) + (voff)[_i]), (LAS unsigned*)(lds + (bufoff) + ldsw + _i * 8192), 16, 0, 0); } while (0)
; #define PG8_LDA(dst, b, h) do { _Pragma("unroll") for (int m = 0; m < 4; ++m) _Pragma("unroll") for (int k = 0; k < 2; ++k) dst[m][k] = *(const LAS bf16x8*)(lds + PG8_SA(b, h) + aoff + m * 2048 + k * 1024); } while (0)
; #define PG8_LDB(dst, b, h) do { _Pragma("unroll") for (int n = 0; n < 2; ++n) _Pragma("unroll") for (int k = 0; k < 2; ++k) dst[n][k] = *(const LAS bf16x8*)(lds + PG8_SB(b, h) + boff + n * 2048 + k * 1024); } while (0)
; #define PG8_MMA(ai, bj, At, Bt) do { __builtin_amdgcn_s_setprio(1); _Pragma("unroll") for (int m = 0; m < 4; ++m) _Pragma("unroll") for (int n = 0; n < 2; ++n) _Pragma("unroll") for (int k = 0; k < 2; ++k) \
;         acc[ai][bj][m][n] = __builtin_amdgcn_mfma_f32_16x16x32_bf16(Bt[n][k], At[m][k], acc[ai][bj][m][n], 0, 0, 0); __builtin_amdgcn_s_setprio(0); } while (0)
; template <class Epi, class Sched>
; __device__ __forceinline__ void gemm_phase(LAS unsigned char* lds, const Gemm g, const Sched& S, const Epi& E) {
;     ...
;         const char* nA = has_next ? (const char*)g.A + (size_t)nxt.pm * tstep : cA; const char* nB = has_next ? (const char*)g.Bt + (size_t)nxt.pn * tstep : cB;
;         for (int t = 0; t < nt; t += 2) {
;             const bool last = (t == nt - 2);
;             const char* a1 = cA + (size_t)(t + 1) * kstep;
;             const char* a2 = last ? nA : cA + (size_t)(t + 2) * kstep; const char* b2 = last ? nB : cB + (size_t)(t + 2) * kstep;
;             const char* a3 = a2 + kstep; const char* b3 = b2 + kstep;
;             PG8_LDB(B0, 0, 0); PG8_SCHED; PG8_LDA(At, 0, 0); PG8_STAGE(PG8_SA(1, 1), a1 + hstep, voffA);
;             PG8_WAIT_L(8); PG8_BAR; PG8_WAIT_L(0); PG8_MMA(0, 0, At, B0); PG8_BAR; PG8_SCHED;
;             PG8_LDB(B1, 0, 1); PG8_STAGE(PG8_SB(0, 0), b2, voffB);
;             PG8_BAR; PG8_WAIT_L(0); PG8_MMA(0, 1, At, B1); PG8_BAR;
;             PG8_LDA(At, 0, 1); PG8_STAGE(PG8_SA(0, 0), a2, voffA);
;             PG8_BAR; PG8_WAIT_L(0); PG8_MMA(1, 0, At, B0); PG8_BAR; PG8_SCHED;
;             PG8_STAGE(PG8_SB(0, 1), b2 + hstep, voffB);
;             PG8_WAIT_V(6); PG8_BAR; PG8_MMA(1, 1, At, B1); PG8_BAR;
.LBB0_825:
	s_ashr_i32 s7, s6, 31
	v_cmp_lt_i64_e32 vcc, s[8:9], v[156:157]
	s_lshl_b64 s[8:9], s[6:7], 20
	s_add_u32 s8, s22, s8
	s_addc_u32 s9, s23, s9
	s_and_b64 s[10:11], vcc, exec
	s_cselect_b32 s7, s9, s15
	s_cselect_b32 s39, s8, s14
	s_ashr_i32 s5, s4, 31
	s_lshl_b64 s[10:11], s[4:5], 20
	s_add_u32 s10, s50, s10
	s_addc_u32 s11, s51, s11
	s_and_b64 s[18:19], vcc, exec
	s_cselect_b32 s5, s11, s17
	s_cselect_b32 s40, s10, s16
	s_add_u32 s14, s14, 0x80080
	s_addc_u32 s15, s15, 0
	s_add_u32 s41, s16, 0x100
	s_addc_u32 s42, s17, 0
	s_mov_b32 s43, -2
	ds_read_b128 v[128:131], v168
	ds_read_b128 v[132:135], v168 offset:1024
	ds_read_b128 v[136:139], v168 offset:2048
	ds_read_b128 v[140:143], v168 offset:3072
	s_add_u32 s16, s14, 0xfff80080
	s_addc_u32 s17, s15, -1
	s_cmp_eq_u32 s43, 28
	s_cselect_b32 s19, s7, s17
	s_cselect_b32 s18, s39, s16
	s_cselect_b32 s17, s5, s42
	s_cselect_b32 s16, s40, s41
	s_add_i32 m0, s13, 0xc000
	ds_read_b128 v[162:165], v169
	ds_read_b128 v[172:175], v169 offset:1024
	ds_read_b128 v[176:179], v169 offset:2048
	ds_read_b128 v[180:183], v169 offset:3072
	ds_read_b128 v[184:187], v169 offset:4096
	ds_read_b128 v[188:191], v169 offset:5120
	ds_read_b128 v[192:195], v169 offset:6144
	ds_read_b128 v[196:199], v169 offset:7168
	global_load_lds_dwordx4 v152, s[14:15]
	s_add_i32 m0, s13, 0xe000
	s_nop 0
	global_load_lds_dwordx4 v154, s[14:15]
	s_waitcnt lgkmcnt(8)
	s_waitcnt vmcnt(8)
	s_setprio 1
	s_barrier
	s_waitcnt lgkmcnt(0)
	v_mfma_f32_16x16x32_bf16 v[124:127], v[128:131], v[162:165], 0
	v_mfma_f32_16x16x32_bf16 v[120:123], v[136:139], v[162:165], 0
	v_mfma_f32_16x16x32_bf16 v[116:119], v[128:131], v[176:179], 0
	v_mfma_f32_16x16x32_bf16 v[112:115], v[136:139], v[176:179], 0
	v_mfma_f32_16x16x32_bf16 v[108:111], v[128:131], v[184:187], 0
	v_mfma_f32_16x16x32_bf16 v[100:103], v[136:139], v[184:187], 0
	v_mfma_f32_16x16x32_bf16 v[76:79], v[128:131], v[192:195], 0
	v_mfma_f32_16x16x32_bf16 v[72:75], v[136:139], v[192:195], 0
	v_mfma_f32_16x16x32_bf16 v[124:127], v[132:135], v[172:175], v[124:127]
	v_mfma_f32_16x16x32_bf16 v[120:123], v[140:143], v[172:175], v[120:123]
	v_mfma_f32_16x16x32_bf16 v[116:119], v[132:135], v[180:183], v[116:119]
	v_mfma_f32_16x16x32_bf16 v[112:115], v[140:143], v[180:183], v[112:115]
	v_mfma_f32_16x16x32_bf16 v[108:111], v[132:135], v[188:191], v[108:111]
	v_mfma_f32_16x16x32_bf16 v[100:103], v[140:143], v[188:191], v[100:103]
	v_mfma_f32_16x16x32_bf16 v[76:79], v[132:135], v[196:199], v[76:79]
	v_mfma_f32_16x16x32_bf16 v[72:75], v[140:143], v[196:199], v[72:75]
	s_barrier
	s_setprio 0
	s_add_i32 s44, s35, s24
	s_mov_b32 m0, s44
	ds_read_b128 v[202:205], v170
	ds_read_b128 v[206:209], v170 offset:1024
	ds_read_b128 v[210:213], v170 offset:2048
	ds_read_b128 v[214:217], v170 offset:3072
	global_load_lds_dwordx4 v146, s[16:17]
	s_add_i32 m0, s44, 0x2000
	s_nop 0
	global_load_lds_dwordx4 v150, s[16:17]
	s_waitcnt vmcnt(8)
	s_setprio 1
	s_barrier
	s_waitcnt lgkmcnt(0)
	v_mfma_f32_16x16x32_bf16 v[104:107], v[202:205], v[162:165], 0
	v_mfma_f32_16x16x32_bf16 v[96:99], v[210:213], v[162:165], 0
	v_mfma_f32_16x16x32_bf16 v[92:95], v[202:205], v[176:179], 0
	v_mfma_f32_16x16x32_bf16 v[88:91], v[210:213], v[176:179], 0
	v_mfma_f32_16x16x32_bf16 v[84:87], v[202:205], v[184:187], 0
	v_mfma_f32_16x16x32_bf16 v[80:83], v[210:213], v[184:187], 0
	v_mfma_f32_16x16x32_bf16 v[68:71], v[202:205], v[192:195], 0
	v_mfma_f32_16x16x32_bf16 v[64:67], v[210:213], v[192:195], 0
	v_mfma_f32_16x16x32_bf16 v[104:107], v[206:209], v[172:175], v[104:107]
	v_mfma_f32_16x16x32_bf16 v[96:99], v[214:217], v[172:175], v[96:99]
	v_mfma_f32_16x16x32_bf16 v[92:95], v[206:209], v[180:183], v[92:95]
	v_mfma_f32_16x16x32_bf16 v[88:91], v[214:217], v[180:183], v[88:91]
	v_mfma_f32_16x16x32_bf16 v[84:87], v[206:209], v[188:191], v[84:87]
	v_mfma_f32_16x16x32_bf16 v[80:83], v[214:217], v[188:191], v[80:83]
	v_mfma_f32_16x16x32_bf16 v[68:71], v[206:209], v[196:199], v[68:71]
	v_mfma_f32_16x16x32_bf16 v[64:67], v[214:217], v[196:199], v[64:67]
	s_mov_b32 m0, s13
	v_lshl_add_u64 v[222:223], s[18:19], 0, v[144:145]
	s_barrier
	s_setprio 0
	ds_read_b128 v[162:165], v169 offset:16384
	ds_read_b128 v[172:175], v169 offset:17408
	ds_read_b128 v[176:179], v169 offset:18432
	ds_read_b128 v[180:183], v169 offset:19456
	ds_read_b128 v[184:187], v169 offset:20480
	ds_read_b128 v[188:191], v169 offset:21504
	ds_read_b128 v[192:195], v169 offset:22528
	ds_read_b128 v[196:199], v169 offset:23552
	global_load_lds_dwordx4 v144, s[18:19]
	v_lshl_add_u64 v[224:225], s[18:19], 0, v[148:149]
	s_mov_b32 m0, s25
	s_nop 0
	global_load_lds_dwordx4 v148, s[18:19]
	s_setprio 1
	s_barrier
	s_waitcnt lgkmcnt(0)
	v_mfma_f32_16x16x32_bf16 v[60:63], v[128:131], v[162:165], 0
	v_mfma_f32_16x16x32_bf16 v[56:59], v[136:139], v[162:165], 0
	v_mfma_f32_16x16x32_bf16 v[48:51], v[128:131], v[176:179], 0
	v_mfma_f32_16x16x32_bf16 v[40:43], v[136:139], v[176:179], 0
	v_mfma_f32_16x16x32_bf16 v[32:35], v[128:131], v[184:187], 0
	v_mfma_f32_16x16x32_bf16 v[24:27], v[136:139], v[184:187], 0
	v_mfma_f32_16x16x32_bf16 v[16:19], v[128:131], v[192:195], 0
	v_mfma_f32_16x16x32_bf16 v[8:11], v[136:139], v[192:195], 0
	v_mfma_f32_16x16x32_bf16 v[60:63], v[132:135], v[172:175], v[60:63]
	v_mfma_f32_16x16x32_bf16 v[56:59], v[140:143], v[172:175], v[56:59]
	v_mfma_f32_16x16x32_bf16 v[48:51], v[132:135], v[180:183], v[48:51]
	v_mfma_f32_16x16x32_bf16 v[40:43], v[140:143], v[180:183], v[40:43]
	v_mfma_f32_16x16x32_bf16 v[32:35], v[132:135], v[188:191], v[32:35]
	v_mfma_f32_16x16x32_bf16 v[24:27], v[140:143], v[188:191], v[24:27]
	v_mfma_f32_16x16x32_bf16 v[16:19], v[132:135], v[196:199], v[16:19]
	v_mfma_f32_16x16x32_bf16 v[8:11], v[140:143], v[196:199], v[8:11]
	s_barrier
; #define PG8_STAGE(bufoff, gbase, voff) do { _Pragma("unroll") for (int _i = 0; _i < 2; ++_i) \
;         __builtin_amdgcn_global_load_lds((const unsigned*)((const char*)(gbase) + (voff)[_i]), (LAS unsigned*)(lds + (bufoff) + ldsw + _i * 8192), 16, 0, 0); } while (0)
; #define PG8_LDA(dst, b, h) do { _Pragma("unroll") for (int m = 0; m < 4; ++m) _Pragma("unroll") for (int k = 0; k < 2; ++k) dst[m][k] = *(const LAS bf16x8*)(lds + PG8_SA(b, h) + aoff + m * 2048 + k * 1024); } while (0)
; #define PG8_LDB(dst, b, h) do { _Pragma("unroll") for (int n = 0; n < 2; ++n) _Pragma("unroll") for (int k = 0; k < 2; ++k) dst[n][k] = *(const LAS bf16x8*)(lds + PG8_SB(b, h) + boff + n * 2048 + k * 1024); } while (0)
; #define PG8_MMA(ai, bj, At, Bt) do { __builtin_amdgcn_s_setprio(1); _Pragma("unroll") for (int m = 0; m < 4; ++m) _Pragma("unroll") for (int n = 0; n < 2; ++n) _Pragma("unroll") for (int k = 0; k < 2; ++k) \
;         acc[ai][bj][m][n] = __builtin_amdgcn_mfma_f32_16x16x32_bf16(Bt[n][k], At[m][k], acc[ai][bj][m][n], 0, 0, 0); __builtin_amdgcn_s_setprio(0); } while (0)
; #define PG8_WAIT_V(n) asm volatile("s_waitcnt vmcnt(" #n ")" ::: "memory")
; #define PG8_WAIT_L(n) asm volatile("s_waitcnt lgkmcnt(" #n ")" ::: "memory")
; #define PG8_BAR __builtin_amdgcn_s_barrier()
; #define PG8_SCHED __builtin_amdgcn_sched_barrier(0)
; template <class Epi, class Sched>
; __device__ __forceinline__ void gemm_phase(LAS unsigned char* lds, const Gemm g, const Sched& S, const Epi& E) {
;     ...
;             PG8_BAR; PG8_WAIT_L(0); PG8_MMA(1, 0, At, B0); PG8_BAR; PG8_SCHED;
;             PG8_STAGE(PG8_SB(0, 1), b2 + hstep, voffB);
;             PG8_WAIT_V(6); PG8_BAR; PG8_MMA(1, 1, At, B1); PG8_BAR;
;             PG8_LDB(B0, 1, 0); PG8_SCHED; PG8_LDA(At, 1, 0); PG8_STAGE(PG8_SA(0, 1), a2 + hstep, voffA);
;             PG8_WAIT_L(8); PG8_BAR; PG8_WAIT_L(0); PG8_MMA(0, 0, At, B0); PG8_BAR; PG8_SCHED;
;             PG8_LDB(B1, 1, 1); PG8_STAGE(PG8_SB(1, 0), b3, voffB);
;             PG8_BAR; PG8_WAIT_L(0); PG8_MMA(0, 1, At, B1); PG8_BAR;
;             PG8_LDA(At, 1, 1); PG8_STAGE(PG8_SA(1, 0), a3, voffA);
;             PG8_BAR; PG8_WAIT_L(0); PG8_MMA(1, 0, At, B0); PG8_BAR; PG8_SCHED;
	s_setprio 0
	s_add_u32 s44, s16, 0x80000
	s_addc_u32 s45, s17, 0
	s_add_i32 s46, s36, s24
	s_mov_b32 m0, s46
	s_nop 0
	global_load_lds_dwordx4 v146, s[44:45]
	s_add_i32 m0, s46, 0x2000
	s_nop 0
	global_load_lds_dwordx4 v150, s[44:45]
	s_add_u32 s18, s18, 0x80000
	s_addc_u32 s19, s19, 0
	s_mov_b32 m0, s26
	s_nop 0
	global_load_lds_dwordx4 v144, s[18:19]
	s_mov_b32 m0, s27
	s_nop 0
	global_load_lds_dwordx4 v148, s[18:19]
	s_waitcnt vmcnt(10)
	s_setprio 1
	s_barrier
	v_mfma_f32_16x16x32_bf16 v[52:55], v[202:205], v[162:165], 0
	v_mfma_f32_16x16x32_bf16 v[44:47], v[210:213], v[162:165], 0
	v_mfma_f32_16x16x32_bf16 v[36:39], v[202:205], v[176:179], 0
	v_mfma_f32_16x16x32_bf16 v[28:31], v[210:213], v[176:179], 0
	v_mfma_f32_16x16x32_bf16 v[20:23], v[202:205], v[184:187], 0
	v_mfma_f32_16x16x32_bf16 v[12:15], v[210:213], v[184:187], 0
	v_mfma_f32_16x16x32_bf16 v[4:7], v[202:205], v[192:195], 0
	v_mfma_f32_16x16x32_bf16 v[0:3], v[210:213], v[192:195], 0
	v_mfma_f32_16x16x32_bf16 v[52:55], v[206:209], v[172:175], v[52:55]
	v_mfma_f32_16x16x32_bf16 v[44:47], v[214:217], v[172:175], v[44:47]
	v_mfma_f32_16x16x32_bf16 v[36:39], v[206:209], v[180:183], v[36:39]
	v_mfma_f32_16x16x32_bf16 v[28:31], v[214:217], v[180:183], v[28:31]
	v_mfma_f32_16x16x32_bf16 v[20:23], v[206:209], v[188:191], v[20:23]
	v_mfma_f32_16x16x32_bf16 v[12:15], v[214:217], v[188:191], v[12:15]
	v_mfma_f32_16x16x32_bf16 v[4:7], v[206:209], v[196:199], v[4:7]
	v_mfma_f32_16x16x32_bf16 v[0:3], v[214:217], v[196:199], v[0:3]
	s_add_i32 s44, 0, 0x18000
	v_add_u32_e32 v140, s44, v167
	s_barrier
	s_setprio 0
	ds_read_b128 v[128:131], v140
	ds_read_b128 v[132:135], v140 offset:1024
	ds_read_b128 v[136:139], v140 offset:2048
	ds_read_b128 v[140:143], v140 offset:3072
	ds_read_b128 v[162:165], v169 offset:32768
	ds_read_b128 v[172:175], v169 offset:33792
	ds_read_b128 v[176:179], v169 offset:34816
	ds_read_b128 v[180:183], v169 offset:35840
	ds_read_b128 v[184:187], v169 offset:36864
	ds_read_b128 v[188:191], v169 offset:37888
	ds_read_b128 v[192:195], v169 offset:38912
	ds_read_b128 v[196:199], v169 offset:39936
	s_waitcnt lgkmcnt(8)
	s_waitcnt vmcnt(8)
	s_setprio 1
	s_barrier
	s_waitcnt lgkmcnt(0)
	v_mfma_f32_16x16x32_bf16 v[124:127], v[128:131], v[162:165], v[124:127]
	v_mfma_f32_16x16x32_bf16 v[120:123], v[136:139], v[162:165], v[120:123]
	v_mfma_f32_16x16x32_bf16 v[116:119], v[128:131], v[176:179], v[116:119]
	v_mfma_f32_16x16x32_bf16 v[112:115], v[136:139], v[176:179], v[112:115]
	v_mfma_f32_16x16x32_bf16 v[108:111], v[128:131], v[184:187], v[108:111]
	v_mfma_f32_16x16x32_bf16 v[100:103], v[136:139], v[184:187], v[100:103]
	v_mfma_f32_16x16x32_bf16 v[76:79], v[128:131], v[192:195], v[76:79]
	v_mfma_f32_16x16x32_bf16 v[72:75], v[136:139], v[192:195], v[72:75]
	v_mfma_f32_16x16x32_bf16 v[124:127], v[132:135], v[172:175], v[124:127]
	v_mfma_f32_16x16x32_bf16 v[120:123], v[140:143], v[172:175], v[120:123]
	v_mfma_f32_16x16x32_bf16 v[116:119], v[132:135], v[180:183], v[116:119]
	v_mfma_f32_16x16x32_bf16 v[112:115], v[140:143], v[180:183], v[112:115]
	v_mfma_f32_16x16x32_bf16 v[108:111], v[132:135], v[188:191], v[108:111]
	v_mfma_f32_16x16x32_bf16 v[100:103], v[140:143], v[188:191], v[100:103]
	v_mfma_f32_16x16x32_bf16 v[76:79], v[132:135], v[196:199], v[76:79]
	v_mfma_f32_16x16x32_bf16 v[72:75], v[140:143], v[196:199], v[72:75]
	s_barrier
	s_setprio 0
	s_add_i32 s18, 0, 0x1c000
	s_add_i32 s19, s44, s24
	v_add_u32_e32 v160, s18, v167
	s_add_u32 s0, s16, 0x80
	s_addc_u32 s1, s17, 0
	s_mov_b32 m0, s19
	ds_read_b128 v[202:205], v160
	ds_read_b128 v[206:209], v160 offset:1024
	ds_read_b128 v[210:213], v160 offset:2048
	ds_read_b128 v[214:217], v160 offset:3072
	global_load_lds_dwordx4 v146, s[0:1]
	s_add_i32 m0, s19, 0x2000
	s_nop 0
	global_load_lds_dwordx4 v150, s[0:1]
	s_waitcnt vmcnt(8)
	s_setprio 1
	s_barrier
	s_waitcnt lgkmcnt(0)
	v_mfma_f32_16x16x32_bf16 v[104:107], v[202:205], v[162:165], v[104:107]
	v_mfma_f32_16x16x32_bf16 v[96:99], v[210:213], v[162:165], v[96:99]
	v_mfma_f32_16x16x32_bf16 v[92:95], v[202:205], v[176:179], v[92:95]
	v_mfma_f32_16x16x32_bf16 v[88:91], v[210:213], v[176:179], v[88:91]
	v_mfma_f32_16x16x32_bf16 v[84:87], v[202:205], v[184:187], v[84:87]
	v_mfma_f32_16x16x32_bf16 v[80:83], v[210:213], v[184:187], v[80:83]
	v_mfma_f32_16x16x32_bf16 v[68:71], v[202:205], v[192:195], v[68:71]
	v_mfma_f32_16x16x32_bf16 v[64:67], v[210:213], v[192:195], v[64:67]
	v_mfma_f32_16x16x32_bf16 v[104:107], v[206:209], v[172:175], v[104:107]
	v_mfma_f32_16x16x32_bf16 v[96:99], v[214:217], v[172:175], v[96:99]
	v_mfma_f32_16x16x32_bf16 v[92:95], v[206:209], v[180:183], v[92:95]
	v_mfma_f32_16x16x32_bf16 v[88:91], v[214:217], v[180:183], v[88:91]
	v_mfma_f32_16x16x32_bf16 v[84:87], v[206:209], v[188:191], v[84:87]
	v_mfma_f32_16x16x32_bf16 v[80:83], v[214:217], v[188:191], v[80:83]
	v_mfma_f32_16x16x32_bf16 v[68:71], v[206:209], v[196:199], v[68:71]
	v_mfma_f32_16x16x32_bf16 v[64:67], v[214:217], v[196:199], v[64:67]
	s_mov_b32 m0, s31
	s_mov_b64 s[0:1], 0x80
	v_lshl_add_u64 v[218:219], v[222:223], 0, s[0:1]
	s_barrier
	s_setprio 0
	ds_read_b128 v[162:165], v169 offset:49152
	ds_read_b128 v[172:175], v169 offset:50176
	ds_read_b128 v[176:179], v169 offset:51200
	ds_read_b128 v[180:183], v169 offset:52224
	ds_read_b128 v[184:187], v169 offset:53248
	ds_read_b128 v[188:191], v169 offset:54272
	ds_read_b128 v[192:195], v169 offset:55296
	ds_read_b128 v[196:199], v169 offset:56320
	global_load_lds_dwordx4 v[218:219], off
	v_lshl_add_u64 v[218:219], v[224:225], 0, s[0:1]
	s_mov_b32 m0, s33
	s_nop 0
	global_load_lds_dwordx4 v[218:219], off
	s_setprio 1
	s_barrier
; #define PG8_STAGE(bufoff, gbase, voff) do { _Pragma("unroll") for (int _i = 0; _i < 2; ++_i) \
;         __builtin_amdgcn_global_load_lds((const unsigned*)((const char*)(gbase) + (voff)[_i]), (LAS unsigned*)(lds + (bufoff) + ldsw + _i * 8192), 16, 0, 0); } while (0)
; #define PG8_LDA(dst, b, h) do { _Pragma("unroll") for (int m = 0; m < 4; ++m) _Pragma("unroll") for (int k = 0; k < 2; ++k) dst[m][k] = *(const LAS bf16x8*)(lds + PG8_SA(b, h) + aoff + m * 2048 + k * 1024); } while (0)
; #define PG8_LDB(dst, b, h) do { _Pragma("unroll") for (int n = 0; n < 2; ++n) _Pragma("unroll") for (int k = 0; k < 2; ++k) dst[n][k] = *(const LAS bf16x8*)(lds + PG8_SB(b, h) + boff + n * 2048 + k * 1024); } while (0)
; #define PG8_MMA(ai, bj, At, Bt) do { __builtin_amdgcn_s_setprio(1); _Pragma("unroll") for (int m = 0; m < 4; ++m) _Pragma("unroll") for (int n = 0; n < 2; ++n) _Pragma("unroll") for (int k = 0; k < 2; ++k) \
;         acc[ai][bj][m][n] = __builtin_amdgcn_mfma_f32_16x16x32_bf16(Bt[n][k], At[m][k], acc[ai][bj][m][n], 0, 0, 0); __builtin_amdgcn_s_setprio(0); } while (0)
; #define PG8_WAIT_V(n) asm volatile("s_waitcnt vmcnt(" #n ")" ::: "memory")
; #define PG8_WAIT_L(n) asm volatile("s_waitcnt lgkmcnt(" #n ")" ::: "memory")
; #define PG8_BAR __builtin_amdgcn_s_barrier()
; #define PG8_SCHED __builtin_amdgcn_sched_barrier(0)
; template <class Epi, class Sched>
; __device__ __forceinline__ void gemm_phase(LAS unsigned char* lds, const Gemm g, const Sched& S, const Epi& E) {
;     ...
;             PG8_LDB(B0, 0, 0); PG8_SCHED; PG8_LDA(At, 0, 0); PG8_STAGE(PG8_SA(1, 1), a1 + hstep, voffA);
;             PG8_WAIT_L(8); PG8_BAR; PG8_WAIT_L(0); PG8_MMA(0, 0, At, B0); PG8_BAR; PG8_SCHED;
;             PG8_LDB(B1, 0, 1); PG8_STAGE(PG8_SB(0, 0), b2, voffB);
;             PG8_BAR; PG8_WAIT_L(0); PG8_MMA(0, 1, At, B1); PG8_BAR;
;     ...
;             PG8_BAR; PG8_WAIT_L(0); PG8_MMA(1, 0, At, B0); PG8_BAR; PG8_SCHED;
;             PG8_STAGE(PG8_SB(1, 1), b3 + hstep, voffB);
;             PG8_WAIT_V(6); PG8_BAR; PG8_MMA(1, 1, At, B1); PG8_BAR;
	s_waitcnt lgkmcnt(0)
	v_mfma_f32_16x16x32_bf16 v[60:63], v[128:131], v[162:165], v[60:63]
	v_mfma_f32_16x16x32_bf16 v[56:59], v[136:139], v[162:165], v[56:59]
	v_mfma_f32_16x16x32_bf16 v[48:51], v[128:131], v[176:179], v[48:51]
	v_mfma_f32_16x16x32_bf16 v[40:43], v[136:139], v[176:179], v[40:43]
	v_mfma_f32_16x16x32_bf16 v[32:35], v[128:131], v[184:187], v[32:35]
	v_mfma_f32_16x16x32_bf16 v[24:27], v[136:139], v[184:187], v[24:27]
	v_mfma_f32_16x16x32_bf16 v[16:19], v[128:131], v[192:195], v[16:19]
	v_mfma_f32_16x16x32_bf16 v[8:11], v[136:139], v[192:195], v[8:11]
	v_mfma_f32_16x16x32_bf16 v[60:63], v[132:135], v[172:175], v[60:63]
	v_mfma_f32_16x16x32_bf16 v[56:59], v[140:143], v[172:175], v[56:59]
	v_mfma_f32_16x16x32_bf16 v[48:51], v[132:135], v[180:183], v[48:51]
	v_mfma_f32_16x16x32_bf16 v[40:43], v[140:143], v[180:183], v[40:43]
	v_mfma_f32_16x16x32_bf16 v[32:35], v[132:135], v[188:191], v[32:35]
	v_mfma_f32_16x16x32_bf16 v[24:27], v[140:143], v[188:191], v[24:27]
	v_mfma_f32_16x16x32_bf16 v[16:19], v[132:135], v[196:199], v[16:19]
	v_mfma_f32_16x16x32_bf16 v[8:11], v[140:143], v[196:199], v[8:11]
	s_barrier
	s_setprio 0
	s_add_u32 s16, s16, 0x80080
	s_addc_u32 s17, s17, 0
	s_add_i32 s18, s18, s24
	s_mov_b32 m0, s18
	s_nop 0
	global_load_lds_dwordx4 v146, s[16:17]
	s_add_i32 m0, s18, 0x2000
	s_nop 0
	global_load_lds_dwordx4 v150, s[16:17]
	s_waitcnt vmcnt(8)
	s_setprio 1
	s_barrier
	v_mfma_f32_16x16x32_bf16 v[52:55], v[202:205], v[162:165], v[52:55]
	v_mfma_f32_16x16x32_bf16 v[44:47], v[210:213], v[162:165], v[44:47]
	v_mfma_f32_16x16x32_bf16 v[36:39], v[202:205], v[176:179], v[36:39]
	v_mfma_f32_16x16x32_bf16 v[28:31], v[210:213], v[176:179], v[28:31]
	v_mfma_f32_16x16x32_bf16 v[20:23], v[202:205], v[184:187], v[20:23]
	v_mfma_f32_16x16x32_bf16 v[12:15], v[210:213], v[184:187], v[12:15]
	v_mfma_f32_16x16x32_bf16 v[4:7], v[202:205], v[192:195], v[4:7]
	v_mfma_f32_16x16x32_bf16 v[0:3], v[210:213], v[192:195], v[0:3]
	v_mfma_f32_16x16x32_bf16 v[52:55], v[206:209], v[172:175], v[52:55]
	v_mfma_f32_16x16x32_bf16 v[44:47], v[214:217], v[172:175], v[44:47]
	v_mfma_f32_16x16x32_bf16 v[36:39], v[206:209], v[180:183], v[36:39]
	v_mfma_f32_16x16x32_bf16 v[28:31], v[214:217], v[180:183], v[28:31]
	v_mfma_f32_16x16x32_bf16 v[20:23], v[206:209], v[188:191], v[20:23]
	v_mfma_f32_16x16x32_bf16 v[12:15], v[214:217], v[188:191], v[12:15]
	v_mfma_f32_16x16x32_bf16 v[4:7], v[206:209], v[196:199], v[4:7]
	v_mfma_f32_16x16x32_bf16 v[0:3], v[214:217], v[196:199], v[0:3]
	s_add_i32 s43, s43, 2
	s_add_u32 s14, s14, 0x100
	s_addc_u32 s15, s15, 0
	s_add_u32 s41, s41, 0x100
	s_addc_u32 s42, s42, 0
	s_cmp_gt_u32 s43, 29
	s_barrier
	s_setprio 0
.LBB0_826:
	ds_read_b128 v[128:131], v168
	ds_read_b128 v[132:135], v168 offset:1024
	ds_read_b128 v[136:139], v168 offset:2048
	ds_read_b128 v[140:143], v168 offset:3072
	s_add_u32 s16, s14, 0xfff80080
	s_addc_u32 s17, s15, -1
	s_cmp_eq_u32 s43, 28
	s_cselect_b32 s19, s7, s17
	s_cselect_b32 s18, s39, s16
	s_cselect_b32 s17, s5, s42
	s_cselect_b32 s16, s40, s41
	s_add_i32 m0, s13, 0xc000
	ds_read_b128 v[162:165], v169
	ds_read_b128 v[172:175], v169 offset:1024
	ds_read_b128 v[176:179], v169 offset:2048
	ds_read_b128 v[180:183], v169 offset:3072
	ds_read_b128 v[184:187], v169 offset:4096
	ds_read_b128 v[188:191], v169 offset:5120
	ds_read_b128 v[192:195], v169 offset:6144
	ds_read_b128 v[196:199], v169 offset:7168
	global_load_lds_dwordx4 v152, s[14:15]
	s_add_i32 m0, s13, 0xe000
	s_nop 0
	global_load_lds_dwordx4 v154, s[14:15]
	s_waitcnt lgkmcnt(8)
	s_waitcnt vmcnt(8)
	s_setprio 1
	s_barrier
	s_waitcnt lgkmcnt(0)
	v_mfma_f32_16x16x32_bf16 v[124:127], v[128:131], v[162:165], v[124:127]
	v_mfma_f32_16x16x32_bf16 v[120:123], v[136:139], v[162:165], v[120:123]
	v_mfma_f32_16x16x32_bf16 v[116:119], v[128:131], v[176:179], v[116:119]
	v_mfma_f32_16x16x32_bf16 v[112:115], v[136:139], v[176:179], v[112:115]
	v_mfma_f32_16x16x32_bf16 v[108:111], v[128:131], v[184:187], v[108:111]
	v_mfma_f32_16x16x32_bf16 v[100:103], v[136:139], v[184:187], v[100:103]
	v_mfma_f32_16x16x32_bf16 v[76:79], v[128:131], v[192:195], v[76:79]
	v_mfma_f32_16x16x32_bf16 v[72:75], v[136:139], v[192:195], v[72:75]
	v_mfma_f32_16x16x32_bf16 v[124:127], v[132:135], v[172:175], v[124:127]
	v_mfma_f32_16x16x32_bf16 v[120:123], v[140:143], v[172:175], v[120:123]
	v_mfma_f32_16x16x32_bf16 v[116:119], v[132:135], v[180:183], v[116:119]
	v_mfma_f32_16x16x32_bf16 v[112:115], v[140:143], v[180:183], v[112:115]
	v_mfma_f32_16x16x32_bf16 v[108:111], v[132:135], v[188:191], v[108:111]
	v_mfma_f32_16x16x32_bf16 v[100:103], v[140:143], v[188:191], v[100:103]
	v_mfma_f32_16x16x32_bf16 v[76:79], v[132:135], v[196:199], v[76:79]
	v_mfma_f32_16x16x32_bf16 v[72:75], v[140:143], v[196:199], v[72:75]
	s_barrier
	s_setprio 0
	s_add_i32 s44, s35, s24
	s_mov_b32 m0, s44
	ds_read_b128 v[202:205], v170
	ds_read_b128 v[206:209], v170 offset:1024
	ds_read_b128 v[210:213], v170 offset:2048
	ds_read_b128 v[214:217], v170 offset:3072
	global_load_lds_dwordx4 v146, s[16:17]
	s_add_i32 m0, s44, 0x2000
	s_nop 0
	global_load_lds_dwordx4 v150, s[16:17]
	s_waitcnt vmcnt(8)
	s_setprio 1
	s_barrier
; #define PG8_STAGE(bufoff, gbase, voff) do { _Pragma("unroll") for (int _i = 0; _i < 2; ++_i) \
;         __builtin_amdgcn_global_load_lds((const unsigned*)((const char*)(gbase) + (voff)[_i]), (LAS unsigned*)(lds + (bufoff) + ldsw + _i * 8192), 16, 0, 0); } while (0)
; #define PG8_LDA(dst, b, h) do { _Pragma("unroll") for (int m = 0; m < 4; ++m) _Pragma("unroll") for (int k = 0; k < 2; ++k) dst[m][k] = *(const LAS bf16x8*)(lds + PG8_SA(b, h) + aoff + m * 2048 + k * 1024); } while (0)
; #define PG8_LDB(dst, b, h) do { _Pragma("unroll") for (int n = 0; n < 2; ++n) _Pragma("unroll") for (int k = 0; k < 2; ++k) dst[n][k] = *(const LAS bf16x8*)(lds + PG8_SB(b, h) + boff + n * 2048 + k * 1024); } while (0)
; #define PG8_MMA(ai, bj, At, Bt) do { __builtin_amdgcn_s_setprio(1); _Pragma("unroll") for (int m = 0; m < 4; ++m) _Pragma("unroll") for (int n = 0; n < 2; ++n) _Pragma("unroll") for (int k = 0; k < 2; ++k) \
;         acc[ai][bj][m][n] = __builtin_amdgcn_mfma_f32_16x16x32_bf16(Bt[n][k], At[m][k], acc[ai][bj][m][n], 0, 0, 0); __builtin_amdgcn_s_setprio(0); } while (0)
; #define PG8_WAIT_V(n) asm volatile("s_waitcnt vmcnt(" #n ")" ::: "memory")
; #define PG8_WAIT_L(n) asm volatile("s_waitcnt lgkmcnt(" #n ")" ::: "memory")
; #define PG8_BAR __builtin_amdgcn_s_barrier()
; #define PG8_SCHED __builtin_amdgcn_sched_barrier(0)
; template <class Epi, class Sched>
; __device__ __forceinline__ void gemm_phase(LAS unsigned char* lds, const Gemm g, const Sched& S, const Epi& E) {
;     ...
;             PG8_BAR; PG8_WAIT_L(0); PG8_MMA(0, 1, At, B1); PG8_BAR;
;             PG8_LDA(At, 0, 1); PG8_STAGE(PG8_SA(0, 0), a2, voffA);
;             PG8_BAR; PG8_WAIT_L(0); PG8_MMA(1, 0, At, B0); PG8_BAR; PG8_SCHED;
;             PG8_STAGE(PG8_SB(0, 1), b2 + hstep, voffB);
;             PG8_WAIT_V(6); PG8_BAR; PG8_MMA(1, 1, At, B1); PG8_BAR;
;             PG8_LDB(B0, 1, 0); PG8_SCHED; PG8_LDA(At, 1, 0); PG8_STAGE(PG8_SA(0, 1), a2 + hstep, voffA);
;             PG8_WAIT_L(8); PG8_BAR; PG8_WAIT_L(0); PG8_MMA(0, 0, At, B0); PG8_BAR; PG8_SCHED;
	s_waitcnt lgkmcnt(0)
	v_mfma_f32_16x16x32_bf16 v[104:107], v[202:205], v[162:165], v[104:107]
	v_mfma_f32_16x16x32_bf16 v[96:99], v[210:213], v[162:165], v[96:99]
	v_mfma_f32_16x16x32_bf16 v[92:95], v[202:205], v[176:179], v[92:95]
	v_mfma_f32_16x16x32_bf16 v[88:91], v[210:213], v[176:179], v[88:91]
	v_mfma_f32_16x16x32_bf16 v[84:87], v[202:205], v[184:187], v[84:87]
	v_mfma_f32_16x16x32_bf16 v[80:83], v[210:213], v[184:187], v[80:83]
	v_mfma_f32_16x16x32_bf16 v[68:71], v[202:205], v[192:195], v[68:71]
	v_mfma_f32_16x16x32_bf16 v[64:67], v[210:213], v[192:195], v[64:67]
	v_mfma_f32_16x16x32_bf16 v[104:107], v[206:209], v[172:175], v[104:107]
	v_mfma_f32_16x16x32_bf16 v[96:99], v[214:217], v[172:175], v[96:99]
	v_mfma_f32_16x16x32_bf16 v[92:95], v[206:209], v[180:183], v[92:95]
	v_mfma_f32_16x16x32_bf16 v[88:91], v[214:217], v[180:183], v[88:91]
	v_mfma_f32_16x16x32_bf16 v[84:87], v[206:209], v[188:191], v[84:87]
	v_mfma_f32_16x16x32_bf16 v[80:83], v[214:217], v[188:191], v[80:83]
	v_mfma_f32_16x16x32_bf16 v[68:71], v[206:209], v[196:199], v[68:71]
	v_mfma_f32_16x16x32_bf16 v[64:67], v[214:217], v[196:199], v[64:67]
	s_mov_b32 m0, s13
	v_lshl_add_u64 v[222:223], s[18:19], 0, v[144:145]
	s_barrier
	s_setprio 0
	ds_read_b128 v[162:165], v169 offset:16384
	ds_read_b128 v[172:175], v169 offset:17408
	ds_read_b128 v[176:179], v169 offset:18432
	ds_read_b128 v[180:183], v169 offset:19456
	ds_read_b128 v[184:187], v169 offset:20480
	ds_read_b128 v[188:191], v169 offset:21504
	ds_read_b128 v[192:195], v169 offset:22528
	ds_read_b128 v[196:199], v169 offset:23552
	global_load_lds_dwordx4 v144, s[18:19]
	v_lshl_add_u64 v[224:225], s[18:19], 0, v[148:149]
	s_mov_b32 m0, s25
	s_nop 0
	global_load_lds_dwordx4 v148, s[18:19]
	s_setprio 1
	s_barrier
	s_waitcnt lgkmcnt(0)
	v_mfma_f32_16x16x32_bf16 v[60:63], v[128:131], v[162:165], v[60:63]
	v_mfma_f32_16x16x32_bf16 v[56:59], v[136:139], v[162:165], v[56:59]
	v_mfma_f32_16x16x32_bf16 v[48:51], v[128:131], v[176:179], v[48:51]
	v_mfma_f32_16x16x32_bf16 v[40:43], v[136:139], v[176:179], v[40:43]
	v_mfma_f32_16x16x32_bf16 v[32:35], v[128:131], v[184:187], v[32:35]
	v_mfma_f32_16x16x32_bf16 v[24:27], v[136:139], v[184:187], v[24:27]
	v_mfma_f32_16x16x32_bf16 v[16:19], v[128:131], v[192:195], v[16:19]
	v_mfma_f32_16x16x32_bf16 v[8:11], v[136:139], v[192:195], v[8:11]
	v_mfma_f32_16x16x32_bf16 v[60:63], v[132:135], v[172:175], v[60:63]
	v_mfma_f32_16x16x32_bf16 v[56:59], v[140:143], v[172:175], v[56:59]
	v_mfma_f32_16x16x32_bf16 v[48:51], v[132:135], v[180:183], v[48:51]
	v_mfma_f32_16x16x32_bf16 v[40:43], v[140:143], v[180:183], v[40:43]
	v_mfma_f32_16x16x32_bf16 v[32:35], v[132:135], v[188:191], v[32:35]
	v_mfma_f32_16x16x32_bf16 v[24:27], v[140:143], v[188:191], v[24:27]
	v_mfma_f32_16x16x32_bf16 v[16:19], v[132:135], v[196:199], v[16:19]
	v_mfma_f32_16x16x32_bf16 v[8:11], v[140:143], v[196:199], v[8:11]
	s_barrier
	s_setprio 0
	s_add_u32 s44, s16, 0x80000
	s_addc_u32 s45, s17, 0
	s_add_i32 s46, s36, s24
	s_mov_b32 m0, s46
	s_nop 0
	global_load_lds_dwordx4 v146, s[44:45]
	s_add_i32 m0, s46, 0x2000
	s_nop 0
	global_load_lds_dwordx4 v150, s[44:45]
	s_add_u32 s18, s18, 0x80000
	s_addc_u32 s19, s19, 0
	s_mov_b32 m0, s26
	s_nop 0
	global_load_lds_dwordx4 v144, s[18:19]
	s_mov_b32 m0, s27
	s_nop 0
	global_load_lds_dwordx4 v148, s[18:19]
	s_waitcnt vmcnt(10)
	s_setprio 1
	s_barrier
	v_mfma_f32_16x16x32_bf16 v[52:55], v[202:205], v[162:165], v[52:55]
	v_mfma_f32_16x16x32_bf16 v[44:47], v[210:213], v[162:165], v[44:47]
	v_mfma_f32_16x16x32_bf16 v[36:39], v[202:205], v[176:179], v[36:39]
	v_mfma_f32_16x16x32_bf16 v[28:31], v[210:213], v[176:179], v[28:31]
	v_mfma_f32_16x16x32_bf16 v[20:23], v[202:205], v[184:187], v[20:23]
	v_mfma_f32_16x16x32_bf16 v[12:15], v[210:213], v[184:187], v[12:15]
	v_mfma_f32_16x16x32_bf16 v[4:7], v[202:205], v[192:195], v[4:7]
	v_mfma_f32_16x16x32_bf16 v[0:3], v[210:213], v[192:195], v[0:3]
	v_mfma_f32_16x16x32_bf16 v[52:55], v[206:209], v[172:175], v[52:55]
	v_mfma_f32_16x16x32_bf16 v[44:47], v[214:217], v[172:175], v[44:47]
	v_mfma_f32_16x16x32_bf16 v[36:39], v[206:209], v[180:183], v[36:39]
	v_mfma_f32_16x16x32_bf16 v[28:31], v[214:217], v[180:183], v[28:31]
	v_mfma_f32_16x16x32_bf16 v[20:23], v[206:209], v[188:191], v[20:23]
	v_mfma_f32_16x16x32_bf16 v[12:15], v[214:217], v[188:191], v[12:15]
	v_mfma_f32_16x16x32_bf16 v[4:7], v[206:209], v[196:199], v[4:7]
	v_mfma_f32_16x16x32_bf16 v[0:3], v[214:217], v[196:199], v[0:3]
	s_add_i32 s44, 0, 0x18000
	v_add_u32_e32 v140, s44, v167
	s_barrier
	s_setprio 0
	ds_read_b128 v[128:131], v140
	ds_read_b128 v[132:135], v140 offset:1024
	ds_read_b128 v[136:139], v140 offset:2048
	ds_read_b128 v[140:143], v140 offset:3072
	ds_read_b128 v[162:165], v169 offset:32768
	ds_read_b128 v[172:175], v169 offset:33792
	ds_read_b128 v[176:179], v169 offset:34816
	ds_read_b128 v[180:183], v169 offset:35840
	ds_read_b128 v[184:187], v169 offset:36864
	ds_read_b128 v[188:191], v169 offset:37888
	ds_read_b128 v[192:195], v169 offset:38912
	ds_read_b128 v[196:199], v169 offset:39936
	s_waitcnt lgkmcnt(8)
	s_waitcnt vmcnt(8)
	s_setprio 1
	s_barrier
; #define PG8_STAGE(bufoff, gbase, voff) do { _Pragma("unroll") for (int _i = 0; _i < 2; ++_i) \
;         __builtin_amdgcn_global_load_lds((const unsigned*)((const char*)(gbase) + (voff)[_i]), (LAS unsigned*)(lds + (bufoff) + ldsw + _i * 8192), 16, 0, 0); } while (0)
; #define PG8_LDA(dst, b, h) do { _Pragma("unroll") for (int m = 0; m < 4; ++m) _Pragma("unroll") for (int k = 0; k < 2; ++k) dst[m][k] = *(const LAS bf16x8*)(lds + PG8_SA(b, h) + aoff + m * 2048 + k * 1024); } while (0)
; #define PG8_LDB(dst, b, h) do { _Pragma("unroll") for (int n = 0; n < 2; ++n) _Pragma("unroll") for (int k = 0; k < 2; ++k) dst[n][k] = *(const LAS bf16x8*)(lds + PG8_SB(b, h) + boff + n * 2048 + k * 1024); } while (0)
; #define PG8_MMA(ai, bj, At, Bt) do { __builtin_amdgcn_s_setprio(1); _Pragma("unroll") for (int m = 0; m < 4; ++m) _Pragma("unroll") for (int n = 0; n < 2; ++n) _Pragma("unroll") for (int k = 0; k < 2; ++k) \
;         acc[ai][bj][m][n] = __builtin_amdgcn_mfma_f32_16x16x32_bf16(Bt[n][k], At[m][k], acc[ai][bj][m][n], 0, 0, 0); __builtin_amdgcn_s_setprio(0); } while (0)
; #define PG8_WAIT_V(n) asm volatile("s_waitcnt vmcnt(" #n ")" ::: "memory")
; #define PG8_WAIT_L(n) asm volatile("s_waitcnt lgkmcnt(" #n ")" ::: "memory")
; #define PG8_BAR __builtin_amdgcn_s_barrier()
; #define PG8_SCHED __builtin_amdgcn_sched_barrier(0)
; template <class Epi, class Sched>
; __device__ __forceinline__ void gemm_phase(LAS unsigned char* lds, const Gemm g, const Sched& S, const Epi& E) {
;     ...
;             PG8_WAIT_L(8); PG8_BAR; PG8_WAIT_L(0); PG8_MMA(0, 0, At, B0); PG8_BAR; PG8_SCHED;
;             PG8_LDB(B1, 1, 1); PG8_STAGE(PG8_SB(1, 0), b3, voffB);
;             PG8_BAR; PG8_WAIT_L(0); PG8_MMA(0, 1, At, B1); PG8_BAR;
;             PG8_LDA(At, 1, 1); PG8_STAGE(PG8_SA(1, 0), a3, voffA);
;             PG8_BAR; PG8_WAIT_L(0); PG8_MMA(1, 0, At, B0); PG8_BAR; PG8_SCHED;
;             PG8_STAGE(PG8_SB(1, 1), b3 + hstep, voffB);
;             PG8_WAIT_V(6); PG8_BAR; PG8_MMA(1, 1, At, B1); PG8_BAR;
	s_waitcnt lgkmcnt(0)
	v_mfma_f32_16x16x32_bf16 v[124:127], v[128:131], v[162:165], v[124:127]
	v_mfma_f32_16x16x32_bf16 v[120:123], v[136:139], v[162:165], v[120:123]
	v_mfma_f32_16x16x32_bf16 v[116:119], v[128:131], v[176:179], v[116:119]
	v_mfma_f32_16x16x32_bf16 v[112:115], v[136:139], v[176:179], v[112:115]
	v_mfma_f32_16x16x32_bf16 v[108:111], v[128:131], v[184:187], v[108:111]
	v_mfma_f32_16x16x32_bf16 v[100:103], v[136:139], v[184:187], v[100:103]
	v_mfma_f32_16x16x32_bf16 v[76:79], v[128:131], v[192:195], v[76:79]
	v_mfma_f32_16x16x32_bf16 v[72:75], v[136:139], v[192:195], v[72:75]
	v_mfma_f32_16x16x32_bf16 v[124:127], v[132:135], v[172:175], v[124:127]
	v_mfma_f32_16x16x32_bf16 v[120:123], v[140:143], v[172:175], v[120:123]
	v_mfma_f32_16x16x32_bf16 v[116:119], v[132:135], v[180:183], v[116:119]
	v_mfma_f32_16x16x32_bf16 v[112:115], v[140:143], v[180:183], v[112:115]
	v_mfma_f32_16x16x32_bf16 v[108:111], v[132:135], v[188:191], v[108:111]
	v_mfma_f32_16x16x32_bf16 v[100:103], v[140:143], v[188:191], v[100:103]
	v_mfma_f32_16x16x32_bf16 v[76:79], v[132:135], v[196:199], v[76:79]
	v_mfma_f32_16x16x32_bf16 v[72:75], v[140:143], v[196:199], v[72:75]
	s_barrier
	s_setprio 0
	s_add_i32 s18, 0, 0x1c000
	s_add_i32 s19, s44, s24
	v_add_u32_e32 v160, s18, v167
	s_add_u32 s0, s16, 0x80
	s_addc_u32 s1, s17, 0
	s_mov_b32 m0, s19
	ds_read_b128 v[202:205], v160
	ds_read_b128 v[206:209], v160 offset:1024
	ds_read_b128 v[210:213], v160 offset:2048
	ds_read_b128 v[214:217], v160 offset:3072
	global_load_lds_dwordx4 v146, s[0:1]
	s_add_i32 m0, s19, 0x2000
	s_nop 0
	global_load_lds_dwordx4 v150, s[0:1]
	s_waitcnt vmcnt(8)
	s_setprio 1
	s_barrier
	s_waitcnt lgkmcnt(0)
	v_mfma_f32_16x16x32_bf16 v[104:107], v[202:205], v[162:165], v[104:107]
	v_mfma_f32_16x16x32_bf16 v[96:99], v[210:213], v[162:165], v[96:99]
	v_mfma_f32_16x16x32_bf16 v[92:95], v[202:205], v[176:179], v[92:95]
	v_mfma_f32_16x16x32_bf16 v[88:91], v[210:213], v[176:179], v[88:91]
	v_mfma_f32_16x16x32_bf16 v[84:87], v[202:205], v[184:187], v[84:87]
	v_mfma_f32_16x16x32_bf16 v[80:83], v[210:213], v[184:187], v[80:83]
	v_mfma_f32_16x16x32_bf16 v[68:71], v[202:205], v[192:195], v[68:71]
	v_mfma_f32_16x16x32_bf16 v[64:67], v[210:213], v[192:195], v[64:67]
	v_mfma_f32_16x16x32_bf16 v[104:107], v[206:209], v[172:175], v[104:107]
	v_mfma_f32_16x16x32_bf16 v[96:99], v[214:217], v[172:175], v[96:99]
	v_mfma_f32_16x16x32_bf16 v[92:95], v[206:209], v[180:183], v[92:95]
	v_mfma_f32_16x16x32_bf16 v[88:91], v[214:217], v[180:183], v[88:91]
	v_mfma_f32_16x16x32_bf16 v[84:87], v[206:209], v[188:191], v[84:87]
	v_mfma_f32_16x16x32_bf16 v[80:83], v[214:217], v[188:191], v[80:83]
	v_mfma_f32_16x16x32_bf16 v[68:71], v[206:209], v[196:199], v[68:71]
	v_mfma_f32_16x16x32_bf16 v[64:67], v[214:217], v[196:199], v[64:67]
	s_mov_b32 m0, s31
	s_mov_b64 s[0:1], 0x80
	v_lshl_add_u64 v[218:219], v[222:223], 0, s[0:1]
	s_barrier
	s_setprio 0
	ds_read_b128 v[162:165], v169 offset:49152
	ds_read_b128 v[172:175], v169 offset:50176
	ds_read_b128 v[176:179], v169 offset:51200
	ds_read_b128 v[180:183], v169 offset:52224
	ds_read_b128 v[184:187], v169 offset:53248
	ds_read_b128 v[188:191], v169 offset:54272
	ds_read_b128 v[192:195], v169 offset:55296
	ds_read_b128 v[196:199], v169 offset:56320
	global_load_lds_dwordx4 v[218:219], off
	v_lshl_add_u64 v[218:219], v[224:225], 0, s[0:1]
	s_mov_b32 m0, s33
	s_nop 0
	global_load_lds_dwordx4 v[218:219], off
	s_setprio 1
	s_barrier
	s_waitcnt lgkmcnt(0)
	v_mfma_f32_16x16x32_bf16 v[60:63], v[128:131], v[162:165], v[60:63]
	v_mfma_f32_16x16x32_bf16 v[56:59], v[136:139], v[162:165], v[56:59]
	v_mfma_f32_16x16x32_bf16 v[48:51], v[128:131], v[176:179], v[48:51]
	v_mfma_f32_16x16x32_bf16 v[40:43], v[136:139], v[176:179], v[40:43]
	v_mfma_f32_16x16x32_bf16 v[32:35], v[128:131], v[184:187], v[32:35]
	v_mfma_f32_16x16x32_bf16 v[24:27], v[136:139], v[184:187], v[24:27]
	v_mfma_f32_16x16x32_bf16 v[16:19], v[128:131], v[192:195], v[16:19]
	v_mfma_f32_16x16x32_bf16 v[8:11], v[136:139], v[192:195], v[8:11]
	v_mfma_f32_16x16x32_bf16 v[60:63], v[132:135], v[172:175], v[60:63]
	v_mfma_f32_16x16x32_bf16 v[56:59], v[140:143], v[172:175], v[56:59]
	v_mfma_f32_16x16x32_bf16 v[48:51], v[132:135], v[180:183], v[48:51]
	v_mfma_f32_16x16x32_bf16 v[40:43], v[140:143], v[180:183], v[40:43]
	v_mfma_f32_16x16x32_bf16 v[32:35], v[132:135], v[188:191], v[32:35]
	v_mfma_f32_16x16x32_bf16 v[24:27], v[140:143], v[188:191], v[24:27]
	v_mfma_f32_16x16x32_bf16 v[16:19], v[132:135], v[196:199], v[16:19]
	v_mfma_f32_16x16x32_bf16 v[8:11], v[140:143], v[196:199], v[8:11]
	s_barrier
	s_setprio 0
	s_add_u32 s16, s16, 0x80080
	s_addc_u32 s17, s17, 0
	s_add_i32 s18, s18, s24
	s_mov_b32 m0, s18
	s_nop 0
	global_load_lds_dwordx4 v146, s[16:17]
	s_add_i32 m0, s18, 0x2000
	s_nop 0
	global_load_lds_dwordx4 v150, s[16:17]
	s_waitcnt vmcnt(8)
	s_setprio 1
	s_barrier
	v_mfma_f32_16x16x32_bf16 v[52:55], v[202:205], v[162:165], v[52:55]
	v_mfma_f32_16x16x32_bf16 v[44:47], v[210:213], v[162:165], v[44:47]
	v_mfma_f32_16x16x32_bf16 v[36:39], v[202:205], v[176:179], v[36:39]
	v_mfma_f32_16x16x32_bf16 v[28:31], v[210:213], v[176:179], v[28:31]
	v_mfma_f32_16x16x32_bf16 v[20:23], v[202:205], v[184:187], v[20:23]
	v_mfma_f32_16x16x32_bf16 v[12:15], v[210:213], v[184:187], v[12:15]
	v_mfma_f32_16x16x32_bf16 v[4:7], v[202:205], v[192:195], v[4:7]
	v_mfma_f32_16x16x32_bf16 v[0:3], v[210:213], v[192:195], v[0:3]
	v_mfma_f32_16x16x32_bf16 v[52:55], v[206:209], v[172:175], v[52:55]
	v_mfma_f32_16x16x32_bf16 v[44:47], v[214:217], v[172:175], v[44:47]
	v_mfma_f32_16x16x32_bf16 v[36:39], v[206:209], v[180:183], v[36:39]
	v_mfma_f32_16x16x32_bf16 v[28:31], v[214:217], v[180:183], v[28:31]
	v_mfma_f32_16x16x32_bf16 v[20:23], v[206:209], v[188:191], v[20:23]
	v_mfma_f32_16x16x32_bf16 v[12:15], v[214:217], v[188:191], v[12:15]
	v_mfma_f32_16x16x32_bf16 v[4:7], v[206:209], v[196:199], v[4:7]
	v_mfma_f32_16x16x32_bf16 v[0:3], v[214:217], v[196:199], v[0:3]
	s_add_i32 s43, s43, 2
	s_add_u32 s14, s14, 0x100
	s_addc_u32 s15, s15, 0
	s_add_u32 s41, s41, 0x100
	s_addc_u32 s42, s42, 0
	s_cmp_gt_u32 s43, 29
	s_barrier
; __device__ __forceinline__ unsigned cvt_pk_bf16(float lo, float hi) { unsigned r; asm volatile("v_cvt_pk_bf16_f32 %0, %1, %2" : "=v"(r) : "v"(lo), "v"(hi)); return r; }
;     __device__ __forceinline__ void operator()(const AccT& acc, const Unit& u, int wr, int wc, int fr, int fq) const {
;     ...
;         const int row0 = u.pm * 256 + wr * 64 + fr; const int b = u.pn >> 1, ch0 = (u.pn & 1) * 256 + wc * 32 + 8 * fq;
;         const float sg = (fr & 1) ? -1.0f : 1.0f;
;         f32x4 yh[2][2];
; #pragma unroll
;         for (int bj = 0; bj < 2; ++bj)
; #pragma unroll
;             for (int n = 0; n < 2; ++n) yh[bj][n] = *(const f32x4*)(YCH + b * 512 + ch0 + bj * 128 + 4 * n) * sg;
; #pragma unroll
;         for (int ai = 0; ai < 2; ++ai)
; #pragma unroll
;             for (int m = 0; m < 4; ++m) {
;                 const int k = row0 + ai * 128 + m * 16;
; #pragma unroll
;                 for (int bj = 0; bj < 2; ++bj) {
;                     const f32x4 v0 = acc[ai][bj][m][0] + yh[bj][0], v1 = acc[ai][bj][m][1] + yh[bj][1];
;                     u32x4 w; w.x = cvt_pk_bf16(v0[0], v0[1]); w.y = cvt_pk_bf16(v0[2], v0[3]); w.z = cvt_pk_bf16(v1[0], v1[1]); w.w = cvt_pk_bf16(v1[2], v1[3]);
;                     *(u32x4*)(CAT + (size_t)(b * 2048 + k) * CATW + 1024 + ch0 + bj * 128) = w;
;                 }
	s_setprio 0
	s_cbranch_scc0 .LBB0_826
	s_ashr_i32 s5, s38, 1
	s_lshl_b32 s7, s38, 8
	s_lshl_b32 s14, s5, 9
	s_and_b32 s7, s7, 0x100
	s_ashr_i32 s15, s14, 31
	v_mov_b32_e32 v171, v161
	v_mov_b32_e32 v128, v166
	s_or_b32 s7, s7, s30
	s_lshl_b64 s[14:15], s[14:15], 2
	s_add_u32 s14, s48, s14
	v_lshl_add_u32 v164, v128, 3, s7
	s_addc_u32 s15, s49, s15
	v_ashrrev_i32_e32 v165, 31, v164
	v_lshl_add_u64 v[128:129], v[164:165], 2, s[14:15]
	global_load_dwordx4 v[140:143], v[128:129], off
	global_load_dwordx4 v[136:139], v[128:129], off offset:16
	global_load_dwordx4 v[132:135], v[128:129], off offset:512
	s_nop 0
	global_load_dwordx4 v[128:131], v[128:129], off offset:528
	s_lshl_b32 s7, s12, 8
	s_lshl_b32 s5, s5, 11
	s_add_i32 s7, s7, s29
	v_and_b32_e32 v160, 1, v171
	s_add_i32 s7, s7, s5
	v_mov_b64_e32 v[162:163], s[96:97]
	v_cmp_eq_u32_e32 vcc, 0, v160
	v_add_u32_e32 v171, s7, v171
	v_lshlrev_b64 v[164:165], 1, v[164:165]
	v_cndmask_b32_e64 v160, -1.0, 1.0, vcc
	v_mad_i64_i32 v[172:173], s[14:15], v171, s37, v[162:163]
	v_add_u32_e32 v174, 16, v171
	v_lshl_add_u64 v[172:173], v[172:173], 0, v[164:165]
	v_mad_i64_i32 v[174:175], s[14:15], v174, s37, v[162:163]
	v_add_u32_e32 v176, 32, v171
	v_lshl_add_u64 v[174:175], v[174:175], 0, v[164:165]
	v_mad_i64_i32 v[176:177], s[14:15], v176, s37, v[162:163]
	v_lshl_add_u64 v[176:177], v[176:177], 0, v[164:165]
	v_add_u32_e32 v182, 48, v171
	s_and_b64 vcc, exec, s[2:3]
	s_mov_b32 s38, s4
	s_mov_b32 s12, s6
	s_mov_b64 s[16:17], s[10:11]
	s_waitcnt vmcnt(0)
	v_pk_fma_f32 v[126:127], v[142:143], v[160:161], v[126:127] op_sel_hi:[1,0,1]
	v_pk_fma_f32 v[124:125], v[140:141], v[160:161], v[124:125] op_sel_hi:[1,0,1]
	v_pk_fma_f32 v[122:123], v[138:139], v[160:161], v[122:123] op_sel_hi:[1,0,1]
	v_pk_fma_f32 v[180:181], v[128:129], v[160:161], v[80:81] op_sel_hi:[1,0,1]
	v_cvt_pk_bf16_f32 v80, v124, v125
	v_cvt_pk_bf16_f32 v81, v126, v127
	v_pk_fma_f32 v[120:121], v[136:137], v[160:161], v[120:121] op_sel_hi:[1,0,1]
	v_pk_fma_f32 v[106:107], v[134:135], v[160:161], v[106:107] op_sel_hi:[1,0,1]
	v_pk_fma_f32 v[104:105], v[132:133], v[160:161], v[104:105] op_sel_hi:[1,0,1]
	v_pk_fma_f32 v[178:179], v[130:131], v[160:161], v[82:83] op_sel_hi:[1,0,1]
	v_cvt_pk_bf16_f32 v82, v120, v121
	v_cvt_pk_bf16_f32 v83, v122, v123
	global_store_dwordx4 v[172:173], v[80:83], off offset:2048
	v_pk_fma_f32 v[98:99], v[130:131], v[160:161], v[98:99] op_sel_hi:[1,0,1]
	v_pk_fma_f32 v[96:97], v[128:129], v[160:161], v[96:97] op_sel_hi:[1,0,1]
	v_cvt_pk_bf16_f32 v80, v104, v105
	v_cvt_pk_bf16_f32 v81, v106, v107
	v_pk_fma_f32 v[118:119], v[142:143], v[160:161], v[118:119] op_sel_hi:[1,0,1]
	v_pk_fma_f32 v[116:117], v[140:141], v[160:161], v[116:117] op_sel_hi:[1,0,1]
	v_cvt_pk_bf16_f32 v82, v96, v97
	v_cvt_pk_bf16_f32 v83, v98, v99
	global_store_dwordx4 v[172:173], v[80:83], off offset:2304
	v_pk_fma_f32 v[114:115], v[138:139], v[160:161], v[114:115] op_sel_hi:[1,0,1]
	v_pk_fma_f32 v[112:113], v[136:137], v[160:161], v[112:113] op_sel_hi:[1,0,1]
	v_cvt_pk_bf16_f32 v80, v116, v117
	v_cvt_pk_bf16_f32 v81, v118, v119
	v_pk_fma_f32 v[94:95], v[134:135], v[160:161], v[94:95] op_sel_hi:[1,0,1]
	v_pk_fma_f32 v[92:93], v[132:133], v[160:161], v[92:93] op_sel_hi:[1,0,1]
	v_cvt_pk_bf16_f32 v82, v112, v113
	v_cvt_pk_bf16_f32 v83, v114, v115
	global_store_dwordx4 v[174:175], v[80:83], off offset:2048
	v_pk_fma_f32 v[90:91], v[130:131], v[160:161], v[90:91] op_sel_hi:[1,0,1]
	v_pk_fma_f32 v[88:89], v[128:129], v[160:161], v[88:89] op_sel_hi:[1,0,1]
	v_cvt_pk_bf16_f32 v80, v92, v93
	v_cvt_pk_bf16_f32 v81, v94, v95
	v_pk_fma_f32 v[110:111], v[142:143], v[160:161], v[110:111] op_sel_hi:[1,0,1]
	v_pk_fma_f32 v[108:109], v[140:141], v[160:161], v[108:109] op_sel_hi:[1,0,1]
	v_cvt_pk_bf16_f32 v82, v88, v89
	v_cvt_pk_bf16_f32 v83, v90, v91
	global_store_dwordx4 v[174:175], v[80:83], off offset:2304
	v_pk_fma_f32 v[102:103], v[138:139], v[160:161], v[102:103] op_sel_hi:[1,0,1]
	v_pk_fma_f32 v[100:101], v[136:137], v[160:161], v[100:101] op_sel_hi:[1,0,1]
	v_cvt_pk_bf16_f32 v80, v108, v109
	v_cvt_pk_bf16_f32 v81, v110, v111
	v_pk_fma_f32 v[86:87], v[134:135], v[160:161], v[86:87] op_sel_hi:[1,0,1]
	v_pk_fma_f32 v[84:85], v[132:133], v[160:161], v[84:85] op_sel_hi:[1,0,1]
	v_cvt_pk_bf16_f32 v82, v100, v101
	v_cvt_pk_bf16_f32 v83, v102, v103
	global_store_dwordx4 v[176:177], v[80:83], off offset:2048
	v_pk_fma_f32 v[76:77], v[140:141], v[160:161], v[76:77] op_sel_hi:[1,0,1]
	v_pk_fma_f32 v[78:79], v[142:143], v[160:161], v[78:79] op_sel_hi:[1,0,1]
	v_cvt_pk_bf16_f32 v80, v84, v85
	v_cvt_pk_bf16_f32 v81, v86, v87
	v_cvt_pk_bf16_f32 v82, v180, v181
	v_cvt_pk_bf16_f32 v83, v178, v179
	global_store_dwordx4 v[176:177], v[80:83], off offset:2304
	v_pk_fma_f32 v[70:71], v[134:135], v[160:161], v[70:71] op_sel_hi:[1,0,1]
	v_pk_fma_f32 v[68:69], v[132:133], v[160:161], v[68:69] op_sel_hi:[1,0,1]
	v_pk_fma_f32 v[80:81], v[138:139], v[160:161], v[74:75] op_sel_hi:[1,0,1]
	v_pk_fma_f32 v[74:75], v[136:137], v[160:161], v[72:73] op_sel_hi:[1,0,1]
	v_cvt_pk_bf16_f32 v72, v76, v77
	v_mad_i64_i32 v[76:77], s[14:15], v182, s37, v[162:163]
	v_cvt_pk_bf16_f32 v73, v78, v79
; __device__ __forceinline__ unsigned cvt_pk_bf16(float lo, float hi) { unsigned r; asm volatile("v_cvt_pk_bf16_f32 %0, %1, %2" : "=v"(r) : "v"(lo), "v"(hi)); return r; }
; #define PG8_WAIT_V(n) asm volatile("s_waitcnt vmcnt(" #n ")" ::: "memory")
; #define PG8_BAR __builtin_amdgcn_s_barrier()
; template <class Epi, class Sched>
; __device__ __forceinline__ void gemm_phase(LAS unsigned char* lds, const Gemm g, const Sched& S, const Epi& E) {
;     ...
;         E(acc, cur, wr, wc, fr, fq);
;         if (!has_next) break;
; #pragma unroll
;         for (int a = 0; a < 2; ++a)
; #pragma unroll
;             for (int b = 0; b < 2; ++b)
; #pragma unroll
;                 for (int m = 0; m < 4; ++m)
; #pragma unroll
;                     for (int n = 0; n < 2; ++n) acc[a][b][m][n] = (f32x4){0.f, 0.f, 0.f, 0.f};
;         cur = nxt; cA = nA; cB = nB; ++ui;
;     }
;     PG8_WAIT_V(0);
;     if (wr == 0) PG8_BAR;
;     PG8_BAR;
;     __device__ __forceinline__ void operator()(const AccT& acc, const Unit& u, int wr, int wc, int fr, int fq) const {
;     ...
;             for (int m = 0; m < 4; ++m) {
;                 const int k = row0 + ai * 128 + m * 16;
; #pragma unroll
;                 for (int bj = 0; bj < 2; ++bj) {
;                     const f32x4 v0 = acc[ai][bj][m][0] + yh[bj][0], v1 = acc[ai][bj][m][1] + yh[bj][1];
;                     u32x4 w; w.x = cvt_pk_bf16(v0[0], v0[1]); w.y = cvt_pk_bf16(v0[2], v0[3]); w.z = cvt_pk_bf16(v1[0], v1[1]); w.w = cvt_pk_bf16(v1[2], v1[3]);
;                     *(u32x4*)(CAT + (size_t)(b * 2048 + k) * CATW + 1024 + ch0 + bj * 128) = w;
;                 }
	v_lshl_add_u64 v[76:77], v[76:77], 0, v[164:165]
	v_cvt_pk_bf16_f32 v74, v74, v75
	v_cvt_pk_bf16_f32 v75, v80, v81
	global_store_dwordx4 v[76:77], v[72:75], off offset:2048
	v_pk_fma_f32 v[60:61], v[140:141], v[160:161], v[60:61] op_sel_hi:[1,0,1]
	v_pk_fma_f32 v[62:63], v[142:143], v[160:161], v[62:63] op_sel_hi:[1,0,1]
	v_pk_fma_f32 v[72:73], v[130:131], v[160:161], v[66:67] op_sel_hi:[1,0,1]
	v_pk_fma_f32 v[66:67], v[128:129], v[160:161], v[64:65] op_sel_hi:[1,0,1]
	v_cvt_pk_bf16_f32 v64, v68, v69
	v_cvt_pk_bf16_f32 v65, v70, v71
	v_pk_fma_f32 v[54:55], v[134:135], v[160:161], v[54:55] op_sel_hi:[1,0,1]
	v_cvt_pk_bf16_f32 v66, v66, v67
	v_cvt_pk_bf16_f32 v67, v72, v73
	global_store_dwordx4 v[76:77], v[64:67], off offset:2304
	v_pk_fma_f32 v[52:53], v[132:133], v[160:161], v[52:53] op_sel_hi:[1,0,1]
	v_pk_fma_f32 v[38:39], v[134:135], v[160:161], v[38:39] op_sel_hi:[1,0,1]
	v_add_u32_e32 v66, 0x80, v171
	v_pk_fma_f32 v[64:65], v[138:139], v[160:161], v[58:59] op_sel_hi:[1,0,1]
	v_pk_fma_f32 v[58:59], v[136:137], v[160:161], v[56:57] op_sel_hi:[1,0,1]
	v_cvt_pk_bf16_f32 v56, v60, v61
	v_mad_i64_i32 v[60:61], s[14:15], v66, s37, v[162:163]
	v_cvt_pk_bf16_f32 v57, v62, v63
	v_lshl_add_u64 v[60:61], v[60:61], 0, v[164:165]
	v_cvt_pk_bf16_f32 v58, v58, v59
	v_cvt_pk_bf16_f32 v59, v64, v65
	global_store_dwordx4 v[60:61], v[56:59], off offset:2048
	v_pk_fma_f32 v[36:37], v[132:133], v[160:161], v[36:37] op_sel_hi:[1,0,1]
	v_pk_fma_f32 v[22:23], v[134:135], v[160:161], v[22:23] op_sel_hi:[1,0,1]
	v_pk_fma_f32 v[56:57], v[130:131], v[160:161], v[46:47] op_sel_hi:[1,0,1]
	v_pk_fma_f32 v[46:47], v[128:129], v[160:161], v[44:45] op_sel_hi:[1,0,1]
	v_cvt_pk_bf16_f32 v44, v52, v53
	v_cvt_pk_bf16_f32 v45, v54, v55
	v_add_u32_e32 v52, 0x90, v171
	v_cvt_pk_bf16_f32 v46, v46, v47
	v_cvt_pk_bf16_f32 v47, v56, v57
	global_store_dwordx4 v[60:61], v[44:47], off offset:2304
	v_pk_fma_f32 v[20:21], v[132:133], v[160:161], v[20:21] op_sel_hi:[1,0,1]
	v_pk_fma_f32 v[6:7], v[134:135], v[160:161], v[6:7] op_sel_hi:[1,0,1]
	v_pk_fma_f32 v[44:45], v[142:143], v[160:161], v[50:51] op_sel_hi:[1,0,1]
	v_pk_fma_f32 v[46:47], v[140:141], v[160:161], v[48:49] op_sel_hi:[1,0,1]
	v_pk_fma_f32 v[48:49], v[138:139], v[160:161], v[42:43] op_sel_hi:[1,0,1]
	v_pk_fma_f32 v[42:43], v[136:137], v[160:161], v[40:41] op_sel_hi:[1,0,1]
	v_cvt_pk_bf16_f32 v40, v46, v47
	v_cvt_pk_bf16_f32 v41, v44, v45
	v_mad_i64_i32 v[44:45], s[14:15], v52, s37, v[162:163]
	v_lshl_add_u64 v[44:45], v[44:45], 0, v[164:165]
	v_cvt_pk_bf16_f32 v42, v42, v43
	v_cvt_pk_bf16_f32 v43, v48, v49
	global_store_dwordx4 v[44:45], v[40:43], off offset:2048
	v_pk_fma_f32 v[4:5], v[132:133], v[160:161], v[4:5] op_sel_hi:[1,0,1]
	s_nop 0
	v_pk_fma_f32 v[40:41], v[130:131], v[160:161], v[30:31] op_sel_hi:[1,0,1]
	v_pk_fma_f32 v[30:31], v[128:129], v[160:161], v[28:29] op_sel_hi:[1,0,1]
	v_cvt_pk_bf16_f32 v28, v36, v37
	v_cvt_pk_bf16_f32 v29, v38, v39
	v_add_u32_e32 v36, 0xa0, v171
	v_cvt_pk_bf16_f32 v30, v30, v31
	v_cvt_pk_bf16_f32 v31, v40, v41
	global_store_dwordx4 v[44:45], v[28:31], off offset:2304
	s_nop 1
	v_pk_fma_f32 v[28:29], v[142:143], v[160:161], v[34:35] op_sel_hi:[1,0,1]
	v_pk_fma_f32 v[30:31], v[140:141], v[160:161], v[32:33] op_sel_hi:[1,0,1]
	v_pk_fma_f32 v[32:33], v[138:139], v[160:161], v[26:27] op_sel_hi:[1,0,1]
	v_pk_fma_f32 v[26:27], v[136:137], v[160:161], v[24:25] op_sel_hi:[1,0,1]
	v_cvt_pk_bf16_f32 v24, v30, v31
	v_cvt_pk_bf16_f32 v25, v28, v29
	v_mad_i64_i32 v[28:29], s[14:15], v36, s37, v[162:163]
	v_lshl_add_u64 v[28:29], v[28:29], 0, v[164:165]
	v_cvt_pk_bf16_f32 v26, v26, v27
	v_cvt_pk_bf16_f32 v27, v32, v33
	global_store_dwordx4 v[28:29], v[24:27], off offset:2048
	s_nop 1
	v_pk_fma_f32 v[24:25], v[130:131], v[160:161], v[14:15] op_sel_hi:[1,0,1]
	v_pk_fma_f32 v[14:15], v[128:129], v[160:161], v[12:13] op_sel_hi:[1,0,1]
	v_cvt_pk_bf16_f32 v12, v20, v21
	v_cvt_pk_bf16_f32 v13, v22, v23
	v_add_u32_e32 v20, 0xb0, v171
	v_cvt_pk_bf16_f32 v14, v14, v15
	v_cvt_pk_bf16_f32 v15, v24, v25
	global_store_dwordx4 v[28:29], v[12:15], off offset:2304
	s_nop 1
	v_pk_fma_f32 v[12:13], v[142:143], v[160:161], v[18:19] op_sel_hi:[1,0,1]
	v_pk_fma_f32 v[14:15], v[140:141], v[160:161], v[16:17] op_sel_hi:[1,0,1]
	v_pk_fma_f32 v[16:17], v[138:139], v[160:161], v[10:11] op_sel_hi:[1,0,1]
	v_pk_fma_f32 v[10:11], v[136:137], v[160:161], v[8:9] op_sel_hi:[1,0,1]
	v_cvt_pk_bf16_f32 v8, v14, v15
	v_cvt_pk_bf16_f32 v9, v12, v13
	v_mad_i64_i32 v[12:13], s[14:15], v20, s37, v[162:163]
	v_lshl_add_u64 v[12:13], v[12:13], 0, v[164:165]
	v_cvt_pk_bf16_f32 v10, v10, v11
	v_cvt_pk_bf16_f32 v11, v16, v17
	global_store_dwordx4 v[12:13], v[8:11], off offset:2048
	s_mov_b64 s[14:15], s[8:9]
	s_nop 0
	v_pk_fma_f32 v[8:9], v[130:131], v[160:161], v[2:3] op_sel_hi:[1,0,1]
	v_pk_fma_f32 v[2:3], v[128:129], v[160:161], v[0:1] op_sel_hi:[1,0,1]
	v_cvt_pk_bf16_f32 v0, v4, v5
	v_cvt_pk_bf16_f32 v1, v6, v7
	s_nop 0
	v_cvt_pk_bf16_f32 v2, v2, v3
	v_cvt_pk_bf16_f32 v3, v8, v9
	global_store_dwordx4 v[12:13], v[0:3], off offset:2304
	s_cbranch_vccz .LBB0_819
	s_waitcnt vmcnt(0)
	s_cmpk_gt_u32 s20, 0xff
	s_cbranch_scc1 .LBB0_830
	s_barrier

; #define PG8_STAGE(bufoff, gbase, voff) do { _Pragma("unroll") for (int _i = 0; _i < 2; ++_i) \
;         __builtin_amdgcn_global_load_lds((const unsigned*)((const char*)(gbase) + (voff)[_i]), (LAS unsigned*)(lds + (bufoff) + ldsw + _i * 8192), 16, 0, 0); } while (0)
; #define PG8_LDA(dst, b, h) do { _Pragma("unroll") for (int m = 0; m < 4; ++m) _Pragma("unroll") for (int k = 0; k < 2; ++k) dst[m][k] = *(const LAS bf16x8*)(lds + PG8_SA(b, h) + aoff + m * 2048 + k * 1024); } while (0)
; #define PG8_LDB(dst, b, h) do { _Pragma("unroll") for (int n = 0; n < 2; ++n) _Pragma("unroll") for (int k = 0; k < 2; ++k) dst[n][k] = *(const LAS bf16x8*)(lds + PG8_SB(b, h) + boff + n * 2048 + k * 1024); } while (0)
; #define PG8_MMA(ai, bj, At, Bt) do { __builtin_amdgcn_s_setprio(1); _Pragma("unroll") for (int m = 0; m < 4; ++m) _Pragma("unroll") for (int n = 0; n < 2; ++n) _Pragma("unroll") for (int k = 0; k < 2; ++k) \
;         acc[ai][bj][m][n] = __builtin_amdgcn_mfma_f32_16x16x32_bf16(Bt[n][k], At[m][k], acc[ai][bj][m][n], 0, 0, 0); __builtin_amdgcn_s_setprio(0); } while (0)
; #define PG8_WAIT_V(n) asm volatile("s_waitcnt vmcnt(" #n ")" ::: "memory")
; #define PG8_WAIT_L(n) asm volatile("s_waitcnt lgkmcnt(" #n ")" ::: "memory")
; template <class Epi, class Sched>
; __device__ __forceinline__ void gemm_phase(LAS unsigned char* lds, const Gemm g, const Sched& S, const Epi& E) {
;     ...
;         for (int t = 0; t < nt; t += 2) {
;             const bool last = (t == nt - 2);
;             const char* a1 = cA + (size_t)(t + 1) * kstep;
;             const char* a2 = last ? nA : cA + (size_t)(t + 2) * kstep; const char* b2 = last ? nB : cB + (size_t)(t + 2) * kstep;
;             const char* a3 = a2 + kstep; const char* b3 = b2 + kstep;
;             PG8_LDB(B0, 0, 0); PG8_SCHED; PG8_LDA(At, 0, 0); PG8_STAGE(PG8_SA(1, 1), a1 + hstep, voffA);
;             PG8_WAIT_L(8); PG8_BAR; PG8_WAIT_L(0); PG8_MMA(0, 0, At, B0); PG8_BAR; PG8_SCHED;
;             PG8_LDB(B1, 0, 1); PG8_STAGE(PG8_SB(0, 0), b2, voffB);
;             PG8_BAR; PG8_WAIT_L(0); PG8_MMA(0, 1, At, B1); PG8_BAR;
;             PG8_LDA(At, 0, 1); PG8_STAGE(PG8_SA(0, 0), a2, voffA);
;             PG8_BAR; PG8_WAIT_L(0); PG8_MMA(1, 0, At, B0); PG8_BAR; PG8_SCHED;
;             PG8_STAGE(PG8_SB(0, 1), b2 + hstep, voffB);
;             PG8_WAIT_V(6); PG8_BAR; PG8_MMA(1, 1, At, B1); PG8_BAR;
.LBB0_901:
	s_add_u32 s56, s26, 0x100
	s_addc_u32 s57, s27, 0
	s_mov_b32 s58, -2
	s_waitcnt vmcnt(0)
	ds_read_b128 v[128:131], v237
	ds_read_b128 v[132:135], v237 offset:1024
	ds_read_b128 v[136:139], v237 offset:2048
	ds_read_b128 v[140:143], v237 offset:3072
	s_add_u32 s26, s24, 0x100
	s_addc_u32 s27, s25, 0
	s_cmp_eq_u32 s58, 20
	s_cselect_b32 s31, s5, s27
	s_cselect_b32 s30, s4, s26
	s_cselect_b32 s29, s7, s57
	s_cselect_b32 s28, s6, s56
	v_lshl_add_u64 v[176:177], s[24:25], 0, v[210:211]
	s_add_i32 m0, s38, 0xc000
	ds_read_b128 v[144:147], v238
	ds_read_b128 v[148:151], v238 offset:1024
	ds_read_b128 v[152:155], v238 offset:2048
	ds_read_b128 v[156:159], v238 offset:3072
	ds_read_b128 v[160:163], v238 offset:4096
	ds_read_b128 v[164:167], v238 offset:5120
	ds_read_b128 v[168:171], v238 offset:6144
	ds_read_b128 v[172:175], v238 offset:7168
	global_load_lds_dwordx4 v[176:177], off
	v_lshl_add_u64 v[176:177], s[24:25], 0, v[212:213]
	s_add_i32 m0, s38, 0xe000
	s_nop 0
	global_load_lds_dwordx4 v[176:177], off
	s_waitcnt lgkmcnt(8)
	s_waitcnt vmcnt(8)
	s_setprio 1
	s_barrier
	s_waitcnt lgkmcnt(0)
	v_mfma_f32_16x16x32_bf16 v[124:127], v[128:131], v[144:147], 0
	v_mfma_f32_16x16x32_bf16 v[120:123], v[136:139], v[144:147], 0
	v_mfma_f32_16x16x32_bf16 v[108:111], v[128:131], v[152:155], 0
	v_mfma_f32_16x16x32_bf16 v[104:107], v[136:139], v[152:155], 0
	v_mfma_f32_16x16x32_bf16 v[92:95], v[128:131], v[160:163], 0
	v_mfma_f32_16x16x32_bf16 v[88:91], v[136:139], v[160:163], 0
	v_mfma_f32_16x16x32_bf16 v[76:79], v[128:131], v[168:171], 0
	v_mfma_f32_16x16x32_bf16 v[72:75], v[136:139], v[168:171], 0
	v_mfma_f32_16x16x32_bf16 v[124:127], v[132:135], v[148:151], v[124:127]
	v_mfma_f32_16x16x32_bf16 v[120:123], v[140:143], v[148:151], v[120:123]
	v_mfma_f32_16x16x32_bf16 v[108:111], v[132:135], v[156:159], v[108:111]
	v_mfma_f32_16x16x32_bf16 v[104:107], v[140:143], v[156:159], v[104:107]
	v_mfma_f32_16x16x32_bf16 v[92:95], v[132:135], v[164:167], v[92:95]
	v_mfma_f32_16x16x32_bf16 v[88:91], v[140:143], v[164:167], v[88:91]
	v_mfma_f32_16x16x32_bf16 v[76:79], v[132:135], v[172:175], v[76:79]
	v_mfma_f32_16x16x32_bf16 v[72:75], v[140:143], v[172:175], v[72:75]
	s_barrier
	s_setprio 0
	s_add_i32 s24, s50, s37
	s_mov_b32 m0, s24
	ds_read_b128 v[176:179], v239
	ds_read_b128 v[180:183], v239 offset:1024
	ds_read_b128 v[184:187], v239 offset:2048
	ds_read_b128 v[188:191], v239 offset:3072
	global_load_lds_dwordx4 v204, s[28:29]
	s_add_i32 m0, s24, 0x2000
	s_nop 0
	global_load_lds_dwordx4 v208, s[28:29]
	s_waitcnt vmcnt(8)
	s_setprio 1
	s_barrier
	s_waitcnt lgkmcnt(0)
	v_mfma_f32_16x16x32_bf16 v[116:119], v[176:179], v[144:147], 0
	v_mfma_f32_16x16x32_bf16 v[112:115], v[184:187], v[144:147], 0
	v_mfma_f32_16x16x32_bf16 v[100:103], v[176:179], v[152:155], 0
	v_mfma_f32_16x16x32_bf16 v[96:99], v[184:187], v[152:155], 0
	v_mfma_f32_16x16x32_bf16 v[84:87], v[176:179], v[160:163], 0
	v_mfma_f32_16x16x32_bf16 v[80:83], v[184:187], v[160:163], 0
	v_mfma_f32_16x16x32_bf16 v[68:71], v[176:179], v[168:171], 0
	v_mfma_f32_16x16x32_bf16 v[64:67], v[184:187], v[168:171], 0
	v_mfma_f32_16x16x32_bf16 v[116:119], v[180:183], v[148:151], v[116:119]
	v_mfma_f32_16x16x32_bf16 v[112:115], v[188:191], v[148:151], v[112:115]
	v_mfma_f32_16x16x32_bf16 v[100:103], v[180:183], v[156:159], v[100:103]
	v_mfma_f32_16x16x32_bf16 v[96:99], v[188:191], v[156:159], v[96:99]
	v_mfma_f32_16x16x32_bf16 v[84:87], v[180:183], v[164:167], v[84:87]
	v_mfma_f32_16x16x32_bf16 v[80:83], v[188:191], v[164:167], v[80:83]
	v_mfma_f32_16x16x32_bf16 v[68:71], v[180:183], v[172:175], v[68:71]
	v_mfma_f32_16x16x32_bf16 v[64:67], v[188:191], v[172:175], v[64:67]
	s_mov_b32 m0, s38
	v_lshl_add_u64 v[196:197], s[30:31], 0, v[202:203]
	s_barrier
	s_setprio 0
	ds_read_b128 v[144:147], v238 offset:16384
	ds_read_b128 v[148:151], v238 offset:17408
	ds_read_b128 v[152:155], v238 offset:18432
	ds_read_b128 v[156:159], v238 offset:19456
	ds_read_b128 v[160:163], v238 offset:20480
	ds_read_b128 v[164:167], v238 offset:21504
	ds_read_b128 v[168:171], v238 offset:22528
	ds_read_b128 v[172:175], v238 offset:23552
	global_load_lds_dwordx4 v202, s[30:31]
	v_lshl_add_u64 v[198:199], s[30:31], 0, v[206:207]
	s_mov_b32 m0, s39
	s_nop 0
	global_load_lds_dwordx4 v206, s[30:31]
	s_setprio 1
	s_barrier
	s_waitcnt lgkmcnt(0)
	v_mfma_f32_16x16x32_bf16 v[60:63], v[128:131], v[144:147], 0
	v_mfma_f32_16x16x32_bf16 v[56:59], v[136:139], v[144:147], 0
	v_mfma_f32_16x16x32_bf16 v[44:47], v[128:131], v[152:155], 0
	v_mfma_f32_16x16x32_bf16 v[40:43], v[136:139], v[152:155], 0
	v_mfma_f32_16x16x32_bf16 v[28:31], v[128:131], v[160:163], 0
	v_mfma_f32_16x16x32_bf16 v[24:27], v[136:139], v[160:163], 0
	v_mfma_f32_16x16x32_bf16 v[12:15], v[128:131], v[168:171], 0
	v_mfma_f32_16x16x32_bf16 v[8:11], v[136:139], v[168:171], 0
	v_mfma_f32_16x16x32_bf16 v[60:63], v[132:135], v[148:151], v[60:63]
	v_mfma_f32_16x16x32_bf16 v[56:59], v[140:143], v[148:151], v[56:59]
	v_mfma_f32_16x16x32_bf16 v[44:47], v[132:135], v[156:159], v[44:47]
	v_mfma_f32_16x16x32_bf16 v[40:43], v[140:143], v[156:159], v[40:43]
	v_mfma_f32_16x16x32_bf16 v[28:31], v[132:135], v[164:167], v[28:31]
	v_mfma_f32_16x16x32_bf16 v[24:27], v[140:143], v[164:167], v[24:27]
	v_mfma_f32_16x16x32_bf16 v[12:15], v[132:135], v[172:175], v[12:15]
	v_mfma_f32_16x16x32_bf16 v[8:11], v[140:143], v[172:175], v[8:11]
	s_barrier
	s_setprio 0
	s_add_u32 s24, s28, 0x60000
	s_addc_u32 s25, s29, 0
	s_add_i32 s59, s51, s37
	s_mov_b32 m0, s59
	s_nop 0
	global_load_lds_dwordx4 v204, s[24:25]
	s_add_i32 m0, s59, 0x2000
	s_nop 0
	global_load_lds_dwordx4 v208, s[24:25]
	s_add_u32 s24, s30, 0x60000
	s_addc_u32 s25, s31, 0
	s_mov_b32 m0, s40
	s_nop 0
	global_load_lds_dwordx4 v202, s[24:25]
	s_mov_b32 m0, s41
	s_nop 0
	global_load_lds_dwordx4 v206, s[24:25]
	s_waitcnt vmcnt(10)
	s_setprio 1
	s_barrier
; #define PG8_STAGE(bufoff, gbase, voff) do { _Pragma("unroll") for (int _i = 0; _i < 2; ++_i) \
;         __builtin_amdgcn_global_load_lds((const unsigned*)((const char*)(gbase) + (voff)[_i]), (LAS unsigned*)(lds + (bufoff) + ldsw + _i * 8192), 16, 0, 0); } while (0)
; #define PG8_LDA(dst, b, h) do { _Pragma("unroll") for (int m = 0; m < 4; ++m) _Pragma("unroll") for (int k = 0; k < 2; ++k) dst[m][k] = *(const LAS bf16x8*)(lds + PG8_SA(b, h) + aoff + m * 2048 + k * 1024); } while (0)
; #define PG8_LDB(dst, b, h) do { _Pragma("unroll") for (int n = 0; n < 2; ++n) _Pragma("unroll") for (int k = 0; k < 2; ++k) dst[n][k] = *(const LAS bf16x8*)(lds + PG8_SB(b, h) + boff + n * 2048 + k * 1024); } while (0)
; #define PG8_MMA(ai, bj, At, Bt) do { __builtin_amdgcn_s_setprio(1); _Pragma("unroll") for (int m = 0; m < 4; ++m) _Pragma("unroll") for (int n = 0; n < 2; ++n) _Pragma("unroll") for (int k = 0; k < 2; ++k) \
;         acc[ai][bj][m][n] = __builtin_amdgcn_mfma_f32_16x16x32_bf16(Bt[n][k], At[m][k], acc[ai][bj][m][n], 0, 0, 0); __builtin_amdgcn_s_setprio(0); } while (0)
; #define PG8_WAIT_V(n) asm volatile("s_waitcnt vmcnt(" #n ")" ::: "memory")
; #define PG8_WAIT_L(n) asm volatile("s_waitcnt lgkmcnt(" #n ")" ::: "memory")
; #define PG8_BAR __builtin_amdgcn_s_barrier()
; #define PG8_SCHED __builtin_amdgcn_sched_barrier(0)
; template <class Epi, class Sched>
; __device__ __forceinline__ void gemm_phase(LAS unsigned char* lds, const Gemm g, const Sched& S, const Epi& E) {
;     ...
;             PG8_BAR; PG8_WAIT_L(0); PG8_MMA(1, 0, At, B0); PG8_BAR; PG8_SCHED;
;             PG8_STAGE(PG8_SB(0, 1), b2 + hstep, voffB);
;             PG8_WAIT_V(6); PG8_BAR; PG8_MMA(1, 1, At, B1); PG8_BAR;
;             PG8_LDB(B0, 1, 0); PG8_SCHED; PG8_LDA(At, 1, 0); PG8_STAGE(PG8_SA(0, 1), a2 + hstep, voffA);
;             PG8_WAIT_L(8); PG8_BAR; PG8_WAIT_L(0); PG8_MMA(0, 0, At, B0); PG8_BAR; PG8_SCHED;
;             PG8_LDB(B1, 1, 1); PG8_STAGE(PG8_SB(1, 0), b3, voffB);
;             PG8_BAR; PG8_WAIT_L(0); PG8_MMA(0, 1, At, B1); PG8_BAR;
;             PG8_LDA(At, 1, 1); PG8_STAGE(PG8_SA(1, 0), a3, voffA);
;             PG8_BAR; PG8_WAIT_L(0); PG8_MMA(1, 0, At, B0); PG8_BAR; PG8_SCHED;
	v_mfma_f32_16x16x32_bf16 v[52:55], v[176:179], v[144:147], 0
	v_mfma_f32_16x16x32_bf16 v[48:51], v[184:187], v[144:147], 0
	v_mfma_f32_16x16x32_bf16 v[36:39], v[176:179], v[152:155], 0
	v_mfma_f32_16x16x32_bf16 v[32:35], v[184:187], v[152:155], 0
	v_mfma_f32_16x16x32_bf16 v[20:23], v[176:179], v[160:163], 0
	v_mfma_f32_16x16x32_bf16 v[16:19], v[184:187], v[160:163], 0
	v_mfma_f32_16x16x32_bf16 v[4:7], v[176:179], v[168:171], 0
	v_mfma_f32_16x16x32_bf16 v[0:3], v[184:187], v[168:171], 0
	v_mfma_f32_16x16x32_bf16 v[52:55], v[180:183], v[148:151], v[52:55]
	v_mfma_f32_16x16x32_bf16 v[48:51], v[188:191], v[148:151], v[48:51]
	v_mfma_f32_16x16x32_bf16 v[36:39], v[180:183], v[156:159], v[36:39]
	v_mfma_f32_16x16x32_bf16 v[32:35], v[188:191], v[156:159], v[32:35]
	v_mfma_f32_16x16x32_bf16 v[20:23], v[180:183], v[164:167], v[20:23]
	v_mfma_f32_16x16x32_bf16 v[16:19], v[188:191], v[164:167], v[16:19]
	v_mfma_f32_16x16x32_bf16 v[4:7], v[180:183], v[172:175], v[4:7]
	v_mfma_f32_16x16x32_bf16 v[0:3], v[188:191], v[172:175], v[0:3]
	s_add_i32 s59, 0, 0x18000
	v_add_u32_e32 v140, s59, v236
	s_barrier
	s_setprio 0
	ds_read_b128 v[128:131], v140
	ds_read_b128 v[132:135], v140 offset:1024
	ds_read_b128 v[136:139], v140 offset:2048
	ds_read_b128 v[140:143], v140 offset:3072
	ds_read_b128 v[144:147], v238 offset:32768
	ds_read_b128 v[148:151], v238 offset:33792
	ds_read_b128 v[152:155], v238 offset:34816
	ds_read_b128 v[156:159], v238 offset:35840
	ds_read_b128 v[160:163], v238 offset:36864
	ds_read_b128 v[164:167], v238 offset:37888
	ds_read_b128 v[168:171], v238 offset:38912
	ds_read_b128 v[172:175], v238 offset:39936
	s_waitcnt lgkmcnt(8)
	s_waitcnt vmcnt(8)
	s_setprio 1
	s_barrier
	s_waitcnt lgkmcnt(0)
	v_mfma_f32_16x16x32_bf16 v[124:127], v[128:131], v[144:147], v[124:127]
	v_mfma_f32_16x16x32_bf16 v[120:123], v[136:139], v[144:147], v[120:123]
	v_mfma_f32_16x16x32_bf16 v[108:111], v[128:131], v[152:155], v[108:111]
	v_mfma_f32_16x16x32_bf16 v[104:107], v[136:139], v[152:155], v[104:107]
	v_mfma_f32_16x16x32_bf16 v[92:95], v[128:131], v[160:163], v[92:95]
	v_mfma_f32_16x16x32_bf16 v[88:91], v[136:139], v[160:163], v[88:91]
	v_mfma_f32_16x16x32_bf16 v[76:79], v[128:131], v[168:171], v[76:79]
	v_mfma_f32_16x16x32_bf16 v[72:75], v[136:139], v[168:171], v[72:75]
	v_mfma_f32_16x16x32_bf16 v[124:127], v[132:135], v[148:151], v[124:127]
	v_mfma_f32_16x16x32_bf16 v[120:123], v[140:143], v[148:151], v[120:123]
	v_mfma_f32_16x16x32_bf16 v[108:111], v[132:135], v[156:159], v[108:111]
	v_mfma_f32_16x16x32_bf16 v[104:107], v[140:143], v[156:159], v[104:107]
	v_mfma_f32_16x16x32_bf16 v[92:95], v[132:135], v[164:167], v[92:95]
	v_mfma_f32_16x16x32_bf16 v[88:91], v[140:143], v[164:167], v[88:91]
	v_mfma_f32_16x16x32_bf16 v[76:79], v[132:135], v[172:175], v[76:79]
	v_mfma_f32_16x16x32_bf16 v[72:75], v[140:143], v[172:175], v[72:75]
	s_barrier
	s_setprio 0
	s_add_i32 s30, 0, 0x1c000
	s_add_i32 s24, s59, s37
	v_add_u32_e32 v188, s30, v236
	s_add_u32 s0, s28, 0x80
	s_addc_u32 s1, s29, 0
	s_mov_b32 m0, s24
	ds_read_b128 v[176:179], v188
	ds_read_b128 v[180:183], v188 offset:1024
	ds_read_b128 v[184:187], v188 offset:2048
	ds_read_b128 v[188:191], v188 offset:3072
	global_load_lds_dwordx4 v204, s[0:1]
	s_add_i32 m0, s24, 0x2000
	s_nop 0
	global_load_lds_dwordx4 v208, s[0:1]
	s_waitcnt vmcnt(8)
	s_setprio 1
	s_barrier
	s_waitcnt lgkmcnt(0)
	v_mfma_f32_16x16x32_bf16 v[116:119], v[176:179], v[144:147], v[116:119]
	v_mfma_f32_16x16x32_bf16 v[112:115], v[184:187], v[144:147], v[112:115]
	v_mfma_f32_16x16x32_bf16 v[100:103], v[176:179], v[152:155], v[100:103]
	v_mfma_f32_16x16x32_bf16 v[96:99], v[184:187], v[152:155], v[96:99]
	v_mfma_f32_16x16x32_bf16 v[84:87], v[176:179], v[160:163], v[84:87]
	v_mfma_f32_16x16x32_bf16 v[80:83], v[184:187], v[160:163], v[80:83]
	v_mfma_f32_16x16x32_bf16 v[68:71], v[176:179], v[168:171], v[68:71]
	v_mfma_f32_16x16x32_bf16 v[64:67], v[184:187], v[168:171], v[64:67]
	v_mfma_f32_16x16x32_bf16 v[116:119], v[180:183], v[148:151], v[116:119]
	v_mfma_f32_16x16x32_bf16 v[112:115], v[188:191], v[148:151], v[112:115]
	v_mfma_f32_16x16x32_bf16 v[100:103], v[180:183], v[156:159], v[100:103]
	v_mfma_f32_16x16x32_bf16 v[96:99], v[188:191], v[156:159], v[96:99]
	v_mfma_f32_16x16x32_bf16 v[84:87], v[180:183], v[164:167], v[84:87]
	v_mfma_f32_16x16x32_bf16 v[80:83], v[188:191], v[164:167], v[80:83]
	v_mfma_f32_16x16x32_bf16 v[68:71], v[180:183], v[172:175], v[68:71]
	v_mfma_f32_16x16x32_bf16 v[64:67], v[188:191], v[172:175], v[64:67]
	s_mov_b32 m0, s47
	s_mov_b64 s[0:1], 0x80
	v_lshl_add_u64 v[192:193], v[196:197], 0, s[0:1]
	s_barrier
	s_setprio 0
	ds_read_b128 v[144:147], v238 offset:49152
	ds_read_b128 v[148:151], v238 offset:50176
	ds_read_b128 v[152:155], v238 offset:51200
	ds_read_b128 v[156:159], v238 offset:52224
	ds_read_b128 v[160:163], v238 offset:53248
	ds_read_b128 v[164:167], v238 offset:54272
	ds_read_b128 v[168:171], v238 offset:55296
	ds_read_b128 v[172:175], v238 offset:56320
	global_load_lds_dwordx4 v[192:193], off
	v_lshl_add_u64 v[192:193], v[198:199], 0, s[0:1]
	s_mov_b32 m0, s48
	s_nop 0
	global_load_lds_dwordx4 v[192:193], off
	s_setprio 1
	s_barrier
; #define PG8_STAGE(bufoff, gbase, voff) do { _Pragma("unroll") for (int _i = 0; _i < 2; ++_i) \
;         __builtin_amdgcn_global_load_lds((const unsigned*)((const char*)(gbase) + (voff)[_i]), (LAS unsigned*)(lds + (bufoff) + ldsw + _i * 8192), 16, 0, 0); } while (0)
; #define PG8_LDA(dst, b, h) do { _Pragma("unroll") for (int m = 0; m < 4; ++m) _Pragma("unroll") for (int k = 0; k < 2; ++k) dst[m][k] = *(const LAS bf16x8*)(lds + PG8_SA(b, h) + aoff + m * 2048 + k * 1024); } while (0)
; #define PG8_LDB(dst, b, h) do { _Pragma("unroll") for (int n = 0; n < 2; ++n) _Pragma("unroll") for (int k = 0; k < 2; ++k) dst[n][k] = *(const LAS bf16x8*)(lds + PG8_SB(b, h) + boff + n * 2048 + k * 1024); } while (0)
; #define PG8_MMA(ai, bj, At, Bt) do { __builtin_amdgcn_s_setprio(1); _Pragma("unroll") for (int m = 0; m < 4; ++m) _Pragma("unroll") for (int n = 0; n < 2; ++n) _Pragma("unroll") for (int k = 0; k < 2; ++k) \
;         acc[ai][bj][m][n] = __builtin_amdgcn_mfma_f32_16x16x32_bf16(Bt[n][k], At[m][k], acc[ai][bj][m][n], 0, 0, 0); __builtin_amdgcn_s_setprio(0); } while (0)
; #define PG8_WAIT_V(n) asm volatile("s_waitcnt vmcnt(" #n ")" ::: "memory")
; #define PG8_WAIT_L(n) asm volatile("s_waitcnt lgkmcnt(" #n ")" ::: "memory")
; #define PG8_BAR __builtin_amdgcn_s_barrier()
; #define PG8_SCHED __builtin_amdgcn_sched_barrier(0)
; template <class Epi, class Sched>
; __device__ __forceinline__ void gemm_phase(LAS unsigned char* lds, const Gemm g, const Sched& S, const Epi& E) {
;     ...
;             PG8_LDB(B0, 0, 0); PG8_SCHED; PG8_LDA(At, 0, 0); PG8_STAGE(PG8_SA(1, 1), a1 + hstep, voffA);
;             PG8_WAIT_L(8); PG8_BAR; PG8_WAIT_L(0); PG8_MMA(0, 0, At, B0); PG8_BAR; PG8_SCHED;
;             PG8_LDB(B1, 0, 1); PG8_STAGE(PG8_SB(0, 0), b2, voffB);
;             PG8_BAR; PG8_WAIT_L(0); PG8_MMA(0, 1, At, B1); PG8_BAR;
;     ...
;             PG8_BAR; PG8_WAIT_L(0); PG8_MMA(1, 0, At, B0); PG8_BAR; PG8_SCHED;
;             PG8_STAGE(PG8_SB(1, 1), b3 + hstep, voffB);
;             PG8_WAIT_V(6); PG8_BAR; PG8_MMA(1, 1, At, B1); PG8_BAR;
	s_waitcnt lgkmcnt(0)
	v_mfma_f32_16x16x32_bf16 v[60:63], v[128:131], v[144:147], v[60:63]
	v_mfma_f32_16x16x32_bf16 v[56:59], v[136:139], v[144:147], v[56:59]
	v_mfma_f32_16x16x32_bf16 v[44:47], v[128:131], v[152:155], v[44:47]
	v_mfma_f32_16x16x32_bf16 v[40:43], v[136:139], v[152:155], v[40:43]
	v_mfma_f32_16x16x32_bf16 v[28:31], v[128:131], v[160:163], v[28:31]
	v_mfma_f32_16x16x32_bf16 v[24:27], v[136:139], v[160:163], v[24:27]
	v_mfma_f32_16x16x32_bf16 v[12:15], v[128:131], v[168:171], v[12:15]
	v_mfma_f32_16x16x32_bf16 v[8:11], v[136:139], v[168:171], v[8:11]
	v_mfma_f32_16x16x32_bf16 v[60:63], v[132:135], v[148:151], v[60:63]
	v_mfma_f32_16x16x32_bf16 v[56:59], v[140:143], v[148:151], v[56:59]
	v_mfma_f32_16x16x32_bf16 v[44:47], v[132:135], v[156:159], v[44:47]
	v_mfma_f32_16x16x32_bf16 v[40:43], v[140:143], v[156:159], v[40:43]
	v_mfma_f32_16x16x32_bf16 v[28:31], v[132:135], v[164:167], v[28:31]
	v_mfma_f32_16x16x32_bf16 v[24:27], v[140:143], v[164:167], v[24:27]
	v_mfma_f32_16x16x32_bf16 v[12:15], v[132:135], v[172:175], v[12:15]
	v_mfma_f32_16x16x32_bf16 v[8:11], v[140:143], v[172:175], v[8:11]
	s_barrier
	s_setprio 0
	s_add_u32 s24, s28, 0x60080
	s_addc_u32 s25, s29, 0
	s_add_i32 s28, s30, s37
	s_mov_b32 m0, s28
	s_nop 0
	global_load_lds_dwordx4 v204, s[24:25]
	s_add_i32 m0, s28, 0x2000
	s_nop 0
	global_load_lds_dwordx4 v208, s[24:25]
	s_waitcnt vmcnt(8)
	s_setprio 1
	s_barrier
	v_mfma_f32_16x16x32_bf16 v[52:55], v[176:179], v[144:147], v[52:55]
	v_mfma_f32_16x16x32_bf16 v[48:51], v[184:187], v[144:147], v[48:51]
	v_mfma_f32_16x16x32_bf16 v[36:39], v[176:179], v[152:155], v[36:39]
	v_mfma_f32_16x16x32_bf16 v[32:35], v[184:187], v[152:155], v[32:35]
	v_mfma_f32_16x16x32_bf16 v[20:23], v[176:179], v[160:163], v[20:23]
	v_mfma_f32_16x16x32_bf16 v[16:19], v[184:187], v[160:163], v[16:19]
	v_mfma_f32_16x16x32_bf16 v[4:7], v[176:179], v[168:171], v[4:7]
	v_mfma_f32_16x16x32_bf16 v[0:3], v[184:187], v[168:171], v[0:3]
	v_mfma_f32_16x16x32_bf16 v[52:55], v[180:183], v[148:151], v[52:55]
	v_mfma_f32_16x16x32_bf16 v[48:51], v[188:191], v[148:151], v[48:51]
	v_mfma_f32_16x16x32_bf16 v[36:39], v[180:183], v[156:159], v[36:39]
	v_mfma_f32_16x16x32_bf16 v[32:35], v[188:191], v[156:159], v[32:35]
	v_mfma_f32_16x16x32_bf16 v[20:23], v[180:183], v[164:167], v[20:23]
	v_mfma_f32_16x16x32_bf16 v[16:19], v[188:191], v[164:167], v[16:19]
	v_mfma_f32_16x16x32_bf16 v[4:7], v[180:183], v[172:175], v[4:7]
	v_mfma_f32_16x16x32_bf16 v[0:3], v[188:191], v[172:175], v[0:3]
	s_add_i32 s58, s58, 2
	s_add_u32 s56, s56, 0x100
	s_addc_u32 s57, s57, 0
	s_cmp_gt_u32 s58, 21
	s_mov_b64 s[24:25], s[26:27]
	s_barrier
	s_setprio 0
.LBB0_902:
	ds_read_b128 v[128:131], v237
	ds_read_b128 v[132:135], v237 offset:1024
	ds_read_b128 v[136:139], v237 offset:2048
	ds_read_b128 v[140:143], v237 offset:3072
	s_add_u32 s26, s24, 0x100
	s_addc_u32 s27, s25, 0
	s_cmp_eq_u32 s58, 20
	s_cselect_b32 s31, s5, s27
	s_cselect_b32 s30, s4, s26
	s_cselect_b32 s29, s7, s57
	s_cselect_b32 s28, s6, s56
	v_lshl_add_u64 v[176:177], s[24:25], 0, v[210:211]
	s_add_i32 m0, s38, 0xc000
	ds_read_b128 v[144:147], v238
	ds_read_b128 v[148:151], v238 offset:1024
	ds_read_b128 v[152:155], v238 offset:2048
	ds_read_b128 v[156:159], v238 offset:3072
	ds_read_b128 v[160:163], v238 offset:4096
	ds_read_b128 v[164:167], v238 offset:5120
	ds_read_b128 v[168:171], v238 offset:6144
	ds_read_b128 v[172:175], v238 offset:7168
	global_load_lds_dwordx4 v[176:177], off
	v_lshl_add_u64 v[176:177], s[24:25], 0, v[212:213]
	s_add_i32 m0, s38, 0xe000
	s_nop 0
	global_load_lds_dwordx4 v[176:177], off
	s_waitcnt lgkmcnt(8)
	s_waitcnt vmcnt(8)
	s_setprio 1
	s_barrier
	s_waitcnt lgkmcnt(0)
	v_mfma_f32_16x16x32_bf16 v[124:127], v[128:131], v[144:147], v[124:127]
	v_mfma_f32_16x16x32_bf16 v[120:123], v[136:139], v[144:147], v[120:123]
	v_mfma_f32_16x16x32_bf16 v[108:111], v[128:131], v[152:155], v[108:111]
	v_mfma_f32_16x16x32_bf16 v[104:107], v[136:139], v[152:155], v[104:107]
	v_mfma_f32_16x16x32_bf16 v[92:95], v[128:131], v[160:163], v[92:95]
	v_mfma_f32_16x16x32_bf16 v[88:91], v[136:139], v[160:163], v[88:91]
	v_mfma_f32_16x16x32_bf16 v[76:79], v[128:131], v[168:171], v[76:79]
	v_mfma_f32_16x16x32_bf16 v[72:75], v[136:139], v[168:171], v[72:75]
	v_mfma_f32_16x16x32_bf16 v[124:127], v[132:135], v[148:151], v[124:127]
	v_mfma_f32_16x16x32_bf16 v[120:123], v[140:143], v[148:151], v[120:123]
	v_mfma_f32_16x16x32_bf16 v[108:111], v[132:135], v[156:159], v[108:111]
	v_mfma_f32_16x16x32_bf16 v[104:107], v[140:143], v[156:159], v[104:107]
	v_mfma_f32_16x16x32_bf16 v[92:95], v[132:135], v[164:167], v[92:95]
	v_mfma_f32_16x16x32_bf16 v[88:91], v[140:143], v[164:167], v[88:91]
	v_mfma_f32_16x16x32_bf16 v[76:79], v[132:135], v[172:175], v[76:79]
	v_mfma_f32_16x16x32_bf16 v[72:75], v[140:143], v[172:175], v[72:75]
	s_barrier
	s_setprio 0
	s_add_i32 s24, s50, s37
	s_mov_b32 m0, s24
	ds_read_b128 v[176:179], v239
	ds_read_b128 v[180:183], v239 offset:1024
	ds_read_b128 v[184:187], v239 offset:2048
	ds_read_b128 v[188:191], v239 offset:3072
	global_load_lds_dwordx4 v204, s[28:29]
	s_add_i32 m0, s24, 0x2000
	s_nop 0
	global_load_lds_dwordx4 v208, s[28:29]
	s_waitcnt vmcnt(8)
	s_setprio 1
	s_barrier
; #define PG8_STAGE(bufoff, gbase, voff) do { _Pragma("unroll") for (int _i = 0; _i < 2; ++_i) \
;         __builtin_amdgcn_global_load_lds((const unsigned*)((const char*)(gbase) + (voff)[_i]), (LAS unsigned*)(lds + (bufoff) + ldsw + _i * 8192), 16, 0, 0); } while (0)
; #define PG8_LDA(dst, b, h) do { _Pragma("unroll") for (int m = 0; m < 4; ++m) _Pragma("unroll") for (int k = 0; k < 2; ++k) dst[m][k] = *(const LAS bf16x8*)(lds + PG8_SA(b, h) + aoff + m * 2048 + k * 1024); } while (0)
; #define PG8_LDB(dst, b, h) do { _Pragma("unroll") for (int n = 0; n < 2; ++n) _Pragma("unroll") for (int k = 0; k < 2; ++k) dst[n][k] = *(const LAS bf16x8*)(lds + PG8_SB(b, h) + boff + n * 2048 + k * 1024); } while (0)
; #define PG8_MMA(ai, bj, At, Bt) do { __builtin_amdgcn_s_setprio(1); _Pragma("unroll") for (int m = 0; m < 4; ++m) _Pragma("unroll") for (int n = 0; n < 2; ++n) _Pragma("unroll") for (int k = 0; k < 2; ++k) \
;         acc[ai][bj][m][n] = __builtin_amdgcn_mfma_f32_16x16x32_bf16(Bt[n][k], At[m][k], acc[ai][bj][m][n], 0, 0, 0); __builtin_amdgcn_s_setprio(0); } while (0)
; #define PG8_WAIT_V(n) asm volatile("s_waitcnt vmcnt(" #n ")" ::: "memory")
; #define PG8_WAIT_L(n) asm volatile("s_waitcnt lgkmcnt(" #n ")" ::: "memory")
; #define PG8_BAR __builtin_amdgcn_s_barrier()
; #define PG8_SCHED __builtin_amdgcn_sched_barrier(0)
; template <class Epi, class Sched>
; __device__ __forceinline__ void gemm_phase(LAS unsigned char* lds, const Gemm g, const Sched& S, const Epi& E) {
;     ...
;             PG8_BAR; PG8_WAIT_L(0); PG8_MMA(0, 1, At, B1); PG8_BAR;
;             PG8_LDA(At, 0, 1); PG8_STAGE(PG8_SA(0, 0), a2, voffA);
;             PG8_BAR; PG8_WAIT_L(0); PG8_MMA(1, 0, At, B0); PG8_BAR; PG8_SCHED;
;             PG8_STAGE(PG8_SB(0, 1), b2 + hstep, voffB);
;             PG8_WAIT_V(6); PG8_BAR; PG8_MMA(1, 1, At, B1); PG8_BAR;
;             PG8_LDB(B0, 1, 0); PG8_SCHED; PG8_LDA(At, 1, 0); PG8_STAGE(PG8_SA(0, 1), a2 + hstep, voffA);
;             PG8_WAIT_L(8); PG8_BAR; PG8_WAIT_L(0); PG8_MMA(0, 0, At, B0); PG8_BAR; PG8_SCHED;
	s_waitcnt lgkmcnt(0)
	v_mfma_f32_16x16x32_bf16 v[116:119], v[176:179], v[144:147], v[116:119]
	v_mfma_f32_16x16x32_bf16 v[112:115], v[184:187], v[144:147], v[112:115]
	v_mfma_f32_16x16x32_bf16 v[100:103], v[176:179], v[152:155], v[100:103]
	v_mfma_f32_16x16x32_bf16 v[96:99], v[184:187], v[152:155], v[96:99]
	v_mfma_f32_16x16x32_bf16 v[84:87], v[176:179], v[160:163], v[84:87]
	v_mfma_f32_16x16x32_bf16 v[80:83], v[184:187], v[160:163], v[80:83]
	v_mfma_f32_16x16x32_bf16 v[68:71], v[176:179], v[168:171], v[68:71]
	v_mfma_f32_16x16x32_bf16 v[64:67], v[184:187], v[168:171], v[64:67]
	v_mfma_f32_16x16x32_bf16 v[116:119], v[180:183], v[148:151], v[116:119]
	v_mfma_f32_16x16x32_bf16 v[112:115], v[188:191], v[148:151], v[112:115]
	v_mfma_f32_16x16x32_bf16 v[100:103], v[180:183], v[156:159], v[100:103]
	v_mfma_f32_16x16x32_bf16 v[96:99], v[188:191], v[156:159], v[96:99]
	v_mfma_f32_16x16x32_bf16 v[84:87], v[180:183], v[164:167], v[84:87]
	v_mfma_f32_16x16x32_bf16 v[80:83], v[188:191], v[164:167], v[80:83]
	v_mfma_f32_16x16x32_bf16 v[68:71], v[180:183], v[172:175], v[68:71]
	v_mfma_f32_16x16x32_bf16 v[64:67], v[188:191], v[172:175], v[64:67]
	s_mov_b32 m0, s38
	v_lshl_add_u64 v[196:197], s[30:31], 0, v[202:203]
	s_barrier
	s_setprio 0
	ds_read_b128 v[144:147], v238 offset:16384
	ds_read_b128 v[148:151], v238 offset:17408
	ds_read_b128 v[152:155], v238 offset:18432
	ds_read_b128 v[156:159], v238 offset:19456
	ds_read_b128 v[160:163], v238 offset:20480
	ds_read_b128 v[164:167], v238 offset:21504
	ds_read_b128 v[168:171], v238 offset:22528
	ds_read_b128 v[172:175], v238 offset:23552
	global_load_lds_dwordx4 v202, s[30:31]
	v_lshl_add_u64 v[198:199], s[30:31], 0, v[206:207]
	s_mov_b32 m0, s39
	s_nop 0
	global_load_lds_dwordx4 v206, s[30:31]
	s_setprio 1
	s_barrier
	s_waitcnt lgkmcnt(0)
	v_mfma_f32_16x16x32_bf16 v[60:63], v[128:131], v[144:147], v[60:63]
	v_mfma_f32_16x16x32_bf16 v[56:59], v[136:139], v[144:147], v[56:59]
	v_mfma_f32_16x16x32_bf16 v[44:47], v[128:131], v[152:155], v[44:47]
	v_mfma_f32_16x16x32_bf16 v[40:43], v[136:139], v[152:155], v[40:43]
	v_mfma_f32_16x16x32_bf16 v[28:31], v[128:131], v[160:163], v[28:31]
	v_mfma_f32_16x16x32_bf16 v[24:27], v[136:139], v[160:163], v[24:27]
	v_mfma_f32_16x16x32_bf16 v[12:15], v[128:131], v[168:171], v[12:15]
	v_mfma_f32_16x16x32_bf16 v[8:11], v[136:139], v[168:171], v[8:11]
	v_mfma_f32_16x16x32_bf16 v[60:63], v[132:135], v[148:151], v[60:63]
	v_mfma_f32_16x16x32_bf16 v[56:59], v[140:143], v[148:151], v[56:59]
	v_mfma_f32_16x16x32_bf16 v[44:47], v[132:135], v[156:159], v[44:47]
	v_mfma_f32_16x16x32_bf16 v[40:43], v[140:143], v[156:159], v[40:43]
	v_mfma_f32_16x16x32_bf16 v[28:31], v[132:135], v[164:167], v[28:31]
	v_mfma_f32_16x16x32_bf16 v[24:27], v[140:143], v[164:167], v[24:27]
	v_mfma_f32_16x16x32_bf16 v[12:15], v[132:135], v[172:175], v[12:15]
	v_mfma_f32_16x16x32_bf16 v[8:11], v[140:143], v[172:175], v[8:11]
	s_barrier
	s_setprio 0
	s_add_u32 s24, s28, 0x60000
	s_addc_u32 s25, s29, 0
	s_add_i32 s59, s51, s37
	s_mov_b32 m0, s59
	s_nop 0
	global_load_lds_dwordx4 v204, s[24:25]
	s_add_i32 m0, s59, 0x2000
	s_nop 0
	global_load_lds_dwordx4 v208, s[24:25]
	s_add_u32 s24, s30, 0x60000
	s_addc_u32 s25, s31, 0
	s_mov_b32 m0, s40
	s_nop 0
	global_load_lds_dwordx4 v202, s[24:25]
	s_mov_b32 m0, s41
	s_nop 0
	global_load_lds_dwordx4 v206, s[24:25]
	s_waitcnt vmcnt(10)
	s_setprio 1
	s_barrier
	v_mfma_f32_16x16x32_bf16 v[52:55], v[176:179], v[144:147], v[52:55]
	v_mfma_f32_16x16x32_bf16 v[48:51], v[184:187], v[144:147], v[48:51]
	v_mfma_f32_16x16x32_bf16 v[36:39], v[176:179], v[152:155], v[36:39]
	v_mfma_f32_16x16x32_bf16 v[32:35], v[184:187], v[152:155], v[32:35]
	v_mfma_f32_16x16x32_bf16 v[20:23], v[176:179], v[160:163], v[20:23]
	v_mfma_f32_16x16x32_bf16 v[16:19], v[184:187], v[160:163], v[16:19]
	v_mfma_f32_16x16x32_bf16 v[4:7], v[176:179], v[168:171], v[4:7]
	v_mfma_f32_16x16x32_bf16 v[0:3], v[184:187], v[168:171], v[0:3]
	v_mfma_f32_16x16x32_bf16 v[52:55], v[180:183], v[148:151], v[52:55]
	v_mfma_f32_16x16x32_bf16 v[48:51], v[188:191], v[148:151], v[48:51]
	v_mfma_f32_16x16x32_bf16 v[36:39], v[180:183], v[156:159], v[36:39]
	v_mfma_f32_16x16x32_bf16 v[32:35], v[188:191], v[156:159], v[32:35]
	v_mfma_f32_16x16x32_bf16 v[20:23], v[180:183], v[164:167], v[20:23]
	v_mfma_f32_16x16x32_bf16 v[16:19], v[188:191], v[164:167], v[16:19]
	v_mfma_f32_16x16x32_bf16 v[4:7], v[180:183], v[172:175], v[4:7]
	v_mfma_f32_16x16x32_bf16 v[0:3], v[188:191], v[172:175], v[0:3]
	s_add_i32 s59, 0, 0x18000
	v_add_u32_e32 v140, s59, v236
	s_barrier
	s_setprio 0
	ds_read_b128 v[128:131], v140
	ds_read_b128 v[132:135], v140 offset:1024
	ds_read_b128 v[136:139], v140 offset:2048
	ds_read_b128 v[140:143], v140 offset:3072
	ds_read_b128 v[144:147], v238 offset:32768
	ds_read_b128 v[148:151], v238 offset:33792
	ds_read_b128 v[152:155], v238 offset:34816
	ds_read_b128 v[156:159], v238 offset:35840
	ds_read_b128 v[160:163], v238 offset:36864
	ds_read_b128 v[164:167], v238 offset:37888
	ds_read_b128 v[168:171], v238 offset:38912
	ds_read_b128 v[172:175], v238 offset:39936
	s_waitcnt lgkmcnt(8)
	s_waitcnt vmcnt(8)
	s_setprio 1
	s_barrier
; #define PG8_STAGE(bufoff, gbase, voff) do { _Pragma("unroll") for (int _i = 0; _i < 2; ++_i) \
;         __builtin_amdgcn_global_load_lds((const unsigned*)((const char*)(gbase) + (voff)[_i]), (LAS unsigned*)(lds + (bufoff) + ldsw + _i * 8192), 16, 0, 0); } while (0)
; #define PG8_LDA(dst, b, h) do { _Pragma("unroll") for (int m = 0; m < 4; ++m) _Pragma("unroll") for (int k = 0; k < 2; ++k) dst[m][k] = *(const LAS bf16x8*)(lds + PG8_SA(b, h) + aoff + m * 2048 + k * 1024); } while (0)
; #define PG8_LDB(dst, b, h) do { _Pragma("unroll") for (int n = 0; n < 2; ++n) _Pragma("unroll") for (int k = 0; k < 2; ++k) dst[n][k] = *(const LAS bf16x8*)(lds + PG8_SB(b, h) + boff + n * 2048 + k * 1024); } while (0)
; #define PG8_MMA(ai, bj, At, Bt) do { __builtin_amdgcn_s_setprio(1); _Pragma("unroll") for (int m = 0; m < 4; ++m) _Pragma("unroll") for (int n = 0; n < 2; ++n) _Pragma("unroll") for (int k = 0; k < 2; ++k) \
;         acc[ai][bj][m][n] = __builtin_amdgcn_mfma_f32_16x16x32_bf16(Bt[n][k], At[m][k], acc[ai][bj][m][n], 0, 0, 0); __builtin_amdgcn_s_setprio(0); } while (0)
; #define PG8_WAIT_V(n) asm volatile("s_waitcnt vmcnt(" #n ")" ::: "memory")
; #define PG8_WAIT_L(n) asm volatile("s_waitcnt lgkmcnt(" #n ")" ::: "memory")
; #define PG8_BAR __builtin_amdgcn_s_barrier()
; #define PG8_SCHED __builtin_amdgcn_sched_barrier(0)
; template <class Epi, class Sched>
; __device__ __forceinline__ void gemm_phase(LAS unsigned char* lds, const Gemm g, const Sched& S, const Epi& E) {
;     ...
;             PG8_LDA(At, 0, 1); PG8_STAGE(PG8_SA(0, 0), a2, voffA);
;             PG8_BAR; PG8_WAIT_L(0); PG8_MMA(1, 0, At, B0); PG8_BAR; PG8_SCHED;
;             PG8_STAGE(PG8_SB(0, 1), b2 + hstep, voffB);
;             PG8_WAIT_V(6); PG8_BAR; PG8_MMA(1, 1, At, B1); PG8_BAR;
;             PG8_LDB(B0, 1, 0); PG8_SCHED; PG8_LDA(At, 1, 0); PG8_STAGE(PG8_SA(0, 1), a2 + hstep, voffA);
;             PG8_WAIT_L(8); PG8_BAR; PG8_WAIT_L(0); PG8_MMA(0, 0, At, B0); PG8_BAR; PG8_SCHED;
;             PG8_LDB(B1, 1, 1); PG8_STAGE(PG8_SB(1, 0), b3, voffB);
;             PG8_BAR; PG8_WAIT_L(0); PG8_MMA(0, 1, At, B1); PG8_BAR;
;             PG8_LDA(At, 1, 1); PG8_STAGE(PG8_SA(1, 0), a3, voffA);
;             PG8_BAR; PG8_WAIT_L(0); PG8_MMA(1, 0, At, B0); PG8_BAR; PG8_SCHED;
;             PG8_STAGE(PG8_SB(1, 1), b3 + hstep, voffB);
;             PG8_WAIT_V(6); PG8_BAR; PG8_MMA(1, 1, At, B1); PG8_BAR;
	s_waitcnt lgkmcnt(0)
	v_mfma_f32_16x16x32_bf16 v[124:127], v[128:131], v[144:147], v[124:127]
	v_mfma_f32_16x16x32_bf16 v[120:123], v[136:139], v[144:147], v[120:123]
	v_mfma_f32_16x16x32_bf16 v[108:111], v[128:131], v[152:155], v[108:111]
	v_mfma_f32_16x16x32_bf16 v[104:107], v[136:139], v[152:155], v[104:107]
	v_mfma_f32_16x16x32_bf16 v[92:95], v[128:131], v[160:163], v[92:95]
	v_mfma_f32_16x16x32_bf16 v[88:91], v[136:139], v[160:163], v[88:91]
	v_mfma_f32_16x16x32_bf16 v[76:79], v[128:131], v[168:171], v[76:79]
	v_mfma_f32_16x16x32_bf16 v[72:75], v[136:139], v[168:171], v[72:75]
	v_mfma_f32_16x16x32_bf16 v[124:127], v[132:135], v[148:151], v[124:127]
	v_mfma_f32_16x16x32_bf16 v[120:123], v[140:143], v[148:151], v[120:123]
	v_mfma_f32_16x16x32_bf16 v[108:111], v[132:135], v[156:159], v[108:111]
	v_mfma_f32_16x16x32_bf16 v[104:107], v[140:143], v[156:159], v[104:107]
	v_mfma_f32_16x16x32_bf16 v[92:95], v[132:135], v[164:167], v[92:95]
	v_mfma_f32_16x16x32_bf16 v[88:91], v[140:143], v[164:167], v[88:91]
	v_mfma_f32_16x16x32_bf16 v[76:79], v[132:135], v[172:175], v[76:79]
	v_mfma_f32_16x16x32_bf16 v[72:75], v[140:143], v[172:175], v[72:75]
	s_barrier
	s_setprio 0
	s_add_i32 s30, 0, 0x1c000
	s_add_i32 s24, s59, s37
	v_add_u32_e32 v188, s30, v236
	s_add_u32 s0, s28, 0x80
	s_addc_u32 s1, s29, 0
	s_mov_b32 m0, s24
	ds_read_b128 v[176:179], v188
	ds_read_b128 v[180:183], v188 offset:1024
	ds_read_b128 v[184:187], v188 offset:2048
	ds_read_b128 v[188:191], v188 offset:3072
	global_load_lds_dwordx4 v204, s[0:1]
	s_add_i32 m0, s24, 0x2000
	s_nop 0
	global_load_lds_dwordx4 v208, s[0:1]
	s_waitcnt vmcnt(8)
	s_setprio 1
	s_barrier
	s_waitcnt lgkmcnt(0)
	v_mfma_f32_16x16x32_bf16 v[116:119], v[176:179], v[144:147], v[116:119]
	v_mfma_f32_16x16x32_bf16 v[112:115], v[184:187], v[144:147], v[112:115]
	v_mfma_f32_16x16x32_bf16 v[100:103], v[176:179], v[152:155], v[100:103]
	v_mfma_f32_16x16x32_bf16 v[96:99], v[184:187], v[152:155], v[96:99]
	v_mfma_f32_16x16x32_bf16 v[84:87], v[176:179], v[160:163], v[84:87]
	v_mfma_f32_16x16x32_bf16 v[80:83], v[184:187], v[160:163], v[80:83]
	v_mfma_f32_16x16x32_bf16 v[68:71], v[176:179], v[168:171], v[68:71]
	v_mfma_f32_16x16x32_bf16 v[64:67], v[184:187], v[168:171], v[64:67]
	v_mfma_f32_16x16x32_bf16 v[116:119], v[180:183], v[148:151], v[116:119]
	v_mfma_f32_16x16x32_bf16 v[112:115], v[188:191], v[148:151], v[112:115]
	v_mfma_f32_16x16x32_bf16 v[100:103], v[180:183], v[156:159], v[100:103]
	v_mfma_f32_16x16x32_bf16 v[96:99], v[188:191], v[156:159], v[96:99]
	v_mfma_f32_16x16x32_bf16 v[84:87], v[180:183], v[164:167], v[84:87]
	v_mfma_f32_16x16x32_bf16 v[80:83], v[188:191], v[164:167], v[80:83]
	v_mfma_f32_16x16x32_bf16 v[68:71], v[180:183], v[172:175], v[68:71]
	v_mfma_f32_16x16x32_bf16 v[64:67], v[188:191], v[172:175], v[64:67]
	s_mov_b32 m0, s47
	s_mov_b64 s[0:1], 0x80
	v_lshl_add_u64 v[192:193], v[196:197], 0, s[0:1]
	s_barrier
	s_setprio 0
	ds_read_b128 v[144:147], v238 offset:49152
	ds_read_b128 v[148:151], v238 offset:50176
	ds_read_b128 v[152:155], v238 offset:51200
	ds_read_b128 v[156:159], v238 offset:52224
	ds_read_b128 v[160:163], v238 offset:53248
	ds_read_b128 v[164:167], v238 offset:54272
	ds_read_b128 v[168:171], v238 offset:55296
	ds_read_b128 v[172:175], v238 offset:56320
	global_load_lds_dwordx4 v[192:193], off
	v_lshl_add_u64 v[192:193], v[198:199], 0, s[0:1]
	s_mov_b32 m0, s48
	s_nop 0
	global_load_lds_dwordx4 v[192:193], off
	s_setprio 1
	s_barrier
	s_waitcnt lgkmcnt(0)
	v_mfma_f32_16x16x32_bf16 v[60:63], v[128:131], v[144:147], v[60:63]
	v_mfma_f32_16x16x32_bf16 v[56:59], v[136:139], v[144:147], v[56:59]
	v_mfma_f32_16x16x32_bf16 v[44:47], v[128:131], v[152:155], v[44:47]
	v_mfma_f32_16x16x32_bf16 v[40:43], v[136:139], v[152:155], v[40:43]
	v_mfma_f32_16x16x32_bf16 v[28:31], v[128:131], v[160:163], v[28:31]
	v_mfma_f32_16x16x32_bf16 v[24:27], v[136:139], v[160:163], v[24:27]
	v_mfma_f32_16x16x32_bf16 v[12:15], v[128:131], v[168:171], v[12:15]
	v_mfma_f32_16x16x32_bf16 v[8:11], v[136:139], v[168:171], v[8:11]
	v_mfma_f32_16x16x32_bf16 v[60:63], v[132:135], v[148:151], v[60:63]
	v_mfma_f32_16x16x32_bf16 v[56:59], v[140:143], v[148:151], v[56:59]
	v_mfma_f32_16x16x32_bf16 v[44:47], v[132:135], v[156:159], v[44:47]
	v_mfma_f32_16x16x32_bf16 v[40:43], v[140:143], v[156:159], v[40:43]
	v_mfma_f32_16x16x32_bf16 v[28:31], v[132:135], v[164:167], v[28:31]
	v_mfma_f32_16x16x32_bf16 v[24:27], v[140:143], v[164:167], v[24:27]
	v_mfma_f32_16x16x32_bf16 v[12:15], v[132:135], v[172:175], v[12:15]
	v_mfma_f32_16x16x32_bf16 v[8:11], v[140:143], v[172:175], v[8:11]
	s_barrier
	s_setprio 0
	s_add_u32 s24, s28, 0x60080
	s_addc_u32 s25, s29, 0
	s_add_i32 s28, s30, s37
	s_mov_b32 m0, s28
	s_nop 0
	global_load_lds_dwordx4 v204, s[24:25]
	s_add_i32 m0, s28, 0x2000
	s_nop 0
	global_load_lds_dwordx4 v208, s[24:25]
	s_waitcnt vmcnt(8)
	s_setprio 1
	s_barrier
	v_mfma_f32_16x16x32_bf16 v[52:55], v[176:179], v[144:147], v[52:55]
	v_mfma_f32_16x16x32_bf16 v[48:51], v[184:187], v[144:147], v[48:51]
	v_mfma_f32_16x16x32_bf16 v[36:39], v[176:179], v[152:155], v[36:39]
	v_mfma_f32_16x16x32_bf16 v[32:35], v[184:187], v[152:155], v[32:35]
	v_mfma_f32_16x16x32_bf16 v[20:23], v[176:179], v[160:163], v[20:23]
	v_mfma_f32_16x16x32_bf16 v[16:19], v[184:187], v[160:163], v[16:19]
	v_mfma_f32_16x16x32_bf16 v[4:7], v[176:179], v[168:171], v[4:7]
	v_mfma_f32_16x16x32_bf16 v[0:3], v[184:187], v[168:171], v[0:3]
	v_mfma_f32_16x16x32_bf16 v[52:55], v[180:183], v[148:151], v[52:55]
	v_mfma_f32_16x16x32_bf16 v[48:51], v[188:191], v[148:151], v[48:51]
	v_mfma_f32_16x16x32_bf16 v[36:39], v[180:183], v[156:159], v[36:39]
	v_mfma_f32_16x16x32_bf16 v[32:35], v[188:191], v[156:159], v[32:35]
	v_mfma_f32_16x16x32_bf16 v[20:23], v[180:183], v[164:167], v[20:23]
	v_mfma_f32_16x16x32_bf16 v[16:19], v[188:191], v[164:167], v[16:19]
	v_mfma_f32_16x16x32_bf16 v[4:7], v[180:183], v[172:175], v[4:7]
	v_mfma_f32_16x16x32_bf16 v[0:3], v[188:191], v[172:175], v[0:3]
	s_add_i32 s58, s58, 2
	s_add_u32 s56, s56, 0x100
	s_addc_u32 s57, s57, 0
	s_cmp_gt_u32 s58, 21
	s_mov_b64 s[24:25], s[26:27]
	s_barrier
; __device__ __forceinline__ unsigned cvt_pk_bf16(float lo, float hi) { unsigned r; asm volatile("v_cvt_pk_bf16_f32 %0, %1, %2" : "=v"(r) : "v"(lo), "v"(hi)); return r; }
; __device__ __forceinline__ float bf_lo(unsigned u) { return __uint_as_float(u << 16); }
; __device__ __forceinline__ float bf_hi(unsigned u) { return __uint_as_float(u & 0xffff0000u); }
;     __device__ __forceinline__ void operator()(const AccT& acc, const Unit& u, int wr, int wc, int fr, int fq) const {
;     ...
;         const int rowt = u.pm * 256; const int b = rowt >> 11;
;         const bf16_t* res = res_b + (size_t)rowt * DM; bf16_t* out = hb + (size_t)rowt * DM;
;         const int col0 = u.pn * 256 + wc * 32 + 8 * fq;
;         f32x4 gv[2][2];
; #pragma unroll
;         for (int bj = 0; bj < 2; ++bj)
; #pragma unroll
;             for (int n = 0; n < 2; ++n) gv[bj][n] = *(const f32x4*)(gate + (size_t)b * NMOD + col0 + bj * 128 + n * 4) * gs;
;         u32x4 r[2][4][2];
; #pragma unroll
;         for (int ai = 0; ai < 2; ++ai)
; #pragma unroll
;             for (int m = 0; m < 4; ++m)
; #pragma unroll
;                 for (int bj = 0; bj < 2; ++bj) r[ai][m][bj] = *(const u32x4*)(res + (size_t)(wr * 64 + fr + ai * 128 + m * 16) * DM + col0 + bj * 128);
; #pragma unroll
;         for (int ai = 0; ai < 2; ++ai)
; #pragma unroll
;             for (int m = 0; m < 4; ++m)
; #pragma unroll
;                 for (int bj = 0; bj < 2; ++bj) {
;                     const u32x4 q = r[ai][m][bj];
;                     const f32x4 r0 = {bf_lo(q.x), bf_hi(q.x), bf_lo(q.y), bf_hi(q.y)}, r1 = {bf_lo(q.z), bf_hi(q.z), bf_lo(q.w), bf_hi(q.w)};
;                     const f32x4 h0 = r0 + gv[bj][0] * acc[ai][bj][m][0], h1 = r1 + gv[bj][1] * acc[ai][bj][m][1];
;                     u32x4 w; w.x = cvt_pk_bf16(h0[0], h0[1]); w.y = cvt_pk_bf16(h0[2], h0[3]); w.z = cvt_pk_bf16(h1[0], h1[1]); w.w = cvt_pk_bf16(h1[2], h1[3]);
;                     *(u32x4*)(out + (size_t)(wr * 64 + fr + ai * 128 + m * 16) * DM + col0 + bj * 128) = w;
;                 }
	s_setprio 0
	s_cbranch_scc0 .LBB0_902
	s_lshl_b32 s27, s55, 8
	v_mov_b32_e32 v146, v235
	v_mov_b32_e32 v128, v234
	s_lshl_b32 s24, s54, 8
	s_ashr_i32 s26, s54, 3
	s_or_b32 s27, s27, s46
	s_ashr_i32 s25, s24, 31
	v_lshl_add_u32 v144, v128, 3, s27
	s_mul_hi_i32 s27, s26, 0x9000
	s_mul_i32 s26, s26, 0x9000
	s_add_u32 s26, s43, s26
	s_addc_u32 s27, s44, s27
	v_ashrrev_i32_e32 v145, 31, v144
	s_lshl_b64 s[24:25], s[24:25], 11
	v_lshl_add_u64 v[132:133], v[144:145], 2, s[26:27]
	s_add_u32 s26, s62, s24
	v_add_u32_e32 v146, s45, v146
	s_addc_u32 s27, s63, s25
	v_lshlrev_b64 v[222:223], 1, v[144:145]
	v_ashrrev_i32_e32 v147, 31, v146
	v_lshl_add_u64 v[144:145], s[26:27], 0, v[222:223]
	v_lshlrev_b64 v[248:249], 11, v[146:147]
	v_lshl_add_u64 v[146:147], v[144:145], 0, v[248:249]
	global_load_dwordx4 v[136:139], v[132:133], off offset:16
	global_load_dwordx4 v[140:143], v[132:133], off
	global_load_dwordx4 v[128:131], v[132:133], off offset:528
	s_nop 0
	global_load_dwordx4 v[132:135], v[132:133], off offset:512
	s_nop 0
	global_load_dwordx4 v[240:243], v[146:147], off
	global_load_dwordx4 v[244:247], v[146:147], off offset:256
	v_lshl_add_u64 v[232:233], v[248:249], 0, s[10:11]
	v_lshl_add_u64 v[146:147], v[144:145], 0, v[232:233]
	global_load_dwordx4 v[196:199], v[146:147], off
	global_load_dwordx4 v[192:195], v[146:147], off offset:256
	v_lshl_add_u64 v[230:231], v[248:249], 0, s[12:13]
	v_lshl_add_u64 v[146:147], v[144:145], 0, v[230:231]
	global_load_dwordx4 v[188:191], v[146:147], off
	global_load_dwordx4 v[184:187], v[146:147], off offset:256
	v_lshl_add_u64 v[228:229], v[248:249], 0, s[14:15]
	v_lshl_add_u64 v[146:147], v[144:145], 0, v[228:229]
	global_load_dwordx4 v[180:183], v[146:147], off
	global_load_dwordx4 v[176:179], v[146:147], off offset:256
	v_lshl_add_u64 v[226:227], v[248:249], 0, s[16:17]
	v_lshl_add_u64 v[146:147], v[144:145], 0, v[226:227]
	global_load_dwordx4 v[172:175], v[146:147], off
	global_load_dwordx4 v[168:171], v[146:147], off offset:256
	v_lshl_add_u64 v[224:225], v[248:249], 0, s[18:19]
	v_lshl_add_u64 v[146:147], v[144:145], 0, v[224:225]
	global_load_dwordx4 v[164:167], v[146:147], off
	global_load_dwordx4 v[160:163], v[146:147], off offset:256
	v_lshl_add_u64 v[220:221], v[248:249], 0, s[20:21]
	v_lshl_add_u64 v[146:147], v[144:145], 0, v[220:221]
	global_load_dwordx4 v[156:159], v[146:147], off
	global_load_dwordx4 v[152:155], v[146:147], off offset:256
	v_lshl_add_u64 v[218:219], v[248:249], 0, s[22:23]
	v_lshl_add_u64 v[144:145], v[144:145], 0, v[218:219]
	global_load_dwordx4 v[148:151], v[144:145], off
	s_nop 0
	global_load_dwordx4 v[144:147], v[144:145], off offset:256
	s_add_u32 s24, s80, s24
	s_addc_u32 s25, s81, s25
	v_lshl_add_u64 v[222:223], s[24:25], 0, v[222:223]
	v_lshl_add_u64 v[248:249], v[222:223], 0, v[248:249]
	s_and_b64 vcc, exec, s[2:3]
	s_mov_b32 s55, s52
	s_mov_b32 s54, s53
	s_mov_b64 s[26:27], s[6:7]
	s_mov_b64 s[24:25], s[4:5]
	s_waitcnt vmcnt(0)
	v_lshlrev_b32_e32 v250, 16, v240
	v_and_b32_e32 v251, 0xffff0000, v240
	v_lshlrev_b32_e32 v240, 16, v241
	v_and_b32_e32 v241, 0xffff0000, v241
	v_lshlrev_b32_e32 v252, 16, v242
	v_and_b32_e32 v253, 0xffff0000, v242
	v_lshlrev_b32_e32 v242, 16, v243
	v_and_b32_e32 v243, 0xffff0000, v243
	v_pk_fma_f32 v[126:127], v[126:127], v[142:143], v[240:241]
	v_pk_fma_f32 v[124:125], v[124:125], v[140:141], v[250:251]
	v_pk_fma_f32 v[240:241], v[122:123], v[138:139], v[242:243]
	v_pk_fma_f32 v[122:123], v[120:121], v[136:137], v[252:253]
	v_cvt_pk_bf16_f32 v120, v124, v125
	v_cvt_pk_bf16_f32 v121, v126, v127
	v_lshlrev_b32_e32 v124, 16, v246
	v_cvt_pk_bf16_f32 v122, v122, v123
	v_cvt_pk_bf16_f32 v123, v240, v241
	global_store_dwordx4 v[248:249], v[120:123], off
	v_and_b32_e32 v125, 0xffff0000, v246
	v_lshlrev_b32_e32 v126, 16, v247
	v_lshlrev_b32_e32 v120, 16, v244
	v_and_b32_e32 v121, 0xffff0000, v244
	v_and_b32_e32 v127, 0xffff0000, v247
	v_lshlrev_b32_e32 v122, 16, v245
	v_and_b32_e32 v123, 0xffff0000, v245
	v_pk_fma_f32 v[116:117], v[116:117], v[132:133], v[120:121]
	v_pk_fma_f32 v[120:121], v[114:115], v[130:131], v[126:127]
	v_pk_fma_f32 v[114:115], v[112:113], v[128:129], v[124:125]
	v_pk_fma_f32 v[118:119], v[118:119], v[134:135], v[122:123]
	v_cvt_pk_bf16_f32 v112, v116, v117
	v_lshlrev_b32_e32 v116, 16, v197
	v_cvt_pk_bf16_f32 v113, v118, v119
	v_cvt_pk_bf16_f32 v114, v114, v115
	v_cvt_pk_bf16_f32 v115, v120, v121
	global_store_dwordx4 v[248:249], v[112:115], off offset:256
	v_and_b32_e32 v117, 0xffff0000, v197
	v_lshlrev_b32_e32 v118, 16, v198
	v_lshlrev_b32_e32 v114, 16, v196
	v_and_b32_e32 v115, 0xffff0000, v196
	v_and_b32_e32 v119, 0xffff0000, v198
	v_lshlrev_b32_e32 v120, 16, v199
	v_and_b32_e32 v121, 0xffff0000, v199
	v_lshl_add_u64 v[112:113], v[222:223], 0, v[232:233]
	v_pk_fma_f32 v[110:111], v[110:111], v[142:143], v[116:117]
	v_pk_fma_f32 v[108:109], v[108:109], v[140:141], v[114:115]
	v_pk_fma_f32 v[114:115], v[106:107], v[138:139], v[120:121]
	v_pk_fma_f32 v[106:107], v[104:105], v[136:137], v[118:119]
	v_cvt_pk_bf16_f32 v104, v108, v109
	v_cvt_pk_bf16_f32 v105, v110, v111
	v_lshlrev_b32_e32 v108, 16, v194
	v_cvt_pk_bf16_f32 v106, v106, v107
	v_cvt_pk_bf16_f32 v107, v114, v115
	global_store_dwordx4 v[112:113], v[104:107], off
	v_and_b32_e32 v109, 0xffff0000, v194
	v_lshlrev_b32_e32 v110, 16, v195
	v_lshlrev_b32_e32 v104, 16, v192
	v_and_b32_e32 v105, 0xffff0000, v192
	v_and_b32_e32 v111, 0xffff0000, v195
	v_lshlrev_b32_e32 v106, 16, v193
	v_and_b32_e32 v107, 0xffff0000, v193
	v_pk_fma_f32 v[100:101], v[100:101], v[132:133], v[104:105]
	v_pk_fma_f32 v[104:105], v[98:99], v[130:131], v[110:111]
	v_pk_fma_f32 v[98:99], v[96:97], v[128:129], v[108:109]
; __device__ __forceinline__ unsigned cvt_pk_bf16(float lo, float hi) { unsigned r; asm volatile("v_cvt_pk_bf16_f32 %0, %1, %2" : "=v"(r) : "v"(lo), "v"(hi)); return r; }
; __device__ __forceinline__ float bf_lo(unsigned u) { return __uint_as_float(u << 16); }
; __device__ __forceinline__ float bf_hi(unsigned u) { return __uint_as_float(u & 0xffff0000u); }
;     __device__ __forceinline__ void operator()(const AccT& acc, const Unit& u, int wr, int wc, int fr, int fq) const {
;     ...
;         for (int ai = 0; ai < 2; ++ai)
; #pragma unroll
;             for (int m = 0; m < 4; ++m)
; #pragma unroll
;                 for (int bj = 0; bj < 2; ++bj) {
;                     const u32x4 q = r[ai][m][bj];
;                     const f32x4 r0 = {bf_lo(q.x), bf_hi(q.x), bf_lo(q.y), bf_hi(q.y)}, r1 = {bf_lo(q.z), bf_hi(q.z), bf_lo(q.w), bf_hi(q.w)};
;                     const f32x4 h0 = r0 + gv[bj][0] * acc[ai][bj][m][0], h1 = r1 + gv[bj][1] * acc[ai][bj][m][1];
;                     u32x4 w; w.x = cvt_pk_bf16(h0[0], h0[1]); w.y = cvt_pk_bf16(h0[2], h0[3]); w.z = cvt_pk_bf16(h1[0], h1[1]); w.w = cvt_pk_bf16(h1[2], h1[3]);
;                     *(u32x4*)(out + (size_t)(wr * 64 + fr + ai * 128 + m * 16) * DM + col0 + bj * 128) = w;
;                 }
	v_pk_fma_f32 v[102:103], v[102:103], v[134:135], v[106:107]
	v_cvt_pk_bf16_f32 v96, v100, v101
	v_lshlrev_b32_e32 v100, 16, v189
	v_cvt_pk_bf16_f32 v97, v102, v103
	v_cvt_pk_bf16_f32 v98, v98, v99
	v_cvt_pk_bf16_f32 v99, v104, v105
	global_store_dwordx4 v[112:113], v[96:99], off offset:256
	v_and_b32_e32 v101, 0xffff0000, v189
	v_lshlrev_b32_e32 v102, 16, v190
	v_lshlrev_b32_e32 v98, 16, v188
	v_and_b32_e32 v99, 0xffff0000, v188
	v_and_b32_e32 v103, 0xffff0000, v190
	v_lshlrev_b32_e32 v104, 16, v191
	v_and_b32_e32 v105, 0xffff0000, v191
	v_lshl_add_u64 v[96:97], v[222:223], 0, v[230:231]
	v_pk_fma_f32 v[94:95], v[94:95], v[142:143], v[100:101]
	v_pk_fma_f32 v[92:93], v[92:93], v[140:141], v[98:99]
	v_pk_fma_f32 v[98:99], v[90:91], v[138:139], v[104:105]
	v_pk_fma_f32 v[90:91], v[88:89], v[136:137], v[102:103]
	v_cvt_pk_bf16_f32 v88, v92, v93
	v_cvt_pk_bf16_f32 v89, v94, v95
	v_lshlrev_b32_e32 v92, 16, v186
	v_cvt_pk_bf16_f32 v90, v90, v91
	v_cvt_pk_bf16_f32 v91, v98, v99
	global_store_dwordx4 v[96:97], v[88:91], off
	v_and_b32_e32 v93, 0xffff0000, v186
	v_lshlrev_b32_e32 v94, 16, v187
	v_lshlrev_b32_e32 v88, 16, v184
	v_and_b32_e32 v89, 0xffff0000, v184
	v_and_b32_e32 v95, 0xffff0000, v187
	v_lshlrev_b32_e32 v90, 16, v185
	v_and_b32_e32 v91, 0xffff0000, v185
	v_pk_fma_f32 v[84:85], v[84:85], v[132:133], v[88:89]
	v_pk_fma_f32 v[88:89], v[82:83], v[130:131], v[94:95]
	v_pk_fma_f32 v[82:83], v[80:81], v[128:129], v[92:93]
	v_pk_fma_f32 v[86:87], v[86:87], v[134:135], v[90:91]
	v_cvt_pk_bf16_f32 v80, v84, v85
	v_lshlrev_b32_e32 v84, 16, v181
	v_cvt_pk_bf16_f32 v81, v86, v87
	v_cvt_pk_bf16_f32 v82, v82, v83
	v_cvt_pk_bf16_f32 v83, v88, v89
	global_store_dwordx4 v[96:97], v[80:83], off offset:256
	v_and_b32_e32 v85, 0xffff0000, v181
	v_lshlrev_b32_e32 v86, 16, v182
	v_lshlrev_b32_e32 v82, 16, v180
	v_and_b32_e32 v83, 0xffff0000, v180
	v_and_b32_e32 v87, 0xffff0000, v182
	v_lshlrev_b32_e32 v88, 16, v183
	v_and_b32_e32 v89, 0xffff0000, v183
	v_lshl_add_u64 v[80:81], v[222:223], 0, v[228:229]
	v_pk_fma_f32 v[78:79], v[78:79], v[142:143], v[84:85]
	v_pk_fma_f32 v[76:77], v[76:77], v[140:141], v[82:83]
	v_pk_fma_f32 v[82:83], v[74:75], v[138:139], v[88:89]
	v_pk_fma_f32 v[74:75], v[72:73], v[136:137], v[86:87]
	v_cvt_pk_bf16_f32 v72, v76, v77
	v_cvt_pk_bf16_f32 v73, v78, v79
	v_lshlrev_b32_e32 v76, 16, v178
	v_cvt_pk_bf16_f32 v74, v74, v75
	v_cvt_pk_bf16_f32 v75, v82, v83
	global_store_dwordx4 v[80:81], v[72:75], off
	v_and_b32_e32 v77, 0xffff0000, v178
	v_lshlrev_b32_e32 v78, 16, v179
	v_lshlrev_b32_e32 v72, 16, v176
	v_and_b32_e32 v73, 0xffff0000, v176
	v_and_b32_e32 v79, 0xffff0000, v179
	v_lshlrev_b32_e32 v74, 16, v177
	v_and_b32_e32 v75, 0xffff0000, v177
	v_pk_fma_f32 v[68:69], v[68:69], v[132:133], v[72:73]
	v_pk_fma_f32 v[72:73], v[66:67], v[130:131], v[78:79]
	v_pk_fma_f32 v[66:67], v[64:65], v[128:129], v[76:77]
	v_pk_fma_f32 v[70:71], v[70:71], v[134:135], v[74:75]
	v_cvt_pk_bf16_f32 v64, v68, v69
	v_lshlrev_b32_e32 v68, 16, v173
	v_cvt_pk_bf16_f32 v65, v70, v71
	v_cvt_pk_bf16_f32 v66, v66, v67
	v_cvt_pk_bf16_f32 v67, v72, v73
	global_store_dwordx4 v[80:81], v[64:67], off offset:256
	v_and_b32_e32 v69, 0xffff0000, v173
	v_lshlrev_b32_e32 v70, 16, v174
	v_lshlrev_b32_e32 v66, 16, v172
	v_and_b32_e32 v67, 0xffff0000, v172
	v_and_b32_e32 v71, 0xffff0000, v174
	v_lshlrev_b32_e32 v72, 16, v175
	v_and_b32_e32 v73, 0xffff0000, v175
	v_lshl_add_u64 v[64:65], v[222:223], 0, v[226:227]
	v_pk_fma_f32 v[62:63], v[62:63], v[142:143], v[68:69]
	v_pk_fma_f32 v[60:61], v[60:61], v[140:141], v[66:67]
	v_pk_fma_f32 v[66:67], v[58:59], v[138:139], v[72:73]
	v_pk_fma_f32 v[58:59], v[56:57], v[136:137], v[70:71]
	v_cvt_pk_bf16_f32 v56, v60, v61
	v_cvt_pk_bf16_f32 v57, v62, v63
	v_lshlrev_b32_e32 v60, 16, v170
	v_cvt_pk_bf16_f32 v58, v58, v59
	v_cvt_pk_bf16_f32 v59, v66, v67
	global_store_dwordx4 v[64:65], v[56:59], off
	v_and_b32_e32 v61, 0xffff0000, v170
	v_lshlrev_b32_e32 v62, 16, v171
	v_lshlrev_b32_e32 v56, 16, v168
	v_and_b32_e32 v57, 0xffff0000, v168
	v_and_b32_e32 v63, 0xffff0000, v171
	v_lshlrev_b32_e32 v58, 16, v169
	v_and_b32_e32 v59, 0xffff0000, v169
	v_pk_fma_f32 v[52:53], v[52:53], v[132:133], v[56:57]
	v_pk_fma_f32 v[56:57], v[50:51], v[130:131], v[62:63]
	v_pk_fma_f32 v[50:51], v[48:49], v[128:129], v[60:61]
	v_pk_fma_f32 v[54:55], v[54:55], v[134:135], v[58:59]
	v_cvt_pk_bf16_f32 v48, v52, v53
	v_lshlrev_b32_e32 v52, 16, v165
	v_cvt_pk_bf16_f32 v49, v54, v55
; __device__ __forceinline__ unsigned cvt_pk_bf16(float lo, float hi) { unsigned r; asm volatile("v_cvt_pk_bf16_f32 %0, %1, %2" : "=v"(r) : "v"(lo), "v"(hi)); return r; }
; __device__ __forceinline__ float bf_lo(unsigned u) { return __uint_as_float(u << 16); }
; __device__ __forceinline__ float bf_hi(unsigned u) { return __uint_as_float(u & 0xffff0000u); }
; #define PG8_WAIT_V(n) asm volatile("s_waitcnt vmcnt(" #n ")" ::: "memory")
; #define PG8_BAR __builtin_amdgcn_s_barrier()
; template <class Epi, class Sched>
; __device__ __forceinline__ void gemm_phase(LAS unsigned char* lds, const Gemm g, const Sched& S, const Epi& E) {
;     ...
;     PG8_WAIT_V(0);
;     if (wr == 0) PG8_BAR;
;     PG8_BAR;
;     __device__ __forceinline__ void operator()(const AccT& acc, const Unit& u, int wr, int wc, int fr, int fq) const {
;     ...
;         for (int ai = 0; ai < 2; ++ai)
; #pragma unroll
;             for (int m = 0; m < 4; ++m)
; #pragma unroll
;                 for (int bj = 0; bj < 2; ++bj) {
;                     const u32x4 q = r[ai][m][bj];
;                     const f32x4 r0 = {bf_lo(q.x), bf_hi(q.x), bf_lo(q.y), bf_hi(q.y)}, r1 = {bf_lo(q.z), bf_hi(q.z), bf_lo(q.w), bf_hi(q.w)};
;                     const f32x4 h0 = r0 + gv[bj][0] * acc[ai][bj][m][0], h1 = r1 + gv[bj][1] * acc[ai][bj][m][1];
;                     u32x4 w; w.x = cvt_pk_bf16(h0[0], h0[1]); w.y = cvt_pk_bf16(h0[2], h0[3]); w.z = cvt_pk_bf16(h1[0], h1[1]); w.w = cvt_pk_bf16(h1[2], h1[3]);
;                     *(u32x4*)(out + (size_t)(wr * 64 + fr + ai * 128 + m * 16) * DM + col0 + bj * 128) = w;
;                 }
	v_cvt_pk_bf16_f32 v50, v50, v51
	v_cvt_pk_bf16_f32 v51, v56, v57
	global_store_dwordx4 v[64:65], v[48:51], off offset:256
	v_and_b32_e32 v53, 0xffff0000, v165
	v_lshlrev_b32_e32 v54, 16, v166
	v_lshlrev_b32_e32 v50, 16, v164
	v_and_b32_e32 v51, 0xffff0000, v164
	v_and_b32_e32 v55, 0xffff0000, v166
	v_lshlrev_b32_e32 v56, 16, v167
	v_and_b32_e32 v57, 0xffff0000, v167
	v_lshl_add_u64 v[48:49], v[222:223], 0, v[224:225]
	v_pk_fma_f32 v[46:47], v[46:47], v[142:143], v[52:53]
	v_pk_fma_f32 v[44:45], v[44:45], v[140:141], v[50:51]
	v_pk_fma_f32 v[50:51], v[42:43], v[138:139], v[56:57]
	v_pk_fma_f32 v[42:43], v[40:41], v[136:137], v[54:55]
	v_cvt_pk_bf16_f32 v40, v44, v45
	v_cvt_pk_bf16_f32 v41, v46, v47
	v_lshlrev_b32_e32 v44, 16, v162
	v_cvt_pk_bf16_f32 v42, v42, v43
	v_cvt_pk_bf16_f32 v43, v50, v51
	global_store_dwordx4 v[48:49], v[40:43], off
	v_and_b32_e32 v45, 0xffff0000, v162
	v_lshlrev_b32_e32 v46, 16, v163
	v_lshlrev_b32_e32 v40, 16, v160
	v_and_b32_e32 v41, 0xffff0000, v160
	v_and_b32_e32 v47, 0xffff0000, v163
	v_lshlrev_b32_e32 v42, 16, v161
	v_and_b32_e32 v43, 0xffff0000, v161
	v_pk_fma_f32 v[36:37], v[36:37], v[132:133], v[40:41]
	v_pk_fma_f32 v[40:41], v[34:35], v[130:131], v[46:47]
	v_pk_fma_f32 v[34:35], v[32:33], v[128:129], v[44:45]
	v_pk_fma_f32 v[38:39], v[38:39], v[134:135], v[42:43]
	v_cvt_pk_bf16_f32 v32, v36, v37
	v_lshlrev_b32_e32 v36, 16, v157
	v_cvt_pk_bf16_f32 v33, v38, v39
	v_cvt_pk_bf16_f32 v34, v34, v35
	v_cvt_pk_bf16_f32 v35, v40, v41
	global_store_dwordx4 v[48:49], v[32:35], off offset:256
	v_and_b32_e32 v37, 0xffff0000, v157
	v_lshlrev_b32_e32 v38, 16, v158
	v_lshlrev_b32_e32 v34, 16, v156
	v_and_b32_e32 v35, 0xffff0000, v156
	v_and_b32_e32 v39, 0xffff0000, v158
	v_lshlrev_b32_e32 v40, 16, v159
	v_and_b32_e32 v41, 0xffff0000, v159
	v_lshl_add_u64 v[32:33], v[222:223], 0, v[220:221]
	v_pk_fma_f32 v[30:31], v[30:31], v[142:143], v[36:37]
	v_pk_fma_f32 v[28:29], v[28:29], v[140:141], v[34:35]
	v_pk_fma_f32 v[34:35], v[26:27], v[138:139], v[40:41]
	v_pk_fma_f32 v[26:27], v[24:25], v[136:137], v[38:39]
	v_cvt_pk_bf16_f32 v24, v28, v29
	v_cvt_pk_bf16_f32 v25, v30, v31
	v_lshlrev_b32_e32 v28, 16, v154
	v_cvt_pk_bf16_f32 v26, v26, v27
	v_cvt_pk_bf16_f32 v27, v34, v35
	global_store_dwordx4 v[32:33], v[24:27], off
	v_and_b32_e32 v29, 0xffff0000, v154
	v_lshlrev_b32_e32 v30, 16, v155
	v_lshlrev_b32_e32 v24, 16, v152
	v_and_b32_e32 v25, 0xffff0000, v152
	v_and_b32_e32 v31, 0xffff0000, v155
	v_lshlrev_b32_e32 v26, 16, v153
	v_and_b32_e32 v27, 0xffff0000, v153
	v_pk_fma_f32 v[20:21], v[20:21], v[132:133], v[24:25]
	v_pk_fma_f32 v[24:25], v[18:19], v[130:131], v[30:31]
	v_pk_fma_f32 v[18:19], v[16:17], v[128:129], v[28:29]
	v_pk_fma_f32 v[22:23], v[22:23], v[134:135], v[26:27]
	v_cvt_pk_bf16_f32 v16, v20, v21
	v_lshlrev_b32_e32 v20, 16, v149
	v_cvt_pk_bf16_f32 v17, v22, v23
	v_cvt_pk_bf16_f32 v18, v18, v19
	v_cvt_pk_bf16_f32 v19, v24, v25
	global_store_dwordx4 v[32:33], v[16:19], off offset:256
	v_and_b32_e32 v21, 0xffff0000, v149
	v_lshlrev_b32_e32 v22, 16, v150
	v_lshlrev_b32_e32 v18, 16, v148
	v_and_b32_e32 v19, 0xffff0000, v148
	v_and_b32_e32 v23, 0xffff0000, v150
	v_lshlrev_b32_e32 v24, 16, v151
	v_and_b32_e32 v25, 0xffff0000, v151
	v_lshl_add_u64 v[16:17], v[222:223], 0, v[218:219]
	v_pk_fma_f32 v[14:15], v[14:15], v[142:143], v[20:21]
	v_pk_fma_f32 v[12:13], v[12:13], v[140:141], v[18:19]
	v_pk_fma_f32 v[18:19], v[10:11], v[138:139], v[24:25]
	v_pk_fma_f32 v[10:11], v[8:9], v[136:137], v[22:23]
	v_cvt_pk_bf16_f32 v8, v12, v13
	v_cvt_pk_bf16_f32 v9, v14, v15
	v_lshlrev_b32_e32 v12, 16, v146
	v_cvt_pk_bf16_f32 v10, v10, v11
	v_cvt_pk_bf16_f32 v11, v18, v19
	global_store_dwordx4 v[16:17], v[8:11], off
	v_and_b32_e32 v13, 0xffff0000, v146
	v_lshlrev_b32_e32 v14, 16, v147
	v_lshlrev_b32_e32 v8, 16, v144
	v_and_b32_e32 v9, 0xffff0000, v144
	v_and_b32_e32 v15, 0xffff0000, v147
	v_lshlrev_b32_e32 v10, 16, v145
	v_and_b32_e32 v11, 0xffff0000, v145
	v_pk_fma_f32 v[4:5], v[4:5], v[132:133], v[8:9]
	v_pk_fma_f32 v[8:9], v[2:3], v[130:131], v[14:15]
	v_pk_fma_f32 v[2:3], v[0:1], v[128:129], v[12:13]
	v_pk_fma_f32 v[6:7], v[6:7], v[134:135], v[10:11]
	v_cvt_pk_bf16_f32 v0, v4, v5
	s_nop 0
	v_cvt_pk_bf16_f32 v1, v6, v7
	v_cvt_pk_bf16_f32 v2, v2, v3
	v_cvt_pk_bf16_f32 v3, v8, v9
	global_store_dwordx4 v[16:17], v[0:3], off offset:256
	s_cbranch_vccz .LBB0_891
	s_waitcnt vmcnt(0)
	s_cmpk_gt_u32 s33, 0xff
	s_cbranch_scc1 .LBB0_906
	s_barrier

; #define PG8_STAGE(bufoff, gbase, voff) do { _Pragma("unroll") for (int _i = 0; _i < 2; ++_i) \
;         __builtin_amdgcn_global_load_lds((const unsigned*)((const char*)(gbase) + (voff)[_i]), (LAS unsigned*)(lds + (bufoff) + ldsw + _i * 8192), 16, 0, 0); } while (0)
; #define PG8_LDA(dst, b, h) do { _Pragma("unroll") for (int m = 0; m < 4; ++m) _Pragma("unroll") for (int k = 0; k < 2; ++k) dst[m][k] = *(const LAS bf16x8*)(lds + PG8_SA(b, h) + aoff + m * 2048 + k * 1024); } while (0)
; #define PG8_LDB(dst, b, h) do { _Pragma("unroll") for (int n = 0; n < 2; ++n) _Pragma("unroll") for (int k = 0; k < 2; ++k) dst[n][k] = *(const LAS bf16x8*)(lds + PG8_SB(b, h) + boff + n * 2048 + k * 1024); } while (0)
; #define PG8_WAIT_V(n) asm volatile("s_waitcnt vmcnt(" #n ")" ::: "memory")
; #define PG8_WAIT_L(n) asm volatile("s_waitcnt lgkmcnt(" #n ")" ::: "memory")
; #define PG8_BAR __builtin_amdgcn_s_barrier()
; #define PG8_SCHED __builtin_amdgcn_sched_barrier(0)
; template <class Epi, class Sched>
; __device__ __forceinline__ void gemm_phase(LAS unsigned char* lds, const Gemm g, const Sched& S, const Epi& E) {
;     ...
;         const bool has_next = S.next(ui + 1, nxt);
;         const char* nA = has_next ? (const char*)g.A + (size_t)nxt.pm * tstep : cA; const char* nB = has_next ? (const char*)g.Bt + (size_t)nxt.pn * tstep : cB;
;         for (int t = 0; t < nt; t += 2) {
;             const bool last = (t == nt - 2);
;             const char* a1 = cA + (size_t)(t + 1) * kstep;
;             const char* a2 = last ? nA : cA + (size_t)(t + 2) * kstep; const char* b2 = last ? nB : cB + (size_t)(t + 2) * kstep;
;             const char* a3 = a2 + kstep; const char* b3 = b2 + kstep;
;             PG8_LDB(B0, 0, 0); PG8_SCHED; PG8_LDA(At, 0, 0); PG8_STAGE(PG8_SA(1, 1), a1 + hstep, voffA);
;             PG8_WAIT_L(8); PG8_BAR; PG8_WAIT_L(0); PG8_MMA(0, 0, At, B0); PG8_BAR; PG8_SCHED;
;             PG8_LDB(B1, 0, 1); PG8_STAGE(PG8_SB(0, 0), b2, voffB);
;             PG8_BAR; PG8_WAIT_L(0); PG8_MMA(0, 1, At, B1); PG8_BAR;
;             PG8_LDA(At, 0, 1); PG8_STAGE(PG8_SA(0, 0), a2, voffA);
;             PG8_BAR; PG8_WAIT_L(0); PG8_MMA(1, 0, At, B0); PG8_BAR; PG8_SCHED;
;             PG8_STAGE(PG8_SB(0, 1), b2 + hstep, voffB);
;             PG8_WAIT_V(6); PG8_BAR; PG8_MMA(1, 1, At, B1); PG8_BAR;
.LBB0_1020:
	s_ashr_i32 s7, s6, 31
	v_cmp_lt_i64_e32 vcc, s[10:11], v[140:141]
	s_lshl_b64 s[10:11], s[6:7], 19
	s_add_u32 s10, s96, s10
	s_addc_u32 s11, s97, s11
	s_and_b64 s[12:13], vcc, exec
	s_cselect_b32 s7, s11, s17
	s_cselect_b32 s42, s10, s16
	s_ashr_i32 s5, s4, 31
	s_lshl_b64 s[12:13], s[4:5], 19
	s_add_u32 s12, s23, s12
	s_addc_u32 s13, s24, s13
	s_and_b64 s[20:21], vcc, exec
	s_cselect_b32 s5, s13, s19
	s_cselect_b32 s43, s12, s18
	s_add_u32 s16, s16, 0x40080
	s_addc_u32 s17, s17, 0
	s_add_u32 s44, s18, 0x100
	s_addc_u32 s45, s19, 0
	s_mov_b32 s46, -2
	ds_read_b128 v[150:153], v147
	ds_read_b128 v[154:157], v147 offset:1024
	ds_read_b128 v[158:161], v147 offset:2048
	ds_read_b128 v[162:165], v147 offset:3072
	s_add_u32 s18, s16, 0xfffc0080
	s_addc_u32 s19, s17, -1
	s_cmp_eq_u32 s46, 12
	s_cselect_b32 s21, s7, s19
	s_cselect_b32 s20, s42, s18
	s_cselect_b32 s19, s5, s45
	s_cselect_b32 s18, s43, s44
	s_add_i32 m0, s15, 0xc000
	ds_read_b128 v[166:169], v148
	ds_read_b128 v[170:173], v148 offset:1024
	ds_read_b128 v[174:177], v148 offset:2048
	ds_read_b128 v[178:181], v148 offset:3072
	ds_read_b128 v[182:185], v148 offset:4096
	ds_read_b128 v[186:189], v148 offset:5120
	ds_read_b128 v[190:193], v148 offset:6144
	ds_read_b128 v[194:197], v148 offset:7168
	global_load_lds_dwordx4 v136, s[16:17]
	s_add_i32 m0, s15, 0xe000
	s_nop 0
	global_load_lds_dwordx4 v138, s[16:17]
	s_waitcnt lgkmcnt(8)
	s_waitcnt vmcnt(8)
	s_setprio 1
	s_barrier
	s_waitcnt lgkmcnt(0)
	v_mfma_f32_16x16x32_bf16 v[124:127], v[150:153], v[166:169], 0
	v_mfma_f32_16x16x32_bf16 v[116:119], v[158:161], v[166:169], 0
	v_mfma_f32_16x16x32_bf16 v[108:111], v[150:153], v[174:177], 0
	v_mfma_f32_16x16x32_bf16 v[100:103], v[158:161], v[174:177], 0
	v_mfma_f32_16x16x32_bf16 v[92:95], v[150:153], v[182:185], 0
	v_mfma_f32_16x16x32_bf16 v[84:87], v[158:161], v[182:185], 0
	v_mfma_f32_16x16x32_bf16 v[76:79], v[150:153], v[190:193], 0
	v_mfma_f32_16x16x32_bf16 v[68:71], v[158:161], v[190:193], 0
	v_mfma_f32_16x16x32_bf16 v[124:127], v[154:157], v[170:173], v[124:127]
	v_mfma_f32_16x16x32_bf16 v[116:119], v[162:165], v[170:173], v[116:119]
	v_mfma_f32_16x16x32_bf16 v[108:111], v[154:157], v[178:181], v[108:111]
	v_mfma_f32_16x16x32_bf16 v[100:103], v[162:165], v[178:181], v[100:103]
	v_mfma_f32_16x16x32_bf16 v[92:95], v[154:157], v[186:189], v[92:95]
	v_mfma_f32_16x16x32_bf16 v[84:87], v[162:165], v[186:189], v[84:87]
	v_mfma_f32_16x16x32_bf16 v[76:79], v[154:157], v[194:197], v[76:79]
	v_mfma_f32_16x16x32_bf16 v[68:71], v[162:165], v[194:197], v[68:71]
	s_barrier
	s_setprio 0
	s_add_i32 s47, s38, s25
	s_mov_b32 m0, s47
	ds_read_b128 v[202:205], v149
	ds_read_b128 v[206:209], v149 offset:1024
	ds_read_b128 v[210:213], v149 offset:2048
	ds_read_b128 v[214:217], v149 offset:3072
	global_load_lds_dwordx4 v132, s[18:19]
	s_add_i32 m0, s47, 0x2000
	s_nop 0
	global_load_lds_dwordx4 v128, s[18:19]
	s_waitcnt vmcnt(8)
	s_setprio 1
	s_barrier
	s_waitcnt lgkmcnt(0)
	v_mfma_f32_16x16x32_bf16 v[120:123], v[202:205], v[166:169], 0
	v_mfma_f32_16x16x32_bf16 v[112:115], v[210:213], v[166:169], 0
	v_mfma_f32_16x16x32_bf16 v[104:107], v[202:205], v[174:177], 0
	v_mfma_f32_16x16x32_bf16 v[96:99], v[210:213], v[174:177], 0
	v_mfma_f32_16x16x32_bf16 v[88:91], v[202:205], v[182:185], 0
	v_mfma_f32_16x16x32_bf16 v[80:83], v[210:213], v[182:185], 0
	v_mfma_f32_16x16x32_bf16 v[72:75], v[202:205], v[190:193], 0
	v_mfma_f32_16x16x32_bf16 v[64:67], v[210:213], v[190:193], 0
	v_mfma_f32_16x16x32_bf16 v[120:123], v[206:209], v[170:173], v[120:123]
	v_mfma_f32_16x16x32_bf16 v[112:115], v[214:217], v[170:173], v[112:115]
	v_mfma_f32_16x16x32_bf16 v[104:107], v[206:209], v[178:181], v[104:107]
	v_mfma_f32_16x16x32_bf16 v[96:99], v[214:217], v[178:181], v[96:99]
	v_mfma_f32_16x16x32_bf16 v[88:91], v[206:209], v[186:189], v[88:91]
	v_mfma_f32_16x16x32_bf16 v[80:83], v[214:217], v[186:189], v[80:83]
	v_mfma_f32_16x16x32_bf16 v[72:75], v[206:209], v[194:197], v[72:75]
	v_mfma_f32_16x16x32_bf16 v[64:67], v[214:217], v[194:197], v[64:67]
	s_mov_b32 m0, s15
	v_lshl_add_u64 v[220:221], s[20:21], 0, v[134:135]
	s_barrier
	s_setprio 0
	ds_read_b128 v[166:169], v148 offset:16384
	ds_read_b128 v[170:173], v148 offset:17408
	ds_read_b128 v[174:177], v148 offset:18432
	ds_read_b128 v[178:181], v148 offset:19456
	ds_read_b128 v[182:185], v148 offset:20480
	ds_read_b128 v[186:189], v148 offset:21504
	ds_read_b128 v[190:193], v148 offset:22528
	ds_read_b128 v[194:197], v148 offset:23552
	global_load_lds_dwordx4 v134, s[20:21]
	v_lshl_add_u64 v[222:223], s[20:21], 0, v[130:131]
	s_mov_b32 m0, s28
	s_nop 0
	global_load_lds_dwordx4 v130, s[20:21]
	s_setprio 1
	s_barrier
	s_waitcnt lgkmcnt(0)
	v_mfma_f32_16x16x32_bf16 v[60:63], v[150:153], v[166:169], 0
	v_mfma_f32_16x16x32_bf16 v[56:59], v[158:161], v[166:169], 0
	v_mfma_f32_16x16x32_bf16 v[44:47], v[150:153], v[174:177], 0
	v_mfma_f32_16x16x32_bf16 v[40:43], v[158:161], v[174:177], 0
	v_mfma_f32_16x16x32_bf16 v[28:31], v[150:153], v[182:185], 0
	v_mfma_f32_16x16x32_bf16 v[24:27], v[158:161], v[182:185], 0
	v_mfma_f32_16x16x32_bf16 v[12:15], v[150:153], v[190:193], 0
	v_mfma_f32_16x16x32_bf16 v[8:11], v[158:161], v[190:193], 0
	v_mfma_f32_16x16x32_bf16 v[60:63], v[154:157], v[170:173], v[60:63]
	v_mfma_f32_16x16x32_bf16 v[56:59], v[162:165], v[170:173], v[56:59]
	v_mfma_f32_16x16x32_bf16 v[44:47], v[154:157], v[178:181], v[44:47]
	v_mfma_f32_16x16x32_bf16 v[40:43], v[162:165], v[178:181], v[40:43]
	v_mfma_f32_16x16x32_bf16 v[28:31], v[154:157], v[186:189], v[28:31]
	v_mfma_f32_16x16x32_bf16 v[24:27], v[162:165], v[186:189], v[24:27]
	v_mfma_f32_16x16x32_bf16 v[12:15], v[154:157], v[194:197], v[12:15]
	v_mfma_f32_16x16x32_bf16 v[8:11], v[162:165], v[194:197], v[8:11]
	s_barrier
; #define PG8_STAGE(bufoff, gbase, voff) do { _Pragma("unroll") for (int _i = 0; _i < 2; ++_i) \
;         __builtin_amdgcn_global_load_lds((const unsigned*)((const char*)(gbase) + (voff)[_i]), (LAS unsigned*)(lds + (bufoff) + ldsw + _i * 8192), 16, 0, 0); } while (0)
; #define PG8_LDA(dst, b, h) do { _Pragma("unroll") for (int m = 0; m < 4; ++m) _Pragma("unroll") for (int k = 0; k < 2; ++k) dst[m][k] = *(const LAS bf16x8*)(lds + PG8_SA(b, h) + aoff + m * 2048 + k * 1024); } while (0)
; #define PG8_LDB(dst, b, h) do { _Pragma("unroll") for (int n = 0; n < 2; ++n) _Pragma("unroll") for (int k = 0; k < 2; ++k) dst[n][k] = *(const LAS bf16x8*)(lds + PG8_SB(b, h) + boff + n * 2048 + k * 1024); } while (0)
; #define PG8_MMA(ai, bj, At, Bt) do { __builtin_amdgcn_s_setprio(1); _Pragma("unroll") for (int m = 0; m < 4; ++m) _Pragma("unroll") for (int n = 0; n < 2; ++n) _Pragma("unroll") for (int k = 0; k < 2; ++k) \
;         acc[ai][bj][m][n] = __builtin_amdgcn_mfma_f32_16x16x32_bf16(Bt[n][k], At[m][k], acc[ai][bj][m][n], 0, 0, 0); __builtin_amdgcn_s_setprio(0); } while (0)
; #define PG8_WAIT_V(n) asm volatile("s_waitcnt vmcnt(" #n ")" ::: "memory")
; #define PG8_WAIT_L(n) asm volatile("s_waitcnt lgkmcnt(" #n ")" ::: "memory")
; #define PG8_BAR __builtin_amdgcn_s_barrier()
; #define PG8_SCHED __builtin_amdgcn_sched_barrier(0)
; template <class Epi, class Sched>
; __device__ __forceinline__ void gemm_phase(LAS unsigned char* lds, const Gemm g, const Sched& S, const Epi& E) {
;     ...
;             PG8_BAR; PG8_WAIT_L(0); PG8_MMA(1, 0, At, B0); PG8_BAR; PG8_SCHED;
;             PG8_STAGE(PG8_SB(0, 1), b2 + hstep, voffB);
;             PG8_WAIT_V(6); PG8_BAR; PG8_MMA(1, 1, At, B1); PG8_BAR;
;             PG8_LDB(B0, 1, 0); PG8_SCHED; PG8_LDA(At, 1, 0); PG8_STAGE(PG8_SA(0, 1), a2 + hstep, voffA);
;             PG8_WAIT_L(8); PG8_BAR; PG8_WAIT_L(0); PG8_MMA(0, 0, At, B0); PG8_BAR; PG8_SCHED;
;             PG8_LDB(B1, 1, 1); PG8_STAGE(PG8_SB(1, 0), b3, voffB);
;             PG8_BAR; PG8_WAIT_L(0); PG8_MMA(0, 1, At, B1); PG8_BAR;
;             PG8_LDA(At, 1, 1); PG8_STAGE(PG8_SA(1, 0), a3, voffA);
;             PG8_BAR; PG8_WAIT_L(0); PG8_MMA(1, 0, At, B0); PG8_BAR; PG8_SCHED;
	s_setprio 0
	s_add_u32 s48, s18, 0x40000
	s_addc_u32 s49, s19, 0
	s_add_i32 s47, s39, s25
	s_mov_b32 m0, s47
	s_nop 0
	global_load_lds_dwordx4 v132, s[48:49]
	s_add_i32 m0, s47, 0x2000
	s_nop 0
	global_load_lds_dwordx4 v128, s[48:49]
	s_add_u32 s20, s20, 0x40000
	s_addc_u32 s21, s21, 0
	s_mov_b32 m0, s29
	s_nop 0
	global_load_lds_dwordx4 v134, s[20:21]
	s_mov_b32 m0, s30
	s_nop 0
	global_load_lds_dwordx4 v130, s[20:21]
	s_waitcnt vmcnt(10)
	s_setprio 1
	s_barrier
	v_mfma_f32_16x16x32_bf16 v[52:55], v[202:205], v[166:169], 0
	v_mfma_f32_16x16x32_bf16 v[48:51], v[210:213], v[166:169], 0
	v_mfma_f32_16x16x32_bf16 v[36:39], v[202:205], v[174:177], 0
	v_mfma_f32_16x16x32_bf16 v[32:35], v[210:213], v[174:177], 0
	v_mfma_f32_16x16x32_bf16 v[20:23], v[202:205], v[182:185], 0
	v_mfma_f32_16x16x32_bf16 v[16:19], v[210:213], v[182:185], 0
	v_mfma_f32_16x16x32_bf16 v[4:7], v[202:205], v[190:193], 0
	v_mfma_f32_16x16x32_bf16 v[0:3], v[210:213], v[190:193], 0
	v_mfma_f32_16x16x32_bf16 v[52:55], v[206:209], v[170:173], v[52:55]
	v_mfma_f32_16x16x32_bf16 v[48:51], v[214:217], v[170:173], v[48:51]
	v_mfma_f32_16x16x32_bf16 v[36:39], v[206:209], v[178:181], v[36:39]
	v_mfma_f32_16x16x32_bf16 v[32:35], v[214:217], v[178:181], v[32:35]
	v_mfma_f32_16x16x32_bf16 v[20:23], v[206:209], v[186:189], v[20:23]
	v_mfma_f32_16x16x32_bf16 v[16:19], v[214:217], v[186:189], v[16:19]
	v_mfma_f32_16x16x32_bf16 v[4:7], v[206:209], v[194:197], v[4:7]
	v_mfma_f32_16x16x32_bf16 v[0:3], v[214:217], v[194:197], v[0:3]
	s_add_i32 s47, 0, 0x18000
	v_add_u32_e32 v162, s47, v146
	s_barrier
	s_setprio 0
	ds_read_b128 v[150:153], v162
	ds_read_b128 v[154:157], v162 offset:1024
	ds_read_b128 v[158:161], v162 offset:2048
	ds_read_b128 v[162:165], v162 offset:3072
	ds_read_b128 v[166:169], v148 offset:32768
	ds_read_b128 v[170:173], v148 offset:33792
	ds_read_b128 v[174:177], v148 offset:34816
	ds_read_b128 v[178:181], v148 offset:35840
	ds_read_b128 v[182:185], v148 offset:36864
	ds_read_b128 v[186:189], v148 offset:37888
	ds_read_b128 v[190:193], v148 offset:38912
	ds_read_b128 v[194:197], v148 offset:39936
	s_waitcnt lgkmcnt(8)
	s_waitcnt vmcnt(8)
	s_setprio 1
	s_barrier
	s_waitcnt lgkmcnt(0)
	v_mfma_f32_16x16x32_bf16 v[124:127], v[150:153], v[166:169], v[124:127]
	v_mfma_f32_16x16x32_bf16 v[116:119], v[158:161], v[166:169], v[116:119]
	v_mfma_f32_16x16x32_bf16 v[108:111], v[150:153], v[174:177], v[108:111]
	v_mfma_f32_16x16x32_bf16 v[100:103], v[158:161], v[174:177], v[100:103]
	v_mfma_f32_16x16x32_bf16 v[92:95], v[150:153], v[182:185], v[92:95]
	v_mfma_f32_16x16x32_bf16 v[84:87], v[158:161], v[182:185], v[84:87]
	v_mfma_f32_16x16x32_bf16 v[76:79], v[150:153], v[190:193], v[76:79]
	v_mfma_f32_16x16x32_bf16 v[68:71], v[158:161], v[190:193], v[68:71]
	v_mfma_f32_16x16x32_bf16 v[124:127], v[154:157], v[170:173], v[124:127]
	v_mfma_f32_16x16x32_bf16 v[116:119], v[162:165], v[170:173], v[116:119]
	v_mfma_f32_16x16x32_bf16 v[108:111], v[154:157], v[178:181], v[108:111]
	v_mfma_f32_16x16x32_bf16 v[100:103], v[162:165], v[178:181], v[100:103]
	v_mfma_f32_16x16x32_bf16 v[92:95], v[154:157], v[186:189], v[92:95]
	v_mfma_f32_16x16x32_bf16 v[84:87], v[162:165], v[186:189], v[84:87]
	v_mfma_f32_16x16x32_bf16 v[76:79], v[154:157], v[194:197], v[76:79]
	v_mfma_f32_16x16x32_bf16 v[68:71], v[162:165], v[194:197], v[68:71]
	s_barrier
	s_setprio 0
	s_add_i32 s20, 0, 0x1c000
	s_add_i32 s21, s47, s25
	v_add_u32_e32 v214, s20, v146
	s_add_u32 s0, s18, 0x80
	s_addc_u32 s1, s19, 0
	s_mov_b32 m0, s21
	ds_read_b128 v[202:205], v214
	ds_read_b128 v[206:209], v214 offset:1024
	ds_read_b128 v[210:213], v214 offset:2048
	ds_read_b128 v[214:217], v214 offset:3072
	global_load_lds_dwordx4 v132, s[0:1]
	s_add_i32 m0, s21, 0x2000
	s_nop 0
	global_load_lds_dwordx4 v128, s[0:1]
	s_waitcnt vmcnt(8)
	s_setprio 1
	s_barrier
	s_waitcnt lgkmcnt(0)
	v_mfma_f32_16x16x32_bf16 v[120:123], v[202:205], v[166:169], v[120:123]
	v_mfma_f32_16x16x32_bf16 v[112:115], v[210:213], v[166:169], v[112:115]
	v_mfma_f32_16x16x32_bf16 v[104:107], v[202:205], v[174:177], v[104:107]
	v_mfma_f32_16x16x32_bf16 v[96:99], v[210:213], v[174:177], v[96:99]
	v_mfma_f32_16x16x32_bf16 v[88:91], v[202:205], v[182:185], v[88:91]
	v_mfma_f32_16x16x32_bf16 v[80:83], v[210:213], v[182:185], v[80:83]
	v_mfma_f32_16x16x32_bf16 v[72:75], v[202:205], v[190:193], v[72:75]
	v_mfma_f32_16x16x32_bf16 v[64:67], v[210:213], v[190:193], v[64:67]
	v_mfma_f32_16x16x32_bf16 v[120:123], v[206:209], v[170:173], v[120:123]
	v_mfma_f32_16x16x32_bf16 v[112:115], v[214:217], v[170:173], v[112:115]
	v_mfma_f32_16x16x32_bf16 v[104:107], v[206:209], v[178:181], v[104:107]
	v_mfma_f32_16x16x32_bf16 v[96:99], v[214:217], v[178:181], v[96:99]
	v_mfma_f32_16x16x32_bf16 v[88:91], v[206:209], v[186:189], v[88:91]
	v_mfma_f32_16x16x32_bf16 v[80:83], v[214:217], v[186:189], v[80:83]
	v_mfma_f32_16x16x32_bf16 v[72:75], v[206:209], v[194:197], v[72:75]
	v_mfma_f32_16x16x32_bf16 v[64:67], v[214:217], v[194:197], v[64:67]
	s_mov_b32 m0, s35
	s_mov_b64 s[0:1], 0x80
	v_lshl_add_u64 v[198:199], v[220:221], 0, s[0:1]
	s_barrier
	s_setprio 0
	ds_read_b128 v[166:169], v148 offset:49152
	ds_read_b128 v[170:173], v148 offset:50176
	ds_read_b128 v[174:177], v148 offset:51200
	ds_read_b128 v[178:181], v148 offset:52224
	ds_read_b128 v[182:185], v148 offset:53248
	ds_read_b128 v[186:189], v148 offset:54272
	ds_read_b128 v[190:193], v148 offset:55296
	ds_read_b128 v[194:197], v148 offset:56320
	global_load_lds_dwordx4 v[198:199], off
	v_lshl_add_u64 v[198:199], v[222:223], 0, s[0:1]
	s_mov_b32 m0, s36
	s_nop 0
	global_load_lds_dwordx4 v[198:199], off
	s_setprio 1
	s_barrier
; #define PG8_STAGE(bufoff, gbase, voff) do { _Pragma("unroll") for (int _i = 0; _i < 2; ++_i) \
;         __builtin_amdgcn_global_load_lds((const unsigned*)((const char*)(gbase) + (voff)[_i]), (LAS unsigned*)(lds + (bufoff) + ldsw + _i * 8192), 16, 0, 0); } while (0)
; #define PG8_LDA(dst, b, h) do { _Pragma("unroll") for (int m = 0; m < 4; ++m) _Pragma("unroll") for (int k = 0; k < 2; ++k) dst[m][k] = *(const LAS bf16x8*)(lds + PG8_SA(b, h) + aoff + m * 2048 + k * 1024); } while (0)
; #define PG8_LDB(dst, b, h) do { _Pragma("unroll") for (int n = 0; n < 2; ++n) _Pragma("unroll") for (int k = 0; k < 2; ++k) dst[n][k] = *(const LAS bf16x8*)(lds + PG8_SB(b, h) + boff + n * 2048 + k * 1024); } while (0)
; #define PG8_MMA(ai, bj, At, Bt) do { __builtin_amdgcn_s_setprio(1); _Pragma("unroll") for (int m = 0; m < 4; ++m) _Pragma("unroll") for (int n = 0; n < 2; ++n) _Pragma("unroll") for (int k = 0; k < 2; ++k) \
;         acc[ai][bj][m][n] = __builtin_amdgcn_mfma_f32_16x16x32_bf16(Bt[n][k], At[m][k], acc[ai][bj][m][n], 0, 0, 0); __builtin_amdgcn_s_setprio(0); } while (0)
; #define PG8_WAIT_V(n) asm volatile("s_waitcnt vmcnt(" #n ")" ::: "memory")
; #define PG8_WAIT_L(n) asm volatile("s_waitcnt lgkmcnt(" #n ")" ::: "memory")
; #define PG8_BAR __builtin_amdgcn_s_barrier()
; #define PG8_SCHED __builtin_amdgcn_sched_barrier(0)
; template <class Epi, class Sched>
; __device__ __forceinline__ void gemm_phase(LAS unsigned char* lds, const Gemm g, const Sched& S, const Epi& E) {
;     ...
;             PG8_LDB(B0, 0, 0); PG8_SCHED; PG8_LDA(At, 0, 0); PG8_STAGE(PG8_SA(1, 1), a1 + hstep, voffA);
;             PG8_WAIT_L(8); PG8_BAR; PG8_WAIT_L(0); PG8_MMA(0, 0, At, B0); PG8_BAR; PG8_SCHED;
;             PG8_LDB(B1, 0, 1); PG8_STAGE(PG8_SB(0, 0), b2, voffB);
;             PG8_BAR; PG8_WAIT_L(0); PG8_MMA(0, 1, At, B1); PG8_BAR;
;             PG8_LDA(At, 0, 1); PG8_STAGE(PG8_SA(0, 0), a2, voffA);
;     ...
;             PG8_BAR; PG8_WAIT_L(0); PG8_MMA(0, 1, At, B1); PG8_BAR;
;             PG8_LDA(At, 1, 1); PG8_STAGE(PG8_SA(1, 0), a3, voffA);
;             PG8_BAR; PG8_WAIT_L(0); PG8_MMA(1, 0, At, B0); PG8_BAR; PG8_SCHED;
;             PG8_STAGE(PG8_SB(1, 1), b3 + hstep, voffB);
;             PG8_WAIT_V(6); PG8_BAR; PG8_MMA(1, 1, At, B1); PG8_BAR;
	s_waitcnt lgkmcnt(0)
	v_mfma_f32_16x16x32_bf16 v[60:63], v[150:153], v[166:169], v[60:63]
	v_mfma_f32_16x16x32_bf16 v[56:59], v[158:161], v[166:169], v[56:59]
	v_mfma_f32_16x16x32_bf16 v[44:47], v[150:153], v[174:177], v[44:47]
	v_mfma_f32_16x16x32_bf16 v[40:43], v[158:161], v[174:177], v[40:43]
	v_mfma_f32_16x16x32_bf16 v[28:31], v[150:153], v[182:185], v[28:31]
	v_mfma_f32_16x16x32_bf16 v[24:27], v[158:161], v[182:185], v[24:27]
	v_mfma_f32_16x16x32_bf16 v[12:15], v[150:153], v[190:193], v[12:15]
	v_mfma_f32_16x16x32_bf16 v[8:11], v[158:161], v[190:193], v[8:11]
	v_mfma_f32_16x16x32_bf16 v[60:63], v[154:157], v[170:173], v[60:63]
	v_mfma_f32_16x16x32_bf16 v[56:59], v[162:165], v[170:173], v[56:59]
	v_mfma_f32_16x16x32_bf16 v[44:47], v[154:157], v[178:181], v[44:47]
	v_mfma_f32_16x16x32_bf16 v[40:43], v[162:165], v[178:181], v[40:43]
	v_mfma_f32_16x16x32_bf16 v[28:31], v[154:157], v[186:189], v[28:31]
	v_mfma_f32_16x16x32_bf16 v[24:27], v[162:165], v[186:189], v[24:27]
	v_mfma_f32_16x16x32_bf16 v[12:15], v[154:157], v[194:197], v[12:15]
	v_mfma_f32_16x16x32_bf16 v[8:11], v[162:165], v[194:197], v[8:11]
	s_barrier
	s_setprio 0
	s_add_u32 s18, s18, 0x40080
	s_addc_u32 s19, s19, 0
	s_add_i32 s20, s20, s25
	s_mov_b32 m0, s20
	s_nop 0
	global_load_lds_dwordx4 v132, s[18:19]
	s_add_i32 m0, s20, 0x2000
	s_nop 0
	global_load_lds_dwordx4 v128, s[18:19]
	s_waitcnt vmcnt(8)
	s_setprio 1
	s_barrier
	v_mfma_f32_16x16x32_bf16 v[52:55], v[202:205], v[166:169], v[52:55]
	v_mfma_f32_16x16x32_bf16 v[48:51], v[210:213], v[166:169], v[48:51]
	v_mfma_f32_16x16x32_bf16 v[36:39], v[202:205], v[174:177], v[36:39]
	v_mfma_f32_16x16x32_bf16 v[32:35], v[210:213], v[174:177], v[32:35]
	v_mfma_f32_16x16x32_bf16 v[20:23], v[202:205], v[182:185], v[20:23]
	v_mfma_f32_16x16x32_bf16 v[16:19], v[210:213], v[182:185], v[16:19]
	v_mfma_f32_16x16x32_bf16 v[4:7], v[202:205], v[190:193], v[4:7]
	v_mfma_f32_16x16x32_bf16 v[0:3], v[210:213], v[190:193], v[0:3]
	v_mfma_f32_16x16x32_bf16 v[52:55], v[206:209], v[170:173], v[52:55]
	v_mfma_f32_16x16x32_bf16 v[48:51], v[214:217], v[170:173], v[48:51]
	v_mfma_f32_16x16x32_bf16 v[36:39], v[206:209], v[178:181], v[36:39]
	v_mfma_f32_16x16x32_bf16 v[32:35], v[214:217], v[178:181], v[32:35]
	v_mfma_f32_16x16x32_bf16 v[20:23], v[206:209], v[186:189], v[20:23]
	v_mfma_f32_16x16x32_bf16 v[16:19], v[214:217], v[186:189], v[16:19]
	v_mfma_f32_16x16x32_bf16 v[4:7], v[206:209], v[194:197], v[4:7]
	v_mfma_f32_16x16x32_bf16 v[0:3], v[214:217], v[194:197], v[0:3]
	s_add_i32 s46, s46, 2
	s_add_u32 s16, s16, 0x100
	s_addc_u32 s17, s17, 0
	s_add_u32 s44, s44, 0x100
	s_addc_u32 s45, s45, 0
	s_cmp_gt_u32 s46, 13
	s_barrier
	s_setprio 0
.LBB0_1021:
	ds_read_b128 v[150:153], v147
	ds_read_b128 v[154:157], v147 offset:1024
	ds_read_b128 v[158:161], v147 offset:2048
	ds_read_b128 v[162:165], v147 offset:3072
	s_add_u32 s18, s16, 0xfffc0080
	s_addc_u32 s19, s17, -1
	s_cmp_eq_u32 s46, 12
	s_cselect_b32 s21, s7, s19
	s_cselect_b32 s20, s42, s18
	s_cselect_b32 s19, s5, s45
	s_cselect_b32 s18, s43, s44
	s_add_i32 m0, s15, 0xc000
	ds_read_b128 v[166:169], v148
	ds_read_b128 v[170:173], v148 offset:1024
	ds_read_b128 v[174:177], v148 offset:2048
	ds_read_b128 v[178:181], v148 offset:3072
	ds_read_b128 v[182:185], v148 offset:4096
	ds_read_b128 v[186:189], v148 offset:5120
	ds_read_b128 v[190:193], v148 offset:6144
	ds_read_b128 v[194:197], v148 offset:7168
	global_load_lds_dwordx4 v136, s[16:17]
	s_add_i32 m0, s15, 0xe000
	s_nop 0
	global_load_lds_dwordx4 v138, s[16:17]
	s_waitcnt lgkmcnt(8)
	s_waitcnt vmcnt(8)
	s_setprio 1
	s_barrier
	s_waitcnt lgkmcnt(0)
	v_mfma_f32_16x16x32_bf16 v[124:127], v[150:153], v[166:169], v[124:127]
	v_mfma_f32_16x16x32_bf16 v[116:119], v[158:161], v[166:169], v[116:119]
	v_mfma_f32_16x16x32_bf16 v[108:111], v[150:153], v[174:177], v[108:111]
	v_mfma_f32_16x16x32_bf16 v[100:103], v[158:161], v[174:177], v[100:103]
	v_mfma_f32_16x16x32_bf16 v[92:95], v[150:153], v[182:185], v[92:95]
	v_mfma_f32_16x16x32_bf16 v[84:87], v[158:161], v[182:185], v[84:87]
	v_mfma_f32_16x16x32_bf16 v[76:79], v[150:153], v[190:193], v[76:79]
	v_mfma_f32_16x16x32_bf16 v[68:71], v[158:161], v[190:193], v[68:71]
	v_mfma_f32_16x16x32_bf16 v[124:127], v[154:157], v[170:173], v[124:127]
	v_mfma_f32_16x16x32_bf16 v[116:119], v[162:165], v[170:173], v[116:119]
	v_mfma_f32_16x16x32_bf16 v[108:111], v[154:157], v[178:181], v[108:111]
	v_mfma_f32_16x16x32_bf16 v[100:103], v[162:165], v[178:181], v[100:103]
	v_mfma_f32_16x16x32_bf16 v[92:95], v[154:157], v[186:189], v[92:95]
	v_mfma_f32_16x16x32_bf16 v[84:87], v[162:165], v[186:189], v[84:87]
	v_mfma_f32_16x16x32_bf16 v[76:79], v[154:157], v[194:197], v[76:79]
	v_mfma_f32_16x16x32_bf16 v[68:71], v[162:165], v[194:197], v[68:71]
	s_barrier
	s_setprio 0
	s_add_i32 s47, s38, s25
	s_mov_b32 m0, s47
	ds_read_b128 v[202:205], v149
	ds_read_b128 v[206:209], v149 offset:1024
	ds_read_b128 v[210:213], v149 offset:2048
	ds_read_b128 v[214:217], v149 offset:3072
	global_load_lds_dwordx4 v132, s[18:19]
	s_add_i32 m0, s47, 0x2000
	s_nop 0
	global_load_lds_dwordx4 v128, s[18:19]
	s_waitcnt vmcnt(8)
	s_setprio 1
	s_barrier
; #define PG8_STAGE(bufoff, gbase, voff) do { _Pragma("unroll") for (int _i = 0; _i < 2; ++_i) \
;         __builtin_amdgcn_global_load_lds((const unsigned*)((const char*)(gbase) + (voff)[_i]), (LAS unsigned*)(lds + (bufoff) + ldsw + _i * 8192), 16, 0, 0); } while (0)
; #define PG8_LDA(dst, b, h) do { _Pragma("unroll") for (int m = 0; m < 4; ++m) _Pragma("unroll") for (int k = 0; k < 2; ++k) dst[m][k] = *(const LAS bf16x8*)(lds + PG8_SA(b, h) + aoff + m * 2048 + k * 1024); } while (0)
; #define PG8_LDB(dst, b, h) do { _Pragma("unroll") for (int n = 0; n < 2; ++n) _Pragma("unroll") for (int k = 0; k < 2; ++k) dst[n][k] = *(const LAS bf16x8*)(lds + PG8_SB(b, h) + boff + n * 2048 + k * 1024); } while (0)
; #define PG8_MMA(ai, bj, At, Bt) do { __builtin_amdgcn_s_setprio(1); _Pragma("unroll") for (int m = 0; m < 4; ++m) _Pragma("unroll") for (int n = 0; n < 2; ++n) _Pragma("unroll") for (int k = 0; k < 2; ++k) \
;         acc[ai][bj][m][n] = __builtin_amdgcn_mfma_f32_16x16x32_bf16(Bt[n][k], At[m][k], acc[ai][bj][m][n], 0, 0, 0); __builtin_amdgcn_s_setprio(0); } while (0)
; #define PG8_WAIT_V(n) asm volatile("s_waitcnt vmcnt(" #n ")" ::: "memory")
; #define PG8_WAIT_L(n) asm volatile("s_waitcnt lgkmcnt(" #n ")" ::: "memory")
; #define PG8_BAR __builtin_amdgcn_s_barrier()
; #define PG8_SCHED __builtin_amdgcn_sched_barrier(0)
; template <class Epi, class Sched>
; __device__ __forceinline__ void gemm_phase(LAS unsigned char* lds, const Gemm g, const Sched& S, const Epi& E) {
;     ...
;             PG8_LDA(At, 0, 1); PG8_STAGE(PG8_SA(0, 0), a2, voffA);
;             PG8_BAR; PG8_WAIT_L(0); PG8_MMA(1, 0, At, B0); PG8_BAR; PG8_SCHED;
;             PG8_STAGE(PG8_SB(0, 1), b2 + hstep, voffB);
;             PG8_WAIT_V(6); PG8_BAR; PG8_MMA(1, 1, At, B1); PG8_BAR;
;             PG8_LDB(B0, 1, 0); PG8_SCHED; PG8_LDA(At, 1, 0); PG8_STAGE(PG8_SA(0, 1), a2 + hstep, voffA);
;             PG8_WAIT_L(8); PG8_BAR; PG8_WAIT_L(0); PG8_MMA(0, 0, At, B0); PG8_BAR; PG8_SCHED;
;             PG8_LDB(B1, 1, 1); PG8_STAGE(PG8_SB(1, 0), b3, voffB);
;             PG8_BAR; PG8_WAIT_L(0); PG8_MMA(0, 1, At, B1); PG8_BAR;
	s_waitcnt lgkmcnt(0)
	v_mfma_f32_16x16x32_bf16 v[120:123], v[202:205], v[166:169], v[120:123]
	v_mfma_f32_16x16x32_bf16 v[112:115], v[210:213], v[166:169], v[112:115]
	v_mfma_f32_16x16x32_bf16 v[104:107], v[202:205], v[174:177], v[104:107]
	v_mfma_f32_16x16x32_bf16 v[96:99], v[210:213], v[174:177], v[96:99]
	v_mfma_f32_16x16x32_bf16 v[88:91], v[202:205], v[182:185], v[88:91]
	v_mfma_f32_16x16x32_bf16 v[80:83], v[210:213], v[182:185], v[80:83]
	v_mfma_f32_16x16x32_bf16 v[72:75], v[202:205], v[190:193], v[72:75]
	v_mfma_f32_16x16x32_bf16 v[64:67], v[210:213], v[190:193], v[64:67]
	v_mfma_f32_16x16x32_bf16 v[120:123], v[206:209], v[170:173], v[120:123]
	v_mfma_f32_16x16x32_bf16 v[112:115], v[214:217], v[170:173], v[112:115]
	v_mfma_f32_16x16x32_bf16 v[104:107], v[206:209], v[178:181], v[104:107]
	v_mfma_f32_16x16x32_bf16 v[96:99], v[214:217], v[178:181], v[96:99]
	v_mfma_f32_16x16x32_bf16 v[88:91], v[206:209], v[186:189], v[88:91]
	v_mfma_f32_16x16x32_bf16 v[80:83], v[214:217], v[186:189], v[80:83]
	v_mfma_f32_16x16x32_bf16 v[72:75], v[206:209], v[194:197], v[72:75]
	v_mfma_f32_16x16x32_bf16 v[64:67], v[214:217], v[194:197], v[64:67]
	s_mov_b32 m0, s15
	v_lshl_add_u64 v[220:221], s[20:21], 0, v[134:135]
	s_barrier
	s_setprio 0
	ds_read_b128 v[166:169], v148 offset:16384
	ds_read_b128 v[170:173], v148 offset:17408
	ds_read_b128 v[174:177], v148 offset:18432
	ds_read_b128 v[178:181], v148 offset:19456
	ds_read_b128 v[182:185], v148 offset:20480
	ds_read_b128 v[186:189], v148 offset:21504
	ds_read_b128 v[190:193], v148 offset:22528
	ds_read_b128 v[194:197], v148 offset:23552
	global_load_lds_dwordx4 v134, s[20:21]
	v_lshl_add_u64 v[222:223], s[20:21], 0, v[130:131]
	s_mov_b32 m0, s28
	s_nop 0
	global_load_lds_dwordx4 v130, s[20:21]
	s_setprio 1
	s_barrier
	s_waitcnt lgkmcnt(0)
	v_mfma_f32_16x16x32_bf16 v[60:63], v[150:153], v[166:169], v[60:63]
	v_mfma_f32_16x16x32_bf16 v[56:59], v[158:161], v[166:169], v[56:59]
	v_mfma_f32_16x16x32_bf16 v[44:47], v[150:153], v[174:177], v[44:47]
	v_mfma_f32_16x16x32_bf16 v[40:43], v[158:161], v[174:177], v[40:43]
	v_mfma_f32_16x16x32_bf16 v[28:31], v[150:153], v[182:185], v[28:31]
	v_mfma_f32_16x16x32_bf16 v[24:27], v[158:161], v[182:185], v[24:27]
	v_mfma_f32_16x16x32_bf16 v[12:15], v[150:153], v[190:193], v[12:15]
	v_mfma_f32_16x16x32_bf16 v[8:11], v[158:161], v[190:193], v[8:11]
	v_mfma_f32_16x16x32_bf16 v[60:63], v[154:157], v[170:173], v[60:63]
	v_mfma_f32_16x16x32_bf16 v[56:59], v[162:165], v[170:173], v[56:59]
	v_mfma_f32_16x16x32_bf16 v[44:47], v[154:157], v[178:181], v[44:47]
	v_mfma_f32_16x16x32_bf16 v[40:43], v[162:165], v[178:181], v[40:43]
	v_mfma_f32_16x16x32_bf16 v[28:31], v[154:157], v[186:189], v[28:31]
	v_mfma_f32_16x16x32_bf16 v[24:27], v[162:165], v[186:189], v[24:27]
	v_mfma_f32_16x16x32_bf16 v[12:15], v[154:157], v[194:197], v[12:15]
	v_mfma_f32_16x16x32_bf16 v[8:11], v[162:165], v[194:197], v[8:11]
	s_barrier
	s_setprio 0
	s_add_u32 s48, s18, 0x40000
	s_addc_u32 s49, s19, 0
	s_add_i32 s47, s39, s25
	s_mov_b32 m0, s47
	s_nop 0
	global_load_lds_dwordx4 v132, s[48:49]
	s_add_i32 m0, s47, 0x2000
	s_nop 0
	global_load_lds_dwordx4 v128, s[48:49]
	s_add_u32 s20, s20, 0x40000
	s_addc_u32 s21, s21, 0
	s_mov_b32 m0, s29
	s_nop 0
	global_load_lds_dwordx4 v134, s[20:21]
	s_mov_b32 m0, s30
	s_nop 0
	global_load_lds_dwordx4 v130, s[20:21]
	s_waitcnt vmcnt(10)
	s_setprio 1
	s_barrier
	v_mfma_f32_16x16x32_bf16 v[52:55], v[202:205], v[166:169], v[52:55]
	v_mfma_f32_16x16x32_bf16 v[48:51], v[210:213], v[166:169], v[48:51]
	v_mfma_f32_16x16x32_bf16 v[36:39], v[202:205], v[174:177], v[36:39]
	v_mfma_f32_16x16x32_bf16 v[32:35], v[210:213], v[174:177], v[32:35]
	v_mfma_f32_16x16x32_bf16 v[20:23], v[202:205], v[182:185], v[20:23]
	v_mfma_f32_16x16x32_bf16 v[16:19], v[210:213], v[182:185], v[16:19]
	v_mfma_f32_16x16x32_bf16 v[4:7], v[202:205], v[190:193], v[4:7]
	v_mfma_f32_16x16x32_bf16 v[0:3], v[210:213], v[190:193], v[0:3]
	v_mfma_f32_16x16x32_bf16 v[52:55], v[206:209], v[170:173], v[52:55]
	v_mfma_f32_16x16x32_bf16 v[48:51], v[214:217], v[170:173], v[48:51]
	v_mfma_f32_16x16x32_bf16 v[36:39], v[206:209], v[178:181], v[36:39]
	v_mfma_f32_16x16x32_bf16 v[32:35], v[214:217], v[178:181], v[32:35]
	v_mfma_f32_16x16x32_bf16 v[20:23], v[206:209], v[186:189], v[20:23]
	v_mfma_f32_16x16x32_bf16 v[16:19], v[214:217], v[186:189], v[16:19]
	v_mfma_f32_16x16x32_bf16 v[4:7], v[206:209], v[194:197], v[4:7]
	v_mfma_f32_16x16x32_bf16 v[0:3], v[214:217], v[194:197], v[0:3]
	s_add_i32 s47, 0, 0x18000
	v_add_u32_e32 v162, s47, v146
	s_barrier
	s_setprio 0
	ds_read_b128 v[150:153], v162
	ds_read_b128 v[154:157], v162 offset:1024
	ds_read_b128 v[158:161], v162 offset:2048
	ds_read_b128 v[162:165], v162 offset:3072
	ds_read_b128 v[166:169], v148 offset:32768
	ds_read_b128 v[170:173], v148 offset:33792
	ds_read_b128 v[174:177], v148 offset:34816
	ds_read_b128 v[178:181], v148 offset:35840
	ds_read_b128 v[182:185], v148 offset:36864
	ds_read_b128 v[186:189], v148 offset:37888
	ds_read_b128 v[190:193], v148 offset:38912
	ds_read_b128 v[194:197], v148 offset:39936
	s_waitcnt lgkmcnt(8)
	s_waitcnt vmcnt(8)
	s_setprio 1
	s_barrier
; #define PG8_STAGE(bufoff, gbase, voff) do { _Pragma("unroll") for (int _i = 0; _i < 2; ++_i) \
;         __builtin_amdgcn_global_load_lds((const unsigned*)((const char*)(gbase) + (voff)[_i]), (LAS unsigned*)(lds + (bufoff) + ldsw + _i * 8192), 16, 0, 0); } while (0)
; #define PG8_LDA(dst, b, h) do { _Pragma("unroll") for (int m = 0; m < 4; ++m) _Pragma("unroll") for (int k = 0; k < 2; ++k) dst[m][k] = *(const LAS bf16x8*)(lds + PG8_SA(b, h) + aoff + m * 2048 + k * 1024); } while (0)
; #define PG8_LDB(dst, b, h) do { _Pragma("unroll") for (int n = 0; n < 2; ++n) _Pragma("unroll") for (int k = 0; k < 2; ++k) dst[n][k] = *(const LAS bf16x8*)(lds + PG8_SB(b, h) + boff + n * 2048 + k * 1024); } while (0)
; #define PG8_MMA(ai, bj, At, Bt) do { __builtin_amdgcn_s_setprio(1); _Pragma("unroll") for (int m = 0; m < 4; ++m) _Pragma("unroll") for (int n = 0; n < 2; ++n) _Pragma("unroll") for (int k = 0; k < 2; ++k) \
;         acc[ai][bj][m][n] = __builtin_amdgcn_mfma_f32_16x16x32_bf16(Bt[n][k], At[m][k], acc[ai][bj][m][n], 0, 0, 0); __builtin_amdgcn_s_setprio(0); } while (0)
; #define PG8_WAIT_V(n) asm volatile("s_waitcnt vmcnt(" #n ")" ::: "memory")
; #define PG8_WAIT_L(n) asm volatile("s_waitcnt lgkmcnt(" #n ")" ::: "memory")
; #define PG8_BAR __builtin_amdgcn_s_barrier()
; #define PG8_SCHED __builtin_amdgcn_sched_barrier(0)
; template <class Epi, class Sched>
; __device__ __forceinline__ void gemm_phase(LAS unsigned char* lds, const Gemm g, const Sched& S, const Epi& E) {
;     ...
;             PG8_WAIT_L(8); PG8_BAR; PG8_WAIT_L(0); PG8_MMA(0, 0, At, B0); PG8_BAR; PG8_SCHED;
;             PG8_LDB(B1, 1, 1); PG8_STAGE(PG8_SB(1, 0), b3, voffB);
;             PG8_BAR; PG8_WAIT_L(0); PG8_MMA(0, 1, At, B1); PG8_BAR;
;             PG8_LDA(At, 1, 1); PG8_STAGE(PG8_SA(1, 0), a3, voffA);
;             PG8_BAR; PG8_WAIT_L(0); PG8_MMA(1, 0, At, B0); PG8_BAR; PG8_SCHED;
;             PG8_STAGE(PG8_SB(1, 1), b3 + hstep, voffB);
;             PG8_WAIT_V(6); PG8_BAR; PG8_MMA(1, 1, At, B1); PG8_BAR;
	s_waitcnt lgkmcnt(0)
	v_mfma_f32_16x16x32_bf16 v[124:127], v[150:153], v[166:169], v[124:127]
	v_mfma_f32_16x16x32_bf16 v[116:119], v[158:161], v[166:169], v[116:119]
	v_mfma_f32_16x16x32_bf16 v[108:111], v[150:153], v[174:177], v[108:111]
	v_mfma_f32_16x16x32_bf16 v[100:103], v[158:161], v[174:177], v[100:103]
	v_mfma_f32_16x16x32_bf16 v[92:95], v[150:153], v[182:185], v[92:95]
	v_mfma_f32_16x16x32_bf16 v[84:87], v[158:161], v[182:185], v[84:87]
	v_mfma_f32_16x16x32_bf16 v[76:79], v[150:153], v[190:193], v[76:79]
	v_mfma_f32_16x16x32_bf16 v[68:71], v[158:161], v[190:193], v[68:71]
	v_mfma_f32_16x16x32_bf16 v[124:127], v[154:157], v[170:173], v[124:127]
	v_mfma_f32_16x16x32_bf16 v[116:119], v[162:165], v[170:173], v[116:119]
	v_mfma_f32_16x16x32_bf16 v[108:111], v[154:157], v[178:181], v[108:111]
	v_mfma_f32_16x16x32_bf16 v[100:103], v[162:165], v[178:181], v[100:103]
	v_mfma_f32_16x16x32_bf16 v[92:95], v[154:157], v[186:189], v[92:95]
	v_mfma_f32_16x16x32_bf16 v[84:87], v[162:165], v[186:189], v[84:87]
	v_mfma_f32_16x16x32_bf16 v[76:79], v[154:157], v[194:197], v[76:79]
	v_mfma_f32_16x16x32_bf16 v[68:71], v[162:165], v[194:197], v[68:71]
	s_barrier
	s_setprio 0
	s_add_i32 s20, 0, 0x1c000
	s_add_i32 s21, s47, s25
	v_add_u32_e32 v214, s20, v146
	s_add_u32 s0, s18, 0x80
	s_addc_u32 s1, s19, 0
	s_mov_b32 m0, s21
	ds_read_b128 v[202:205], v214
	ds_read_b128 v[206:209], v214 offset:1024
	ds_read_b128 v[210:213], v214 offset:2048
	ds_read_b128 v[214:217], v214 offset:3072
	global_load_lds_dwordx4 v132, s[0:1]
	s_add_i32 m0, s21, 0x2000
	s_nop 0
	global_load_lds_dwordx4 v128, s[0:1]
	s_waitcnt vmcnt(8)
	s_setprio 1
	s_barrier
	s_waitcnt lgkmcnt(0)
	v_mfma_f32_16x16x32_bf16 v[120:123], v[202:205], v[166:169], v[120:123]
	v_mfma_f32_16x16x32_bf16 v[112:115], v[210:213], v[166:169], v[112:115]
	v_mfma_f32_16x16x32_bf16 v[104:107], v[202:205], v[174:177], v[104:107]
	v_mfma_f32_16x16x32_bf16 v[96:99], v[210:213], v[174:177], v[96:99]
	v_mfma_f32_16x16x32_bf16 v[88:91], v[202:205], v[182:185], v[88:91]
	v_mfma_f32_16x16x32_bf16 v[80:83], v[210:213], v[182:185], v[80:83]
	v_mfma_f32_16x16x32_bf16 v[72:75], v[202:205], v[190:193], v[72:75]
	v_mfma_f32_16x16x32_bf16 v[64:67], v[210:213], v[190:193], v[64:67]
	v_mfma_f32_16x16x32_bf16 v[120:123], v[206:209], v[170:173], v[120:123]
	v_mfma_f32_16x16x32_bf16 v[112:115], v[214:217], v[170:173], v[112:115]
	v_mfma_f32_16x16x32_bf16 v[104:107], v[206:209], v[178:181], v[104:107]
	v_mfma_f32_16x16x32_bf16 v[96:99], v[214:217], v[178:181], v[96:99]
	v_mfma_f32_16x16x32_bf16 v[88:91], v[206:209], v[186:189], v[88:91]
	v_mfma_f32_16x16x32_bf16 v[80:83], v[214:217], v[186:189], v[80:83]
	v_mfma_f32_16x16x32_bf16 v[72:75], v[206:209], v[194:197], v[72:75]
	v_mfma_f32_16x16x32_bf16 v[64:67], v[214:217], v[194:197], v[64:67]
	s_mov_b32 m0, s35
	s_mov_b64 s[0:1], 0x80
	v_lshl_add_u64 v[198:199], v[220:221], 0, s[0:1]
	s_barrier
	s_setprio 0
	ds_read_b128 v[166:169], v148 offset:49152
	ds_read_b128 v[170:173], v148 offset:50176
	ds_read_b128 v[174:177], v148 offset:51200
	ds_read_b128 v[178:181], v148 offset:52224
	ds_read_b128 v[182:185], v148 offset:53248
	ds_read_b128 v[186:189], v148 offset:54272
	ds_read_b128 v[190:193], v148 offset:55296
	ds_read_b128 v[194:197], v148 offset:56320
	global_load_lds_dwordx4 v[198:199], off
	v_lshl_add_u64 v[198:199], v[222:223], 0, s[0:1]
	s_mov_b32 m0, s36
	s_nop 0
	global_load_lds_dwordx4 v[198:199], off
	s_setprio 1
	s_barrier
	s_waitcnt lgkmcnt(0)
	v_mfma_f32_16x16x32_bf16 v[60:63], v[150:153], v[166:169], v[60:63]
	v_mfma_f32_16x16x32_bf16 v[56:59], v[158:161], v[166:169], v[56:59]
	v_mfma_f32_16x16x32_bf16 v[44:47], v[150:153], v[174:177], v[44:47]
	v_mfma_f32_16x16x32_bf16 v[40:43], v[158:161], v[174:177], v[40:43]
	v_mfma_f32_16x16x32_bf16 v[28:31], v[150:153], v[182:185], v[28:31]
	v_mfma_f32_16x16x32_bf16 v[24:27], v[158:161], v[182:185], v[24:27]
	v_mfma_f32_16x16x32_bf16 v[12:15], v[150:153], v[190:193], v[12:15]
	v_mfma_f32_16x16x32_bf16 v[8:11], v[158:161], v[190:193], v[8:11]
	v_mfma_f32_16x16x32_bf16 v[60:63], v[154:157], v[170:173], v[60:63]
	v_mfma_f32_16x16x32_bf16 v[56:59], v[162:165], v[170:173], v[56:59]
	v_mfma_f32_16x16x32_bf16 v[44:47], v[154:157], v[178:181], v[44:47]
	v_mfma_f32_16x16x32_bf16 v[40:43], v[162:165], v[178:181], v[40:43]
	v_mfma_f32_16x16x32_bf16 v[28:31], v[154:157], v[186:189], v[28:31]
	v_mfma_f32_16x16x32_bf16 v[24:27], v[162:165], v[186:189], v[24:27]
	v_mfma_f32_16x16x32_bf16 v[12:15], v[154:157], v[194:197], v[12:15]
	v_mfma_f32_16x16x32_bf16 v[8:11], v[162:165], v[194:197], v[8:11]
	s_barrier
	s_setprio 0
	s_add_u32 s18, s18, 0x40080
	s_addc_u32 s19, s19, 0
	s_add_i32 s20, s20, s25
	s_mov_b32 m0, s20
	s_nop 0
	global_load_lds_dwordx4 v132, s[18:19]
	s_add_i32 m0, s20, 0x2000
	s_nop 0
	global_load_lds_dwordx4 v128, s[18:19]
	s_waitcnt vmcnt(8)
	s_setprio 1
	s_barrier
	v_mfma_f32_16x16x32_bf16 v[52:55], v[202:205], v[166:169], v[52:55]
	v_mfma_f32_16x16x32_bf16 v[48:51], v[210:213], v[166:169], v[48:51]
	v_mfma_f32_16x16x32_bf16 v[36:39], v[202:205], v[174:177], v[36:39]
	v_mfma_f32_16x16x32_bf16 v[32:35], v[210:213], v[174:177], v[32:35]
	v_mfma_f32_16x16x32_bf16 v[20:23], v[202:205], v[182:185], v[20:23]
	v_mfma_f32_16x16x32_bf16 v[16:19], v[210:213], v[182:185], v[16:19]
	v_mfma_f32_16x16x32_bf16 v[4:7], v[202:205], v[190:193], v[4:7]
	v_mfma_f32_16x16x32_bf16 v[0:3], v[210:213], v[190:193], v[0:3]
	v_mfma_f32_16x16x32_bf16 v[52:55], v[206:209], v[170:173], v[52:55]
	v_mfma_f32_16x16x32_bf16 v[48:51], v[214:217], v[170:173], v[48:51]
	v_mfma_f32_16x16x32_bf16 v[36:39], v[206:209], v[178:181], v[36:39]
	v_mfma_f32_16x16x32_bf16 v[32:35], v[214:217], v[178:181], v[32:35]
	v_mfma_f32_16x16x32_bf16 v[20:23], v[206:209], v[186:189], v[20:23]
	v_mfma_f32_16x16x32_bf16 v[16:19], v[214:217], v[186:189], v[16:19]
	v_mfma_f32_16x16x32_bf16 v[4:7], v[206:209], v[194:197], v[4:7]
	v_mfma_f32_16x16x32_bf16 v[0:3], v[214:217], v[194:197], v[0:3]
	s_setprio 0
	s_add_i32 s46, s46, 2
	s_add_u32 s16, s16, 0x100
	s_addc_u32 s17, s17, 0
	s_add_u32 s44, s44, 0x100
	s_addc_u32 s45, s45, 0
	s_cmp_gt_u32 s46, 13
	s_cbranch_scc1 .Lconc_last_g11
	s_barrier
	s_branch .LBB0_1021

; #define PG8_STAGE(bufoff, gbase, voff) do { _Pragma("unroll") for (int _i = 0; _i < 2; ++_i) \
;         __builtin_amdgcn_global_load_lds((const unsigned*)((const char*)(gbase) + (voff)[_i]), (LAS unsigned*)(lds + (bufoff) + ldsw + _i * 8192), 16, 0, 0); } while (0)
; #define PG8_LDA(dst, b, h) do { _Pragma("unroll") for (int m = 0; m < 4; ++m) _Pragma("unroll") for (int k = 0; k < 2; ++k) dst[m][k] = *(const LAS bf16x8*)(lds + PG8_SA(b, h) + aoff + m * 2048 + k * 1024); } while (0)
; #define PG8_LDB(dst, b, h) do { _Pragma("unroll") for (int n = 0; n < 2; ++n) _Pragma("unroll") for (int k = 0; k < 2; ++k) dst[n][k] = *(const LAS bf16x8*)(lds + PG8_SB(b, h) + boff + n * 2048 + k * 1024); } while (0)
; #define PG8_WAIT_V(n) asm volatile("s_waitcnt vmcnt(" #n ")" ::: "memory")
; #define PG8_WAIT_L(n) asm volatile("s_waitcnt lgkmcnt(" #n ")" ::: "memory")
; template <class Epi, class Sched>
; __device__ __forceinline__ void gemm_phase(LAS unsigned char* lds, const Gemm g, const Sched& S, const Epi& E) {
;     ...
;         const char* nA = has_next ? (const char*)g.A + (size_t)nxt.pm * tstep : cA; const char* nB = has_next ? (const char*)g.Bt + (size_t)nxt.pn * tstep : cB;
;         for (int t = 0; t < nt; t += 2) {
;             const bool last = (t == nt - 2);
;             const char* a1 = cA + (size_t)(t + 1) * kstep;
;             const char* a2 = last ? nA : cA + (size_t)(t + 2) * kstep; const char* b2 = last ? nB : cB + (size_t)(t + 2) * kstep;
;             const char* a3 = a2 + kstep; const char* b3 = b2 + kstep;
;             PG8_LDB(B0, 0, 0); PG8_SCHED; PG8_LDA(At, 0, 0); PG8_STAGE(PG8_SA(1, 1), a1 + hstep, voffA);
;             PG8_WAIT_L(8); PG8_BAR; PG8_WAIT_L(0); PG8_MMA(0, 0, At, B0); PG8_BAR; PG8_SCHED;
;             PG8_LDB(B1, 0, 1); PG8_STAGE(PG8_SB(0, 0), b2, voffB);
;             PG8_BAR; PG8_WAIT_L(0); PG8_MMA(0, 1, At, B1); PG8_BAR;
;             PG8_LDA(At, 0, 1); PG8_STAGE(PG8_SA(0, 0), a2, voffA);
;             PG8_BAR; PG8_WAIT_L(0); PG8_MMA(1, 0, At, B0); PG8_BAR; PG8_SCHED;
;             PG8_STAGE(PG8_SB(0, 1), b2 + hstep, voffB);
;             PG8_WAIT_V(6); PG8_BAR; PG8_MMA(1, 1, At, B1); PG8_BAR;
;             PG8_LDB(B0, 1, 0); PG8_SCHED; PG8_LDA(At, 1, 0); PG8_STAGE(PG8_SA(0, 1), a2 + hstep, voffA);
;             PG8_WAIT_L(8); PG8_BAR; PG8_WAIT_L(0); PG8_MMA(0, 0, At, B0); PG8_BAR; PG8_SCHED;
.LBB0_1096:
	s_add_u32 s54, s24, 0x100
	s_addc_u32 s55, s25, 0
	s_mov_b32 s56, -2
	ds_read_b128 v[128:131], v241
	ds_read_b128 v[132:135], v241 offset:1024
	ds_read_b128 v[136:139], v241 offset:2048
	ds_read_b128 v[140:143], v241 offset:3072
	s_add_u32 s24, s22, 0x100
	s_addc_u32 s25, s23, 0
	s_cmp_eq_u32 s56, 40
	s_cselect_b32 s29, s5, s25
	s_cselect_b32 s28, s4, s24
	s_cselect_b32 s27, s7, s55
	s_cselect_b32 s26, s6, s54
	v_lshl_add_u64 v[176:177], s[22:23], 0, v[196:197]
	s_add_i32 m0, s35, 0xc000
	ds_read_b128 v[144:147], v242
	ds_read_b128 v[148:151], v242 offset:1024
	ds_read_b128 v[152:155], v242 offset:2048
	ds_read_b128 v[156:159], v242 offset:3072
	ds_read_b128 v[160:163], v242 offset:4096
	ds_read_b128 v[164:167], v242 offset:5120
	ds_read_b128 v[168:171], v242 offset:6144
	ds_read_b128 v[172:175], v242 offset:7168
	global_load_lds_dwordx4 v[176:177], off
	v_lshl_add_u64 v[176:177], s[22:23], 0, v[198:199]
	s_add_i32 m0, s35, 0xe000
	s_nop 0
	global_load_lds_dwordx4 v[176:177], off
	s_waitcnt lgkmcnt(8)
	s_waitcnt vmcnt(8)
	s_setprio 1
	s_barrier
	s_waitcnt lgkmcnt(0)
	v_mfma_f32_16x16x32_bf16 v[124:127], v[128:131], v[144:147], 0
	v_mfma_f32_16x16x32_bf16 v[120:123], v[136:139], v[144:147], 0
	v_mfma_f32_16x16x32_bf16 v[108:111], v[128:131], v[152:155], 0
	v_mfma_f32_16x16x32_bf16 v[104:107], v[136:139], v[152:155], 0
	v_mfma_f32_16x16x32_bf16 v[92:95], v[128:131], v[160:163], 0
	v_mfma_f32_16x16x32_bf16 v[88:91], v[136:139], v[160:163], 0
	v_mfma_f32_16x16x32_bf16 v[76:79], v[128:131], v[168:171], 0
	v_mfma_f32_16x16x32_bf16 v[72:75], v[136:139], v[168:171], 0
	v_mfma_f32_16x16x32_bf16 v[124:127], v[132:135], v[148:151], v[124:127]
	v_mfma_f32_16x16x32_bf16 v[120:123], v[140:143], v[148:151], v[120:123]
	v_mfma_f32_16x16x32_bf16 v[108:111], v[132:135], v[156:159], v[108:111]
	v_mfma_f32_16x16x32_bf16 v[104:107], v[140:143], v[156:159], v[104:107]
	v_mfma_f32_16x16x32_bf16 v[92:95], v[132:135], v[164:167], v[92:95]
	v_mfma_f32_16x16x32_bf16 v[88:91], v[140:143], v[164:167], v[88:91]
	v_mfma_f32_16x16x32_bf16 v[76:79], v[132:135], v[172:175], v[76:79]
	v_mfma_f32_16x16x32_bf16 v[72:75], v[140:143], v[172:175], v[72:75]
	s_barrier
	s_setprio 0
	s_add_i32 s22, s48, s34
	s_mov_b32 m0, s22
	ds_read_b128 v[176:179], v243
	ds_read_b128 v[180:183], v243 offset:1024
	ds_read_b128 v[184:187], v243 offset:2048
	ds_read_b128 v[206:209], v243 offset:3072
	global_load_lds_dwordx4 v190, s[26:27]
	s_add_i32 m0, s22, 0x2000
	s_nop 0
	global_load_lds_dwordx4 v194, s[26:27]
	s_waitcnt vmcnt(8)
	s_setprio 1
	s_barrier
	s_waitcnt lgkmcnt(0)
	v_mfma_f32_16x16x32_bf16 v[116:119], v[176:179], v[144:147], 0
	v_mfma_f32_16x16x32_bf16 v[112:115], v[184:187], v[144:147], 0
	v_mfma_f32_16x16x32_bf16 v[100:103], v[176:179], v[152:155], 0
	v_mfma_f32_16x16x32_bf16 v[96:99], v[184:187], v[152:155], 0
	v_mfma_f32_16x16x32_bf16 v[84:87], v[176:179], v[160:163], 0
	v_mfma_f32_16x16x32_bf16 v[80:83], v[184:187], v[160:163], 0
	v_mfma_f32_16x16x32_bf16 v[68:71], v[176:179], v[168:171], 0
	v_mfma_f32_16x16x32_bf16 v[64:67], v[184:187], v[168:171], 0
	v_mfma_f32_16x16x32_bf16 v[116:119], v[180:183], v[148:151], v[116:119]
	v_mfma_f32_16x16x32_bf16 v[112:115], v[206:209], v[148:151], v[112:115]
	v_mfma_f32_16x16x32_bf16 v[100:103], v[180:183], v[156:159], v[100:103]
	v_mfma_f32_16x16x32_bf16 v[96:99], v[206:209], v[156:159], v[96:99]
	v_mfma_f32_16x16x32_bf16 v[84:87], v[180:183], v[164:167], v[84:87]
	v_mfma_f32_16x16x32_bf16 v[80:83], v[206:209], v[164:167], v[80:83]
	v_mfma_f32_16x16x32_bf16 v[68:71], v[180:183], v[172:175], v[68:71]
	v_mfma_f32_16x16x32_bf16 v[64:67], v[206:209], v[172:175], v[64:67]
	s_mov_b32 m0, s35
	v_lshl_add_u64 v[214:215], s[28:29], 0, v[188:189]
	s_barrier
	s_setprio 0
	ds_read_b128 v[144:147], v242 offset:16384
	ds_read_b128 v[148:151], v242 offset:17408
	ds_read_b128 v[152:155], v242 offset:18432
	ds_read_b128 v[156:159], v242 offset:19456
	ds_read_b128 v[160:163], v242 offset:20480
	ds_read_b128 v[164:167], v242 offset:21504
	ds_read_b128 v[168:171], v242 offset:22528
	ds_read_b128 v[172:175], v242 offset:23552
	global_load_lds_dwordx4 v188, s[28:29]
	v_lshl_add_u64 v[216:217], s[28:29], 0, v[192:193]
	s_mov_b32 m0, s36
	s_nop 0
	global_load_lds_dwordx4 v192, s[28:29]
	s_setprio 1
	s_barrier
	s_waitcnt lgkmcnt(0)
	v_mfma_f32_16x16x32_bf16 v[60:63], v[128:131], v[144:147], 0
	v_mfma_f32_16x16x32_bf16 v[56:59], v[136:139], v[144:147], 0
	v_mfma_f32_16x16x32_bf16 v[44:47], v[128:131], v[152:155], 0
	v_mfma_f32_16x16x32_bf16 v[40:43], v[136:139], v[152:155], 0
	v_mfma_f32_16x16x32_bf16 v[28:31], v[128:131], v[160:163], 0
	v_mfma_f32_16x16x32_bf16 v[24:27], v[136:139], v[160:163], 0
	v_mfma_f32_16x16x32_bf16 v[12:15], v[128:131], v[168:171], 0
	v_mfma_f32_16x16x32_bf16 v[8:11], v[136:139], v[168:171], 0
	v_mfma_f32_16x16x32_bf16 v[60:63], v[132:135], v[148:151], v[60:63]
	v_mfma_f32_16x16x32_bf16 v[56:59], v[140:143], v[148:151], v[56:59]
	v_mfma_f32_16x16x32_bf16 v[44:47], v[132:135], v[156:159], v[44:47]
	v_mfma_f32_16x16x32_bf16 v[40:43], v[140:143], v[156:159], v[40:43]
	v_mfma_f32_16x16x32_bf16 v[28:31], v[132:135], v[164:167], v[28:31]
	v_mfma_f32_16x16x32_bf16 v[24:27], v[140:143], v[164:167], v[24:27]
	v_mfma_f32_16x16x32_bf16 v[12:15], v[132:135], v[172:175], v[12:15]
	v_mfma_f32_16x16x32_bf16 v[8:11], v[140:143], v[172:175], v[8:11]
	s_barrier
	s_setprio 0
	s_add_u32 s22, s26, 0xb0000
	s_addc_u32 s23, s27, 0
	s_add_i32 s57, s49, s34
	s_mov_b32 m0, s57
	s_nop 0
	global_load_lds_dwordx4 v190, s[22:23]
	s_add_i32 m0, s57, 0x2000
	s_nop 0
	global_load_lds_dwordx4 v194, s[22:23]
	s_add_u32 s22, s28, 0xb0000
	s_addc_u32 s23, s29, 0
	s_mov_b32 m0, s37
	s_nop 0
	global_load_lds_dwordx4 v188, s[22:23]
	s_mov_b32 m0, s38
	s_nop 0
	global_load_lds_dwordx4 v192, s[22:23]
	s_waitcnt vmcnt(10)
	s_setprio 1
	s_barrier
; #define PG8_STAGE(bufoff, gbase, voff) do { _Pragma("unroll") for (int _i = 0; _i < 2; ++_i) \
;         __builtin_amdgcn_global_load_lds((const unsigned*)((const char*)(gbase) + (voff)[_i]), (LAS unsigned*)(lds + (bufoff) + ldsw + _i * 8192), 16, 0, 0); } while (0)
; #define PG8_LDA(dst, b, h) do { _Pragma("unroll") for (int m = 0; m < 4; ++m) _Pragma("unroll") for (int k = 0; k < 2; ++k) dst[m][k] = *(const LAS bf16x8*)(lds + PG8_SA(b, h) + aoff + m * 2048 + k * 1024); } while (0)
; #define PG8_LDB(dst, b, h) do { _Pragma("unroll") for (int n = 0; n < 2; ++n) _Pragma("unroll") for (int k = 0; k < 2; ++k) dst[n][k] = *(const LAS bf16x8*)(lds + PG8_SB(b, h) + boff + n * 2048 + k * 1024); } while (0)
; #define PG8_MMA(ai, bj, At, Bt) do { __builtin_amdgcn_s_setprio(1); _Pragma("unroll") for (int m = 0; m < 4; ++m) _Pragma("unroll") for (int n = 0; n < 2; ++n) _Pragma("unroll") for (int k = 0; k < 2; ++k) \
;         acc[ai][bj][m][n] = __builtin_amdgcn_mfma_f32_16x16x32_bf16(Bt[n][k], At[m][k], acc[ai][bj][m][n], 0, 0, 0); __builtin_amdgcn_s_setprio(0); } while (0)
; #define PG8_WAIT_V(n) asm volatile("s_waitcnt vmcnt(" #n ")" ::: "memory")
; #define PG8_WAIT_L(n) asm volatile("s_waitcnt lgkmcnt(" #n ")" ::: "memory")
; #define PG8_BAR __builtin_amdgcn_s_barrier()
; #define PG8_SCHED __builtin_amdgcn_sched_barrier(0)
; template <class Epi, class Sched>
; __device__ __forceinline__ void gemm_phase(LAS unsigned char* lds, const Gemm g, const Sched& S, const Epi& E) {
;     ...
;             PG8_WAIT_V(6); PG8_BAR; PG8_MMA(1, 1, At, B1); PG8_BAR;
;             PG8_LDB(B0, 1, 0); PG8_SCHED; PG8_LDA(At, 1, 0); PG8_STAGE(PG8_SA(0, 1), a2 + hstep, voffA);
;             PG8_WAIT_L(8); PG8_BAR; PG8_WAIT_L(0); PG8_MMA(0, 0, At, B0); PG8_BAR; PG8_SCHED;
;             PG8_LDB(B1, 1, 1); PG8_STAGE(PG8_SB(1, 0), b3, voffB);
;             PG8_BAR; PG8_WAIT_L(0); PG8_MMA(0, 1, At, B1); PG8_BAR;
;             PG8_LDA(At, 1, 1); PG8_STAGE(PG8_SA(1, 0), a3, voffA);
;             PG8_BAR; PG8_WAIT_L(0); PG8_MMA(1, 0, At, B0); PG8_BAR; PG8_SCHED;
	v_mfma_f32_16x16x32_bf16 v[52:55], v[176:179], v[144:147], 0
	v_mfma_f32_16x16x32_bf16 v[48:51], v[184:187], v[144:147], 0
	v_mfma_f32_16x16x32_bf16 v[36:39], v[176:179], v[152:155], 0
	v_mfma_f32_16x16x32_bf16 v[32:35], v[184:187], v[152:155], 0
	v_mfma_f32_16x16x32_bf16 v[20:23], v[176:179], v[160:163], 0
	v_mfma_f32_16x16x32_bf16 v[16:19], v[184:187], v[160:163], 0
	v_mfma_f32_16x16x32_bf16 v[4:7], v[176:179], v[168:171], 0
	v_mfma_f32_16x16x32_bf16 v[0:3], v[184:187], v[168:171], 0
	v_mfma_f32_16x16x32_bf16 v[52:55], v[180:183], v[148:151], v[52:55]
	v_mfma_f32_16x16x32_bf16 v[48:51], v[206:209], v[148:151], v[48:51]
	v_mfma_f32_16x16x32_bf16 v[36:39], v[180:183], v[156:159], v[36:39]
	v_mfma_f32_16x16x32_bf16 v[32:35], v[206:209], v[156:159], v[32:35]
	v_mfma_f32_16x16x32_bf16 v[20:23], v[180:183], v[164:167], v[20:23]
	v_mfma_f32_16x16x32_bf16 v[16:19], v[206:209], v[164:167], v[16:19]
	v_mfma_f32_16x16x32_bf16 v[4:7], v[180:183], v[172:175], v[4:7]
	v_mfma_f32_16x16x32_bf16 v[0:3], v[206:209], v[172:175], v[0:3]
	s_add_i32 s57, 0, 0x18000
	v_add_u32_e32 v140, s57, v240
	s_barrier
	s_setprio 0
	ds_read_b128 v[128:131], v140
	ds_read_b128 v[132:135], v140 offset:1024
	ds_read_b128 v[136:139], v140 offset:2048
	ds_read_b128 v[140:143], v140 offset:3072
	ds_read_b128 v[144:147], v242 offset:32768
	ds_read_b128 v[148:151], v242 offset:33792
	ds_read_b128 v[152:155], v242 offset:34816
	ds_read_b128 v[156:159], v242 offset:35840
	ds_read_b128 v[160:163], v242 offset:36864
	ds_read_b128 v[164:167], v242 offset:37888
	ds_read_b128 v[168:171], v242 offset:38912
	ds_read_b128 v[172:175], v242 offset:39936
	s_waitcnt lgkmcnt(8)
	s_waitcnt vmcnt(8)
	s_setprio 1
	s_barrier
	s_waitcnt lgkmcnt(0)
	v_mfma_f32_16x16x32_bf16 v[124:127], v[128:131], v[144:147], v[124:127]
	v_mfma_f32_16x16x32_bf16 v[120:123], v[136:139], v[144:147], v[120:123]
	v_mfma_f32_16x16x32_bf16 v[108:111], v[128:131], v[152:155], v[108:111]
	v_mfma_f32_16x16x32_bf16 v[104:107], v[136:139], v[152:155], v[104:107]
	v_mfma_f32_16x16x32_bf16 v[92:95], v[128:131], v[160:163], v[92:95]
	v_mfma_f32_16x16x32_bf16 v[88:91], v[136:139], v[160:163], v[88:91]
	v_mfma_f32_16x16x32_bf16 v[76:79], v[128:131], v[168:171], v[76:79]
	v_mfma_f32_16x16x32_bf16 v[72:75], v[136:139], v[168:171], v[72:75]
	v_mfma_f32_16x16x32_bf16 v[124:127], v[132:135], v[148:151], v[124:127]
	v_mfma_f32_16x16x32_bf16 v[120:123], v[140:143], v[148:151], v[120:123]
	v_mfma_f32_16x16x32_bf16 v[108:111], v[132:135], v[156:159], v[108:111]
	v_mfma_f32_16x16x32_bf16 v[104:107], v[140:143], v[156:159], v[104:107]
	v_mfma_f32_16x16x32_bf16 v[92:95], v[132:135], v[164:167], v[92:95]
	v_mfma_f32_16x16x32_bf16 v[88:91], v[140:143], v[164:167], v[88:91]
	v_mfma_f32_16x16x32_bf16 v[76:79], v[132:135], v[172:175], v[76:79]
	v_mfma_f32_16x16x32_bf16 v[72:75], v[140:143], v[172:175], v[72:75]
	s_barrier
	s_setprio 0
	s_add_i32 s28, 0, 0x1c000
	s_add_i32 s22, s57, s34
	v_add_u32_e32 v206, s28, v240
	s_add_u32 s0, s26, 0x80
	s_addc_u32 s1, s27, 0
	s_mov_b32 m0, s22
	ds_read_b128 v[176:179], v206
	ds_read_b128 v[180:183], v206 offset:1024
	ds_read_b128 v[184:187], v206 offset:2048
	ds_read_b128 v[206:209], v206 offset:3072
	global_load_lds_dwordx4 v190, s[0:1]
	s_add_i32 m0, s22, 0x2000
	s_nop 0
	global_load_lds_dwordx4 v194, s[0:1]
	s_waitcnt vmcnt(8)
	s_setprio 1
	s_barrier
	s_waitcnt lgkmcnt(0)
	v_mfma_f32_16x16x32_bf16 v[116:119], v[176:179], v[144:147], v[116:119]
	v_mfma_f32_16x16x32_bf16 v[112:115], v[184:187], v[144:147], v[112:115]
	v_mfma_f32_16x16x32_bf16 v[100:103], v[176:179], v[152:155], v[100:103]
	v_mfma_f32_16x16x32_bf16 v[96:99], v[184:187], v[152:155], v[96:99]
	v_mfma_f32_16x16x32_bf16 v[84:87], v[176:179], v[160:163], v[84:87]
	v_mfma_f32_16x16x32_bf16 v[80:83], v[184:187], v[160:163], v[80:83]
	v_mfma_f32_16x16x32_bf16 v[68:71], v[176:179], v[168:171], v[68:71]
	v_mfma_f32_16x16x32_bf16 v[64:67], v[184:187], v[168:171], v[64:67]
	v_mfma_f32_16x16x32_bf16 v[116:119], v[180:183], v[148:151], v[116:119]
	v_mfma_f32_16x16x32_bf16 v[112:115], v[206:209], v[148:151], v[112:115]
	v_mfma_f32_16x16x32_bf16 v[100:103], v[180:183], v[156:159], v[100:103]
	v_mfma_f32_16x16x32_bf16 v[96:99], v[206:209], v[156:159], v[96:99]
	v_mfma_f32_16x16x32_bf16 v[84:87], v[180:183], v[164:167], v[84:87]
	v_mfma_f32_16x16x32_bf16 v[80:83], v[206:209], v[164:167], v[80:83]
	v_mfma_f32_16x16x32_bf16 v[68:71], v[180:183], v[172:175], v[68:71]
	v_mfma_f32_16x16x32_bf16 v[64:67], v[206:209], v[172:175], v[64:67]
	s_mov_b32 m0, s44
	s_mov_b64 s[0:1], 0x80
	v_lshl_add_u64 v[210:211], v[214:215], 0, s[0:1]
	s_barrier
	s_setprio 0
	ds_read_b128 v[144:147], v242 offset:49152
	ds_read_b128 v[148:151], v242 offset:50176
	ds_read_b128 v[152:155], v242 offset:51200
	ds_read_b128 v[156:159], v242 offset:52224
	ds_read_b128 v[160:163], v242 offset:53248
	ds_read_b128 v[164:167], v242 offset:54272
	ds_read_b128 v[168:171], v242 offset:55296
	ds_read_b128 v[172:175], v242 offset:56320
	global_load_lds_dwordx4 v[210:211], off
	v_lshl_add_u64 v[210:211], v[216:217], 0, s[0:1]
	s_mov_b32 m0, s45
	s_nop 0
	global_load_lds_dwordx4 v[210:211], off
	s_setprio 1
	s_barrier
; #define PG8_STAGE(bufoff, gbase, voff) do { _Pragma("unroll") for (int _i = 0; _i < 2; ++_i) \
;         __builtin_amdgcn_global_load_lds((const unsigned*)((const char*)(gbase) + (voff)[_i]), (LAS unsigned*)(lds + (bufoff) + ldsw + _i * 8192), 16, 0, 0); } while (0)
; #define PG8_LDA(dst, b, h) do { _Pragma("unroll") for (int m = 0; m < 4; ++m) _Pragma("unroll") for (int k = 0; k < 2; ++k) dst[m][k] = *(const LAS bf16x8*)(lds + PG8_SA(b, h) + aoff + m * 2048 + k * 1024); } while (0)
; #define PG8_LDB(dst, b, h) do { _Pragma("unroll") for (int n = 0; n < 2; ++n) _Pragma("unroll") for (int k = 0; k < 2; ++k) dst[n][k] = *(const LAS bf16x8*)(lds + PG8_SB(b, h) + boff + n * 2048 + k * 1024); } while (0)
; #define PG8_MMA(ai, bj, At, Bt) do { __builtin_amdgcn_s_setprio(1); _Pragma("unroll") for (int m = 0; m < 4; ++m) _Pragma("unroll") for (int n = 0; n < 2; ++n) _Pragma("unroll") for (int k = 0; k < 2; ++k) \
;         acc[ai][bj][m][n] = __builtin_amdgcn_mfma_f32_16x16x32_bf16(Bt[n][k], At[m][k], acc[ai][bj][m][n], 0, 0, 0); __builtin_amdgcn_s_setprio(0); } while (0)
; #define PG8_WAIT_V(n) asm volatile("s_waitcnt vmcnt(" #n ")" ::: "memory")
; #define PG8_WAIT_L(n) asm volatile("s_waitcnt lgkmcnt(" #n ")" ::: "memory")
; #define PG8_BAR __builtin_amdgcn_s_barrier()
; #define PG8_SCHED __builtin_amdgcn_sched_barrier(0)
; template <class Epi, class Sched>
; __device__ __forceinline__ void gemm_phase(LAS unsigned char* lds, const Gemm g, const Sched& S, const Epi& E) {
;     ...
;             PG8_LDB(B0, 0, 0); PG8_SCHED; PG8_LDA(At, 0, 0); PG8_STAGE(PG8_SA(1, 1), a1 + hstep, voffA);
;             PG8_WAIT_L(8); PG8_BAR; PG8_WAIT_L(0); PG8_MMA(0, 0, At, B0); PG8_BAR; PG8_SCHED;
;             PG8_LDB(B1, 0, 1); PG8_STAGE(PG8_SB(0, 0), b2, voffB);
;             PG8_BAR; PG8_WAIT_L(0); PG8_MMA(0, 1, At, B1); PG8_BAR;
;             PG8_LDA(At, 0, 1); PG8_STAGE(PG8_SA(0, 0), a2, voffA);
;     ...
;             PG8_BAR; PG8_WAIT_L(0); PG8_MMA(0, 1, At, B1); PG8_BAR;
;             PG8_LDA(At, 1, 1); PG8_STAGE(PG8_SA(1, 0), a3, voffA);
;             PG8_BAR; PG8_WAIT_L(0); PG8_MMA(1, 0, At, B0); PG8_BAR; PG8_SCHED;
;             PG8_STAGE(PG8_SB(1, 1), b3 + hstep, voffB);
;             PG8_WAIT_V(6); PG8_BAR; PG8_MMA(1, 1, At, B1); PG8_BAR;
	s_waitcnt lgkmcnt(0)
	v_mfma_f32_16x16x32_bf16 v[60:63], v[128:131], v[144:147], v[60:63]
	v_mfma_f32_16x16x32_bf16 v[56:59], v[136:139], v[144:147], v[56:59]
	v_mfma_f32_16x16x32_bf16 v[44:47], v[128:131], v[152:155], v[44:47]
	v_mfma_f32_16x16x32_bf16 v[40:43], v[136:139], v[152:155], v[40:43]
	v_mfma_f32_16x16x32_bf16 v[28:31], v[128:131], v[160:163], v[28:31]
	v_mfma_f32_16x16x32_bf16 v[24:27], v[136:139], v[160:163], v[24:27]
	v_mfma_f32_16x16x32_bf16 v[12:15], v[128:131], v[168:171], v[12:15]
	v_mfma_f32_16x16x32_bf16 v[8:11], v[136:139], v[168:171], v[8:11]
	v_mfma_f32_16x16x32_bf16 v[60:63], v[132:135], v[148:151], v[60:63]
	v_mfma_f32_16x16x32_bf16 v[56:59], v[140:143], v[148:151], v[56:59]
	v_mfma_f32_16x16x32_bf16 v[44:47], v[132:135], v[156:159], v[44:47]
	v_mfma_f32_16x16x32_bf16 v[40:43], v[140:143], v[156:159], v[40:43]
	v_mfma_f32_16x16x32_bf16 v[28:31], v[132:135], v[164:167], v[28:31]
	v_mfma_f32_16x16x32_bf16 v[24:27], v[140:143], v[164:167], v[24:27]
	v_mfma_f32_16x16x32_bf16 v[12:15], v[132:135], v[172:175], v[12:15]
	v_mfma_f32_16x16x32_bf16 v[8:11], v[140:143], v[172:175], v[8:11]
	s_barrier
	s_setprio 0
	s_add_u32 s22, s26, 0xb0080
	s_addc_u32 s23, s27, 0
	s_add_i32 s26, s28, s34
	s_mov_b32 m0, s26
	s_nop 0
	global_load_lds_dwordx4 v190, s[22:23]
	s_add_i32 m0, s26, 0x2000
	s_nop 0
	global_load_lds_dwordx4 v194, s[22:23]
	s_waitcnt vmcnt(8)
	s_setprio 1
	s_barrier
	v_mfma_f32_16x16x32_bf16 v[52:55], v[176:179], v[144:147], v[52:55]
	v_mfma_f32_16x16x32_bf16 v[48:51], v[184:187], v[144:147], v[48:51]
	v_mfma_f32_16x16x32_bf16 v[36:39], v[176:179], v[152:155], v[36:39]
	v_mfma_f32_16x16x32_bf16 v[32:35], v[184:187], v[152:155], v[32:35]
	v_mfma_f32_16x16x32_bf16 v[20:23], v[176:179], v[160:163], v[20:23]
	v_mfma_f32_16x16x32_bf16 v[16:19], v[184:187], v[160:163], v[16:19]
	v_mfma_f32_16x16x32_bf16 v[4:7], v[176:179], v[168:171], v[4:7]
	v_mfma_f32_16x16x32_bf16 v[0:3], v[184:187], v[168:171], v[0:3]
	v_mfma_f32_16x16x32_bf16 v[52:55], v[180:183], v[148:151], v[52:55]
	v_mfma_f32_16x16x32_bf16 v[48:51], v[206:209], v[148:151], v[48:51]
	v_mfma_f32_16x16x32_bf16 v[36:39], v[180:183], v[156:159], v[36:39]
	v_mfma_f32_16x16x32_bf16 v[32:35], v[206:209], v[156:159], v[32:35]
	v_mfma_f32_16x16x32_bf16 v[20:23], v[180:183], v[164:167], v[20:23]
	v_mfma_f32_16x16x32_bf16 v[16:19], v[206:209], v[164:167], v[16:19]
	v_mfma_f32_16x16x32_bf16 v[4:7], v[180:183], v[172:175], v[4:7]
	v_mfma_f32_16x16x32_bf16 v[0:3], v[206:209], v[172:175], v[0:3]
	s_add_i32 s56, s56, 2
	s_add_u32 s54, s54, 0x100
	s_addc_u32 s55, s55, 0
	s_cmp_gt_u32 s56, 41
	s_mov_b64 s[22:23], s[24:25]
	s_barrier
	s_setprio 0
.LBB0_1097:
	ds_read_b128 v[128:131], v241
	ds_read_b128 v[132:135], v241 offset:1024
	ds_read_b128 v[136:139], v241 offset:2048
	ds_read_b128 v[140:143], v241 offset:3072
	s_add_u32 s24, s22, 0x100
	s_addc_u32 s25, s23, 0
	s_cmp_eq_u32 s56, 40
	s_cselect_b32 s29, s5, s25
	s_cselect_b32 s28, s4, s24
	s_cselect_b32 s27, s7, s55
	s_cselect_b32 s26, s6, s54
	v_lshl_add_u64 v[176:177], s[22:23], 0, v[196:197]
	s_add_i32 m0, s35, 0xc000
	ds_read_b128 v[144:147], v242
	ds_read_b128 v[148:151], v242 offset:1024
	ds_read_b128 v[152:155], v242 offset:2048
	ds_read_b128 v[156:159], v242 offset:3072
	ds_read_b128 v[160:163], v242 offset:4096
	ds_read_b128 v[164:167], v242 offset:5120
	ds_read_b128 v[168:171], v242 offset:6144
	ds_read_b128 v[172:175], v242 offset:7168
	global_load_lds_dwordx4 v[176:177], off
	v_lshl_add_u64 v[176:177], s[22:23], 0, v[198:199]
	s_add_i32 m0, s35, 0xe000
	s_nop 0
	global_load_lds_dwordx4 v[176:177], off
	s_waitcnt lgkmcnt(8)
	s_waitcnt vmcnt(8)
	s_setprio 1
	s_barrier
	s_waitcnt lgkmcnt(0)
	v_mfma_f32_16x16x32_bf16 v[124:127], v[128:131], v[144:147], v[124:127]
	v_mfma_f32_16x16x32_bf16 v[120:123], v[136:139], v[144:147], v[120:123]
	v_mfma_f32_16x16x32_bf16 v[108:111], v[128:131], v[152:155], v[108:111]
	v_mfma_f32_16x16x32_bf16 v[104:107], v[136:139], v[152:155], v[104:107]
	v_mfma_f32_16x16x32_bf16 v[92:95], v[128:131], v[160:163], v[92:95]
	v_mfma_f32_16x16x32_bf16 v[88:91], v[136:139], v[160:163], v[88:91]
	v_mfma_f32_16x16x32_bf16 v[76:79], v[128:131], v[168:171], v[76:79]
	v_mfma_f32_16x16x32_bf16 v[72:75], v[136:139], v[168:171], v[72:75]
	v_mfma_f32_16x16x32_bf16 v[124:127], v[132:135], v[148:151], v[124:127]
	v_mfma_f32_16x16x32_bf16 v[120:123], v[140:143], v[148:151], v[120:123]
	v_mfma_f32_16x16x32_bf16 v[108:111], v[132:135], v[156:159], v[108:111]
	v_mfma_f32_16x16x32_bf16 v[104:107], v[140:143], v[156:159], v[104:107]
	v_mfma_f32_16x16x32_bf16 v[92:95], v[132:135], v[164:167], v[92:95]
	v_mfma_f32_16x16x32_bf16 v[88:91], v[140:143], v[164:167], v[88:91]
	v_mfma_f32_16x16x32_bf16 v[76:79], v[132:135], v[172:175], v[76:79]
	v_mfma_f32_16x16x32_bf16 v[72:75], v[140:143], v[172:175], v[72:75]
	s_barrier
	s_setprio 0
	s_add_i32 s22, s48, s34
	s_mov_b32 m0, s22
	ds_read_b128 v[176:179], v243
	ds_read_b128 v[180:183], v243 offset:1024
	ds_read_b128 v[184:187], v243 offset:2048
	ds_read_b128 v[206:209], v243 offset:3072
	global_load_lds_dwordx4 v190, s[26:27]
	s_add_i32 m0, s22, 0x2000
	s_nop 0
	global_load_lds_dwordx4 v194, s[26:27]
	s_waitcnt vmcnt(8)
	s_setprio 1
	s_barrier
; #define PG8_STAGE(bufoff, gbase, voff) do { _Pragma("unroll") for (int _i = 0; _i < 2; ++_i) \
;         __builtin_amdgcn_global_load_lds((const unsigned*)((const char*)(gbase) + (voff)[_i]), (LAS unsigned*)(lds + (bufoff) + ldsw + _i * 8192), 16, 0, 0); } while (0)
; #define PG8_LDA(dst, b, h) do { _Pragma("unroll") for (int m = 0; m < 4; ++m) _Pragma("unroll") for (int k = 0; k < 2; ++k) dst[m][k] = *(const LAS bf16x8*)(lds + PG8_SA(b, h) + aoff + m * 2048 + k * 1024); } while (0)
; #define PG8_LDB(dst, b, h) do { _Pragma("unroll") for (int n = 0; n < 2; ++n) _Pragma("unroll") for (int k = 0; k < 2; ++k) dst[n][k] = *(const LAS bf16x8*)(lds + PG8_SB(b, h) + boff + n * 2048 + k * 1024); } while (0)
; #define PG8_MMA(ai, bj, At, Bt) do { __builtin_amdgcn_s_setprio(1); _Pragma("unroll") for (int m = 0; m < 4; ++m) _Pragma("unroll") for (int n = 0; n < 2; ++n) _Pragma("unroll") for (int k = 0; k < 2; ++k) \
;         acc[ai][bj][m][n] = __builtin_amdgcn_mfma_f32_16x16x32_bf16(Bt[n][k], At[m][k], acc[ai][bj][m][n], 0, 0, 0); __builtin_amdgcn_s_setprio(0); } while (0)
; #define PG8_WAIT_V(n) asm volatile("s_waitcnt vmcnt(" #n ")" ::: "memory")
; #define PG8_WAIT_L(n) asm volatile("s_waitcnt lgkmcnt(" #n ")" ::: "memory")
; #define PG8_BAR __builtin_amdgcn_s_barrier()
; #define PG8_SCHED __builtin_amdgcn_sched_barrier(0)
; template <class Epi, class Sched>
; __device__ __forceinline__ void gemm_phase(LAS unsigned char* lds, const Gemm g, const Sched& S, const Epi& E) {
;     ...
;             PG8_LDA(At, 0, 1); PG8_STAGE(PG8_SA(0, 0), a2, voffA);
;             PG8_BAR; PG8_WAIT_L(0); PG8_MMA(1, 0, At, B0); PG8_BAR; PG8_SCHED;
;             PG8_STAGE(PG8_SB(0, 1), b2 + hstep, voffB);
;             PG8_WAIT_V(6); PG8_BAR; PG8_MMA(1, 1, At, B1); PG8_BAR;
;             PG8_LDB(B0, 1, 0); PG8_SCHED; PG8_LDA(At, 1, 0); PG8_STAGE(PG8_SA(0, 1), a2 + hstep, voffA);
;             PG8_WAIT_L(8); PG8_BAR; PG8_WAIT_L(0); PG8_MMA(0, 0, At, B0); PG8_BAR; PG8_SCHED;
;             PG8_LDB(B1, 1, 1); PG8_STAGE(PG8_SB(1, 0), b3, voffB);
;             PG8_BAR; PG8_WAIT_L(0); PG8_MMA(0, 1, At, B1); PG8_BAR;
	s_waitcnt lgkmcnt(0)
	v_mfma_f32_16x16x32_bf16 v[116:119], v[176:179], v[144:147], v[116:119]
	v_mfma_f32_16x16x32_bf16 v[112:115], v[184:187], v[144:147], v[112:115]
	v_mfma_f32_16x16x32_bf16 v[100:103], v[176:179], v[152:155], v[100:103]
	v_mfma_f32_16x16x32_bf16 v[96:99], v[184:187], v[152:155], v[96:99]
	v_mfma_f32_16x16x32_bf16 v[84:87], v[176:179], v[160:163], v[84:87]
	v_mfma_f32_16x16x32_bf16 v[80:83], v[184:187], v[160:163], v[80:83]
	v_mfma_f32_16x16x32_bf16 v[68:71], v[176:179], v[168:171], v[68:71]
	v_mfma_f32_16x16x32_bf16 v[64:67], v[184:187], v[168:171], v[64:67]
	v_mfma_f32_16x16x32_bf16 v[116:119], v[180:183], v[148:151], v[116:119]
	v_mfma_f32_16x16x32_bf16 v[112:115], v[206:209], v[148:151], v[112:115]
	v_mfma_f32_16x16x32_bf16 v[100:103], v[180:183], v[156:159], v[100:103]
	v_mfma_f32_16x16x32_bf16 v[96:99], v[206:209], v[156:159], v[96:99]
	v_mfma_f32_16x16x32_bf16 v[84:87], v[180:183], v[164:167], v[84:87]
	v_mfma_f32_16x16x32_bf16 v[80:83], v[206:209], v[164:167], v[80:83]
	v_mfma_f32_16x16x32_bf16 v[68:71], v[180:183], v[172:175], v[68:71]
	v_mfma_f32_16x16x32_bf16 v[64:67], v[206:209], v[172:175], v[64:67]
	s_mov_b32 m0, s35
	v_lshl_add_u64 v[214:215], s[28:29], 0, v[188:189]
	s_barrier
	s_setprio 0
	ds_read_b128 v[144:147], v242 offset:16384
	ds_read_b128 v[148:151], v242 offset:17408
	ds_read_b128 v[152:155], v242 offset:18432
	ds_read_b128 v[156:159], v242 offset:19456
	ds_read_b128 v[160:163], v242 offset:20480
	ds_read_b128 v[164:167], v242 offset:21504
	ds_read_b128 v[168:171], v242 offset:22528
	ds_read_b128 v[172:175], v242 offset:23552
	global_load_lds_dwordx4 v188, s[28:29]
	v_lshl_add_u64 v[216:217], s[28:29], 0, v[192:193]
	s_mov_b32 m0, s36
	s_nop 0
	global_load_lds_dwordx4 v192, s[28:29]
	s_setprio 1
	s_barrier
	s_waitcnt lgkmcnt(0)
	v_mfma_f32_16x16x32_bf16 v[60:63], v[128:131], v[144:147], v[60:63]
	v_mfma_f32_16x16x32_bf16 v[56:59], v[136:139], v[144:147], v[56:59]
	v_mfma_f32_16x16x32_bf16 v[44:47], v[128:131], v[152:155], v[44:47]
	v_mfma_f32_16x16x32_bf16 v[40:43], v[136:139], v[152:155], v[40:43]
	v_mfma_f32_16x16x32_bf16 v[28:31], v[128:131], v[160:163], v[28:31]
	v_mfma_f32_16x16x32_bf16 v[24:27], v[136:139], v[160:163], v[24:27]
	v_mfma_f32_16x16x32_bf16 v[12:15], v[128:131], v[168:171], v[12:15]
	v_mfma_f32_16x16x32_bf16 v[8:11], v[136:139], v[168:171], v[8:11]
	v_mfma_f32_16x16x32_bf16 v[60:63], v[132:135], v[148:151], v[60:63]
	v_mfma_f32_16x16x32_bf16 v[56:59], v[140:143], v[148:151], v[56:59]
	v_mfma_f32_16x16x32_bf16 v[44:47], v[132:135], v[156:159], v[44:47]
	v_mfma_f32_16x16x32_bf16 v[40:43], v[140:143], v[156:159], v[40:43]
	v_mfma_f32_16x16x32_bf16 v[28:31], v[132:135], v[164:167], v[28:31]
	v_mfma_f32_16x16x32_bf16 v[24:27], v[140:143], v[164:167], v[24:27]
	v_mfma_f32_16x16x32_bf16 v[12:15], v[132:135], v[172:175], v[12:15]
	v_mfma_f32_16x16x32_bf16 v[8:11], v[140:143], v[172:175], v[8:11]
	s_barrier
	s_setprio 0
	s_add_u32 s22, s26, 0xb0000
	s_addc_u32 s23, s27, 0
	s_add_i32 s57, s49, s34
	s_mov_b32 m0, s57
	s_nop 0
	global_load_lds_dwordx4 v190, s[22:23]
	s_add_i32 m0, s57, 0x2000
	s_nop 0
	global_load_lds_dwordx4 v194, s[22:23]
	s_add_u32 s22, s28, 0xb0000
	s_addc_u32 s23, s29, 0
	s_mov_b32 m0, s37
	s_nop 0
	global_load_lds_dwordx4 v188, s[22:23]
	s_mov_b32 m0, s38
	s_nop 0
	global_load_lds_dwordx4 v192, s[22:23]
	s_waitcnt vmcnt(10)
	s_setprio 1
	s_barrier
	v_mfma_f32_16x16x32_bf16 v[52:55], v[176:179], v[144:147], v[52:55]
	v_mfma_f32_16x16x32_bf16 v[48:51], v[184:187], v[144:147], v[48:51]
	v_mfma_f32_16x16x32_bf16 v[36:39], v[176:179], v[152:155], v[36:39]
	v_mfma_f32_16x16x32_bf16 v[32:35], v[184:187], v[152:155], v[32:35]
	v_mfma_f32_16x16x32_bf16 v[20:23], v[176:179], v[160:163], v[20:23]
	v_mfma_f32_16x16x32_bf16 v[16:19], v[184:187], v[160:163], v[16:19]
	v_mfma_f32_16x16x32_bf16 v[4:7], v[176:179], v[168:171], v[4:7]
	v_mfma_f32_16x16x32_bf16 v[0:3], v[184:187], v[168:171], v[0:3]
	v_mfma_f32_16x16x32_bf16 v[52:55], v[180:183], v[148:151], v[52:55]
	v_mfma_f32_16x16x32_bf16 v[48:51], v[206:209], v[148:151], v[48:51]
	v_mfma_f32_16x16x32_bf16 v[36:39], v[180:183], v[156:159], v[36:39]
	v_mfma_f32_16x16x32_bf16 v[32:35], v[206:209], v[156:159], v[32:35]
	v_mfma_f32_16x16x32_bf16 v[20:23], v[180:183], v[164:167], v[20:23]
	v_mfma_f32_16x16x32_bf16 v[16:19], v[206:209], v[164:167], v[16:19]
	v_mfma_f32_16x16x32_bf16 v[4:7], v[180:183], v[172:175], v[4:7]
	v_mfma_f32_16x16x32_bf16 v[0:3], v[206:209], v[172:175], v[0:3]
	s_add_i32 s57, 0, 0x18000
	v_add_u32_e32 v140, s57, v240
	s_barrier
	s_setprio 0
	ds_read_b128 v[128:131], v140
	ds_read_b128 v[132:135], v140 offset:1024
	ds_read_b128 v[136:139], v140 offset:2048
	ds_read_b128 v[140:143], v140 offset:3072
	ds_read_b128 v[144:147], v242 offset:32768
	ds_read_b128 v[148:151], v242 offset:33792
	ds_read_b128 v[152:155], v242 offset:34816
	ds_read_b128 v[156:159], v242 offset:35840
	ds_read_b128 v[160:163], v242 offset:36864
	ds_read_b128 v[164:167], v242 offset:37888
	ds_read_b128 v[168:171], v242 offset:38912
	ds_read_b128 v[172:175], v242 offset:39936
	s_waitcnt lgkmcnt(8)
	s_waitcnt vmcnt(8)
	s_setprio 1
	s_barrier
; #define PG8_STAGE(bufoff, gbase, voff) do { _Pragma("unroll") for (int _i = 0; _i < 2; ++_i) \
;         __builtin_amdgcn_global_load_lds((const unsigned*)((const char*)(gbase) + (voff)[_i]), (LAS unsigned*)(lds + (bufoff) + ldsw + _i * 8192), 16, 0, 0); } while (0)
; #define PG8_LDA(dst, b, h) do { _Pragma("unroll") for (int m = 0; m < 4; ++m) _Pragma("unroll") for (int k = 0; k < 2; ++k) dst[m][k] = *(const LAS bf16x8*)(lds + PG8_SA(b, h) + aoff + m * 2048 + k * 1024); } while (0)
; #define PG8_LDB(dst, b, h) do { _Pragma("unroll") for (int n = 0; n < 2; ++n) _Pragma("unroll") for (int k = 0; k < 2; ++k) dst[n][k] = *(const LAS bf16x8*)(lds + PG8_SB(b, h) + boff + n * 2048 + k * 1024); } while (0)
; #define PG8_MMA(ai, bj, At, Bt) do { __builtin_amdgcn_s_setprio(1); _Pragma("unroll") for (int m = 0; m < 4; ++m) _Pragma("unroll") for (int n = 0; n < 2; ++n) _Pragma("unroll") for (int k = 0; k < 2; ++k) \
;         acc[ai][bj][m][n] = __builtin_amdgcn_mfma_f32_16x16x32_bf16(Bt[n][k], At[m][k], acc[ai][bj][m][n], 0, 0, 0); __builtin_amdgcn_s_setprio(0); } while (0)
; #define PG8_WAIT_V(n) asm volatile("s_waitcnt vmcnt(" #n ")" ::: "memory")
; #define PG8_WAIT_L(n) asm volatile("s_waitcnt lgkmcnt(" #n ")" ::: "memory")
; #define PG8_BAR __builtin_amdgcn_s_barrier()
; #define PG8_SCHED __builtin_amdgcn_sched_barrier(0)
; template <class Epi, class Sched>
; __device__ __forceinline__ void gemm_phase(LAS unsigned char* lds, const Gemm g, const Sched& S, const Epi& E) {
;     ...
;             PG8_WAIT_L(8); PG8_BAR; PG8_WAIT_L(0); PG8_MMA(0, 0, At, B0); PG8_BAR; PG8_SCHED;
;             PG8_LDB(B1, 1, 1); PG8_STAGE(PG8_SB(1, 0), b3, voffB);
;             PG8_BAR; PG8_WAIT_L(0); PG8_MMA(0, 1, At, B1); PG8_BAR;
;             PG8_LDA(At, 1, 1); PG8_STAGE(PG8_SA(1, 0), a3, voffA);
;             PG8_BAR; PG8_WAIT_L(0); PG8_MMA(1, 0, At, B0); PG8_BAR; PG8_SCHED;
;             PG8_STAGE(PG8_SB(1, 1), b3 + hstep, voffB);
;             PG8_WAIT_V(6); PG8_BAR; PG8_MMA(1, 1, At, B1); PG8_BAR;
	s_waitcnt lgkmcnt(0)
	v_mfma_f32_16x16x32_bf16 v[124:127], v[128:131], v[144:147], v[124:127]
	v_mfma_f32_16x16x32_bf16 v[120:123], v[136:139], v[144:147], v[120:123]
	v_mfma_f32_16x16x32_bf16 v[108:111], v[128:131], v[152:155], v[108:111]
	v_mfma_f32_16x16x32_bf16 v[104:107], v[136:139], v[152:155], v[104:107]
	v_mfma_f32_16x16x32_bf16 v[92:95], v[128:131], v[160:163], v[92:95]
	v_mfma_f32_16x16x32_bf16 v[88:91], v[136:139], v[160:163], v[88:91]
	v_mfma_f32_16x16x32_bf16 v[76:79], v[128:131], v[168:171], v[76:79]
	v_mfma_f32_16x16x32_bf16 v[72:75], v[136:139], v[168:171], v[72:75]
	v_mfma_f32_16x16x32_bf16 v[124:127], v[132:135], v[148:151], v[124:127]
	v_mfma_f32_16x16x32_bf16 v[120:123], v[140:143], v[148:151], v[120:123]
	v_mfma_f32_16x16x32_bf16 v[108:111], v[132:135], v[156:159], v[108:111]
	v_mfma_f32_16x16x32_bf16 v[104:107], v[140:143], v[156:159], v[104:107]
	v_mfma_f32_16x16x32_bf16 v[92:95], v[132:135], v[164:167], v[92:95]
	v_mfma_f32_16x16x32_bf16 v[88:91], v[140:143], v[164:167], v[88:91]
	v_mfma_f32_16x16x32_bf16 v[76:79], v[132:135], v[172:175], v[76:79]
	v_mfma_f32_16x16x32_bf16 v[72:75], v[140:143], v[172:175], v[72:75]
	s_barrier
	s_setprio 0
	s_add_i32 s28, 0, 0x1c000
	s_add_i32 s22, s57, s34
	v_add_u32_e32 v206, s28, v240
	s_add_u32 s0, s26, 0x80
	s_addc_u32 s1, s27, 0
	s_mov_b32 m0, s22
	ds_read_b128 v[176:179], v206
	ds_read_b128 v[180:183], v206 offset:1024
	ds_read_b128 v[184:187], v206 offset:2048
	ds_read_b128 v[206:209], v206 offset:3072
	global_load_lds_dwordx4 v190, s[0:1]
	s_add_i32 m0, s22, 0x2000
	s_nop 0
	global_load_lds_dwordx4 v194, s[0:1]
	s_waitcnt vmcnt(8)
	s_setprio 1
	s_barrier
	s_waitcnt lgkmcnt(0)
	v_mfma_f32_16x16x32_bf16 v[116:119], v[176:179], v[144:147], v[116:119]
	v_mfma_f32_16x16x32_bf16 v[112:115], v[184:187], v[144:147], v[112:115]
	v_mfma_f32_16x16x32_bf16 v[100:103], v[176:179], v[152:155], v[100:103]
	v_mfma_f32_16x16x32_bf16 v[96:99], v[184:187], v[152:155], v[96:99]
	v_mfma_f32_16x16x32_bf16 v[84:87], v[176:179], v[160:163], v[84:87]
	v_mfma_f32_16x16x32_bf16 v[80:83], v[184:187], v[160:163], v[80:83]
	v_mfma_f32_16x16x32_bf16 v[68:71], v[176:179], v[168:171], v[68:71]
	v_mfma_f32_16x16x32_bf16 v[64:67], v[184:187], v[168:171], v[64:67]
	v_mfma_f32_16x16x32_bf16 v[116:119], v[180:183], v[148:151], v[116:119]
	v_mfma_f32_16x16x32_bf16 v[112:115], v[206:209], v[148:151], v[112:115]
	v_mfma_f32_16x16x32_bf16 v[100:103], v[180:183], v[156:159], v[100:103]
	v_mfma_f32_16x16x32_bf16 v[96:99], v[206:209], v[156:159], v[96:99]
	v_mfma_f32_16x16x32_bf16 v[84:87], v[180:183], v[164:167], v[84:87]
	v_mfma_f32_16x16x32_bf16 v[80:83], v[206:209], v[164:167], v[80:83]
	v_mfma_f32_16x16x32_bf16 v[68:71], v[180:183], v[172:175], v[68:71]
	v_mfma_f32_16x16x32_bf16 v[64:67], v[206:209], v[172:175], v[64:67]
	s_mov_b32 m0, s44
	s_mov_b64 s[0:1], 0x80
	v_lshl_add_u64 v[210:211], v[214:215], 0, s[0:1]
	s_barrier
	s_setprio 0
	ds_read_b128 v[144:147], v242 offset:49152
	ds_read_b128 v[148:151], v242 offset:50176
	ds_read_b128 v[152:155], v242 offset:51200
	ds_read_b128 v[156:159], v242 offset:52224
	ds_read_b128 v[160:163], v242 offset:53248
	ds_read_b128 v[164:167], v242 offset:54272
	ds_read_b128 v[168:171], v242 offset:55296
	ds_read_b128 v[172:175], v242 offset:56320
	global_load_lds_dwordx4 v[210:211], off
	v_lshl_add_u64 v[210:211], v[216:217], 0, s[0:1]
	s_mov_b32 m0, s45
	s_nop 0
	global_load_lds_dwordx4 v[210:211], off
	s_setprio 1
	s_barrier
	s_waitcnt lgkmcnt(0)
	v_mfma_f32_16x16x32_bf16 v[60:63], v[128:131], v[144:147], v[60:63]
	v_mfma_f32_16x16x32_bf16 v[56:59], v[136:139], v[144:147], v[56:59]
	v_mfma_f32_16x16x32_bf16 v[44:47], v[128:131], v[152:155], v[44:47]
	v_mfma_f32_16x16x32_bf16 v[40:43], v[136:139], v[152:155], v[40:43]
	v_mfma_f32_16x16x32_bf16 v[28:31], v[128:131], v[160:163], v[28:31]
	v_mfma_f32_16x16x32_bf16 v[24:27], v[136:139], v[160:163], v[24:27]
	v_mfma_f32_16x16x32_bf16 v[12:15], v[128:131], v[168:171], v[12:15]
	v_mfma_f32_16x16x32_bf16 v[8:11], v[136:139], v[168:171], v[8:11]
	v_mfma_f32_16x16x32_bf16 v[60:63], v[132:135], v[148:151], v[60:63]
	v_mfma_f32_16x16x32_bf16 v[56:59], v[140:143], v[148:151], v[56:59]
	v_mfma_f32_16x16x32_bf16 v[44:47], v[132:135], v[156:159], v[44:47]
	v_mfma_f32_16x16x32_bf16 v[40:43], v[140:143], v[156:159], v[40:43]
	v_mfma_f32_16x16x32_bf16 v[28:31], v[132:135], v[164:167], v[28:31]
	v_mfma_f32_16x16x32_bf16 v[24:27], v[140:143], v[164:167], v[24:27]
	v_mfma_f32_16x16x32_bf16 v[12:15], v[132:135], v[172:175], v[12:15]
	v_mfma_f32_16x16x32_bf16 v[8:11], v[140:143], v[172:175], v[8:11]
	s_barrier
	s_setprio 0
	s_add_u32 s22, s26, 0xb0080
	s_addc_u32 s23, s27, 0
	s_add_i32 s26, s28, s34
	s_mov_b32 m0, s26
	s_nop 0
	global_load_lds_dwordx4 v190, s[22:23]
	s_add_i32 m0, s26, 0x2000
	s_nop 0
	global_load_lds_dwordx4 v194, s[22:23]
	s_waitcnt vmcnt(8)
	s_setprio 1
	s_barrier
	v_mfma_f32_16x16x32_bf16 v[52:55], v[176:179], v[144:147], v[52:55]
	v_mfma_f32_16x16x32_bf16 v[48:51], v[184:187], v[144:147], v[48:51]
	v_mfma_f32_16x16x32_bf16 v[36:39], v[176:179], v[152:155], v[36:39]
	v_mfma_f32_16x16x32_bf16 v[32:35], v[184:187], v[152:155], v[32:35]
	v_mfma_f32_16x16x32_bf16 v[20:23], v[176:179], v[160:163], v[20:23]
	v_mfma_f32_16x16x32_bf16 v[16:19], v[184:187], v[160:163], v[16:19]
	v_mfma_f32_16x16x32_bf16 v[4:7], v[176:179], v[168:171], v[4:7]
	v_mfma_f32_16x16x32_bf16 v[0:3], v[184:187], v[168:171], v[0:3]
	v_mfma_f32_16x16x32_bf16 v[52:55], v[180:183], v[148:151], v[52:55]
	v_mfma_f32_16x16x32_bf16 v[48:51], v[206:209], v[148:151], v[48:51]
	v_mfma_f32_16x16x32_bf16 v[36:39], v[180:183], v[156:159], v[36:39]
	v_mfma_f32_16x16x32_bf16 v[32:35], v[206:209], v[156:159], v[32:35]
	v_mfma_f32_16x16x32_bf16 v[20:23], v[180:183], v[164:167], v[20:23]
	v_mfma_f32_16x16x32_bf16 v[16:19], v[206:209], v[164:167], v[16:19]
	v_mfma_f32_16x16x32_bf16 v[4:7], v[180:183], v[172:175], v[4:7]
	v_mfma_f32_16x16x32_bf16 v[0:3], v[206:209], v[172:175], v[0:3]
	s_add_i32 s56, s56, 2
	s_add_u32 s54, s54, 0x100
	s_addc_u32 s55, s55, 0
	s_cmp_gt_u32 s56, 41
	s_mov_b64 s[22:23], s[24:25]
	s_barrier
; __device__ __forceinline__ unsigned cvt_pk_bf16(float lo, float hi) { unsigned r; asm volatile("v_cvt_pk_bf16_f32 %0, %1, %2" : "=v"(r) : "v"(lo), "v"(hi)); return r; }
; __device__ __forceinline__ float bf_lo(unsigned u) { return __uint_as_float(u << 16); }
; __device__ __forceinline__ float bf_hi(unsigned u) { return __uint_as_float(u & 0xffff0000u); }
;     __device__ __forceinline__ void operator()(const AccT& acc, const Unit& u, int wr, int wc, int fr, int fq) const {
;     ...
;         const int rowt = u.pm * 256; const int b = rowt >> 11;
;         const bf16_t* res = res_b + (size_t)rowt * DM; bf16_t* out = hb + (size_t)rowt * DM;
;         const int col0 = u.pn * 256 + wc * 32 + 8 * fq;
;         f32x4 gv[2][2];
; #pragma unroll
;         for (int bj = 0; bj < 2; ++bj)
; #pragma unroll
;             for (int n = 0; n < 2; ++n) gv[bj][n] = *(const f32x4*)(gate + (size_t)b * NMOD + col0 + bj * 128 + n * 4) * gs;
;         u32x4 r[2][4][2];
; #pragma unroll
;         for (int ai = 0; ai < 2; ++ai)
; #pragma unroll
;             for (int m = 0; m < 4; ++m)
; #pragma unroll
;                 for (int bj = 0; bj < 2; ++bj) r[ai][m][bj] = *(const u32x4*)(res + (size_t)(wr * 64 + fr + ai * 128 + m * 16) * DM + col0 + bj * 128);
; #pragma unroll
;         for (int ai = 0; ai < 2; ++ai)
; #pragma unroll
;             for (int m = 0; m < 4; ++m)
; #pragma unroll
;                 for (int bj = 0; bj < 2; ++bj) {
;                     const u32x4 q = r[ai][m][bj];
;                     const f32x4 r0 = {bf_lo(q.x), bf_hi(q.x), bf_lo(q.y), bf_hi(q.y)}, r1 = {bf_lo(q.z), bf_hi(q.z), bf_lo(q.w), bf_hi(q.w)};
;                     const f32x4 h0 = r0 + gv[bj][0] * acc[ai][bj][m][0], h1 = r1 + gv[bj][1] * acc[ai][bj][m][1];
;                     u32x4 w; w.x = cvt_pk_bf16(h0[0], h0[1]); w.y = cvt_pk_bf16(h0[2], h0[3]); w.z = cvt_pk_bf16(h1[0], h1[1]); w.w = cvt_pk_bf16(h1[2], h1[3]);
;                     *(u32x4*)(out + (size_t)(wr * 64 + fr + ai * 128 + m * 16) * DM + col0 + bj * 128) = w;
;                 }
	s_setprio 0
	s_cbranch_scc0 .LBB0_1097
	s_lshl_b32 s25, s52, 8
	v_mov_b32_e32 v140, v239
	v_mov_b32_e32 v128, v238
	s_lshl_b32 s22, s53, 8
	s_ashr_i32 s24, s53, 3
	s_or_b32 s25, s25, s43
	s_ashr_i32 s23, s22, 31
	v_lshl_add_u32 v136, v128, 3, s25
	s_mul_hi_i32 s25, s24, 0x9000
	s_mul_i32 s24, s24, 0x9000
	s_add_u32 s24, s40, s24
	s_addc_u32 s25, s41, s25
	v_ashrrev_i32_e32 v137, 31, v136
	v_lshl_add_u64 v[138:139], v[136:137], 2, s[24:25]
	global_load_dwordx4 v[128:131], v[138:139], off offset:16
	global_load_dwordx4 v[132:135], v[138:139], off
	s_lshl_b64 s[22:23], s[22:23], 11
	s_add_u32 s24, s80, s22
	s_addc_u32 s25, s81, s23
	v_lshlrev_b64 v[226:227], 1, v[136:137]
	s_add_u32 s22, s96, s22
	s_addc_u32 s23, s97, s23
	s_and_b64 vcc, exec, s[2:3]
	s_mov_b32 s52, s50
	s_mov_b32 s53, s51
	s_waitcnt vmcnt(0)
	v_pk_mul_f32 v[216:217], v[130:131], 0.5 op_sel_hi:[1,0]
	v_pk_mul_f32 v[220:221], v[134:135], 0.5 op_sel_hi:[1,0]
	v_pk_mul_f32 v[218:219], v[132:133], 0.5 op_sel_hi:[1,0]
	v_pk_mul_f32 v[214:215], v[128:129], 0.5 op_sel_hi:[1,0]
	global_load_dwordx4 v[128:131], v[138:139], off offset:528
	global_load_dwordx4 v[132:135], v[138:139], off offset:512
	s_waitcnt vmcnt(0)
	v_pk_mul_f32 v[206:207], v[128:129], 0.5 op_sel_hi:[1,0]
	v_add_u32_e32 v128, s42, v140
	v_ashrrev_i32_e32 v129, 31, v128
	v_pk_mul_f32 v[208:209], v[130:131], 0.5 op_sel_hi:[1,0]
	v_lshl_add_u64 v[130:131], s[24:25], 0, v[226:227]
	v_lshlrev_b64 v[248:249], 11, v[128:129]
	v_lshl_add_u64 v[128:129], v[130:131], 0, v[248:249]
	global_load_dwordx4 v[244:247], v[128:129], off
	global_load_dwordx4 v[184:187], v[128:129], off offset:256
	v_lshl_add_u64 v[236:237], v[248:249], 0, s[8:9]
	v_lshl_add_u64 v[128:129], v[130:131], 0, v[236:237]
	global_load_dwordx4 v[180:183], v[128:129], off
	global_load_dwordx4 v[176:179], v[128:129], off offset:256
	v_lshl_add_u64 v[234:235], v[248:249], 0, s[10:11]
	v_lshl_add_u64 v[128:129], v[130:131], 0, v[234:235]
	global_load_dwordx4 v[172:175], v[128:129], off
	global_load_dwordx4 v[168:171], v[128:129], off offset:256
	v_lshl_add_u64 v[232:233], v[248:249], 0, s[12:13]
	v_lshl_add_u64 v[128:129], v[130:131], 0, v[232:233]
	global_load_dwordx4 v[164:167], v[128:129], off
	global_load_dwordx4 v[160:163], v[128:129], off offset:256
	v_lshl_add_u64 v[230:231], v[248:249], 0, s[14:15]
	v_lshl_add_u64 v[128:129], v[130:131], 0, v[230:231]
	global_load_dwordx4 v[156:159], v[128:129], off
	global_load_dwordx4 v[152:155], v[128:129], off offset:256
	v_lshl_add_u64 v[228:229], v[248:249], 0, s[16:17]
	v_lshl_add_u64 v[128:129], v[130:131], 0, v[228:229]
	global_load_dwordx4 v[148:151], v[128:129], off
	global_load_dwordx4 v[144:147], v[128:129], off offset:256
	v_lshl_add_u64 v[224:225], v[248:249], 0, s[18:19]
	v_lshl_add_u64 v[128:129], v[130:131], 0, v[224:225]
	global_load_dwordx4 v[140:143], v[128:129], off
	global_load_dwordx4 v[136:139], v[128:129], off offset:256
	v_lshl_add_u64 v[222:223], v[248:249], 0, s[20:21]
	v_lshl_add_u64 v[128:129], v[130:131], 0, v[222:223]
	v_pk_mul_f32 v[212:213], v[134:135], 0.5 op_sel_hi:[1,0]
	v_pk_mul_f32 v[210:211], v[132:133], 0.5 op_sel_hi:[1,0]
	global_load_dwordx4 v[132:135], v[128:129], off
	s_nop 0
	global_load_dwordx4 v[128:131], v[128:129], off offset:256
	v_lshl_add_u64 v[226:227], s[22:23], 0, v[226:227]
	v_lshl_add_u64 v[248:249], v[226:227], 0, v[248:249]
	s_mov_b64 s[24:25], s[6:7]
	s_mov_b64 s[22:23], s[4:5]
	s_waitcnt vmcnt(0)
	v_lshlrev_b32_e32 v250, 16, v244
	v_and_b32_e32 v251, 0xffff0000, v244
	v_lshlrev_b32_e32 v244, 16, v245
	v_and_b32_e32 v245, 0xffff0000, v245
	v_lshlrev_b32_e32 v252, 16, v246
	v_and_b32_e32 v253, 0xffff0000, v246
	v_lshlrev_b32_e32 v246, 16, v247
	v_and_b32_e32 v247, 0xffff0000, v247
	v_pk_fma_f32 v[126:127], v[126:127], v[220:221], v[244:245]
	v_pk_fma_f32 v[124:125], v[124:125], v[218:219], v[250:251]
	v_pk_fma_f32 v[244:245], v[122:123], v[216:217], v[246:247]
	v_pk_fma_f32 v[122:123], v[120:121], v[214:215], v[252:253]
	v_cvt_pk_bf16_f32 v120, v124, v125
	v_cvt_pk_bf16_f32 v121, v126, v127
	v_lshlrev_b32_e32 v124, 16, v186
	v_cvt_pk_bf16_f32 v122, v122, v123
	v_cvt_pk_bf16_f32 v123, v244, v245
	global_store_dwordx4 v[248:249], v[120:123], off
	v_and_b32_e32 v125, 0xffff0000, v186
	v_lshlrev_b32_e32 v126, 16, v187
	v_lshlrev_b32_e32 v120, 16, v184
	v_and_b32_e32 v121, 0xffff0000, v184
	v_and_b32_e32 v127, 0xffff0000, v187
	v_lshlrev_b32_e32 v122, 16, v185
	v_and_b32_e32 v123, 0xffff0000, v185
	v_pk_fma_f32 v[116:117], v[116:117], v[210:211], v[120:121]
	v_pk_fma_f32 v[120:121], v[114:115], v[208:209], v[126:127]
	v_pk_fma_f32 v[114:115], v[112:113], v[206:207], v[124:125]
	v_pk_fma_f32 v[118:119], v[118:119], v[212:213], v[122:123]
	v_cvt_pk_bf16_f32 v112, v116, v117
	v_lshlrev_b32_e32 v116, 16, v181
	v_cvt_pk_bf16_f32 v113, v118, v119
	v_cvt_pk_bf16_f32 v114, v114, v115
	v_cvt_pk_bf16_f32 v115, v120, v121
	global_store_dwordx4 v[248:249], v[112:115], off offset:256
	v_and_b32_e32 v117, 0xffff0000, v181
	v_lshlrev_b32_e32 v118, 16, v182
	v_lshlrev_b32_e32 v114, 16, v180
	v_and_b32_e32 v115, 0xffff0000, v180
	v_and_b32_e32 v119, 0xffff0000, v182
	v_lshlrev_b32_e32 v120, 16, v183
	v_and_b32_e32 v121, 0xffff0000, v183
	v_lshl_add_u64 v[112:113], v[226:227], 0, v[236:237]
	v_pk_fma_f32 v[110:111], v[110:111], v[220:221], v[116:117]
	v_pk_fma_f32 v[108:109], v[108:109], v[218:219], v[114:115]
	v_pk_fma_f32 v[114:115], v[106:107], v[216:217], v[120:121]
	v_pk_fma_f32 v[106:107], v[104:105], v[214:215], v[118:119]
	v_cvt_pk_bf16_f32 v104, v108, v109
	v_cvt_pk_bf16_f32 v105, v110, v111
	v_lshlrev_b32_e32 v108, 16, v178
	v_cvt_pk_bf16_f32 v106, v106, v107
; __device__ __forceinline__ unsigned cvt_pk_bf16(float lo, float hi) { unsigned r; asm volatile("v_cvt_pk_bf16_f32 %0, %1, %2" : "=v"(r) : "v"(lo), "v"(hi)); return r; }
; __device__ __forceinline__ float bf_lo(unsigned u) { return __uint_as_float(u << 16); }
; __device__ __forceinline__ float bf_hi(unsigned u) { return __uint_as_float(u & 0xffff0000u); }
;     __device__ __forceinline__ void operator()(const AccT& acc, const Unit& u, int wr, int wc, int fr, int fq) const {
;     ...
;         for (int ai = 0; ai < 2; ++ai)
; #pragma unroll
;             for (int m = 0; m < 4; ++m)
; #pragma unroll
;                 for (int bj = 0; bj < 2; ++bj) {
;                     const u32x4 q = r[ai][m][bj];
;                     const f32x4 r0 = {bf_lo(q.x), bf_hi(q.x), bf_lo(q.y), bf_hi(q.y)}, r1 = {bf_lo(q.z), bf_hi(q.z), bf_lo(q.w), bf_hi(q.w)};
;                     const f32x4 h0 = r0 + gv[bj][0] * acc[ai][bj][m][0], h1 = r1 + gv[bj][1] * acc[ai][bj][m][1];
;                     u32x4 w; w.x = cvt_pk_bf16(h0[0], h0[1]); w.y = cvt_pk_bf16(h0[2], h0[3]); w.z = cvt_pk_bf16(h1[0], h1[1]); w.w = cvt_pk_bf16(h1[2], h1[3]);
;                     *(u32x4*)(out + (size_t)(wr * 64 + fr + ai * 128 + m * 16) * DM + col0 + bj * 128) = w;
;                 }
	v_cvt_pk_bf16_f32 v107, v114, v115
	global_store_dwordx4 v[112:113], v[104:107], off
	v_and_b32_e32 v109, 0xffff0000, v178
	v_lshlrev_b32_e32 v110, 16, v179
	v_lshlrev_b32_e32 v104, 16, v176
	v_and_b32_e32 v105, 0xffff0000, v176
	v_and_b32_e32 v111, 0xffff0000, v179
	v_lshlrev_b32_e32 v106, 16, v177
	v_and_b32_e32 v107, 0xffff0000, v177
	v_pk_fma_f32 v[100:101], v[100:101], v[210:211], v[104:105]
	v_pk_fma_f32 v[104:105], v[98:99], v[208:209], v[110:111]
	v_pk_fma_f32 v[98:99], v[96:97], v[206:207], v[108:109]
	v_pk_fma_f32 v[102:103], v[102:103], v[212:213], v[106:107]
	v_cvt_pk_bf16_f32 v96, v100, v101
	v_lshlrev_b32_e32 v100, 16, v173
	v_cvt_pk_bf16_f32 v97, v102, v103
	v_cvt_pk_bf16_f32 v98, v98, v99
	v_cvt_pk_bf16_f32 v99, v104, v105
	global_store_dwordx4 v[112:113], v[96:99], off offset:256
	v_and_b32_e32 v101, 0xffff0000, v173
	v_lshlrev_b32_e32 v102, 16, v174
	v_lshlrev_b32_e32 v98, 16, v172
	v_and_b32_e32 v99, 0xffff0000, v172
	v_and_b32_e32 v103, 0xffff0000, v174
	v_lshlrev_b32_e32 v104, 16, v175
	v_and_b32_e32 v105, 0xffff0000, v175
	v_lshl_add_u64 v[96:97], v[226:227], 0, v[234:235]
	v_pk_fma_f32 v[94:95], v[94:95], v[220:221], v[100:101]
	v_pk_fma_f32 v[92:93], v[92:93], v[218:219], v[98:99]
	v_pk_fma_f32 v[98:99], v[90:91], v[216:217], v[104:105]
	v_pk_fma_f32 v[90:91], v[88:89], v[214:215], v[102:103]
	v_cvt_pk_bf16_f32 v88, v92, v93
	v_cvt_pk_bf16_f32 v89, v94, v95
	v_lshlrev_b32_e32 v92, 16, v170
	v_cvt_pk_bf16_f32 v90, v90, v91
	v_cvt_pk_bf16_f32 v91, v98, v99
	global_store_dwordx4 v[96:97], v[88:91], off
	v_and_b32_e32 v93, 0xffff0000, v170
	v_lshlrev_b32_e32 v94, 16, v171
	v_lshlrev_b32_e32 v88, 16, v168
	v_and_b32_e32 v89, 0xffff0000, v168
	v_and_b32_e32 v95, 0xffff0000, v171
	v_lshlrev_b32_e32 v90, 16, v169
	v_and_b32_e32 v91, 0xffff0000, v169
	v_pk_fma_f32 v[84:85], v[84:85], v[210:211], v[88:89]
	v_pk_fma_f32 v[88:89], v[82:83], v[208:209], v[94:95]
	v_pk_fma_f32 v[82:83], v[80:81], v[206:207], v[92:93]
	v_pk_fma_f32 v[86:87], v[86:87], v[212:213], v[90:91]
	v_cvt_pk_bf16_f32 v80, v84, v85
	v_lshlrev_b32_e32 v84, 16, v165
	v_cvt_pk_bf16_f32 v81, v86, v87
	v_cvt_pk_bf16_f32 v82, v82, v83
	v_cvt_pk_bf16_f32 v83, v88, v89
	global_store_dwordx4 v[96:97], v[80:83], off offset:256
	v_and_b32_e32 v85, 0xffff0000, v165
	v_lshlrev_b32_e32 v86, 16, v166
	v_lshlrev_b32_e32 v82, 16, v164
	v_and_b32_e32 v83, 0xffff0000, v164
	v_and_b32_e32 v87, 0xffff0000, v166
	v_lshlrev_b32_e32 v88, 16, v167
	v_and_b32_e32 v89, 0xffff0000, v167
	v_lshl_add_u64 v[80:81], v[226:227], 0, v[232:233]
	v_pk_fma_f32 v[78:79], v[78:79], v[220:221], v[84:85]
	v_pk_fma_f32 v[76:77], v[76:77], v[218:219], v[82:83]
	v_pk_fma_f32 v[82:83], v[74:75], v[216:217], v[88:89]
	v_pk_fma_f32 v[74:75], v[72:73], v[214:215], v[86:87]
	v_cvt_pk_bf16_f32 v72, v76, v77
	v_cvt_pk_bf16_f32 v73, v78, v79
	v_lshlrev_b32_e32 v76, 16, v162
	v_cvt_pk_bf16_f32 v74, v74, v75
	v_cvt_pk_bf16_f32 v75, v82, v83
	global_store_dwordx4 v[80:81], v[72:75], off
	v_and_b32_e32 v77, 0xffff0000, v162
	v_lshlrev_b32_e32 v78, 16, v163
	v_lshlrev_b32_e32 v72, 16, v160
	v_and_b32_e32 v73, 0xffff0000, v160
	v_and_b32_e32 v79, 0xffff0000, v163
	v_lshlrev_b32_e32 v74, 16, v161
	v_and_b32_e32 v75, 0xffff0000, v161
	v_pk_fma_f32 v[68:69], v[68:69], v[210:211], v[72:73]
	v_pk_fma_f32 v[72:73], v[66:67], v[208:209], v[78:79]
	v_pk_fma_f32 v[66:67], v[64:65], v[206:207], v[76:77]
	v_pk_fma_f32 v[70:71], v[70:71], v[212:213], v[74:75]
	v_cvt_pk_bf16_f32 v64, v68, v69
	v_lshlrev_b32_e32 v68, 16, v157
	v_cvt_pk_bf16_f32 v65, v70, v71
	v_cvt_pk_bf16_f32 v66, v66, v67
	v_cvt_pk_bf16_f32 v67, v72, v73
	global_store_dwordx4 v[80:81], v[64:67], off offset:256
	v_and_b32_e32 v69, 0xffff0000, v157
	v_lshlrev_b32_e32 v70, 16, v158
	v_lshlrev_b32_e32 v66, 16, v156
	v_and_b32_e32 v67, 0xffff0000, v156
	v_and_b32_e32 v71, 0xffff0000, v158
	v_lshlrev_b32_e32 v72, 16, v159
	v_and_b32_e32 v73, 0xffff0000, v159
	v_lshl_add_u64 v[64:65], v[226:227], 0, v[230:231]
	v_pk_fma_f32 v[62:63], v[62:63], v[220:221], v[68:69]
	v_pk_fma_f32 v[60:61], v[60:61], v[218:219], v[66:67]
	v_pk_fma_f32 v[66:67], v[58:59], v[216:217], v[72:73]
	v_pk_fma_f32 v[58:59], v[56:57], v[214:215], v[70:71]
	v_cvt_pk_bf16_f32 v56, v60, v61
	v_cvt_pk_bf16_f32 v57, v62, v63
	v_lshlrev_b32_e32 v60, 16, v154
	v_cvt_pk_bf16_f32 v58, v58, v59
	v_cvt_pk_bf16_f32 v59, v66, v67
	global_store_dwordx4 v[64:65], v[56:59], off
	v_and_b32_e32 v61, 0xffff0000, v154
	v_lshlrev_b32_e32 v62, 16, v155
	v_lshlrev_b32_e32 v56, 16, v152
	v_and_b32_e32 v57, 0xffff0000, v152
	v_and_b32_e32 v63, 0xffff0000, v155
	v_lshlrev_b32_e32 v58, 16, v153
	v_and_b32_e32 v59, 0xffff0000, v153
	v_pk_fma_f32 v[52:53], v[52:53], v[210:211], v[56:57]
; __device__ __forceinline__ unsigned cvt_pk_bf16(float lo, float hi) { unsigned r; asm volatile("v_cvt_pk_bf16_f32 %0, %1, %2" : "=v"(r) : "v"(lo), "v"(hi)); return r; }
; __device__ __forceinline__ float bf_lo(unsigned u) { return __uint_as_float(u << 16); }
; __device__ __forceinline__ float bf_hi(unsigned u) { return __uint_as_float(u & 0xffff0000u); }
; #define PG8_WAIT_V(n) asm volatile("s_waitcnt vmcnt(" #n ")" ::: "memory")
; #define PG8_BAR __builtin_amdgcn_s_barrier()
; template <class Epi, class Sched>
; __device__ __forceinline__ void gemm_phase(LAS unsigned char* lds, const Gemm g, const Sched& S, const Epi& E) {
;     ...
;     PG8_WAIT_V(0);
;     if (wr == 0) PG8_BAR;
;     PG8_BAR;
;     __device__ __forceinline__ void operator()(const AccT& acc, const Unit& u, int wr, int wc, int fr, int fq) const {
;     ...
;         for (int ai = 0; ai < 2; ++ai)
; #pragma unroll
;             for (int m = 0; m < 4; ++m)
; #pragma unroll
;                 for (int bj = 0; bj < 2; ++bj) {
;                     const u32x4 q = r[ai][m][bj];
;                     const f32x4 r0 = {bf_lo(q.x), bf_hi(q.x), bf_lo(q.y), bf_hi(q.y)}, r1 = {bf_lo(q.z), bf_hi(q.z), bf_lo(q.w), bf_hi(q.w)};
;                     const f32x4 h0 = r0 + gv[bj][0] * acc[ai][bj][m][0], h1 = r1 + gv[bj][1] * acc[ai][bj][m][1];
;                     u32x4 w; w.x = cvt_pk_bf16(h0[0], h0[1]); w.y = cvt_pk_bf16(h0[2], h0[3]); w.z = cvt_pk_bf16(h1[0], h1[1]); w.w = cvt_pk_bf16(h1[2], h1[3]);
;                     *(u32x4*)(out + (size_t)(wr * 64 + fr + ai * 128 + m * 16) * DM + col0 + bj * 128) = w;
;                 }
	v_pk_fma_f32 v[56:57], v[50:51], v[208:209], v[62:63]
	v_pk_fma_f32 v[50:51], v[48:49], v[206:207], v[60:61]
	v_pk_fma_f32 v[54:55], v[54:55], v[212:213], v[58:59]
	v_cvt_pk_bf16_f32 v48, v52, v53
	v_lshlrev_b32_e32 v52, 16, v149
	v_cvt_pk_bf16_f32 v49, v54, v55
	v_cvt_pk_bf16_f32 v50, v50, v51
	v_cvt_pk_bf16_f32 v51, v56, v57
	global_store_dwordx4 v[64:65], v[48:51], off offset:256
	v_and_b32_e32 v53, 0xffff0000, v149
	v_lshlrev_b32_e32 v54, 16, v150
	v_lshlrev_b32_e32 v50, 16, v148
	v_and_b32_e32 v51, 0xffff0000, v148
	v_and_b32_e32 v55, 0xffff0000, v150
	v_lshlrev_b32_e32 v56, 16, v151
	v_and_b32_e32 v57, 0xffff0000, v151
	v_lshl_add_u64 v[48:49], v[226:227], 0, v[228:229]
	v_pk_fma_f32 v[46:47], v[46:47], v[220:221], v[52:53]
	v_pk_fma_f32 v[44:45], v[44:45], v[218:219], v[50:51]
	v_pk_fma_f32 v[50:51], v[42:43], v[216:217], v[56:57]
	v_pk_fma_f32 v[42:43], v[40:41], v[214:215], v[54:55]
	v_cvt_pk_bf16_f32 v40, v44, v45
	v_cvt_pk_bf16_f32 v41, v46, v47
	v_lshlrev_b32_e32 v44, 16, v146
	v_cvt_pk_bf16_f32 v42, v42, v43
	v_cvt_pk_bf16_f32 v43, v50, v51
	global_store_dwordx4 v[48:49], v[40:43], off
	v_and_b32_e32 v45, 0xffff0000, v146
	v_lshlrev_b32_e32 v46, 16, v147
	v_lshlrev_b32_e32 v40, 16, v144
	v_and_b32_e32 v41, 0xffff0000, v144
	v_and_b32_e32 v47, 0xffff0000, v147
	v_lshlrev_b32_e32 v42, 16, v145
	v_and_b32_e32 v43, 0xffff0000, v145
	v_pk_fma_f32 v[36:37], v[36:37], v[210:211], v[40:41]
	v_pk_fma_f32 v[40:41], v[34:35], v[208:209], v[46:47]
	v_pk_fma_f32 v[34:35], v[32:33], v[206:207], v[44:45]
	v_pk_fma_f32 v[38:39], v[38:39], v[212:213], v[42:43]
	v_cvt_pk_bf16_f32 v32, v36, v37
	v_lshlrev_b32_e32 v36, 16, v141
	v_cvt_pk_bf16_f32 v33, v38, v39
	v_cvt_pk_bf16_f32 v34, v34, v35
	v_cvt_pk_bf16_f32 v35, v40, v41
	global_store_dwordx4 v[48:49], v[32:35], off offset:256
	v_and_b32_e32 v37, 0xffff0000, v141
	v_lshlrev_b32_e32 v38, 16, v142
	v_lshlrev_b32_e32 v34, 16, v140
	v_and_b32_e32 v35, 0xffff0000, v140
	v_and_b32_e32 v39, 0xffff0000, v142
	v_lshlrev_b32_e32 v40, 16, v143
	v_and_b32_e32 v41, 0xffff0000, v143
	v_lshl_add_u64 v[32:33], v[226:227], 0, v[224:225]
	v_pk_fma_f32 v[30:31], v[30:31], v[220:221], v[36:37]
	v_pk_fma_f32 v[28:29], v[28:29], v[218:219], v[34:35]
	v_pk_fma_f32 v[34:35], v[26:27], v[216:217], v[40:41]
	v_pk_fma_f32 v[26:27], v[24:25], v[214:215], v[38:39]
	v_cvt_pk_bf16_f32 v24, v28, v29
	v_cvt_pk_bf16_f32 v25, v30, v31
	v_lshlrev_b32_e32 v28, 16, v138
	v_cvt_pk_bf16_f32 v26, v26, v27
	v_cvt_pk_bf16_f32 v27, v34, v35
	global_store_dwordx4 v[32:33], v[24:27], off
	v_and_b32_e32 v29, 0xffff0000, v138
	v_lshlrev_b32_e32 v30, 16, v139
	v_lshlrev_b32_e32 v24, 16, v136
	v_and_b32_e32 v25, 0xffff0000, v136
	v_and_b32_e32 v31, 0xffff0000, v139
	v_lshlrev_b32_e32 v26, 16, v137
	v_and_b32_e32 v27, 0xffff0000, v137
	v_pk_fma_f32 v[20:21], v[20:21], v[210:211], v[24:25]
	v_pk_fma_f32 v[24:25], v[18:19], v[208:209], v[30:31]
	v_pk_fma_f32 v[18:19], v[16:17], v[206:207], v[28:29]
	v_pk_fma_f32 v[22:23], v[22:23], v[212:213], v[26:27]
	v_cvt_pk_bf16_f32 v16, v20, v21
	v_lshlrev_b32_e32 v20, 16, v133
	v_cvt_pk_bf16_f32 v17, v22, v23
	v_cvt_pk_bf16_f32 v18, v18, v19
	v_cvt_pk_bf16_f32 v19, v24, v25
	global_store_dwordx4 v[32:33], v[16:19], off offset:256
	v_and_b32_e32 v21, 0xffff0000, v133
	v_lshlrev_b32_e32 v22, 16, v134
	v_lshlrev_b32_e32 v18, 16, v132
	v_and_b32_e32 v19, 0xffff0000, v132
	v_and_b32_e32 v23, 0xffff0000, v134
	v_lshlrev_b32_e32 v24, 16, v135
	v_and_b32_e32 v25, 0xffff0000, v135
	v_lshl_add_u64 v[16:17], v[226:227], 0, v[222:223]
	v_pk_fma_f32 v[14:15], v[14:15], v[220:221], v[20:21]
	v_pk_fma_f32 v[12:13], v[12:13], v[218:219], v[18:19]
	v_pk_fma_f32 v[18:19], v[10:11], v[216:217], v[24:25]
	v_pk_fma_f32 v[10:11], v[8:9], v[214:215], v[22:23]
	v_cvt_pk_bf16_f32 v8, v12, v13
	v_cvt_pk_bf16_f32 v9, v14, v15
	v_lshlrev_b32_e32 v12, 16, v130
	v_cvt_pk_bf16_f32 v10, v10, v11
	v_cvt_pk_bf16_f32 v11, v18, v19
	global_store_dwordx4 v[16:17], v[8:11], off
	v_and_b32_e32 v13, 0xffff0000, v130
	v_lshlrev_b32_e32 v14, 16, v131
	v_lshlrev_b32_e32 v8, 16, v128
	v_and_b32_e32 v9, 0xffff0000, v128
	v_and_b32_e32 v15, 0xffff0000, v131
	v_lshlrev_b32_e32 v10, 16, v129
	v_and_b32_e32 v11, 0xffff0000, v129
	v_pk_fma_f32 v[4:5], v[4:5], v[210:211], v[8:9]
	v_pk_fma_f32 v[8:9], v[2:3], v[208:209], v[14:15]
	v_pk_fma_f32 v[2:3], v[0:1], v[206:207], v[12:13]
	v_pk_fma_f32 v[6:7], v[6:7], v[212:213], v[10:11]
	v_cvt_pk_bf16_f32 v0, v4, v5
	s_nop 0
	v_cvt_pk_bf16_f32 v1, v6, v7
	v_cvt_pk_bf16_f32 v2, v2, v3
	v_cvt_pk_bf16_f32 v3, v8, v9
	global_store_dwordx4 v[16:17], v[0:3], off offset:256
	s_cbranch_vccz .LBB0_1086
	s_waitcnt vmcnt(0)
	s_cmpk_gt_u32 s30, 0xff
	s_cbranch_scc1 .LBB0_1101
	s_barrier
